# v23 + in-proj (bf16 and fp8 streams) and out/final epilogue flat stores/loads converted to global ops (no lgkmcnt coupling at the unit transition)
# speedup vs baseline: 1.0053x; 1.0021x over previous
.LBB0_110:
	s_cmp_gt_u32 s76, 15
	s_cbranch_scc0 .LBB0_150
	s_cmp_gt_u32 s76, 23
	s_cbranch_scc0 .LBB0_147
	s_cmp_gt_u32 s76, 31
	s_cbranch_scc0 .LBB0_144
	s_cmp_gt_u32 s76, 39
	s_cbranch_scc0 .LBB0_141
	s_cmp_gt_u32 s76, 47
	s_cbranch_scc0 .LBB0_138
	s_cmp_gt_u32 s76, 51
	s_cbranch_scc0 .LBB0_135
	s_cmp_gt_u32 s76, 55
	s_cbranch_scc0 .LBB0_132
	s_cmp_gt_u32 s76, 63
	s_cbranch_scc0 .LBB0_129
	s_cmpk_gt_u32 s76, 0x47
	s_cbranch_scc0 .LBB0_126
	s_cmpk_gt_u32 s76, 0x77
	s_cbranch_scc0 .LBB0_123
	s_and_saveexec_b64 s[6:7], s[36:37]
	s_cbranch_execz .LBB0_122
	v_or_b32_e32 v134, 16, v154
	v_ashrrev_i32_e32 v155, 31, v154
	v_ashrrev_i32_e32 v135, 31, v134
	v_lshlrev_b64 v[132:133], 6, v[154:155]
	v_lshlrev_b64 v[134:135], 6, v[134:135]
	v_lshl_add_u64 v[132:133], v[148:149], 0, v[132:133]
	v_lshl_add_u64 v[134:135], v[148:149], 0, v[134:135]
	global_store_dwordx4 v[132:133], v[128:131], off
	global_store_dwordx4 v[132:133], v[124:127], off offset:16
	global_store_dwordx4 v[134:135], v[112:115], off
	global_store_dwordx4 v[134:135], v[108:111], off offset:16
	v_or_b32_e32 v134, 32, v154
	v_ashrrev_i32_e32 v135, 31, v134
	v_lshlrev_b64 v[134:135], 6, v[134:135]
	v_lshl_add_u64 v[134:135], v[148:149], 0, v[134:135]
	global_store_dwordx4 v[134:135], v[96:99], off
	global_store_dwordx4 v[134:135], v[92:95], off offset:16
	v_or_b32_e32 v134, 48, v154
	v_ashrrev_i32_e32 v135, 31, v134
	v_lshlrev_b64 v[134:135], 6, v[134:135]
	v_lshl_add_u64 v[134:135], v[148:149], 0, v[134:135]
	s_mov_b64 s[8:9], 0x2000
	v_add_co_u32_e32 v136, vcc, 0x2000, v132
	global_store_dwordx4 v[134:135], v[80:83], off
	global_store_dwordx4 v[134:135], v[76:79], off offset:16
	v_lshl_add_u64 v[134:135], v[132:133], 0, s[8:9]
	v_addc_co_u32_e32 v137, vcc, 0, v133, vcc
	s_mov_b64 s[8:9], 0x2400
	global_store_dwordx4 v[136:137], v[64:67], off
	global_store_dwordx4 v[134:135], v[60:63], off offset:16
	v_lshl_add_u64 v[134:135], v[132:133], 0, s[8:9]
	s_mov_b64 s[8:9], 0x2800
	global_store_dwordx4 v[136:137], v[48:51], off offset:1024
	global_store_dwordx4 v[134:135], v[44:47], off offset:16
	v_lshl_add_u64 v[134:135], v[132:133], 0, s[8:9]
	s_mov_b64 s[8:9], 0x2c00
	global_store_dwordx4 v[136:137], v[30:33], off offset:2048
	global_store_dwordx4 v[134:135], v[26:29], off offset:16
	v_lshl_add_u64 v[132:133], v[132:133], 0, s[8:9]
	global_store_dwordx4 v[136:137], v[14:17], off offset:3072
	global_store_dwordx4 v[132:133], v[10:13], off offset:16

.LBB0_123:
	s_andn2_b64 vcc, exec, s[6:7]
	s_cbranch_vccnz .LBB0_125
	v_mul_f32_e32 v134, 0x3c800000, v128
	v_mul_f32_e32 v134, 0xbfb8aa3b, v134
	v_mul_f32_e32 v139, 0x3c800000, v129
	v_exp_f32_e32 v134, v134
	v_mul_f32_e32 v139, 0xbfb8aa3b, v139
	v_mul_f32_e32 v156, 0x3c800000, v130
	v_mul_f32_e32 v135, 0x3c800000, v124
	v_exp_f32_e32 v139, v139
	v_mul_f32_e32 v156, 0xbfb8aa3b, v156
	v_mul_f32_e32 v158, 0x3c800000, v131
	v_mul_f32_e32 v135, 0xbfb8aa3b, v135
	v_mul_f32_e32 v155, 0x3c800000, v125
	v_exp_f32_e32 v156, v156
	v_mul_f32_e32 v158, 0xbfb8aa3b, v158
	v_exp_f32_e32 v135, v135
	v_mul_f32_e32 v155, 0xbfb8aa3b, v155
	v_mul_f32_e32 v157, 0x3c800000, v126
	v_exp_f32_e32 v158, v158
	v_add_f32_e32 v134, 1.0, v134
	v_exp_f32_e32 v155, v155
	v_mul_f32_e32 v157, 0xbfb8aa3b, v157
	v_mul_f32_e32 v159, 0x3c800000, v127
	v_rcp_f32_e32 v137, v134
	v_add_f32_e32 v139, 1.0, v139
	v_exp_f32_e32 v157, v157
	v_mul_f32_e32 v159, 0xbfb8aa3b, v159
	v_rcp_f32_e32 v139, v139
	v_add_f32_e32 v156, 1.0, v156
	v_exp_f32_e32 v159, v159
	v_add_f32_e32 v134, 1.0, v135
	v_rcp_f32_e32 v156, v156
	v_add_f32_e32 v158, 1.0, v158
	v_rcp_f32_e32 v138, v134
	s_mov_b32 s9, 0x437f0000
	v_add_f32_e32 v155, 1.0, v155
	v_rcp_f32_e32 v158, v158
	v_fma_f32 v137, v137, s9, 0.5
	v_rcp_f32_e32 v155, v155
	v_add_f32_e32 v157, 1.0, v157
	v_or_b32_e32 v132, 0xffffb800, v163
	v_max_f32_e32 v137, 1.0, v137
	v_fma_f32 v139, v139, s9, 0.5
	v_rcp_f32_e32 v157, v157
	v_add_f32_e32 v159, 1.0, v159
	v_lshl_add_u32 v132, s76, 8, v132
	v_max_f32_e32 v139, 1.0, v139
	v_fma_f32 v156, v156, s9, 0.5
	v_rcp_f32_e32 v159, v159
	v_cvt_pk_u8_f32 v137, v137, 0, 0
	v_fma_f32 v138, v138, s9, 0.5
	v_bfe_u32 v133, v132, 3, 1
	v_max_f32_e32 v156, 1.0, v156
	v_fma_f32 v158, v158, s9, 0.5
	v_cvt_pk_u8_f32 v137, v139, 1, v137
	v_lshl_or_b32 v136, v133, 4, v154
	v_lshlrev_b32_e32 v133, 3, v133
	v_max_f32_e32 v138, 1.0, v138
	v_fma_f32 v155, v155, s9, 0.5
	v_max_f32_e32 v158, 1.0, v158
	v_cvt_pk_u8_f32 v137, v156, 2, v137
	v_sub_u32_e32 v132, v132, v133
	v_max_f32_e32 v155, 1.0, v155
	v_fma_f32 v157, v157, s9, 0.5
	v_cvt_pk_u8_f32 v156, v158, 3, v137
	v_cvt_pk_u8_f32 v137, v138, 0, 0
	v_ashrrev_i32_e32 v133, 31, v132
	v_max_f32_e32 v157, 1.0, v157
	v_fma_f32 v159, v159, s9, 0.5
	v_cvt_pk_u8_f32 v137, v155, 1, v137
	v_lshl_add_u64 v[132:133], s[58:59], 0, v[132:133]
	s_movk_i32 s8, 0x3000
	v_max_f32_e32 v159, 1.0, v159
	v_cvt_pk_u8_f32 v137, v157, 2, v137
	v_mad_i64_i32 v[134:135], s[6:7], v136, s8, v[132:133]
	v_cvt_pk_u8_f32 v157, v159, 3, v137
	v_mul_f32_e32 v137, 0x3c800000, v112
	v_mul_f32_e32 v137, 0xbfb8aa3b, v137
	v_mul_f32_e32 v139, 0x3c800000, v113
	v_exp_f32_e32 v137, v137
	v_mul_f32_e32 v139, 0xbfb8aa3b, v139
	v_mul_f32_e32 v158, 0x3c800000, v114
	v_mul_f32_e32 v138, 0x3c800000, v108
	v_exp_f32_e32 v139, v139
	v_mul_f32_e32 v158, 0xbfb8aa3b, v158
	v_mul_f32_e32 v160, 0x3c800000, v115
	v_mul_f32_e32 v138, 0xbfb8aa3b, v138
	v_mul_f32_e32 v155, 0x3c800000, v109
	v_exp_f32_e32 v158, v158
	v_mul_f32_e32 v160, 0xbfb8aa3b, v160
	v_exp_f32_e32 v138, v138
	v_mul_f32_e32 v155, 0xbfb8aa3b, v155
	v_mul_f32_e32 v159, 0x3c800000, v110
	v_exp_f32_e32 v160, v160
	v_add_f32_e32 v137, 1.0, v137
	v_exp_f32_e32 v155, v155
	v_mul_f32_e32 v159, 0xbfb8aa3b, v159
	v_mul_f32_e32 v161, 0x3c800000, v111
	v_rcp_f32_e32 v137, v137
	v_add_f32_e32 v139, 1.0, v139
	v_exp_f32_e32 v159, v159
	v_mul_f32_e32 v161, 0xbfb8aa3b, v161
	v_rcp_f32_e32 v139, v139
	v_add_f32_e32 v158, 1.0, v158
	v_exp_f32_e32 v161, v161
	v_add_f32_e32 v138, 1.0, v138
	v_rcp_f32_e32 v158, v158
	v_add_f32_e32 v160, 1.0, v160
	v_rcp_f32_e32 v138, v138
	v_add_f32_e32 v155, 1.0, v155
	v_rcp_f32_e32 v160, v160
	v_fma_f32 v137, v137, s9, 0.5
	v_rcp_f32_e32 v155, v155
	v_add_f32_e32 v159, 1.0, v159
	v_max_f32_e32 v137, 1.0, v137
	v_fma_f32 v139, v139, s9, 0.5
	v_rcp_f32_e32 v159, v159
	v_add_f32_e32 v161, 1.0, v161
	v_max_f32_e32 v139, 1.0, v139
	v_fma_f32 v158, v158, s9, 0.5
	v_rcp_f32_e32 v161, v161
	v_cvt_pk_u8_f32 v137, v137, 0, 0
	v_fma_f32 v138, v138, s9, 0.5
	v_max_f32_e32 v158, 1.0, v158
	v_fma_f32 v160, v160, s9, 0.5
	v_cvt_pk_u8_f32 v137, v139, 1, v137
	v_max_f32_e32 v138, 1.0, v138
	v_fma_f32 v155, v155, s9, 0.5
	v_max_f32_e32 v160, 1.0, v160
	v_cvt_pk_u8_f32 v137, v158, 2, v137
	v_max_f32_e32 v155, 1.0, v155
	v_fma_f32 v159, v159, s9, 0.5
	v_cvt_pk_u8_f32 v158, v160, 3, v137
	v_cvt_pk_u8_f32 v137, v138, 0, 0
	v_max_f32_e32 v159, 1.0, v159
	v_fma_f32 v161, v161, s9, 0.5
	v_cvt_pk_u8_f32 v137, v155, 1, v137
	v_max_f32_e32 v161, 1.0, v161
	v_cvt_pk_u8_f32 v137, v159, 2, v137
	v_cvt_pk_u8_f32 v159, v161, 3, v137
	v_mul_f32_e32 v137, 0x3c800000, v120
	v_permlane16_swap_b32_e32 v156, v158
	v_mul_f32_e32 v137, 0xbfb8aa3b, v137
	v_permlane16_swap_b32_e32 v157, v159
	v_mul_f32_e32 v139, 0x3c800000, v121
	v_exp_f32_e32 v137, v137
	global_store_dwordx4 v[134:135], v[156:159], off
	v_mul_f32_e32 v139, 0xbfb8aa3b, v139
	v_mul_f32_e32 v138, 0x3c800000, v116
	v_mul_f32_e32 v156, 0x3c800000, v122
	v_exp_f32_e32 v139, v139
	v_mul_f32_e32 v156, 0xbfb8aa3b, v156
	v_mul_f32_e32 v158, 0x3c800000, v123
	v_mul_f32_e32 v138, 0xbfb8aa3b, v138
	v_mul_f32_e32 v155, 0x3c800000, v117
	v_exp_f32_e32 v156, v156
	v_mul_f32_e32 v158, 0xbfb8aa3b, v158
	v_exp_f32_e32 v138, v138
	v_mul_f32_e32 v155, 0xbfb8aa3b, v155
	v_mul_f32_e32 v157, 0x3c800000, v118
	v_exp_f32_e32 v158, v158
	v_add_f32_e32 v137, 1.0, v137
	v_exp_f32_e32 v155, v155
	v_mul_f32_e32 v157, 0xbfb8aa3b, v157
	v_mul_f32_e32 v159, 0x3c800000, v119
	v_rcp_f32_e32 v137, v137
	v_add_f32_e32 v139, 1.0, v139
	v_exp_f32_e32 v157, v157
	v_mul_f32_e32 v159, 0xbfb8aa3b, v159
	v_rcp_f32_e32 v139, v139
	v_add_f32_e32 v156, 1.0, v156
	v_exp_f32_e32 v159, v159
	v_add_f32_e32 v138, 1.0, v138
	v_rcp_f32_e32 v156, v156
	v_add_f32_e32 v158, 1.0, v158
	v_rcp_f32_e32 v138, v138
	v_add_f32_e32 v155, 1.0, v155
	v_rcp_f32_e32 v158, v158
	v_fma_f32 v137, v137, s9, 0.5
	v_rcp_f32_e32 v155, v155
	v_add_f32_e32 v157, 1.0, v157
	v_max_f32_e32 v137, 1.0, v137
	v_fma_f32 v139, v139, s9, 0.5
	v_rcp_f32_e32 v157, v157
	v_add_f32_e32 v159, 1.0, v159
	v_max_f32_e32 v139, 1.0, v139
	v_fma_f32 v156, v156, s9, 0.5
	v_rcp_f32_e32 v159, v159
	v_cvt_pk_u8_f32 v137, v137, 0, 0
	v_fma_f32 v138, v138, s9, 0.5
	v_max_f32_e32 v156, 1.0, v156
	v_fma_f32 v158, v158, s9, 0.5
	v_cvt_pk_u8_f32 v137, v139, 1, v137
	v_max_f32_e32 v138, 1.0, v138
	v_fma_f32 v155, v155, s9, 0.5
	v_max_f32_e32 v158, 1.0, v158
	v_cvt_pk_u8_f32 v137, v156, 2, v137
	v_max_f32_e32 v155, 1.0, v155
	v_fma_f32 v157, v157, s9, 0.5
	v_cvt_pk_u8_f32 v156, v158, 3, v137
	v_cvt_pk_u8_f32 v137, v138, 0, 0
	v_max_f32_e32 v157, 1.0, v157
	v_fma_f32 v159, v159, s9, 0.5
	v_cvt_pk_u8_f32 v137, v155, 1, v137
	v_max_f32_e32 v159, 1.0, v159
	v_cvt_pk_u8_f32 v137, v157, 2, v137
	v_cvt_pk_u8_f32 v157, v159, 3, v137
	v_mul_f32_e32 v137, 0x3c800000, v104
	v_mul_f32_e32 v137, 0xbfb8aa3b, v137
	v_mul_f32_e32 v139, 0x3c800000, v105
	v_exp_f32_e32 v137, v137
	v_mul_f32_e32 v139, 0xbfb8aa3b, v139
	v_mul_f32_e32 v158, 0x3c800000, v106
	v_mul_f32_e32 v138, 0x3c800000, v100
	v_exp_f32_e32 v139, v139
	v_mul_f32_e32 v158, 0xbfb8aa3b, v158
	v_mul_f32_e32 v160, 0x3c800000, v107
	v_mul_f32_e32 v138, 0xbfb8aa3b, v138
	v_mul_f32_e32 v155, 0x3c800000, v101
	v_exp_f32_e32 v158, v158
	v_mul_f32_e32 v160, 0xbfb8aa3b, v160
	v_exp_f32_e32 v138, v138
	v_mul_f32_e32 v155, 0xbfb8aa3b, v155
	v_mul_f32_e32 v159, 0x3c800000, v102
	v_exp_f32_e32 v160, v160
	v_add_f32_e32 v137, 1.0, v137
	v_exp_f32_e32 v155, v155
	v_mul_f32_e32 v159, 0xbfb8aa3b, v159
	v_mul_f32_e32 v161, 0x3c800000, v103
	v_rcp_f32_e32 v137, v137
	v_add_f32_e32 v139, 1.0, v139
	v_exp_f32_e32 v159, v159
	v_mul_f32_e32 v161, 0xbfb8aa3b, v161
	v_rcp_f32_e32 v139, v139
	v_add_f32_e32 v158, 1.0, v158
	v_exp_f32_e32 v161, v161
	v_add_f32_e32 v138, 1.0, v138
	v_rcp_f32_e32 v158, v158
	v_add_f32_e32 v160, 1.0, v160
	v_rcp_f32_e32 v138, v138
	v_add_f32_e32 v155, 1.0, v155
	v_rcp_f32_e32 v160, v160
	v_fma_f32 v137, v137, s9, 0.5
	v_rcp_f32_e32 v155, v155
	v_add_f32_e32 v159, 1.0, v159
	v_max_f32_e32 v137, 1.0, v137
	v_fma_f32 v139, v139, s9, 0.5
	v_rcp_f32_e32 v159, v159
	v_add_f32_e32 v161, 1.0, v161
	v_max_f32_e32 v139, 1.0, v139
	v_fma_f32 v158, v158, s9, 0.5
	v_rcp_f32_e32 v161, v161
	v_cvt_pk_u8_f32 v137, v137, 0, 0
	v_fma_f32 v138, v138, s9, 0.5
	v_max_f32_e32 v158, 1.0, v158
	v_fma_f32 v160, v160, s9, 0.5
	v_cvt_pk_u8_f32 v137, v139, 1, v137
	v_max_f32_e32 v138, 1.0, v138
	v_fma_f32 v155, v155, s9, 0.5
	v_max_f32_e32 v160, 1.0, v160
	v_cvt_pk_u8_f32 v137, v158, 2, v137
	v_max_f32_e32 v155, 1.0, v155
	v_fma_f32 v159, v159, s9, 0.5
	v_cvt_pk_u8_f32 v158, v160, 3, v137
	v_cvt_pk_u8_f32 v137, v138, 0, 0
	v_max_f32_e32 v159, 1.0, v159
	v_fma_f32 v161, v161, s9, 0.5
	v_cvt_pk_u8_f32 v137, v155, 1, v137
	v_max_f32_e32 v161, 1.0, v161
	v_cvt_pk_u8_f32 v137, v159, 2, v137
	v_cvt_pk_u8_f32 v159, v161, 3, v137
	v_permlane16_swap_b32_e32 v156, v158
	s_nop 0
	v_permlane16_swap_b32_e32 v157, v159
	global_store_dwordx4 v[134:135], v[156:159], off offset:128
	v_mul_f32_e32 v134, 0x3c800000, v96
	v_mul_f32_e32 v134, 0xbfb8aa3b, v134
	v_mul_f32_e32 v135, 0x3c800000, v92
	v_exp_f32_e32 v134, v134
	v_mul_f32_e32 v135, 0xbfb8aa3b, v135
	v_exp_f32_e32 v135, v135
	v_or_b32_e32 v137, 32, v136
	v_add_f32_e32 v134, 1.0, v134
	v_rcp_f32_e32 v138, v134
	v_add_f32_e32 v134, 1.0, v135
	v_rcp_f32_e32 v139, v134
	v_mad_i64_i32 v[134:135], s[6:7], v137, s8, v[132:133]
	v_fma_f32 v137, v138, s9, 0.5
	v_fma_f32 v138, v139, s9, 0.5
	v_mul_f32_e32 v139, 0x3c800000, v97
	v_mul_f32_e32 v139, 0xbfb8aa3b, v139
	v_mul_f32_e32 v156, 0x3c800000, v98
	v_exp_f32_e32 v139, v139
	v_mul_f32_e32 v156, 0xbfb8aa3b, v156
	v_mul_f32_e32 v158, 0x3c800000, v99
	v_mul_f32_e32 v155, 0x3c800000, v93
	v_exp_f32_e32 v156, v156
	v_mul_f32_e32 v158, 0xbfb8aa3b, v158
	v_mul_f32_e32 v155, 0xbfb8aa3b, v155
	v_mul_f32_e32 v157, 0x3c800000, v94
	v_exp_f32_e32 v158, v158
	v_exp_f32_e32 v155, v155
	v_mul_f32_e32 v157, 0xbfb8aa3b, v157
	v_mul_f32_e32 v159, 0x3c800000, v95
	v_add_f32_e32 v139, 1.0, v139
	v_exp_f32_e32 v157, v157
	v_mul_f32_e32 v159, 0xbfb8aa3b, v159
	v_rcp_f32_e32 v139, v139
	v_add_f32_e32 v156, 1.0, v156
	v_exp_f32_e32 v159, v159
	v_rcp_f32_e32 v156, v156
	v_add_f32_e32 v158, 1.0, v158
	v_add_f32_e32 v155, 1.0, v155
	v_rcp_f32_e32 v158, v158
	v_rcp_f32_e32 v155, v155
	v_add_f32_e32 v157, 1.0, v157
	v_max_f32_e32 v137, 1.0, v137
	v_fma_f32 v139, v139, s9, 0.5
	v_rcp_f32_e32 v157, v157
	v_add_f32_e32 v159, 1.0, v159
	v_max_f32_e32 v139, 1.0, v139
	v_fma_f32 v156, v156, s9, 0.5
	v_rcp_f32_e32 v159, v159
	v_cvt_pk_u8_f32 v137, v137, 0, 0
	v_max_f32_e32 v156, 1.0, v156
	v_fma_f32 v158, v158, s9, 0.5
	v_cvt_pk_u8_f32 v137, v139, 1, v137
	v_max_f32_e32 v138, 1.0, v138
	v_fma_f32 v155, v155, s9, 0.5
	v_max_f32_e32 v158, 1.0, v158
	v_cvt_pk_u8_f32 v137, v156, 2, v137
	v_max_f32_e32 v155, 1.0, v155
	v_fma_f32 v157, v157, s9, 0.5
	v_cvt_pk_u8_f32 v156, v158, 3, v137
	v_cvt_pk_u8_f32 v137, v138, 0, 0
	v_max_f32_e32 v157, 1.0, v157
	v_fma_f32 v159, v159, s9, 0.5
	v_cvt_pk_u8_f32 v137, v155, 1, v137
	v_max_f32_e32 v159, 1.0, v159
	v_cvt_pk_u8_f32 v137, v157, 2, v137
	v_cvt_pk_u8_f32 v157, v159, 3, v137
	v_mul_f32_e32 v137, 0x3c800000, v80
	v_mul_f32_e32 v137, 0xbfb8aa3b, v137
	v_mul_f32_e32 v139, 0x3c800000, v81
	v_exp_f32_e32 v137, v137
	v_mul_f32_e32 v139, 0xbfb8aa3b, v139
	v_mul_f32_e32 v158, 0x3c800000, v82
	v_mul_f32_e32 v138, 0x3c800000, v76
	v_exp_f32_e32 v139, v139
	v_mul_f32_e32 v158, 0xbfb8aa3b, v158
	v_mul_f32_e32 v160, 0x3c800000, v83
	v_mul_f32_e32 v138, 0xbfb8aa3b, v138
	v_mul_f32_e32 v155, 0x3c800000, v77
	v_exp_f32_e32 v158, v158
	v_mul_f32_e32 v160, 0xbfb8aa3b, v160
	v_exp_f32_e32 v138, v138
	v_mul_f32_e32 v155, 0xbfb8aa3b, v155
	v_mul_f32_e32 v159, 0x3c800000, v78
	v_exp_f32_e32 v160, v160
	v_add_f32_e32 v137, 1.0, v137
	v_exp_f32_e32 v155, v155
	v_mul_f32_e32 v159, 0xbfb8aa3b, v159
	v_mul_f32_e32 v161, 0x3c800000, v79
	v_rcp_f32_e32 v137, v137
	v_add_f32_e32 v139, 1.0, v139
	v_exp_f32_e32 v159, v159
	v_mul_f32_e32 v161, 0xbfb8aa3b, v161
	v_rcp_f32_e32 v139, v139
	v_add_f32_e32 v158, 1.0, v158
	v_exp_f32_e32 v161, v161
	v_add_f32_e32 v138, 1.0, v138
	v_rcp_f32_e32 v158, v158
	v_add_f32_e32 v160, 1.0, v160
	v_rcp_f32_e32 v138, v138
	v_add_f32_e32 v155, 1.0, v155
	v_rcp_f32_e32 v160, v160
	v_fma_f32 v137, v137, s9, 0.5
	v_rcp_f32_e32 v155, v155
	v_add_f32_e32 v159, 1.0, v159
	v_max_f32_e32 v137, 1.0, v137
	v_fma_f32 v139, v139, s9, 0.5
	v_rcp_f32_e32 v159, v159
	v_add_f32_e32 v161, 1.0, v161
	v_max_f32_e32 v139, 1.0, v139
	v_fma_f32 v158, v158, s9, 0.5
	v_rcp_f32_e32 v161, v161
	v_cvt_pk_u8_f32 v137, v137, 0, 0
	v_fma_f32 v138, v138, s9, 0.5
	v_max_f32_e32 v158, 1.0, v158
	v_fma_f32 v160, v160, s9, 0.5
	v_cvt_pk_u8_f32 v137, v139, 1, v137
	v_max_f32_e32 v138, 1.0, v138
	v_fma_f32 v155, v155, s9, 0.5
	v_max_f32_e32 v160, 1.0, v160
	v_cvt_pk_u8_f32 v137, v158, 2, v137
	v_max_f32_e32 v155, 1.0, v155
	v_fma_f32 v159, v159, s9, 0.5
	v_cvt_pk_u8_f32 v158, v160, 3, v137
	v_cvt_pk_u8_f32 v137, v138, 0, 0
	v_max_f32_e32 v159, 1.0, v159
	v_fma_f32 v161, v161, s9, 0.5
	v_cvt_pk_u8_f32 v137, v155, 1, v137
	v_max_f32_e32 v161, 1.0, v161
	v_cvt_pk_u8_f32 v137, v159, 2, v137
	v_cvt_pk_u8_f32 v159, v161, 3, v137
	v_mul_f32_e32 v137, 0x3c800000, v88
	v_permlane16_swap_b32_e32 v156, v158
	v_mul_f32_e32 v137, 0xbfb8aa3b, v137
	v_permlane16_swap_b32_e32 v157, v159
	v_mul_f32_e32 v139, 0x3c800000, v89
	v_exp_f32_e32 v137, v137
	global_store_dwordx4 v[134:135], v[156:159], off
	v_mul_f32_e32 v139, 0xbfb8aa3b, v139
	v_mul_f32_e32 v138, 0x3c800000, v84
	v_mul_f32_e32 v156, 0x3c800000, v90
	v_exp_f32_e32 v139, v139
	v_mul_f32_e32 v156, 0xbfb8aa3b, v156
	v_mul_f32_e32 v158, 0x3c800000, v91
	v_mul_f32_e32 v138, 0xbfb8aa3b, v138
	v_mul_f32_e32 v155, 0x3c800000, v85
	v_exp_f32_e32 v156, v156
	v_mul_f32_e32 v158, 0xbfb8aa3b, v158
	v_exp_f32_e32 v138, v138
	v_mul_f32_e32 v155, 0xbfb8aa3b, v155
	v_mul_f32_e32 v157, 0x3c800000, v86
	v_exp_f32_e32 v158, v158
	v_add_f32_e32 v137, 1.0, v137
	v_exp_f32_e32 v155, v155
	v_mul_f32_e32 v157, 0xbfb8aa3b, v157
	v_mul_f32_e32 v159, 0x3c800000, v87
	v_rcp_f32_e32 v137, v137
	v_add_f32_e32 v139, 1.0, v139
	v_exp_f32_e32 v157, v157
	v_mul_f32_e32 v159, 0xbfb8aa3b, v159
	v_rcp_f32_e32 v139, v139
	v_add_f32_e32 v156, 1.0, v156
	v_exp_f32_e32 v159, v159
	v_add_f32_e32 v138, 1.0, v138
	v_rcp_f32_e32 v156, v156
	v_add_f32_e32 v158, 1.0, v158
	v_rcp_f32_e32 v138, v138
	v_add_f32_e32 v155, 1.0, v155
	v_rcp_f32_e32 v158, v158
	v_fma_f32 v137, v137, s9, 0.5
	v_rcp_f32_e32 v155, v155
	v_add_f32_e32 v157, 1.0, v157
	v_max_f32_e32 v137, 1.0, v137
	v_fma_f32 v139, v139, s9, 0.5
	v_rcp_f32_e32 v157, v157
	v_add_f32_e32 v159, 1.0, v159
	v_max_f32_e32 v139, 1.0, v139
	v_fma_f32 v156, v156, s9, 0.5
	v_rcp_f32_e32 v159, v159
	v_cvt_pk_u8_f32 v137, v137, 0, 0
	v_fma_f32 v138, v138, s9, 0.5
	v_max_f32_e32 v156, 1.0, v156
	v_fma_f32 v158, v158, s9, 0.5
	v_cvt_pk_u8_f32 v137, v139, 1, v137
	v_max_f32_e32 v138, 1.0, v138
	v_fma_f32 v155, v155, s9, 0.5
	v_max_f32_e32 v158, 1.0, v158
	v_cvt_pk_u8_f32 v137, v156, 2, v137
	v_max_f32_e32 v155, 1.0, v155
	v_fma_f32 v157, v157, s9, 0.5
	v_cvt_pk_u8_f32 v156, v158, 3, v137
	v_cvt_pk_u8_f32 v137, v138, 0, 0
	v_max_f32_e32 v157, 1.0, v157
	v_fma_f32 v159, v159, s9, 0.5
	v_cvt_pk_u8_f32 v137, v155, 1, v137
	v_max_f32_e32 v159, 1.0, v159
	v_cvt_pk_u8_f32 v137, v157, 2, v137
	v_cvt_pk_u8_f32 v157, v159, 3, v137
	v_mul_f32_e32 v137, 0x3c800000, v72
	v_mul_f32_e32 v137, 0xbfb8aa3b, v137
	v_mul_f32_e32 v139, 0x3c800000, v73
	v_exp_f32_e32 v137, v137
	v_mul_f32_e32 v139, 0xbfb8aa3b, v139
	v_mul_f32_e32 v158, 0x3c800000, v74
	v_mul_f32_e32 v138, 0x3c800000, v68
	v_exp_f32_e32 v139, v139
	v_mul_f32_e32 v158, 0xbfb8aa3b, v158
	v_mul_f32_e32 v160, 0x3c800000, v75
	v_mul_f32_e32 v138, 0xbfb8aa3b, v138
	v_mul_f32_e32 v155, 0x3c800000, v69
	v_exp_f32_e32 v158, v158
	v_mul_f32_e32 v160, 0xbfb8aa3b, v160
	v_exp_f32_e32 v138, v138
	v_mul_f32_e32 v155, 0xbfb8aa3b, v155
	v_mul_f32_e32 v159, 0x3c800000, v70
	v_exp_f32_e32 v160, v160
	v_add_f32_e32 v137, 1.0, v137
	v_exp_f32_e32 v155, v155
	v_mul_f32_e32 v159, 0xbfb8aa3b, v159
	v_mul_f32_e32 v161, 0x3c800000, v71
	v_rcp_f32_e32 v137, v137
	v_add_f32_e32 v139, 1.0, v139
	v_exp_f32_e32 v159, v159
	v_mul_f32_e32 v161, 0xbfb8aa3b, v161
	v_rcp_f32_e32 v139, v139
	v_add_f32_e32 v158, 1.0, v158
	v_exp_f32_e32 v161, v161
	v_add_f32_e32 v138, 1.0, v138
	v_rcp_f32_e32 v158, v158
	v_add_f32_e32 v160, 1.0, v160
	v_rcp_f32_e32 v138, v138
	v_add_f32_e32 v155, 1.0, v155
	v_rcp_f32_e32 v160, v160
	v_fma_f32 v137, v137, s9, 0.5
	v_rcp_f32_e32 v155, v155
	v_add_f32_e32 v159, 1.0, v159
	v_max_f32_e32 v137, 1.0, v137
	v_fma_f32 v139, v139, s9, 0.5
	v_rcp_f32_e32 v159, v159
	v_add_f32_e32 v161, 1.0, v161
	v_max_f32_e32 v139, 1.0, v139
	v_fma_f32 v158, v158, s9, 0.5
	v_rcp_f32_e32 v161, v161
	v_cvt_pk_u8_f32 v137, v137, 0, 0
	v_fma_f32 v138, v138, s9, 0.5
	v_max_f32_e32 v158, 1.0, v158
	v_fma_f32 v160, v160, s9, 0.5
	v_cvt_pk_u8_f32 v137, v139, 1, v137
	v_max_f32_e32 v138, 1.0, v138
	v_fma_f32 v155, v155, s9, 0.5
	v_max_f32_e32 v160, 1.0, v160
	v_cvt_pk_u8_f32 v137, v158, 2, v137
	v_max_f32_e32 v155, 1.0, v155
	v_fma_f32 v159, v159, s9, 0.5
	v_cvt_pk_u8_f32 v158, v160, 3, v137
	v_cvt_pk_u8_f32 v137, v138, 0, 0
	v_max_f32_e32 v159, 1.0, v159
	v_fma_f32 v161, v161, s9, 0.5
	v_cvt_pk_u8_f32 v137, v155, 1, v137
	v_max_f32_e32 v161, 1.0, v161
	v_cvt_pk_u8_f32 v137, v159, 2, v137
	v_cvt_pk_u8_f32 v159, v161, 3, v137
	v_permlane16_swap_b32_e32 v156, v158
	s_nop 0
	v_permlane16_swap_b32_e32 v157, v159
	global_store_dwordx4 v[134:135], v[156:159], off offset:128
	v_mul_f32_e32 v134, 0x3c800000, v64
	v_mul_f32_e32 v134, 0xbfb8aa3b, v134
	v_mul_f32_e32 v135, 0x3c800000, v60
	v_exp_f32_e32 v134, v134
	v_mul_f32_e32 v135, 0xbfb8aa3b, v135
	v_exp_f32_e32 v135, v135
	v_add_u32_e32 v137, 0x80, v136
	v_add_f32_e32 v134, 1.0, v134
	v_rcp_f32_e32 v138, v134
	v_add_f32_e32 v134, 1.0, v135
	v_rcp_f32_e32 v139, v134
	v_mad_i64_i32 v[134:135], s[6:7], v137, s8, v[132:133]
	v_fma_f32 v137, v138, s9, 0.5
	v_fma_f32 v138, v139, s9, 0.5
	v_mul_f32_e32 v139, 0x3c800000, v65
	v_mul_f32_e32 v139, 0xbfb8aa3b, v139
	v_mul_f32_e32 v156, 0x3c800000, v66
	v_exp_f32_e32 v139, v139
	v_mul_f32_e32 v156, 0xbfb8aa3b, v156
	v_mul_f32_e32 v158, 0x3c800000, v67
	v_mul_f32_e32 v155, 0x3c800000, v61
	v_exp_f32_e32 v156, v156
	v_mul_f32_e32 v158, 0xbfb8aa3b, v158
	v_mul_f32_e32 v155, 0xbfb8aa3b, v155
	v_mul_f32_e32 v157, 0x3c800000, v62
	v_exp_f32_e32 v158, v158
	v_exp_f32_e32 v155, v155
	v_mul_f32_e32 v157, 0xbfb8aa3b, v157
	v_mul_f32_e32 v159, 0x3c800000, v63
	v_add_f32_e32 v139, 1.0, v139
	v_exp_f32_e32 v157, v157
	v_mul_f32_e32 v159, 0xbfb8aa3b, v159
	v_rcp_f32_e32 v139, v139
	v_add_f32_e32 v156, 1.0, v156
	v_exp_f32_e32 v159, v159
	v_rcp_f32_e32 v156, v156
	v_add_f32_e32 v158, 1.0, v158
	v_add_f32_e32 v155, 1.0, v155
	v_rcp_f32_e32 v158, v158
	v_rcp_f32_e32 v155, v155
	v_add_f32_e32 v157, 1.0, v157
	v_max_f32_e32 v137, 1.0, v137
	v_fma_f32 v139, v139, s9, 0.5
	v_rcp_f32_e32 v157, v157
	v_add_f32_e32 v159, 1.0, v159
	v_max_f32_e32 v139, 1.0, v139
	v_fma_f32 v156, v156, s9, 0.5
	v_rcp_f32_e32 v159, v159
	v_cvt_pk_u8_f32 v137, v137, 0, 0
	v_max_f32_e32 v156, 1.0, v156
	v_fma_f32 v158, v158, s9, 0.5
	v_cvt_pk_u8_f32 v137, v139, 1, v137
	v_max_f32_e32 v138, 1.0, v138
	v_fma_f32 v155, v155, s9, 0.5
	v_max_f32_e32 v158, 1.0, v158
	v_cvt_pk_u8_f32 v137, v156, 2, v137
	v_max_f32_e32 v155, 1.0, v155
	v_fma_f32 v157, v157, s9, 0.5
	v_cvt_pk_u8_f32 v156, v158, 3, v137
	v_cvt_pk_u8_f32 v137, v138, 0, 0
	v_max_f32_e32 v157, 1.0, v157
	v_fma_f32 v159, v159, s9, 0.5
	v_cvt_pk_u8_f32 v137, v155, 1, v137
	v_max_f32_e32 v159, 1.0, v159
	v_cvt_pk_u8_f32 v137, v157, 2, v137
	v_cvt_pk_u8_f32 v157, v159, 3, v137
	v_mul_f32_e32 v137, 0x3c800000, v48
	v_mul_f32_e32 v137, 0xbfb8aa3b, v137
	v_mul_f32_e32 v139, 0x3c800000, v49
	v_exp_f32_e32 v137, v137
	v_mul_f32_e32 v139, 0xbfb8aa3b, v139
	v_mul_f32_e32 v158, 0x3c800000, v50
	v_mul_f32_e32 v138, 0x3c800000, v44
	v_exp_f32_e32 v139, v139
	v_mul_f32_e32 v158, 0xbfb8aa3b, v158
	v_mul_f32_e32 v160, 0x3c800000, v51
	v_mul_f32_e32 v138, 0xbfb8aa3b, v138
	v_mul_f32_e32 v155, 0x3c800000, v45
	v_exp_f32_e32 v158, v158
	v_mul_f32_e32 v160, 0xbfb8aa3b, v160
	v_exp_f32_e32 v138, v138
	v_mul_f32_e32 v155, 0xbfb8aa3b, v155
	v_mul_f32_e32 v159, 0x3c800000, v46
	v_exp_f32_e32 v160, v160
	v_add_f32_e32 v137, 1.0, v137
	v_exp_f32_e32 v155, v155
	v_mul_f32_e32 v159, 0xbfb8aa3b, v159
	v_mul_f32_e32 v161, 0x3c800000, v47
	v_rcp_f32_e32 v137, v137
	v_add_f32_e32 v139, 1.0, v139
	v_exp_f32_e32 v159, v159
	v_mul_f32_e32 v161, 0xbfb8aa3b, v161
	v_rcp_f32_e32 v139, v139
	v_add_f32_e32 v158, 1.0, v158
	v_exp_f32_e32 v161, v161
	v_add_f32_e32 v138, 1.0, v138
	v_rcp_f32_e32 v158, v158
	v_add_f32_e32 v160, 1.0, v160
	v_rcp_f32_e32 v138, v138
	v_add_f32_e32 v155, 1.0, v155
	v_rcp_f32_e32 v160, v160
	v_fma_f32 v137, v137, s9, 0.5
	v_rcp_f32_e32 v155, v155
	v_add_f32_e32 v159, 1.0, v159
	v_max_f32_e32 v137, 1.0, v137
	v_fma_f32 v139, v139, s9, 0.5
	v_rcp_f32_e32 v159, v159
	v_add_f32_e32 v161, 1.0, v161
	v_max_f32_e32 v139, 1.0, v139
	v_fma_f32 v158, v158, s9, 0.5
	v_rcp_f32_e32 v161, v161
	v_cvt_pk_u8_f32 v137, v137, 0, 0
	v_fma_f32 v138, v138, s9, 0.5
	v_max_f32_e32 v158, 1.0, v158
	v_fma_f32 v160, v160, s9, 0.5
	v_cvt_pk_u8_f32 v137, v139, 1, v137
	v_max_f32_e32 v138, 1.0, v138
	v_fma_f32 v155, v155, s9, 0.5
	v_max_f32_e32 v160, 1.0, v160
	v_cvt_pk_u8_f32 v137, v158, 2, v137
	v_max_f32_e32 v155, 1.0, v155
	v_fma_f32 v159, v159, s9, 0.5
	v_cvt_pk_u8_f32 v158, v160, 3, v137
	v_cvt_pk_u8_f32 v137, v138, 0, 0
	v_max_f32_e32 v159, 1.0, v159
	v_fma_f32 v161, v161, s9, 0.5
	v_cvt_pk_u8_f32 v137, v155, 1, v137
	v_max_f32_e32 v161, 1.0, v161
	v_cvt_pk_u8_f32 v137, v159, 2, v137
	v_cvt_pk_u8_f32 v159, v161, 3, v137
	v_mul_f32_e32 v137, 0x3c800000, v56
	v_permlane16_swap_b32_e32 v156, v158
	v_mul_f32_e32 v137, 0xbfb8aa3b, v137
	v_permlane16_swap_b32_e32 v157, v159
	v_mul_f32_e32 v139, 0x3c800000, v57
	v_exp_f32_e32 v137, v137
	global_store_dwordx4 v[134:135], v[156:159], off
	v_mul_f32_e32 v139, 0xbfb8aa3b, v139
	v_mul_f32_e32 v138, 0x3c800000, v52
	v_mul_f32_e32 v156, 0x3c800000, v58
	v_exp_f32_e32 v139, v139
	v_mul_f32_e32 v156, 0xbfb8aa3b, v156
	v_mul_f32_e32 v158, 0x3c800000, v59
	v_mul_f32_e32 v138, 0xbfb8aa3b, v138
	v_mul_f32_e32 v155, 0x3c800000, v53
	v_exp_f32_e32 v156, v156
	v_mul_f32_e32 v158, 0xbfb8aa3b, v158
	v_exp_f32_e32 v138, v138
	v_mul_f32_e32 v155, 0xbfb8aa3b, v155
	v_mul_f32_e32 v157, 0x3c800000, v54
	v_exp_f32_e32 v158, v158
	v_add_f32_e32 v137, 1.0, v137
	v_exp_f32_e32 v155, v155
	v_mul_f32_e32 v157, 0xbfb8aa3b, v157
	v_mul_f32_e32 v159, 0x3c800000, v55
	v_rcp_f32_e32 v137, v137
	v_add_f32_e32 v139, 1.0, v139
	v_exp_f32_e32 v157, v157
	v_mul_f32_e32 v159, 0xbfb8aa3b, v159
	v_rcp_f32_e32 v139, v139
	v_add_f32_e32 v156, 1.0, v156
	v_exp_f32_e32 v159, v159
	v_add_f32_e32 v138, 1.0, v138
	v_rcp_f32_e32 v156, v156
	v_add_f32_e32 v158, 1.0, v158
	v_rcp_f32_e32 v138, v138
	v_add_f32_e32 v155, 1.0, v155
	v_rcp_f32_e32 v158, v158
	v_fma_f32 v137, v137, s9, 0.5
	v_rcp_f32_e32 v155, v155
	v_add_f32_e32 v157, 1.0, v157
	v_max_f32_e32 v137, 1.0, v137
	v_fma_f32 v139, v139, s9, 0.5
	v_rcp_f32_e32 v157, v157
	v_add_f32_e32 v159, 1.0, v159
	v_max_f32_e32 v139, 1.0, v139
	v_fma_f32 v156, v156, s9, 0.5
	v_rcp_f32_e32 v159, v159
	v_cvt_pk_u8_f32 v137, v137, 0, 0
	v_fma_f32 v138, v138, s9, 0.5
	v_max_f32_e32 v156, 1.0, v156
	v_fma_f32 v158, v158, s9, 0.5
	v_cvt_pk_u8_f32 v137, v139, 1, v137
	v_max_f32_e32 v138, 1.0, v138
	v_fma_f32 v155, v155, s9, 0.5
	v_max_f32_e32 v158, 1.0, v158
	v_cvt_pk_u8_f32 v137, v156, 2, v137
	v_max_f32_e32 v155, 1.0, v155
	v_fma_f32 v157, v157, s9, 0.5
	v_cvt_pk_u8_f32 v156, v158, 3, v137
	v_cvt_pk_u8_f32 v137, v138, 0, 0
	v_max_f32_e32 v157, 1.0, v157
	v_fma_f32 v159, v159, s9, 0.5
	v_cvt_pk_u8_f32 v137, v155, 1, v137
	v_max_f32_e32 v159, 1.0, v159
	v_cvt_pk_u8_f32 v137, v157, 2, v137
	v_cvt_pk_u8_f32 v157, v159, 3, v137
	v_mul_f32_e32 v137, 0x3c800000, v40
	v_mul_f32_e32 v137, 0xbfb8aa3b, v137
	v_mul_f32_e32 v139, 0x3c800000, v41
	v_exp_f32_e32 v137, v137
	v_mul_f32_e32 v139, 0xbfb8aa3b, v139
	v_mul_f32_e32 v158, 0x3c800000, v42
	v_mul_f32_e32 v138, 0x3c800000, v36
	v_exp_f32_e32 v139, v139
	v_mul_f32_e32 v158, 0xbfb8aa3b, v158
	v_mul_f32_e32 v160, 0x3c800000, v43
	v_mul_f32_e32 v138, 0xbfb8aa3b, v138
	v_mul_f32_e32 v155, 0x3c800000, v37
	v_exp_f32_e32 v158, v158
	v_mul_f32_e32 v160, 0xbfb8aa3b, v160
	v_exp_f32_e32 v138, v138
	v_mul_f32_e32 v155, 0xbfb8aa3b, v155
	v_mul_f32_e32 v159, 0x3c800000, v38
	v_exp_f32_e32 v160, v160
	v_add_f32_e32 v137, 1.0, v137
	v_exp_f32_e32 v155, v155
	v_mul_f32_e32 v159, 0xbfb8aa3b, v159
	v_mul_f32_e32 v161, 0x3c800000, v39
	v_rcp_f32_e32 v137, v137
	v_add_f32_e32 v139, 1.0, v139
	v_exp_f32_e32 v159, v159
	v_mul_f32_e32 v161, 0xbfb8aa3b, v161
	v_rcp_f32_e32 v139, v139
	v_add_f32_e32 v158, 1.0, v158
	v_exp_f32_e32 v161, v161
	v_add_f32_e32 v138, 1.0, v138
	v_rcp_f32_e32 v158, v158
	v_add_f32_e32 v160, 1.0, v160
	v_rcp_f32_e32 v138, v138
	v_add_f32_e32 v155, 1.0, v155
	v_rcp_f32_e32 v160, v160
	v_fma_f32 v137, v137, s9, 0.5
	v_rcp_f32_e32 v155, v155
	v_add_f32_e32 v159, 1.0, v159
	v_max_f32_e32 v137, 1.0, v137
	v_fma_f32 v139, v139, s9, 0.5
	v_rcp_f32_e32 v159, v159
	v_add_f32_e32 v161, 1.0, v161
	v_max_f32_e32 v139, 1.0, v139
	v_fma_f32 v158, v158, s9, 0.5
	v_rcp_f32_e32 v161, v161
	v_cvt_pk_u8_f32 v137, v137, 0, 0
	v_fma_f32 v138, v138, s9, 0.5
	v_max_f32_e32 v158, 1.0, v158
	v_fma_f32 v160, v160, s9, 0.5
	v_cvt_pk_u8_f32 v137, v139, 1, v137
	v_max_f32_e32 v138, 1.0, v138
	v_fma_f32 v155, v155, s9, 0.5
	v_max_f32_e32 v160, 1.0, v160
	v_cvt_pk_u8_f32 v137, v158, 2, v137
	v_max_f32_e32 v155, 1.0, v155
	v_fma_f32 v159, v159, s9, 0.5
	v_cvt_pk_u8_f32 v158, v160, 3, v137
	v_cvt_pk_u8_f32 v137, v138, 0, 0
	v_max_f32_e32 v159, 1.0, v159
	v_fma_f32 v161, v161, s9, 0.5
	v_cvt_pk_u8_f32 v137, v155, 1, v137
	v_max_f32_e32 v161, 1.0, v161
	v_cvt_pk_u8_f32 v137, v159, 2, v137
	v_cvt_pk_u8_f32 v159, v161, 3, v137
	v_permlane16_swap_b32_e32 v156, v158
	s_nop 0
	v_permlane16_swap_b32_e32 v157, v159
	global_store_dwordx4 v[134:135], v[156:159], off offset:128
	v_mul_f32_e32 v134, 0x3c800000, v30
	v_mul_f32_e32 v135, 0x3c800000, v26
	v_add_u32_e32 v136, 0xa0, v136
	v_mul_f32_e32 v134, 0xbfb8aa3b, v134
	v_mul_f32_e32 v135, 0xbfb8aa3b, v135
	v_mad_i64_i32 v[132:133], s[6:7], v136, s8, v[132:133]
	v_mul_f32_e32 v136, 0x3c800000, v31
	v_mul_f32_e32 v137, 0x3c800000, v27
	v_exp_f32_e32 v134, v134
	v_exp_f32_e32 v135, v135
	v_mul_f32_e32 v136, 0xbfb8aa3b, v136
	v_mul_f32_e32 v137, 0xbfb8aa3b, v137
	v_mul_f32_e32 v138, 0x3c800000, v32
	v_mul_f32_e32 v139, 0x3c800000, v28
	v_exp_f32_e32 v136, v136
	v_exp_f32_e32 v137, v137
	v_mul_f32_e32 v138, 0xbfb8aa3b, v138
	v_mul_f32_e32 v139, 0xbfb8aa3b, v139
	v_mul_f32_e32 v155, 0x3c800000, v33
	v_mul_f32_e32 v156, 0x3c800000, v29
	v_exp_f32_e32 v138, v138
	v_exp_f32_e32 v139, v139
	v_mul_f32_e32 v155, 0xbfb8aa3b, v155
	v_mul_f32_e32 v156, 0xbfb8aa3b, v156
	v_exp_f32_e32 v155, v155
	v_exp_f32_e32 v156, v156
	v_add_f32_e32 v134, 1.0, v134
	v_add_f32_e32 v135, 1.0, v135
	v_rcp_f32_e32 v134, v134
	v_rcp_f32_e32 v135, v135
	v_add_f32_e32 v136, 1.0, v136
	v_add_f32_e32 v137, 1.0, v137
	v_rcp_f32_e32 v136, v136
	v_rcp_f32_e32 v137, v137
	v_add_f32_e32 v138, 1.0, v138
	v_add_f32_e32 v139, 1.0, v139
	v_rcp_f32_e32 v138, v138
	v_rcp_f32_e32 v139, v139
	v_add_f32_e32 v155, 1.0, v155
	v_add_f32_e32 v156, 1.0, v156
	v_rcp_f32_e32 v155, v155
	v_rcp_f32_e32 v156, v156
	v_fma_f32 v134, v134, s9, 0.5
	v_fma_f32 v135, v135, s9, 0.5
	v_max_f32_e32 v134, 1.0, v134
	v_max_f32_e32 v135, 1.0, v135
	v_fma_f32 v136, v136, s9, 0.5
	v_fma_f32 v137, v137, s9, 0.5
	v_max_f32_e32 v136, 1.0, v136
	v_max_f32_e32 v137, 1.0, v137
	v_fma_f32 v138, v138, s9, 0.5
	v_fma_f32 v139, v139, s9, 0.5
	v_cvt_pk_u8_f32 v134, v134, 0, 0
	v_cvt_pk_u8_f32 v135, v135, 0, 0
	v_max_f32_e32 v138, 1.0, v138
	v_max_f32_e32 v139, 1.0, v139
	v_fma_f32 v155, v155, s9, 0.5
	v_fma_f32 v156, v156, s9, 0.5
	v_cvt_pk_u8_f32 v134, v136, 1, v134
	v_cvt_pk_u8_f32 v135, v137, 1, v135
	v_max_f32_e32 v155, 1.0, v155
	v_max_f32_e32 v156, 1.0, v156
	v_cvt_pk_u8_f32 v134, v138, 2, v134
	v_cvt_pk_u8_f32 v135, v139, 2, v135
	v_cvt_pk_u8_f32 v134, v155, 3, v134
	v_cvt_pk_u8_f32 v135, v156, 3, v135
	v_mul_f32_e32 v136, 0x3c800000, v14
	v_mul_f32_e32 v137, 0x3c800000, v10
	v_mul_f32_e32 v136, 0xbfb8aa3b, v136
	v_mul_f32_e32 v137, 0xbfb8aa3b, v137
	v_mul_f32_e32 v138, 0x3c800000, v15
	v_mul_f32_e32 v139, 0x3c800000, v11
	v_exp_f32_e32 v136, v136
	v_exp_f32_e32 v137, v137
	v_mul_f32_e32 v138, 0xbfb8aa3b, v138
	v_mul_f32_e32 v139, 0xbfb8aa3b, v139
	v_mul_f32_e32 v155, 0x3c800000, v16
	v_mul_f32_e32 v156, 0x3c800000, v12
	v_exp_f32_e32 v138, v138
	v_exp_f32_e32 v139, v139
	v_mul_f32_e32 v155, 0xbfb8aa3b, v155
	v_mul_f32_e32 v156, 0xbfb8aa3b, v156
	v_mul_f32_e32 v157, 0x3c800000, v17
	v_mul_f32_e32 v158, 0x3c800000, v13
	v_exp_f32_e32 v155, v155
	v_exp_f32_e32 v156, v156
	v_mul_f32_e32 v157, 0xbfb8aa3b, v157
	v_mul_f32_e32 v158, 0xbfb8aa3b, v158
	v_exp_f32_e32 v157, v157
	v_exp_f32_e32 v158, v158
	v_add_f32_e32 v136, 1.0, v136
	v_add_f32_e32 v137, 1.0, v137
	v_rcp_f32_e32 v136, v136
	v_rcp_f32_e32 v137, v137
	v_add_f32_e32 v138, 1.0, v138
	v_add_f32_e32 v139, 1.0, v139
	v_rcp_f32_e32 v138, v138
	v_rcp_f32_e32 v139, v139
	v_add_f32_e32 v155, 1.0, v155
	v_add_f32_e32 v156, 1.0, v156
	v_rcp_f32_e32 v155, v155
	v_rcp_f32_e32 v156, v156
	v_add_f32_e32 v157, 1.0, v157
	v_add_f32_e32 v158, 1.0, v158
	v_rcp_f32_e32 v157, v157
	v_rcp_f32_e32 v158, v158
	v_fma_f32 v136, v136, s9, 0.5
	v_fma_f32 v137, v137, s9, 0.5
	v_max_f32_e32 v136, 1.0, v136
	v_max_f32_e32 v137, 1.0, v137
	v_fma_f32 v138, v138, s9, 0.5
	v_fma_f32 v139, v139, s9, 0.5
	v_max_f32_e32 v138, 1.0, v138
	v_max_f32_e32 v139, 1.0, v139
	v_fma_f32 v155, v155, s9, 0.5
	v_fma_f32 v156, v156, s9, 0.5
	v_cvt_pk_u8_f32 v136, v136, 0, 0
	v_cvt_pk_u8_f32 v137, v137, 0, 0
	v_max_f32_e32 v155, 1.0, v155
	v_max_f32_e32 v156, 1.0, v156
	v_fma_f32 v157, v157, s9, 0.5
	v_fma_f32 v158, v158, s9, 0.5
	v_cvt_pk_u8_f32 v136, v138, 1, v136
	v_cvt_pk_u8_f32 v137, v139, 1, v137
	v_max_f32_e32 v157, 1.0, v157
	v_max_f32_e32 v158, 1.0, v158
	v_cvt_pk_u8_f32 v136, v155, 2, v136
	v_cvt_pk_u8_f32 v137, v156, 2, v137
	v_cvt_pk_u8_f32 v136, v157, 3, v136
	v_cvt_pk_u8_f32 v137, v158, 3, v137
	v_mul_f32_e32 v138, 0x3c800000, v22
	v_mul_f32_e32 v139, 0x3c800000, v18
	v_mul_f32_e32 v138, 0xbfb8aa3b, v138
	v_mul_f32_e32 v139, 0xbfb8aa3b, v139
	v_exp_f32_e32 v138, v138
	v_exp_f32_e32 v139, v139
	v_permlane16_swap_b32_e32 v134, v136
	v_add_f32_e32 v138, 1.0, v138
	v_add_f32_e32 v139, 1.0, v139
	v_rcp_f32_e32 v138, v138
	v_rcp_f32_e32 v139, v139
	v_permlane16_swap_b32_e32 v135, v137
	global_store_dwordx4 v[132:133], v[134:137], off
	v_mul_f32_e32 v155, 0x3c800000, v25
	v_mul_f32_e32 v156, 0x3c800000, v21
	v_mul_f32_e32 v136, 0x3c800000, v23
	v_mul_f32_e32 v137, 0x3c800000, v19
	v_fma_f32 v134, v138, s9, 0.5
	v_fma_f32 v135, v139, s9, 0.5
	v_mul_f32_e32 v136, 0xbfb8aa3b, v136
	v_mul_f32_e32 v137, 0xbfb8aa3b, v137
	v_mul_f32_e32 v138, 0x3c800000, v24
	v_mul_f32_e32 v139, 0x3c800000, v20
	v_exp_f32_e32 v136, v136
	v_exp_f32_e32 v137, v137
	v_mul_f32_e32 v138, 0xbfb8aa3b, v138
	v_mul_f32_e32 v139, 0xbfb8aa3b, v139
	v_exp_f32_e32 v138, v138
	v_exp_f32_e32 v139, v139
	v_mul_f32_e32 v155, 0xbfb8aa3b, v155
	v_mul_f32_e32 v156, 0xbfb8aa3b, v156
	v_exp_f32_e32 v155, v155
	v_exp_f32_e32 v156, v156
	v_add_f32_e32 v136, 1.0, v136
	v_add_f32_e32 v137, 1.0, v137
	v_rcp_f32_e32 v136, v136
	v_rcp_f32_e32 v137, v137
	v_add_f32_e32 v138, 1.0, v138
	v_add_f32_e32 v139, 1.0, v139
	v_rcp_f32_e32 v138, v138
	v_rcp_f32_e32 v139, v139
	v_add_f32_e32 v155, 1.0, v155
	v_add_f32_e32 v156, 1.0, v156
	v_rcp_f32_e32 v155, v155
	v_rcp_f32_e32 v156, v156
	v_max_f32_e32 v134, 1.0, v134
	v_max_f32_e32 v135, 1.0, v135
	v_fma_f32 v136, v136, s9, 0.5
	v_fma_f32 v137, v137, s9, 0.5
	v_max_f32_e32 v136, 1.0, v136
	v_max_f32_e32 v137, 1.0, v137
	v_fma_f32 v138, v138, s9, 0.5
	v_fma_f32 v139, v139, s9, 0.5
	v_cvt_pk_u8_f32 v134, v134, 0, 0
	v_cvt_pk_u8_f32 v135, v135, 0, 0
	v_max_f32_e32 v138, 1.0, v138
	v_max_f32_e32 v139, 1.0, v139
	v_fma_f32 v155, v155, s9, 0.5
	v_fma_f32 v156, v156, s9, 0.5
	v_cvt_pk_u8_f32 v134, v136, 1, v134
	v_cvt_pk_u8_f32 v135, v137, 1, v135
	v_max_f32_e32 v155, 1.0, v155
	v_max_f32_e32 v156, 1.0, v156
	v_cvt_pk_u8_f32 v134, v138, 2, v134
	v_cvt_pk_u8_f32 v135, v139, 2, v135
	v_cvt_pk_u8_f32 v134, v155, 3, v134
	v_cvt_pk_u8_f32 v135, v156, 3, v135
	v_mul_f32_e32 v136, 0x3c800000, v6
	v_mul_f32_e32 v137, 0x3c800000, v2
	v_mul_f32_e32 v136, 0xbfb8aa3b, v136
	v_mul_f32_e32 v137, 0xbfb8aa3b, v137
	v_mul_f32_e32 v138, 0x3c800000, v7
	v_mul_f32_e32 v139, 0x3c800000, v3
	v_exp_f32_e32 v136, v136
	v_exp_f32_e32 v137, v137
	v_mul_f32_e32 v138, 0xbfb8aa3b, v138
	v_mul_f32_e32 v139, 0xbfb8aa3b, v139
	v_mul_f32_e32 v155, 0x3c800000, v8
	v_mul_f32_e32 v156, 0x3c800000, v4
	v_exp_f32_e32 v138, v138
	v_exp_f32_e32 v139, v139
	v_mul_f32_e32 v155, 0xbfb8aa3b, v155
	v_mul_f32_e32 v156, 0xbfb8aa3b, v156
	v_mul_f32_e32 v157, 0x3c800000, v9
	v_mul_f32_e32 v158, 0x3c800000, v5
	v_exp_f32_e32 v155, v155
	v_exp_f32_e32 v156, v156
	v_mul_f32_e32 v157, 0xbfb8aa3b, v157
	v_mul_f32_e32 v158, 0xbfb8aa3b, v158
	v_exp_f32_e32 v157, v157
	v_exp_f32_e32 v158, v158
	v_add_f32_e32 v136, 1.0, v136
	v_add_f32_e32 v137, 1.0, v137
	v_rcp_f32_e32 v136, v136
	v_rcp_f32_e32 v137, v137
	v_add_f32_e32 v138, 1.0, v138
	v_add_f32_e32 v139, 1.0, v139
	v_rcp_f32_e32 v138, v138
	v_rcp_f32_e32 v139, v139
	v_add_f32_e32 v155, 1.0, v155
	v_add_f32_e32 v156, 1.0, v156
	v_rcp_f32_e32 v155, v155
	v_rcp_f32_e32 v156, v156
	v_add_f32_e32 v157, 1.0, v157
	v_add_f32_e32 v158, 1.0, v158
	v_rcp_f32_e32 v157, v157
	v_rcp_f32_e32 v158, v158
	v_fma_f32 v136, v136, s9, 0.5
	v_fma_f32 v137, v137, s9, 0.5
	v_max_f32_e32 v136, 1.0, v136
	v_max_f32_e32 v137, 1.0, v137
	v_fma_f32 v138, v138, s9, 0.5
	v_fma_f32 v139, v139, s9, 0.5
	v_max_f32_e32 v138, 1.0, v138
	v_max_f32_e32 v139, 1.0, v139
	v_fma_f32 v155, v155, s9, 0.5
	v_fma_f32 v156, v156, s9, 0.5
	v_cvt_pk_u8_f32 v136, v136, 0, 0
	v_cvt_pk_u8_f32 v137, v137, 0, 0
	v_max_f32_e32 v155, 1.0, v155
	v_max_f32_e32 v156, 1.0, v156
	v_fma_f32 v157, v157, s9, 0.5
	v_fma_f32 v158, v158, s9, 0.5
	v_cvt_pk_u8_f32 v136, v138, 1, v136
	v_cvt_pk_u8_f32 v137, v139, 1, v137
	v_max_f32_e32 v157, 1.0, v157
	v_max_f32_e32 v158, 1.0, v158
	v_cvt_pk_u8_f32 v136, v155, 2, v136
	v_cvt_pk_u8_f32 v137, v156, 2, v137
	v_cvt_pk_u8_f32 v136, v157, 3, v136
	v_cvt_pk_u8_f32 v137, v158, 3, v137
	s_nop 0
	v_permlane16_swap_b32_e32 v134, v136
	v_permlane16_swap_b32_e32 v135, v137
	global_store_dwordx4 v[132:133], v[134:137], off offset:128

.LBB0_126:
	s_andn2_b64 vcc, exec, s[6:7]
	s_cbranch_vccnz .LBB0_128
	v_mul_f32_e32 v133, 0xbfb8aa3b, v128
	v_exp_f32_e32 v133, v133
	v_mul_f32_e32 v136, 0xbfb8aa3b, v124
	v_exp_f32_e32 v136, v136
	v_ashrrev_i32_e32 v155, 31, v154
	v_lshlrev_b64 v[134:135], 12, v[154:155]
	v_lshl_add_u64 v[156:157], s[56:57], 0, v[134:135]
	v_add_f32_e32 v133, 1.0, v133
	v_mul_f32_e32 v135, 0xbfb8aa3b, v129
	v_rcp_f32_e32 v134, v133
	v_add_f32_e32 v133, 1.0, v136
	v_exp_f32_e32 v135, v135
	v_mul_f32_e32 v136, 0xbfb8aa3b, v125
	v_exp_f32_e32 v137, v136
	v_rcp_f32_e32 v136, v133
	v_add_f32_e32 v133, 1.0, v135
	v_rcp_f32_e32 v135, v133
	v_add_f32_e32 v133, 1.0, v137
	v_mul_f32_e32 v137, 0xbfb8aa3b, v130
	v_exp_f32_e32 v138, v137
	v_mul_f32_e32 v137, 0xbfb8aa3b, v126
	v_exp_f32_e32 v139, v137
	v_rcp_f32_e32 v137, v133
	v_add_f32_e32 v133, 1.0, v138
	v_rcp_f32_e32 v138, v133
	v_add_f32_e32 v133, 1.0, v139
	v_mul_f32_e32 v139, 0xbfb8aa3b, v131
	v_exp_f32_e32 v139, v139
	v_mul_f32_e32 v155, 0xbfb8aa3b, v127
	v_exp_f32_e32 v155, v155
	v_rcp_f32_e32 v158, v133
	v_add_f32_e32 v133, 1.0, v139
	v_rcp_f32_e32 v139, v133
	v_add_f32_e32 v133, 1.0, v155
	v_rcp_f32_e32 v159, v133
	v_or_b32_e32 v132, 0xffffc000, v163
	v_lshl_add_u32 v132, s76, 8, v132
	v_pk_mul_f32 v[134:135], v[128:129], v[134:135]
	v_mov_b32_e32 v133, v34
	v_mul_f32_e32 v155, 0xbfb8aa3b, v120
	v_pk_mul_f32 v[160:161], v[124:125], v[136:137]
	v_pk_mul_f32 v[138:139], v[130:131], v[138:139]
	v_pk_mul_f32 v[158:159], v[126:127], v[158:159]
	v_cvt_pk_bf16_f32 v136, v134, v135
	v_lshlrev_b64 v[134:135], 1, v[132:133]
	v_exp_f32_e32 v155, v155
	v_cvt_pk_bf16_f32 v137, v138, v139
	v_cvt_pk_bf16_f32 v138, v160, v161
	v_cvt_pk_bf16_f32 v139, v158, v159
	v_lshl_add_u64 v[132:133], v[156:157], 0, v[134:135]
	v_mul_f32_e32 v156, 0xbfb8aa3b, v116
	global_store_dwordx4 v[132:133], v[136:139], off
	v_exp_f32_e32 v156, v156
	v_mul_f32_e32 v158, 0xbfb8aa3b, v119
	v_mul_f32_e32 v138, 0xbfb8aa3b, v121
	v_exp_f32_e32 v139, v138
	v_mul_f32_e32 v138, 0xbfb8aa3b, v117
	v_add_f32_e32 v136, 1.0, v155
	v_exp_f32_e32 v155, v138
	v_add_f32_e32 v137, 1.0, v156
	v_rcp_f32_e32 v138, v137
	v_add_f32_e32 v137, 1.0, v139
	v_add_f32_e32 v139, 1.0, v155
	v_mul_f32_e32 v155, 0xbfb8aa3b, v122
	v_exp_f32_e32 v155, v155
	v_mul_f32_e32 v156, 0xbfb8aa3b, v118
	v_exp_f32_e32 v157, v156
	v_exp_f32_e32 v159, v158
	v_add_f32_e32 v155, 1.0, v155
	v_rcp_f32_e32 v156, v155
	v_add_f32_e32 v155, 1.0, v157
	v_mul_f32_e32 v157, 0xbfb8aa3b, v123
	v_exp_f32_e32 v157, v157
	v_rcp_f32_e32 v158, v155
	v_rcp_f32_e32 v136, v136
	v_rcp_f32_e32 v137, v137
	v_add_f32_e32 v155, 1.0, v157
	v_rcp_f32_e32 v157, v155
	v_add_f32_e32 v155, 1.0, v159
	v_rcp_f32_e32 v139, v139
	v_rcp_f32_e32 v159, v155
	v_pk_mul_f32 v[136:137], v[120:121], v[136:137]
	v_pk_mul_f32 v[156:157], v[122:123], v[156:157]
	v_pk_mul_f32 v[138:139], v[116:117], v[138:139]
	v_pk_mul_f32 v[158:159], v[118:119], v[158:159]
	v_cvt_pk_bf16_f32 v136, v136, v137
	v_cvt_pk_bf16_f32 v137, v156, v157
	v_cvt_pk_bf16_f32 v138, v138, v139
	v_cvt_pk_bf16_f32 v139, v158, v159
	global_store_dwordx4 v[132:133], v[136:139], off offset:256
	v_mul_f32_e32 v158, 0xbfb8aa3b, v110
	v_exp_f32_e32 v159, v158
	v_mul_f32_e32 v138, 0xbfb8aa3b, v112
	v_exp_f32_e32 v138, v138
	v_mul_f32_e32 v139, 0xbfb8aa3b, v108
	v_or_b32_e32 v136, 16, v154
	v_exp_f32_e32 v139, v139
	v_ashrrev_i32_e32 v137, 31, v136
	v_lshlrev_b64 v[136:137], 12, v[136:137]
	v_lshl_add_u64 v[156:157], s[56:57], 0, v[136:137]
	v_add_f32_e32 v136, 1.0, v138
	v_mul_f32_e32 v138, 0xbfb8aa3b, v113
	v_add_f32_e32 v137, 1.0, v139
	v_exp_f32_e32 v139, v138
	v_mul_f32_e32 v138, 0xbfb8aa3b, v109
	v_exp_f32_e32 v155, v138
	v_rcp_f32_e32 v138, v137
	v_add_f32_e32 v137, 1.0, v139
	v_mul_f32_e32 v160, 0xbfb8aa3b, v111
	v_add_f32_e32 v139, 1.0, v155
	v_mul_f32_e32 v155, 0xbfb8aa3b, v114
	v_exp_f32_e32 v155, v155
	v_exp_f32_e32 v161, v160
	v_rcp_f32_e32 v136, v136
	v_rcp_f32_e32 v137, v137
	v_add_f32_e32 v155, 1.0, v155
	v_rcp_f32_e32 v158, v155
	v_add_f32_e32 v155, 1.0, v159
	v_mul_f32_e32 v159, 0xbfb8aa3b, v115
	v_exp_f32_e32 v159, v159
	v_rcp_f32_e32 v160, v155
	v_rcp_f32_e32 v139, v139
	v_pk_mul_f32 v[136:137], v[112:113], v[136:137]
	v_add_f32_e32 v155, 1.0, v159
	v_rcp_f32_e32 v159, v155
	v_add_f32_e32 v155, 1.0, v161
	v_rcp_f32_e32 v161, v155
	v_mul_f32_e32 v155, 0xbfb8aa3b, v104
	v_pk_mul_f32 v[138:139], v[108:109], v[138:139]
	v_pk_mul_f32 v[158:159], v[114:115], v[158:159]
	v_pk_mul_f32 v[160:161], v[110:111], v[160:161]
	v_exp_f32_e32 v155, v155
	v_cvt_pk_bf16_f32 v136, v136, v137
	v_cvt_pk_bf16_f32 v137, v158, v159
	v_cvt_pk_bf16_f32 v138, v138, v139
	v_cvt_pk_bf16_f32 v139, v160, v161
	v_lshl_add_u64 v[156:157], v[156:157], 0, v[134:135]
	v_mul_f32_e32 v158, 0xbfb8aa3b, v100
	global_store_dwordx4 v[156:157], v[136:139], off
	v_exp_f32_e32 v158, v158
	v_mul_f32_e32 v160, 0xbfb8aa3b, v103
	v_mul_f32_e32 v138, 0xbfb8aa3b, v105
	v_exp_f32_e32 v139, v138
	v_mul_f32_e32 v138, 0xbfb8aa3b, v101
	v_add_f32_e32 v136, 1.0, v155
	v_exp_f32_e32 v155, v138
	v_add_f32_e32 v137, 1.0, v158
	v_rcp_f32_e32 v138, v137
	v_add_f32_e32 v137, 1.0, v139
	v_add_f32_e32 v139, 1.0, v155
	v_mul_f32_e32 v155, 0xbfb8aa3b, v106
	v_exp_f32_e32 v155, v155
	v_mul_f32_e32 v158, 0xbfb8aa3b, v102
	v_exp_f32_e32 v159, v158
	v_exp_f32_e32 v161, v160
	v_add_f32_e32 v155, 1.0, v155
	v_rcp_f32_e32 v158, v155
	v_add_f32_e32 v155, 1.0, v159
	v_mul_f32_e32 v159, 0xbfb8aa3b, v107
	v_exp_f32_e32 v159, v159
	v_rcp_f32_e32 v160, v155
	v_rcp_f32_e32 v136, v136
	v_rcp_f32_e32 v137, v137
	v_add_f32_e32 v155, 1.0, v159
	v_rcp_f32_e32 v159, v155
	v_add_f32_e32 v155, 1.0, v161
	v_rcp_f32_e32 v139, v139
	v_rcp_f32_e32 v161, v155
	v_pk_mul_f32 v[136:137], v[104:105], v[136:137]
	v_pk_mul_f32 v[158:159], v[106:107], v[158:159]
	v_pk_mul_f32 v[138:139], v[100:101], v[138:139]
	v_pk_mul_f32 v[160:161], v[102:103], v[160:161]
	v_cvt_pk_bf16_f32 v136, v136, v137
	v_cvt_pk_bf16_f32 v137, v158, v159
	v_cvt_pk_bf16_f32 v138, v138, v139
	v_cvt_pk_bf16_f32 v139, v160, v161
	global_store_dwordx4 v[156:157], v[136:139], off offset:256
	v_mul_f32_e32 v158, 0xbfb8aa3b, v94
	v_exp_f32_e32 v159, v158
	v_mul_f32_e32 v138, 0xbfb8aa3b, v96
	v_exp_f32_e32 v138, v138
	v_mul_f32_e32 v139, 0xbfb8aa3b, v92
	v_or_b32_e32 v136, 32, v154
	v_exp_f32_e32 v139, v139
	v_ashrrev_i32_e32 v137, 31, v136
	v_lshlrev_b64 v[136:137], 12, v[136:137]
	v_lshl_add_u64 v[156:157], s[56:57], 0, v[136:137]
	v_add_f32_e32 v136, 1.0, v138
	v_mul_f32_e32 v138, 0xbfb8aa3b, v97
	v_add_f32_e32 v137, 1.0, v139
	v_exp_f32_e32 v139, v138
	v_mul_f32_e32 v138, 0xbfb8aa3b, v93
	v_exp_f32_e32 v155, v138
	v_rcp_f32_e32 v138, v137
	v_add_f32_e32 v137, 1.0, v139
	v_mul_f32_e32 v160, 0xbfb8aa3b, v95
	v_add_f32_e32 v139, 1.0, v155
	v_mul_f32_e32 v155, 0xbfb8aa3b, v98
	v_exp_f32_e32 v155, v155
	v_exp_f32_e32 v161, v160
	v_rcp_f32_e32 v136, v136
	v_rcp_f32_e32 v137, v137
	v_add_f32_e32 v155, 1.0, v155
	v_rcp_f32_e32 v158, v155
	v_add_f32_e32 v155, 1.0, v159
	v_mul_f32_e32 v159, 0xbfb8aa3b, v99
	v_exp_f32_e32 v159, v159
	v_rcp_f32_e32 v160, v155
	v_rcp_f32_e32 v139, v139
	v_pk_mul_f32 v[136:137], v[96:97], v[136:137]
	v_add_f32_e32 v155, 1.0, v159
	v_rcp_f32_e32 v159, v155
	v_add_f32_e32 v155, 1.0, v161
	v_rcp_f32_e32 v161, v155
	v_mul_f32_e32 v155, 0xbfb8aa3b, v88
	v_pk_mul_f32 v[138:139], v[92:93], v[138:139]
	v_pk_mul_f32 v[158:159], v[98:99], v[158:159]
	v_pk_mul_f32 v[160:161], v[94:95], v[160:161]
	v_exp_f32_e32 v155, v155
	v_cvt_pk_bf16_f32 v136, v136, v137
	v_cvt_pk_bf16_f32 v137, v158, v159
	v_cvt_pk_bf16_f32 v138, v138, v139
	v_cvt_pk_bf16_f32 v139, v160, v161
	v_lshl_add_u64 v[156:157], v[156:157], 0, v[134:135]
	v_mul_f32_e32 v158, 0xbfb8aa3b, v84
	global_store_dwordx4 v[156:157], v[136:139], off
	v_exp_f32_e32 v158, v158
	v_mul_f32_e32 v160, 0xbfb8aa3b, v87
	v_mul_f32_e32 v138, 0xbfb8aa3b, v89
	v_exp_f32_e32 v139, v138
	v_mul_f32_e32 v138, 0xbfb8aa3b, v85
	v_add_f32_e32 v136, 1.0, v155
	v_exp_f32_e32 v155, v138
	v_add_f32_e32 v137, 1.0, v158
	v_rcp_f32_e32 v138, v137
	v_add_f32_e32 v137, 1.0, v139
	v_add_f32_e32 v139, 1.0, v155
	v_mul_f32_e32 v155, 0xbfb8aa3b, v90
	v_exp_f32_e32 v155, v155
	v_mul_f32_e32 v158, 0xbfb8aa3b, v86
	v_exp_f32_e32 v159, v158
	v_exp_f32_e32 v161, v160
	v_add_f32_e32 v155, 1.0, v155
	v_rcp_f32_e32 v158, v155
	v_add_f32_e32 v155, 1.0, v159
	v_mul_f32_e32 v159, 0xbfb8aa3b, v91
	v_exp_f32_e32 v159, v159
	v_rcp_f32_e32 v160, v155
	v_rcp_f32_e32 v136, v136
	v_rcp_f32_e32 v137, v137
	v_add_f32_e32 v155, 1.0, v159
	v_rcp_f32_e32 v159, v155
	v_add_f32_e32 v155, 1.0, v161
	v_rcp_f32_e32 v139, v139
	v_rcp_f32_e32 v161, v155
	v_pk_mul_f32 v[136:137], v[88:89], v[136:137]
	v_pk_mul_f32 v[158:159], v[90:91], v[158:159]
	v_pk_mul_f32 v[138:139], v[84:85], v[138:139]
	v_pk_mul_f32 v[160:161], v[86:87], v[160:161]
	v_cvt_pk_bf16_f32 v136, v136, v137
	v_cvt_pk_bf16_f32 v137, v158, v159
	v_cvt_pk_bf16_f32 v138, v138, v139
	v_cvt_pk_bf16_f32 v139, v160, v161
	global_store_dwordx4 v[156:157], v[136:139], off offset:256
	v_mul_f32_e32 v158, 0xbfb8aa3b, v78
	v_exp_f32_e32 v159, v158
	v_mul_f32_e32 v138, 0xbfb8aa3b, v80
	v_exp_f32_e32 v138, v138
	v_mul_f32_e32 v139, 0xbfb8aa3b, v76
	v_or_b32_e32 v136, 48, v154
	v_exp_f32_e32 v139, v139
	v_ashrrev_i32_e32 v137, 31, v136
	v_lshlrev_b64 v[136:137], 12, v[136:137]
	v_lshl_add_u64 v[156:157], s[56:57], 0, v[136:137]
	v_add_f32_e32 v136, 1.0, v138
	v_mul_f32_e32 v138, 0xbfb8aa3b, v81
	v_add_f32_e32 v137, 1.0, v139
	v_exp_f32_e32 v139, v138
	v_mul_f32_e32 v138, 0xbfb8aa3b, v77
	v_exp_f32_e32 v155, v138
	v_rcp_f32_e32 v138, v137
	v_add_f32_e32 v137, 1.0, v139
	v_mul_f32_e32 v160, 0xbfb8aa3b, v79
	v_add_f32_e32 v139, 1.0, v155
	v_mul_f32_e32 v155, 0xbfb8aa3b, v82
	v_exp_f32_e32 v155, v155
	v_exp_f32_e32 v161, v160
	v_rcp_f32_e32 v136, v136
	v_rcp_f32_e32 v137, v137
	v_add_f32_e32 v155, 1.0, v155
	v_rcp_f32_e32 v158, v155
	v_add_f32_e32 v155, 1.0, v159
	v_mul_f32_e32 v159, 0xbfb8aa3b, v83
	v_exp_f32_e32 v159, v159
	v_rcp_f32_e32 v160, v155
	v_rcp_f32_e32 v139, v139
	v_pk_mul_f32 v[136:137], v[80:81], v[136:137]
	v_add_f32_e32 v155, 1.0, v159
	v_rcp_f32_e32 v159, v155
	v_add_f32_e32 v155, 1.0, v161
	v_rcp_f32_e32 v161, v155
	v_pk_mul_f32 v[138:139], v[76:77], v[138:139]
	v_pk_mul_f32 v[158:159], v[82:83], v[158:159]
	v_cvt_pk_bf16_f32 v136, v136, v137
	v_pk_mul_f32 v[160:161], v[78:79], v[160:161]
	v_cvt_pk_bf16_f32 v137, v158, v159
	v_cvt_pk_bf16_f32 v138, v138, v139
	v_cvt_pk_bf16_f32 v139, v160, v161
	v_lshl_add_u64 v[156:157], v[156:157], 0, v[134:135]
	v_mul_f32_e32 v135, 0xbfb8aa3b, v68
	global_store_dwordx4 v[156:157], v[136:139], off
	v_exp_f32_e32 v135, v135
	v_mul_f32_e32 v134, 0xbfb8aa3b, v72
	v_mul_f32_e32 v136, 0xbfb8aa3b, v73
	v_exp_f32_e32 v137, v136
	v_mul_f32_e32 v136, 0xbfb8aa3b, v69
	v_exp_f32_e32 v138, v136
	v_add_f32_e32 v135, 1.0, v135
	v_mul_f32_e32 v139, 0xbfb8aa3b, v70
	v_rcp_f32_e32 v136, v135
	v_add_f32_e32 v135, 1.0, v137
	v_add_f32_e32 v137, 1.0, v138
	v_mul_f32_e32 v138, 0xbfb8aa3b, v74
	v_exp_f32_e32 v139, v139
	v_mul_f32_e32 v155, 0xbfb8aa3b, v75
	v_exp_f32_e32 v134, v134
	v_exp_f32_e32 v138, v138
	v_exp_f32_e32 v155, v155
	v_mul_f32_e32 v158, 0xbfb8aa3b, v71
	v_exp_f32_e32 v159, v158
	v_add_f32_e32 v139, 1.0, v139
	v_add_f32_e32 v134, 1.0, v134
	v_add_f32_e32 v138, 1.0, v138
	v_rcp_f32_e32 v158, v139
	v_add_f32_e32 v139, 1.0, v155
	v_rcp_f32_e32 v134, v134
	v_rcp_f32_e32 v135, v135
	v_rcp_f32_e32 v138, v138
	v_rcp_f32_e32 v139, v139
	v_add_f32_e32 v155, 1.0, v159
	v_rcp_f32_e32 v137, v137
	v_rcp_f32_e32 v159, v155
	v_pk_mul_f32 v[134:135], v[72:73], v[134:135]
	v_pk_mul_f32 v[138:139], v[74:75], v[138:139]
	v_cvt_pk_bf16_f32 v134, v134, v135
	v_cvt_pk_bf16_f32 v135, v138, v139
	v_mul_f32_e32 v138, 0xbfb8aa3b, v64
	v_pk_mul_f32 v[136:137], v[68:69], v[136:137]
	v_pk_mul_f32 v[158:159], v[70:71], v[158:159]
	v_exp_f32_e32 v138, v138
	v_cvt_pk_bf16_f32 v136, v136, v137
	v_cvt_pk_bf16_f32 v137, v158, v159
	v_mul_f32_e32 v139, 0xbfb8aa3b, v60
	global_store_dwordx4 v[156:157], v[134:137], off offset:256
	v_exp_f32_e32 v139, v139
	v_mul_f32_e32 v155, 0xbfb8aa3b, v67
	v_mul_f32_e32 v136, 0xbfb8aa3b, v65
	v_exp_f32_e32 v137, v136
	v_mul_f32_e32 v136, 0xbfb8aa3b, v61
	v_add_f32_e32 v134, 1.0, v138
	v_exp_f32_e32 v138, v136
	v_add_f32_e32 v135, 1.0, v139
	v_mul_f32_e32 v139, 0xbfb8aa3b, v62
	v_rcp_f32_e32 v136, v135
	v_add_f32_e32 v135, 1.0, v137
	v_add_f32_e32 v137, 1.0, v138
	v_mul_f32_e32 v138, 0xbfb8aa3b, v66
	v_exp_f32_e32 v139, v139
	v_exp_f32_e32 v138, v138
	v_exp_f32_e32 v155, v155
	v_mul_f32_e32 v156, 0xbfb8aa3b, v63
	v_exp_f32_e32 v157, v156
	v_add_f32_e32 v139, 1.0, v139
	v_add_f32_e32 v138, 1.0, v138
	v_rcp_f32_e32 v156, v139
	v_add_f32_e32 v139, 1.0, v155
	v_rcp_f32_e32 v134, v134
	v_rcp_f32_e32 v135, v135
	v_rcp_f32_e32 v138, v138
	v_rcp_f32_e32 v139, v139
	v_add_f32_e32 v155, 1.0, v157
	v_rcp_f32_e32 v137, v137
	v_rcp_f32_e32 v157, v155
	v_pk_mul_f32 v[134:135], v[64:65], v[134:135]
	v_pk_mul_f32 v[138:139], v[66:67], v[138:139]
	s_mov_b64 s[6:7], 0x80000
	v_pk_mul_f32 v[136:137], v[60:61], v[136:137]
	v_pk_mul_f32 v[156:157], v[62:63], v[156:157]
	v_cvt_pk_bf16_f32 v134, v134, v135
	v_cvt_pk_bf16_f32 v135, v138, v139
	v_lshl_add_u64 v[138:139], v[132:133], 0, s[6:7]
	s_mov_b32 s6, 0x80000
	v_mul_f32_e32 v155, 0xbfb8aa3b, v56
	v_cvt_pk_bf16_f32 v136, v136, v137
	v_cvt_pk_bf16_f32 v137, v156, v157
	v_add_co_u32_e32 v156, vcc, s6, v132
	v_exp_f32_e32 v155, v155
	s_nop 0
	v_addc_co_u32_e32 v157, vcc, 0, v133, vcc
	v_mul_f32_e32 v158, 0xbfb8aa3b, v52
	global_store_dwordx4 v[156:157], v[134:137], off
	v_exp_f32_e32 v158, v158
	v_mul_f32_e32 v156, 0xbfb8aa3b, v54
	v_mul_f32_e32 v136, 0xbfb8aa3b, v57
	v_exp_f32_e32 v137, v136
	v_mul_f32_e32 v136, 0xbfb8aa3b, v53
	v_add_f32_e32 v134, 1.0, v155
	v_exp_f32_e32 v155, v136
	v_add_f32_e32 v135, 1.0, v158
	v_rcp_f32_e32 v136, v135
	v_add_f32_e32 v135, 1.0, v137
	v_add_f32_e32 v137, 1.0, v155
	v_mul_f32_e32 v155, 0xbfb8aa3b, v58
	v_exp_f32_e32 v155, v155
	v_exp_f32_e32 v157, v156
	v_mul_f32_e32 v158, 0xbfb8aa3b, v55
	v_exp_f32_e32 v159, v158
	v_add_f32_e32 v155, 1.0, v155
	v_rcp_f32_e32 v156, v155
	v_add_f32_e32 v155, 1.0, v157
	v_mul_f32_e32 v157, 0xbfb8aa3b, v59
	v_exp_f32_e32 v157, v157
	v_rcp_f32_e32 v158, v155
	v_rcp_f32_e32 v134, v134
	v_rcp_f32_e32 v135, v135
	v_add_f32_e32 v155, 1.0, v157
	v_rcp_f32_e32 v157, v155
	v_add_f32_e32 v155, 1.0, v159
	v_rcp_f32_e32 v137, v137
	v_rcp_f32_e32 v159, v155
	v_pk_mul_f32 v[134:135], v[56:57], v[134:135]
	v_pk_mul_f32 v[156:157], v[58:59], v[156:157]
	v_pk_mul_f32 v[136:137], v[52:53], v[136:137]
	v_pk_mul_f32 v[158:159], v[54:55], v[158:159]
	v_cvt_pk_bf16_f32 v134, v134, v135
	v_cvt_pk_bf16_f32 v135, v156, v157
	v_cvt_pk_bf16_f32 v136, v136, v137
	v_cvt_pk_bf16_f32 v137, v158, v159
	v_mul_f32_e32 v156, 0xbfb8aa3b, v44
	global_store_dwordx4 v[138:139], v[134:137], off offset:256
	v_mul_f32_e32 v155, 0xbfb8aa3b, v48
	v_exp_f32_e32 v156, v156
	v_mul_f32_e32 v136, 0xbfb8aa3b, v49
	v_exp_f32_e32 v137, v136
	v_mul_f32_e32 v136, 0xbfb8aa3b, v45
	v_exp_f32_e32 v155, v155
	v_exp_f32_e32 v138, v136
	v_add_f32_e32 v135, 1.0, v156
	v_mul_f32_e32 v139, 0xbfb8aa3b, v46
	v_add_f32_e32 v134, 1.0, v155
	v_rcp_f32_e32 v136, v135
	v_add_f32_e32 v135, 1.0, v137
	v_add_f32_e32 v137, 1.0, v138
	v_mul_f32_e32 v138, 0xbfb8aa3b, v50
	v_exp_f32_e32 v139, v139
	v_mul_f32_e32 v155, 0xbfb8aa3b, v51
	v_exp_f32_e32 v138, v138
	v_exp_f32_e32 v155, v155
	v_mul_f32_e32 v156, 0xbfb8aa3b, v47
	v_exp_f32_e32 v157, v156
	v_add_f32_e32 v139, 1.0, v139
	v_add_f32_e32 v138, 1.0, v138
	v_rcp_f32_e32 v156, v139
	v_add_f32_e32 v139, 1.0, v155
	v_rcp_f32_e32 v134, v134
	v_rcp_f32_e32 v135, v135
	v_rcp_f32_e32 v138, v138
	v_rcp_f32_e32 v139, v139
	v_add_f32_e32 v155, 1.0, v157
	v_rcp_f32_e32 v137, v137
	v_rcp_f32_e32 v157, v155
	v_pk_mul_f32 v[134:135], v[48:49], v[134:135]
	v_pk_mul_f32 v[138:139], v[50:51], v[138:139]
	s_mov_b64 s[6:7], 0x90000
	v_pk_mul_f32 v[136:137], v[44:45], v[136:137]
	v_pk_mul_f32 v[156:157], v[46:47], v[156:157]
	v_cvt_pk_bf16_f32 v134, v134, v135
	v_cvt_pk_bf16_f32 v135, v138, v139
	v_lshl_add_u64 v[138:139], v[132:133], 0, s[6:7]
	s_mov_b32 s6, 0x90000
	v_mul_f32_e32 v155, 0xbfb8aa3b, v40
	v_cvt_pk_bf16_f32 v136, v136, v137
	v_cvt_pk_bf16_f32 v137, v156, v157
	v_add_co_u32_e32 v156, vcc, s6, v132
	v_exp_f32_e32 v155, v155
	s_nop 0
	v_addc_co_u32_e32 v157, vcc, 0, v133, vcc
	v_mul_f32_e32 v158, 0xbfb8aa3b, v36
	global_store_dwordx4 v[156:157], v[134:137], off
	v_exp_f32_e32 v158, v158
	v_mul_f32_e32 v156, 0xbfb8aa3b, v38
	v_mul_f32_e32 v136, 0xbfb8aa3b, v41
	v_exp_f32_e32 v137, v136
	v_mul_f32_e32 v136, 0xbfb8aa3b, v37
	v_add_f32_e32 v134, 1.0, v155
	v_exp_f32_e32 v155, v136
	v_add_f32_e32 v135, 1.0, v158
	v_rcp_f32_e32 v136, v135
	v_add_f32_e32 v135, 1.0, v137
	v_add_f32_e32 v137, 1.0, v155
	v_mul_f32_e32 v155, 0xbfb8aa3b, v42
	v_exp_f32_e32 v155, v155
	v_exp_f32_e32 v157, v156
	v_mul_f32_e32 v158, 0xbfb8aa3b, v39
	v_exp_f32_e32 v159, v158
	v_add_f32_e32 v155, 1.0, v155
	v_rcp_f32_e32 v156, v155
	v_add_f32_e32 v155, 1.0, v157
	v_mul_f32_e32 v157, 0xbfb8aa3b, v43
	v_exp_f32_e32 v157, v157
	v_rcp_f32_e32 v158, v155
	v_rcp_f32_e32 v134, v134
	v_rcp_f32_e32 v135, v135
	v_add_f32_e32 v155, 1.0, v157
	v_rcp_f32_e32 v157, v155
	v_add_f32_e32 v155, 1.0, v159
	v_rcp_f32_e32 v137, v137
	v_rcp_f32_e32 v159, v155
	v_pk_mul_f32 v[134:135], v[40:41], v[134:135]
	v_pk_mul_f32 v[156:157], v[42:43], v[156:157]
	v_pk_mul_f32 v[136:137], v[36:37], v[136:137]
	v_pk_mul_f32 v[158:159], v[38:39], v[158:159]
	v_cvt_pk_bf16_f32 v134, v134, v135
	v_cvt_pk_bf16_f32 v135, v156, v157
	v_cvt_pk_bf16_f32 v136, v136, v137
	v_cvt_pk_bf16_f32 v137, v158, v159
	v_mul_f32_e32 v156, 0xbfb8aa3b, v26
	global_store_dwordx4 v[138:139], v[134:137], off offset:256
	v_mul_f32_e32 v155, 0xbfb8aa3b, v30
	v_exp_f32_e32 v156, v156
	v_mul_f32_e32 v136, 0xbfb8aa3b, v31
	v_exp_f32_e32 v137, v136
	v_mul_f32_e32 v136, 0xbfb8aa3b, v27
	v_exp_f32_e32 v155, v155
	v_exp_f32_e32 v138, v136
	v_add_f32_e32 v135, 1.0, v156
	v_mul_f32_e32 v139, 0xbfb8aa3b, v28
	v_add_f32_e32 v134, 1.0, v155
	v_rcp_f32_e32 v136, v135
	v_add_f32_e32 v135, 1.0, v137
	v_add_f32_e32 v137, 1.0, v138
	v_mul_f32_e32 v138, 0xbfb8aa3b, v32
	v_exp_f32_e32 v139, v139
	v_mul_f32_e32 v155, 0xbfb8aa3b, v33
	v_exp_f32_e32 v138, v138
	v_exp_f32_e32 v155, v155
	v_mul_f32_e32 v156, 0xbfb8aa3b, v29
	v_exp_f32_e32 v157, v156
	v_add_f32_e32 v139, 1.0, v139
	v_add_f32_e32 v138, 1.0, v138
	v_rcp_f32_e32 v156, v139
	v_add_f32_e32 v139, 1.0, v155
	v_rcp_f32_e32 v134, v134
	v_rcp_f32_e32 v135, v135
	v_rcp_f32_e32 v138, v138
	v_rcp_f32_e32 v139, v139
	v_add_f32_e32 v155, 1.0, v157
	v_rcp_f32_e32 v137, v137
	v_rcp_f32_e32 v157, v155
	v_pk_mul_f32 v[134:135], v[30:31], v[134:135]
	v_pk_mul_f32 v[138:139], v[32:33], v[138:139]
	s_mov_b64 s[6:7], 0xa0000
	v_pk_mul_f32 v[136:137], v[26:27], v[136:137]
	v_pk_mul_f32 v[156:157], v[28:29], v[156:157]
	v_cvt_pk_bf16_f32 v134, v134, v135
	v_cvt_pk_bf16_f32 v135, v138, v139
	v_lshl_add_u64 v[138:139], v[132:133], 0, s[6:7]
	s_mov_b32 s6, 0xa0000
	v_mul_f32_e32 v155, 0xbfb8aa3b, v22
	v_cvt_pk_bf16_f32 v136, v136, v137
	v_cvt_pk_bf16_f32 v137, v156, v157
	v_add_co_u32_e32 v156, vcc, s6, v132
	v_exp_f32_e32 v155, v155
	s_nop 0
	v_addc_co_u32_e32 v157, vcc, 0, v133, vcc
	v_mul_f32_e32 v158, 0xbfb8aa3b, v18
	global_store_dwordx4 v[156:157], v[134:137], off
	v_exp_f32_e32 v158, v158
	v_mul_f32_e32 v156, 0xbfb8aa3b, v20
	v_mul_f32_e32 v136, 0xbfb8aa3b, v23
	v_exp_f32_e32 v137, v136
	v_mul_f32_e32 v136, 0xbfb8aa3b, v19
	v_add_f32_e32 v134, 1.0, v155
	v_exp_f32_e32 v155, v136
	v_add_f32_e32 v135, 1.0, v158
	v_rcp_f32_e32 v136, v135
	v_add_f32_e32 v135, 1.0, v137
	v_add_f32_e32 v137, 1.0, v155
	v_mul_f32_e32 v155, 0xbfb8aa3b, v24
	v_exp_f32_e32 v155, v155
	v_exp_f32_e32 v157, v156
	v_mul_f32_e32 v158, 0xbfb8aa3b, v21
	v_exp_f32_e32 v159, v158
	v_add_f32_e32 v155, 1.0, v155
	v_rcp_f32_e32 v156, v155
	v_add_f32_e32 v155, 1.0, v157
	v_mul_f32_e32 v157, 0xbfb8aa3b, v25
	v_exp_f32_e32 v157, v157
	v_rcp_f32_e32 v158, v155
	v_rcp_f32_e32 v134, v134
	v_rcp_f32_e32 v135, v135
	v_add_f32_e32 v155, 1.0, v157
	v_rcp_f32_e32 v157, v155
	v_add_f32_e32 v155, 1.0, v159
	v_rcp_f32_e32 v137, v137
	v_rcp_f32_e32 v159, v155
	v_pk_mul_f32 v[134:135], v[22:23], v[134:135]
	v_pk_mul_f32 v[156:157], v[24:25], v[156:157]
	v_pk_mul_f32 v[136:137], v[18:19], v[136:137]
	v_pk_mul_f32 v[158:159], v[20:21], v[158:159]
	v_cvt_pk_bf16_f32 v134, v134, v135
	v_cvt_pk_bf16_f32 v135, v156, v157
	v_cvt_pk_bf16_f32 v136, v136, v137
	v_cvt_pk_bf16_f32 v137, v158, v159
	v_mul_f32_e32 v156, 0xbfb8aa3b, v10
	global_store_dwordx4 v[138:139], v[134:137], off offset:256
	v_mul_f32_e32 v155, 0xbfb8aa3b, v14
	v_exp_f32_e32 v156, v156
	v_mul_f32_e32 v136, 0xbfb8aa3b, v15
	v_exp_f32_e32 v137, v136
	v_mul_f32_e32 v136, 0xbfb8aa3b, v11
	v_exp_f32_e32 v155, v155
	v_exp_f32_e32 v138, v136
	v_add_f32_e32 v135, 1.0, v156
	v_mul_f32_e32 v139, 0xbfb8aa3b, v12
	v_add_f32_e32 v134, 1.0, v155
	v_rcp_f32_e32 v136, v135
	v_add_f32_e32 v135, 1.0, v137
	v_add_f32_e32 v137, 1.0, v138
	v_mul_f32_e32 v138, 0xbfb8aa3b, v16
	v_exp_f32_e32 v139, v139
	v_mul_f32_e32 v155, 0xbfb8aa3b, v17
	v_exp_f32_e32 v138, v138
	v_exp_f32_e32 v155, v155
	v_mul_f32_e32 v156, 0xbfb8aa3b, v13
	v_exp_f32_e32 v157, v156
	v_add_f32_e32 v139, 1.0, v139
	v_add_f32_e32 v138, 1.0, v138
	v_rcp_f32_e32 v156, v139
	v_add_f32_e32 v139, 1.0, v155
	v_rcp_f32_e32 v134, v134
	v_rcp_f32_e32 v135, v135
	v_rcp_f32_e32 v138, v138
	v_rcp_f32_e32 v139, v139
	v_add_f32_e32 v155, 1.0, v157
	v_rcp_f32_e32 v137, v137
	v_rcp_f32_e32 v157, v155
	v_pk_mul_f32 v[134:135], v[14:15], v[134:135]
	v_pk_mul_f32 v[138:139], v[16:17], v[138:139]
	s_mov_b64 s[6:7], 0xb0000
	v_cvt_pk_bf16_f32 v134, v134, v135
	v_cvt_pk_bf16_f32 v135, v138, v139
	v_lshl_add_u64 v[138:139], v[132:133], 0, s[6:7]
	s_mov_b32 s6, 0xb0000
	v_pk_mul_f32 v[136:137], v[10:11], v[136:137]
	v_pk_mul_f32 v[156:157], v[12:13], v[156:157]
	v_add_co_u32_e32 v132, vcc, s6, v132
	v_cvt_pk_bf16_f32 v136, v136, v137
	v_cvt_pk_bf16_f32 v137, v156, v157
	v_addc_co_u32_e32 v133, vcc, 0, v133, vcc
	v_mul_f32_e32 v156, 0xbfb8aa3b, v2
	global_store_dwordx4 v[132:133], v[134:137], off
	v_mul_f32_e32 v155, 0xbfb8aa3b, v6
	v_exp_f32_e32 v156, v156
	v_mul_f32_e32 v134, 0xbfb8aa3b, v7
	v_exp_f32_e32 v135, v134
	v_mul_f32_e32 v134, 0xbfb8aa3b, v3
	v_exp_f32_e32 v155, v155
	v_exp_f32_e32 v136, v134
	v_add_f32_e32 v133, 1.0, v156
	v_mul_f32_e32 v137, 0xbfb8aa3b, v4
	v_add_f32_e32 v132, 1.0, v155
	v_rcp_f32_e32 v134, v133
	v_add_f32_e32 v133, 1.0, v135
	v_add_f32_e32 v135, 1.0, v136
	v_mul_f32_e32 v136, 0xbfb8aa3b, v8
	v_exp_f32_e32 v137, v137
	v_mul_f32_e32 v155, 0xbfb8aa3b, v9
	v_mul_f32_e32 v156, 0xbfb8aa3b, v5
	v_exp_f32_e32 v136, v136
	v_exp_f32_e32 v155, v155
	v_exp_f32_e32 v157, v156
	v_add_f32_e32 v137, 1.0, v137
	v_add_f32_e32 v136, 1.0, v136
	v_rcp_f32_e32 v156, v137
	v_add_f32_e32 v137, 1.0, v155
	v_add_f32_e32 v155, 1.0, v157
	v_rcp_f32_e32 v132, v132
	v_rcp_f32_e32 v133, v133
	v_rcp_f32_e32 v135, v135
	v_rcp_f32_e32 v136, v136
	v_rcp_f32_e32 v137, v137
	v_rcp_f32_e32 v157, v155
	v_pk_mul_f32 v[132:133], v[6:7], v[132:133]
	v_pk_mul_f32 v[134:135], v[2:3], v[134:135]
	v_pk_mul_f32 v[136:137], v[8:9], v[136:137]
	v_pk_mul_f32 v[156:157], v[4:5], v[156:157]
	v_cvt_pk_bf16_f32 v132, v132, v133
	v_cvt_pk_bf16_f32 v133, v136, v137
	v_cvt_pk_bf16_f32 v134, v134, v135
	v_cvt_pk_bf16_f32 v135, v156, v157
	global_store_dwordx4 v[138:139], v[132:135], off offset:256

.LBB0_129:
	s_andn2_b64 vcc, exec, s[6:7]
	s_cbranch_vccnz .LBB0_131
	v_or_b32_e32 v132, 0xffffc800, v163
	v_ashrrev_i32_e32 v155, 31, v154
	v_lshl_add_u32 v136, s76, 8, v132
	v_lshlrev_b64 v[132:133], 12, v[154:155]
	v_mov_b32_e32 v137, v34
	v_lshl_add_u64 v[138:139], s[54:55], 0, v[132:133]
	v_lshlrev_b64 v[136:137], 1, v[136:137]
	v_cvt_pk_bf16_f32 v132, v128, v129
	v_cvt_pk_bf16_f32 v133, v130, v131
	v_cvt_pk_bf16_f32 v134, v124, v125
	v_cvt_pk_bf16_f32 v135, v126, v127
	v_lshl_add_u64 v[138:139], v[138:139], 0, v[136:137]
	global_store_dwordx4 v[138:139], v[132:135], off
	s_mov_b64 s[6:7], 0x80000
	s_nop 0
	v_cvt_pk_bf16_f32 v132, v120, v121
	v_cvt_pk_bf16_f32 v133, v122, v123
	v_cvt_pk_bf16_f32 v134, v116, v117
	v_cvt_pk_bf16_f32 v135, v118, v119
	global_store_dwordx4 v[138:139], v[132:135], off offset:256
	s_nop 1
	v_or_b32_e32 v132, 16, v154
	v_ashrrev_i32_e32 v133, 31, v132
	v_lshlrev_b64 v[132:133], 12, v[132:133]
	v_lshl_add_u64 v[156:157], s[54:55], 0, v[132:133]
	v_cvt_pk_bf16_f32 v132, v112, v113
	v_cvt_pk_bf16_f32 v133, v114, v115
	v_cvt_pk_bf16_f32 v134, v108, v109
	v_cvt_pk_bf16_f32 v135, v110, v111
	v_lshl_add_u64 v[156:157], v[156:157], 0, v[136:137]
	global_store_dwordx4 v[156:157], v[132:135], off
	s_nop 1
	v_cvt_pk_bf16_f32 v132, v104, v105
	v_cvt_pk_bf16_f32 v133, v106, v107
	v_cvt_pk_bf16_f32 v134, v100, v101
	v_cvt_pk_bf16_f32 v135, v102, v103
	global_store_dwordx4 v[156:157], v[132:135], off offset:256
	s_nop 1
	v_or_b32_e32 v132, 32, v154
	v_ashrrev_i32_e32 v133, 31, v132
	v_lshlrev_b64 v[132:133], 12, v[132:133]
	v_lshl_add_u64 v[156:157], s[54:55], 0, v[132:133]
	v_cvt_pk_bf16_f32 v132, v96, v97
	v_cvt_pk_bf16_f32 v133, v98, v99
	v_cvt_pk_bf16_f32 v134, v92, v93
	v_cvt_pk_bf16_f32 v135, v94, v95
	v_lshl_add_u64 v[156:157], v[156:157], 0, v[136:137]
	global_store_dwordx4 v[156:157], v[132:135], off
	s_nop 1
	v_cvt_pk_bf16_f32 v132, v88, v89
	v_cvt_pk_bf16_f32 v133, v90, v91
	v_cvt_pk_bf16_f32 v134, v84, v85
	v_cvt_pk_bf16_f32 v135, v86, v87
	global_store_dwordx4 v[156:157], v[132:135], off offset:256
	s_nop 1
	v_or_b32_e32 v132, 48, v154
	v_ashrrev_i32_e32 v133, 31, v132
	v_lshlrev_b64 v[132:133], 12, v[132:133]
	v_lshl_add_u64 v[156:157], s[54:55], 0, v[132:133]
	v_cvt_pk_bf16_f32 v132, v80, v81
	v_cvt_pk_bf16_f32 v133, v82, v83
	v_cvt_pk_bf16_f32 v134, v76, v77
	v_cvt_pk_bf16_f32 v135, v78, v79
	v_lshl_add_u64 v[136:137], v[156:157], 0, v[136:137]
	global_store_dwordx4 v[136:137], v[132:135], off
	s_nop 1
	v_cvt_pk_bf16_f32 v132, v72, v73
	v_cvt_pk_bf16_f32 v133, v74, v75
	v_cvt_pk_bf16_f32 v134, v68, v69
	v_cvt_pk_bf16_f32 v135, v70, v71
	global_store_dwordx4 v[136:137], v[132:135], off offset:256
	v_lshl_add_u64 v[136:137], v[138:139], 0, s[6:7]
	s_mov_b32 s6, 0x80000
	v_add_co_u32_e32 v156, vcc, s6, v138
	v_cvt_pk_bf16_f32 v132, v64, v65
	v_cvt_pk_bf16_f32 v133, v66, v67
	v_cvt_pk_bf16_f32 v134, v60, v61
	v_cvt_pk_bf16_f32 v135, v62, v63
	v_addc_co_u32_e32 v157, vcc, 0, v139, vcc
	global_store_dwordx4 v[156:157], v[132:135], off
	s_mov_b64 s[6:7], 0x90000
	s_nop 0
	v_cvt_pk_bf16_f32 v132, v56, v57
	v_cvt_pk_bf16_f32 v133, v58, v59
	v_cvt_pk_bf16_f32 v134, v52, v53
	v_cvt_pk_bf16_f32 v135, v54, v55
	global_store_dwordx4 v[136:137], v[132:135], off offset:256
	v_lshl_add_u64 v[136:137], v[138:139], 0, s[6:7]
	s_mov_b32 s6, 0x90000
	v_add_co_u32_e32 v156, vcc, s6, v138
	v_cvt_pk_bf16_f32 v132, v48, v49
	v_cvt_pk_bf16_f32 v133, v50, v51
	v_cvt_pk_bf16_f32 v134, v44, v45
	v_cvt_pk_bf16_f32 v135, v46, v47
	v_addc_co_u32_e32 v157, vcc, 0, v139, vcc
	global_store_dwordx4 v[156:157], v[132:135], off
	s_mov_b64 s[6:7], 0xa0000
	s_nop 0
	v_cvt_pk_bf16_f32 v132, v40, v41
	v_cvt_pk_bf16_f32 v133, v42, v43
	v_cvt_pk_bf16_f32 v134, v36, v37
	v_cvt_pk_bf16_f32 v135, v38, v39
	global_store_dwordx4 v[136:137], v[132:135], off offset:256
	v_lshl_add_u64 v[136:137], v[138:139], 0, s[6:7]
	s_mov_b32 s6, 0xa0000
	v_add_co_u32_e32 v156, vcc, s6, v138
	v_cvt_pk_bf16_f32 v132, v30, v31
	v_cvt_pk_bf16_f32 v133, v32, v33
	v_cvt_pk_bf16_f32 v134, v26, v27
	v_cvt_pk_bf16_f32 v135, v28, v29
	v_addc_co_u32_e32 v157, vcc, 0, v139, vcc
	global_store_dwordx4 v[156:157], v[132:135], off
	s_mov_b64 s[6:7], 0xb0000
	s_nop 0
	v_cvt_pk_bf16_f32 v132, v22, v23
	v_cvt_pk_bf16_f32 v133, v24, v25
	v_cvt_pk_bf16_f32 v134, v18, v19
	v_cvt_pk_bf16_f32 v135, v20, v21
	global_store_dwordx4 v[136:137], v[132:135], off offset:256
	v_lshl_add_u64 v[136:137], v[138:139], 0, s[6:7]
	s_mov_b32 s6, 0xb0000
	v_add_co_u32_e32 v138, vcc, s6, v138
	v_cvt_pk_bf16_f32 v132, v14, v15
	v_cvt_pk_bf16_f32 v133, v16, v17
	v_cvt_pk_bf16_f32 v134, v10, v11
	v_cvt_pk_bf16_f32 v135, v12, v13
	v_addc_co_u32_e32 v139, vcc, 0, v139, vcc
	global_store_dwordx4 v[138:139], v[132:135], off
	s_nop 1
	v_cvt_pk_bf16_f32 v132, v6, v7
	v_cvt_pk_bf16_f32 v133, v8, v9
	v_cvt_pk_bf16_f32 v134, v2, v3
	v_cvt_pk_bf16_f32 v135, v4, v5
	global_store_dwordx4 v[136:137], v[132:135], off offset:256

.LBB0_132:
	s_andn2_b64 vcc, exec, s[6:7]
	s_cbranch_vccnz .LBB0_134
	v_or_b32_e32 v132, 0xffffcc00, v163
	v_ashrrev_i32_e32 v155, 31, v154
	v_lshl_add_u32 v136, s76, 8, v132
	v_lshlrev_b64 v[132:133], 11, v[154:155]
	v_mov_b32_e32 v137, v34
	v_lshl_add_u64 v[138:139], s[52:53], 0, v[132:133]
	v_lshlrev_b64 v[136:137], 1, v[136:137]
	v_cvt_pk_bf16_f32 v132, v128, v129
	v_cvt_pk_bf16_f32 v133, v130, v131
	v_cvt_pk_bf16_f32 v134, v124, v125
	v_cvt_pk_bf16_f32 v135, v126, v127
	v_lshl_add_u64 v[138:139], v[138:139], 0, v[136:137]
	global_store_dwordx4 v[138:139], v[132:135], off
	s_mov_b64 s[6:7], 0x40000
	s_nop 0
	v_cvt_pk_bf16_f32 v132, v120, v121
	v_cvt_pk_bf16_f32 v133, v122, v123
	v_cvt_pk_bf16_f32 v134, v116, v117
	v_cvt_pk_bf16_f32 v135, v118, v119
	global_store_dwordx4 v[138:139], v[132:135], off offset:256
	s_nop 1
	v_or_b32_e32 v132, 16, v154
	v_ashrrev_i32_e32 v133, 31, v132
	v_lshlrev_b64 v[132:133], 11, v[132:133]
	v_lshl_add_u64 v[156:157], s[52:53], 0, v[132:133]
	v_cvt_pk_bf16_f32 v132, v112, v113
	v_cvt_pk_bf16_f32 v133, v114, v115
	v_cvt_pk_bf16_f32 v134, v108, v109
	v_cvt_pk_bf16_f32 v135, v110, v111
	v_lshl_add_u64 v[156:157], v[156:157], 0, v[136:137]
	global_store_dwordx4 v[156:157], v[132:135], off
	s_nop 1
	v_cvt_pk_bf16_f32 v132, v104, v105
	v_cvt_pk_bf16_f32 v133, v106, v107
	v_cvt_pk_bf16_f32 v134, v100, v101
	v_cvt_pk_bf16_f32 v135, v102, v103
	global_store_dwordx4 v[156:157], v[132:135], off offset:256
	s_nop 1
	v_or_b32_e32 v132, 32, v154
	v_ashrrev_i32_e32 v133, 31, v132
	v_lshlrev_b64 v[132:133], 11, v[132:133]
	v_lshl_add_u64 v[156:157], s[52:53], 0, v[132:133]
	v_cvt_pk_bf16_f32 v132, v96, v97
	v_cvt_pk_bf16_f32 v133, v98, v99
	v_cvt_pk_bf16_f32 v134, v92, v93
	v_cvt_pk_bf16_f32 v135, v94, v95
	v_lshl_add_u64 v[156:157], v[156:157], 0, v[136:137]
	global_store_dwordx4 v[156:157], v[132:135], off
	s_nop 1
	v_cvt_pk_bf16_f32 v132, v88, v89
	v_cvt_pk_bf16_f32 v133, v90, v91
	v_cvt_pk_bf16_f32 v134, v84, v85
	v_cvt_pk_bf16_f32 v135, v86, v87
	global_store_dwordx4 v[156:157], v[132:135], off offset:256
	s_nop 1
	v_or_b32_e32 v132, 48, v154
	v_ashrrev_i32_e32 v133, 31, v132
	v_lshlrev_b64 v[132:133], 11, v[132:133]
	v_lshl_add_u64 v[156:157], s[52:53], 0, v[132:133]
	v_cvt_pk_bf16_f32 v132, v80, v81
	v_cvt_pk_bf16_f32 v133, v82, v83
	v_cvt_pk_bf16_f32 v134, v76, v77
	v_cvt_pk_bf16_f32 v135, v78, v79
	v_lshl_add_u64 v[136:137], v[156:157], 0, v[136:137]
	global_store_dwordx4 v[136:137], v[132:135], off
	s_nop 1
	v_cvt_pk_bf16_f32 v132, v72, v73
	v_cvt_pk_bf16_f32 v133, v74, v75
	v_cvt_pk_bf16_f32 v134, v68, v69
	v_cvt_pk_bf16_f32 v135, v70, v71
	global_store_dwordx4 v[136:137], v[132:135], off offset:256
	v_lshl_add_u64 v[136:137], v[138:139], 0, s[6:7]
	s_mov_b32 s6, 0x40000
	v_add_co_u32_e32 v156, vcc, s6, v138
	v_cvt_pk_bf16_f32 v132, v64, v65
	v_cvt_pk_bf16_f32 v133, v66, v67
	v_cvt_pk_bf16_f32 v134, v60, v61
	v_cvt_pk_bf16_f32 v135, v62, v63
	v_addc_co_u32_e32 v157, vcc, 0, v139, vcc
	global_store_dwordx4 v[156:157], v[132:135], off
	s_mov_b64 s[6:7], 0x48000
	s_nop 0
	v_cvt_pk_bf16_f32 v132, v56, v57
	v_cvt_pk_bf16_f32 v133, v58, v59
	v_cvt_pk_bf16_f32 v134, v52, v53
	v_cvt_pk_bf16_f32 v135, v54, v55
	global_store_dwordx4 v[136:137], v[132:135], off offset:256
	v_lshl_add_u64 v[136:137], v[138:139], 0, s[6:7]
	s_mov_b32 s6, 0x48000
	v_add_co_u32_e32 v156, vcc, s6, v138
	v_cvt_pk_bf16_f32 v132, v48, v49
	v_cvt_pk_bf16_f32 v133, v50, v51
	v_cvt_pk_bf16_f32 v134, v44, v45
	v_cvt_pk_bf16_f32 v135, v46, v47
	v_addc_co_u32_e32 v157, vcc, 0, v139, vcc
	global_store_dwordx4 v[156:157], v[132:135], off
	s_mov_b64 s[6:7], 0x50000
	s_nop 0
	v_cvt_pk_bf16_f32 v132, v40, v41
	v_cvt_pk_bf16_f32 v133, v42, v43
	v_cvt_pk_bf16_f32 v134, v36, v37
	v_cvt_pk_bf16_f32 v135, v38, v39
	global_store_dwordx4 v[136:137], v[132:135], off offset:256
	v_lshl_add_u64 v[136:137], v[138:139], 0, s[6:7]
	s_mov_b32 s6, 0x50000
	v_add_co_u32_e32 v156, vcc, s6, v138
	v_cvt_pk_bf16_f32 v132, v30, v31
	v_cvt_pk_bf16_f32 v133, v32, v33
	v_cvt_pk_bf16_f32 v134, v26, v27
	v_cvt_pk_bf16_f32 v135, v28, v29
	v_addc_co_u32_e32 v157, vcc, 0, v139, vcc
	global_store_dwordx4 v[156:157], v[132:135], off
	s_mov_b64 s[6:7], 0x58000
	s_nop 0
	v_cvt_pk_bf16_f32 v132, v22, v23
	v_cvt_pk_bf16_f32 v133, v24, v25
	v_cvt_pk_bf16_f32 v134, v18, v19
	v_cvt_pk_bf16_f32 v135, v20, v21
	global_store_dwordx4 v[136:137], v[132:135], off offset:256
	v_lshl_add_u64 v[136:137], v[138:139], 0, s[6:7]
	s_mov_b32 s6, 0x58000
	v_add_co_u32_e32 v138, vcc, s6, v138
	v_cvt_pk_bf16_f32 v132, v14, v15
	v_cvt_pk_bf16_f32 v133, v16, v17
	v_cvt_pk_bf16_f32 v134, v10, v11
	v_cvt_pk_bf16_f32 v135, v12, v13
	v_addc_co_u32_e32 v139, vcc, 0, v139, vcc
	global_store_dwordx4 v[138:139], v[132:135], off
	s_nop 1
	v_cvt_pk_bf16_f32 v132, v6, v7
	v_cvt_pk_bf16_f32 v133, v8, v9
	v_cvt_pk_bf16_f32 v134, v2, v3
	v_cvt_pk_bf16_f32 v135, v4, v5
	global_store_dwordx4 v[136:137], v[132:135], off offset:256

.LBB0_135:
	s_andn2_b64 vcc, exec, s[6:7]
	s_cbranch_vccnz .LBB0_137
	v_ashrrev_i32_e32 v155, 31, v154
	v_lshlrev_b64 v[134:135], 11, v[154:155]
	s_mov_b32 s8, 0x3d800000
	v_lshl_add_u32 v132, s76, 8, v1
	v_lshl_add_u64 v[138:139], s[50:51], 0, v[134:135]
	v_pk_mul_f32 v[134:135], v[128:129], s[8:9] op_sel_hi:[1,0]
	v_pk_mul_f32 v[156:157], v[130:131], s[8:9] op_sel_hi:[1,0]
	v_mov_b32_e32 v133, v34
	v_pk_mul_f32 v[136:137], v[124:125], s[8:9] op_sel_hi:[1,0]
	v_pk_mul_f32 v[158:159], v[126:127], s[8:9] op_sel_hi:[1,0]
	v_cvt_pk_bf16_f32 v134, v134, v135
	v_cvt_pk_bf16_f32 v135, v156, v157
	v_lshlrev_b64 v[156:157], 1, v[132:133]
	v_cvt_pk_bf16_f32 v136, v136, v137
	v_cvt_pk_bf16_f32 v137, v158, v159
	v_lshl_add_u64 v[132:133], v[138:139], 0, v[156:157]
	global_store_dwordx4 v[132:133], v[134:137], off
	v_pk_mul_f32 v[138:139], v[122:123], s[8:9] op_sel_hi:[1,0]
	v_pk_mul_f32 v[158:159], v[118:119], s[8:9] op_sel_hi:[1,0]
	v_pk_mul_f32 v[134:135], v[120:121], s[8:9] op_sel_hi:[1,0]
	v_pk_mul_f32 v[136:137], v[116:117], s[8:9] op_sel_hi:[1,0]
	v_cvt_pk_bf16_f32 v134, v134, v135
	v_cvt_pk_bf16_f32 v135, v138, v139
	v_cvt_pk_bf16_f32 v136, v136, v137
	v_cvt_pk_bf16_f32 v137, v158, v159
	global_store_dwordx4 v[132:133], v[134:137], off offset:256
	v_pk_mul_f32 v[158:159], v[114:115], s[8:9] op_sel_hi:[1,0]
	v_pk_mul_f32 v[160:161], v[110:111], s[8:9] op_sel_hi:[1,0]
	v_or_b32_e32 v134, 16, v154
	v_ashrrev_i32_e32 v135, 31, v134
	v_lshlrev_b64 v[134:135], 11, v[134:135]
	v_lshl_add_u64 v[138:139], s[50:51], 0, v[134:135]
	v_pk_mul_f32 v[134:135], v[112:113], s[8:9] op_sel_hi:[1,0]
	v_pk_mul_f32 v[136:137], v[108:109], s[8:9] op_sel_hi:[1,0]
	v_cvt_pk_bf16_f32 v134, v134, v135
	v_cvt_pk_bf16_f32 v135, v158, v159
	v_cvt_pk_bf16_f32 v136, v136, v137
	v_cvt_pk_bf16_f32 v137, v160, v161
	v_lshl_add_u64 v[138:139], v[138:139], 0, v[156:157]
	global_store_dwordx4 v[138:139], v[134:137], off
	v_pk_mul_f32 v[158:159], v[106:107], s[8:9] op_sel_hi:[1,0]
	v_pk_mul_f32 v[160:161], v[102:103], s[8:9] op_sel_hi:[1,0]
	v_pk_mul_f32 v[134:135], v[104:105], s[8:9] op_sel_hi:[1,0]
	v_pk_mul_f32 v[136:137], v[100:101], s[8:9] op_sel_hi:[1,0]
	v_cvt_pk_bf16_f32 v134, v134, v135
	v_cvt_pk_bf16_f32 v135, v158, v159
	v_cvt_pk_bf16_f32 v136, v136, v137
	v_cvt_pk_bf16_f32 v137, v160, v161
	global_store_dwordx4 v[138:139], v[134:137], off offset:256
	v_pk_mul_f32 v[158:159], v[98:99], s[8:9] op_sel_hi:[1,0]
	v_pk_mul_f32 v[160:161], v[94:95], s[8:9] op_sel_hi:[1,0]
	v_or_b32_e32 v134, 32, v154
	v_ashrrev_i32_e32 v135, 31, v134
	v_lshlrev_b64 v[134:135], 11, v[134:135]
	v_lshl_add_u64 v[138:139], s[50:51], 0, v[134:135]
	v_pk_mul_f32 v[134:135], v[96:97], s[8:9] op_sel_hi:[1,0]
	v_pk_mul_f32 v[136:137], v[92:93], s[8:9] op_sel_hi:[1,0]
	v_cvt_pk_bf16_f32 v134, v134, v135
	v_cvt_pk_bf16_f32 v135, v158, v159
	v_cvt_pk_bf16_f32 v136, v136, v137
	v_cvt_pk_bf16_f32 v137, v160, v161
	v_lshl_add_u64 v[138:139], v[138:139], 0, v[156:157]
	global_store_dwordx4 v[138:139], v[134:137], off
	v_pk_mul_f32 v[158:159], v[90:91], s[8:9] op_sel_hi:[1,0]
	v_pk_mul_f32 v[160:161], v[86:87], s[8:9] op_sel_hi:[1,0]
	v_pk_mul_f32 v[134:135], v[88:89], s[8:9] op_sel_hi:[1,0]
	v_pk_mul_f32 v[136:137], v[84:85], s[8:9] op_sel_hi:[1,0]
	v_cvt_pk_bf16_f32 v134, v134, v135
	v_cvt_pk_bf16_f32 v135, v158, v159
	v_cvt_pk_bf16_f32 v136, v136, v137
	v_cvt_pk_bf16_f32 v137, v160, v161
	global_store_dwordx4 v[138:139], v[134:137], off offset:256
	v_pk_mul_f32 v[158:159], v[82:83], s[8:9] op_sel_hi:[1,0]
	v_pk_mul_f32 v[160:161], v[78:79], s[8:9] op_sel_hi:[1,0]
	v_or_b32_e32 v134, 48, v154
	v_ashrrev_i32_e32 v135, 31, v134
	v_lshlrev_b64 v[134:135], 11, v[134:135]
	v_lshl_add_u64 v[138:139], s[50:51], 0, v[134:135]
	v_pk_mul_f32 v[134:135], v[80:81], s[8:9] op_sel_hi:[1,0]
	v_pk_mul_f32 v[136:137], v[76:77], s[8:9] op_sel_hi:[1,0]
	v_cvt_pk_bf16_f32 v134, v134, v135
	v_cvt_pk_bf16_f32 v135, v158, v159
	v_cvt_pk_bf16_f32 v136, v136, v137
	v_cvt_pk_bf16_f32 v137, v160, v161
	v_lshl_add_u64 v[138:139], v[138:139], 0, v[156:157]
	global_store_dwordx4 v[138:139], v[134:137], off
	v_pk_mul_f32 v[156:157], v[74:75], s[8:9] op_sel_hi:[1,0]
	v_pk_mul_f32 v[158:159], v[70:71], s[8:9] op_sel_hi:[1,0]
	v_pk_mul_f32 v[134:135], v[72:73], s[8:9] op_sel_hi:[1,0]
	v_pk_mul_f32 v[136:137], v[68:69], s[8:9] op_sel_hi:[1,0]
	v_cvt_pk_bf16_f32 v134, v134, v135
	v_cvt_pk_bf16_f32 v135, v156, v157
	v_cvt_pk_bf16_f32 v136, v136, v137
	v_cvt_pk_bf16_f32 v137, v158, v159
	global_store_dwordx4 v[138:139], v[134:137], off offset:256
	v_pk_mul_f32 v[138:139], v[66:67], s[8:9] op_sel_hi:[1,0]
	s_mov_b64 s[6:7], 0x40000
	v_pk_mul_f32 v[134:135], v[64:65], s[8:9] op_sel_hi:[1,0]
	v_pk_mul_f32 v[136:137], v[60:61], s[8:9] op_sel_hi:[1,0]
	v_pk_mul_f32 v[156:157], v[62:63], s[8:9] op_sel_hi:[1,0]
	v_cvt_pk_bf16_f32 v134, v134, v135
	v_cvt_pk_bf16_f32 v135, v138, v139
	v_lshl_add_u64 v[138:139], v[132:133], 0, s[6:7]
	s_mov_b32 s6, 0x40000
	v_cvt_pk_bf16_f32 v136, v136, v137
	v_cvt_pk_bf16_f32 v137, v156, v157
	v_add_co_u32_e32 v156, vcc, s6, v132
	v_pk_mul_f32 v[158:159], v[54:55], s[8:9] op_sel_hi:[1,0]
	s_nop 0
	v_addc_co_u32_e32 v157, vcc, 0, v133, vcc
	global_store_dwordx4 v[156:157], v[134:137], off
	v_pk_mul_f32 v[156:157], v[58:59], s[8:9] op_sel_hi:[1,0]
	s_mov_b64 s[6:7], 0x48000
	v_pk_mul_f32 v[134:135], v[56:57], s[8:9] op_sel_hi:[1,0]
	v_pk_mul_f32 v[136:137], v[52:53], s[8:9] op_sel_hi:[1,0]
	v_cvt_pk_bf16_f32 v134, v134, v135
	v_cvt_pk_bf16_f32 v135, v156, v157
	v_cvt_pk_bf16_f32 v136, v136, v137
	v_cvt_pk_bf16_f32 v137, v158, v159
	global_store_dwordx4 v[138:139], v[134:137], off offset:256
	v_pk_mul_f32 v[138:139], v[50:51], s[8:9] op_sel_hi:[1,0]
	v_pk_mul_f32 v[156:157], v[46:47], s[8:9] op_sel_hi:[1,0]
	v_pk_mul_f32 v[134:135], v[48:49], s[8:9] op_sel_hi:[1,0]
	v_pk_mul_f32 v[136:137], v[44:45], s[8:9] op_sel_hi:[1,0]
	v_cvt_pk_bf16_f32 v134, v134, v135
	v_cvt_pk_bf16_f32 v135, v138, v139
	v_lshl_add_u64 v[138:139], v[132:133], 0, s[6:7]
	s_mov_b32 s6, 0x48000
	v_cvt_pk_bf16_f32 v136, v136, v137
	v_cvt_pk_bf16_f32 v137, v156, v157
	v_add_co_u32_e32 v156, vcc, s6, v132
	v_pk_mul_f32 v[158:159], v[38:39], s[8:9] op_sel_hi:[1,0]
	s_nop 0
	v_addc_co_u32_e32 v157, vcc, 0, v133, vcc
	global_store_dwordx4 v[156:157], v[134:137], off
	v_pk_mul_f32 v[156:157], v[42:43], s[8:9] op_sel_hi:[1,0]
	s_mov_b64 s[6:7], 0x50000
	v_pk_mul_f32 v[134:135], v[40:41], s[8:9] op_sel_hi:[1,0]
	v_pk_mul_f32 v[136:137], v[36:37], s[8:9] op_sel_hi:[1,0]
	v_cvt_pk_bf16_f32 v134, v134, v135
	v_cvt_pk_bf16_f32 v135, v156, v157
	v_cvt_pk_bf16_f32 v136, v136, v137
	v_cvt_pk_bf16_f32 v137, v158, v159
	global_store_dwordx4 v[138:139], v[134:137], off offset:256
	v_pk_mul_f32 v[138:139], v[32:33], s[8:9] op_sel_hi:[1,0]
	v_pk_mul_f32 v[156:157], v[28:29], s[8:9] op_sel_hi:[1,0]
	v_pk_mul_f32 v[134:135], v[30:31], s[8:9] op_sel_hi:[1,0]
	v_pk_mul_f32 v[136:137], v[26:27], s[8:9] op_sel_hi:[1,0]
	v_cvt_pk_bf16_f32 v134, v134, v135
	v_cvt_pk_bf16_f32 v135, v138, v139
	v_lshl_add_u64 v[138:139], v[132:133], 0, s[6:7]
	s_mov_b32 s6, 0x50000
	v_cvt_pk_bf16_f32 v136, v136, v137
	v_cvt_pk_bf16_f32 v137, v156, v157
	v_add_co_u32_e32 v156, vcc, s6, v132
	v_pk_mul_f32 v[158:159], v[20:21], s[8:9] op_sel_hi:[1,0]
	s_nop 0
	v_addc_co_u32_e32 v157, vcc, 0, v133, vcc
	global_store_dwordx4 v[156:157], v[134:137], off
	v_pk_mul_f32 v[156:157], v[24:25], s[8:9] op_sel_hi:[1,0]
	s_mov_b64 s[6:7], 0x58000
	v_pk_mul_f32 v[134:135], v[22:23], s[8:9] op_sel_hi:[1,0]
	v_pk_mul_f32 v[136:137], v[18:19], s[8:9] op_sel_hi:[1,0]
	v_cvt_pk_bf16_f32 v134, v134, v135
	v_cvt_pk_bf16_f32 v135, v156, v157
	v_cvt_pk_bf16_f32 v136, v136, v137
	v_cvt_pk_bf16_f32 v137, v158, v159
	global_store_dwordx4 v[138:139], v[134:137], off offset:256
	v_pk_mul_f32 v[138:139], v[16:17], s[8:9] op_sel_hi:[1,0]
	v_pk_mul_f32 v[156:157], v[12:13], s[8:9] op_sel_hi:[1,0]
	v_pk_mul_f32 v[134:135], v[14:15], s[8:9] op_sel_hi:[1,0]
	v_pk_mul_f32 v[136:137], v[10:11], s[8:9] op_sel_hi:[1,0]
	v_cvt_pk_bf16_f32 v134, v134, v135
	v_cvt_pk_bf16_f32 v135, v138, v139
	v_lshl_add_u64 v[138:139], v[132:133], 0, s[6:7]
	s_mov_b32 s6, 0x58000
	v_add_co_u32_e32 v132, vcc, s6, v132
	v_cvt_pk_bf16_f32 v136, v136, v137
	v_cvt_pk_bf16_f32 v137, v156, v157
	v_addc_co_u32_e32 v133, vcc, 0, v133, vcc
	global_store_dwordx4 v[132:133], v[134:137], off
	v_pk_mul_f32 v[132:133], v[6:7], s[8:9] op_sel_hi:[1,0]
	v_pk_mul_f32 v[156:157], v[4:5], s[8:9] op_sel_hi:[1,0]
	v_pk_mul_f32 v[134:135], v[2:3], s[8:9] op_sel_hi:[1,0]
	v_pk_mul_f32 v[136:137], v[8:9], s[8:9] op_sel_hi:[1,0]
	v_cvt_pk_bf16_f32 v132, v132, v133
	v_cvt_pk_bf16_f32 v133, v136, v137
	v_cvt_pk_bf16_f32 v134, v134, v135
	v_cvt_pk_bf16_f32 v135, v156, v157
	global_store_dwordx4 v[138:139], v[132:135], off offset:256

.LBB0_138:
	s_andn2_b64 vcc, exec, s[6:7]
	s_cbranch_vccnz .LBB0_140
	v_mul_f32_e32 v133, 0xbfb8aa3b, v128
	v_exp_f32_e32 v133, v133
	v_mul_f32_e32 v136, 0xbfb8aa3b, v124
	v_exp_f32_e32 v136, v136
	v_ashrrev_i32_e32 v155, 31, v154
	v_lshlrev_b64 v[134:135], 12, v[154:155]
	v_lshl_add_u64 v[156:157], s[48:49], 0, v[134:135]
	v_add_f32_e32 v133, 1.0, v133
	v_mul_f32_e32 v135, 0xbfb8aa3b, v129
	v_rcp_f32_e32 v134, v133
	v_add_f32_e32 v133, 1.0, v136
	v_exp_f32_e32 v135, v135
	v_mul_f32_e32 v136, 0xbfb8aa3b, v125
	v_exp_f32_e32 v137, v136
	v_rcp_f32_e32 v136, v133
	v_add_f32_e32 v133, 1.0, v135
	v_rcp_f32_e32 v135, v133
	v_add_f32_e32 v133, 1.0, v137
	v_mul_f32_e32 v137, 0xbfb8aa3b, v130
	v_exp_f32_e32 v138, v137
	v_mul_f32_e32 v137, 0xbfb8aa3b, v126
	v_exp_f32_e32 v139, v137
	v_rcp_f32_e32 v137, v133
	v_add_f32_e32 v133, 1.0, v138
	v_rcp_f32_e32 v138, v133
	v_add_f32_e32 v133, 1.0, v139
	v_mul_f32_e32 v139, 0xbfb8aa3b, v131
	v_exp_f32_e32 v139, v139
	v_mul_f32_e32 v155, 0xbfb8aa3b, v127
	v_exp_f32_e32 v155, v155
	v_rcp_f32_e32 v158, v133
	v_add_f32_e32 v133, 1.0, v139
	v_rcp_f32_e32 v139, v133
	v_add_f32_e32 v133, 1.0, v155
	v_rcp_f32_e32 v159, v133
	v_lshl_add_u32 v132, s76, 8, v218
	v_pk_mul_f32 v[134:135], v[128:129], v[134:135]
	v_mov_b32_e32 v133, v34
	v_mul_f32_e32 v155, 0xbfb8aa3b, v120
	v_pk_mul_f32 v[160:161], v[124:125], v[136:137]
	v_pk_mul_f32 v[138:139], v[130:131], v[138:139]
	v_pk_mul_f32 v[158:159], v[126:127], v[158:159]
	v_cvt_pk_bf16_f32 v136, v134, v135
	v_lshlrev_b64 v[134:135], 1, v[132:133]
	v_exp_f32_e32 v155, v155
	v_cvt_pk_bf16_f32 v137, v138, v139
	v_cvt_pk_bf16_f32 v138, v160, v161
	v_cvt_pk_bf16_f32 v139, v158, v159
	v_lshl_add_u64 v[132:133], v[156:157], 0, v[134:135]
	v_mul_f32_e32 v156, 0xbfb8aa3b, v116
	global_store_dwordx4 v[132:133], v[136:139], off
	v_exp_f32_e32 v156, v156
	v_mul_f32_e32 v158, 0xbfb8aa3b, v119
	v_mul_f32_e32 v138, 0xbfb8aa3b, v121
	v_exp_f32_e32 v139, v138
	v_mul_f32_e32 v138, 0xbfb8aa3b, v117
	v_add_f32_e32 v136, 1.0, v155
	v_exp_f32_e32 v155, v138
	v_add_f32_e32 v137, 1.0, v156
	v_rcp_f32_e32 v138, v137
	v_add_f32_e32 v137, 1.0, v139
	v_add_f32_e32 v139, 1.0, v155
	v_mul_f32_e32 v155, 0xbfb8aa3b, v122
	v_exp_f32_e32 v155, v155
	v_mul_f32_e32 v156, 0xbfb8aa3b, v118
	v_exp_f32_e32 v157, v156
	v_exp_f32_e32 v159, v158
	v_add_f32_e32 v155, 1.0, v155
	v_rcp_f32_e32 v156, v155
	v_add_f32_e32 v155, 1.0, v157
	v_mul_f32_e32 v157, 0xbfb8aa3b, v123
	v_exp_f32_e32 v157, v157
	v_rcp_f32_e32 v158, v155
	v_rcp_f32_e32 v136, v136
	v_rcp_f32_e32 v137, v137
	v_add_f32_e32 v155, 1.0, v157
	v_rcp_f32_e32 v157, v155
	v_add_f32_e32 v155, 1.0, v159
	v_rcp_f32_e32 v139, v139
	v_rcp_f32_e32 v159, v155
	v_pk_mul_f32 v[136:137], v[120:121], v[136:137]
	v_pk_mul_f32 v[156:157], v[122:123], v[156:157]
	v_pk_mul_f32 v[138:139], v[116:117], v[138:139]
	v_pk_mul_f32 v[158:159], v[118:119], v[158:159]
	v_cvt_pk_bf16_f32 v136, v136, v137
	v_cvt_pk_bf16_f32 v137, v156, v157
	v_cvt_pk_bf16_f32 v138, v138, v139
	v_cvt_pk_bf16_f32 v139, v158, v159
	global_store_dwordx4 v[132:133], v[136:139], off offset:256
	v_mul_f32_e32 v158, 0xbfb8aa3b, v110
	v_exp_f32_e32 v159, v158
	v_mul_f32_e32 v138, 0xbfb8aa3b, v112
	v_exp_f32_e32 v138, v138
	v_mul_f32_e32 v139, 0xbfb8aa3b, v108
	v_or_b32_e32 v136, 16, v154
	v_exp_f32_e32 v139, v139
	v_ashrrev_i32_e32 v137, 31, v136
	v_lshlrev_b64 v[136:137], 12, v[136:137]
	v_lshl_add_u64 v[156:157], s[48:49], 0, v[136:137]
	v_add_f32_e32 v136, 1.0, v138
	v_mul_f32_e32 v138, 0xbfb8aa3b, v113
	v_add_f32_e32 v137, 1.0, v139
	v_exp_f32_e32 v139, v138
	v_mul_f32_e32 v138, 0xbfb8aa3b, v109
	v_exp_f32_e32 v155, v138
	v_rcp_f32_e32 v138, v137
	v_add_f32_e32 v137, 1.0, v139
	v_mul_f32_e32 v160, 0xbfb8aa3b, v111
	v_add_f32_e32 v139, 1.0, v155
	v_mul_f32_e32 v155, 0xbfb8aa3b, v114
	v_exp_f32_e32 v155, v155
	v_exp_f32_e32 v161, v160
	v_rcp_f32_e32 v136, v136
	v_rcp_f32_e32 v137, v137
	v_add_f32_e32 v155, 1.0, v155
	v_rcp_f32_e32 v158, v155
	v_add_f32_e32 v155, 1.0, v159
	v_mul_f32_e32 v159, 0xbfb8aa3b, v115
	v_exp_f32_e32 v159, v159
	v_rcp_f32_e32 v160, v155
	v_rcp_f32_e32 v139, v139
	v_pk_mul_f32 v[136:137], v[112:113], v[136:137]
	v_add_f32_e32 v155, 1.0, v159
	v_rcp_f32_e32 v159, v155
	v_add_f32_e32 v155, 1.0, v161
	v_rcp_f32_e32 v161, v155
	v_mul_f32_e32 v155, 0xbfb8aa3b, v104
	v_pk_mul_f32 v[138:139], v[108:109], v[138:139]
	v_pk_mul_f32 v[158:159], v[114:115], v[158:159]
	v_pk_mul_f32 v[160:161], v[110:111], v[160:161]
	v_exp_f32_e32 v155, v155
	v_cvt_pk_bf16_f32 v136, v136, v137
	v_cvt_pk_bf16_f32 v137, v158, v159
	v_cvt_pk_bf16_f32 v138, v138, v139
	v_cvt_pk_bf16_f32 v139, v160, v161
	v_lshl_add_u64 v[156:157], v[156:157], 0, v[134:135]
	v_mul_f32_e32 v158, 0xbfb8aa3b, v100
	global_store_dwordx4 v[156:157], v[136:139], off
	v_exp_f32_e32 v158, v158
	v_mul_f32_e32 v160, 0xbfb8aa3b, v103
	v_mul_f32_e32 v138, 0xbfb8aa3b, v105
	v_exp_f32_e32 v139, v138
	v_mul_f32_e32 v138, 0xbfb8aa3b, v101
	v_add_f32_e32 v136, 1.0, v155
	v_exp_f32_e32 v155, v138
	v_add_f32_e32 v137, 1.0, v158
	v_rcp_f32_e32 v138, v137
	v_add_f32_e32 v137, 1.0, v139
	v_add_f32_e32 v139, 1.0, v155
	v_mul_f32_e32 v155, 0xbfb8aa3b, v106
	v_exp_f32_e32 v155, v155
	v_mul_f32_e32 v158, 0xbfb8aa3b, v102
	v_exp_f32_e32 v159, v158
	v_exp_f32_e32 v161, v160
	v_add_f32_e32 v155, 1.0, v155
	v_rcp_f32_e32 v158, v155
	v_add_f32_e32 v155, 1.0, v159
	v_mul_f32_e32 v159, 0xbfb8aa3b, v107
	v_exp_f32_e32 v159, v159
	v_rcp_f32_e32 v160, v155
	v_rcp_f32_e32 v136, v136
	v_rcp_f32_e32 v137, v137
	v_add_f32_e32 v155, 1.0, v159
	v_rcp_f32_e32 v159, v155
	v_add_f32_e32 v155, 1.0, v161
	v_rcp_f32_e32 v139, v139
	v_rcp_f32_e32 v161, v155
	v_pk_mul_f32 v[136:137], v[104:105], v[136:137]
	v_pk_mul_f32 v[158:159], v[106:107], v[158:159]
	v_pk_mul_f32 v[138:139], v[100:101], v[138:139]
	v_pk_mul_f32 v[160:161], v[102:103], v[160:161]
	v_cvt_pk_bf16_f32 v136, v136, v137
	v_cvt_pk_bf16_f32 v137, v158, v159
	v_cvt_pk_bf16_f32 v138, v138, v139
	v_cvt_pk_bf16_f32 v139, v160, v161
	global_store_dwordx4 v[156:157], v[136:139], off offset:256
	v_mul_f32_e32 v158, 0xbfb8aa3b, v94
	v_exp_f32_e32 v159, v158
	v_mul_f32_e32 v138, 0xbfb8aa3b, v96
	v_exp_f32_e32 v138, v138
	v_mul_f32_e32 v139, 0xbfb8aa3b, v92
	v_or_b32_e32 v136, 32, v154
	v_exp_f32_e32 v139, v139
	v_ashrrev_i32_e32 v137, 31, v136
	v_lshlrev_b64 v[136:137], 12, v[136:137]
	v_lshl_add_u64 v[156:157], s[48:49], 0, v[136:137]
	v_add_f32_e32 v136, 1.0, v138
	v_mul_f32_e32 v138, 0xbfb8aa3b, v97
	v_add_f32_e32 v137, 1.0, v139
	v_exp_f32_e32 v139, v138
	v_mul_f32_e32 v138, 0xbfb8aa3b, v93
	v_exp_f32_e32 v155, v138
	v_rcp_f32_e32 v138, v137
	v_add_f32_e32 v137, 1.0, v139
	v_mul_f32_e32 v160, 0xbfb8aa3b, v95
	v_add_f32_e32 v139, 1.0, v155
	v_mul_f32_e32 v155, 0xbfb8aa3b, v98
	v_exp_f32_e32 v155, v155
	v_exp_f32_e32 v161, v160
	v_rcp_f32_e32 v136, v136
	v_rcp_f32_e32 v137, v137
	v_add_f32_e32 v155, 1.0, v155
	v_rcp_f32_e32 v158, v155
	v_add_f32_e32 v155, 1.0, v159
	v_mul_f32_e32 v159, 0xbfb8aa3b, v99
	v_exp_f32_e32 v159, v159
	v_rcp_f32_e32 v160, v155
	v_rcp_f32_e32 v139, v139
	v_pk_mul_f32 v[136:137], v[96:97], v[136:137]
	v_add_f32_e32 v155, 1.0, v159
	v_rcp_f32_e32 v159, v155
	v_add_f32_e32 v155, 1.0, v161
	v_rcp_f32_e32 v161, v155
	v_mul_f32_e32 v155, 0xbfb8aa3b, v88
	v_pk_mul_f32 v[138:139], v[92:93], v[138:139]
	v_pk_mul_f32 v[158:159], v[98:99], v[158:159]
	v_pk_mul_f32 v[160:161], v[94:95], v[160:161]
	v_exp_f32_e32 v155, v155
	v_cvt_pk_bf16_f32 v136, v136, v137
	v_cvt_pk_bf16_f32 v137, v158, v159
	v_cvt_pk_bf16_f32 v138, v138, v139
	v_cvt_pk_bf16_f32 v139, v160, v161
	v_lshl_add_u64 v[156:157], v[156:157], 0, v[134:135]
	v_mul_f32_e32 v158, 0xbfb8aa3b, v84
	global_store_dwordx4 v[156:157], v[136:139], off
	v_exp_f32_e32 v158, v158
	v_mul_f32_e32 v160, 0xbfb8aa3b, v87
	v_mul_f32_e32 v138, 0xbfb8aa3b, v89
	v_exp_f32_e32 v139, v138
	v_mul_f32_e32 v138, 0xbfb8aa3b, v85
	v_add_f32_e32 v136, 1.0, v155
	v_exp_f32_e32 v155, v138
	v_add_f32_e32 v137, 1.0, v158
	v_rcp_f32_e32 v138, v137
	v_add_f32_e32 v137, 1.0, v139
	v_add_f32_e32 v139, 1.0, v155
	v_mul_f32_e32 v155, 0xbfb8aa3b, v90
	v_exp_f32_e32 v155, v155
	v_mul_f32_e32 v158, 0xbfb8aa3b, v86
	v_exp_f32_e32 v159, v158
	v_exp_f32_e32 v161, v160
	v_add_f32_e32 v155, 1.0, v155
	v_rcp_f32_e32 v158, v155
	v_add_f32_e32 v155, 1.0, v159
	v_mul_f32_e32 v159, 0xbfb8aa3b, v91
	v_exp_f32_e32 v159, v159
	v_rcp_f32_e32 v160, v155
	v_rcp_f32_e32 v136, v136
	v_rcp_f32_e32 v137, v137
	v_add_f32_e32 v155, 1.0, v159
	v_rcp_f32_e32 v159, v155
	v_add_f32_e32 v155, 1.0, v161
	v_rcp_f32_e32 v139, v139
	v_rcp_f32_e32 v161, v155
	v_pk_mul_f32 v[136:137], v[88:89], v[136:137]
	v_pk_mul_f32 v[158:159], v[90:91], v[158:159]
	v_pk_mul_f32 v[138:139], v[84:85], v[138:139]
	v_pk_mul_f32 v[160:161], v[86:87], v[160:161]
	v_cvt_pk_bf16_f32 v136, v136, v137
	v_cvt_pk_bf16_f32 v137, v158, v159
	v_cvt_pk_bf16_f32 v138, v138, v139
	v_cvt_pk_bf16_f32 v139, v160, v161
	global_store_dwordx4 v[156:157], v[136:139], off offset:256
	v_mul_f32_e32 v158, 0xbfb8aa3b, v78
	v_exp_f32_e32 v159, v158
	v_mul_f32_e32 v138, 0xbfb8aa3b, v80
	v_exp_f32_e32 v138, v138
	v_mul_f32_e32 v139, 0xbfb8aa3b, v76
	v_or_b32_e32 v136, 48, v154
	v_exp_f32_e32 v139, v139
	v_ashrrev_i32_e32 v137, 31, v136
	v_lshlrev_b64 v[136:137], 12, v[136:137]
	v_lshl_add_u64 v[156:157], s[48:49], 0, v[136:137]
	v_add_f32_e32 v136, 1.0, v138
	v_mul_f32_e32 v138, 0xbfb8aa3b, v81
	v_add_f32_e32 v137, 1.0, v139
	v_exp_f32_e32 v139, v138
	v_mul_f32_e32 v138, 0xbfb8aa3b, v77
	v_exp_f32_e32 v155, v138
	v_rcp_f32_e32 v138, v137
	v_add_f32_e32 v137, 1.0, v139
	v_mul_f32_e32 v160, 0xbfb8aa3b, v79
	v_add_f32_e32 v139, 1.0, v155
	v_mul_f32_e32 v155, 0xbfb8aa3b, v82
	v_exp_f32_e32 v155, v155
	v_exp_f32_e32 v161, v160
	v_rcp_f32_e32 v136, v136
	v_rcp_f32_e32 v137, v137
	v_add_f32_e32 v155, 1.0, v155
	v_rcp_f32_e32 v158, v155
	v_add_f32_e32 v155, 1.0, v159
	v_mul_f32_e32 v159, 0xbfb8aa3b, v83
	v_exp_f32_e32 v159, v159
	v_rcp_f32_e32 v160, v155
	v_rcp_f32_e32 v139, v139
	v_pk_mul_f32 v[136:137], v[80:81], v[136:137]
	v_add_f32_e32 v155, 1.0, v159
	v_rcp_f32_e32 v159, v155
	v_add_f32_e32 v155, 1.0, v161
	v_rcp_f32_e32 v161, v155
	v_pk_mul_f32 v[138:139], v[76:77], v[138:139]
	v_pk_mul_f32 v[158:159], v[82:83], v[158:159]
	v_cvt_pk_bf16_f32 v136, v136, v137
	v_pk_mul_f32 v[160:161], v[78:79], v[160:161]
	v_cvt_pk_bf16_f32 v137, v158, v159
	v_cvt_pk_bf16_f32 v138, v138, v139
	v_cvt_pk_bf16_f32 v139, v160, v161
	v_lshl_add_u64 v[156:157], v[156:157], 0, v[134:135]
	v_mul_f32_e32 v135, 0xbfb8aa3b, v68
	global_store_dwordx4 v[156:157], v[136:139], off
	v_exp_f32_e32 v135, v135
	v_mul_f32_e32 v134, 0xbfb8aa3b, v72
	v_mul_f32_e32 v136, 0xbfb8aa3b, v73
	v_exp_f32_e32 v137, v136
	v_mul_f32_e32 v136, 0xbfb8aa3b, v69
	v_exp_f32_e32 v138, v136
	v_add_f32_e32 v135, 1.0, v135
	v_mul_f32_e32 v139, 0xbfb8aa3b, v70
	v_rcp_f32_e32 v136, v135
	v_add_f32_e32 v135, 1.0, v137
	v_add_f32_e32 v137, 1.0, v138
	v_mul_f32_e32 v138, 0xbfb8aa3b, v74
	v_exp_f32_e32 v139, v139
	v_mul_f32_e32 v155, 0xbfb8aa3b, v75
	v_exp_f32_e32 v134, v134
	v_exp_f32_e32 v138, v138
	v_exp_f32_e32 v155, v155
	v_mul_f32_e32 v158, 0xbfb8aa3b, v71
	v_exp_f32_e32 v159, v158
	v_add_f32_e32 v139, 1.0, v139
	v_add_f32_e32 v134, 1.0, v134
	v_add_f32_e32 v138, 1.0, v138
	v_rcp_f32_e32 v158, v139
	v_add_f32_e32 v139, 1.0, v155
	v_rcp_f32_e32 v134, v134
	v_rcp_f32_e32 v135, v135
	v_rcp_f32_e32 v138, v138
	v_rcp_f32_e32 v139, v139
	v_add_f32_e32 v155, 1.0, v159
	v_rcp_f32_e32 v137, v137
	v_rcp_f32_e32 v159, v155
	v_pk_mul_f32 v[134:135], v[72:73], v[134:135]
	v_pk_mul_f32 v[138:139], v[74:75], v[138:139]
	v_cvt_pk_bf16_f32 v134, v134, v135
	v_cvt_pk_bf16_f32 v135, v138, v139
	v_mul_f32_e32 v138, 0xbfb8aa3b, v64
	v_pk_mul_f32 v[136:137], v[68:69], v[136:137]
	v_pk_mul_f32 v[158:159], v[70:71], v[158:159]
	v_exp_f32_e32 v138, v138
	v_cvt_pk_bf16_f32 v136, v136, v137
	v_cvt_pk_bf16_f32 v137, v158, v159
	v_mul_f32_e32 v139, 0xbfb8aa3b, v60
	global_store_dwordx4 v[156:157], v[134:137], off offset:256
	v_exp_f32_e32 v139, v139
	v_mul_f32_e32 v155, 0xbfb8aa3b, v67
	v_mul_f32_e32 v136, 0xbfb8aa3b, v65
	v_exp_f32_e32 v137, v136
	v_mul_f32_e32 v136, 0xbfb8aa3b, v61
	v_add_f32_e32 v134, 1.0, v138
	v_exp_f32_e32 v138, v136
	v_add_f32_e32 v135, 1.0, v139
	v_mul_f32_e32 v139, 0xbfb8aa3b, v62
	v_rcp_f32_e32 v136, v135
	v_add_f32_e32 v135, 1.0, v137
	v_add_f32_e32 v137, 1.0, v138
	v_mul_f32_e32 v138, 0xbfb8aa3b, v66
	v_exp_f32_e32 v139, v139
	v_exp_f32_e32 v138, v138
	v_exp_f32_e32 v155, v155
	v_mul_f32_e32 v156, 0xbfb8aa3b, v63
	v_exp_f32_e32 v157, v156
	v_add_f32_e32 v139, 1.0, v139
	v_add_f32_e32 v138, 1.0, v138
	v_rcp_f32_e32 v156, v139
	v_add_f32_e32 v139, 1.0, v155
	v_rcp_f32_e32 v134, v134
	v_rcp_f32_e32 v135, v135
	v_rcp_f32_e32 v138, v138
	v_rcp_f32_e32 v139, v139
	v_add_f32_e32 v155, 1.0, v157
	v_rcp_f32_e32 v137, v137
	v_rcp_f32_e32 v157, v155
	v_pk_mul_f32 v[134:135], v[64:65], v[134:135]
	v_pk_mul_f32 v[138:139], v[66:67], v[138:139]
	s_mov_b64 s[6:7], 0x80000
	v_pk_mul_f32 v[136:137], v[60:61], v[136:137]
	v_pk_mul_f32 v[156:157], v[62:63], v[156:157]
	v_cvt_pk_bf16_f32 v134, v134, v135
	v_cvt_pk_bf16_f32 v135, v138, v139
	v_lshl_add_u64 v[138:139], v[132:133], 0, s[6:7]
	s_mov_b32 s6, 0x80000
	v_mul_f32_e32 v155, 0xbfb8aa3b, v56
	v_cvt_pk_bf16_f32 v136, v136, v137
	v_cvt_pk_bf16_f32 v137, v156, v157
	v_add_co_u32_e32 v156, vcc, s6, v132
	v_exp_f32_e32 v155, v155
	s_nop 0
	v_addc_co_u32_e32 v157, vcc, 0, v133, vcc
	v_mul_f32_e32 v158, 0xbfb8aa3b, v52
	global_store_dwordx4 v[156:157], v[134:137], off
	v_exp_f32_e32 v158, v158
	v_mul_f32_e32 v156, 0xbfb8aa3b, v54
	v_mul_f32_e32 v136, 0xbfb8aa3b, v57
	v_exp_f32_e32 v137, v136
	v_mul_f32_e32 v136, 0xbfb8aa3b, v53
	v_add_f32_e32 v134, 1.0, v155
	v_exp_f32_e32 v155, v136
	v_add_f32_e32 v135, 1.0, v158
	v_rcp_f32_e32 v136, v135
	v_add_f32_e32 v135, 1.0, v137
	v_add_f32_e32 v137, 1.0, v155
	v_mul_f32_e32 v155, 0xbfb8aa3b, v58
	v_exp_f32_e32 v155, v155
	v_exp_f32_e32 v157, v156
	v_mul_f32_e32 v158, 0xbfb8aa3b, v55
	v_exp_f32_e32 v159, v158
	v_add_f32_e32 v155, 1.0, v155
	v_rcp_f32_e32 v156, v155
	v_add_f32_e32 v155, 1.0, v157
	v_mul_f32_e32 v157, 0xbfb8aa3b, v59
	v_exp_f32_e32 v157, v157
	v_rcp_f32_e32 v158, v155
	v_rcp_f32_e32 v134, v134
	v_rcp_f32_e32 v135, v135
	v_add_f32_e32 v155, 1.0, v157
	v_rcp_f32_e32 v157, v155
	v_add_f32_e32 v155, 1.0, v159
	v_rcp_f32_e32 v137, v137
	v_rcp_f32_e32 v159, v155
	v_pk_mul_f32 v[134:135], v[56:57], v[134:135]
	v_pk_mul_f32 v[156:157], v[58:59], v[156:157]
	v_pk_mul_f32 v[136:137], v[52:53], v[136:137]
	v_pk_mul_f32 v[158:159], v[54:55], v[158:159]
	v_cvt_pk_bf16_f32 v134, v134, v135
	v_cvt_pk_bf16_f32 v135, v156, v157
	v_cvt_pk_bf16_f32 v136, v136, v137
	v_cvt_pk_bf16_f32 v137, v158, v159
	v_mul_f32_e32 v156, 0xbfb8aa3b, v44
	global_store_dwordx4 v[138:139], v[134:137], off offset:256
	v_mul_f32_e32 v155, 0xbfb8aa3b, v48
	v_exp_f32_e32 v156, v156
	v_mul_f32_e32 v136, 0xbfb8aa3b, v49
	v_exp_f32_e32 v137, v136
	v_mul_f32_e32 v136, 0xbfb8aa3b, v45
	v_exp_f32_e32 v155, v155
	v_exp_f32_e32 v138, v136
	v_add_f32_e32 v135, 1.0, v156
	v_mul_f32_e32 v139, 0xbfb8aa3b, v46
	v_add_f32_e32 v134, 1.0, v155
	v_rcp_f32_e32 v136, v135
	v_add_f32_e32 v135, 1.0, v137
	v_add_f32_e32 v137, 1.0, v138
	v_mul_f32_e32 v138, 0xbfb8aa3b, v50
	v_exp_f32_e32 v139, v139
	v_mul_f32_e32 v155, 0xbfb8aa3b, v51
	v_exp_f32_e32 v138, v138
	v_exp_f32_e32 v155, v155
	v_mul_f32_e32 v156, 0xbfb8aa3b, v47
	v_exp_f32_e32 v157, v156
	v_add_f32_e32 v139, 1.0, v139
	v_add_f32_e32 v138, 1.0, v138
	v_rcp_f32_e32 v156, v139
	v_add_f32_e32 v139, 1.0, v155
	v_rcp_f32_e32 v134, v134
	v_rcp_f32_e32 v135, v135
	v_rcp_f32_e32 v138, v138
	v_rcp_f32_e32 v139, v139
	v_add_f32_e32 v155, 1.0, v157
	v_rcp_f32_e32 v137, v137
	v_rcp_f32_e32 v157, v155
	v_pk_mul_f32 v[134:135], v[48:49], v[134:135]
	v_pk_mul_f32 v[138:139], v[50:51], v[138:139]
	s_mov_b64 s[6:7], 0x90000
	v_pk_mul_f32 v[136:137], v[44:45], v[136:137]
	v_pk_mul_f32 v[156:157], v[46:47], v[156:157]
	v_cvt_pk_bf16_f32 v134, v134, v135
	v_cvt_pk_bf16_f32 v135, v138, v139
	v_lshl_add_u64 v[138:139], v[132:133], 0, s[6:7]
	s_mov_b32 s6, 0x90000
	v_mul_f32_e32 v155, 0xbfb8aa3b, v40
	v_cvt_pk_bf16_f32 v136, v136, v137
	v_cvt_pk_bf16_f32 v137, v156, v157
	v_add_co_u32_e32 v156, vcc, s6, v132
	v_exp_f32_e32 v155, v155
	s_nop 0
	v_addc_co_u32_e32 v157, vcc, 0, v133, vcc
	v_mul_f32_e32 v158, 0xbfb8aa3b, v36
	global_store_dwordx4 v[156:157], v[134:137], off
	v_exp_f32_e32 v158, v158
	v_mul_f32_e32 v156, 0xbfb8aa3b, v38
	v_mul_f32_e32 v136, 0xbfb8aa3b, v41
	v_exp_f32_e32 v137, v136
	v_mul_f32_e32 v136, 0xbfb8aa3b, v37
	v_add_f32_e32 v134, 1.0, v155
	v_exp_f32_e32 v155, v136
	v_add_f32_e32 v135, 1.0, v158
	v_rcp_f32_e32 v136, v135
	v_add_f32_e32 v135, 1.0, v137
	v_add_f32_e32 v137, 1.0, v155
	v_mul_f32_e32 v155, 0xbfb8aa3b, v42
	v_exp_f32_e32 v155, v155
	v_exp_f32_e32 v157, v156
	v_mul_f32_e32 v158, 0xbfb8aa3b, v39
	v_exp_f32_e32 v159, v158
	v_add_f32_e32 v155, 1.0, v155
	v_rcp_f32_e32 v156, v155
	v_add_f32_e32 v155, 1.0, v157
	v_mul_f32_e32 v157, 0xbfb8aa3b, v43
	v_exp_f32_e32 v157, v157
	v_rcp_f32_e32 v158, v155
	v_rcp_f32_e32 v134, v134
	v_rcp_f32_e32 v135, v135
	v_add_f32_e32 v155, 1.0, v157
	v_rcp_f32_e32 v157, v155
	v_add_f32_e32 v155, 1.0, v159
	v_rcp_f32_e32 v137, v137
	v_rcp_f32_e32 v159, v155
	v_pk_mul_f32 v[134:135], v[40:41], v[134:135]
	v_pk_mul_f32 v[156:157], v[42:43], v[156:157]
	v_pk_mul_f32 v[136:137], v[36:37], v[136:137]
	v_pk_mul_f32 v[158:159], v[38:39], v[158:159]
	v_cvt_pk_bf16_f32 v134, v134, v135
	v_cvt_pk_bf16_f32 v135, v156, v157
	v_cvt_pk_bf16_f32 v136, v136, v137
	v_cvt_pk_bf16_f32 v137, v158, v159
	v_mul_f32_e32 v156, 0xbfb8aa3b, v26
	global_store_dwordx4 v[138:139], v[134:137], off offset:256
	v_mul_f32_e32 v155, 0xbfb8aa3b, v30
	v_exp_f32_e32 v156, v156
	v_mul_f32_e32 v136, 0xbfb8aa3b, v31
	v_exp_f32_e32 v137, v136
	v_mul_f32_e32 v136, 0xbfb8aa3b, v27
	v_exp_f32_e32 v155, v155
	v_exp_f32_e32 v138, v136
	v_add_f32_e32 v135, 1.0, v156
	v_mul_f32_e32 v139, 0xbfb8aa3b, v28
	v_add_f32_e32 v134, 1.0, v155
	v_rcp_f32_e32 v136, v135
	v_add_f32_e32 v135, 1.0, v137
	v_add_f32_e32 v137, 1.0, v138
	v_mul_f32_e32 v138, 0xbfb8aa3b, v32
	v_exp_f32_e32 v139, v139
	v_mul_f32_e32 v155, 0xbfb8aa3b, v33
	v_exp_f32_e32 v138, v138
	v_exp_f32_e32 v155, v155
	v_mul_f32_e32 v156, 0xbfb8aa3b, v29
	v_exp_f32_e32 v157, v156
	v_add_f32_e32 v139, 1.0, v139
	v_add_f32_e32 v138, 1.0, v138
	v_rcp_f32_e32 v156, v139
	v_add_f32_e32 v139, 1.0, v155
	v_rcp_f32_e32 v134, v134
	v_rcp_f32_e32 v135, v135
	v_rcp_f32_e32 v138, v138
	v_rcp_f32_e32 v139, v139
	v_add_f32_e32 v155, 1.0, v157
	v_rcp_f32_e32 v137, v137
	v_rcp_f32_e32 v157, v155
	v_pk_mul_f32 v[134:135], v[30:31], v[134:135]
	v_pk_mul_f32 v[138:139], v[32:33], v[138:139]
	s_mov_b64 s[6:7], 0xa0000
	v_pk_mul_f32 v[136:137], v[26:27], v[136:137]
	v_pk_mul_f32 v[156:157], v[28:29], v[156:157]
	v_cvt_pk_bf16_f32 v134, v134, v135
	v_cvt_pk_bf16_f32 v135, v138, v139
	v_lshl_add_u64 v[138:139], v[132:133], 0, s[6:7]
	s_mov_b32 s6, 0xa0000
	v_mul_f32_e32 v155, 0xbfb8aa3b, v22
	v_cvt_pk_bf16_f32 v136, v136, v137
	v_cvt_pk_bf16_f32 v137, v156, v157
	v_add_co_u32_e32 v156, vcc, s6, v132
	v_exp_f32_e32 v155, v155
	s_nop 0
	v_addc_co_u32_e32 v157, vcc, 0, v133, vcc
	v_mul_f32_e32 v158, 0xbfb8aa3b, v18
	global_store_dwordx4 v[156:157], v[134:137], off
	v_exp_f32_e32 v158, v158
	v_mul_f32_e32 v156, 0xbfb8aa3b, v20
	v_mul_f32_e32 v136, 0xbfb8aa3b, v23
	v_exp_f32_e32 v137, v136
	v_mul_f32_e32 v136, 0xbfb8aa3b, v19
	v_add_f32_e32 v134, 1.0, v155
	v_exp_f32_e32 v155, v136
	v_add_f32_e32 v135, 1.0, v158
	v_rcp_f32_e32 v136, v135
	v_add_f32_e32 v135, 1.0, v137
	v_add_f32_e32 v137, 1.0, v155
	v_mul_f32_e32 v155, 0xbfb8aa3b, v24
	v_exp_f32_e32 v155, v155
	v_exp_f32_e32 v157, v156
	v_mul_f32_e32 v158, 0xbfb8aa3b, v21
	v_exp_f32_e32 v159, v158
	v_add_f32_e32 v155, 1.0, v155
	v_rcp_f32_e32 v156, v155
	v_add_f32_e32 v155, 1.0, v157
	v_mul_f32_e32 v157, 0xbfb8aa3b, v25
	v_exp_f32_e32 v157, v157
	v_rcp_f32_e32 v158, v155
	v_rcp_f32_e32 v134, v134
	v_rcp_f32_e32 v135, v135
	v_add_f32_e32 v155, 1.0, v157
	v_rcp_f32_e32 v157, v155
	v_add_f32_e32 v155, 1.0, v159
	v_rcp_f32_e32 v137, v137
	v_rcp_f32_e32 v159, v155
	v_pk_mul_f32 v[134:135], v[22:23], v[134:135]
	v_pk_mul_f32 v[156:157], v[24:25], v[156:157]
	v_pk_mul_f32 v[136:137], v[18:19], v[136:137]
	v_pk_mul_f32 v[158:159], v[20:21], v[158:159]
	v_cvt_pk_bf16_f32 v134, v134, v135
	v_cvt_pk_bf16_f32 v135, v156, v157
	v_cvt_pk_bf16_f32 v136, v136, v137
	v_cvt_pk_bf16_f32 v137, v158, v159
	v_mul_f32_e32 v156, 0xbfb8aa3b, v10
	global_store_dwordx4 v[138:139], v[134:137], off offset:256
	v_mul_f32_e32 v155, 0xbfb8aa3b, v14
	v_exp_f32_e32 v156, v156
	v_mul_f32_e32 v136, 0xbfb8aa3b, v15
	v_exp_f32_e32 v137, v136
	v_mul_f32_e32 v136, 0xbfb8aa3b, v11
	v_exp_f32_e32 v155, v155
	v_exp_f32_e32 v138, v136
	v_add_f32_e32 v135, 1.0, v156
	v_mul_f32_e32 v139, 0xbfb8aa3b, v12
	v_add_f32_e32 v134, 1.0, v155
	v_rcp_f32_e32 v136, v135
	v_add_f32_e32 v135, 1.0, v137
	v_add_f32_e32 v137, 1.0, v138
	v_mul_f32_e32 v138, 0xbfb8aa3b, v16
	v_exp_f32_e32 v139, v139
	v_mul_f32_e32 v155, 0xbfb8aa3b, v17
	v_exp_f32_e32 v138, v138
	v_exp_f32_e32 v155, v155
	v_mul_f32_e32 v156, 0xbfb8aa3b, v13
	v_exp_f32_e32 v157, v156
	v_add_f32_e32 v139, 1.0, v139
	v_add_f32_e32 v138, 1.0, v138
	v_rcp_f32_e32 v156, v139
	v_add_f32_e32 v139, 1.0, v155
	v_rcp_f32_e32 v134, v134
	v_rcp_f32_e32 v135, v135
	v_rcp_f32_e32 v138, v138
	v_rcp_f32_e32 v139, v139
	v_add_f32_e32 v155, 1.0, v157
	v_rcp_f32_e32 v137, v137
	v_rcp_f32_e32 v157, v155
	v_pk_mul_f32 v[134:135], v[14:15], v[134:135]
	v_pk_mul_f32 v[138:139], v[16:17], v[138:139]
	s_mov_b64 s[6:7], 0xb0000
	v_cvt_pk_bf16_f32 v134, v134, v135
	v_cvt_pk_bf16_f32 v135, v138, v139
	v_lshl_add_u64 v[138:139], v[132:133], 0, s[6:7]
	s_mov_b32 s6, 0xb0000
	v_pk_mul_f32 v[136:137], v[10:11], v[136:137]
	v_pk_mul_f32 v[156:157], v[12:13], v[156:157]
	v_add_co_u32_e32 v132, vcc, s6, v132
	v_cvt_pk_bf16_f32 v136, v136, v137
	v_cvt_pk_bf16_f32 v137, v156, v157
	v_addc_co_u32_e32 v133, vcc, 0, v133, vcc
	v_mul_f32_e32 v156, 0xbfb8aa3b, v2
	global_store_dwordx4 v[132:133], v[134:137], off
	v_mul_f32_e32 v155, 0xbfb8aa3b, v6
	v_exp_f32_e32 v156, v156
	v_mul_f32_e32 v134, 0xbfb8aa3b, v7
	v_exp_f32_e32 v135, v134
	v_mul_f32_e32 v134, 0xbfb8aa3b, v3
	v_exp_f32_e32 v155, v155
	v_exp_f32_e32 v136, v134
	v_add_f32_e32 v133, 1.0, v156
	v_mul_f32_e32 v137, 0xbfb8aa3b, v4
	v_add_f32_e32 v132, 1.0, v155
	v_rcp_f32_e32 v134, v133
	v_add_f32_e32 v133, 1.0, v135
	v_add_f32_e32 v135, 1.0, v136
	v_mul_f32_e32 v136, 0xbfb8aa3b, v8
	v_exp_f32_e32 v137, v137
	v_mul_f32_e32 v155, 0xbfb8aa3b, v9
	v_mul_f32_e32 v156, 0xbfb8aa3b, v5
	v_exp_f32_e32 v136, v136
	v_exp_f32_e32 v155, v155
	v_exp_f32_e32 v157, v156
	v_add_f32_e32 v137, 1.0, v137
	v_add_f32_e32 v136, 1.0, v136
	v_rcp_f32_e32 v156, v137
	v_add_f32_e32 v137, 1.0, v155
	v_add_f32_e32 v155, 1.0, v157
	v_rcp_f32_e32 v132, v132
	v_rcp_f32_e32 v133, v133
	v_rcp_f32_e32 v135, v135
	v_rcp_f32_e32 v136, v136
	v_rcp_f32_e32 v137, v137
	v_rcp_f32_e32 v157, v155
	v_pk_mul_f32 v[132:133], v[6:7], v[132:133]
	v_pk_mul_f32 v[134:135], v[2:3], v[134:135]
	v_pk_mul_f32 v[136:137], v[8:9], v[136:137]
	v_pk_mul_f32 v[156:157], v[4:5], v[156:157]
	v_cvt_pk_bf16_f32 v132, v132, v133
	v_cvt_pk_bf16_f32 v133, v136, v137
	v_cvt_pk_bf16_f32 v134, v134, v135
	v_cvt_pk_bf16_f32 v135, v156, v157
	global_store_dwordx4 v[138:139], v[132:135], off offset:256

.LBB0_141:
	s_andn2_b64 vcc, exec, s[6:7]
	s_cbranch_vccnz .LBB0_143
	v_or_b32_e32 v136, 16, v154
	v_ashrrev_i32_e32 v155, 31, v154
	v_ashrrev_i32_e32 v137, 31, v136
	v_lshl_add_u32 v132, s76, 8, v178
	v_lshlrev_b64 v[134:135], 13, v[154:155]
	v_mov_b32_e32 v133, v34
	v_lshlrev_b64 v[136:137], 13, v[136:137]
	v_lshl_add_u64 v[134:135], s[62:63], 0, v[134:135]
	v_lshlrev_b64 v[132:133], 2, v[132:133]
	v_lshl_add_u64 v[136:137], s[62:63], 0, v[136:137]
	v_lshl_add_u64 v[134:135], v[134:135], 0, v[132:133]
	v_lshl_add_u64 v[136:137], v[136:137], 0, v[132:133]
	global_store_dwordx4 v[134:135], v[128:131], off
	global_store_dwordx4 v[134:135], v[124:127], off offset:16
	global_store_dwordx4 v[134:135], v[120:123], off offset:512
	global_store_dwordx4 v[134:135], v[116:119], off offset:528
	global_store_dwordx4 v[136:137], v[112:115], off
	global_store_dwordx4 v[136:137], v[108:111], off offset:16
	global_store_dwordx4 v[136:137], v[104:107], off offset:512
	global_store_dwordx4 v[136:137], v[100:103], off offset:528
	v_or_b32_e32 v136, 32, v154
	v_ashrrev_i32_e32 v137, 31, v136
	v_lshlrev_b64 v[136:137], 13, v[136:137]
	v_lshl_add_u64 v[136:137], s[62:63], 0, v[136:137]
	v_lshl_add_u64 v[136:137], v[136:137], 0, v[132:133]
	global_store_dwordx4 v[136:137], v[96:99], off
	global_store_dwordx4 v[136:137], v[92:95], off offset:16
	global_store_dwordx4 v[136:137], v[88:91], off offset:512
	global_store_dwordx4 v[136:137], v[84:87], off offset:528
	v_or_b32_e32 v136, 48, v154
	v_ashrrev_i32_e32 v137, 31, v136
	v_lshlrev_b64 v[136:137], 13, v[136:137]
	v_lshl_add_u64 v[136:137], s[62:63], 0, v[136:137]
	v_lshl_add_u64 v[132:133], v[136:137], 0, v[132:133]
	s_mov_b64 s[6:7], 0x100000
	global_store_dwordx4 v[132:133], v[80:83], off
	global_store_dwordx4 v[132:133], v[76:79], off offset:16
	global_store_dwordx4 v[132:133], v[72:75], off offset:512
	global_store_dwordx4 v[132:133], v[68:71], off offset:528
	v_lshl_add_u64 v[132:133], v[134:135], 0, s[6:7]
	s_mov_b32 s6, 0x100000
	v_add_co_u32_e32 v136, vcc, s6, v134
	s_mov_b64 s[6:7], 0x120000
	s_nop 0
	v_addc_co_u32_e32 v137, vcc, 0, v135, vcc
	global_store_dwordx4 v[136:137], v[64:67], off
	global_store_dwordx4 v[132:133], v[60:63], off offset:16
	global_store_dwordx4 v[132:133], v[56:59], off offset:512
	global_store_dwordx4 v[132:133], v[52:55], off offset:528
	v_lshl_add_u64 v[132:133], v[134:135], 0, s[6:7]
	s_mov_b32 s6, 0x120000
	v_add_co_u32_e32 v136, vcc, s6, v134
	s_mov_b64 s[6:7], 0x140000
	s_nop 0
	v_addc_co_u32_e32 v137, vcc, 0, v135, vcc
	global_store_dwordx4 v[136:137], v[48:51], off
	global_store_dwordx4 v[132:133], v[44:47], off offset:16
	global_store_dwordx4 v[132:133], v[40:43], off offset:512
	global_store_dwordx4 v[132:133], v[36:39], off offset:528
	v_add_co_u32_e32 v136, vcc, 0x140000, v134
	v_lshl_add_u64 v[132:133], v[134:135], 0, s[6:7]
	s_nop 0
	v_addc_co_u32_e32 v137, vcc, 0, v135, vcc
	s_mov_b64 s[6:7], 0x160000
	global_store_dwordx4 v[136:137], v[30:33], off
	global_store_dwordx4 v[132:133], v[26:29], off offset:16
	global_store_dwordx4 v[132:133], v[22:25], off offset:512
	global_store_dwordx4 v[132:133], v[18:21], off offset:528
	v_lshl_add_u64 v[132:133], v[134:135], 0, s[6:7]
	v_add_co_u32_e32 v134, vcc, 0x160000, v134
	s_nop 1
	v_addc_co_u32_e32 v135, vcc, 0, v135, vcc
	global_store_dwordx4 v[134:135], v[14:17], off
	global_store_dwordx4 v[132:133], v[10:13], off offset:16
	global_store_dwordx4 v[132:133], v[6:9], off offset:512
	global_store_dwordx4 v[132:133], v[2:5], off offset:528

.LBB0_144:
	s_andn2_b64 vcc, exec, s[6:7]
	s_cbranch_vccnz .LBB0_146
	v_mul_f32_e32 v133, 0xbfb8aa3b, v128
	v_exp_f32_e32 v133, v133
	v_mul_f32_e32 v136, 0xbfb8aa3b, v124
	v_exp_f32_e32 v136, v136
	v_ashrrev_i32_e32 v155, 31, v154
	v_lshlrev_b64 v[134:135], 12, v[154:155]
	v_lshl_add_u64 v[156:157], s[46:47], 0, v[134:135]
	v_add_f32_e32 v133, 1.0, v133
	v_mul_f32_e32 v135, 0xbfb8aa3b, v129
	v_rcp_f32_e32 v134, v133
	v_add_f32_e32 v133, 1.0, v136
	v_exp_f32_e32 v135, v135
	v_mul_f32_e32 v136, 0xbfb8aa3b, v125
	v_exp_f32_e32 v137, v136
	v_rcp_f32_e32 v136, v133
	v_add_f32_e32 v133, 1.0, v135
	v_rcp_f32_e32 v135, v133
	v_add_f32_e32 v133, 1.0, v137
	v_mul_f32_e32 v137, 0xbfb8aa3b, v130
	v_exp_f32_e32 v138, v137
	v_mul_f32_e32 v137, 0xbfb8aa3b, v126
	v_exp_f32_e32 v139, v137
	v_rcp_f32_e32 v137, v133
	v_add_f32_e32 v133, 1.0, v138
	v_rcp_f32_e32 v138, v133
	v_add_f32_e32 v133, 1.0, v139
	v_mul_f32_e32 v139, 0xbfb8aa3b, v131
	v_exp_f32_e32 v139, v139
	v_mul_f32_e32 v155, 0xbfb8aa3b, v127
	v_exp_f32_e32 v155, v155
	v_rcp_f32_e32 v158, v133
	v_add_f32_e32 v133, 1.0, v139
	v_rcp_f32_e32 v139, v133
	v_add_f32_e32 v133, 1.0, v155
	v_rcp_f32_e32 v159, v133
	v_lshl_add_u32 v132, s76, 8, v179
	v_pk_mul_f32 v[134:135], v[128:129], v[134:135]
	v_mov_b32_e32 v133, v34
	v_mul_f32_e32 v155, 0xbfb8aa3b, v120
	v_pk_mul_f32 v[160:161], v[124:125], v[136:137]
	v_pk_mul_f32 v[138:139], v[130:131], v[138:139]
	v_pk_mul_f32 v[158:159], v[126:127], v[158:159]
	v_cvt_pk_bf16_f32 v136, v134, v135
	v_lshlrev_b64 v[134:135], 1, v[132:133]
	v_exp_f32_e32 v155, v155
	v_cvt_pk_bf16_f32 v137, v138, v139
	v_cvt_pk_bf16_f32 v138, v160, v161
	v_cvt_pk_bf16_f32 v139, v158, v159
	v_lshl_add_u64 v[132:133], v[156:157], 0, v[134:135]
	v_mul_f32_e32 v156, 0xbfb8aa3b, v116
	global_store_dwordx4 v[132:133], v[136:139], off
	v_exp_f32_e32 v156, v156
	v_mul_f32_e32 v158, 0xbfb8aa3b, v119
	v_mul_f32_e32 v138, 0xbfb8aa3b, v121
	v_exp_f32_e32 v139, v138
	v_mul_f32_e32 v138, 0xbfb8aa3b, v117
	v_add_f32_e32 v136, 1.0, v155
	v_exp_f32_e32 v155, v138
	v_add_f32_e32 v137, 1.0, v156
	v_rcp_f32_e32 v138, v137
	v_add_f32_e32 v137, 1.0, v139
	v_add_f32_e32 v139, 1.0, v155
	v_mul_f32_e32 v155, 0xbfb8aa3b, v122
	v_exp_f32_e32 v155, v155
	v_mul_f32_e32 v156, 0xbfb8aa3b, v118
	v_exp_f32_e32 v157, v156
	v_exp_f32_e32 v159, v158
	v_add_f32_e32 v155, 1.0, v155
	v_rcp_f32_e32 v156, v155
	v_add_f32_e32 v155, 1.0, v157
	v_mul_f32_e32 v157, 0xbfb8aa3b, v123
	v_exp_f32_e32 v157, v157
	v_rcp_f32_e32 v158, v155
	v_rcp_f32_e32 v136, v136
	v_rcp_f32_e32 v137, v137
	v_add_f32_e32 v155, 1.0, v157
	v_rcp_f32_e32 v157, v155
	v_add_f32_e32 v155, 1.0, v159
	v_rcp_f32_e32 v139, v139
	v_rcp_f32_e32 v159, v155
	v_pk_mul_f32 v[136:137], v[120:121], v[136:137]
	v_pk_mul_f32 v[156:157], v[122:123], v[156:157]
	v_pk_mul_f32 v[138:139], v[116:117], v[138:139]
	v_pk_mul_f32 v[158:159], v[118:119], v[158:159]
	v_cvt_pk_bf16_f32 v136, v136, v137
	v_cvt_pk_bf16_f32 v137, v156, v157
	v_cvt_pk_bf16_f32 v138, v138, v139
	v_cvt_pk_bf16_f32 v139, v158, v159
	global_store_dwordx4 v[132:133], v[136:139], off offset:256
	v_mul_f32_e32 v158, 0xbfb8aa3b, v110
	v_exp_f32_e32 v159, v158
	v_mul_f32_e32 v138, 0xbfb8aa3b, v112
	v_exp_f32_e32 v138, v138
	v_mul_f32_e32 v139, 0xbfb8aa3b, v108
	v_or_b32_e32 v136, 16, v154
	v_exp_f32_e32 v139, v139
	v_ashrrev_i32_e32 v137, 31, v136
	v_lshlrev_b64 v[136:137], 12, v[136:137]
	v_lshl_add_u64 v[156:157], s[46:47], 0, v[136:137]
	v_add_f32_e32 v136, 1.0, v138
	v_mul_f32_e32 v138, 0xbfb8aa3b, v113
	v_add_f32_e32 v137, 1.0, v139
	v_exp_f32_e32 v139, v138
	v_mul_f32_e32 v138, 0xbfb8aa3b, v109
	v_exp_f32_e32 v155, v138
	v_rcp_f32_e32 v138, v137
	v_add_f32_e32 v137, 1.0, v139
	v_mul_f32_e32 v160, 0xbfb8aa3b, v111
	v_add_f32_e32 v139, 1.0, v155
	v_mul_f32_e32 v155, 0xbfb8aa3b, v114
	v_exp_f32_e32 v155, v155
	v_exp_f32_e32 v161, v160
	v_rcp_f32_e32 v136, v136
	v_rcp_f32_e32 v137, v137
	v_add_f32_e32 v155, 1.0, v155
	v_rcp_f32_e32 v158, v155
	v_add_f32_e32 v155, 1.0, v159
	v_mul_f32_e32 v159, 0xbfb8aa3b, v115
	v_exp_f32_e32 v159, v159
	v_rcp_f32_e32 v160, v155
	v_rcp_f32_e32 v139, v139
	v_pk_mul_f32 v[136:137], v[112:113], v[136:137]
	v_add_f32_e32 v155, 1.0, v159
	v_rcp_f32_e32 v159, v155
	v_add_f32_e32 v155, 1.0, v161
	v_rcp_f32_e32 v161, v155
	v_mul_f32_e32 v155, 0xbfb8aa3b, v104
	v_pk_mul_f32 v[138:139], v[108:109], v[138:139]
	v_pk_mul_f32 v[158:159], v[114:115], v[158:159]
	v_pk_mul_f32 v[160:161], v[110:111], v[160:161]
	v_exp_f32_e32 v155, v155
	v_cvt_pk_bf16_f32 v136, v136, v137
	v_cvt_pk_bf16_f32 v137, v158, v159
	v_cvt_pk_bf16_f32 v138, v138, v139
	v_cvt_pk_bf16_f32 v139, v160, v161
	v_lshl_add_u64 v[156:157], v[156:157], 0, v[134:135]
	v_mul_f32_e32 v158, 0xbfb8aa3b, v100
	global_store_dwordx4 v[156:157], v[136:139], off
	v_exp_f32_e32 v158, v158
	v_mul_f32_e32 v160, 0xbfb8aa3b, v103
	v_mul_f32_e32 v138, 0xbfb8aa3b, v105
	v_exp_f32_e32 v139, v138
	v_mul_f32_e32 v138, 0xbfb8aa3b, v101
	v_add_f32_e32 v136, 1.0, v155
	v_exp_f32_e32 v155, v138
	v_add_f32_e32 v137, 1.0, v158
	v_rcp_f32_e32 v138, v137
	v_add_f32_e32 v137, 1.0, v139
	v_add_f32_e32 v139, 1.0, v155
	v_mul_f32_e32 v155, 0xbfb8aa3b, v106
	v_exp_f32_e32 v155, v155
	v_mul_f32_e32 v158, 0xbfb8aa3b, v102
	v_exp_f32_e32 v159, v158
	v_exp_f32_e32 v161, v160
	v_add_f32_e32 v155, 1.0, v155
	v_rcp_f32_e32 v158, v155
	v_add_f32_e32 v155, 1.0, v159
	v_mul_f32_e32 v159, 0xbfb8aa3b, v107
	v_exp_f32_e32 v159, v159
	v_rcp_f32_e32 v160, v155
	v_rcp_f32_e32 v136, v136
	v_rcp_f32_e32 v137, v137
	v_add_f32_e32 v155, 1.0, v159
	v_rcp_f32_e32 v159, v155
	v_add_f32_e32 v155, 1.0, v161
	v_rcp_f32_e32 v139, v139
	v_rcp_f32_e32 v161, v155
	v_pk_mul_f32 v[136:137], v[104:105], v[136:137]
	v_pk_mul_f32 v[158:159], v[106:107], v[158:159]
	v_pk_mul_f32 v[138:139], v[100:101], v[138:139]
	v_pk_mul_f32 v[160:161], v[102:103], v[160:161]
	v_cvt_pk_bf16_f32 v136, v136, v137
	v_cvt_pk_bf16_f32 v137, v158, v159
	v_cvt_pk_bf16_f32 v138, v138, v139
	v_cvt_pk_bf16_f32 v139, v160, v161
	global_store_dwordx4 v[156:157], v[136:139], off offset:256
	v_mul_f32_e32 v158, 0xbfb8aa3b, v94
	v_exp_f32_e32 v159, v158
	v_mul_f32_e32 v138, 0xbfb8aa3b, v96
	v_exp_f32_e32 v138, v138
	v_mul_f32_e32 v139, 0xbfb8aa3b, v92
	v_or_b32_e32 v136, 32, v154
	v_exp_f32_e32 v139, v139
	v_ashrrev_i32_e32 v137, 31, v136
	v_lshlrev_b64 v[136:137], 12, v[136:137]
	v_lshl_add_u64 v[156:157], s[46:47], 0, v[136:137]
	v_add_f32_e32 v136, 1.0, v138
	v_mul_f32_e32 v138, 0xbfb8aa3b, v97
	v_add_f32_e32 v137, 1.0, v139
	v_exp_f32_e32 v139, v138
	v_mul_f32_e32 v138, 0xbfb8aa3b, v93
	v_exp_f32_e32 v155, v138
	v_rcp_f32_e32 v138, v137
	v_add_f32_e32 v137, 1.0, v139
	v_mul_f32_e32 v160, 0xbfb8aa3b, v95
	v_add_f32_e32 v139, 1.0, v155
	v_mul_f32_e32 v155, 0xbfb8aa3b, v98
	v_exp_f32_e32 v155, v155
	v_exp_f32_e32 v161, v160
	v_rcp_f32_e32 v136, v136
	v_rcp_f32_e32 v137, v137
	v_add_f32_e32 v155, 1.0, v155
	v_rcp_f32_e32 v158, v155
	v_add_f32_e32 v155, 1.0, v159
	v_mul_f32_e32 v159, 0xbfb8aa3b, v99
	v_exp_f32_e32 v159, v159
	v_rcp_f32_e32 v160, v155
	v_rcp_f32_e32 v139, v139
	v_pk_mul_f32 v[136:137], v[96:97], v[136:137]
	v_add_f32_e32 v155, 1.0, v159
	v_rcp_f32_e32 v159, v155
	v_add_f32_e32 v155, 1.0, v161
	v_rcp_f32_e32 v161, v155
	v_mul_f32_e32 v155, 0xbfb8aa3b, v88
	v_pk_mul_f32 v[138:139], v[92:93], v[138:139]
	v_pk_mul_f32 v[158:159], v[98:99], v[158:159]
	v_pk_mul_f32 v[160:161], v[94:95], v[160:161]
	v_exp_f32_e32 v155, v155
	v_cvt_pk_bf16_f32 v136, v136, v137
	v_cvt_pk_bf16_f32 v137, v158, v159
	v_cvt_pk_bf16_f32 v138, v138, v139
	v_cvt_pk_bf16_f32 v139, v160, v161
	v_lshl_add_u64 v[156:157], v[156:157], 0, v[134:135]
	v_mul_f32_e32 v158, 0xbfb8aa3b, v84
	global_store_dwordx4 v[156:157], v[136:139], off
	v_exp_f32_e32 v158, v158
	v_mul_f32_e32 v160, 0xbfb8aa3b, v87
	v_mul_f32_e32 v138, 0xbfb8aa3b, v89
	v_exp_f32_e32 v139, v138
	v_mul_f32_e32 v138, 0xbfb8aa3b, v85
	v_add_f32_e32 v136, 1.0, v155
	v_exp_f32_e32 v155, v138
	v_add_f32_e32 v137, 1.0, v158
	v_rcp_f32_e32 v138, v137
	v_add_f32_e32 v137, 1.0, v139
	v_add_f32_e32 v139, 1.0, v155
	v_mul_f32_e32 v155, 0xbfb8aa3b, v90
	v_exp_f32_e32 v155, v155
	v_mul_f32_e32 v158, 0xbfb8aa3b, v86
	v_exp_f32_e32 v159, v158
	v_exp_f32_e32 v161, v160
	v_add_f32_e32 v155, 1.0, v155
	v_rcp_f32_e32 v158, v155
	v_add_f32_e32 v155, 1.0, v159
	v_mul_f32_e32 v159, 0xbfb8aa3b, v91
	v_exp_f32_e32 v159, v159
	v_rcp_f32_e32 v160, v155
	v_rcp_f32_e32 v136, v136
	v_rcp_f32_e32 v137, v137
	v_add_f32_e32 v155, 1.0, v159
	v_rcp_f32_e32 v159, v155
	v_add_f32_e32 v155, 1.0, v161
	v_rcp_f32_e32 v139, v139
	v_rcp_f32_e32 v161, v155
	v_pk_mul_f32 v[136:137], v[88:89], v[136:137]
	v_pk_mul_f32 v[158:159], v[90:91], v[158:159]
	v_pk_mul_f32 v[138:139], v[84:85], v[138:139]
	v_pk_mul_f32 v[160:161], v[86:87], v[160:161]
	v_cvt_pk_bf16_f32 v136, v136, v137
	v_cvt_pk_bf16_f32 v137, v158, v159
	v_cvt_pk_bf16_f32 v138, v138, v139
	v_cvt_pk_bf16_f32 v139, v160, v161
	global_store_dwordx4 v[156:157], v[136:139], off offset:256
	v_mul_f32_e32 v158, 0xbfb8aa3b, v78
	v_exp_f32_e32 v159, v158
	v_mul_f32_e32 v138, 0xbfb8aa3b, v80
	v_exp_f32_e32 v138, v138
	v_mul_f32_e32 v139, 0xbfb8aa3b, v76
	v_or_b32_e32 v136, 48, v154
	v_exp_f32_e32 v139, v139
	v_ashrrev_i32_e32 v137, 31, v136
	v_lshlrev_b64 v[136:137], 12, v[136:137]
	v_lshl_add_u64 v[156:157], s[46:47], 0, v[136:137]
	v_add_f32_e32 v136, 1.0, v138
	v_mul_f32_e32 v138, 0xbfb8aa3b, v81
	v_add_f32_e32 v137, 1.0, v139
	v_exp_f32_e32 v139, v138
	v_mul_f32_e32 v138, 0xbfb8aa3b, v77
	v_exp_f32_e32 v155, v138
	v_rcp_f32_e32 v138, v137
	v_add_f32_e32 v137, 1.0, v139
	v_mul_f32_e32 v160, 0xbfb8aa3b, v79
	v_add_f32_e32 v139, 1.0, v155
	v_mul_f32_e32 v155, 0xbfb8aa3b, v82
	v_exp_f32_e32 v155, v155
	v_exp_f32_e32 v161, v160
	v_rcp_f32_e32 v136, v136
	v_rcp_f32_e32 v137, v137
	v_add_f32_e32 v155, 1.0, v155
	v_rcp_f32_e32 v158, v155
	v_add_f32_e32 v155, 1.0, v159
	v_mul_f32_e32 v159, 0xbfb8aa3b, v83
	v_exp_f32_e32 v159, v159
	v_rcp_f32_e32 v160, v155
	v_rcp_f32_e32 v139, v139
	v_pk_mul_f32 v[136:137], v[80:81], v[136:137]
	v_add_f32_e32 v155, 1.0, v159
	v_rcp_f32_e32 v159, v155
	v_add_f32_e32 v155, 1.0, v161
	v_rcp_f32_e32 v161, v155
	v_pk_mul_f32 v[138:139], v[76:77], v[138:139]
	v_pk_mul_f32 v[158:159], v[82:83], v[158:159]
	v_cvt_pk_bf16_f32 v136, v136, v137
	v_pk_mul_f32 v[160:161], v[78:79], v[160:161]
	v_cvt_pk_bf16_f32 v137, v158, v159
	v_cvt_pk_bf16_f32 v138, v138, v139
	v_cvt_pk_bf16_f32 v139, v160, v161
	v_lshl_add_u64 v[156:157], v[156:157], 0, v[134:135]
	v_mul_f32_e32 v135, 0xbfb8aa3b, v68
	global_store_dwordx4 v[156:157], v[136:139], off
	v_exp_f32_e32 v135, v135
	v_mul_f32_e32 v134, 0xbfb8aa3b, v72
	v_mul_f32_e32 v136, 0xbfb8aa3b, v73
	v_exp_f32_e32 v137, v136
	v_mul_f32_e32 v136, 0xbfb8aa3b, v69
	v_exp_f32_e32 v138, v136
	v_add_f32_e32 v135, 1.0, v135
	v_mul_f32_e32 v139, 0xbfb8aa3b, v70
	v_rcp_f32_e32 v136, v135
	v_add_f32_e32 v135, 1.0, v137
	v_add_f32_e32 v137, 1.0, v138
	v_mul_f32_e32 v138, 0xbfb8aa3b, v74
	v_exp_f32_e32 v139, v139
	v_mul_f32_e32 v155, 0xbfb8aa3b, v75
	v_exp_f32_e32 v134, v134
	v_exp_f32_e32 v138, v138
	v_exp_f32_e32 v155, v155
	v_mul_f32_e32 v158, 0xbfb8aa3b, v71
	v_exp_f32_e32 v159, v158
	v_add_f32_e32 v139, 1.0, v139
	v_add_f32_e32 v134, 1.0, v134
	v_add_f32_e32 v138, 1.0, v138
	v_rcp_f32_e32 v158, v139
	v_add_f32_e32 v139, 1.0, v155
	v_rcp_f32_e32 v134, v134
	v_rcp_f32_e32 v135, v135
	v_rcp_f32_e32 v138, v138
	v_rcp_f32_e32 v139, v139
	v_add_f32_e32 v155, 1.0, v159
	v_rcp_f32_e32 v137, v137
	v_rcp_f32_e32 v159, v155
	v_pk_mul_f32 v[134:135], v[72:73], v[134:135]
	v_pk_mul_f32 v[138:139], v[74:75], v[138:139]
	v_cvt_pk_bf16_f32 v134, v134, v135
	v_cvt_pk_bf16_f32 v135, v138, v139
	v_mul_f32_e32 v138, 0xbfb8aa3b, v64
	v_pk_mul_f32 v[136:137], v[68:69], v[136:137]
	v_pk_mul_f32 v[158:159], v[70:71], v[158:159]
	v_exp_f32_e32 v138, v138
	v_cvt_pk_bf16_f32 v136, v136, v137
	v_cvt_pk_bf16_f32 v137, v158, v159
	v_mul_f32_e32 v139, 0xbfb8aa3b, v60
	global_store_dwordx4 v[156:157], v[134:137], off offset:256
	v_exp_f32_e32 v139, v139
	v_mul_f32_e32 v155, 0xbfb8aa3b, v67
	v_mul_f32_e32 v136, 0xbfb8aa3b, v65
	v_exp_f32_e32 v137, v136
	v_mul_f32_e32 v136, 0xbfb8aa3b, v61
	v_add_f32_e32 v134, 1.0, v138
	v_exp_f32_e32 v138, v136
	v_add_f32_e32 v135, 1.0, v139
	v_mul_f32_e32 v139, 0xbfb8aa3b, v62
	v_rcp_f32_e32 v136, v135
	v_add_f32_e32 v135, 1.0, v137
	v_add_f32_e32 v137, 1.0, v138
	v_mul_f32_e32 v138, 0xbfb8aa3b, v66
	v_exp_f32_e32 v139, v139
	v_exp_f32_e32 v138, v138
	v_exp_f32_e32 v155, v155
	v_mul_f32_e32 v156, 0xbfb8aa3b, v63
	v_exp_f32_e32 v157, v156
	v_add_f32_e32 v139, 1.0, v139
	v_add_f32_e32 v138, 1.0, v138
	v_rcp_f32_e32 v156, v139
	v_add_f32_e32 v139, 1.0, v155
	v_rcp_f32_e32 v134, v134
	v_rcp_f32_e32 v135, v135
	v_rcp_f32_e32 v138, v138
	v_rcp_f32_e32 v139, v139
	v_add_f32_e32 v155, 1.0, v157
	v_rcp_f32_e32 v137, v137
	v_rcp_f32_e32 v157, v155
	v_pk_mul_f32 v[134:135], v[64:65], v[134:135]
	v_pk_mul_f32 v[138:139], v[66:67], v[138:139]
	s_mov_b64 s[6:7], 0x80000
	v_pk_mul_f32 v[136:137], v[60:61], v[136:137]
	v_pk_mul_f32 v[156:157], v[62:63], v[156:157]
	v_cvt_pk_bf16_f32 v134, v134, v135
	v_cvt_pk_bf16_f32 v135, v138, v139
	v_lshl_add_u64 v[138:139], v[132:133], 0, s[6:7]
	s_mov_b32 s6, 0x80000
	v_mul_f32_e32 v155, 0xbfb8aa3b, v56
	v_cvt_pk_bf16_f32 v136, v136, v137
	v_cvt_pk_bf16_f32 v137, v156, v157
	v_add_co_u32_e32 v156, vcc, s6, v132
	v_exp_f32_e32 v155, v155
	s_nop 0
	v_addc_co_u32_e32 v157, vcc, 0, v133, vcc
	v_mul_f32_e32 v158, 0xbfb8aa3b, v52
	global_store_dwordx4 v[156:157], v[134:137], off
	v_exp_f32_e32 v158, v158
	v_mul_f32_e32 v156, 0xbfb8aa3b, v54
	v_mul_f32_e32 v136, 0xbfb8aa3b, v57
	v_exp_f32_e32 v137, v136
	v_mul_f32_e32 v136, 0xbfb8aa3b, v53
	v_add_f32_e32 v134, 1.0, v155
	v_exp_f32_e32 v155, v136
	v_add_f32_e32 v135, 1.0, v158
	v_rcp_f32_e32 v136, v135
	v_add_f32_e32 v135, 1.0, v137
	v_add_f32_e32 v137, 1.0, v155
	v_mul_f32_e32 v155, 0xbfb8aa3b, v58
	v_exp_f32_e32 v155, v155
	v_exp_f32_e32 v157, v156
	v_mul_f32_e32 v158, 0xbfb8aa3b, v55
	v_exp_f32_e32 v159, v158
	v_add_f32_e32 v155, 1.0, v155
	v_rcp_f32_e32 v156, v155
	v_add_f32_e32 v155, 1.0, v157
	v_mul_f32_e32 v157, 0xbfb8aa3b, v59
	v_exp_f32_e32 v157, v157
	v_rcp_f32_e32 v158, v155
	v_rcp_f32_e32 v134, v134
	v_rcp_f32_e32 v135, v135
	v_add_f32_e32 v155, 1.0, v157
	v_rcp_f32_e32 v157, v155
	v_add_f32_e32 v155, 1.0, v159
	v_rcp_f32_e32 v137, v137
	v_rcp_f32_e32 v159, v155
	v_pk_mul_f32 v[134:135], v[56:57], v[134:135]
	v_pk_mul_f32 v[156:157], v[58:59], v[156:157]
	v_pk_mul_f32 v[136:137], v[52:53], v[136:137]
	v_pk_mul_f32 v[158:159], v[54:55], v[158:159]
	v_cvt_pk_bf16_f32 v134, v134, v135
	v_cvt_pk_bf16_f32 v135, v156, v157
	v_cvt_pk_bf16_f32 v136, v136, v137
	v_cvt_pk_bf16_f32 v137, v158, v159
	v_mul_f32_e32 v156, 0xbfb8aa3b, v44
	global_store_dwordx4 v[138:139], v[134:137], off offset:256
	v_mul_f32_e32 v155, 0xbfb8aa3b, v48
	v_exp_f32_e32 v156, v156
	v_mul_f32_e32 v136, 0xbfb8aa3b, v49
	v_exp_f32_e32 v137, v136
	v_mul_f32_e32 v136, 0xbfb8aa3b, v45
	v_exp_f32_e32 v155, v155
	v_exp_f32_e32 v138, v136
	v_add_f32_e32 v135, 1.0, v156
	v_mul_f32_e32 v139, 0xbfb8aa3b, v46
	v_add_f32_e32 v134, 1.0, v155
	v_rcp_f32_e32 v136, v135
	v_add_f32_e32 v135, 1.0, v137
	v_add_f32_e32 v137, 1.0, v138
	v_mul_f32_e32 v138, 0xbfb8aa3b, v50
	v_exp_f32_e32 v139, v139
	v_mul_f32_e32 v155, 0xbfb8aa3b, v51
	v_exp_f32_e32 v138, v138
	v_exp_f32_e32 v155, v155
	v_mul_f32_e32 v156, 0xbfb8aa3b, v47
	v_exp_f32_e32 v157, v156
	v_add_f32_e32 v139, 1.0, v139
	v_add_f32_e32 v138, 1.0, v138
	v_rcp_f32_e32 v156, v139
	v_add_f32_e32 v139, 1.0, v155
	v_rcp_f32_e32 v134, v134
	v_rcp_f32_e32 v135, v135
	v_rcp_f32_e32 v138, v138
	v_rcp_f32_e32 v139, v139
	v_add_f32_e32 v155, 1.0, v157
	v_rcp_f32_e32 v137, v137
	v_rcp_f32_e32 v157, v155
	v_pk_mul_f32 v[134:135], v[48:49], v[134:135]
	v_pk_mul_f32 v[138:139], v[50:51], v[138:139]
	s_mov_b64 s[6:7], 0x90000
	v_pk_mul_f32 v[136:137], v[44:45], v[136:137]
	v_pk_mul_f32 v[156:157], v[46:47], v[156:157]
	v_cvt_pk_bf16_f32 v134, v134, v135
	v_cvt_pk_bf16_f32 v135, v138, v139
	v_lshl_add_u64 v[138:139], v[132:133], 0, s[6:7]
	s_mov_b32 s6, 0x90000
	v_mul_f32_e32 v155, 0xbfb8aa3b, v40
	v_cvt_pk_bf16_f32 v136, v136, v137
	v_cvt_pk_bf16_f32 v137, v156, v157
	v_add_co_u32_e32 v156, vcc, s6, v132
	v_exp_f32_e32 v155, v155
	s_nop 0
	v_addc_co_u32_e32 v157, vcc, 0, v133, vcc
	v_mul_f32_e32 v158, 0xbfb8aa3b, v36
	global_store_dwordx4 v[156:157], v[134:137], off
	v_exp_f32_e32 v158, v158
	v_mul_f32_e32 v156, 0xbfb8aa3b, v38
	v_mul_f32_e32 v136, 0xbfb8aa3b, v41
	v_exp_f32_e32 v137, v136
	v_mul_f32_e32 v136, 0xbfb8aa3b, v37
	v_add_f32_e32 v134, 1.0, v155
	v_exp_f32_e32 v155, v136
	v_add_f32_e32 v135, 1.0, v158
	v_rcp_f32_e32 v136, v135
	v_add_f32_e32 v135, 1.0, v137
	v_add_f32_e32 v137, 1.0, v155
	v_mul_f32_e32 v155, 0xbfb8aa3b, v42
	v_exp_f32_e32 v155, v155
	v_exp_f32_e32 v157, v156
	v_mul_f32_e32 v158, 0xbfb8aa3b, v39
	v_exp_f32_e32 v159, v158
	v_add_f32_e32 v155, 1.0, v155
	v_rcp_f32_e32 v156, v155
	v_add_f32_e32 v155, 1.0, v157
	v_mul_f32_e32 v157, 0xbfb8aa3b, v43
	v_exp_f32_e32 v157, v157
	v_rcp_f32_e32 v158, v155
	v_rcp_f32_e32 v134, v134
	v_rcp_f32_e32 v135, v135
	v_add_f32_e32 v155, 1.0, v157
	v_rcp_f32_e32 v157, v155
	v_add_f32_e32 v155, 1.0, v159
	v_rcp_f32_e32 v137, v137
	v_rcp_f32_e32 v159, v155
	v_pk_mul_f32 v[134:135], v[40:41], v[134:135]
	v_pk_mul_f32 v[156:157], v[42:43], v[156:157]
	v_pk_mul_f32 v[136:137], v[36:37], v[136:137]
	v_pk_mul_f32 v[158:159], v[38:39], v[158:159]
	v_cvt_pk_bf16_f32 v134, v134, v135
	v_cvt_pk_bf16_f32 v135, v156, v157
	v_cvt_pk_bf16_f32 v136, v136, v137
	v_cvt_pk_bf16_f32 v137, v158, v159
	v_mul_f32_e32 v156, 0xbfb8aa3b, v26
	global_store_dwordx4 v[138:139], v[134:137], off offset:256
	v_mul_f32_e32 v155, 0xbfb8aa3b, v30
	v_exp_f32_e32 v156, v156
	v_mul_f32_e32 v136, 0xbfb8aa3b, v31
	v_exp_f32_e32 v137, v136
	v_mul_f32_e32 v136, 0xbfb8aa3b, v27
	v_exp_f32_e32 v155, v155
	v_exp_f32_e32 v138, v136
	v_add_f32_e32 v135, 1.0, v156
	v_mul_f32_e32 v139, 0xbfb8aa3b, v28
	v_add_f32_e32 v134, 1.0, v155
	v_rcp_f32_e32 v136, v135
	v_add_f32_e32 v135, 1.0, v137
	v_add_f32_e32 v137, 1.0, v138
	v_mul_f32_e32 v138, 0xbfb8aa3b, v32
	v_exp_f32_e32 v139, v139
	v_mul_f32_e32 v155, 0xbfb8aa3b, v33
	v_exp_f32_e32 v138, v138
	v_exp_f32_e32 v155, v155
	v_mul_f32_e32 v156, 0xbfb8aa3b, v29
	v_exp_f32_e32 v157, v156
	v_add_f32_e32 v139, 1.0, v139
	v_add_f32_e32 v138, 1.0, v138
	v_rcp_f32_e32 v156, v139
	v_add_f32_e32 v139, 1.0, v155
	v_rcp_f32_e32 v134, v134
	v_rcp_f32_e32 v135, v135
	v_rcp_f32_e32 v138, v138
	v_rcp_f32_e32 v139, v139
	v_add_f32_e32 v155, 1.0, v157
	v_rcp_f32_e32 v137, v137
	v_rcp_f32_e32 v157, v155
	v_pk_mul_f32 v[134:135], v[30:31], v[134:135]
	v_pk_mul_f32 v[138:139], v[32:33], v[138:139]
	s_mov_b64 s[6:7], 0xa0000
	v_pk_mul_f32 v[136:137], v[26:27], v[136:137]
	v_pk_mul_f32 v[156:157], v[28:29], v[156:157]
	v_cvt_pk_bf16_f32 v134, v134, v135
	v_cvt_pk_bf16_f32 v135, v138, v139
	v_lshl_add_u64 v[138:139], v[132:133], 0, s[6:7]
	s_mov_b32 s6, 0xa0000
	v_mul_f32_e32 v155, 0xbfb8aa3b, v22
	v_cvt_pk_bf16_f32 v136, v136, v137
	v_cvt_pk_bf16_f32 v137, v156, v157
	v_add_co_u32_e32 v156, vcc, s6, v132
	v_exp_f32_e32 v155, v155
	s_nop 0
	v_addc_co_u32_e32 v157, vcc, 0, v133, vcc
	v_mul_f32_e32 v158, 0xbfb8aa3b, v18
	global_store_dwordx4 v[156:157], v[134:137], off
	v_exp_f32_e32 v158, v158
	v_mul_f32_e32 v156, 0xbfb8aa3b, v20
	v_mul_f32_e32 v136, 0xbfb8aa3b, v23
	v_exp_f32_e32 v137, v136
	v_mul_f32_e32 v136, 0xbfb8aa3b, v19
	v_add_f32_e32 v134, 1.0, v155
	v_exp_f32_e32 v155, v136
	v_add_f32_e32 v135, 1.0, v158
	v_rcp_f32_e32 v136, v135
	v_add_f32_e32 v135, 1.0, v137
	v_add_f32_e32 v137, 1.0, v155
	v_mul_f32_e32 v155, 0xbfb8aa3b, v24
	v_exp_f32_e32 v155, v155
	v_exp_f32_e32 v157, v156
	v_mul_f32_e32 v158, 0xbfb8aa3b, v21
	v_exp_f32_e32 v159, v158
	v_add_f32_e32 v155, 1.0, v155
	v_rcp_f32_e32 v156, v155
	v_add_f32_e32 v155, 1.0, v157
	v_mul_f32_e32 v157, 0xbfb8aa3b, v25
	v_exp_f32_e32 v157, v157
	v_rcp_f32_e32 v158, v155
	v_rcp_f32_e32 v134, v134
	v_rcp_f32_e32 v135, v135
	v_add_f32_e32 v155, 1.0, v157
	v_rcp_f32_e32 v157, v155
	v_add_f32_e32 v155, 1.0, v159
	v_rcp_f32_e32 v137, v137
	v_rcp_f32_e32 v159, v155
	v_pk_mul_f32 v[134:135], v[22:23], v[134:135]
	v_pk_mul_f32 v[156:157], v[24:25], v[156:157]
	v_pk_mul_f32 v[136:137], v[18:19], v[136:137]
	v_pk_mul_f32 v[158:159], v[20:21], v[158:159]
	v_cvt_pk_bf16_f32 v134, v134, v135
	v_cvt_pk_bf16_f32 v135, v156, v157
	v_cvt_pk_bf16_f32 v136, v136, v137
	v_cvt_pk_bf16_f32 v137, v158, v159
	v_mul_f32_e32 v156, 0xbfb8aa3b, v10
	global_store_dwordx4 v[138:139], v[134:137], off offset:256
	v_mul_f32_e32 v155, 0xbfb8aa3b, v14
	v_exp_f32_e32 v156, v156
	v_mul_f32_e32 v136, 0xbfb8aa3b, v15
	v_exp_f32_e32 v137, v136
	v_mul_f32_e32 v136, 0xbfb8aa3b, v11
	v_exp_f32_e32 v155, v155
	v_exp_f32_e32 v138, v136
	v_add_f32_e32 v135, 1.0, v156
	v_mul_f32_e32 v139, 0xbfb8aa3b, v12
	v_add_f32_e32 v134, 1.0, v155
	v_rcp_f32_e32 v136, v135
	v_add_f32_e32 v135, 1.0, v137
	v_add_f32_e32 v137, 1.0, v138
	v_mul_f32_e32 v138, 0xbfb8aa3b, v16
	v_exp_f32_e32 v139, v139
	v_mul_f32_e32 v155, 0xbfb8aa3b, v17
	v_exp_f32_e32 v138, v138
	v_exp_f32_e32 v155, v155
	v_mul_f32_e32 v156, 0xbfb8aa3b, v13
	v_exp_f32_e32 v157, v156
	v_add_f32_e32 v139, 1.0, v139
	v_add_f32_e32 v138, 1.0, v138
	v_rcp_f32_e32 v156, v139
	v_add_f32_e32 v139, 1.0, v155
	v_rcp_f32_e32 v134, v134
	v_rcp_f32_e32 v135, v135
	v_rcp_f32_e32 v138, v138
	v_rcp_f32_e32 v139, v139
	v_add_f32_e32 v155, 1.0, v157
	v_rcp_f32_e32 v137, v137
	v_rcp_f32_e32 v157, v155
	v_pk_mul_f32 v[134:135], v[14:15], v[134:135]
	v_pk_mul_f32 v[138:139], v[16:17], v[138:139]
	s_mov_b64 s[6:7], 0xb0000
	v_cvt_pk_bf16_f32 v134, v134, v135
	v_cvt_pk_bf16_f32 v135, v138, v139
	v_lshl_add_u64 v[138:139], v[132:133], 0, s[6:7]
	s_mov_b32 s6, 0xb0000
	v_pk_mul_f32 v[136:137], v[10:11], v[136:137]
	v_pk_mul_f32 v[156:157], v[12:13], v[156:157]
	v_add_co_u32_e32 v132, vcc, s6, v132
	v_cvt_pk_bf16_f32 v136, v136, v137
	v_cvt_pk_bf16_f32 v137, v156, v157
	v_addc_co_u32_e32 v133, vcc, 0, v133, vcc
	v_mul_f32_e32 v156, 0xbfb8aa3b, v2
	global_store_dwordx4 v[132:133], v[134:137], off
	v_mul_f32_e32 v155, 0xbfb8aa3b, v6
	v_exp_f32_e32 v156, v156
	v_mul_f32_e32 v134, 0xbfb8aa3b, v7
	v_exp_f32_e32 v135, v134
	v_mul_f32_e32 v134, 0xbfb8aa3b, v3
	v_exp_f32_e32 v155, v155
	v_exp_f32_e32 v136, v134
	v_add_f32_e32 v133, 1.0, v156
	v_mul_f32_e32 v137, 0xbfb8aa3b, v4
	v_add_f32_e32 v132, 1.0, v155
	v_rcp_f32_e32 v134, v133
	v_add_f32_e32 v133, 1.0, v135
	v_add_f32_e32 v135, 1.0, v136
	v_mul_f32_e32 v136, 0xbfb8aa3b, v8
	v_exp_f32_e32 v137, v137
	v_mul_f32_e32 v155, 0xbfb8aa3b, v9
	v_mul_f32_e32 v156, 0xbfb8aa3b, v5
	v_exp_f32_e32 v136, v136
	v_exp_f32_e32 v155, v155
	v_exp_f32_e32 v157, v156
	v_add_f32_e32 v137, 1.0, v137
	v_add_f32_e32 v136, 1.0, v136
	v_rcp_f32_e32 v156, v137
	v_add_f32_e32 v137, 1.0, v155
	v_add_f32_e32 v155, 1.0, v157
	v_rcp_f32_e32 v132, v132
	v_rcp_f32_e32 v133, v133
	v_rcp_f32_e32 v135, v135
	v_rcp_f32_e32 v136, v136
	v_rcp_f32_e32 v137, v137
	v_rcp_f32_e32 v157, v155
	v_pk_mul_f32 v[132:133], v[6:7], v[132:133]
	v_pk_mul_f32 v[134:135], v[2:3], v[134:135]
	v_pk_mul_f32 v[136:137], v[8:9], v[136:137]
	v_pk_mul_f32 v[156:157], v[4:5], v[156:157]
	v_cvt_pk_bf16_f32 v132, v132, v133
	v_cvt_pk_bf16_f32 v133, v136, v137
	v_cvt_pk_bf16_f32 v134, v134, v135
	v_cvt_pk_bf16_f32 v135, v156, v157
	global_store_dwordx4 v[138:139], v[132:135], off offset:256

.LBB0_147:
	s_andn2_b64 vcc, exec, s[6:7]
	s_cbranch_vccnz .LBB0_149
	v_ashrrev_i32_e32 v155, 31, v154
	v_lshl_add_u32 v136, s76, 8, v180
	v_lshlrev_b64 v[132:133], 12, v[154:155]
	v_mov_b32_e32 v137, v34
	v_lshl_add_u64 v[138:139], s[44:45], 0, v[132:133]
	v_lshlrev_b64 v[136:137], 1, v[136:137]
	v_cvt_pk_bf16_f32 v132, v128, v129
	v_cvt_pk_bf16_f32 v133, v130, v131
	v_cvt_pk_bf16_f32 v134, v124, v125
	v_cvt_pk_bf16_f32 v135, v126, v127
	v_lshl_add_u64 v[138:139], v[138:139], 0, v[136:137]
	global_store_dwordx4 v[138:139], v[132:135], off
	s_mov_b64 s[6:7], 0x80000
	s_nop 0
	v_cvt_pk_bf16_f32 v132, v120, v121
	v_cvt_pk_bf16_f32 v133, v122, v123
	v_cvt_pk_bf16_f32 v134, v116, v117
	v_cvt_pk_bf16_f32 v135, v118, v119
	global_store_dwordx4 v[138:139], v[132:135], off offset:256
	s_nop 1
	v_or_b32_e32 v132, 16, v154
	v_ashrrev_i32_e32 v133, 31, v132
	v_lshlrev_b64 v[132:133], 12, v[132:133]
	v_lshl_add_u64 v[156:157], s[44:45], 0, v[132:133]
	v_cvt_pk_bf16_f32 v132, v112, v113
	v_cvt_pk_bf16_f32 v133, v114, v115
	v_cvt_pk_bf16_f32 v134, v108, v109
	v_cvt_pk_bf16_f32 v135, v110, v111
	v_lshl_add_u64 v[156:157], v[156:157], 0, v[136:137]
	global_store_dwordx4 v[156:157], v[132:135], off
	s_nop 1
	v_cvt_pk_bf16_f32 v132, v104, v105
	v_cvt_pk_bf16_f32 v133, v106, v107
	v_cvt_pk_bf16_f32 v134, v100, v101
	v_cvt_pk_bf16_f32 v135, v102, v103
	global_store_dwordx4 v[156:157], v[132:135], off offset:256
	s_nop 1
	v_or_b32_e32 v132, 32, v154
	v_ashrrev_i32_e32 v133, 31, v132
	v_lshlrev_b64 v[132:133], 12, v[132:133]
	v_lshl_add_u64 v[156:157], s[44:45], 0, v[132:133]
	v_cvt_pk_bf16_f32 v132, v96, v97
	v_cvt_pk_bf16_f32 v133, v98, v99
	v_cvt_pk_bf16_f32 v134, v92, v93
	v_cvt_pk_bf16_f32 v135, v94, v95
	v_lshl_add_u64 v[156:157], v[156:157], 0, v[136:137]
	global_store_dwordx4 v[156:157], v[132:135], off
	s_nop 1
	v_cvt_pk_bf16_f32 v132, v88, v89
	v_cvt_pk_bf16_f32 v133, v90, v91
	v_cvt_pk_bf16_f32 v134, v84, v85
	v_cvt_pk_bf16_f32 v135, v86, v87
	global_store_dwordx4 v[156:157], v[132:135], off offset:256
	s_nop 1
	v_or_b32_e32 v132, 48, v154
	v_ashrrev_i32_e32 v133, 31, v132
	v_lshlrev_b64 v[132:133], 12, v[132:133]
	v_lshl_add_u64 v[156:157], s[44:45], 0, v[132:133]
	v_cvt_pk_bf16_f32 v132, v80, v81
	v_cvt_pk_bf16_f32 v133, v82, v83
	v_cvt_pk_bf16_f32 v134, v76, v77
	v_cvt_pk_bf16_f32 v135, v78, v79
	v_lshl_add_u64 v[136:137], v[156:157], 0, v[136:137]
	global_store_dwordx4 v[136:137], v[132:135], off
	s_nop 1
	v_cvt_pk_bf16_f32 v132, v72, v73
	v_cvt_pk_bf16_f32 v133, v74, v75
	v_cvt_pk_bf16_f32 v134, v68, v69
	v_cvt_pk_bf16_f32 v135, v70, v71
	global_store_dwordx4 v[136:137], v[132:135], off offset:256
	v_lshl_add_u64 v[136:137], v[138:139], 0, s[6:7]
	s_mov_b32 s6, 0x80000
	v_add_co_u32_e32 v156, vcc, s6, v138
	v_cvt_pk_bf16_f32 v132, v64, v65
	v_cvt_pk_bf16_f32 v133, v66, v67
	v_cvt_pk_bf16_f32 v134, v60, v61
	v_cvt_pk_bf16_f32 v135, v62, v63
	v_addc_co_u32_e32 v157, vcc, 0, v139, vcc
	global_store_dwordx4 v[156:157], v[132:135], off
	s_mov_b64 s[6:7], 0x90000
	s_nop 0
	v_cvt_pk_bf16_f32 v132, v56, v57
	v_cvt_pk_bf16_f32 v133, v58, v59
	v_cvt_pk_bf16_f32 v134, v52, v53
	v_cvt_pk_bf16_f32 v135, v54, v55
	global_store_dwordx4 v[136:137], v[132:135], off offset:256
	v_lshl_add_u64 v[136:137], v[138:139], 0, s[6:7]
	s_mov_b32 s6, 0x90000
	v_add_co_u32_e32 v156, vcc, s6, v138
	v_cvt_pk_bf16_f32 v132, v48, v49
	v_cvt_pk_bf16_f32 v133, v50, v51
	v_cvt_pk_bf16_f32 v134, v44, v45
	v_cvt_pk_bf16_f32 v135, v46, v47
	v_addc_co_u32_e32 v157, vcc, 0, v139, vcc
	global_store_dwordx4 v[156:157], v[132:135], off
	s_mov_b64 s[6:7], 0xa0000
	s_nop 0
	v_cvt_pk_bf16_f32 v132, v40, v41
	v_cvt_pk_bf16_f32 v133, v42, v43
	v_cvt_pk_bf16_f32 v134, v36, v37
	v_cvt_pk_bf16_f32 v135, v38, v39
	global_store_dwordx4 v[136:137], v[132:135], off offset:256
	v_lshl_add_u64 v[136:137], v[138:139], 0, s[6:7]
	s_mov_b32 s6, 0xa0000
	v_add_co_u32_e32 v156, vcc, s6, v138
	v_cvt_pk_bf16_f32 v132, v30, v31
	v_cvt_pk_bf16_f32 v133, v32, v33
	v_cvt_pk_bf16_f32 v134, v26, v27
	v_cvt_pk_bf16_f32 v135, v28, v29
	v_addc_co_u32_e32 v157, vcc, 0, v139, vcc
	global_store_dwordx4 v[156:157], v[132:135], off
	s_mov_b64 s[6:7], 0xb0000
	s_nop 0
	v_cvt_pk_bf16_f32 v132, v22, v23
	v_cvt_pk_bf16_f32 v133, v24, v25
	v_cvt_pk_bf16_f32 v134, v18, v19
	v_cvt_pk_bf16_f32 v135, v20, v21
	global_store_dwordx4 v[136:137], v[132:135], off offset:256
	v_lshl_add_u64 v[136:137], v[138:139], 0, s[6:7]
	s_mov_b32 s6, 0xb0000
	v_add_co_u32_e32 v138, vcc, s6, v138
	v_cvt_pk_bf16_f32 v132, v14, v15
	v_cvt_pk_bf16_f32 v133, v16, v17
	v_cvt_pk_bf16_f32 v134, v10, v11
	v_cvt_pk_bf16_f32 v135, v12, v13
	v_addc_co_u32_e32 v139, vcc, 0, v139, vcc
	global_store_dwordx4 v[138:139], v[132:135], off
	s_nop 1
	v_cvt_pk_bf16_f32 v132, v6, v7
	v_cvt_pk_bf16_f32 v133, v8, v9
	v_cvt_pk_bf16_f32 v134, v2, v3
	v_cvt_pk_bf16_f32 v135, v4, v5
	global_store_dwordx4 v[136:137], v[132:135], off offset:256

.LBB0_171:
	v_ashrrev_i32_e32 v155, 31, v154
	s_waitcnt vmcnt(0)
	v_lshlrev_b64 v[132:133], 13, v[154:155]
	v_lshl_add_u64 v[156:157], s[60:61], 0, v[132:133]
	v_mul_f32_e32 v132, 0xbfb8aa3b, v128
	v_exp_f32_e32 v132, v132
	v_sub_f32_e32 v199, 1.0, v197
	s_mov_b32 s7, 0x800000
	s_mov_b32 s8, 0x3f317217
	v_add_f32_e32 v132, 1.0, v132
	v_rcp_f32_e32 v132, v132
	s_mov_b32 s9, 0x7f800000
	v_sub_f32_e32 v155, 1.0, v198
	v_sub_f32_e32 v201, 1.0, v195
	v_fma_f32 v132, v132, v199, v197
	v_max_f32_e32 v132, 0x358637bd, v132
	v_cmp_gt_f32_e32 vcc, s7, v132
	v_sub_f32_e32 v200, 1.0, v196
	v_sub_f32_e32 v203, 1.0, v193
	v_cndmask_b32_e64 v133, 0, 32, vcc
	v_ldexp_f32 v132, v132, v133
	v_log_f32_e32 v132, v132
	v_sub_f32_e32 v202, 1.0, v194
	v_sub_f32_e32 v204, 1.0, v189
	v_sub_f32_e32 v205, 1.0, v191
	v_mul_f32_e32 v133, 0x3f317217, v132
	v_fma_f32 v133, v132, s8, -v133
	v_fmac_f32_e32 v133, 0x3377d1cf, v132
	v_fmac_f32_e32 v133, 0x3f317217, v132
	v_cmp_lt_f32_e64 s[40:41], |v132|, s9
	v_lshl_add_u64 v[156:157], v[156:157], 0, v[158:159]
	v_sub_f32_e32 v206, 1.0, v190
	v_cndmask_b32_e64 v132, v132, v133, s[40:41]
	v_cndmask_b32_e32 v133, 0, v226, vcc
	v_sub_f32_e32 v132, v132, v133
	v_mul_f32_e32 v133, 0xbfb8aa3b, v124
	v_exp_f32_e32 v133, v133
	v_sub_f32_e32 v207, 1.0, v192
	v_sub_f32_e32 v209, 1.0, v187
	v_sub_f32_e32 v208, 1.0, v188
	v_add_f32_e32 v133, 1.0, v133
	v_rcp_f32_e32 v133, v133
	v_sub_f32_e32 v211, 1.0, v185
	v_sub_f32_e32 v210, 1.0, v186
	v_sub_f32_e32 v212, 1.0, v183
	v_fma_f32 v133, v133, v155, v198
	v_max_f32_e32 v133, 0x358637bd, v133
	v_cmp_gt_f32_e32 vcc, s7, v133
	v_sub_f32_e32 v213, 1.0, v184
	s_mov_b32 s6, 0x100000
	v_cndmask_b32_e64 v134, 0, 32, vcc
	v_ldexp_f32 v133, v133, v134
	v_log_f32_e32 v133, v133
	s_mov_b64 s[10:11], 0x100000
	v_mul_f32_e32 v134, 0x3f317217, v133
	v_fma_f32 v134, v133, s8, -v134
	v_fmac_f32_e32 v134, 0x3377d1cf, v133
	v_fmac_f32_e32 v134, 0x3f317217, v133
	v_cmp_lt_f32_e64 s[40:41], |v133|, s9
	s_nop 1
	v_cndmask_b32_e64 v133, v133, v134, s[40:41]
	v_cndmask_b32_e32 v134, 0, v226, vcc
	v_sub_f32_e32 v136, v133, v134
	v_mul_f32_e32 v133, 0xbfb8aa3b, v129
	v_exp_f32_e32 v133, v133
	s_nop 0
	v_add_f32_e32 v133, 1.0, v133
	v_rcp_f32_e32 v133, v133
	s_nop 0
	v_fma_f32 v133, v133, v201, v195
	v_max_f32_e32 v133, 0x358637bd, v133
	v_cmp_gt_f32_e32 vcc, s7, v133
	s_nop 1
	v_cndmask_b32_e64 v134, 0, 32, vcc
	v_ldexp_f32 v133, v133, v134
	v_log_f32_e32 v133, v133
	s_nop 0
	v_mul_f32_e32 v134, 0x3f317217, v133
	v_fma_f32 v134, v133, s8, -v134
	v_fmac_f32_e32 v134, 0x3377d1cf, v133
	v_fmac_f32_e32 v134, 0x3f317217, v133
	v_cmp_lt_f32_e64 s[40:41], |v133|, s9
	s_nop 1
	v_cndmask_b32_e64 v133, v133, v134, s[40:41]
	v_cndmask_b32_e32 v134, 0, v226, vcc
	v_sub_f32_e32 v133, v133, v134
	v_mul_f32_e32 v134, 0xbfb8aa3b, v125
	v_exp_f32_e32 v134, v134
	s_nop 0
	v_add_f32_e32 v134, 1.0, v134
	v_rcp_f32_e32 v134, v134
	s_nop 0
	v_fma_f32 v134, v134, v200, v196
	v_max_f32_e32 v134, 0x358637bd, v134
	v_cmp_gt_f32_e32 vcc, s7, v134
	s_nop 1
	v_cndmask_b32_e64 v135, 0, 32, vcc
	v_ldexp_f32 v134, v134, v135
	v_log_f32_e32 v134, v134
	s_nop 0
	v_mul_f32_e32 v135, 0x3f317217, v134
	v_fma_f32 v135, v134, s8, -v135
	v_fmac_f32_e32 v135, 0x3377d1cf, v134
	v_fmac_f32_e32 v135, 0x3f317217, v134
	v_cmp_lt_f32_e64 s[40:41], |v134|, s9
	s_nop 1
	v_cndmask_b32_e64 v134, v134, v135, s[40:41]
	v_cndmask_b32_e32 v135, 0, v226, vcc
	v_sub_f32_e32 v137, v134, v135
	v_mul_f32_e32 v134, 0xbfb8aa3b, v130
	v_exp_f32_e32 v134, v134
	s_nop 0
	v_add_f32_e32 v134, 1.0, v134
	v_rcp_f32_e32 v134, v134
	s_nop 0
	v_fma_f32 v134, v134, v203, v193
	v_max_f32_e32 v134, 0x358637bd, v134
	v_cmp_gt_f32_e32 vcc, s7, v134
	s_nop 1
	v_cndmask_b32_e64 v135, 0, 32, vcc
	v_ldexp_f32 v134, v134, v135
	v_log_f32_e32 v134, v134
	s_nop 0
	v_mul_f32_e32 v135, 0x3f317217, v134
	v_fma_f32 v135, v134, s8, -v135
	v_fmac_f32_e32 v135, 0x3377d1cf, v134
	v_fmac_f32_e32 v135, 0x3f317217, v134
	v_cmp_lt_f32_e64 s[40:41], |v134|, s9
	s_nop 1
	v_cndmask_b32_e64 v134, v134, v135, s[40:41]
	v_cndmask_b32_e32 v135, 0, v226, vcc
	v_sub_f32_e32 v134, v134, v135
	v_mul_f32_e32 v135, 0xbfb8aa3b, v126
	v_exp_f32_e32 v135, v135
	s_nop 0
	v_add_f32_e32 v135, 1.0, v135
	v_rcp_f32_e32 v135, v135
	s_nop 0
	v_fma_f32 v135, v135, v202, v194
	v_max_f32_e32 v135, 0x358637bd, v135
	v_cmp_gt_f32_e32 vcc, s7, v135
	s_nop 1
	v_cndmask_b32_e64 v138, 0, 32, vcc
	v_ldexp_f32 v135, v135, v138
	v_log_f32_e32 v135, v135
	s_nop 0
	v_mul_f32_e32 v138, 0x3f317217, v135
	v_fma_f32 v138, v135, s8, -v138
	v_fmac_f32_e32 v138, 0x3377d1cf, v135
	v_fmac_f32_e32 v138, 0x3f317217, v135
	v_cmp_lt_f32_e64 s[40:41], |v135|, s9
	s_nop 1
	v_cndmask_b32_e64 v135, v135, v138, s[40:41]
	v_cndmask_b32_e32 v138, 0, v226, vcc
	v_sub_f32_e32 v138, v135, v138
	v_mul_f32_e32 v135, 0xbfb8aa3b, v131
	v_exp_f32_e32 v135, v135
	s_nop 0
	v_add_f32_e32 v135, 1.0, v135
	v_rcp_f32_e32 v135, v135
	s_nop 0
	v_fma_f32 v135, v135, v204, v189
	v_max_f32_e32 v135, 0x358637bd, v135
	v_cmp_gt_f32_e32 vcc, s7, v135
	s_nop 1
	v_cndmask_b32_e64 v139, 0, 32, vcc
	v_ldexp_f32 v135, v135, v139
	v_log_f32_e32 v135, v135
	s_nop 0
	v_mul_f32_e32 v139, 0x3f317217, v135
	v_fma_f32 v139, v135, s8, -v139
	v_fmac_f32_e32 v139, 0x3377d1cf, v135
	v_fmac_f32_e32 v139, 0x3f317217, v135
	v_cmp_lt_f32_e64 s[40:41], |v135|, s9
	s_nop 1
	v_cndmask_b32_e64 v135, v135, v139, s[40:41]
	v_cndmask_b32_e32 v139, 0, v226, vcc
	v_sub_f32_e32 v135, v135, v139
	v_mul_f32_e32 v139, 0xbfb8aa3b, v127
	v_exp_f32_e32 v139, v139
	s_nop 0
	v_add_f32_e32 v139, 1.0, v139
	v_rcp_f32_e32 v139, v139
	s_nop 0
	v_fma_f32 v139, v139, v205, v191
	v_max_f32_e32 v139, 0x358637bd, v139
	v_cmp_gt_f32_e32 vcc, s7, v139
	s_nop 1
	v_cndmask_b32_e64 v160, 0, 32, vcc
	v_ldexp_f32 v139, v139, v160
	v_log_f32_e32 v139, v139
	s_nop 0
	v_mul_f32_e32 v160, 0x3f317217, v139
	v_fma_f32 v160, v139, s8, -v160
	v_fmac_f32_e32 v160, 0x3377d1cf, v139
	v_fmac_f32_e32 v160, 0x3f317217, v139
	v_cmp_lt_f32_e64 s[40:41], |v139|, s9
	s_nop 1
	v_cndmask_b32_e64 v139, v139, v160, s[40:41]
	v_cndmask_b32_e32 v160, 0, v226, vcc
	v_sub_f32_e32 v139, v139, v160
	global_store_dwordx4 v[156:157], v[132:135], off
	global_store_dwordx4 v[156:157], v[136:139], off offset:16
	s_nop 0
	v_mul_f32_e32 v132, 0xbfb8aa3b, v120
	v_exp_f32_e32 v132, v132
	s_nop 0
	v_add_f32_e32 v132, 1.0, v132
	v_rcp_f32_e32 v132, v132
	s_nop 0
	v_fma_f32 v132, v132, v206, v190
	v_max_f32_e32 v132, 0x358637bd, v132
	v_cmp_gt_f32_e32 vcc, s7, v132
	s_nop 1
	v_cndmask_b32_e64 v133, 0, 32, vcc
	v_ldexp_f32 v132, v132, v133
	v_log_f32_e32 v132, v132
	s_nop 0
	v_mul_f32_e32 v133, 0x3f317217, v132
	v_fma_f32 v133, v132, s8, -v133
	v_fmac_f32_e32 v133, 0x3377d1cf, v132
	v_fmac_f32_e32 v133, 0x3f317217, v132
	v_cmp_lt_f32_e64 s[40:41], |v132|, s9
	s_nop 1
	v_cndmask_b32_e64 v132, v132, v133, s[40:41]
	v_cndmask_b32_e32 v133, 0, v226, vcc
	v_sub_f32_e32 v132, v132, v133
	v_mul_f32_e32 v133, 0xbfb8aa3b, v116
	v_exp_f32_e32 v133, v133
	s_nop 0
	v_add_f32_e32 v133, 1.0, v133
	v_rcp_f32_e32 v133, v133
	s_nop 0
	v_fma_f32 v133, v133, v207, v192
	v_max_f32_e32 v133, 0x358637bd, v133
	v_cmp_gt_f32_e32 vcc, s7, v133
	s_nop 1
	v_cndmask_b32_e64 v134, 0, 32, vcc
	v_ldexp_f32 v133, v133, v134
	v_log_f32_e32 v133, v133
	s_nop 0
	v_mul_f32_e32 v134, 0x3f317217, v133
	v_fma_f32 v134, v133, s8, -v134
	v_fmac_f32_e32 v134, 0x3377d1cf, v133
	v_fmac_f32_e32 v134, 0x3f317217, v133
	v_cmp_lt_f32_e64 s[40:41], |v133|, s9
	s_nop 1
	v_cndmask_b32_e64 v133, v133, v134, s[40:41]
	v_cndmask_b32_e32 v134, 0, v226, vcc
	v_sub_f32_e32 v136, v133, v134
	v_mul_f32_e32 v133, 0xbfb8aa3b, v121
	v_exp_f32_e32 v133, v133
	s_nop 0
	v_add_f32_e32 v133, 1.0, v133
	v_rcp_f32_e32 v133, v133
	s_nop 0
	v_fma_f32 v133, v133, v209, v187
	v_max_f32_e32 v133, 0x358637bd, v133
	v_cmp_gt_f32_e32 vcc, s7, v133
	s_nop 1
	v_cndmask_b32_e64 v134, 0, 32, vcc
	v_ldexp_f32 v133, v133, v134
	v_log_f32_e32 v133, v133
	s_nop 0
	v_mul_f32_e32 v134, 0x3f317217, v133
	v_fma_f32 v134, v133, s8, -v134
	v_fmac_f32_e32 v134, 0x3377d1cf, v133
	v_fmac_f32_e32 v134, 0x3f317217, v133
	v_cmp_lt_f32_e64 s[40:41], |v133|, s9
	s_nop 1
	v_cndmask_b32_e64 v133, v133, v134, s[40:41]
	v_cndmask_b32_e32 v134, 0, v226, vcc
	v_sub_f32_e32 v133, v133, v134
	v_mul_f32_e32 v134, 0xbfb8aa3b, v117
	v_exp_f32_e32 v134, v134
	s_nop 0
	v_add_f32_e32 v134, 1.0, v134
	v_rcp_f32_e32 v134, v134
	s_nop 0
	v_fma_f32 v134, v134, v208, v188
	v_max_f32_e32 v134, 0x358637bd, v134
	v_cmp_gt_f32_e32 vcc, s7, v134
	s_nop 1
	v_cndmask_b32_e64 v135, 0, 32, vcc
	v_ldexp_f32 v134, v134, v135
	v_log_f32_e32 v134, v134
	s_nop 0
	v_mul_f32_e32 v135, 0x3f317217, v134
	v_fma_f32 v135, v134, s8, -v135
	v_fmac_f32_e32 v135, 0x3377d1cf, v134
	v_fmac_f32_e32 v135, 0x3f317217, v134
	v_cmp_lt_f32_e64 s[40:41], |v134|, s9
	s_nop 1
	v_cndmask_b32_e64 v134, v134, v135, s[40:41]
	v_cndmask_b32_e32 v135, 0, v226, vcc
	v_sub_f32_e32 v137, v134, v135
	v_mul_f32_e32 v134, 0xbfb8aa3b, v122
	v_exp_f32_e32 v134, v134
	s_nop 0
	v_add_f32_e32 v134, 1.0, v134
	v_rcp_f32_e32 v134, v134
	s_nop 0
	v_fma_f32 v134, v134, v211, v185
	v_max_f32_e32 v134, 0x358637bd, v134
	v_cmp_gt_f32_e32 vcc, s7, v134
	s_nop 1
	v_cndmask_b32_e64 v135, 0, 32, vcc
	v_ldexp_f32 v134, v134, v135
	v_log_f32_e32 v134, v134
	s_nop 0
	v_mul_f32_e32 v135, 0x3f317217, v134
	v_fma_f32 v135, v134, s8, -v135
	v_fmac_f32_e32 v135, 0x3377d1cf, v134
	v_fmac_f32_e32 v135, 0x3f317217, v134
	v_cmp_lt_f32_e64 s[40:41], |v134|, s9
	s_nop 1
	v_cndmask_b32_e64 v134, v134, v135, s[40:41]
	v_cndmask_b32_e32 v135, 0, v226, vcc
	v_sub_f32_e32 v134, v134, v135
	v_mul_f32_e32 v135, 0xbfb8aa3b, v118
	v_exp_f32_e32 v135, v135
	s_nop 0
	v_add_f32_e32 v135, 1.0, v135
	v_rcp_f32_e32 v135, v135
	s_nop 0
	v_fma_f32 v135, v135, v210, v186
	v_max_f32_e32 v135, 0x358637bd, v135
	v_cmp_gt_f32_e32 vcc, s7, v135
	s_nop 1
	v_cndmask_b32_e64 v138, 0, 32, vcc
	v_ldexp_f32 v135, v135, v138
	v_log_f32_e32 v135, v135
	s_nop 0
	v_mul_f32_e32 v138, 0x3f317217, v135
	v_fma_f32 v138, v135, s8, -v138
	v_fmac_f32_e32 v138, 0x3377d1cf, v135
	v_fmac_f32_e32 v138, 0x3f317217, v135
	v_cmp_lt_f32_e64 s[40:41], |v135|, s9
	s_nop 1
	v_cndmask_b32_e64 v135, v135, v138, s[40:41]
	v_cndmask_b32_e32 v138, 0, v226, vcc
	v_sub_f32_e32 v138, v135, v138
	v_mul_f32_e32 v135, 0xbfb8aa3b, v123
	v_exp_f32_e32 v135, v135
	s_nop 0
	v_add_f32_e32 v135, 1.0, v135
	v_rcp_f32_e32 v135, v135
	s_nop 0
	v_fma_f32 v135, v135, v212, v183
	v_max_f32_e32 v135, 0x358637bd, v135
	v_cmp_gt_f32_e32 vcc, s7, v135
	s_nop 1
	v_cndmask_b32_e64 v139, 0, 32, vcc
	v_ldexp_f32 v135, v135, v139
	v_log_f32_e32 v135, v135
	s_nop 0
	v_mul_f32_e32 v139, 0x3f317217, v135
	v_fma_f32 v139, v135, s8, -v139
	v_fmac_f32_e32 v139, 0x3377d1cf, v135
	v_fmac_f32_e32 v139, 0x3f317217, v135
	v_cmp_lt_f32_e64 s[40:41], |v135|, s9
	s_nop 1
	v_cndmask_b32_e64 v135, v135, v139, s[40:41]
	v_cndmask_b32_e32 v139, 0, v226, vcc
	v_sub_f32_e32 v135, v135, v139
	v_mul_f32_e32 v139, 0xbfb8aa3b, v119
	v_exp_f32_e32 v139, v139
	s_nop 0
	v_add_f32_e32 v139, 1.0, v139
	v_rcp_f32_e32 v139, v139
	s_nop 0
	v_fma_f32 v139, v139, v213, v184
	v_max_f32_e32 v139, 0x358637bd, v139
	v_cmp_gt_f32_e32 vcc, s7, v139
	s_nop 1
	v_cndmask_b32_e64 v160, 0, 32, vcc
	v_ldexp_f32 v139, v139, v160
	v_log_f32_e32 v139, v139
	s_nop 0
	v_mul_f32_e32 v160, 0x3f317217, v139
	v_fma_f32 v160, v139, s8, -v160
	v_fmac_f32_e32 v160, 0x3377d1cf, v139
	v_fmac_f32_e32 v160, 0x3f317217, v139
	v_cmp_lt_f32_e64 s[40:41], |v139|, s9
	s_nop 1
	v_cndmask_b32_e64 v139, v139, v160, s[40:41]
	v_cndmask_b32_e32 v160, 0, v226, vcc
	v_sub_f32_e32 v139, v139, v160
	global_store_dwordx4 v[156:157], v[132:135], off offset:512
	global_store_dwordx4 v[156:157], v[136:139], off offset:528
	s_nop 0
	v_or_b32_e32 v132, 16, v154
	v_ashrrev_i32_e32 v133, 31, v132
	v_lshlrev_b64 v[132:133], 13, v[132:133]
	v_lshl_add_u64 v[160:161], s[60:61], 0, v[132:133]
	v_mul_f32_e32 v132, 0xbfb8aa3b, v112
	v_exp_f32_e32 v132, v132
	v_lshl_add_u64 v[160:161], v[160:161], 0, v[158:159]
	v_add_f32_e32 v132, 1.0, v132
	v_rcp_f32_e32 v132, v132
	s_nop 0
	v_fma_f32 v132, v132, v199, v197
	v_max_f32_e32 v132, 0x358637bd, v132
	v_cmp_gt_f32_e32 vcc, s7, v132
	s_nop 1
	v_cndmask_b32_e64 v133, 0, 32, vcc
	v_ldexp_f32 v132, v132, v133
	v_log_f32_e32 v132, v132
	s_nop 0
	v_mul_f32_e32 v133, 0x3f317217, v132
	v_fma_f32 v133, v132, s8, -v133
	v_fmac_f32_e32 v133, 0x3377d1cf, v132
	v_fmac_f32_e32 v133, 0x3f317217, v132
	v_cmp_lt_f32_e64 s[40:41], |v132|, s9
	s_nop 1
	v_cndmask_b32_e64 v132, v132, v133, s[40:41]
	v_cndmask_b32_e32 v133, 0, v226, vcc
	v_sub_f32_e32 v132, v132, v133
	v_mul_f32_e32 v133, 0xbfb8aa3b, v108
	v_exp_f32_e32 v133, v133
	s_nop 0
	v_add_f32_e32 v133, 1.0, v133
	v_rcp_f32_e32 v133, v133
	s_nop 0
	v_fma_f32 v133, v133, v155, v198
	v_max_f32_e32 v133, 0x358637bd, v133
	v_cmp_gt_f32_e32 vcc, s7, v133
	s_nop 1
	v_cndmask_b32_e64 v134, 0, 32, vcc
	v_ldexp_f32 v133, v133, v134
	v_log_f32_e32 v133, v133
	s_nop 0
	v_mul_f32_e32 v134, 0x3f317217, v133
	v_fma_f32 v134, v133, s8, -v134
	v_fmac_f32_e32 v134, 0x3377d1cf, v133
	v_fmac_f32_e32 v134, 0x3f317217, v133
	v_cmp_lt_f32_e64 s[40:41], |v133|, s9
	s_nop 1
	v_cndmask_b32_e64 v133, v133, v134, s[40:41]
	v_cndmask_b32_e32 v134, 0, v226, vcc
	v_sub_f32_e32 v136, v133, v134
	v_mul_f32_e32 v133, 0xbfb8aa3b, v113
	v_exp_f32_e32 v133, v133
	s_nop 0
	v_add_f32_e32 v133, 1.0, v133
	v_rcp_f32_e32 v133, v133
	s_nop 0
	v_fma_f32 v133, v133, v201, v195
	v_max_f32_e32 v133, 0x358637bd, v133
	v_cmp_gt_f32_e32 vcc, s7, v133
	s_nop 1
	v_cndmask_b32_e64 v134, 0, 32, vcc
	v_ldexp_f32 v133, v133, v134
	v_log_f32_e32 v133, v133
	s_nop 0
	v_mul_f32_e32 v134, 0x3f317217, v133
	v_fma_f32 v134, v133, s8, -v134
	v_fmac_f32_e32 v134, 0x3377d1cf, v133
	v_fmac_f32_e32 v134, 0x3f317217, v133
	v_cmp_lt_f32_e64 s[40:41], |v133|, s9
	s_nop 1
	v_cndmask_b32_e64 v133, v133, v134, s[40:41]
	v_cndmask_b32_e32 v134, 0, v226, vcc
	v_sub_f32_e32 v133, v133, v134
	v_mul_f32_e32 v134, 0xbfb8aa3b, v109
	v_exp_f32_e32 v134, v134
	s_nop 0
	v_add_f32_e32 v134, 1.0, v134
	v_rcp_f32_e32 v134, v134
	s_nop 0
	v_fma_f32 v134, v134, v200, v196
	v_max_f32_e32 v134, 0x358637bd, v134
	v_cmp_gt_f32_e32 vcc, s7, v134
	s_nop 1
	v_cndmask_b32_e64 v135, 0, 32, vcc
	v_ldexp_f32 v134, v134, v135
	v_log_f32_e32 v134, v134
	s_nop 0
	v_mul_f32_e32 v135, 0x3f317217, v134
	v_fma_f32 v135, v134, s8, -v135
	v_fmac_f32_e32 v135, 0x3377d1cf, v134
	v_fmac_f32_e32 v135, 0x3f317217, v134
	v_cmp_lt_f32_e64 s[40:41], |v134|, s9
	s_nop 1
	v_cndmask_b32_e64 v134, v134, v135, s[40:41]
	v_cndmask_b32_e32 v135, 0, v226, vcc
	v_sub_f32_e32 v137, v134, v135
	v_mul_f32_e32 v134, 0xbfb8aa3b, v114
	v_exp_f32_e32 v134, v134
	s_nop 0
	v_add_f32_e32 v134, 1.0, v134
	v_rcp_f32_e32 v134, v134
	s_nop 0
	v_fma_f32 v134, v134, v203, v193
	v_max_f32_e32 v134, 0x358637bd, v134
	v_cmp_gt_f32_e32 vcc, s7, v134
	s_nop 1
	v_cndmask_b32_e64 v135, 0, 32, vcc
	v_ldexp_f32 v134, v134, v135
	v_log_f32_e32 v134, v134
	s_nop 0
	v_mul_f32_e32 v135, 0x3f317217, v134
	v_fma_f32 v135, v134, s8, -v135
	v_fmac_f32_e32 v135, 0x3377d1cf, v134
	v_fmac_f32_e32 v135, 0x3f317217, v134
	v_cmp_lt_f32_e64 s[40:41], |v134|, s9
	s_nop 1
	v_cndmask_b32_e64 v134, v134, v135, s[40:41]
	v_cndmask_b32_e32 v135, 0, v226, vcc
	v_sub_f32_e32 v134, v134, v135
	v_mul_f32_e32 v135, 0xbfb8aa3b, v110
	v_exp_f32_e32 v135, v135
	s_nop 0
	v_add_f32_e32 v135, 1.0, v135
	v_rcp_f32_e32 v135, v135
	s_nop 0
	v_fma_f32 v135, v135, v202, v194
	v_max_f32_e32 v135, 0x358637bd, v135
	v_cmp_gt_f32_e32 vcc, s7, v135
	s_nop 1
	v_cndmask_b32_e64 v138, 0, 32, vcc
	v_ldexp_f32 v135, v135, v138
	v_log_f32_e32 v135, v135
	s_nop 0
	v_mul_f32_e32 v138, 0x3f317217, v135
	v_fma_f32 v138, v135, s8, -v138
	v_fmac_f32_e32 v138, 0x3377d1cf, v135
	v_fmac_f32_e32 v138, 0x3f317217, v135
	v_cmp_lt_f32_e64 s[40:41], |v135|, s9
	s_nop 1
	v_cndmask_b32_e64 v135, v135, v138, s[40:41]
	v_cndmask_b32_e32 v138, 0, v226, vcc
	v_sub_f32_e32 v138, v135, v138
	v_mul_f32_e32 v135, 0xbfb8aa3b, v115
	v_exp_f32_e32 v135, v135
	s_nop 0
	v_add_f32_e32 v135, 1.0, v135
	v_rcp_f32_e32 v135, v135
	s_nop 0
	v_fma_f32 v135, v135, v204, v189
	v_max_f32_e32 v135, 0x358637bd, v135
	v_cmp_gt_f32_e32 vcc, s7, v135
	s_nop 1
	v_cndmask_b32_e64 v139, 0, 32, vcc
	v_ldexp_f32 v135, v135, v139
	v_log_f32_e32 v135, v135
	s_nop 0
	v_mul_f32_e32 v139, 0x3f317217, v135
	v_fma_f32 v139, v135, s8, -v139
	v_fmac_f32_e32 v139, 0x3377d1cf, v135
	v_fmac_f32_e32 v139, 0x3f317217, v135
	v_cmp_lt_f32_e64 s[40:41], |v135|, s9
	s_nop 1
	v_cndmask_b32_e64 v135, v135, v139, s[40:41]
	v_cndmask_b32_e32 v139, 0, v226, vcc
	v_sub_f32_e32 v135, v135, v139
	v_mul_f32_e32 v139, 0xbfb8aa3b, v111
	v_exp_f32_e32 v139, v139
	s_nop 0
	v_add_f32_e32 v139, 1.0, v139
	v_rcp_f32_e32 v139, v139
	s_nop 0
	v_fma_f32 v139, v139, v205, v191
	v_max_f32_e32 v139, 0x358637bd, v139
	v_cmp_gt_f32_e32 vcc, s7, v139
	s_nop 1
	v_cndmask_b32_e64 v172, 0, 32, vcc
	v_ldexp_f32 v139, v139, v172
	v_log_f32_e32 v139, v139
	s_nop 0
	v_mul_f32_e32 v172, 0x3f317217, v139
	v_fma_f32 v172, v139, s8, -v172
	v_fmac_f32_e32 v172, 0x3377d1cf, v139
	v_fmac_f32_e32 v172, 0x3f317217, v139
	v_cmp_lt_f32_e64 s[40:41], |v139|, s9
	s_nop 1
	v_cndmask_b32_e64 v139, v139, v172, s[40:41]
	v_cndmask_b32_e32 v172, 0, v226, vcc
	v_sub_f32_e32 v139, v139, v172
	global_store_dwordx4 v[160:161], v[132:135], off
	global_store_dwordx4 v[160:161], v[136:139], off offset:16
	s_nop 0
	v_mul_f32_e32 v132, 0xbfb8aa3b, v104
	v_exp_f32_e32 v132, v132
	s_nop 0
	v_add_f32_e32 v132, 1.0, v132
	v_rcp_f32_e32 v132, v132
	s_nop 0
	v_fma_f32 v132, v132, v206, v190
	v_max_f32_e32 v132, 0x358637bd, v132
	v_cmp_gt_f32_e32 vcc, s7, v132
	s_nop 1
	v_cndmask_b32_e64 v133, 0, 32, vcc
	v_ldexp_f32 v132, v132, v133
	v_log_f32_e32 v132, v132
	s_nop 0
	v_mul_f32_e32 v133, 0x3f317217, v132
	v_fma_f32 v133, v132, s8, -v133
	v_fmac_f32_e32 v133, 0x3377d1cf, v132
	v_fmac_f32_e32 v133, 0x3f317217, v132
	v_cmp_lt_f32_e64 s[40:41], |v132|, s9
	s_nop 1
	v_cndmask_b32_e64 v132, v132, v133, s[40:41]
	v_cndmask_b32_e32 v133, 0, v226, vcc
	v_sub_f32_e32 v132, v132, v133
	v_mul_f32_e32 v133, 0xbfb8aa3b, v100
	v_exp_f32_e32 v133, v133
	s_nop 0
	v_add_f32_e32 v133, 1.0, v133
	v_rcp_f32_e32 v133, v133
	s_nop 0
	v_fma_f32 v133, v133, v207, v192
	v_max_f32_e32 v133, 0x358637bd, v133
	v_cmp_gt_f32_e32 vcc, s7, v133
	s_nop 1
	v_cndmask_b32_e64 v134, 0, 32, vcc
	v_ldexp_f32 v133, v133, v134
	v_log_f32_e32 v133, v133
	s_nop 0
	v_mul_f32_e32 v134, 0x3f317217, v133
	v_fma_f32 v134, v133, s8, -v134
	v_fmac_f32_e32 v134, 0x3377d1cf, v133
	v_fmac_f32_e32 v134, 0x3f317217, v133
	v_cmp_lt_f32_e64 s[40:41], |v133|, s9
	s_nop 1
	v_cndmask_b32_e64 v133, v133, v134, s[40:41]
	v_cndmask_b32_e32 v134, 0, v226, vcc
	v_sub_f32_e32 v136, v133, v134
	v_mul_f32_e32 v133, 0xbfb8aa3b, v105
	v_exp_f32_e32 v133, v133
	s_nop 0
	v_add_f32_e32 v133, 1.0, v133
	v_rcp_f32_e32 v133, v133
	s_nop 0
	v_fma_f32 v133, v133, v209, v187
	v_max_f32_e32 v133, 0x358637bd, v133
	v_cmp_gt_f32_e32 vcc, s7, v133
	s_nop 1
	v_cndmask_b32_e64 v134, 0, 32, vcc
	v_ldexp_f32 v133, v133, v134
	v_log_f32_e32 v133, v133
	s_nop 0
	v_mul_f32_e32 v134, 0x3f317217, v133
	v_fma_f32 v134, v133, s8, -v134
	v_fmac_f32_e32 v134, 0x3377d1cf, v133
	v_fmac_f32_e32 v134, 0x3f317217, v133
	v_cmp_lt_f32_e64 s[40:41], |v133|, s9
	s_nop 1
	v_cndmask_b32_e64 v133, v133, v134, s[40:41]
	v_cndmask_b32_e32 v134, 0, v226, vcc
	v_sub_f32_e32 v133, v133, v134
	v_mul_f32_e32 v134, 0xbfb8aa3b, v101
	v_exp_f32_e32 v134, v134
	s_nop 0
	v_add_f32_e32 v134, 1.0, v134
	v_rcp_f32_e32 v134, v134
	s_nop 0
	v_fma_f32 v134, v134, v208, v188
	v_max_f32_e32 v134, 0x358637bd, v134
	v_cmp_gt_f32_e32 vcc, s7, v134
	s_nop 1
	v_cndmask_b32_e64 v135, 0, 32, vcc
	v_ldexp_f32 v134, v134, v135
	v_log_f32_e32 v134, v134
	s_nop 0
	v_mul_f32_e32 v135, 0x3f317217, v134
	v_fma_f32 v135, v134, s8, -v135
	v_fmac_f32_e32 v135, 0x3377d1cf, v134
	v_fmac_f32_e32 v135, 0x3f317217, v134
	v_cmp_lt_f32_e64 s[40:41], |v134|, s9
	s_nop 1
	v_cndmask_b32_e64 v134, v134, v135, s[40:41]
	v_cndmask_b32_e32 v135, 0, v226, vcc
	v_sub_f32_e32 v137, v134, v135
	v_mul_f32_e32 v134, 0xbfb8aa3b, v106
	v_exp_f32_e32 v134, v134
	s_nop 0
	v_add_f32_e32 v134, 1.0, v134
	v_rcp_f32_e32 v134, v134
	s_nop 0
	v_fma_f32 v134, v134, v211, v185
	v_max_f32_e32 v134, 0x358637bd, v134
	v_cmp_gt_f32_e32 vcc, s7, v134
	s_nop 1
	v_cndmask_b32_e64 v135, 0, 32, vcc
	v_ldexp_f32 v134, v134, v135
	v_log_f32_e32 v134, v134
	s_nop 0
	v_mul_f32_e32 v135, 0x3f317217, v134
	v_fma_f32 v135, v134, s8, -v135
	v_fmac_f32_e32 v135, 0x3377d1cf, v134
	v_fmac_f32_e32 v135, 0x3f317217, v134
	v_cmp_lt_f32_e64 s[40:41], |v134|, s9
	s_nop 1
	v_cndmask_b32_e64 v134, v134, v135, s[40:41]
	v_cndmask_b32_e32 v135, 0, v226, vcc
	v_sub_f32_e32 v134, v134, v135
	v_mul_f32_e32 v135, 0xbfb8aa3b, v102
	v_exp_f32_e32 v135, v135
	s_nop 0
	v_add_f32_e32 v135, 1.0, v135
	v_rcp_f32_e32 v135, v135
	s_nop 0
	v_fma_f32 v135, v135, v210, v186
	v_max_f32_e32 v135, 0x358637bd, v135
	v_cmp_gt_f32_e32 vcc, s7, v135
	s_nop 1
	v_cndmask_b32_e64 v138, 0, 32, vcc
	v_ldexp_f32 v135, v135, v138
	v_log_f32_e32 v135, v135
	s_nop 0
	v_mul_f32_e32 v138, 0x3f317217, v135
	v_fma_f32 v138, v135, s8, -v138
	v_fmac_f32_e32 v138, 0x3377d1cf, v135
	v_fmac_f32_e32 v138, 0x3f317217, v135
	v_cmp_lt_f32_e64 s[40:41], |v135|, s9
	s_nop 1
	v_cndmask_b32_e64 v135, v135, v138, s[40:41]
	v_cndmask_b32_e32 v138, 0, v226, vcc
	v_sub_f32_e32 v138, v135, v138
	v_mul_f32_e32 v135, 0xbfb8aa3b, v107
	v_exp_f32_e32 v135, v135
	s_nop 0
	v_add_f32_e32 v135, 1.0, v135
	v_rcp_f32_e32 v135, v135
	s_nop 0
	v_fma_f32 v135, v135, v212, v183
	v_max_f32_e32 v135, 0x358637bd, v135
	v_cmp_gt_f32_e32 vcc, s7, v135
	s_nop 1
	v_cndmask_b32_e64 v139, 0, 32, vcc
	v_ldexp_f32 v135, v135, v139
	v_log_f32_e32 v135, v135
	s_nop 0
	v_mul_f32_e32 v139, 0x3f317217, v135
	v_fma_f32 v139, v135, s8, -v139
	v_fmac_f32_e32 v139, 0x3377d1cf, v135
	v_fmac_f32_e32 v139, 0x3f317217, v135
	v_cmp_lt_f32_e64 s[40:41], |v135|, s9
	s_nop 1
	v_cndmask_b32_e64 v135, v135, v139, s[40:41]
	v_cndmask_b32_e32 v139, 0, v226, vcc
	v_sub_f32_e32 v135, v135, v139
	v_mul_f32_e32 v139, 0xbfb8aa3b, v103
	v_exp_f32_e32 v139, v139
	s_nop 0
	v_add_f32_e32 v139, 1.0, v139
	v_rcp_f32_e32 v139, v139
	s_nop 0
	v_fma_f32 v139, v139, v213, v184
	v_max_f32_e32 v139, 0x358637bd, v139
	v_cmp_gt_f32_e32 vcc, s7, v139
	s_nop 1
	v_cndmask_b32_e64 v172, 0, 32, vcc
	v_ldexp_f32 v139, v139, v172
	v_log_f32_e32 v139, v139
	s_nop 0
	v_mul_f32_e32 v172, 0x3f317217, v139
	v_fma_f32 v172, v139, s8, -v172
	v_fmac_f32_e32 v172, 0x3377d1cf, v139
	v_fmac_f32_e32 v172, 0x3f317217, v139
	v_cmp_lt_f32_e64 s[40:41], |v139|, s9
	s_nop 1
	v_cndmask_b32_e64 v139, v139, v172, s[40:41]
	v_cndmask_b32_e32 v172, 0, v226, vcc
	v_sub_f32_e32 v139, v139, v172
	global_store_dwordx4 v[160:161], v[132:135], off offset:512
	global_store_dwordx4 v[160:161], v[136:139], off offset:528
	s_nop 0
	v_or_b32_e32 v132, 32, v154
	v_ashrrev_i32_e32 v133, 31, v132
	v_lshlrev_b64 v[132:133], 13, v[132:133]
	v_lshl_add_u64 v[160:161], s[60:61], 0, v[132:133]
	v_mul_f32_e32 v132, 0xbfb8aa3b, v96
	v_exp_f32_e32 v132, v132
	v_lshl_add_u64 v[160:161], v[160:161], 0, v[158:159]
	v_add_f32_e32 v132, 1.0, v132
	v_rcp_f32_e32 v132, v132
	s_nop 0
	v_fma_f32 v132, v132, v199, v197
	v_max_f32_e32 v132, 0x358637bd, v132
	v_cmp_gt_f32_e32 vcc, s7, v132
	s_nop 1
	v_cndmask_b32_e64 v133, 0, 32, vcc
	v_ldexp_f32 v132, v132, v133
	v_log_f32_e32 v132, v132
	s_nop 0
	v_mul_f32_e32 v133, 0x3f317217, v132
	v_fma_f32 v133, v132, s8, -v133
	v_fmac_f32_e32 v133, 0x3377d1cf, v132
	v_fmac_f32_e32 v133, 0x3f317217, v132
	v_cmp_lt_f32_e64 s[40:41], |v132|, s9
	s_nop 1
	v_cndmask_b32_e64 v132, v132, v133, s[40:41]
	v_cndmask_b32_e32 v133, 0, v226, vcc
	v_sub_f32_e32 v132, v132, v133
	v_mul_f32_e32 v133, 0xbfb8aa3b, v92
	v_exp_f32_e32 v133, v133
	s_nop 0
	v_add_f32_e32 v133, 1.0, v133
	v_rcp_f32_e32 v133, v133
	s_nop 0
	v_fma_f32 v133, v133, v155, v198
	v_max_f32_e32 v133, 0x358637bd, v133
	v_cmp_gt_f32_e32 vcc, s7, v133
	s_nop 1
	v_cndmask_b32_e64 v134, 0, 32, vcc
	v_ldexp_f32 v133, v133, v134
	v_log_f32_e32 v133, v133
	s_nop 0
	v_mul_f32_e32 v134, 0x3f317217, v133
	v_fma_f32 v134, v133, s8, -v134
	v_fmac_f32_e32 v134, 0x3377d1cf, v133
	v_fmac_f32_e32 v134, 0x3f317217, v133
	v_cmp_lt_f32_e64 s[40:41], |v133|, s9
	s_nop 1
	v_cndmask_b32_e64 v133, v133, v134, s[40:41]
	v_cndmask_b32_e32 v134, 0, v226, vcc
	v_sub_f32_e32 v136, v133, v134
	v_mul_f32_e32 v133, 0xbfb8aa3b, v97
	v_exp_f32_e32 v133, v133
	s_nop 0
	v_add_f32_e32 v133, 1.0, v133
	v_rcp_f32_e32 v133, v133
	s_nop 0
	v_fma_f32 v133, v133, v201, v195
	v_max_f32_e32 v133, 0x358637bd, v133
	v_cmp_gt_f32_e32 vcc, s7, v133
	s_nop 1
	v_cndmask_b32_e64 v134, 0, 32, vcc
	v_ldexp_f32 v133, v133, v134
	v_log_f32_e32 v133, v133
	s_nop 0
	v_mul_f32_e32 v134, 0x3f317217, v133
	v_fma_f32 v134, v133, s8, -v134
	v_fmac_f32_e32 v134, 0x3377d1cf, v133
	v_fmac_f32_e32 v134, 0x3f317217, v133
	v_cmp_lt_f32_e64 s[40:41], |v133|, s9
	s_nop 1
	v_cndmask_b32_e64 v133, v133, v134, s[40:41]
	v_cndmask_b32_e32 v134, 0, v226, vcc
	v_sub_f32_e32 v133, v133, v134
	v_mul_f32_e32 v134, 0xbfb8aa3b, v93
	v_exp_f32_e32 v134, v134
	s_nop 0
	v_add_f32_e32 v134, 1.0, v134
	v_rcp_f32_e32 v134, v134
	s_nop 0
	v_fma_f32 v134, v134, v200, v196
	v_max_f32_e32 v134, 0x358637bd, v134
	v_cmp_gt_f32_e32 vcc, s7, v134
	s_nop 1
	v_cndmask_b32_e64 v135, 0, 32, vcc
	v_ldexp_f32 v134, v134, v135
	v_log_f32_e32 v134, v134
	s_nop 0
	v_mul_f32_e32 v135, 0x3f317217, v134
	v_fma_f32 v135, v134, s8, -v135
	v_fmac_f32_e32 v135, 0x3377d1cf, v134
	v_fmac_f32_e32 v135, 0x3f317217, v134
	v_cmp_lt_f32_e64 s[40:41], |v134|, s9
	s_nop 1
	v_cndmask_b32_e64 v134, v134, v135, s[40:41]
	v_cndmask_b32_e32 v135, 0, v226, vcc
	v_sub_f32_e32 v137, v134, v135
	v_mul_f32_e32 v134, 0xbfb8aa3b, v98
	v_exp_f32_e32 v134, v134
	s_nop 0
	v_add_f32_e32 v134, 1.0, v134
	v_rcp_f32_e32 v134, v134
	s_nop 0
	v_fma_f32 v134, v134, v203, v193
	v_max_f32_e32 v134, 0x358637bd, v134
	v_cmp_gt_f32_e32 vcc, s7, v134
	s_nop 1
	v_cndmask_b32_e64 v135, 0, 32, vcc
	v_ldexp_f32 v134, v134, v135
	v_log_f32_e32 v134, v134
	s_nop 0
	v_mul_f32_e32 v135, 0x3f317217, v134
	v_fma_f32 v135, v134, s8, -v135
	v_fmac_f32_e32 v135, 0x3377d1cf, v134
	v_fmac_f32_e32 v135, 0x3f317217, v134
	v_cmp_lt_f32_e64 s[40:41], |v134|, s9
	s_nop 1
	v_cndmask_b32_e64 v134, v134, v135, s[40:41]
	v_cndmask_b32_e32 v135, 0, v226, vcc
	v_sub_f32_e32 v134, v134, v135
	v_mul_f32_e32 v135, 0xbfb8aa3b, v94
	v_exp_f32_e32 v135, v135
	s_nop 0
	v_add_f32_e32 v135, 1.0, v135
	v_rcp_f32_e32 v135, v135
	s_nop 0
	v_fma_f32 v135, v135, v202, v194
	v_max_f32_e32 v135, 0x358637bd, v135
	v_cmp_gt_f32_e32 vcc, s7, v135
	s_nop 1
	v_cndmask_b32_e64 v138, 0, 32, vcc
	v_ldexp_f32 v135, v135, v138
	v_log_f32_e32 v135, v135
	s_nop 0
	v_mul_f32_e32 v138, 0x3f317217, v135
	v_fma_f32 v138, v135, s8, -v138
	v_fmac_f32_e32 v138, 0x3377d1cf, v135
	v_fmac_f32_e32 v138, 0x3f317217, v135
	v_cmp_lt_f32_e64 s[40:41], |v135|, s9
	s_nop 1
	v_cndmask_b32_e64 v135, v135, v138, s[40:41]
	v_cndmask_b32_e32 v138, 0, v226, vcc
	v_sub_f32_e32 v138, v135, v138
	v_mul_f32_e32 v135, 0xbfb8aa3b, v99
	v_exp_f32_e32 v135, v135
	s_nop 0
	v_add_f32_e32 v135, 1.0, v135
	v_rcp_f32_e32 v135, v135
	s_nop 0
	v_fma_f32 v135, v135, v204, v189
	v_max_f32_e32 v135, 0x358637bd, v135
	v_cmp_gt_f32_e32 vcc, s7, v135
	s_nop 1
	v_cndmask_b32_e64 v139, 0, 32, vcc
	v_ldexp_f32 v135, v135, v139
	v_log_f32_e32 v135, v135
	s_nop 0
	v_mul_f32_e32 v139, 0x3f317217, v135
	v_fma_f32 v139, v135, s8, -v139
	v_fmac_f32_e32 v139, 0x3377d1cf, v135
	v_fmac_f32_e32 v139, 0x3f317217, v135
	v_cmp_lt_f32_e64 s[40:41], |v135|, s9
	s_nop 1
	v_cndmask_b32_e64 v135, v135, v139, s[40:41]
	v_cndmask_b32_e32 v139, 0, v226, vcc
	v_sub_f32_e32 v135, v135, v139
	v_mul_f32_e32 v139, 0xbfb8aa3b, v95
	v_exp_f32_e32 v139, v139
	s_nop 0
	v_add_f32_e32 v139, 1.0, v139
	v_rcp_f32_e32 v139, v139
	s_nop 0
	v_fma_f32 v139, v139, v205, v191
	v_max_f32_e32 v139, 0x358637bd, v139
	v_cmp_gt_f32_e32 vcc, s7, v139
	s_nop 1
	v_cndmask_b32_e64 v172, 0, 32, vcc
	v_ldexp_f32 v139, v139, v172
	v_log_f32_e32 v139, v139
	s_nop 0
	v_mul_f32_e32 v172, 0x3f317217, v139
	v_fma_f32 v172, v139, s8, -v172
	v_fmac_f32_e32 v172, 0x3377d1cf, v139
	v_fmac_f32_e32 v172, 0x3f317217, v139
	v_cmp_lt_f32_e64 s[40:41], |v139|, s9
	s_nop 1
	v_cndmask_b32_e64 v139, v139, v172, s[40:41]
	v_cndmask_b32_e32 v172, 0, v226, vcc
	v_sub_f32_e32 v139, v139, v172
	global_store_dwordx4 v[160:161], v[132:135], off
	global_store_dwordx4 v[160:161], v[136:139], off offset:16
	s_nop 0
	v_mul_f32_e32 v132, 0xbfb8aa3b, v88
	v_exp_f32_e32 v132, v132
	s_nop 0
	v_add_f32_e32 v132, 1.0, v132
	v_rcp_f32_e32 v132, v132
	s_nop 0
	v_fma_f32 v132, v132, v206, v190
	v_max_f32_e32 v132, 0x358637bd, v132
	v_cmp_gt_f32_e32 vcc, s7, v132
	s_nop 1
	v_cndmask_b32_e64 v133, 0, 32, vcc
	v_ldexp_f32 v132, v132, v133
	v_log_f32_e32 v132, v132
	s_nop 0
	v_mul_f32_e32 v133, 0x3f317217, v132
	v_fma_f32 v133, v132, s8, -v133
	v_fmac_f32_e32 v133, 0x3377d1cf, v132
	v_fmac_f32_e32 v133, 0x3f317217, v132
	v_cmp_lt_f32_e64 s[40:41], |v132|, s9
	s_nop 1
	v_cndmask_b32_e64 v132, v132, v133, s[40:41]
	v_cndmask_b32_e32 v133, 0, v226, vcc
	v_sub_f32_e32 v132, v132, v133
	v_mul_f32_e32 v133, 0xbfb8aa3b, v84
	v_exp_f32_e32 v133, v133
	s_nop 0
	v_add_f32_e32 v133, 1.0, v133
	v_rcp_f32_e32 v133, v133
	s_nop 0
	v_fma_f32 v133, v133, v207, v192
	v_max_f32_e32 v133, 0x358637bd, v133
	v_cmp_gt_f32_e32 vcc, s7, v133
	s_nop 1
	v_cndmask_b32_e64 v134, 0, 32, vcc
	v_ldexp_f32 v133, v133, v134
	v_log_f32_e32 v133, v133
	s_nop 0
	v_mul_f32_e32 v134, 0x3f317217, v133
	v_fma_f32 v134, v133, s8, -v134
	v_fmac_f32_e32 v134, 0x3377d1cf, v133
	v_fmac_f32_e32 v134, 0x3f317217, v133
	v_cmp_lt_f32_e64 s[40:41], |v133|, s9
	s_nop 1
	v_cndmask_b32_e64 v133, v133, v134, s[40:41]
	v_cndmask_b32_e32 v134, 0, v226, vcc
	v_sub_f32_e32 v136, v133, v134
	v_mul_f32_e32 v133, 0xbfb8aa3b, v89
	v_exp_f32_e32 v133, v133
	s_nop 0
	v_add_f32_e32 v133, 1.0, v133
	v_rcp_f32_e32 v133, v133
	s_nop 0
	v_fma_f32 v133, v133, v209, v187
	v_max_f32_e32 v133, 0x358637bd, v133
	v_cmp_gt_f32_e32 vcc, s7, v133
	s_nop 1
	v_cndmask_b32_e64 v134, 0, 32, vcc
	v_ldexp_f32 v133, v133, v134
	v_log_f32_e32 v133, v133
	s_nop 0
	v_mul_f32_e32 v134, 0x3f317217, v133
	v_fma_f32 v134, v133, s8, -v134
	v_fmac_f32_e32 v134, 0x3377d1cf, v133
	v_fmac_f32_e32 v134, 0x3f317217, v133
	v_cmp_lt_f32_e64 s[40:41], |v133|, s9
	s_nop 1
	v_cndmask_b32_e64 v133, v133, v134, s[40:41]
	v_cndmask_b32_e32 v134, 0, v226, vcc
	v_sub_f32_e32 v133, v133, v134
	v_mul_f32_e32 v134, 0xbfb8aa3b, v85
	v_exp_f32_e32 v134, v134
	s_nop 0
	v_add_f32_e32 v134, 1.0, v134
	v_rcp_f32_e32 v134, v134
	s_nop 0
	v_fma_f32 v134, v134, v208, v188
	v_max_f32_e32 v134, 0x358637bd, v134
	v_cmp_gt_f32_e32 vcc, s7, v134
	s_nop 1
	v_cndmask_b32_e64 v135, 0, 32, vcc
	v_ldexp_f32 v134, v134, v135
	v_log_f32_e32 v134, v134
	s_nop 0
	v_mul_f32_e32 v135, 0x3f317217, v134
	v_fma_f32 v135, v134, s8, -v135
	v_fmac_f32_e32 v135, 0x3377d1cf, v134
	v_fmac_f32_e32 v135, 0x3f317217, v134
	v_cmp_lt_f32_e64 s[40:41], |v134|, s9
	s_nop 1
	v_cndmask_b32_e64 v134, v134, v135, s[40:41]
	v_cndmask_b32_e32 v135, 0, v226, vcc
	v_sub_f32_e32 v137, v134, v135
	v_mul_f32_e32 v134, 0xbfb8aa3b, v90
	v_exp_f32_e32 v134, v134
	s_nop 0
	v_add_f32_e32 v134, 1.0, v134
	v_rcp_f32_e32 v134, v134
	s_nop 0
	v_fma_f32 v134, v134, v211, v185
	v_max_f32_e32 v134, 0x358637bd, v134
	v_cmp_gt_f32_e32 vcc, s7, v134
	s_nop 1
	v_cndmask_b32_e64 v135, 0, 32, vcc
	v_ldexp_f32 v134, v134, v135
	v_log_f32_e32 v134, v134
	s_nop 0
	v_mul_f32_e32 v135, 0x3f317217, v134
	v_fma_f32 v135, v134, s8, -v135
	v_fmac_f32_e32 v135, 0x3377d1cf, v134
	v_fmac_f32_e32 v135, 0x3f317217, v134
	v_cmp_lt_f32_e64 s[40:41], |v134|, s9
	s_nop 1
	v_cndmask_b32_e64 v134, v134, v135, s[40:41]
	v_cndmask_b32_e32 v135, 0, v226, vcc
	v_sub_f32_e32 v134, v134, v135
	v_mul_f32_e32 v135, 0xbfb8aa3b, v86
	v_exp_f32_e32 v135, v135
	s_nop 0
	v_add_f32_e32 v135, 1.0, v135
	v_rcp_f32_e32 v135, v135
	s_nop 0
	v_fma_f32 v135, v135, v210, v186
	v_max_f32_e32 v135, 0x358637bd, v135
	v_cmp_gt_f32_e32 vcc, s7, v135
	s_nop 1
	v_cndmask_b32_e64 v138, 0, 32, vcc
	v_ldexp_f32 v135, v135, v138
	v_log_f32_e32 v135, v135
	s_nop 0
	v_mul_f32_e32 v138, 0x3f317217, v135
	v_fma_f32 v138, v135, s8, -v138
	v_fmac_f32_e32 v138, 0x3377d1cf, v135
	v_fmac_f32_e32 v138, 0x3f317217, v135
	v_cmp_lt_f32_e64 s[40:41], |v135|, s9
	s_nop 1
	v_cndmask_b32_e64 v135, v135, v138, s[40:41]
	v_cndmask_b32_e32 v138, 0, v226, vcc
	v_sub_f32_e32 v138, v135, v138
	v_mul_f32_e32 v135, 0xbfb8aa3b, v91
	v_exp_f32_e32 v135, v135
	s_nop 0
	v_add_f32_e32 v135, 1.0, v135
	v_rcp_f32_e32 v135, v135
	s_nop 0
	v_fma_f32 v135, v135, v212, v183
	v_max_f32_e32 v135, 0x358637bd, v135
	v_cmp_gt_f32_e32 vcc, s7, v135
	s_nop 1
	v_cndmask_b32_e64 v139, 0, 32, vcc
	v_ldexp_f32 v135, v135, v139
	v_log_f32_e32 v135, v135
	s_nop 0
	v_mul_f32_e32 v139, 0x3f317217, v135
	v_fma_f32 v139, v135, s8, -v139
	v_fmac_f32_e32 v139, 0x3377d1cf, v135
	v_fmac_f32_e32 v139, 0x3f317217, v135
	v_cmp_lt_f32_e64 s[40:41], |v135|, s9
	s_nop 1
	v_cndmask_b32_e64 v135, v135, v139, s[40:41]
	v_cndmask_b32_e32 v139, 0, v226, vcc
	v_sub_f32_e32 v135, v135, v139
	v_mul_f32_e32 v139, 0xbfb8aa3b, v87
	v_exp_f32_e32 v139, v139
	s_nop 0
	v_add_f32_e32 v139, 1.0, v139
	v_rcp_f32_e32 v139, v139
	s_nop 0
	v_fma_f32 v139, v139, v213, v184
	v_max_f32_e32 v139, 0x358637bd, v139
	v_cmp_gt_f32_e32 vcc, s7, v139
	s_nop 1
	v_cndmask_b32_e64 v172, 0, 32, vcc
	v_ldexp_f32 v139, v139, v172
	v_log_f32_e32 v139, v139
	s_nop 0
	v_mul_f32_e32 v172, 0x3f317217, v139
	v_fma_f32 v172, v139, s8, -v172
	v_fmac_f32_e32 v172, 0x3377d1cf, v139
	v_fmac_f32_e32 v172, 0x3f317217, v139
	v_cmp_lt_f32_e64 s[40:41], |v139|, s9
	s_nop 1
	v_cndmask_b32_e64 v139, v139, v172, s[40:41]
	v_cndmask_b32_e32 v172, 0, v226, vcc
	v_sub_f32_e32 v139, v139, v172
	global_store_dwordx4 v[160:161], v[132:135], off offset:512
	global_store_dwordx4 v[160:161], v[136:139], off offset:528
	s_nop 0
	v_or_b32_e32 v132, 48, v154
	v_ashrrev_i32_e32 v133, 31, v132
	v_lshlrev_b64 v[132:133], 13, v[132:133]
	v_lshl_add_u64 v[160:161], s[60:61], 0, v[132:133]
	v_mul_f32_e32 v132, 0xbfb8aa3b, v80
	v_exp_f32_e32 v132, v132
	v_lshl_add_u64 v[158:159], v[160:161], 0, v[158:159]
	v_add_f32_e32 v132, 1.0, v132
	v_rcp_f32_e32 v132, v132
	s_nop 0
	v_fma_f32 v132, v132, v199, v197
	v_max_f32_e32 v132, 0x358637bd, v132
	v_cmp_gt_f32_e32 vcc, s7, v132
	s_nop 1
	v_cndmask_b32_e64 v133, 0, 32, vcc
	v_ldexp_f32 v132, v132, v133
	v_log_f32_e32 v132, v132
	s_nop 0
	v_mul_f32_e32 v133, 0x3f317217, v132
	v_fma_f32 v133, v132, s8, -v133
	v_fmac_f32_e32 v133, 0x3377d1cf, v132
	v_fmac_f32_e32 v133, 0x3f317217, v132
	v_cmp_lt_f32_e64 s[40:41], |v132|, s9
	s_nop 1
	v_cndmask_b32_e64 v132, v132, v133, s[40:41]
	v_cndmask_b32_e32 v133, 0, v226, vcc
	v_sub_f32_e32 v132, v132, v133
	v_mul_f32_e32 v133, 0xbfb8aa3b, v76
	v_exp_f32_e32 v133, v133
	s_nop 0
	v_add_f32_e32 v133, 1.0, v133
	v_rcp_f32_e32 v133, v133
	s_nop 0
	v_fma_f32 v133, v133, v155, v198
	v_max_f32_e32 v133, 0x358637bd, v133
	v_cmp_gt_f32_e32 vcc, s7, v133
	s_nop 1
	v_cndmask_b32_e64 v134, 0, 32, vcc
	v_ldexp_f32 v133, v133, v134
	v_log_f32_e32 v133, v133
	s_nop 0
	v_mul_f32_e32 v134, 0x3f317217, v133
	v_fma_f32 v134, v133, s8, -v134
	v_fmac_f32_e32 v134, 0x3377d1cf, v133
	v_fmac_f32_e32 v134, 0x3f317217, v133
	v_cmp_lt_f32_e64 s[40:41], |v133|, s9
	s_nop 1
	v_cndmask_b32_e64 v133, v133, v134, s[40:41]
	v_cndmask_b32_e32 v134, 0, v226, vcc
	v_sub_f32_e32 v136, v133, v134
	v_mul_f32_e32 v133, 0xbfb8aa3b, v81
	v_exp_f32_e32 v133, v133
	s_nop 0
	v_add_f32_e32 v133, 1.0, v133
	v_rcp_f32_e32 v133, v133
	s_nop 0
	v_fma_f32 v133, v133, v201, v195
	v_max_f32_e32 v133, 0x358637bd, v133
	v_cmp_gt_f32_e32 vcc, s7, v133
	s_nop 1
	v_cndmask_b32_e64 v134, 0, 32, vcc
	v_ldexp_f32 v133, v133, v134
	v_log_f32_e32 v133, v133
	s_nop 0
	v_mul_f32_e32 v134, 0x3f317217, v133
	v_fma_f32 v134, v133, s8, -v134
	v_fmac_f32_e32 v134, 0x3377d1cf, v133
	v_fmac_f32_e32 v134, 0x3f317217, v133
	v_cmp_lt_f32_e64 s[40:41], |v133|, s9
	s_nop 1
	v_cndmask_b32_e64 v133, v133, v134, s[40:41]
	v_cndmask_b32_e32 v134, 0, v226, vcc
	v_sub_f32_e32 v133, v133, v134
	v_mul_f32_e32 v134, 0xbfb8aa3b, v77
	v_exp_f32_e32 v134, v134
	s_nop 0
	v_add_f32_e32 v134, 1.0, v134
	v_rcp_f32_e32 v134, v134
	s_nop 0
	v_fma_f32 v134, v134, v200, v196
	v_max_f32_e32 v134, 0x358637bd, v134
	v_cmp_gt_f32_e32 vcc, s7, v134
	s_nop 1
	v_cndmask_b32_e64 v135, 0, 32, vcc
	v_ldexp_f32 v134, v134, v135
	v_log_f32_e32 v134, v134
	s_nop 0
	v_mul_f32_e32 v135, 0x3f317217, v134
	v_fma_f32 v135, v134, s8, -v135
	v_fmac_f32_e32 v135, 0x3377d1cf, v134
	v_fmac_f32_e32 v135, 0x3f317217, v134
	v_cmp_lt_f32_e64 s[40:41], |v134|, s9
	s_nop 1
	v_cndmask_b32_e64 v134, v134, v135, s[40:41]
	v_cndmask_b32_e32 v135, 0, v226, vcc
	v_sub_f32_e32 v137, v134, v135
	v_mul_f32_e32 v134, 0xbfb8aa3b, v82
	v_exp_f32_e32 v134, v134
	s_nop 0
	v_add_f32_e32 v134, 1.0, v134
	v_rcp_f32_e32 v134, v134
	s_nop 0
	v_fma_f32 v134, v134, v203, v193
	v_max_f32_e32 v134, 0x358637bd, v134
	v_cmp_gt_f32_e32 vcc, s7, v134
	s_nop 1
	v_cndmask_b32_e64 v135, 0, 32, vcc
	v_ldexp_f32 v134, v134, v135
	v_log_f32_e32 v134, v134
	s_nop 0
	v_mul_f32_e32 v135, 0x3f317217, v134
	v_fma_f32 v135, v134, s8, -v135
	v_fmac_f32_e32 v135, 0x3377d1cf, v134
	v_fmac_f32_e32 v135, 0x3f317217, v134
	v_cmp_lt_f32_e64 s[40:41], |v134|, s9
	s_nop 1
	v_cndmask_b32_e64 v134, v134, v135, s[40:41]
	v_cndmask_b32_e32 v135, 0, v226, vcc
	v_sub_f32_e32 v134, v134, v135
	v_mul_f32_e32 v135, 0xbfb8aa3b, v78
	v_exp_f32_e32 v135, v135
	s_nop 0
	v_add_f32_e32 v135, 1.0, v135
	v_rcp_f32_e32 v135, v135
	s_nop 0
	v_fma_f32 v135, v135, v202, v194
	v_max_f32_e32 v135, 0x358637bd, v135
	v_cmp_gt_f32_e32 vcc, s7, v135
	s_nop 1
	v_cndmask_b32_e64 v138, 0, 32, vcc
	v_ldexp_f32 v135, v135, v138
	v_log_f32_e32 v135, v135
	s_nop 0
	v_mul_f32_e32 v138, 0x3f317217, v135
	v_fma_f32 v138, v135, s8, -v138
	v_fmac_f32_e32 v138, 0x3377d1cf, v135
	v_fmac_f32_e32 v138, 0x3f317217, v135
	v_cmp_lt_f32_e64 s[40:41], |v135|, s9
	s_nop 1
	v_cndmask_b32_e64 v135, v135, v138, s[40:41]
	v_cndmask_b32_e32 v138, 0, v226, vcc
	v_sub_f32_e32 v138, v135, v138
	v_mul_f32_e32 v135, 0xbfb8aa3b, v83
	v_exp_f32_e32 v135, v135
	s_nop 0
	v_add_f32_e32 v135, 1.0, v135
	v_rcp_f32_e32 v135, v135
	s_nop 0
	v_fma_f32 v135, v135, v204, v189
	v_max_f32_e32 v135, 0x358637bd, v135
	v_cmp_gt_f32_e32 vcc, s7, v135
	s_nop 1
	v_cndmask_b32_e64 v139, 0, 32, vcc
	v_ldexp_f32 v135, v135, v139
	v_log_f32_e32 v135, v135
	s_nop 0
	v_mul_f32_e32 v139, 0x3f317217, v135
	v_fma_f32 v139, v135, s8, -v139
	v_fmac_f32_e32 v139, 0x3377d1cf, v135
	v_fmac_f32_e32 v139, 0x3f317217, v135
	v_cmp_lt_f32_e64 s[40:41], |v135|, s9
	s_nop 1
	v_cndmask_b32_e64 v135, v135, v139, s[40:41]
	v_cndmask_b32_e32 v139, 0, v226, vcc
	v_sub_f32_e32 v135, v135, v139
	v_mul_f32_e32 v139, 0xbfb8aa3b, v79
	v_exp_f32_e32 v139, v139
	s_nop 0
	v_add_f32_e32 v139, 1.0, v139
	v_rcp_f32_e32 v139, v139
	s_nop 0
	v_fma_f32 v139, v139, v205, v191
	v_max_f32_e32 v139, 0x358637bd, v139
	v_cmp_gt_f32_e32 vcc, s7, v139
	s_nop 1
	v_cndmask_b32_e64 v172, 0, 32, vcc
	v_ldexp_f32 v139, v139, v172
	v_log_f32_e32 v139, v139
	s_nop 0
	v_mul_f32_e32 v172, 0x3f317217, v139
	v_fma_f32 v172, v139, s8, -v172
	v_fmac_f32_e32 v172, 0x3377d1cf, v139
	v_fmac_f32_e32 v172, 0x3f317217, v139
	v_cmp_lt_f32_e64 s[40:41], |v139|, s9
	s_nop 1
	v_cndmask_b32_e64 v139, v139, v172, s[40:41]
	v_cndmask_b32_e32 v172, 0, v226, vcc
	v_sub_f32_e32 v139, v139, v172
	global_store_dwordx4 v[158:159], v[132:135], off
	global_store_dwordx4 v[158:159], v[136:139], off offset:16
	s_nop 0
	v_mul_f32_e32 v132, 0xbfb8aa3b, v72
	v_exp_f32_e32 v132, v132
	s_nop 0
	v_add_f32_e32 v132, 1.0, v132
	v_rcp_f32_e32 v132, v132
	s_nop 0
	v_fma_f32 v132, v132, v206, v190
	v_max_f32_e32 v132, 0x358637bd, v132
	v_cmp_gt_f32_e32 vcc, s7, v132
	s_nop 1
	v_cndmask_b32_e64 v133, 0, 32, vcc
	v_ldexp_f32 v132, v132, v133
	v_log_f32_e32 v132, v132
	s_nop 0
	v_mul_f32_e32 v133, 0x3f317217, v132
	v_fma_f32 v133, v132, s8, -v133
	v_fmac_f32_e32 v133, 0x3377d1cf, v132
	v_fmac_f32_e32 v133, 0x3f317217, v132
	v_cmp_lt_f32_e64 s[40:41], |v132|, s9
	s_nop 1
	v_cndmask_b32_e64 v132, v132, v133, s[40:41]
	v_cndmask_b32_e32 v133, 0, v226, vcc
	v_sub_f32_e32 v132, v132, v133
	v_mul_f32_e32 v133, 0xbfb8aa3b, v68
	v_exp_f32_e32 v133, v133
	s_nop 0
	v_add_f32_e32 v133, 1.0, v133
	v_rcp_f32_e32 v133, v133
	s_nop 0
	v_fma_f32 v133, v133, v207, v192
	v_max_f32_e32 v133, 0x358637bd, v133
	v_cmp_gt_f32_e32 vcc, s7, v133
	s_nop 1
	v_cndmask_b32_e64 v134, 0, 32, vcc
	v_ldexp_f32 v133, v133, v134
	v_log_f32_e32 v133, v133
	s_nop 0
	v_mul_f32_e32 v134, 0x3f317217, v133
	v_fma_f32 v134, v133, s8, -v134
	v_fmac_f32_e32 v134, 0x3377d1cf, v133
	v_fmac_f32_e32 v134, 0x3f317217, v133
	v_cmp_lt_f32_e64 s[40:41], |v133|, s9
	s_nop 1
	v_cndmask_b32_e64 v133, v133, v134, s[40:41]
	v_cndmask_b32_e32 v134, 0, v226, vcc
	v_sub_f32_e32 v136, v133, v134
	v_mul_f32_e32 v133, 0xbfb8aa3b, v73
	v_exp_f32_e32 v133, v133
	s_nop 0
	v_add_f32_e32 v133, 1.0, v133
	v_rcp_f32_e32 v133, v133
	s_nop 0
	v_fma_f32 v133, v133, v209, v187
	v_max_f32_e32 v133, 0x358637bd, v133
	v_cmp_gt_f32_e32 vcc, s7, v133
	s_nop 1
	v_cndmask_b32_e64 v134, 0, 32, vcc
	v_ldexp_f32 v133, v133, v134
	v_log_f32_e32 v133, v133
	s_nop 0
	v_mul_f32_e32 v134, 0x3f317217, v133
	v_fma_f32 v134, v133, s8, -v134
	v_fmac_f32_e32 v134, 0x3377d1cf, v133
	v_fmac_f32_e32 v134, 0x3f317217, v133
	v_cmp_lt_f32_e64 s[40:41], |v133|, s9
	s_nop 1
	v_cndmask_b32_e64 v133, v133, v134, s[40:41]
	v_cndmask_b32_e32 v134, 0, v226, vcc
	v_sub_f32_e32 v133, v133, v134
	v_mul_f32_e32 v134, 0xbfb8aa3b, v69
	v_exp_f32_e32 v134, v134
	s_nop 0
	v_add_f32_e32 v134, 1.0, v134
	v_rcp_f32_e32 v134, v134
	s_nop 0
	v_fma_f32 v134, v134, v208, v188
	v_max_f32_e32 v134, 0x358637bd, v134
	v_cmp_gt_f32_e32 vcc, s7, v134
	s_nop 1
	v_cndmask_b32_e64 v135, 0, 32, vcc
	v_ldexp_f32 v134, v134, v135
	v_log_f32_e32 v134, v134
	s_nop 0
	v_mul_f32_e32 v135, 0x3f317217, v134
	v_fma_f32 v135, v134, s8, -v135
	v_fmac_f32_e32 v135, 0x3377d1cf, v134
	v_fmac_f32_e32 v135, 0x3f317217, v134
	v_cmp_lt_f32_e64 s[40:41], |v134|, s9
	s_nop 1
	v_cndmask_b32_e64 v134, v134, v135, s[40:41]
	v_cndmask_b32_e32 v135, 0, v226, vcc
	v_sub_f32_e32 v137, v134, v135
	v_mul_f32_e32 v134, 0xbfb8aa3b, v74
	v_exp_f32_e32 v134, v134
	s_nop 0
	v_add_f32_e32 v134, 1.0, v134
	v_rcp_f32_e32 v134, v134
	s_nop 0
	v_fma_f32 v134, v134, v211, v185
	v_max_f32_e32 v134, 0x358637bd, v134
	v_cmp_gt_f32_e32 vcc, s7, v134
	s_nop 1
	v_cndmask_b32_e64 v135, 0, 32, vcc
	v_ldexp_f32 v134, v134, v135
	v_log_f32_e32 v134, v134
	s_nop 0
	v_mul_f32_e32 v135, 0x3f317217, v134
	v_fma_f32 v135, v134, s8, -v135
	v_fmac_f32_e32 v135, 0x3377d1cf, v134
	v_fmac_f32_e32 v135, 0x3f317217, v134
	v_cmp_lt_f32_e64 s[40:41], |v134|, s9
	s_nop 1
	v_cndmask_b32_e64 v134, v134, v135, s[40:41]
	v_cndmask_b32_e32 v135, 0, v226, vcc
	v_sub_f32_e32 v134, v134, v135
	v_mul_f32_e32 v135, 0xbfb8aa3b, v70
	v_exp_f32_e32 v135, v135
	s_nop 0
	v_add_f32_e32 v135, 1.0, v135
	v_rcp_f32_e32 v135, v135
	s_nop 0
	v_fma_f32 v135, v135, v210, v186
	v_max_f32_e32 v135, 0x358637bd, v135
	v_cmp_gt_f32_e32 vcc, s7, v135
	s_nop 1
	v_cndmask_b32_e64 v138, 0, 32, vcc
	v_ldexp_f32 v135, v135, v138
	v_log_f32_e32 v135, v135
	s_nop 0
	v_mul_f32_e32 v138, 0x3f317217, v135
	v_fma_f32 v138, v135, s8, -v138
	v_fmac_f32_e32 v138, 0x3377d1cf, v135
	v_fmac_f32_e32 v138, 0x3f317217, v135
	v_cmp_lt_f32_e64 s[40:41], |v135|, s9
	s_nop 1
	v_cndmask_b32_e64 v135, v135, v138, s[40:41]
	v_cndmask_b32_e32 v138, 0, v226, vcc
	v_sub_f32_e32 v138, v135, v138
	v_mul_f32_e32 v135, 0xbfb8aa3b, v75
	v_exp_f32_e32 v135, v135
	s_nop 0
	v_add_f32_e32 v135, 1.0, v135
	v_rcp_f32_e32 v135, v135
	s_nop 0
	v_fma_f32 v135, v135, v212, v183
	v_max_f32_e32 v135, 0x358637bd, v135
	v_cmp_gt_f32_e32 vcc, s7, v135
	s_nop 1
	v_cndmask_b32_e64 v139, 0, 32, vcc
	v_ldexp_f32 v135, v135, v139
	v_log_f32_e32 v135, v135
	s_nop 0
	v_mul_f32_e32 v139, 0x3f317217, v135
	v_fma_f32 v139, v135, s8, -v139
	v_fmac_f32_e32 v139, 0x3377d1cf, v135
	v_fmac_f32_e32 v139, 0x3f317217, v135
	v_cmp_lt_f32_e64 s[40:41], |v135|, s9
	s_nop 1
	v_cndmask_b32_e64 v135, v135, v139, s[40:41]
	v_cndmask_b32_e32 v139, 0, v226, vcc
	v_sub_f32_e32 v135, v135, v139
	v_mul_f32_e32 v139, 0xbfb8aa3b, v71
	v_exp_f32_e32 v139, v139
	s_nop 0
	v_add_f32_e32 v139, 1.0, v139
	v_rcp_f32_e32 v139, v139
	s_nop 0
	v_fma_f32 v139, v139, v213, v184
	v_max_f32_e32 v139, 0x358637bd, v139
	v_cmp_gt_f32_e32 vcc, s7, v139
	s_nop 1
	v_cndmask_b32_e64 v160, 0, 32, vcc
	v_ldexp_f32 v139, v139, v160
	v_log_f32_e32 v139, v139
	s_nop 0
	v_mul_f32_e32 v160, 0x3f317217, v139
	v_fma_f32 v160, v139, s8, -v160
	v_fmac_f32_e32 v160, 0x3377d1cf, v139
	v_fmac_f32_e32 v160, 0x3f317217, v139
	v_cmp_lt_f32_e64 s[40:41], |v139|, s9
	s_nop 1
	v_cndmask_b32_e64 v139, v139, v160, s[40:41]
	v_cndmask_b32_e32 v160, 0, v226, vcc
	v_sub_f32_e32 v139, v139, v160
	global_store_dwordx4 v[158:159], v[132:135], off offset:512
	global_store_dwordx4 v[158:159], v[136:139], off offset:528
	s_nop 0
	v_mul_f32_e32 v132, 0xbfb8aa3b, v64
	v_exp_f32_e32 v132, v132
	s_nop 0
	v_add_f32_e32 v132, 1.0, v132
	v_rcp_f32_e32 v132, v132
	s_nop 0
	v_fma_f32 v132, v132, v199, v197
	v_max_f32_e32 v132, 0x358637bd, v132
	v_cmp_gt_f32_e32 vcc, s7, v132
	s_nop 1
	v_cndmask_b32_e64 v133, 0, 32, vcc
	v_ldexp_f32 v132, v132, v133
	v_log_f32_e32 v132, v132
	s_nop 0
	v_mul_f32_e32 v133, 0x3f317217, v132
	v_fma_f32 v133, v132, s8, -v133
	v_fmac_f32_e32 v133, 0x3377d1cf, v132
	v_fmac_f32_e32 v133, 0x3f317217, v132
	v_cmp_lt_f32_e64 s[40:41], |v132|, s9
	s_nop 1
	v_cndmask_b32_e64 v132, v132, v133, s[40:41]
	v_cndmask_b32_e32 v133, 0, v226, vcc
	v_sub_f32_e32 v132, v132, v133
	v_mul_f32_e32 v133, 0xbfb8aa3b, v60
	v_exp_f32_e32 v133, v133
	s_nop 0
	v_add_f32_e32 v133, 1.0, v133
	v_rcp_f32_e32 v133, v133
	s_nop 0
	v_fma_f32 v133, v133, v155, v198
	v_max_f32_e32 v133, 0x358637bd, v133
	v_cmp_gt_f32_e32 vcc, s7, v133
	s_nop 1
	v_cndmask_b32_e64 v134, 0, 32, vcc
	v_ldexp_f32 v133, v133, v134
	v_log_f32_e32 v133, v133
	s_nop 0
	v_mul_f32_e32 v134, 0x3f317217, v133
	v_fma_f32 v134, v133, s8, -v134
	v_fmac_f32_e32 v134, 0x3377d1cf, v133
	v_fmac_f32_e32 v134, 0x3f317217, v133
	v_cmp_lt_f32_e64 s[40:41], |v133|, s9
	s_nop 1
	v_cndmask_b32_e64 v133, v133, v134, s[40:41]
	v_cndmask_b32_e32 v134, 0, v226, vcc
	v_sub_f32_e32 v136, v133, v134
	v_mul_f32_e32 v133, 0xbfb8aa3b, v65
	v_exp_f32_e32 v133, v133
	s_nop 0
	v_add_f32_e32 v133, 1.0, v133
	v_rcp_f32_e32 v133, v133
	s_nop 0
	v_fma_f32 v133, v133, v201, v195
	v_max_f32_e32 v133, 0x358637bd, v133
	v_cmp_gt_f32_e32 vcc, s7, v133
	s_nop 1
	v_cndmask_b32_e64 v134, 0, 32, vcc
	v_ldexp_f32 v133, v133, v134
	v_log_f32_e32 v133, v133
	s_nop 0
	v_mul_f32_e32 v134, 0x3f317217, v133
	v_fma_f32 v134, v133, s8, -v134
	v_fmac_f32_e32 v134, 0x3377d1cf, v133
	v_fmac_f32_e32 v134, 0x3f317217, v133
	v_cmp_lt_f32_e64 s[40:41], |v133|, s9
	s_nop 1
	v_cndmask_b32_e64 v133, v133, v134, s[40:41]
	v_cndmask_b32_e32 v134, 0, v226, vcc
	v_sub_f32_e32 v133, v133, v134
	v_mul_f32_e32 v134, 0xbfb8aa3b, v61
	v_exp_f32_e32 v134, v134
	s_nop 0
	v_add_f32_e32 v134, 1.0, v134
	v_rcp_f32_e32 v134, v134
	s_nop 0
	v_fma_f32 v134, v134, v200, v196
	v_max_f32_e32 v134, 0x358637bd, v134
	v_cmp_gt_f32_e32 vcc, s7, v134
	s_nop 1
	v_cndmask_b32_e64 v135, 0, 32, vcc
	v_ldexp_f32 v134, v134, v135
	v_log_f32_e32 v134, v134
	s_nop 0
	v_mul_f32_e32 v135, 0x3f317217, v134
	v_fma_f32 v135, v134, s8, -v135
	v_fmac_f32_e32 v135, 0x3377d1cf, v134
	v_fmac_f32_e32 v135, 0x3f317217, v134
	v_cmp_lt_f32_e64 s[40:41], |v134|, s9
	s_nop 1
	v_cndmask_b32_e64 v134, v134, v135, s[40:41]
	v_cndmask_b32_e32 v135, 0, v226, vcc
	v_sub_f32_e32 v137, v134, v135
	v_mul_f32_e32 v134, 0xbfb8aa3b, v66
	v_exp_f32_e32 v134, v134
	s_nop 0
	v_add_f32_e32 v134, 1.0, v134
	v_rcp_f32_e32 v134, v134
	s_nop 0
	v_fma_f32 v134, v134, v203, v193
	v_max_f32_e32 v134, 0x358637bd, v134
	v_cmp_gt_f32_e32 vcc, s7, v134
	s_nop 1
	v_cndmask_b32_e64 v135, 0, 32, vcc
	v_ldexp_f32 v134, v134, v135
	v_log_f32_e32 v134, v134
	s_nop 0
	v_mul_f32_e32 v135, 0x3f317217, v134
	v_fma_f32 v135, v134, s8, -v135
	v_fmac_f32_e32 v135, 0x3377d1cf, v134
	v_fmac_f32_e32 v135, 0x3f317217, v134
	v_cmp_lt_f32_e64 s[40:41], |v134|, s9
	s_nop 1
	v_cndmask_b32_e64 v134, v134, v135, s[40:41]
	v_cndmask_b32_e32 v135, 0, v226, vcc
	v_sub_f32_e32 v134, v134, v135
	v_mul_f32_e32 v135, 0xbfb8aa3b, v62
	v_exp_f32_e32 v135, v135
	s_nop 0
	v_add_f32_e32 v135, 1.0, v135
	v_rcp_f32_e32 v135, v135
	s_nop 0
	v_fma_f32 v135, v135, v202, v194
	v_max_f32_e32 v135, 0x358637bd, v135
	v_cmp_gt_f32_e32 vcc, s7, v135
	s_nop 1
	v_cndmask_b32_e64 v138, 0, 32, vcc
	v_ldexp_f32 v135, v135, v138
	v_log_f32_e32 v135, v135
	s_nop 0
	v_mul_f32_e32 v138, 0x3f317217, v135
	v_fma_f32 v138, v135, s8, -v138
	v_fmac_f32_e32 v138, 0x3377d1cf, v135
	v_fmac_f32_e32 v138, 0x3f317217, v135
	v_cmp_lt_f32_e64 s[40:41], |v135|, s9
	s_nop 1
	v_cndmask_b32_e64 v135, v135, v138, s[40:41]
	v_cndmask_b32_e32 v138, 0, v226, vcc
	v_sub_f32_e32 v138, v135, v138
	v_mul_f32_e32 v135, 0xbfb8aa3b, v67
	v_exp_f32_e32 v135, v135
	s_nop 0
	v_add_f32_e32 v135, 1.0, v135
	v_rcp_f32_e32 v135, v135
	s_nop 0
	v_fma_f32 v135, v135, v204, v189
	v_max_f32_e32 v135, 0x358637bd, v135
	v_cmp_gt_f32_e32 vcc, s7, v135
	s_nop 1
	v_cndmask_b32_e64 v139, 0, 32, vcc
	v_ldexp_f32 v135, v135, v139
	v_log_f32_e32 v135, v135
	s_nop 0
	v_mul_f32_e32 v139, 0x3f317217, v135
	v_fma_f32 v139, v135, s8, -v139
	v_fmac_f32_e32 v139, 0x3377d1cf, v135
	v_fmac_f32_e32 v139, 0x3f317217, v135
	v_cmp_lt_f32_e64 s[40:41], |v135|, s9
	s_nop 1
	v_cndmask_b32_e64 v135, v135, v139, s[40:41]
	v_cndmask_b32_e32 v139, 0, v226, vcc
	v_sub_f32_e32 v135, v135, v139
	v_mul_f32_e32 v139, 0xbfb8aa3b, v63
	v_exp_f32_e32 v139, v139
	s_nop 0
	v_add_f32_e32 v139, 1.0, v139
	v_rcp_f32_e32 v139, v139
	s_nop 0
	v_fma_f32 v139, v139, v205, v191
	v_max_f32_e32 v139, 0x358637bd, v139
	v_cmp_gt_f32_e32 vcc, s7, v139
	s_nop 1
	v_cndmask_b32_e64 v158, 0, 32, vcc
	v_ldexp_f32 v139, v139, v158
	v_log_f32_e32 v139, v139
	s_nop 0
	v_mul_f32_e32 v158, 0x3f317217, v139
	v_fma_f32 v158, v139, s8, -v158
	v_fmac_f32_e32 v158, 0x3377d1cf, v139
	v_fmac_f32_e32 v158, 0x3f317217, v139
	v_cmp_lt_f32_e64 s[40:41], |v139|, s9
	s_nop 1
	v_cndmask_b32_e64 v139, v139, v158, s[40:41]
	v_cndmask_b32_e32 v158, 0, v226, vcc
	v_add_co_u32_e32 v160, vcc, s6, v156
	v_sub_f32_e32 v139, v139, v158
	s_nop 0
	v_addc_co_u32_e32 v161, vcc, 0, v157, vcc
	v_lshl_add_u64 v[158:159], v[156:157], 0, s[10:11]
	global_store_dwordx4 v[160:161], v[132:135], off
	global_store_dwordx4 v[158:159], v[136:139], off offset:16
	s_mov_b32 s6, 0x120000
	v_mul_f32_e32 v132, 0xbfb8aa3b, v56
	v_exp_f32_e32 v132, v132
	s_mov_b64 s[10:11], 0x120000
	v_add_f32_e32 v132, 1.0, v132
	v_rcp_f32_e32 v132, v132
	s_nop 0
	v_fma_f32 v132, v132, v206, v190
	v_max_f32_e32 v132, 0x358637bd, v132
	v_cmp_gt_f32_e32 vcc, s7, v132
	s_nop 1
	v_cndmask_b32_e64 v133, 0, 32, vcc
	v_ldexp_f32 v132, v132, v133
	v_log_f32_e32 v132, v132
	s_nop 0
	v_mul_f32_e32 v133, 0x3f317217, v132
	v_fma_f32 v133, v132, s8, -v133
	v_fmac_f32_e32 v133, 0x3377d1cf, v132
	v_fmac_f32_e32 v133, 0x3f317217, v132
	v_cmp_lt_f32_e64 s[40:41], |v132|, s9
	s_nop 1
	v_cndmask_b32_e64 v132, v132, v133, s[40:41]
	v_cndmask_b32_e32 v133, 0, v226, vcc
	v_sub_f32_e32 v132, v132, v133
	v_mul_f32_e32 v133, 0xbfb8aa3b, v52
	v_exp_f32_e32 v133, v133
	s_nop 0
	v_add_f32_e32 v133, 1.0, v133
	v_rcp_f32_e32 v133, v133
	s_nop 0
	v_fma_f32 v133, v133, v207, v192
	v_max_f32_e32 v133, 0x358637bd, v133
	v_cmp_gt_f32_e32 vcc, s7, v133
	s_nop 1
	v_cndmask_b32_e64 v134, 0, 32, vcc
	v_ldexp_f32 v133, v133, v134
	v_log_f32_e32 v133, v133
	s_nop 0
	v_mul_f32_e32 v134, 0x3f317217, v133
	v_fma_f32 v134, v133, s8, -v134
	v_fmac_f32_e32 v134, 0x3377d1cf, v133
	v_fmac_f32_e32 v134, 0x3f317217, v133
	v_cmp_lt_f32_e64 s[40:41], |v133|, s9
	s_nop 1
	v_cndmask_b32_e64 v133, v133, v134, s[40:41]
	v_cndmask_b32_e32 v134, 0, v226, vcc
	v_sub_f32_e32 v136, v133, v134
	v_mul_f32_e32 v133, 0xbfb8aa3b, v57
	v_exp_f32_e32 v133, v133
	s_nop 0
	v_add_f32_e32 v133, 1.0, v133
	v_rcp_f32_e32 v133, v133
	s_nop 0
	v_fma_f32 v133, v133, v209, v187
	v_max_f32_e32 v133, 0x358637bd, v133
	v_cmp_gt_f32_e32 vcc, s7, v133
	s_nop 1
	v_cndmask_b32_e64 v134, 0, 32, vcc
	v_ldexp_f32 v133, v133, v134
	v_log_f32_e32 v133, v133
	s_nop 0
	v_mul_f32_e32 v134, 0x3f317217, v133
	v_fma_f32 v134, v133, s8, -v134
	v_fmac_f32_e32 v134, 0x3377d1cf, v133
	v_fmac_f32_e32 v134, 0x3f317217, v133
	v_cmp_lt_f32_e64 s[40:41], |v133|, s9
	s_nop 1
	v_cndmask_b32_e64 v133, v133, v134, s[40:41]
	v_cndmask_b32_e32 v134, 0, v226, vcc
	v_sub_f32_e32 v133, v133, v134
	v_mul_f32_e32 v134, 0xbfb8aa3b, v53
	v_exp_f32_e32 v134, v134
	s_nop 0
	v_add_f32_e32 v134, 1.0, v134
	v_rcp_f32_e32 v134, v134
	s_nop 0
	v_fma_f32 v134, v134, v208, v188
	v_max_f32_e32 v134, 0x358637bd, v134
	v_cmp_gt_f32_e32 vcc, s7, v134
	s_nop 1
	v_cndmask_b32_e64 v135, 0, 32, vcc
	v_ldexp_f32 v134, v134, v135
	v_log_f32_e32 v134, v134
	s_nop 0
	v_mul_f32_e32 v135, 0x3f317217, v134
	v_fma_f32 v135, v134, s8, -v135
	v_fmac_f32_e32 v135, 0x3377d1cf, v134
	v_fmac_f32_e32 v135, 0x3f317217, v134
	v_cmp_lt_f32_e64 s[40:41], |v134|, s9
	s_nop 1
	v_cndmask_b32_e64 v134, v134, v135, s[40:41]
	v_cndmask_b32_e32 v135, 0, v226, vcc
	v_sub_f32_e32 v137, v134, v135
	v_mul_f32_e32 v134, 0xbfb8aa3b, v58
	v_exp_f32_e32 v134, v134
	s_nop 0
	v_add_f32_e32 v134, 1.0, v134
	v_rcp_f32_e32 v134, v134
	s_nop 0
	v_fma_f32 v134, v134, v211, v185
	v_max_f32_e32 v134, 0x358637bd, v134
	v_cmp_gt_f32_e32 vcc, s7, v134
	s_nop 1
	v_cndmask_b32_e64 v135, 0, 32, vcc
	v_ldexp_f32 v134, v134, v135
	v_log_f32_e32 v134, v134
	s_nop 0
	v_mul_f32_e32 v135, 0x3f317217, v134
	v_fma_f32 v135, v134, s8, -v135
	v_fmac_f32_e32 v135, 0x3377d1cf, v134
	v_fmac_f32_e32 v135, 0x3f317217, v134
	v_cmp_lt_f32_e64 s[40:41], |v134|, s9
	s_nop 1
	v_cndmask_b32_e64 v134, v134, v135, s[40:41]
	v_cndmask_b32_e32 v135, 0, v226, vcc
	v_sub_f32_e32 v134, v134, v135
	v_mul_f32_e32 v135, 0xbfb8aa3b, v54
	v_exp_f32_e32 v135, v135
	s_nop 0
	v_add_f32_e32 v135, 1.0, v135
	v_rcp_f32_e32 v135, v135
	s_nop 0
	v_fma_f32 v135, v135, v210, v186
	v_max_f32_e32 v135, 0x358637bd, v135
	v_cmp_gt_f32_e32 vcc, s7, v135
	s_nop 1
	v_cndmask_b32_e64 v138, 0, 32, vcc
	v_ldexp_f32 v135, v135, v138
	v_log_f32_e32 v135, v135
	s_nop 0
	v_mul_f32_e32 v138, 0x3f317217, v135
	v_fma_f32 v138, v135, s8, -v138
	v_fmac_f32_e32 v138, 0x3377d1cf, v135
	v_fmac_f32_e32 v138, 0x3f317217, v135
	v_cmp_lt_f32_e64 s[40:41], |v135|, s9
	s_nop 1
	v_cndmask_b32_e64 v135, v135, v138, s[40:41]
	v_cndmask_b32_e32 v138, 0, v226, vcc
	v_sub_f32_e32 v138, v135, v138
	v_mul_f32_e32 v135, 0xbfb8aa3b, v59
	v_exp_f32_e32 v135, v135
	s_nop 0
	v_add_f32_e32 v135, 1.0, v135
	v_rcp_f32_e32 v135, v135
	s_nop 0
	v_fma_f32 v135, v135, v212, v183
	v_max_f32_e32 v135, 0x358637bd, v135
	v_cmp_gt_f32_e32 vcc, s7, v135
	s_nop 1
	v_cndmask_b32_e64 v139, 0, 32, vcc
	v_ldexp_f32 v135, v135, v139
	v_log_f32_e32 v135, v135
	s_nop 0
	v_mul_f32_e32 v139, 0x3f317217, v135
	v_fma_f32 v139, v135, s8, -v139
	v_fmac_f32_e32 v139, 0x3377d1cf, v135
	v_fmac_f32_e32 v139, 0x3f317217, v135
	v_cmp_lt_f32_e64 s[40:41], |v135|, s9
	s_nop 1
	v_cndmask_b32_e64 v135, v135, v139, s[40:41]
	v_cndmask_b32_e32 v139, 0, v226, vcc
	v_sub_f32_e32 v135, v135, v139
	v_mul_f32_e32 v139, 0xbfb8aa3b, v55
	v_exp_f32_e32 v139, v139
	s_nop 0
	v_add_f32_e32 v139, 1.0, v139
	v_rcp_f32_e32 v139, v139
	s_nop 0
	v_fma_f32 v139, v139, v213, v184
	v_max_f32_e32 v139, 0x358637bd, v139
	v_cmp_gt_f32_e32 vcc, s7, v139
	s_nop 1
	v_cndmask_b32_e64 v160, 0, 32, vcc
	v_ldexp_f32 v139, v139, v160
	v_log_f32_e32 v139, v139
	s_nop 0
	v_mul_f32_e32 v160, 0x3f317217, v139
	v_fma_f32 v160, v139, s8, -v160
	v_fmac_f32_e32 v160, 0x3377d1cf, v139
	v_fmac_f32_e32 v160, 0x3f317217, v139
	v_cmp_lt_f32_e64 s[40:41], |v139|, s9
	s_nop 1
	v_cndmask_b32_e64 v139, v139, v160, s[40:41]
	v_cndmask_b32_e32 v160, 0, v226, vcc
	v_sub_f32_e32 v139, v139, v160
	global_store_dwordx4 v[158:159], v[132:135], off offset:512
	global_store_dwordx4 v[158:159], v[136:139], off offset:528
	s_nop 0
	v_mul_f32_e32 v132, 0xbfb8aa3b, v48
	v_exp_f32_e32 v132, v132
	s_nop 0
	v_add_f32_e32 v132, 1.0, v132
	v_rcp_f32_e32 v132, v132
	s_nop 0
	v_fma_f32 v132, v132, v199, v197
	v_max_f32_e32 v132, 0x358637bd, v132
	v_cmp_gt_f32_e32 vcc, s7, v132
	s_nop 1
	v_cndmask_b32_e64 v133, 0, 32, vcc
	v_ldexp_f32 v132, v132, v133
	v_log_f32_e32 v132, v132
	s_nop 0
	v_mul_f32_e32 v133, 0x3f317217, v132
	v_fma_f32 v133, v132, s8, -v133
	v_fmac_f32_e32 v133, 0x3377d1cf, v132
	v_fmac_f32_e32 v133, 0x3f317217, v132
	v_cmp_lt_f32_e64 s[40:41], |v132|, s9
	s_nop 1
	v_cndmask_b32_e64 v132, v132, v133, s[40:41]
	v_cndmask_b32_e32 v133, 0, v226, vcc
	v_sub_f32_e32 v132, v132, v133
	v_mul_f32_e32 v133, 0xbfb8aa3b, v44
	v_exp_f32_e32 v133, v133
	s_nop 0
	v_add_f32_e32 v133, 1.0, v133
	v_rcp_f32_e32 v133, v133
	s_nop 0
	v_fma_f32 v133, v133, v155, v198
	v_max_f32_e32 v133, 0x358637bd, v133
	v_cmp_gt_f32_e32 vcc, s7, v133
	s_nop 1
	v_cndmask_b32_e64 v134, 0, 32, vcc
	v_ldexp_f32 v133, v133, v134
	v_log_f32_e32 v133, v133
	s_nop 0
	v_mul_f32_e32 v134, 0x3f317217, v133
	v_fma_f32 v134, v133, s8, -v134
	v_fmac_f32_e32 v134, 0x3377d1cf, v133
	v_fmac_f32_e32 v134, 0x3f317217, v133
	v_cmp_lt_f32_e64 s[40:41], |v133|, s9
	s_nop 1
	v_cndmask_b32_e64 v133, v133, v134, s[40:41]
	v_cndmask_b32_e32 v134, 0, v226, vcc
	v_sub_f32_e32 v136, v133, v134
	v_mul_f32_e32 v133, 0xbfb8aa3b, v49
	v_exp_f32_e32 v133, v133
	s_nop 0
	v_add_f32_e32 v133, 1.0, v133
	v_rcp_f32_e32 v133, v133
	s_nop 0
	v_fma_f32 v133, v133, v201, v195
	v_max_f32_e32 v133, 0x358637bd, v133
	v_cmp_gt_f32_e32 vcc, s7, v133
	s_nop 1
	v_cndmask_b32_e64 v134, 0, 32, vcc
	v_ldexp_f32 v133, v133, v134
	v_log_f32_e32 v133, v133
	s_nop 0
	v_mul_f32_e32 v134, 0x3f317217, v133
	v_fma_f32 v134, v133, s8, -v134
	v_fmac_f32_e32 v134, 0x3377d1cf, v133
	v_fmac_f32_e32 v134, 0x3f317217, v133
	v_cmp_lt_f32_e64 s[40:41], |v133|, s9
	s_nop 1
	v_cndmask_b32_e64 v133, v133, v134, s[40:41]
	v_cndmask_b32_e32 v134, 0, v226, vcc
	v_sub_f32_e32 v133, v133, v134
	v_mul_f32_e32 v134, 0xbfb8aa3b, v45
	v_exp_f32_e32 v134, v134
	s_nop 0
	v_add_f32_e32 v134, 1.0, v134
	v_rcp_f32_e32 v134, v134
	s_nop 0
	v_fma_f32 v134, v134, v200, v196
	v_max_f32_e32 v134, 0x358637bd, v134
	v_cmp_gt_f32_e32 vcc, s7, v134
	s_nop 1
	v_cndmask_b32_e64 v135, 0, 32, vcc
	v_ldexp_f32 v134, v134, v135
	v_log_f32_e32 v134, v134
	s_nop 0
	v_mul_f32_e32 v135, 0x3f317217, v134
	v_fma_f32 v135, v134, s8, -v135
	v_fmac_f32_e32 v135, 0x3377d1cf, v134
	v_fmac_f32_e32 v135, 0x3f317217, v134
	v_cmp_lt_f32_e64 s[40:41], |v134|, s9
	s_nop 1
	v_cndmask_b32_e64 v134, v134, v135, s[40:41]
	v_cndmask_b32_e32 v135, 0, v226, vcc
	v_sub_f32_e32 v137, v134, v135
	v_mul_f32_e32 v134, 0xbfb8aa3b, v50
	v_exp_f32_e32 v134, v134
	s_nop 0
	v_add_f32_e32 v134, 1.0, v134
	v_rcp_f32_e32 v134, v134
	s_nop 0
	v_fma_f32 v134, v134, v203, v193
	v_max_f32_e32 v134, 0x358637bd, v134
	v_cmp_gt_f32_e32 vcc, s7, v134
	s_nop 1
	v_cndmask_b32_e64 v135, 0, 32, vcc
	v_ldexp_f32 v134, v134, v135
	v_log_f32_e32 v134, v134
	s_nop 0
	v_mul_f32_e32 v135, 0x3f317217, v134
	v_fma_f32 v135, v134, s8, -v135
	v_fmac_f32_e32 v135, 0x3377d1cf, v134
	v_fmac_f32_e32 v135, 0x3f317217, v134
	v_cmp_lt_f32_e64 s[40:41], |v134|, s9
	s_nop 1
	v_cndmask_b32_e64 v134, v134, v135, s[40:41]
	v_cndmask_b32_e32 v135, 0, v226, vcc
	v_sub_f32_e32 v134, v134, v135
	v_mul_f32_e32 v135, 0xbfb8aa3b, v46
	v_exp_f32_e32 v135, v135
	s_nop 0
	v_add_f32_e32 v135, 1.0, v135
	v_rcp_f32_e32 v135, v135
	s_nop 0
	v_fma_f32 v135, v135, v202, v194
	v_max_f32_e32 v135, 0x358637bd, v135
	v_cmp_gt_f32_e32 vcc, s7, v135
	s_nop 1
	v_cndmask_b32_e64 v138, 0, 32, vcc
	v_ldexp_f32 v135, v135, v138
	v_log_f32_e32 v135, v135
	s_nop 0
	v_mul_f32_e32 v138, 0x3f317217, v135
	v_fma_f32 v138, v135, s8, -v138
	v_fmac_f32_e32 v138, 0x3377d1cf, v135
	v_fmac_f32_e32 v138, 0x3f317217, v135
	v_cmp_lt_f32_e64 s[40:41], |v135|, s9
	s_nop 1
	v_cndmask_b32_e64 v135, v135, v138, s[40:41]
	v_cndmask_b32_e32 v138, 0, v226, vcc
	v_sub_f32_e32 v138, v135, v138
	v_mul_f32_e32 v135, 0xbfb8aa3b, v51
	v_exp_f32_e32 v135, v135
	s_nop 0
	v_add_f32_e32 v135, 1.0, v135
	v_rcp_f32_e32 v135, v135
	s_nop 0
	v_fma_f32 v135, v135, v204, v189
	v_max_f32_e32 v135, 0x358637bd, v135
	v_cmp_gt_f32_e32 vcc, s7, v135
	s_nop 1
	v_cndmask_b32_e64 v139, 0, 32, vcc
	v_ldexp_f32 v135, v135, v139
	v_log_f32_e32 v135, v135
	s_nop 0
	v_mul_f32_e32 v139, 0x3f317217, v135
	v_fma_f32 v139, v135, s8, -v139
	v_fmac_f32_e32 v139, 0x3377d1cf, v135
	v_fmac_f32_e32 v139, 0x3f317217, v135
	v_cmp_lt_f32_e64 s[40:41], |v135|, s9
	s_nop 1
	v_cndmask_b32_e64 v135, v135, v139, s[40:41]
	v_cndmask_b32_e32 v139, 0, v226, vcc
	v_sub_f32_e32 v135, v135, v139
	v_mul_f32_e32 v139, 0xbfb8aa3b, v47
	v_exp_f32_e32 v139, v139
	s_nop 0
	v_add_f32_e32 v139, 1.0, v139
	v_rcp_f32_e32 v139, v139
	s_nop 0
	v_fma_f32 v139, v139, v205, v191
	v_max_f32_e32 v139, 0x358637bd, v139
	v_cmp_gt_f32_e32 vcc, s7, v139
	s_nop 1
	v_cndmask_b32_e64 v158, 0, 32, vcc
	v_ldexp_f32 v139, v139, v158
	v_log_f32_e32 v139, v139
	s_nop 0
	v_mul_f32_e32 v158, 0x3f317217, v139
	v_fma_f32 v158, v139, s8, -v158
	v_fmac_f32_e32 v158, 0x3377d1cf, v139
	v_fmac_f32_e32 v158, 0x3f317217, v139
	v_cmp_lt_f32_e64 s[40:41], |v139|, s9
	s_nop 1
	v_cndmask_b32_e64 v139, v139, v158, s[40:41]
	v_cndmask_b32_e32 v158, 0, v226, vcc
	v_add_co_u32_e32 v160, vcc, s6, v156
	v_sub_f32_e32 v139, v139, v158
	s_nop 0
	v_addc_co_u32_e32 v161, vcc, 0, v157, vcc
	v_lshl_add_u64 v[158:159], v[156:157], 0, s[10:11]
	global_store_dwordx4 v[160:161], v[132:135], off
	global_store_dwordx4 v[158:159], v[136:139], off offset:16
	s_mov_b32 s6, 0x140000
	v_mul_f32_e32 v132, 0xbfb8aa3b, v40
	v_exp_f32_e32 v132, v132
	s_mov_b64 s[10:11], 0x140000
	v_add_f32_e32 v132, 1.0, v132
	v_rcp_f32_e32 v132, v132
	s_nop 0
	v_fma_f32 v132, v132, v206, v190
	v_max_f32_e32 v132, 0x358637bd, v132
	v_cmp_gt_f32_e32 vcc, s7, v132
	s_nop 1
	v_cndmask_b32_e64 v133, 0, 32, vcc
	v_ldexp_f32 v132, v132, v133
	v_log_f32_e32 v132, v132
	s_nop 0
	v_mul_f32_e32 v133, 0x3f317217, v132
	v_fma_f32 v133, v132, s8, -v133
	v_fmac_f32_e32 v133, 0x3377d1cf, v132
	v_fmac_f32_e32 v133, 0x3f317217, v132
	v_cmp_lt_f32_e64 s[40:41], |v132|, s9
	s_nop 1
	v_cndmask_b32_e64 v132, v132, v133, s[40:41]
	v_cndmask_b32_e32 v133, 0, v226, vcc
	v_sub_f32_e32 v132, v132, v133
	v_mul_f32_e32 v133, 0xbfb8aa3b, v36
	v_exp_f32_e32 v133, v133
	s_nop 0
	v_add_f32_e32 v133, 1.0, v133
	v_rcp_f32_e32 v133, v133
	s_nop 0
	v_fma_f32 v133, v133, v207, v192
	v_max_f32_e32 v133, 0x358637bd, v133
	v_cmp_gt_f32_e32 vcc, s7, v133
	s_nop 1
	v_cndmask_b32_e64 v134, 0, 32, vcc
	v_ldexp_f32 v133, v133, v134
	v_log_f32_e32 v133, v133
	s_nop 0
	v_mul_f32_e32 v134, 0x3f317217, v133
	v_fma_f32 v134, v133, s8, -v134
	v_fmac_f32_e32 v134, 0x3377d1cf, v133
	v_fmac_f32_e32 v134, 0x3f317217, v133
	v_cmp_lt_f32_e64 s[40:41], |v133|, s9
	s_nop 1
	v_cndmask_b32_e64 v133, v133, v134, s[40:41]
	v_cndmask_b32_e32 v134, 0, v226, vcc
	v_sub_f32_e32 v136, v133, v134
	v_mul_f32_e32 v133, 0xbfb8aa3b, v41
	v_exp_f32_e32 v133, v133
	s_nop 0
	v_add_f32_e32 v133, 1.0, v133
	v_rcp_f32_e32 v133, v133
	s_nop 0
	v_fma_f32 v133, v133, v209, v187
	v_max_f32_e32 v133, 0x358637bd, v133
	v_cmp_gt_f32_e32 vcc, s7, v133
	s_nop 1
	v_cndmask_b32_e64 v134, 0, 32, vcc
	v_ldexp_f32 v133, v133, v134
	v_log_f32_e32 v133, v133
	s_nop 0
	v_mul_f32_e32 v134, 0x3f317217, v133
	v_fma_f32 v134, v133, s8, -v134
	v_fmac_f32_e32 v134, 0x3377d1cf, v133
	v_fmac_f32_e32 v134, 0x3f317217, v133
	v_cmp_lt_f32_e64 s[40:41], |v133|, s9
	s_nop 1
	v_cndmask_b32_e64 v133, v133, v134, s[40:41]
	v_cndmask_b32_e32 v134, 0, v226, vcc
	v_sub_f32_e32 v133, v133, v134
	v_mul_f32_e32 v134, 0xbfb8aa3b, v37
	v_exp_f32_e32 v134, v134
	s_nop 0
	v_add_f32_e32 v134, 1.0, v134
	v_rcp_f32_e32 v134, v134
	s_nop 0
	v_fma_f32 v134, v134, v208, v188
	v_max_f32_e32 v134, 0x358637bd, v134
	v_cmp_gt_f32_e32 vcc, s7, v134
	s_nop 1
	v_cndmask_b32_e64 v135, 0, 32, vcc
	v_ldexp_f32 v134, v134, v135
	v_log_f32_e32 v134, v134
	s_nop 0
	v_mul_f32_e32 v135, 0x3f317217, v134
	v_fma_f32 v135, v134, s8, -v135
	v_fmac_f32_e32 v135, 0x3377d1cf, v134
	v_fmac_f32_e32 v135, 0x3f317217, v134
	v_cmp_lt_f32_e64 s[40:41], |v134|, s9
	s_nop 1
	v_cndmask_b32_e64 v134, v134, v135, s[40:41]
	v_cndmask_b32_e32 v135, 0, v226, vcc
	v_sub_f32_e32 v137, v134, v135
	v_mul_f32_e32 v134, 0xbfb8aa3b, v42
	v_exp_f32_e32 v134, v134
	s_nop 0
	v_add_f32_e32 v134, 1.0, v134
	v_rcp_f32_e32 v134, v134
	s_nop 0
	v_fma_f32 v134, v134, v211, v185
	v_max_f32_e32 v134, 0x358637bd, v134
	v_cmp_gt_f32_e32 vcc, s7, v134
	s_nop 1
	v_cndmask_b32_e64 v135, 0, 32, vcc
	v_ldexp_f32 v134, v134, v135
	v_log_f32_e32 v134, v134
	s_nop 0
	v_mul_f32_e32 v135, 0x3f317217, v134
	v_fma_f32 v135, v134, s8, -v135
	v_fmac_f32_e32 v135, 0x3377d1cf, v134
	v_fmac_f32_e32 v135, 0x3f317217, v134
	v_cmp_lt_f32_e64 s[40:41], |v134|, s9
	s_nop 1
	v_cndmask_b32_e64 v134, v134, v135, s[40:41]
	v_cndmask_b32_e32 v135, 0, v226, vcc
	v_sub_f32_e32 v134, v134, v135
	v_mul_f32_e32 v135, 0xbfb8aa3b, v38
	v_exp_f32_e32 v135, v135
	s_nop 0
	v_add_f32_e32 v135, 1.0, v135
	v_rcp_f32_e32 v135, v135
	s_nop 0
	v_fma_f32 v135, v135, v210, v186
	v_max_f32_e32 v135, 0x358637bd, v135
	v_cmp_gt_f32_e32 vcc, s7, v135
	s_nop 1
	v_cndmask_b32_e64 v138, 0, 32, vcc
	v_ldexp_f32 v135, v135, v138
	v_log_f32_e32 v135, v135
	s_nop 0
	v_mul_f32_e32 v138, 0x3f317217, v135
	v_fma_f32 v138, v135, s8, -v138
	v_fmac_f32_e32 v138, 0x3377d1cf, v135
	v_fmac_f32_e32 v138, 0x3f317217, v135
	v_cmp_lt_f32_e64 s[40:41], |v135|, s9
	s_nop 1
	v_cndmask_b32_e64 v135, v135, v138, s[40:41]
	v_cndmask_b32_e32 v138, 0, v226, vcc
	v_sub_f32_e32 v138, v135, v138
	v_mul_f32_e32 v135, 0xbfb8aa3b, v43
	v_exp_f32_e32 v135, v135
	s_nop 0
	v_add_f32_e32 v135, 1.0, v135
	v_rcp_f32_e32 v135, v135
	s_nop 0
	v_fma_f32 v135, v135, v212, v183
	v_max_f32_e32 v135, 0x358637bd, v135
	v_cmp_gt_f32_e32 vcc, s7, v135
	s_nop 1
	v_cndmask_b32_e64 v139, 0, 32, vcc
	v_ldexp_f32 v135, v135, v139
	v_log_f32_e32 v135, v135
	s_nop 0
	v_mul_f32_e32 v139, 0x3f317217, v135
	v_fma_f32 v139, v135, s8, -v139
	v_fmac_f32_e32 v139, 0x3377d1cf, v135
	v_fmac_f32_e32 v139, 0x3f317217, v135
	v_cmp_lt_f32_e64 s[40:41], |v135|, s9
	s_nop 1
	v_cndmask_b32_e64 v135, v135, v139, s[40:41]
	v_cndmask_b32_e32 v139, 0, v226, vcc
	v_sub_f32_e32 v135, v135, v139
	v_mul_f32_e32 v139, 0xbfb8aa3b, v39
	v_exp_f32_e32 v139, v139
	s_nop 0
	v_add_f32_e32 v139, 1.0, v139
	v_rcp_f32_e32 v139, v139
	s_nop 0
	v_fma_f32 v139, v139, v213, v184
	v_max_f32_e32 v139, 0x358637bd, v139
	v_cmp_gt_f32_e32 vcc, s7, v139
	s_nop 1
	v_cndmask_b32_e64 v160, 0, 32, vcc
	v_ldexp_f32 v139, v139, v160
	v_log_f32_e32 v139, v139
	s_nop 0
	v_mul_f32_e32 v160, 0x3f317217, v139
	v_fma_f32 v160, v139, s8, -v160
	v_fmac_f32_e32 v160, 0x3377d1cf, v139
	v_fmac_f32_e32 v160, 0x3f317217, v139
	v_cmp_lt_f32_e64 s[40:41], |v139|, s9
	s_nop 1
	v_cndmask_b32_e64 v139, v139, v160, s[40:41]
	v_cndmask_b32_e32 v160, 0, v226, vcc
	v_sub_f32_e32 v139, v139, v160
	global_store_dwordx4 v[158:159], v[132:135], off offset:512
	global_store_dwordx4 v[158:159], v[136:139], off offset:528
	s_nop 0
	v_mul_f32_e32 v132, 0xbfb8aa3b, v30
	v_exp_f32_e32 v132, v132
	s_nop 0
	v_add_f32_e32 v132, 1.0, v132
	v_rcp_f32_e32 v132, v132
	s_nop 0
	v_fma_f32 v132, v132, v199, v197
	v_max_f32_e32 v132, 0x358637bd, v132
	v_cmp_gt_f32_e32 vcc, s7, v132
	s_nop 1
	v_cndmask_b32_e64 v133, 0, 32, vcc
	v_ldexp_f32 v132, v132, v133
	v_log_f32_e32 v132, v132
	s_nop 0
	v_mul_f32_e32 v133, 0x3f317217, v132
	v_fma_f32 v133, v132, s8, -v133
	v_fmac_f32_e32 v133, 0x3377d1cf, v132
	v_fmac_f32_e32 v133, 0x3f317217, v132
	v_cmp_lt_f32_e64 s[40:41], |v132|, s9
	s_nop 1
	v_cndmask_b32_e64 v132, v132, v133, s[40:41]
	v_cndmask_b32_e32 v133, 0, v226, vcc
	v_sub_f32_e32 v132, v132, v133
	v_mul_f32_e32 v133, 0xbfb8aa3b, v26
	v_exp_f32_e32 v133, v133
	s_nop 0
	v_add_f32_e32 v133, 1.0, v133
	v_rcp_f32_e32 v133, v133
	s_nop 0
	v_fma_f32 v133, v133, v155, v198
	v_max_f32_e32 v133, 0x358637bd, v133
	v_cmp_gt_f32_e32 vcc, s7, v133
	s_nop 1
	v_cndmask_b32_e64 v134, 0, 32, vcc
	v_ldexp_f32 v133, v133, v134
	v_log_f32_e32 v133, v133
	s_nop 0
	v_mul_f32_e32 v134, 0x3f317217, v133
	v_fma_f32 v134, v133, s8, -v134
	v_fmac_f32_e32 v134, 0x3377d1cf, v133
	v_fmac_f32_e32 v134, 0x3f317217, v133
	v_cmp_lt_f32_e64 s[40:41], |v133|, s9
	s_nop 1
	v_cndmask_b32_e64 v133, v133, v134, s[40:41]
	v_cndmask_b32_e32 v134, 0, v226, vcc
	v_sub_f32_e32 v136, v133, v134
	v_mul_f32_e32 v133, 0xbfb8aa3b, v31
	v_exp_f32_e32 v133, v133
	s_nop 0
	v_add_f32_e32 v133, 1.0, v133
	v_rcp_f32_e32 v133, v133
	s_nop 0
	v_fma_f32 v133, v133, v201, v195
	v_max_f32_e32 v133, 0x358637bd, v133
	v_cmp_gt_f32_e32 vcc, s7, v133
	s_nop 1
	v_cndmask_b32_e64 v134, 0, 32, vcc
	v_ldexp_f32 v133, v133, v134
	v_log_f32_e32 v133, v133
	s_nop 0
	v_mul_f32_e32 v134, 0x3f317217, v133
	v_fma_f32 v134, v133, s8, -v134
	v_fmac_f32_e32 v134, 0x3377d1cf, v133
	v_fmac_f32_e32 v134, 0x3f317217, v133
	v_cmp_lt_f32_e64 s[40:41], |v133|, s9
	s_nop 1
	v_cndmask_b32_e64 v133, v133, v134, s[40:41]
	v_cndmask_b32_e32 v134, 0, v226, vcc
	v_sub_f32_e32 v133, v133, v134
	v_mul_f32_e32 v134, 0xbfb8aa3b, v27
	v_exp_f32_e32 v134, v134
	s_nop 0
	v_add_f32_e32 v134, 1.0, v134
	v_rcp_f32_e32 v134, v134
	s_nop 0
	v_fma_f32 v134, v134, v200, v196
	v_max_f32_e32 v134, 0x358637bd, v134
	v_cmp_gt_f32_e32 vcc, s7, v134
	s_nop 1
	v_cndmask_b32_e64 v135, 0, 32, vcc
	v_ldexp_f32 v134, v134, v135
	v_log_f32_e32 v134, v134
	s_nop 0
	v_mul_f32_e32 v135, 0x3f317217, v134
	v_fma_f32 v135, v134, s8, -v135
	v_fmac_f32_e32 v135, 0x3377d1cf, v134
	v_fmac_f32_e32 v135, 0x3f317217, v134
	v_cmp_lt_f32_e64 s[40:41], |v134|, s9
	s_nop 1
	v_cndmask_b32_e64 v134, v134, v135, s[40:41]
	v_cndmask_b32_e32 v135, 0, v226, vcc
	v_sub_f32_e32 v137, v134, v135
	v_mul_f32_e32 v134, 0xbfb8aa3b, v32
	v_exp_f32_e32 v134, v134
	s_nop 0
	v_add_f32_e32 v134, 1.0, v134
	v_rcp_f32_e32 v134, v134
	s_nop 0
	v_fma_f32 v134, v134, v203, v193
	v_max_f32_e32 v134, 0x358637bd, v134
	v_cmp_gt_f32_e32 vcc, s7, v134
	s_nop 1
	v_cndmask_b32_e64 v135, 0, 32, vcc
	v_ldexp_f32 v134, v134, v135
	v_log_f32_e32 v134, v134
	s_nop 0
	v_mul_f32_e32 v135, 0x3f317217, v134
	v_fma_f32 v135, v134, s8, -v135
	v_fmac_f32_e32 v135, 0x3377d1cf, v134
	v_fmac_f32_e32 v135, 0x3f317217, v134
	v_cmp_lt_f32_e64 s[40:41], |v134|, s9
	s_nop 1
	v_cndmask_b32_e64 v134, v134, v135, s[40:41]
	v_cndmask_b32_e32 v135, 0, v226, vcc
	v_sub_f32_e32 v134, v134, v135
	v_mul_f32_e32 v135, 0xbfb8aa3b, v28
	v_exp_f32_e32 v135, v135
	s_nop 0
	v_add_f32_e32 v135, 1.0, v135
	v_rcp_f32_e32 v135, v135
	s_nop 0
	v_fma_f32 v135, v135, v202, v194
	v_max_f32_e32 v135, 0x358637bd, v135
	v_cmp_gt_f32_e32 vcc, s7, v135
	s_nop 1
	v_cndmask_b32_e64 v138, 0, 32, vcc
	v_ldexp_f32 v135, v135, v138
	v_log_f32_e32 v135, v135
	s_nop 0
	v_mul_f32_e32 v138, 0x3f317217, v135
	v_fma_f32 v138, v135, s8, -v138
	v_fmac_f32_e32 v138, 0x3377d1cf, v135
	v_fmac_f32_e32 v138, 0x3f317217, v135
	v_cmp_lt_f32_e64 s[40:41], |v135|, s9
	s_nop 1
	v_cndmask_b32_e64 v135, v135, v138, s[40:41]
	v_cndmask_b32_e32 v138, 0, v226, vcc
	v_sub_f32_e32 v138, v135, v138
	v_mul_f32_e32 v135, 0xbfb8aa3b, v33
	v_exp_f32_e32 v135, v135
	s_nop 0
	v_add_f32_e32 v135, 1.0, v135
	v_rcp_f32_e32 v135, v135
	s_nop 0
	v_fma_f32 v135, v135, v204, v189
	v_max_f32_e32 v135, 0x358637bd, v135
	v_cmp_gt_f32_e32 vcc, s7, v135
	s_nop 1
	v_cndmask_b32_e64 v139, 0, 32, vcc
	v_ldexp_f32 v135, v135, v139
	v_log_f32_e32 v135, v135
	s_nop 0
	v_mul_f32_e32 v139, 0x3f317217, v135
	v_fma_f32 v139, v135, s8, -v139
	v_fmac_f32_e32 v139, 0x3377d1cf, v135
	v_fmac_f32_e32 v139, 0x3f317217, v135
	v_cmp_lt_f32_e64 s[40:41], |v135|, s9
	s_nop 1
	v_cndmask_b32_e64 v135, v135, v139, s[40:41]
	v_cndmask_b32_e32 v139, 0, v226, vcc
	v_sub_f32_e32 v135, v135, v139
	v_mul_f32_e32 v139, 0xbfb8aa3b, v29
	v_exp_f32_e32 v139, v139
	s_nop 0
	v_add_f32_e32 v139, 1.0, v139
	v_rcp_f32_e32 v139, v139
	s_nop 0
	v_fma_f32 v139, v139, v205, v191
	v_max_f32_e32 v139, 0x358637bd, v139
	v_cmp_gt_f32_e32 vcc, s7, v139
	s_nop 1
	v_cndmask_b32_e64 v158, 0, 32, vcc
	v_ldexp_f32 v139, v139, v158
	v_log_f32_e32 v139, v139
	s_nop 0
	v_mul_f32_e32 v158, 0x3f317217, v139
	v_fma_f32 v158, v139, s8, -v158
	v_fmac_f32_e32 v158, 0x3377d1cf, v139
	v_fmac_f32_e32 v158, 0x3f317217, v139
	v_cmp_lt_f32_e64 s[40:41], |v139|, s9
	s_nop 1
	v_cndmask_b32_e64 v139, v139, v158, s[40:41]
	v_cndmask_b32_e32 v158, 0, v226, vcc
	v_add_co_u32_e32 v160, vcc, s6, v156
	v_sub_f32_e32 v139, v139, v158
	s_nop 0
	v_addc_co_u32_e32 v161, vcc, 0, v157, vcc
	v_lshl_add_u64 v[158:159], v[156:157], 0, s[10:11]
	global_store_dwordx4 v[160:161], v[132:135], off
	global_store_dwordx4 v[158:159], v[136:139], off offset:16
	s_mov_b64 s[10:11], 0x160000
	v_mul_f32_e32 v132, 0xbfb8aa3b, v22
	v_exp_f32_e32 v132, v132
	s_mov_b32 s6, 0x160000
	v_add_f32_e32 v132, 1.0, v132
	v_rcp_f32_e32 v132, v132
	s_nop 0
	v_fma_f32 v132, v132, v206, v190
	v_max_f32_e32 v132, 0x358637bd, v132
	v_cmp_gt_f32_e32 vcc, s7, v132
	s_nop 1
	v_cndmask_b32_e64 v133, 0, 32, vcc
	v_ldexp_f32 v132, v132, v133
	v_log_f32_e32 v132, v132
	s_nop 0
	v_mul_f32_e32 v133, 0x3f317217, v132
	v_fma_f32 v133, v132, s8, -v133
	v_fmac_f32_e32 v133, 0x3377d1cf, v132
	v_fmac_f32_e32 v133, 0x3f317217, v132
	v_cmp_lt_f32_e64 s[40:41], |v132|, s9
	s_nop 1
	v_cndmask_b32_e64 v132, v132, v133, s[40:41]
	v_cndmask_b32_e32 v133, 0, v226, vcc
	v_sub_f32_e32 v132, v132, v133
	v_mul_f32_e32 v133, 0xbfb8aa3b, v18
	v_exp_f32_e32 v133, v133
	s_nop 0
	v_add_f32_e32 v133, 1.0, v133
	v_rcp_f32_e32 v133, v133
	s_nop 0
	v_fma_f32 v133, v133, v207, v192
	v_max_f32_e32 v133, 0x358637bd, v133
	v_cmp_gt_f32_e32 vcc, s7, v133
	s_nop 1
	v_cndmask_b32_e64 v134, 0, 32, vcc
	v_ldexp_f32 v133, v133, v134
	v_log_f32_e32 v133, v133
	s_nop 0
	v_mul_f32_e32 v134, 0x3f317217, v133
	v_fma_f32 v134, v133, s8, -v134
	v_fmac_f32_e32 v134, 0x3377d1cf, v133
	v_fmac_f32_e32 v134, 0x3f317217, v133
	v_cmp_lt_f32_e64 s[40:41], |v133|, s9
	s_nop 1
	v_cndmask_b32_e64 v133, v133, v134, s[40:41]
	v_cndmask_b32_e32 v134, 0, v226, vcc
	v_sub_f32_e32 v136, v133, v134
	v_mul_f32_e32 v133, 0xbfb8aa3b, v23
	v_exp_f32_e32 v133, v133
	s_nop 0
	v_add_f32_e32 v133, 1.0, v133
	v_rcp_f32_e32 v133, v133
	s_nop 0
	v_fma_f32 v133, v133, v209, v187
	v_max_f32_e32 v133, 0x358637bd, v133
	v_cmp_gt_f32_e32 vcc, s7, v133
	s_nop 1
	v_cndmask_b32_e64 v134, 0, 32, vcc
	v_ldexp_f32 v133, v133, v134
	v_log_f32_e32 v133, v133
	s_nop 0
	v_mul_f32_e32 v134, 0x3f317217, v133
	v_fma_f32 v134, v133, s8, -v134
	v_fmac_f32_e32 v134, 0x3377d1cf, v133
	v_fmac_f32_e32 v134, 0x3f317217, v133
	v_cmp_lt_f32_e64 s[40:41], |v133|, s9
	s_nop 1
	v_cndmask_b32_e64 v133, v133, v134, s[40:41]
	v_cndmask_b32_e32 v134, 0, v226, vcc
	v_sub_f32_e32 v133, v133, v134
	v_mul_f32_e32 v134, 0xbfb8aa3b, v19
	v_exp_f32_e32 v134, v134
	s_nop 0
	v_add_f32_e32 v134, 1.0, v134
	v_rcp_f32_e32 v134, v134
	s_nop 0
	v_fma_f32 v134, v134, v208, v188
	v_max_f32_e32 v134, 0x358637bd, v134
	v_cmp_gt_f32_e32 vcc, s7, v134
	s_nop 1
	v_cndmask_b32_e64 v135, 0, 32, vcc
	v_ldexp_f32 v134, v134, v135
	v_log_f32_e32 v134, v134
	s_nop 0
	v_mul_f32_e32 v135, 0x3f317217, v134
	v_fma_f32 v135, v134, s8, -v135
	v_fmac_f32_e32 v135, 0x3377d1cf, v134
	v_fmac_f32_e32 v135, 0x3f317217, v134
	v_cmp_lt_f32_e64 s[40:41], |v134|, s9
	s_nop 1
	v_cndmask_b32_e64 v134, v134, v135, s[40:41]
	v_cndmask_b32_e32 v135, 0, v226, vcc
	v_sub_f32_e32 v137, v134, v135
	v_mul_f32_e32 v134, 0xbfb8aa3b, v24
	v_exp_f32_e32 v134, v134
	s_nop 0
	v_add_f32_e32 v134, 1.0, v134
	v_rcp_f32_e32 v134, v134
	s_nop 0
	v_fma_f32 v134, v134, v211, v185
	v_max_f32_e32 v134, 0x358637bd, v134
	v_cmp_gt_f32_e32 vcc, s7, v134
	s_nop 1
	v_cndmask_b32_e64 v135, 0, 32, vcc
	v_ldexp_f32 v134, v134, v135
	v_log_f32_e32 v134, v134
	s_nop 0
	v_mul_f32_e32 v135, 0x3f317217, v134
	v_fma_f32 v135, v134, s8, -v135
	v_fmac_f32_e32 v135, 0x3377d1cf, v134
	v_fmac_f32_e32 v135, 0x3f317217, v134
	v_cmp_lt_f32_e64 s[40:41], |v134|, s9
	s_nop 1
	v_cndmask_b32_e64 v134, v134, v135, s[40:41]
	v_cndmask_b32_e32 v135, 0, v226, vcc
	v_sub_f32_e32 v134, v134, v135
	v_mul_f32_e32 v135, 0xbfb8aa3b, v20
	v_exp_f32_e32 v135, v135
	s_nop 0
	v_add_f32_e32 v135, 1.0, v135
	v_rcp_f32_e32 v135, v135
	s_nop 0
	v_fma_f32 v135, v135, v210, v186
	v_max_f32_e32 v135, 0x358637bd, v135
	v_cmp_gt_f32_e32 vcc, s7, v135
	s_nop 1
	v_cndmask_b32_e64 v138, 0, 32, vcc
	v_ldexp_f32 v135, v135, v138
	v_log_f32_e32 v135, v135
	s_nop 0
	v_mul_f32_e32 v138, 0x3f317217, v135
	v_fma_f32 v138, v135, s8, -v138
	v_fmac_f32_e32 v138, 0x3377d1cf, v135
	v_fmac_f32_e32 v138, 0x3f317217, v135
	v_cmp_lt_f32_e64 s[40:41], |v135|, s9
	s_nop 1
	v_cndmask_b32_e64 v135, v135, v138, s[40:41]
	v_cndmask_b32_e32 v138, 0, v226, vcc
	v_sub_f32_e32 v138, v135, v138
	v_mul_f32_e32 v135, 0xbfb8aa3b, v25
	v_exp_f32_e32 v135, v135
	s_nop 0
	v_add_f32_e32 v135, 1.0, v135
	v_rcp_f32_e32 v135, v135
	s_nop 0
	v_fma_f32 v135, v135, v212, v183
	v_max_f32_e32 v135, 0x358637bd, v135
	v_cmp_gt_f32_e32 vcc, s7, v135
	s_nop 1
	v_cndmask_b32_e64 v139, 0, 32, vcc
	v_ldexp_f32 v135, v135, v139
	v_log_f32_e32 v135, v135
	s_nop 0
	v_mul_f32_e32 v139, 0x3f317217, v135
	v_fma_f32 v139, v135, s8, -v139
	v_fmac_f32_e32 v139, 0x3377d1cf, v135
	v_fmac_f32_e32 v139, 0x3f317217, v135
	v_cmp_lt_f32_e64 s[40:41], |v135|, s9
	s_nop 1
	v_cndmask_b32_e64 v135, v135, v139, s[40:41]
	v_cndmask_b32_e32 v139, 0, v226, vcc
	v_sub_f32_e32 v135, v135, v139
	v_mul_f32_e32 v139, 0xbfb8aa3b, v21
	v_exp_f32_e32 v139, v139
	s_nop 0
	v_add_f32_e32 v139, 1.0, v139
	v_rcp_f32_e32 v139, v139
	s_nop 0
	v_fma_f32 v139, v139, v213, v184
	v_max_f32_e32 v139, 0x358637bd, v139
	v_cmp_gt_f32_e32 vcc, s7, v139
	s_nop 1
	v_cndmask_b32_e64 v160, 0, 32, vcc
	v_ldexp_f32 v139, v139, v160
	v_log_f32_e32 v139, v139
	s_nop 0
	v_mul_f32_e32 v160, 0x3f317217, v139
	v_fma_f32 v160, v139, s8, -v160
	v_fmac_f32_e32 v160, 0x3377d1cf, v139
	v_fmac_f32_e32 v160, 0x3f317217, v139
	v_cmp_lt_f32_e64 s[40:41], |v139|, s9
	s_nop 1
	v_cndmask_b32_e64 v139, v139, v160, s[40:41]
	v_cndmask_b32_e32 v160, 0, v226, vcc
	v_sub_f32_e32 v139, v139, v160
	global_store_dwordx4 v[158:159], v[132:135], off offset:512
	global_store_dwordx4 v[158:159], v[136:139], off offset:528
	v_lshl_add_u64 v[158:159], v[156:157], 0, s[10:11]
	v_mul_f32_e32 v132, 0xbfb8aa3b, v14
	v_exp_f32_e32 v132, v132
	s_nop 0
	v_add_f32_e32 v132, 1.0, v132
	v_rcp_f32_e32 v132, v132
	s_nop 0
	v_fmac_f32_e32 v197, v132, v199
	v_max_f32_e32 v132, 0x358637bd, v197
	v_cmp_gt_f32_e32 vcc, s7, v132
	s_nop 1
	v_cndmask_b32_e64 v133, 0, 32, vcc
	v_ldexp_f32 v132, v132, v133
	v_log_f32_e32 v132, v132
	s_nop 0
	v_mul_f32_e32 v133, 0x3f317217, v132
	v_fma_f32 v133, v132, s8, -v133
	v_fmac_f32_e32 v133, 0x3377d1cf, v132
	v_fmac_f32_e32 v133, 0x3f317217, v132
	v_cmp_lt_f32_e64 s[40:41], |v132|, s9
	s_nop 1
	v_cndmask_b32_e64 v132, v132, v133, s[40:41]
	v_cndmask_b32_e32 v133, 0, v226, vcc
	v_sub_f32_e32 v132, v132, v133
	v_mul_f32_e32 v133, 0xbfb8aa3b, v10
	v_exp_f32_e32 v133, v133
	s_nop 0
	v_add_f32_e32 v133, 1.0, v133
	v_rcp_f32_e32 v133, v133
	s_nop 0
	v_fmac_f32_e32 v198, v133, v155
	v_max_f32_e32 v133, 0x358637bd, v198
	v_cmp_gt_f32_e32 vcc, s7, v133
	s_nop 1
	v_cndmask_b32_e64 v134, 0, 32, vcc
	v_ldexp_f32 v133, v133, v134
	v_log_f32_e32 v133, v133
	s_nop 0
	v_mul_f32_e32 v134, 0x3f317217, v133
	v_fma_f32 v134, v133, s8, -v134
	v_fmac_f32_e32 v134, 0x3377d1cf, v133
	v_fmac_f32_e32 v134, 0x3f317217, v133
	v_cmp_lt_f32_e64 s[40:41], |v133|, s9
	s_nop 1
	v_cndmask_b32_e64 v133, v133, v134, s[40:41]
	v_cndmask_b32_e32 v134, 0, v226, vcc
	v_sub_f32_e32 v136, v133, v134
	v_mul_f32_e32 v133, 0xbfb8aa3b, v15
	v_exp_f32_e32 v133, v133
	s_nop 0
	v_add_f32_e32 v133, 1.0, v133
	v_rcp_f32_e32 v133, v133
	s_nop 0
	v_fmac_f32_e32 v195, v133, v201
	v_max_f32_e32 v133, 0x358637bd, v195
	v_cmp_gt_f32_e32 vcc, s7, v133
	s_nop 1
	v_cndmask_b32_e64 v134, 0, 32, vcc
	v_ldexp_f32 v133, v133, v134
	v_log_f32_e32 v133, v133
	s_nop 0
	v_mul_f32_e32 v134, 0x3f317217, v133
	v_fma_f32 v134, v133, s8, -v134
	v_fmac_f32_e32 v134, 0x3377d1cf, v133
	v_fmac_f32_e32 v134, 0x3f317217, v133
	v_cmp_lt_f32_e64 s[40:41], |v133|, s9
	s_nop 1
	v_cndmask_b32_e64 v133, v133, v134, s[40:41]
	v_cndmask_b32_e32 v134, 0, v226, vcc
	v_sub_f32_e32 v133, v133, v134
	v_mul_f32_e32 v134, 0xbfb8aa3b, v11
	v_exp_f32_e32 v134, v134
	s_nop 0
	v_add_f32_e32 v134, 1.0, v134
	v_rcp_f32_e32 v134, v134
	s_nop 0
	v_fmac_f32_e32 v196, v134, v200
	v_max_f32_e32 v134, 0x358637bd, v196
	v_cmp_gt_f32_e32 vcc, s7, v134
	s_nop 1
	v_cndmask_b32_e64 v135, 0, 32, vcc
	v_ldexp_f32 v134, v134, v135
	v_log_f32_e32 v134, v134
	s_nop 0
	v_mul_f32_e32 v135, 0x3f317217, v134
	v_fma_f32 v135, v134, s8, -v135
	v_fmac_f32_e32 v135, 0x3377d1cf, v134
	v_fmac_f32_e32 v135, 0x3f317217, v134
	v_cmp_lt_f32_e64 s[40:41], |v134|, s9
	s_nop 1
	v_cndmask_b32_e64 v134, v134, v135, s[40:41]
	v_cndmask_b32_e32 v135, 0, v226, vcc
	v_sub_f32_e32 v137, v134, v135
	v_mul_f32_e32 v134, 0xbfb8aa3b, v16
	v_exp_f32_e32 v134, v134
	s_nop 0
	v_add_f32_e32 v134, 1.0, v134
	v_rcp_f32_e32 v134, v134
	s_nop 0
	v_fmac_f32_e32 v193, v134, v203
	v_max_f32_e32 v134, 0x358637bd, v193
	v_cmp_gt_f32_e32 vcc, s7, v134
	s_nop 1
	v_cndmask_b32_e64 v135, 0, 32, vcc
	v_ldexp_f32 v134, v134, v135
	v_log_f32_e32 v134, v134
	s_nop 0
	v_mul_f32_e32 v135, 0x3f317217, v134
	v_fma_f32 v135, v134, s8, -v135
	v_fmac_f32_e32 v135, 0x3377d1cf, v134
	v_fmac_f32_e32 v135, 0x3f317217, v134
	v_cmp_lt_f32_e64 s[40:41], |v134|, s9
	s_nop 1
	v_cndmask_b32_e64 v134, v134, v135, s[40:41]
	v_cndmask_b32_e32 v135, 0, v226, vcc
	v_sub_f32_e32 v134, v134, v135
	v_mul_f32_e32 v135, 0xbfb8aa3b, v12
	v_exp_f32_e32 v135, v135
	s_nop 0
	v_add_f32_e32 v135, 1.0, v135
	v_rcp_f32_e32 v135, v135
	s_nop 0
	v_fmac_f32_e32 v194, v135, v202
	v_max_f32_e32 v135, 0x358637bd, v194
	v_cmp_gt_f32_e32 vcc, s7, v135
	s_nop 1
	v_cndmask_b32_e64 v138, 0, 32, vcc
	v_ldexp_f32 v135, v135, v138
	v_log_f32_e32 v135, v135
	s_nop 0
	v_mul_f32_e32 v138, 0x3f317217, v135
	v_fma_f32 v138, v135, s8, -v138
	v_fmac_f32_e32 v138, 0x3377d1cf, v135
	v_fmac_f32_e32 v138, 0x3f317217, v135
	v_cmp_lt_f32_e64 s[40:41], |v135|, s9
	s_nop 1
	v_cndmask_b32_e64 v135, v135, v138, s[40:41]
	v_cndmask_b32_e32 v138, 0, v226, vcc
	v_sub_f32_e32 v138, v135, v138
	v_mul_f32_e32 v135, 0xbfb8aa3b, v17
	v_exp_f32_e32 v135, v135
	s_nop 0
	v_add_f32_e32 v135, 1.0, v135
	v_rcp_f32_e32 v135, v135
	s_nop 0
	v_fmac_f32_e32 v189, v135, v204
	v_max_f32_e32 v135, 0x358637bd, v189
	v_cmp_gt_f32_e32 vcc, s7, v135
	s_nop 1
	v_cndmask_b32_e64 v139, 0, 32, vcc
	v_ldexp_f32 v135, v135, v139
	v_log_f32_e32 v135, v135
	s_nop 0
	v_mul_f32_e32 v139, 0x3f317217, v135
	v_fma_f32 v139, v135, s8, -v139
	v_fmac_f32_e32 v139, 0x3377d1cf, v135
	v_fmac_f32_e32 v139, 0x3f317217, v135
	v_cmp_lt_f32_e64 s[40:41], |v135|, s9
	s_nop 1
	v_cndmask_b32_e64 v135, v135, v139, s[40:41]
	v_cndmask_b32_e32 v139, 0, v226, vcc
	v_sub_f32_e32 v135, v135, v139
	v_mul_f32_e32 v139, 0xbfb8aa3b, v13
	v_exp_f32_e32 v139, v139
	s_nop 0
	v_add_f32_e32 v139, 1.0, v139
	v_rcp_f32_e32 v139, v139
	s_nop 0
	v_fmac_f32_e32 v191, v139, v205
	v_max_f32_e32 v139, 0x358637bd, v191
	v_cmp_gt_f32_e32 vcc, s7, v139
	s_nop 1
	v_cndmask_b32_e64 v155, 0, 32, vcc
	v_ldexp_f32 v139, v139, v155
	v_log_f32_e32 v139, v139
	s_nop 0
	v_mul_f32_e32 v155, 0x3f317217, v139
	v_fma_f32 v155, v139, s8, -v155
	v_fmac_f32_e32 v155, 0x3377d1cf, v139
	v_fmac_f32_e32 v155, 0x3f317217, v139
	v_cmp_lt_f32_e64 s[40:41], |v139|, s9
	s_nop 1
	v_cndmask_b32_e64 v139, v139, v155, s[40:41]
	v_cndmask_b32_e32 v155, 0, v226, vcc
	v_add_co_u32_e32 v156, vcc, s6, v156
	v_sub_f32_e32 v139, v139, v155
	s_nop 0
	v_addc_co_u32_e32 v157, vcc, 0, v157, vcc
	global_store_dwordx4 v[156:157], v[132:135], off
	global_store_dwordx4 v[158:159], v[136:139], off offset:16
	s_nop 0
	v_mul_f32_e32 v132, 0xbfb8aa3b, v6
	v_exp_f32_e32 v132, v132
	s_nop 0
	v_add_f32_e32 v132, 1.0, v132
	v_rcp_f32_e32 v132, v132
	s_nop 0
	v_fmac_f32_e32 v190, v132, v206
	v_max_f32_e32 v132, 0x358637bd, v190
	v_cmp_gt_f32_e32 vcc, s7, v132
	s_nop 1
	v_cndmask_b32_e64 v133, 0, 32, vcc
	v_ldexp_f32 v132, v132, v133
	v_log_f32_e32 v132, v132
	s_nop 0
	v_mul_f32_e32 v133, 0x3f317217, v132
	v_fma_f32 v133, v132, s8, -v133
	v_fmac_f32_e32 v133, 0x3377d1cf, v132
	v_fmac_f32_e32 v133, 0x3f317217, v132
	v_cmp_lt_f32_e64 s[40:41], |v132|, s9
	s_nop 1
	v_cndmask_b32_e64 v132, v132, v133, s[40:41]
	v_cndmask_b32_e32 v133, 0, v226, vcc
	v_sub_f32_e32 v132, v132, v133
	v_mul_f32_e32 v133, 0xbfb8aa3b, v2
	v_exp_f32_e32 v133, v133
	s_nop 0
	v_add_f32_e32 v133, 1.0, v133
	v_rcp_f32_e32 v133, v133
	s_nop 0
	v_fmac_f32_e32 v192, v133, v207
	v_max_f32_e32 v133, 0x358637bd, v192
	v_cmp_gt_f32_e32 vcc, s7, v133
	s_nop 1
	v_cndmask_b32_e64 v134, 0, 32, vcc
	v_ldexp_f32 v133, v133, v134
	v_log_f32_e32 v133, v133
	s_nop 0
	v_mul_f32_e32 v134, 0x3f317217, v133
	v_fma_f32 v134, v133, s8, -v134
	v_fmac_f32_e32 v134, 0x3377d1cf, v133
	v_fmac_f32_e32 v134, 0x3f317217, v133
	v_cmp_lt_f32_e64 s[40:41], |v133|, s9
	s_nop 1
	v_cndmask_b32_e64 v133, v133, v134, s[40:41]
	v_cndmask_b32_e32 v134, 0, v226, vcc
	v_sub_f32_e32 v136, v133, v134
	v_mul_f32_e32 v133, 0xbfb8aa3b, v7
	v_exp_f32_e32 v133, v133
	s_nop 0
	v_add_f32_e32 v133, 1.0, v133
	v_rcp_f32_e32 v133, v133
	s_nop 0
	v_fmac_f32_e32 v187, v133, v209
	v_max_f32_e32 v133, 0x358637bd, v187
	v_cmp_gt_f32_e32 vcc, s7, v133
	s_nop 1
	v_cndmask_b32_e64 v134, 0, 32, vcc
	v_ldexp_f32 v133, v133, v134
	v_log_f32_e32 v133, v133
	s_nop 0
	v_mul_f32_e32 v134, 0x3f317217, v133
	v_fma_f32 v134, v133, s8, -v134
	v_fmac_f32_e32 v134, 0x3377d1cf, v133
	v_fmac_f32_e32 v134, 0x3f317217, v133
	v_cmp_lt_f32_e64 s[40:41], |v133|, s9
	s_nop 1
	v_cndmask_b32_e64 v133, v133, v134, s[40:41]
	v_cndmask_b32_e32 v134, 0, v226, vcc
	v_sub_f32_e32 v133, v133, v134
	v_mul_f32_e32 v134, 0xbfb8aa3b, v3
	v_exp_f32_e32 v134, v134
	s_nop 0
	v_add_f32_e32 v134, 1.0, v134
	v_rcp_f32_e32 v134, v134
	s_nop 0
	v_fmac_f32_e32 v188, v134, v208
	v_max_f32_e32 v134, 0x358637bd, v188
	v_cmp_gt_f32_e32 vcc, s7, v134
	s_nop 1
	v_cndmask_b32_e64 v135, 0, 32, vcc
	v_ldexp_f32 v134, v134, v135
	v_log_f32_e32 v134, v134
	s_nop 0
	v_mul_f32_e32 v135, 0x3f317217, v134
	v_fma_f32 v135, v134, s8, -v135
	v_fmac_f32_e32 v135, 0x3377d1cf, v134
	v_fmac_f32_e32 v135, 0x3f317217, v134
	v_cmp_lt_f32_e64 s[40:41], |v134|, s9
	s_nop 1
	v_cndmask_b32_e64 v134, v134, v135, s[40:41]
	v_cndmask_b32_e32 v135, 0, v226, vcc
	v_sub_f32_e32 v137, v134, v135
	v_mul_f32_e32 v134, 0xbfb8aa3b, v8
	v_exp_f32_e32 v134, v134
	s_nop 0
	v_add_f32_e32 v134, 1.0, v134
	v_rcp_f32_e32 v134, v134
	s_nop 0
	v_fmac_f32_e32 v185, v134, v211
	v_max_f32_e32 v134, 0x358637bd, v185
	v_cmp_gt_f32_e32 vcc, s7, v134
	s_nop 1
	v_cndmask_b32_e64 v135, 0, 32, vcc
	v_ldexp_f32 v134, v134, v135
	v_log_f32_e32 v134, v134
	s_nop 0
	v_mul_f32_e32 v135, 0x3f317217, v134
	v_fma_f32 v135, v134, s8, -v135
	v_fmac_f32_e32 v135, 0x3377d1cf, v134
	v_fmac_f32_e32 v135, 0x3f317217, v134
	v_cmp_lt_f32_e64 s[40:41], |v134|, s9
	s_nop 1
	v_cndmask_b32_e64 v134, v134, v135, s[40:41]
	v_cndmask_b32_e32 v135, 0, v226, vcc
	v_sub_f32_e32 v134, v134, v135
	v_mul_f32_e32 v135, 0xbfb8aa3b, v4
	v_exp_f32_e32 v135, v135
	s_nop 0
	v_add_f32_e32 v135, 1.0, v135
	v_rcp_f32_e32 v135, v135
	s_nop 0
	v_fmac_f32_e32 v186, v135, v210
	v_max_f32_e32 v135, 0x358637bd, v186
	v_cmp_gt_f32_e32 vcc, s7, v135
	s_nop 1
	v_cndmask_b32_e64 v138, 0, 32, vcc
	v_ldexp_f32 v135, v135, v138
	v_log_f32_e32 v135, v135
	s_nop 0
	v_mul_f32_e32 v138, 0x3f317217, v135
	v_fma_f32 v138, v135, s8, -v138
	v_fmac_f32_e32 v138, 0x3377d1cf, v135
	v_fmac_f32_e32 v138, 0x3f317217, v135
	v_cmp_lt_f32_e64 s[40:41], |v135|, s9
	s_nop 1
	v_cndmask_b32_e64 v135, v135, v138, s[40:41]
	v_cndmask_b32_e32 v138, 0, v226, vcc
	v_sub_f32_e32 v138, v135, v138
	v_mul_f32_e32 v135, 0xbfb8aa3b, v9
	v_exp_f32_e32 v135, v135
	s_nop 0
	v_add_f32_e32 v135, 1.0, v135
	v_rcp_f32_e32 v135, v135
	s_nop 0
	v_fmac_f32_e32 v183, v135, v212
	v_max_f32_e32 v135, 0x358637bd, v183
	v_cmp_gt_f32_e32 vcc, s7, v135
	s_nop 1
	v_cndmask_b32_e64 v139, 0, 32, vcc
	v_ldexp_f32 v135, v135, v139
	v_log_f32_e32 v135, v135
	s_nop 0
	v_mul_f32_e32 v139, 0x3f317217, v135
	v_fma_f32 v139, v135, s8, -v139
	v_fmac_f32_e32 v139, 0x3377d1cf, v135
	v_fmac_f32_e32 v139, 0x3f317217, v135
	v_cmp_lt_f32_e64 s[40:41], |v135|, s9
	s_nop 1
	v_cndmask_b32_e64 v135, v135, v139, s[40:41]
	v_cndmask_b32_e32 v139, 0, v226, vcc
	v_sub_f32_e32 v135, v135, v139
	v_mul_f32_e32 v139, 0xbfb8aa3b, v5
	v_exp_f32_e32 v139, v139
	s_nop 0
	v_add_f32_e32 v139, 1.0, v139
	v_rcp_f32_e32 v139, v139
	s_nop 0
	v_fmac_f32_e32 v184, v139, v213
	v_max_f32_e32 v139, 0x358637bd, v184
	v_cmp_gt_f32_e32 vcc, s7, v139
	s_nop 1
	v_cndmask_b32_e64 v155, 0, 32, vcc
	v_ldexp_f32 v139, v139, v155
	v_log_f32_e32 v139, v139
	s_nop 0
	v_mul_f32_e32 v155, 0x3f317217, v139
	v_fma_f32 v155, v139, s8, -v155
	v_fmac_f32_e32 v155, 0x3377d1cf, v139
	v_fmac_f32_e32 v155, 0x3f317217, v139
	v_cmp_lt_f32_e64 s[40:41], |v139|, s9
	s_nop 1
	v_cndmask_b32_e64 v139, v139, v155, s[40:41]
	v_cndmask_b32_e32 v155, 0, v226, vcc
	v_sub_f32_e32 v139, v139, v155
	global_store_dwordx4 v[158:159], v[132:135], off offset:512
	global_store_dwordx4 v[158:159], v[136:139], off offset:528

.LBB0_173:
	v_mul_f32_e32 v133, 0xbfb8aa3b, v128
	v_exp_f32_e32 v133, v133
	v_lshl_or_b32 v132, s76, 8, v163
	v_ashrrev_i32_e32 v155, 31, v154
	v_lshlrev_b64 v[134:135], 12, v[154:155]
	v_add_f32_e32 v133, 1.0, v133
	v_rcp_f32_e32 v136, v133
	v_mul_f32_e32 v133, 0xbfb8aa3b, v124
	v_exp_f32_e32 v133, v133
	v_lshl_add_u64 v[134:135], s[42:43], 0, v[134:135]
	s_mov_b64 s[6:7], 0x80000
	v_add_f32_e32 v133, 1.0, v133
	v_rcp_f32_e32 v138, v133
	v_mul_f32_e32 v133, 0xbfb8aa3b, v129
	v_exp_f32_e32 v133, v133
	s_nop 0
	v_add_f32_e32 v133, 1.0, v133
	v_rcp_f32_e32 v137, v133
	v_mul_f32_e32 v133, 0xbfb8aa3b, v125
	v_exp_f32_e32 v133, v133
	v_pk_mul_f32 v[128:129], v[128:129], v[136:137]
	s_nop 0
	v_cvt_pk_bf16_f32 v128, v128, v129
	v_add_f32_e32 v133, 1.0, v133
	v_rcp_f32_e32 v139, v133
	v_mul_f32_e32 v133, 0xbfb8aa3b, v130
	v_exp_f32_e32 v133, v133
	v_pk_mul_f32 v[124:125], v[124:125], v[138:139]
	v_add_f32_e32 v133, 1.0, v133
	v_rcp_f32_e32 v136, v133
	v_mul_f32_e32 v133, 0xbfb8aa3b, v126
	v_exp_f32_e32 v133, v133
	s_nop 0
	v_add_f32_e32 v133, 1.0, v133
	v_rcp_f32_e32 v138, v133
	v_mul_f32_e32 v133, 0xbfb8aa3b, v131
	v_exp_f32_e32 v133, v133
	s_nop 0
	v_add_f32_e32 v133, 1.0, v133
	v_rcp_f32_e32 v137, v133
	v_mul_f32_e32 v133, 0xbfb8aa3b, v127
	v_exp_f32_e32 v133, v133
	v_pk_mul_f32 v[130:131], v[130:131], v[136:137]
	s_nop 0
	v_cvt_pk_bf16_f32 v129, v130, v131
	v_add_f32_e32 v133, 1.0, v133
	v_rcp_f32_e32 v139, v133
	v_ashrrev_i32_e32 v133, 31, v132
	v_cvt_pk_bf16_f32 v130, v124, v125
	v_pk_mul_f32 v[126:127], v[126:127], v[138:139]
	s_nop 0
	v_cvt_pk_bf16_f32 v131, v126, v127
	v_lshlrev_b64 v[126:127], 1, v[132:133]
	v_lshl_add_u64 v[124:125], v[134:135], 0, v[126:127]
	global_store_dwordx4 v[124:125], v[128:131], off
	s_nop 1
	v_mul_f32_e32 v129, 0xbfb8aa3b, v116
	v_exp_f32_e32 v129, v129
	v_mul_f32_e32 v128, 0xbfb8aa3b, v120
	v_exp_f32_e32 v128, v128
	v_add_f32_e32 v129, 1.0, v129
	v_rcp_f32_e32 v130, v129
	v_mul_f32_e32 v129, 0xbfb8aa3b, v121
	v_exp_f32_e32 v129, v129
	v_add_f32_e32 v128, 1.0, v128
	v_rcp_f32_e32 v128, v128
	v_add_f32_e32 v129, 1.0, v129
	v_rcp_f32_e32 v129, v129
	s_nop 0
	v_pk_mul_f32 v[120:121], v[120:121], v[128:129]
	v_mul_f32_e32 v128, 0xbfb8aa3b, v117
	v_exp_f32_e32 v128, v128
	s_nop 0
	v_add_f32_e32 v128, 1.0, v128
	v_rcp_f32_e32 v131, v128
	s_nop 0
	v_pk_mul_f32 v[128:129], v[116:117], v[130:131]
	v_mul_f32_e32 v117, 0xbfb8aa3b, v118
	v_exp_f32_e32 v117, v117
	v_mul_f32_e32 v116, 0xbfb8aa3b, v122
	v_exp_f32_e32 v116, v116
	v_add_f32_e32 v117, 1.0, v117
	v_rcp_f32_e32 v130, v117
	v_mul_f32_e32 v117, 0xbfb8aa3b, v123
	v_exp_f32_e32 v117, v117
	v_add_f32_e32 v116, 1.0, v116
	v_rcp_f32_e32 v116, v116
	v_add_f32_e32 v117, 1.0, v117
	v_rcp_f32_e32 v117, v117
	s_nop 0
	v_pk_mul_f32 v[122:123], v[122:123], v[116:117]
	v_mul_f32_e32 v116, 0xbfb8aa3b, v119
	v_exp_f32_e32 v116, v116
	v_cvt_pk_bf16_f32 v117, v122, v123
	v_add_f32_e32 v116, 1.0, v116
	v_rcp_f32_e32 v131, v116
	v_cvt_pk_bf16_f32 v116, v120, v121
	v_pk_mul_f32 v[130:131], v[118:119], v[130:131]
	v_cvt_pk_bf16_f32 v118, v128, v129
	v_cvt_pk_bf16_f32 v119, v130, v131
	global_store_dwordx4 v[124:125], v[116:119], off offset:256
	s_nop 1
	v_mul_f32_e32 v119, 0xbfb8aa3b, v108
	v_exp_f32_e32 v119, v119
	v_mul_f32_e32 v118, 0xbfb8aa3b, v112
	v_exp_f32_e32 v118, v118
	v_or_b32_e32 v116, 16, v154
	v_add_f32_e32 v119, 1.0, v119
	v_rcp_f32_e32 v120, v119
	v_mul_f32_e32 v119, 0xbfb8aa3b, v113
	v_exp_f32_e32 v119, v119
	v_add_f32_e32 v118, 1.0, v118
	v_rcp_f32_e32 v118, v118
	v_ashrrev_i32_e32 v117, 31, v116
	v_add_f32_e32 v119, 1.0, v119
	v_rcp_f32_e32 v119, v119
	v_lshlrev_b64 v[116:117], 12, v[116:117]
	v_lshl_add_u64 v[116:117], s[42:43], 0, v[116:117]
	v_pk_mul_f32 v[112:113], v[112:113], v[118:119]
	v_mul_f32_e32 v118, 0xbfb8aa3b, v109
	v_exp_f32_e32 v118, v118
	s_nop 0
	v_add_f32_e32 v118, 1.0, v118
	v_rcp_f32_e32 v121, v118
	s_nop 0
	v_pk_mul_f32 v[118:119], v[108:109], v[120:121]
	v_mul_f32_e32 v109, 0xbfb8aa3b, v110
	v_exp_f32_e32 v109, v109
	v_mul_f32_e32 v108, 0xbfb8aa3b, v114
	v_exp_f32_e32 v108, v108
	v_add_f32_e32 v109, 1.0, v109
	v_rcp_f32_e32 v120, v109
	v_mul_f32_e32 v109, 0xbfb8aa3b, v115
	v_exp_f32_e32 v109, v109
	v_add_f32_e32 v108, 1.0, v108
	v_rcp_f32_e32 v108, v108
	v_add_f32_e32 v109, 1.0, v109
	v_rcp_f32_e32 v109, v109
	s_nop 0
	v_pk_mul_f32 v[114:115], v[114:115], v[108:109]
	v_mul_f32_e32 v108, 0xbfb8aa3b, v111
	v_exp_f32_e32 v108, v108
	v_cvt_pk_bf16_f32 v109, v114, v115
	v_add_f32_e32 v108, 1.0, v108
	v_rcp_f32_e32 v121, v108
	v_cvt_pk_bf16_f32 v108, v112, v113
	v_lshl_add_u64 v[112:113], v[116:117], 0, v[126:127]
	v_pk_mul_f32 v[120:121], v[110:111], v[120:121]
	v_cvt_pk_bf16_f32 v110, v118, v119
	v_cvt_pk_bf16_f32 v111, v120, v121
	global_store_dwordx4 v[112:113], v[108:111], off
	s_nop 1
	v_mul_f32_e32 v109, 0xbfb8aa3b, v100
	v_exp_f32_e32 v109, v109
	v_mul_f32_e32 v108, 0xbfb8aa3b, v104
	v_exp_f32_e32 v108, v108
	v_add_f32_e32 v109, 1.0, v109
	v_rcp_f32_e32 v110, v109
	v_mul_f32_e32 v109, 0xbfb8aa3b, v105
	v_exp_f32_e32 v109, v109
	v_add_f32_e32 v108, 1.0, v108
	v_rcp_f32_e32 v108, v108
	v_add_f32_e32 v109, 1.0, v109
	v_rcp_f32_e32 v109, v109
	s_nop 0
	v_pk_mul_f32 v[104:105], v[104:105], v[108:109]
	v_mul_f32_e32 v108, 0xbfb8aa3b, v101
	v_exp_f32_e32 v108, v108
	s_nop 0
	v_add_f32_e32 v108, 1.0, v108
	v_rcp_f32_e32 v111, v108
	s_nop 0
	v_pk_mul_f32 v[108:109], v[100:101], v[110:111]
	v_mul_f32_e32 v101, 0xbfb8aa3b, v102
	v_exp_f32_e32 v101, v101
	v_mul_f32_e32 v100, 0xbfb8aa3b, v106
	v_exp_f32_e32 v100, v100
	v_add_f32_e32 v101, 1.0, v101
	v_rcp_f32_e32 v110, v101
	v_mul_f32_e32 v101, 0xbfb8aa3b, v107
	v_exp_f32_e32 v101, v101
	v_add_f32_e32 v100, 1.0, v100
	v_rcp_f32_e32 v100, v100
	v_add_f32_e32 v101, 1.0, v101
	v_rcp_f32_e32 v101, v101
	s_nop 0
	v_pk_mul_f32 v[106:107], v[106:107], v[100:101]
	v_mul_f32_e32 v100, 0xbfb8aa3b, v103
	v_exp_f32_e32 v100, v100
	v_cvt_pk_bf16_f32 v101, v106, v107
	v_add_f32_e32 v100, 1.0, v100
	v_rcp_f32_e32 v111, v100
	v_cvt_pk_bf16_f32 v100, v104, v105
	v_pk_mul_f32 v[110:111], v[102:103], v[110:111]
	v_cvt_pk_bf16_f32 v102, v108, v109
	v_cvt_pk_bf16_f32 v103, v110, v111
	global_store_dwordx4 v[112:113], v[100:103], off offset:256
	s_nop 1
	v_mul_f32_e32 v103, 0xbfb8aa3b, v92
	v_exp_f32_e32 v103, v103
	v_mul_f32_e32 v102, 0xbfb8aa3b, v96
	v_exp_f32_e32 v102, v102
	v_or_b32_e32 v100, 32, v154
	v_add_f32_e32 v103, 1.0, v103
	v_rcp_f32_e32 v104, v103
	v_mul_f32_e32 v103, 0xbfb8aa3b, v97
	v_exp_f32_e32 v103, v103
	v_add_f32_e32 v102, 1.0, v102
	v_rcp_f32_e32 v102, v102
	v_ashrrev_i32_e32 v101, 31, v100
	v_add_f32_e32 v103, 1.0, v103
	v_rcp_f32_e32 v103, v103
	v_lshlrev_b64 v[100:101], 12, v[100:101]
	v_lshl_add_u64 v[100:101], s[42:43], 0, v[100:101]
	v_pk_mul_f32 v[96:97], v[96:97], v[102:103]
	v_mul_f32_e32 v102, 0xbfb8aa3b, v93
	v_exp_f32_e32 v102, v102
	s_nop 0
	v_add_f32_e32 v102, 1.0, v102
	v_rcp_f32_e32 v105, v102
	s_nop 0
	v_pk_mul_f32 v[102:103], v[92:93], v[104:105]
	v_mul_f32_e32 v93, 0xbfb8aa3b, v94
	v_exp_f32_e32 v93, v93
	v_mul_f32_e32 v92, 0xbfb8aa3b, v98
	v_exp_f32_e32 v92, v92
	v_add_f32_e32 v93, 1.0, v93
	v_rcp_f32_e32 v104, v93
	v_mul_f32_e32 v93, 0xbfb8aa3b, v99
	v_exp_f32_e32 v93, v93
	v_add_f32_e32 v92, 1.0, v92
	v_rcp_f32_e32 v92, v92
	v_add_f32_e32 v93, 1.0, v93
	v_rcp_f32_e32 v93, v93
	s_nop 0
	v_pk_mul_f32 v[98:99], v[98:99], v[92:93]
	v_mul_f32_e32 v92, 0xbfb8aa3b, v95
	v_exp_f32_e32 v92, v92
	v_cvt_pk_bf16_f32 v93, v98, v99
	v_add_f32_e32 v92, 1.0, v92
	v_rcp_f32_e32 v105, v92
	v_cvt_pk_bf16_f32 v92, v96, v97
	v_lshl_add_u64 v[96:97], v[100:101], 0, v[126:127]
	v_pk_mul_f32 v[104:105], v[94:95], v[104:105]
	v_cvt_pk_bf16_f32 v94, v102, v103
	v_cvt_pk_bf16_f32 v95, v104, v105
	global_store_dwordx4 v[96:97], v[92:95], off
	s_nop 1
	v_mul_f32_e32 v93, 0xbfb8aa3b, v84
	v_exp_f32_e32 v93, v93
	v_mul_f32_e32 v92, 0xbfb8aa3b, v88
	v_exp_f32_e32 v92, v92
	v_add_f32_e32 v93, 1.0, v93
	v_rcp_f32_e32 v94, v93
	v_mul_f32_e32 v93, 0xbfb8aa3b, v89
	v_exp_f32_e32 v93, v93
	v_add_f32_e32 v92, 1.0, v92
	v_rcp_f32_e32 v92, v92
	v_add_f32_e32 v93, 1.0, v93
	v_rcp_f32_e32 v93, v93
	s_nop 0
	v_pk_mul_f32 v[88:89], v[88:89], v[92:93]
	v_mul_f32_e32 v92, 0xbfb8aa3b, v85
	v_exp_f32_e32 v92, v92
	s_nop 0
	v_add_f32_e32 v92, 1.0, v92
	v_rcp_f32_e32 v95, v92
	s_nop 0
	v_pk_mul_f32 v[92:93], v[84:85], v[94:95]
	v_mul_f32_e32 v85, 0xbfb8aa3b, v86
	v_exp_f32_e32 v85, v85
	v_mul_f32_e32 v84, 0xbfb8aa3b, v90
	v_exp_f32_e32 v84, v84
	v_add_f32_e32 v85, 1.0, v85
	v_rcp_f32_e32 v94, v85
	v_mul_f32_e32 v85, 0xbfb8aa3b, v91
	v_exp_f32_e32 v85, v85
	v_add_f32_e32 v84, 1.0, v84
	v_rcp_f32_e32 v84, v84
	v_add_f32_e32 v85, 1.0, v85
	v_rcp_f32_e32 v85, v85
	s_nop 0
	v_pk_mul_f32 v[90:91], v[90:91], v[84:85]
	v_mul_f32_e32 v84, 0xbfb8aa3b, v87
	v_exp_f32_e32 v84, v84
	v_cvt_pk_bf16_f32 v85, v90, v91
	v_add_f32_e32 v84, 1.0, v84
	v_rcp_f32_e32 v95, v84
	v_cvt_pk_bf16_f32 v84, v88, v89
	v_pk_mul_f32 v[94:95], v[86:87], v[94:95]
	v_cvt_pk_bf16_f32 v86, v92, v93
	v_cvt_pk_bf16_f32 v87, v94, v95
	global_store_dwordx4 v[96:97], v[84:87], off offset:256
	s_nop 1
	v_mul_f32_e32 v87, 0xbfb8aa3b, v76
	v_exp_f32_e32 v87, v87
	v_mul_f32_e32 v86, 0xbfb8aa3b, v80
	v_exp_f32_e32 v86, v86
	v_or_b32_e32 v84, 48, v154
	v_add_f32_e32 v87, 1.0, v87
	v_rcp_f32_e32 v88, v87
	v_mul_f32_e32 v87, 0xbfb8aa3b, v81
	v_exp_f32_e32 v87, v87
	v_add_f32_e32 v86, 1.0, v86
	v_rcp_f32_e32 v86, v86
	v_ashrrev_i32_e32 v85, 31, v84
	v_add_f32_e32 v87, 1.0, v87
	v_rcp_f32_e32 v87, v87
	v_lshlrev_b64 v[84:85], 12, v[84:85]
	v_lshl_add_u64 v[84:85], s[42:43], 0, v[84:85]
	v_pk_mul_f32 v[80:81], v[80:81], v[86:87]
	v_mul_f32_e32 v86, 0xbfb8aa3b, v77
	v_exp_f32_e32 v86, v86
	s_nop 0
	v_add_f32_e32 v86, 1.0, v86
	v_rcp_f32_e32 v89, v86
	s_nop 0
	v_pk_mul_f32 v[86:87], v[76:77], v[88:89]
	v_mul_f32_e32 v77, 0xbfb8aa3b, v78
	v_exp_f32_e32 v77, v77
	v_mul_f32_e32 v76, 0xbfb8aa3b, v82
	v_exp_f32_e32 v76, v76
	v_add_f32_e32 v77, 1.0, v77
	v_rcp_f32_e32 v88, v77
	v_mul_f32_e32 v77, 0xbfb8aa3b, v83
	v_exp_f32_e32 v77, v77
	v_add_f32_e32 v76, 1.0, v76
	v_rcp_f32_e32 v76, v76
	v_add_f32_e32 v77, 1.0, v77
	v_rcp_f32_e32 v77, v77
	s_nop 0
	v_pk_mul_f32 v[82:83], v[82:83], v[76:77]
	v_mul_f32_e32 v76, 0xbfb8aa3b, v79
	v_exp_f32_e32 v76, v76
	v_cvt_pk_bf16_f32 v77, v82, v83
	v_add_f32_e32 v76, 1.0, v76
	v_rcp_f32_e32 v89, v76
	v_cvt_pk_bf16_f32 v76, v80, v81
	v_lshl_add_u64 v[80:81], v[84:85], 0, v[126:127]
	v_pk_mul_f32 v[88:89], v[78:79], v[88:89]
	v_cvt_pk_bf16_f32 v78, v86, v87
	v_cvt_pk_bf16_f32 v79, v88, v89
	global_store_dwordx4 v[80:81], v[76:79], off
	s_nop 1
	v_mul_f32_e32 v77, 0xbfb8aa3b, v68
	v_exp_f32_e32 v77, v77
	v_mul_f32_e32 v76, 0xbfb8aa3b, v72
	v_exp_f32_e32 v76, v76
	v_add_f32_e32 v77, 1.0, v77
	v_rcp_f32_e32 v78, v77
	v_mul_f32_e32 v77, 0xbfb8aa3b, v73
	v_exp_f32_e32 v77, v77
	v_add_f32_e32 v76, 1.0, v76
	v_rcp_f32_e32 v76, v76
	v_add_f32_e32 v77, 1.0, v77
	v_rcp_f32_e32 v77, v77
	s_nop 0
	v_pk_mul_f32 v[72:73], v[72:73], v[76:77]
	v_mul_f32_e32 v76, 0xbfb8aa3b, v69
	v_exp_f32_e32 v76, v76
	s_nop 0
	v_add_f32_e32 v76, 1.0, v76
	v_rcp_f32_e32 v79, v76
	s_nop 0
	v_pk_mul_f32 v[76:77], v[68:69], v[78:79]
	v_mul_f32_e32 v69, 0xbfb8aa3b, v70
	v_exp_f32_e32 v69, v69
	v_mul_f32_e32 v68, 0xbfb8aa3b, v74
	v_exp_f32_e32 v68, v68
	v_add_f32_e32 v69, 1.0, v69
	v_rcp_f32_e32 v78, v69
	v_mul_f32_e32 v69, 0xbfb8aa3b, v75
	v_exp_f32_e32 v69, v69
	v_add_f32_e32 v68, 1.0, v68
	v_rcp_f32_e32 v68, v68
	v_add_f32_e32 v69, 1.0, v69
	v_rcp_f32_e32 v69, v69
	s_nop 0
	v_pk_mul_f32 v[74:75], v[74:75], v[68:69]
	v_mul_f32_e32 v68, 0xbfb8aa3b, v71
	v_exp_f32_e32 v68, v68
	v_cvt_pk_bf16_f32 v69, v74, v75
	v_add_f32_e32 v68, 1.0, v68
	v_rcp_f32_e32 v79, v68
	v_cvt_pk_bf16_f32 v68, v72, v73
	v_pk_mul_f32 v[78:79], v[70:71], v[78:79]
	v_cvt_pk_bf16_f32 v70, v76, v77
	v_cvt_pk_bf16_f32 v71, v78, v79
	global_store_dwordx4 v[80:81], v[68:71], off offset:256
	s_nop 1
	v_mul_f32_e32 v69, 0xbfb8aa3b, v60
	v_exp_f32_e32 v69, v69
	v_mul_f32_e32 v68, 0xbfb8aa3b, v64
	v_exp_f32_e32 v68, v68
	v_add_f32_e32 v69, 1.0, v69
	v_rcp_f32_e32 v70, v69
	v_mul_f32_e32 v69, 0xbfb8aa3b, v65
	v_exp_f32_e32 v69, v69
	v_add_f32_e32 v68, 1.0, v68
	v_rcp_f32_e32 v68, v68
	v_add_f32_e32 v69, 1.0, v69
	v_rcp_f32_e32 v69, v69
	s_nop 0
	v_pk_mul_f32 v[64:65], v[64:65], v[68:69]
	v_mul_f32_e32 v68, 0xbfb8aa3b, v61
	v_exp_f32_e32 v68, v68
	s_nop 0
	v_add_f32_e32 v68, 1.0, v68
	v_rcp_f32_e32 v71, v68
	s_nop 0
	v_pk_mul_f32 v[68:69], v[60:61], v[70:71]
	v_mul_f32_e32 v61, 0xbfb8aa3b, v62
	v_exp_f32_e32 v61, v61
	v_mul_f32_e32 v60, 0xbfb8aa3b, v66
	v_exp_f32_e32 v60, v60
	v_add_f32_e32 v61, 1.0, v61
	v_rcp_f32_e32 v70, v61
	v_mul_f32_e32 v61, 0xbfb8aa3b, v67
	v_exp_f32_e32 v61, v61
	v_add_f32_e32 v60, 1.0, v60
	v_rcp_f32_e32 v60, v60
	v_add_f32_e32 v61, 1.0, v61
	v_rcp_f32_e32 v61, v61
	s_nop 0
	v_pk_mul_f32 v[66:67], v[66:67], v[60:61]
	v_mul_f32_e32 v60, 0xbfb8aa3b, v63
	v_exp_f32_e32 v60, v60
	v_cvt_pk_bf16_f32 v61, v66, v67
	v_add_f32_e32 v60, 1.0, v60
	v_rcp_f32_e32 v71, v60
	v_cvt_pk_bf16_f32 v60, v64, v65
	v_lshl_add_u64 v[64:65], v[124:125], 0, s[6:7]
	s_mov_b32 s6, 0x80000
	v_pk_mul_f32 v[70:71], v[62:63], v[70:71]
	v_add_co_u32_e32 v66, vcc, s6, v124
	v_cvt_pk_bf16_f32 v62, v68, v69
	v_cvt_pk_bf16_f32 v63, v70, v71
	v_addc_co_u32_e32 v67, vcc, 0, v125, vcc
	global_store_dwordx4 v[66:67], v[60:63], off
	s_mov_b64 s[6:7], 0x90000
	s_nop 0
	v_mul_f32_e32 v61, 0xbfb8aa3b, v52
	v_exp_f32_e32 v61, v61
	v_mul_f32_e32 v60, 0xbfb8aa3b, v56
	v_exp_f32_e32 v60, v60
	v_add_f32_e32 v61, 1.0, v61
	v_rcp_f32_e32 v62, v61
	v_mul_f32_e32 v61, 0xbfb8aa3b, v57
	v_exp_f32_e32 v61, v61
	v_add_f32_e32 v60, 1.0, v60
	v_rcp_f32_e32 v60, v60
	v_add_f32_e32 v61, 1.0, v61
	v_rcp_f32_e32 v61, v61
	s_nop 0
	v_pk_mul_f32 v[56:57], v[56:57], v[60:61]
	v_mul_f32_e32 v60, 0xbfb8aa3b, v53
	v_exp_f32_e32 v60, v60
	s_nop 0
	v_add_f32_e32 v60, 1.0, v60
	v_rcp_f32_e32 v63, v60
	s_nop 0
	v_pk_mul_f32 v[60:61], v[52:53], v[62:63]
	v_mul_f32_e32 v53, 0xbfb8aa3b, v54
	v_exp_f32_e32 v53, v53
	v_mul_f32_e32 v52, 0xbfb8aa3b, v58
	v_exp_f32_e32 v52, v52
	v_add_f32_e32 v53, 1.0, v53
	v_rcp_f32_e32 v62, v53
	v_mul_f32_e32 v53, 0xbfb8aa3b, v59
	v_exp_f32_e32 v53, v53
	v_add_f32_e32 v52, 1.0, v52
	v_rcp_f32_e32 v52, v52
	v_add_f32_e32 v53, 1.0, v53
	v_rcp_f32_e32 v53, v53
	s_nop 0
	v_pk_mul_f32 v[58:59], v[58:59], v[52:53]
	v_mul_f32_e32 v52, 0xbfb8aa3b, v55
	v_exp_f32_e32 v52, v52
	v_cvt_pk_bf16_f32 v53, v58, v59
	v_add_f32_e32 v52, 1.0, v52
	v_rcp_f32_e32 v63, v52
	v_cvt_pk_bf16_f32 v52, v56, v57
	v_pk_mul_f32 v[62:63], v[54:55], v[62:63]
	v_cvt_pk_bf16_f32 v54, v60, v61
	v_cvt_pk_bf16_f32 v55, v62, v63
	global_store_dwordx4 v[64:65], v[52:55], off offset:256
	s_nop 1
	v_mul_f32_e32 v53, 0xbfb8aa3b, v44
	v_exp_f32_e32 v53, v53
	v_mul_f32_e32 v52, 0xbfb8aa3b, v48
	v_exp_f32_e32 v52, v52
	v_add_f32_e32 v53, 1.0, v53
	v_rcp_f32_e32 v54, v53
	v_mul_f32_e32 v53, 0xbfb8aa3b, v49
	v_exp_f32_e32 v53, v53
	v_add_f32_e32 v52, 1.0, v52
	v_rcp_f32_e32 v52, v52
	v_add_f32_e32 v53, 1.0, v53
	v_rcp_f32_e32 v53, v53
	s_nop 0
	v_pk_mul_f32 v[48:49], v[48:49], v[52:53]
	v_mul_f32_e32 v52, 0xbfb8aa3b, v45
	v_exp_f32_e32 v52, v52
	s_nop 0
	v_add_f32_e32 v52, 1.0, v52
	v_rcp_f32_e32 v55, v52
	s_nop 0
	v_pk_mul_f32 v[52:53], v[44:45], v[54:55]
	v_mul_f32_e32 v45, 0xbfb8aa3b, v46
	v_exp_f32_e32 v45, v45
	v_mul_f32_e32 v44, 0xbfb8aa3b, v50
	v_exp_f32_e32 v44, v44
	v_add_f32_e32 v45, 1.0, v45
	v_rcp_f32_e32 v54, v45
	v_mul_f32_e32 v45, 0xbfb8aa3b, v51
	v_exp_f32_e32 v45, v45
	v_add_f32_e32 v44, 1.0, v44
	v_rcp_f32_e32 v44, v44
	v_add_f32_e32 v45, 1.0, v45
	v_rcp_f32_e32 v45, v45
	s_nop 0
	v_pk_mul_f32 v[50:51], v[50:51], v[44:45]
	v_mul_f32_e32 v44, 0xbfb8aa3b, v47
	v_exp_f32_e32 v44, v44
	v_cvt_pk_bf16_f32 v45, v50, v51
	v_add_f32_e32 v44, 1.0, v44
	v_rcp_f32_e32 v55, v44
	v_cvt_pk_bf16_f32 v44, v48, v49
	v_lshl_add_u64 v[48:49], v[124:125], 0, s[6:7]
	s_mov_b32 s6, 0x90000
	v_pk_mul_f32 v[54:55], v[46:47], v[54:55]
	v_add_co_u32_e32 v50, vcc, s6, v124
	v_cvt_pk_bf16_f32 v46, v52, v53
	v_cvt_pk_bf16_f32 v47, v54, v55
	v_addc_co_u32_e32 v51, vcc, 0, v125, vcc
	global_store_dwordx4 v[50:51], v[44:47], off
	s_mov_b64 s[6:7], 0xa0000
	s_nop 0
	v_mul_f32_e32 v45, 0xbfb8aa3b, v36
	v_exp_f32_e32 v45, v45
	v_mul_f32_e32 v44, 0xbfb8aa3b, v40
	v_exp_f32_e32 v44, v44
	v_add_f32_e32 v45, 1.0, v45
	v_rcp_f32_e32 v46, v45
	v_mul_f32_e32 v45, 0xbfb8aa3b, v41
	v_exp_f32_e32 v45, v45
	v_add_f32_e32 v44, 1.0, v44
	v_rcp_f32_e32 v44, v44
	v_add_f32_e32 v45, 1.0, v45
	v_rcp_f32_e32 v45, v45
	s_nop 0
	v_pk_mul_f32 v[40:41], v[40:41], v[44:45]
	v_mul_f32_e32 v44, 0xbfb8aa3b, v37
	v_exp_f32_e32 v44, v44
	s_nop 0
	v_add_f32_e32 v44, 1.0, v44
	v_rcp_f32_e32 v47, v44
	s_nop 0
	v_pk_mul_f32 v[44:45], v[36:37], v[46:47]
	v_mul_f32_e32 v37, 0xbfb8aa3b, v38
	v_exp_f32_e32 v37, v37
	v_mul_f32_e32 v36, 0xbfb8aa3b, v42
	v_exp_f32_e32 v36, v36
	v_add_f32_e32 v37, 1.0, v37
	v_rcp_f32_e32 v46, v37
	v_mul_f32_e32 v37, 0xbfb8aa3b, v43
	v_exp_f32_e32 v37, v37
	v_add_f32_e32 v36, 1.0, v36
	v_rcp_f32_e32 v36, v36
	v_add_f32_e32 v37, 1.0, v37
	v_rcp_f32_e32 v37, v37
	s_nop 0
	v_pk_mul_f32 v[42:43], v[42:43], v[36:37]
	v_mul_f32_e32 v36, 0xbfb8aa3b, v39
	v_exp_f32_e32 v36, v36
	v_cvt_pk_bf16_f32 v37, v42, v43
	v_add_f32_e32 v36, 1.0, v36
	v_rcp_f32_e32 v47, v36
	v_cvt_pk_bf16_f32 v36, v40, v41
	v_pk_mul_f32 v[46:47], v[38:39], v[46:47]
	v_cvt_pk_bf16_f32 v38, v44, v45
	v_cvt_pk_bf16_f32 v39, v46, v47
	global_store_dwordx4 v[48:49], v[36:39], off offset:256
	s_nop 1
	v_mul_f32_e32 v37, 0xbfb8aa3b, v26
	v_exp_f32_e32 v37, v37
	v_mul_f32_e32 v36, 0xbfb8aa3b, v30
	v_exp_f32_e32 v36, v36
	v_add_f32_e32 v37, 1.0, v37
	v_rcp_f32_e32 v38, v37
	v_mul_f32_e32 v37, 0xbfb8aa3b, v31
	v_exp_f32_e32 v37, v37
	v_add_f32_e32 v36, 1.0, v36
	v_rcp_f32_e32 v36, v36
	v_add_f32_e32 v37, 1.0, v37
	v_rcp_f32_e32 v37, v37
	s_nop 0
	v_pk_mul_f32 v[30:31], v[30:31], v[36:37]
	v_mul_f32_e32 v36, 0xbfb8aa3b, v27
	v_exp_f32_e32 v36, v36
	s_nop 0
	v_add_f32_e32 v36, 1.0, v36
	v_rcp_f32_e32 v39, v36
	s_nop 0
	v_pk_mul_f32 v[36:37], v[26:27], v[38:39]
	v_mul_f32_e32 v27, 0xbfb8aa3b, v28
	v_exp_f32_e32 v27, v27
	v_mul_f32_e32 v26, 0xbfb8aa3b, v32
	v_exp_f32_e32 v26, v26
	v_add_f32_e32 v27, 1.0, v27
	v_rcp_f32_e32 v38, v27
	v_mul_f32_e32 v27, 0xbfb8aa3b, v33
	v_exp_f32_e32 v27, v27
	v_add_f32_e32 v26, 1.0, v26
	v_rcp_f32_e32 v26, v26
	v_add_f32_e32 v27, 1.0, v27
	v_rcp_f32_e32 v27, v27
	s_nop 0
	v_pk_mul_f32 v[32:33], v[32:33], v[26:27]
	v_mul_f32_e32 v26, 0xbfb8aa3b, v29
	v_exp_f32_e32 v26, v26
	v_cvt_pk_bf16_f32 v27, v32, v33
	v_add_f32_e32 v26, 1.0, v26
	v_rcp_f32_e32 v39, v26
	v_cvt_pk_bf16_f32 v26, v30, v31
	v_lshl_add_u64 v[30:31], v[124:125], 0, s[6:7]
	s_mov_b32 s6, 0xa0000
	v_pk_mul_f32 v[38:39], v[28:29], v[38:39]
	v_add_co_u32_e32 v32, vcc, s6, v124
	v_cvt_pk_bf16_f32 v28, v36, v37
	v_cvt_pk_bf16_f32 v29, v38, v39
	v_addc_co_u32_e32 v33, vcc, 0, v125, vcc
	global_store_dwordx4 v[32:33], v[26:29], off
	s_mov_b64 s[6:7], 0xb0000
	s_nop 0
	v_mul_f32_e32 v27, 0xbfb8aa3b, v18
	v_exp_f32_e32 v27, v27
	v_mul_f32_e32 v26, 0xbfb8aa3b, v22
	v_exp_f32_e32 v26, v26
	v_add_f32_e32 v27, 1.0, v27
	v_rcp_f32_e32 v28, v27
	v_mul_f32_e32 v27, 0xbfb8aa3b, v23
	v_exp_f32_e32 v27, v27
	v_add_f32_e32 v26, 1.0, v26
	v_rcp_f32_e32 v26, v26
	v_add_f32_e32 v27, 1.0, v27
	v_rcp_f32_e32 v27, v27
	s_nop 0
	v_pk_mul_f32 v[22:23], v[22:23], v[26:27]
	v_mul_f32_e32 v26, 0xbfb8aa3b, v19
	v_exp_f32_e32 v26, v26
	s_nop 0
	v_add_f32_e32 v26, 1.0, v26
	v_rcp_f32_e32 v29, v26
	s_nop 0
	v_pk_mul_f32 v[26:27], v[18:19], v[28:29]
	v_mul_f32_e32 v19, 0xbfb8aa3b, v20
	v_exp_f32_e32 v19, v19
	v_mul_f32_e32 v18, 0xbfb8aa3b, v24
	v_exp_f32_e32 v18, v18
	v_add_f32_e32 v19, 1.0, v19
	v_rcp_f32_e32 v28, v19
	v_mul_f32_e32 v19, 0xbfb8aa3b, v25
	v_exp_f32_e32 v19, v19
	v_add_f32_e32 v18, 1.0, v18
	v_rcp_f32_e32 v18, v18
	v_add_f32_e32 v19, 1.0, v19
	v_rcp_f32_e32 v19, v19
	s_nop 0
	v_pk_mul_f32 v[24:25], v[24:25], v[18:19]
	v_mul_f32_e32 v18, 0xbfb8aa3b, v21
	v_exp_f32_e32 v18, v18
	v_cvt_pk_bf16_f32 v19, v24, v25
	v_add_f32_e32 v18, 1.0, v18
	v_rcp_f32_e32 v29, v18
	v_cvt_pk_bf16_f32 v18, v22, v23
	v_pk_mul_f32 v[28:29], v[20:21], v[28:29]
	v_cvt_pk_bf16_f32 v20, v26, v27
	v_cvt_pk_bf16_f32 v21, v28, v29
	global_store_dwordx4 v[30:31], v[18:21], off offset:256
	s_nop 1
	v_mul_f32_e32 v19, 0xbfb8aa3b, v10
	v_exp_f32_e32 v19, v19
	v_mul_f32_e32 v18, 0xbfb8aa3b, v14
	v_exp_f32_e32 v18, v18
	v_add_f32_e32 v19, 1.0, v19
	v_rcp_f32_e32 v20, v19
	v_mul_f32_e32 v19, 0xbfb8aa3b, v15
	v_exp_f32_e32 v19, v19
	v_add_f32_e32 v18, 1.0, v18
	v_rcp_f32_e32 v18, v18
	v_add_f32_e32 v19, 1.0, v19
	v_rcp_f32_e32 v19, v19
	s_nop 0
	v_pk_mul_f32 v[14:15], v[14:15], v[18:19]
	v_mul_f32_e32 v18, 0xbfb8aa3b, v11
	v_exp_f32_e32 v18, v18
	s_nop 0
	v_add_f32_e32 v18, 1.0, v18
	v_rcp_f32_e32 v21, v18
	s_nop 0
	v_pk_mul_f32 v[18:19], v[10:11], v[20:21]
	v_mul_f32_e32 v11, 0xbfb8aa3b, v12
	v_exp_f32_e32 v11, v11
	v_mul_f32_e32 v10, 0xbfb8aa3b, v16
	v_exp_f32_e32 v10, v10
	v_add_f32_e32 v11, 1.0, v11
	v_rcp_f32_e32 v20, v11
	v_mul_f32_e32 v11, 0xbfb8aa3b, v17
	v_exp_f32_e32 v11, v11
	v_add_f32_e32 v10, 1.0, v10
	v_rcp_f32_e32 v10, v10
	v_add_f32_e32 v11, 1.0, v11
	v_rcp_f32_e32 v11, v11
	s_nop 0
	v_pk_mul_f32 v[16:17], v[16:17], v[10:11]
	v_mul_f32_e32 v10, 0xbfb8aa3b, v13
	v_exp_f32_e32 v10, v10
	v_cvt_pk_bf16_f32 v11, v16, v17
	v_add_f32_e32 v10, 1.0, v10
	v_rcp_f32_e32 v21, v10
	v_cvt_pk_bf16_f32 v10, v14, v15
	v_lshl_add_u64 v[14:15], v[124:125], 0, s[6:7]
	s_mov_b32 s6, 0xb0000
	v_pk_mul_f32 v[20:21], v[12:13], v[20:21]
	v_add_co_u32_e32 v16, vcc, s6, v124
	v_cvt_pk_bf16_f32 v12, v18, v19
	v_cvt_pk_bf16_f32 v13, v20, v21
	v_addc_co_u32_e32 v17, vcc, 0, v125, vcc
	global_store_dwordx4 v[16:17], v[10:13], off
	s_nop 1
	v_mul_f32_e32 v11, 0xbfb8aa3b, v2
	v_exp_f32_e32 v11, v11
	v_mul_f32_e32 v10, 0xbfb8aa3b, v6
	v_exp_f32_e32 v10, v10
	v_add_f32_e32 v11, 1.0, v11
	v_rcp_f32_e32 v12, v11
	v_mul_f32_e32 v11, 0xbfb8aa3b, v7
	v_exp_f32_e32 v11, v11
	v_add_f32_e32 v10, 1.0, v10
	v_rcp_f32_e32 v10, v10
	v_add_f32_e32 v11, 1.0, v11
	v_rcp_f32_e32 v11, v11
	s_nop 0
	v_pk_mul_f32 v[6:7], v[6:7], v[10:11]
	v_mul_f32_e32 v10, 0xbfb8aa3b, v3
	v_exp_f32_e32 v10, v10
	s_nop 0
	v_add_f32_e32 v10, 1.0, v10
	v_rcp_f32_e32 v13, v10
	s_nop 0
	v_pk_mul_f32 v[10:11], v[2:3], v[12:13]
	v_mul_f32_e32 v3, 0xbfb8aa3b, v4
	v_exp_f32_e32 v3, v3
	v_mul_f32_e32 v2, 0xbfb8aa3b, v8
	v_exp_f32_e32 v2, v2
	v_add_f32_e32 v3, 1.0, v3
	v_rcp_f32_e32 v12, v3
	v_mul_f32_e32 v3, 0xbfb8aa3b, v9
	v_exp_f32_e32 v3, v3
	v_add_f32_e32 v2, 1.0, v2
	v_rcp_f32_e32 v2, v2
	v_add_f32_e32 v3, 1.0, v3
	v_rcp_f32_e32 v3, v3
	s_nop 0
	v_pk_mul_f32 v[8:9], v[8:9], v[2:3]
	v_mul_f32_e32 v2, 0xbfb8aa3b, v5
	v_exp_f32_e32 v2, v2
	v_cvt_pk_bf16_f32 v3, v8, v9
	v_add_f32_e32 v2, 1.0, v2
	v_rcp_f32_e32 v13, v2
	v_cvt_pk_bf16_f32 v2, v6, v7
	v_pk_mul_f32 v[12:13], v[4:5], v[12:13]
	v_cvt_pk_bf16_f32 v4, v10, v11
	v_cvt_pk_bf16_f32 v5, v12, v13
	global_store_dwordx4 v[14:15], v[2:5], off offset:256
	s_andn2_b64 vcc, exec, s[38:39]
	s_mov_b64 s[6:7], -1
	s_cbranch_vccnz .LBB0_96

.LBB0_206:
	s_cmp_gt_u32 s74, 15
	s_cbranch_scc0 .LBB0_246
	s_cmp_gt_u32 s74, 23
	s_cbranch_scc0 .LBB0_243
	s_cmp_gt_u32 s74, 31
	s_cbranch_scc0 .LBB0_240
	s_cmp_gt_u32 s74, 39
	s_cbranch_scc0 .LBB0_237
	s_cmp_gt_u32 s74, 47
	s_cbranch_scc0 .LBB0_234
	s_cmp_gt_u32 s74, 51
	s_cbranch_scc0 .LBB0_231
	s_cmp_gt_u32 s74, 55
	s_cbranch_scc0 .LBB0_228
	s_cmp_gt_u32 s74, 63
	s_cbranch_scc0 .LBB0_225
	s_cmpk_gt_u32 s74, 0x47
	s_cbranch_scc0 .LBB0_222
	s_cmpk_gt_u32 s74, 0x77
	s_cbranch_scc0 .LBB0_219
	s_and_saveexec_b64 s[6:7], s[36:37]
	s_cbranch_execz .LBB0_218
	v_or_b32_e32 v4, 16, v10
	v_ashrrev_i32_e32 v11, 31, v10
	v_ashrrev_i32_e32 v5, 31, v4
	v_lshlrev_b64 v[2:3], 6, v[10:11]
	v_mov_b64_e32 v[6:7], v[220:221]
	v_lshlrev_b64 v[4:5], 6, v[4:5]
	v_lshl_add_u64 v[2:3], v[6:7], 0, v[2:3]
	v_lshl_add_u64 v[4:5], v[6:7], 0, v[4:5]
	global_store_dwordx4 v[2:3], v[160:163], off
	global_store_dwordx4 v[2:3], v[156:159], off offset:16
	global_store_dwordx4 v[4:5], v[144:147], off
	global_store_dwordx4 v[4:5], v[140:143], off offset:16
	v_or_b32_e32 v4, 32, v10
	v_ashrrev_i32_e32 v5, 31, v4
	v_lshlrev_b64 v[4:5], 6, v[4:5]
	v_lshl_add_u64 v[4:5], v[6:7], 0, v[4:5]
	global_store_dwordx4 v[4:5], v[128:131], off
	global_store_dwordx4 v[4:5], v[124:127], off offset:16
	v_or_b32_e32 v4, 48, v10
	v_ashrrev_i32_e32 v5, 31, v4
	v_lshlrev_b64 v[4:5], 6, v[4:5]
	v_lshl_add_u64 v[4:5], v[6:7], 0, v[4:5]
	s_mov_b64 s[8:9], 0x2000
	v_add_co_u32_e32 v6, vcc, 0x2000, v2
	global_store_dwordx4 v[4:5], v[112:115], off
	global_store_dwordx4 v[4:5], v[108:111], off offset:16
	v_lshl_add_u64 v[4:5], v[2:3], 0, s[8:9]
	v_addc_co_u32_e32 v7, vcc, 0, v3, vcc
	s_mov_b64 s[8:9], 0x2400
	global_store_dwordx4 v[6:7], v[96:99], off
	global_store_dwordx4 v[4:5], v[92:95], off offset:16
	v_lshl_add_u64 v[4:5], v[2:3], 0, s[8:9]
	s_mov_b64 s[8:9], 0x2800
	global_store_dwordx4 v[6:7], v[80:83], off offset:1024
	global_store_dwordx4 v[4:5], v[76:79], off offset:16
	v_lshl_add_u64 v[4:5], v[2:3], 0, s[8:9]
	s_mov_b64 s[8:9], 0x2c00
	global_store_dwordx4 v[6:7], v[64:67], off offset:2048
	global_store_dwordx4 v[4:5], v[60:63], off offset:16
	v_lshl_add_u64 v[2:3], v[2:3], 0, s[8:9]
	global_store_dwordx4 v[6:7], v[48:51], off offset:3072
	global_store_dwordx4 v[2:3], v[44:47], off offset:16

.LBB0_219:
	s_andn2_b64 vcc, exec, s[6:7]
	s_cbranch_vccnz .LBB0_221
	v_mul_f32_e32 v4, 0x3c800000, v160
	v_mul_f32_e32 v4, 0xbfb8aa3b, v4
	v_mul_f32_e32 v9, 0x3c800000, v161
	v_exp_f32_e32 v4, v4
	v_mul_f32_e32 v9, 0xbfb8aa3b, v9
	v_mul_f32_e32 v12, 0x3c800000, v162
	v_mul_f32_e32 v5, 0x3c800000, v156
	v_exp_f32_e32 v9, v9
	v_mul_f32_e32 v12, 0xbfb8aa3b, v12
	v_mul_f32_e32 v14, 0x3c800000, v163
	v_mul_f32_e32 v5, 0xbfb8aa3b, v5
	v_mul_f32_e32 v11, 0x3c800000, v157
	v_exp_f32_e32 v12, v12
	v_mul_f32_e32 v14, 0xbfb8aa3b, v14
	v_exp_f32_e32 v5, v5
	v_mul_f32_e32 v11, 0xbfb8aa3b, v11
	v_mul_f32_e32 v13, 0x3c800000, v158
	v_exp_f32_e32 v14, v14
	v_add_f32_e32 v4, 1.0, v4
	v_exp_f32_e32 v11, v11
	v_mul_f32_e32 v13, 0xbfb8aa3b, v13
	v_mul_f32_e32 v15, 0x3c800000, v159
	v_rcp_f32_e32 v7, v4
	v_add_f32_e32 v9, 1.0, v9
	v_exp_f32_e32 v13, v13
	v_mul_f32_e32 v15, 0xbfb8aa3b, v15
	v_rcp_f32_e32 v9, v9
	v_add_f32_e32 v12, 1.0, v12
	v_exp_f32_e32 v15, v15
	v_add_f32_e32 v4, 1.0, v5
	v_rcp_f32_e32 v12, v12
	v_add_f32_e32 v14, 1.0, v14
	v_rcp_f32_e32 v8, v4
	s_mov_b32 s9, 0x437f0000
	v_add_f32_e32 v11, 1.0, v11
	v_rcp_f32_e32 v14, v14
	v_fma_f32 v7, v7, s9, 0.5
	v_rcp_f32_e32 v11, v11
	v_add_f32_e32 v13, 1.0, v13
	v_or_b32_e32 v2, 0xffffb800, v195
	v_max_f32_e32 v7, 1.0, v7
	v_fma_f32 v9, v9, s9, 0.5
	v_rcp_f32_e32 v13, v13
	v_add_f32_e32 v15, 1.0, v15
	v_lshl_add_u32 v2, s74, 8, v2
	v_max_f32_e32 v9, 1.0, v9
	v_fma_f32 v12, v12, s9, 0.5
	v_rcp_f32_e32 v15, v15
	v_cvt_pk_u8_f32 v7, v7, 0, 0
	v_fma_f32 v8, v8, s9, 0.5
	v_bfe_u32 v3, v2, 3, 1
	v_max_f32_e32 v12, 1.0, v12
	v_fma_f32 v14, v14, s9, 0.5
	v_cvt_pk_u8_f32 v7, v9, 1, v7
	v_lshl_or_b32 v6, v3, 4, v10
	v_lshlrev_b32_e32 v3, 3, v3
	v_max_f32_e32 v8, 1.0, v8
	v_fma_f32 v11, v11, s9, 0.5
	v_max_f32_e32 v14, 1.0, v14
	v_cvt_pk_u8_f32 v7, v12, 2, v7
	v_sub_u32_e32 v2, v2, v3
	v_max_f32_e32 v11, 1.0, v11
	v_fma_f32 v13, v13, s9, 0.5
	v_cvt_pk_u8_f32 v12, v14, 3, v7
	v_cvt_pk_u8_f32 v7, v8, 0, 0
	v_ashrrev_i32_e32 v3, 31, v2
	v_max_f32_e32 v13, 1.0, v13
	v_fma_f32 v15, v15, s9, 0.5
	v_cvt_pk_u8_f32 v7, v11, 1, v7
	v_lshl_add_u64 v[2:3], s[58:59], 0, v[2:3]
	s_movk_i32 s8, 0x3000
	v_max_f32_e32 v15, 1.0, v15
	v_cvt_pk_u8_f32 v7, v13, 2, v7
	v_mad_i64_i32 v[4:5], s[6:7], v6, s8, v[2:3]
	v_cvt_pk_u8_f32 v13, v15, 3, v7
	v_mul_f32_e32 v7, 0x3c800000, v144
	v_mul_f32_e32 v7, 0xbfb8aa3b, v7
	v_mul_f32_e32 v9, 0x3c800000, v145
	v_exp_f32_e32 v7, v7
	v_mul_f32_e32 v9, 0xbfb8aa3b, v9
	v_mul_f32_e32 v14, 0x3c800000, v146
	v_mul_f32_e32 v8, 0x3c800000, v140
	v_exp_f32_e32 v9, v9
	v_mul_f32_e32 v14, 0xbfb8aa3b, v14
	v_mul_f32_e32 v16, 0x3c800000, v147
	v_mul_f32_e32 v8, 0xbfb8aa3b, v8
	v_mul_f32_e32 v11, 0x3c800000, v141
	v_exp_f32_e32 v14, v14
	v_mul_f32_e32 v16, 0xbfb8aa3b, v16
	v_exp_f32_e32 v8, v8
	v_mul_f32_e32 v11, 0xbfb8aa3b, v11
	v_mul_f32_e32 v15, 0x3c800000, v142
	v_exp_f32_e32 v16, v16
	v_add_f32_e32 v7, 1.0, v7
	v_exp_f32_e32 v11, v11
	v_mul_f32_e32 v15, 0xbfb8aa3b, v15
	v_mul_f32_e32 v17, 0x3c800000, v143
	v_rcp_f32_e32 v7, v7
	v_add_f32_e32 v9, 1.0, v9
	v_exp_f32_e32 v15, v15
	v_mul_f32_e32 v17, 0xbfb8aa3b, v17
	v_rcp_f32_e32 v9, v9
	v_add_f32_e32 v14, 1.0, v14
	v_exp_f32_e32 v17, v17
	v_add_f32_e32 v8, 1.0, v8
	v_rcp_f32_e32 v14, v14
	v_add_f32_e32 v16, 1.0, v16
	v_rcp_f32_e32 v8, v8
	v_add_f32_e32 v11, 1.0, v11
	v_rcp_f32_e32 v16, v16
	v_fma_f32 v7, v7, s9, 0.5
	v_rcp_f32_e32 v11, v11
	v_add_f32_e32 v15, 1.0, v15
	v_max_f32_e32 v7, 1.0, v7
	v_fma_f32 v9, v9, s9, 0.5
	v_rcp_f32_e32 v15, v15
	v_add_f32_e32 v17, 1.0, v17
	v_max_f32_e32 v9, 1.0, v9
	v_fma_f32 v14, v14, s9, 0.5
	v_rcp_f32_e32 v17, v17
	v_cvt_pk_u8_f32 v7, v7, 0, 0
	v_fma_f32 v8, v8, s9, 0.5
	v_max_f32_e32 v14, 1.0, v14
	v_fma_f32 v16, v16, s9, 0.5
	v_cvt_pk_u8_f32 v7, v9, 1, v7
	v_max_f32_e32 v8, 1.0, v8
	v_fma_f32 v11, v11, s9, 0.5
	v_max_f32_e32 v16, 1.0, v16
	v_cvt_pk_u8_f32 v7, v14, 2, v7
	v_max_f32_e32 v11, 1.0, v11
	v_fma_f32 v15, v15, s9, 0.5
	v_cvt_pk_u8_f32 v14, v16, 3, v7
	v_cvt_pk_u8_f32 v7, v8, 0, 0
	v_max_f32_e32 v15, 1.0, v15
	v_fma_f32 v17, v17, s9, 0.5
	v_cvt_pk_u8_f32 v7, v11, 1, v7
	v_max_f32_e32 v17, 1.0, v17
	v_cvt_pk_u8_f32 v7, v15, 2, v7
	v_cvt_pk_u8_f32 v15, v17, 3, v7
	v_mul_f32_e32 v7, 0x3c800000, v152
	v_permlane16_swap_b32_e32 v12, v14
	v_mul_f32_e32 v7, 0xbfb8aa3b, v7
	v_permlane16_swap_b32_e32 v13, v15
	v_mul_f32_e32 v9, 0x3c800000, v153
	v_exp_f32_e32 v7, v7
	global_store_dwordx4 v[4:5], v[12:15], off
	v_mul_f32_e32 v9, 0xbfb8aa3b, v9
	v_mul_f32_e32 v8, 0x3c800000, v148
	v_mul_f32_e32 v12, 0x3c800000, v154
	v_exp_f32_e32 v9, v9
	v_mul_f32_e32 v12, 0xbfb8aa3b, v12
	v_mul_f32_e32 v14, 0x3c800000, v155
	v_mul_f32_e32 v8, 0xbfb8aa3b, v8
	v_mul_f32_e32 v11, 0x3c800000, v149
	v_exp_f32_e32 v12, v12
	v_mul_f32_e32 v14, 0xbfb8aa3b, v14
	v_exp_f32_e32 v8, v8
	v_mul_f32_e32 v11, 0xbfb8aa3b, v11
	v_mul_f32_e32 v13, 0x3c800000, v150
	v_exp_f32_e32 v14, v14
	v_add_f32_e32 v7, 1.0, v7
	v_exp_f32_e32 v11, v11
	v_mul_f32_e32 v13, 0xbfb8aa3b, v13
	v_mul_f32_e32 v15, 0x3c800000, v151
	v_rcp_f32_e32 v7, v7
	v_add_f32_e32 v9, 1.0, v9
	v_exp_f32_e32 v13, v13
	v_mul_f32_e32 v15, 0xbfb8aa3b, v15
	v_rcp_f32_e32 v9, v9
	v_add_f32_e32 v12, 1.0, v12
	v_exp_f32_e32 v15, v15
	v_add_f32_e32 v8, 1.0, v8
	v_rcp_f32_e32 v12, v12
	v_add_f32_e32 v14, 1.0, v14
	v_rcp_f32_e32 v8, v8
	v_add_f32_e32 v11, 1.0, v11
	v_rcp_f32_e32 v14, v14
	v_fma_f32 v7, v7, s9, 0.5
	v_rcp_f32_e32 v11, v11
	v_add_f32_e32 v13, 1.0, v13
	v_max_f32_e32 v7, 1.0, v7
	v_fma_f32 v9, v9, s9, 0.5
	v_rcp_f32_e32 v13, v13
	v_add_f32_e32 v15, 1.0, v15
	v_max_f32_e32 v9, 1.0, v9
	v_fma_f32 v12, v12, s9, 0.5
	v_rcp_f32_e32 v15, v15
	v_cvt_pk_u8_f32 v7, v7, 0, 0
	v_fma_f32 v8, v8, s9, 0.5
	v_max_f32_e32 v12, 1.0, v12
	v_fma_f32 v14, v14, s9, 0.5
	v_cvt_pk_u8_f32 v7, v9, 1, v7
	v_max_f32_e32 v8, 1.0, v8
	v_fma_f32 v11, v11, s9, 0.5
	v_max_f32_e32 v14, 1.0, v14
	v_cvt_pk_u8_f32 v7, v12, 2, v7
	v_max_f32_e32 v11, 1.0, v11
	v_fma_f32 v13, v13, s9, 0.5
	v_cvt_pk_u8_f32 v12, v14, 3, v7
	v_cvt_pk_u8_f32 v7, v8, 0, 0
	v_max_f32_e32 v13, 1.0, v13
	v_fma_f32 v15, v15, s9, 0.5
	v_cvt_pk_u8_f32 v7, v11, 1, v7
	v_max_f32_e32 v15, 1.0, v15
	v_cvt_pk_u8_f32 v7, v13, 2, v7
	v_cvt_pk_u8_f32 v13, v15, 3, v7
	v_mul_f32_e32 v7, 0x3c800000, v136
	v_mul_f32_e32 v7, 0xbfb8aa3b, v7
	v_mul_f32_e32 v9, 0x3c800000, v137
	v_exp_f32_e32 v7, v7
	v_mul_f32_e32 v9, 0xbfb8aa3b, v9
	v_mul_f32_e32 v14, 0x3c800000, v138
	v_mul_f32_e32 v8, 0x3c800000, v132
	v_exp_f32_e32 v9, v9
	v_mul_f32_e32 v14, 0xbfb8aa3b, v14
	v_mul_f32_e32 v16, 0x3c800000, v139
	v_mul_f32_e32 v8, 0xbfb8aa3b, v8
	v_mul_f32_e32 v11, 0x3c800000, v133
	v_exp_f32_e32 v14, v14
	v_mul_f32_e32 v16, 0xbfb8aa3b, v16
	v_exp_f32_e32 v8, v8
	v_mul_f32_e32 v11, 0xbfb8aa3b, v11
	v_mul_f32_e32 v15, 0x3c800000, v134
	v_exp_f32_e32 v16, v16
	v_add_f32_e32 v7, 1.0, v7
	v_exp_f32_e32 v11, v11
	v_mul_f32_e32 v15, 0xbfb8aa3b, v15
	v_mul_f32_e32 v17, 0x3c800000, v135
	v_rcp_f32_e32 v7, v7
	v_add_f32_e32 v9, 1.0, v9
	v_exp_f32_e32 v15, v15
	v_mul_f32_e32 v17, 0xbfb8aa3b, v17
	v_rcp_f32_e32 v9, v9
	v_add_f32_e32 v14, 1.0, v14
	v_exp_f32_e32 v17, v17
	v_add_f32_e32 v8, 1.0, v8
	v_rcp_f32_e32 v14, v14
	v_add_f32_e32 v16, 1.0, v16
	v_rcp_f32_e32 v8, v8
	v_add_f32_e32 v11, 1.0, v11
	v_rcp_f32_e32 v16, v16
	v_fma_f32 v7, v7, s9, 0.5
	v_rcp_f32_e32 v11, v11
	v_add_f32_e32 v15, 1.0, v15
	v_max_f32_e32 v7, 1.0, v7
	v_fma_f32 v9, v9, s9, 0.5
	v_rcp_f32_e32 v15, v15
	v_add_f32_e32 v17, 1.0, v17
	v_max_f32_e32 v9, 1.0, v9
	v_fma_f32 v14, v14, s9, 0.5
	v_rcp_f32_e32 v17, v17
	v_cvt_pk_u8_f32 v7, v7, 0, 0
	v_fma_f32 v8, v8, s9, 0.5
	v_max_f32_e32 v14, 1.0, v14
	v_fma_f32 v16, v16, s9, 0.5
	v_cvt_pk_u8_f32 v7, v9, 1, v7
	v_max_f32_e32 v8, 1.0, v8
	v_fma_f32 v11, v11, s9, 0.5
	v_max_f32_e32 v16, 1.0, v16
	v_cvt_pk_u8_f32 v7, v14, 2, v7
	v_max_f32_e32 v11, 1.0, v11
	v_fma_f32 v15, v15, s9, 0.5
	v_cvt_pk_u8_f32 v14, v16, 3, v7
	v_cvt_pk_u8_f32 v7, v8, 0, 0
	v_max_f32_e32 v15, 1.0, v15
	v_fma_f32 v17, v17, s9, 0.5
	v_cvt_pk_u8_f32 v7, v11, 1, v7
	v_max_f32_e32 v17, 1.0, v17
	v_cvt_pk_u8_f32 v7, v15, 2, v7
	v_cvt_pk_u8_f32 v15, v17, 3, v7
	v_permlane16_swap_b32_e32 v12, v14
	s_nop 0
	v_permlane16_swap_b32_e32 v13, v15
	global_store_dwordx4 v[4:5], v[12:15], off offset:128
	v_mul_f32_e32 v4, 0x3c800000, v128
	v_mul_f32_e32 v4, 0xbfb8aa3b, v4
	v_mul_f32_e32 v5, 0x3c800000, v124
	v_exp_f32_e32 v4, v4
	v_mul_f32_e32 v5, 0xbfb8aa3b, v5
	v_exp_f32_e32 v5, v5
	v_or_b32_e32 v7, 32, v6
	v_add_f32_e32 v4, 1.0, v4
	v_rcp_f32_e32 v8, v4
	v_add_f32_e32 v4, 1.0, v5
	v_rcp_f32_e32 v9, v4
	v_mad_i64_i32 v[4:5], s[6:7], v7, s8, v[2:3]
	v_fma_f32 v7, v8, s9, 0.5
	v_fma_f32 v8, v9, s9, 0.5
	v_mul_f32_e32 v9, 0x3c800000, v129
	v_mul_f32_e32 v9, 0xbfb8aa3b, v9
	v_mul_f32_e32 v12, 0x3c800000, v130
	v_exp_f32_e32 v9, v9
	v_mul_f32_e32 v12, 0xbfb8aa3b, v12
	v_mul_f32_e32 v14, 0x3c800000, v131
	v_mul_f32_e32 v11, 0x3c800000, v125
	v_exp_f32_e32 v12, v12
	v_mul_f32_e32 v14, 0xbfb8aa3b, v14
	v_mul_f32_e32 v11, 0xbfb8aa3b, v11
	v_mul_f32_e32 v13, 0x3c800000, v126
	v_exp_f32_e32 v14, v14
	v_exp_f32_e32 v11, v11
	v_mul_f32_e32 v13, 0xbfb8aa3b, v13
	v_mul_f32_e32 v15, 0x3c800000, v127
	v_add_f32_e32 v9, 1.0, v9
	v_exp_f32_e32 v13, v13
	v_mul_f32_e32 v15, 0xbfb8aa3b, v15
	v_rcp_f32_e32 v9, v9
	v_add_f32_e32 v12, 1.0, v12
	v_exp_f32_e32 v15, v15
	v_rcp_f32_e32 v12, v12
	v_add_f32_e32 v14, 1.0, v14
	v_add_f32_e32 v11, 1.0, v11
	v_rcp_f32_e32 v14, v14
	v_rcp_f32_e32 v11, v11
	v_add_f32_e32 v13, 1.0, v13
	v_max_f32_e32 v7, 1.0, v7
	v_fma_f32 v9, v9, s9, 0.5
	v_rcp_f32_e32 v13, v13
	v_add_f32_e32 v15, 1.0, v15
	v_max_f32_e32 v9, 1.0, v9
	v_fma_f32 v12, v12, s9, 0.5
	v_rcp_f32_e32 v15, v15
	v_cvt_pk_u8_f32 v7, v7, 0, 0
	v_max_f32_e32 v12, 1.0, v12
	v_fma_f32 v14, v14, s9, 0.5
	v_cvt_pk_u8_f32 v7, v9, 1, v7
	v_max_f32_e32 v8, 1.0, v8
	v_fma_f32 v11, v11, s9, 0.5
	v_max_f32_e32 v14, 1.0, v14
	v_cvt_pk_u8_f32 v7, v12, 2, v7
	v_max_f32_e32 v11, 1.0, v11
	v_fma_f32 v13, v13, s9, 0.5
	v_cvt_pk_u8_f32 v12, v14, 3, v7
	v_cvt_pk_u8_f32 v7, v8, 0, 0
	v_max_f32_e32 v13, 1.0, v13
	v_fma_f32 v15, v15, s9, 0.5
	v_cvt_pk_u8_f32 v7, v11, 1, v7
	v_max_f32_e32 v15, 1.0, v15
	v_cvt_pk_u8_f32 v7, v13, 2, v7
	v_cvt_pk_u8_f32 v13, v15, 3, v7
	v_mul_f32_e32 v7, 0x3c800000, v112
	v_mul_f32_e32 v7, 0xbfb8aa3b, v7
	v_mul_f32_e32 v9, 0x3c800000, v113
	v_exp_f32_e32 v7, v7
	v_mul_f32_e32 v9, 0xbfb8aa3b, v9
	v_mul_f32_e32 v14, 0x3c800000, v114
	v_mul_f32_e32 v8, 0x3c800000, v108
	v_exp_f32_e32 v9, v9
	v_mul_f32_e32 v14, 0xbfb8aa3b, v14
	v_mul_f32_e32 v16, 0x3c800000, v115
	v_mul_f32_e32 v8, 0xbfb8aa3b, v8
	v_mul_f32_e32 v11, 0x3c800000, v109
	v_exp_f32_e32 v14, v14
	v_mul_f32_e32 v16, 0xbfb8aa3b, v16
	v_exp_f32_e32 v8, v8
	v_mul_f32_e32 v11, 0xbfb8aa3b, v11
	v_mul_f32_e32 v15, 0x3c800000, v110
	v_exp_f32_e32 v16, v16
	v_add_f32_e32 v7, 1.0, v7
	v_exp_f32_e32 v11, v11
	v_mul_f32_e32 v15, 0xbfb8aa3b, v15
	v_mul_f32_e32 v17, 0x3c800000, v111
	v_rcp_f32_e32 v7, v7
	v_add_f32_e32 v9, 1.0, v9
	v_exp_f32_e32 v15, v15
	v_mul_f32_e32 v17, 0xbfb8aa3b, v17
	v_rcp_f32_e32 v9, v9
	v_add_f32_e32 v14, 1.0, v14
	v_exp_f32_e32 v17, v17
	v_add_f32_e32 v8, 1.0, v8
	v_rcp_f32_e32 v14, v14
	v_add_f32_e32 v16, 1.0, v16
	v_rcp_f32_e32 v8, v8
	v_add_f32_e32 v11, 1.0, v11
	v_rcp_f32_e32 v16, v16
	v_fma_f32 v7, v7, s9, 0.5
	v_rcp_f32_e32 v11, v11
	v_add_f32_e32 v15, 1.0, v15
	v_max_f32_e32 v7, 1.0, v7
	v_fma_f32 v9, v9, s9, 0.5
	v_rcp_f32_e32 v15, v15
	v_add_f32_e32 v17, 1.0, v17
	v_max_f32_e32 v9, 1.0, v9
	v_fma_f32 v14, v14, s9, 0.5
	v_rcp_f32_e32 v17, v17
	v_cvt_pk_u8_f32 v7, v7, 0, 0
	v_fma_f32 v8, v8, s9, 0.5
	v_max_f32_e32 v14, 1.0, v14
	v_fma_f32 v16, v16, s9, 0.5
	v_cvt_pk_u8_f32 v7, v9, 1, v7
	v_max_f32_e32 v8, 1.0, v8
	v_fma_f32 v11, v11, s9, 0.5
	v_max_f32_e32 v16, 1.0, v16
	v_cvt_pk_u8_f32 v7, v14, 2, v7
	v_max_f32_e32 v11, 1.0, v11
	v_fma_f32 v15, v15, s9, 0.5
	v_cvt_pk_u8_f32 v14, v16, 3, v7
	v_cvt_pk_u8_f32 v7, v8, 0, 0
	v_max_f32_e32 v15, 1.0, v15
	v_fma_f32 v17, v17, s9, 0.5
	v_cvt_pk_u8_f32 v7, v11, 1, v7
	v_max_f32_e32 v17, 1.0, v17
	v_cvt_pk_u8_f32 v7, v15, 2, v7
	v_cvt_pk_u8_f32 v15, v17, 3, v7
	v_mul_f32_e32 v7, 0x3c800000, v120
	v_permlane16_swap_b32_e32 v12, v14
	v_mul_f32_e32 v7, 0xbfb8aa3b, v7
	v_permlane16_swap_b32_e32 v13, v15
	v_mul_f32_e32 v9, 0x3c800000, v121
	v_exp_f32_e32 v7, v7
	global_store_dwordx4 v[4:5], v[12:15], off
	v_mul_f32_e32 v9, 0xbfb8aa3b, v9
	v_mul_f32_e32 v8, 0x3c800000, v116
	v_mul_f32_e32 v12, 0x3c800000, v122
	v_exp_f32_e32 v9, v9
	v_mul_f32_e32 v12, 0xbfb8aa3b, v12
	v_mul_f32_e32 v14, 0x3c800000, v123
	v_mul_f32_e32 v8, 0xbfb8aa3b, v8
	v_mul_f32_e32 v11, 0x3c800000, v117
	v_exp_f32_e32 v12, v12
	v_mul_f32_e32 v14, 0xbfb8aa3b, v14
	v_exp_f32_e32 v8, v8
	v_mul_f32_e32 v11, 0xbfb8aa3b, v11
	v_mul_f32_e32 v13, 0x3c800000, v118
	v_exp_f32_e32 v14, v14
	v_add_f32_e32 v7, 1.0, v7
	v_exp_f32_e32 v11, v11
	v_mul_f32_e32 v13, 0xbfb8aa3b, v13
	v_mul_f32_e32 v15, 0x3c800000, v119
	v_rcp_f32_e32 v7, v7
	v_add_f32_e32 v9, 1.0, v9
	v_exp_f32_e32 v13, v13
	v_mul_f32_e32 v15, 0xbfb8aa3b, v15
	v_rcp_f32_e32 v9, v9
	v_add_f32_e32 v12, 1.0, v12
	v_exp_f32_e32 v15, v15
	v_add_f32_e32 v8, 1.0, v8
	v_rcp_f32_e32 v12, v12
	v_add_f32_e32 v14, 1.0, v14
	v_rcp_f32_e32 v8, v8
	v_add_f32_e32 v11, 1.0, v11
	v_rcp_f32_e32 v14, v14
	v_fma_f32 v7, v7, s9, 0.5
	v_rcp_f32_e32 v11, v11
	v_add_f32_e32 v13, 1.0, v13
	v_max_f32_e32 v7, 1.0, v7
	v_fma_f32 v9, v9, s9, 0.5
	v_rcp_f32_e32 v13, v13
	v_add_f32_e32 v15, 1.0, v15
	v_max_f32_e32 v9, 1.0, v9
	v_fma_f32 v12, v12, s9, 0.5
	v_rcp_f32_e32 v15, v15
	v_cvt_pk_u8_f32 v7, v7, 0, 0
	v_fma_f32 v8, v8, s9, 0.5
	v_max_f32_e32 v12, 1.0, v12
	v_fma_f32 v14, v14, s9, 0.5
	v_cvt_pk_u8_f32 v7, v9, 1, v7
	v_max_f32_e32 v8, 1.0, v8
	v_fma_f32 v11, v11, s9, 0.5
	v_max_f32_e32 v14, 1.0, v14
	v_cvt_pk_u8_f32 v7, v12, 2, v7
	v_max_f32_e32 v11, 1.0, v11
	v_fma_f32 v13, v13, s9, 0.5
	v_cvt_pk_u8_f32 v12, v14, 3, v7
	v_cvt_pk_u8_f32 v7, v8, 0, 0
	v_max_f32_e32 v13, 1.0, v13
	v_fma_f32 v15, v15, s9, 0.5
	v_cvt_pk_u8_f32 v7, v11, 1, v7
	v_max_f32_e32 v15, 1.0, v15
	v_cvt_pk_u8_f32 v7, v13, 2, v7
	v_cvt_pk_u8_f32 v13, v15, 3, v7
	v_mul_f32_e32 v7, 0x3c800000, v104
	v_mul_f32_e32 v7, 0xbfb8aa3b, v7
	v_mul_f32_e32 v9, 0x3c800000, v105
	v_exp_f32_e32 v7, v7
	v_mul_f32_e32 v9, 0xbfb8aa3b, v9
	v_mul_f32_e32 v14, 0x3c800000, v106
	v_mul_f32_e32 v8, 0x3c800000, v100
	v_exp_f32_e32 v9, v9
	v_mul_f32_e32 v14, 0xbfb8aa3b, v14
	v_mul_f32_e32 v16, 0x3c800000, v107
	v_mul_f32_e32 v8, 0xbfb8aa3b, v8
	v_mul_f32_e32 v11, 0x3c800000, v101
	v_exp_f32_e32 v14, v14
	v_mul_f32_e32 v16, 0xbfb8aa3b, v16
	v_exp_f32_e32 v8, v8
	v_mul_f32_e32 v11, 0xbfb8aa3b, v11
	v_mul_f32_e32 v15, 0x3c800000, v102
	v_exp_f32_e32 v16, v16
	v_add_f32_e32 v7, 1.0, v7
	v_exp_f32_e32 v11, v11
	v_mul_f32_e32 v15, 0xbfb8aa3b, v15
	v_mul_f32_e32 v17, 0x3c800000, v103
	v_rcp_f32_e32 v7, v7
	v_add_f32_e32 v9, 1.0, v9
	v_exp_f32_e32 v15, v15
	v_mul_f32_e32 v17, 0xbfb8aa3b, v17
	v_rcp_f32_e32 v9, v9
	v_add_f32_e32 v14, 1.0, v14
	v_exp_f32_e32 v17, v17
	v_add_f32_e32 v8, 1.0, v8
	v_rcp_f32_e32 v14, v14
	v_add_f32_e32 v16, 1.0, v16
	v_rcp_f32_e32 v8, v8
	v_add_f32_e32 v11, 1.0, v11
	v_rcp_f32_e32 v16, v16
	v_fma_f32 v7, v7, s9, 0.5
	v_rcp_f32_e32 v11, v11
	v_add_f32_e32 v15, 1.0, v15
	v_max_f32_e32 v7, 1.0, v7
	v_fma_f32 v9, v9, s9, 0.5
	v_rcp_f32_e32 v15, v15
	v_add_f32_e32 v17, 1.0, v17
	v_max_f32_e32 v9, 1.0, v9
	v_fma_f32 v14, v14, s9, 0.5
	v_rcp_f32_e32 v17, v17
	v_cvt_pk_u8_f32 v7, v7, 0, 0
	v_fma_f32 v8, v8, s9, 0.5
	v_max_f32_e32 v14, 1.0, v14
	v_fma_f32 v16, v16, s9, 0.5
	v_cvt_pk_u8_f32 v7, v9, 1, v7
	v_max_f32_e32 v8, 1.0, v8
	v_fma_f32 v11, v11, s9, 0.5
	v_max_f32_e32 v16, 1.0, v16
	v_cvt_pk_u8_f32 v7, v14, 2, v7
	v_max_f32_e32 v11, 1.0, v11
	v_fma_f32 v15, v15, s9, 0.5
	v_cvt_pk_u8_f32 v14, v16, 3, v7
	v_cvt_pk_u8_f32 v7, v8, 0, 0
	v_max_f32_e32 v15, 1.0, v15
	v_fma_f32 v17, v17, s9, 0.5
	v_cvt_pk_u8_f32 v7, v11, 1, v7
	v_max_f32_e32 v17, 1.0, v17
	v_cvt_pk_u8_f32 v7, v15, 2, v7
	v_cvt_pk_u8_f32 v15, v17, 3, v7
	v_permlane16_swap_b32_e32 v12, v14
	s_nop 0
	v_permlane16_swap_b32_e32 v13, v15
	global_store_dwordx4 v[4:5], v[12:15], off offset:128
	v_mul_f32_e32 v4, 0x3c800000, v96
	v_mul_f32_e32 v4, 0xbfb8aa3b, v4
	v_mul_f32_e32 v5, 0x3c800000, v92
	v_exp_f32_e32 v4, v4
	v_mul_f32_e32 v5, 0xbfb8aa3b, v5
	v_exp_f32_e32 v5, v5
	v_add_u32_e32 v7, 0x80, v6
	v_add_f32_e32 v4, 1.0, v4
	v_rcp_f32_e32 v8, v4
	v_add_f32_e32 v4, 1.0, v5
	v_rcp_f32_e32 v9, v4
	v_mad_i64_i32 v[4:5], s[6:7], v7, s8, v[2:3]
	v_fma_f32 v7, v8, s9, 0.5
	v_fma_f32 v8, v9, s9, 0.5
	v_mul_f32_e32 v9, 0x3c800000, v97
	v_mul_f32_e32 v9, 0xbfb8aa3b, v9
	v_mul_f32_e32 v12, 0x3c800000, v98
	v_exp_f32_e32 v9, v9
	v_mul_f32_e32 v12, 0xbfb8aa3b, v12
	v_mul_f32_e32 v14, 0x3c800000, v99
	v_mul_f32_e32 v11, 0x3c800000, v93
	v_exp_f32_e32 v12, v12
	v_mul_f32_e32 v14, 0xbfb8aa3b, v14
	v_mul_f32_e32 v11, 0xbfb8aa3b, v11
	v_mul_f32_e32 v13, 0x3c800000, v94
	v_exp_f32_e32 v14, v14
	v_exp_f32_e32 v11, v11
	v_mul_f32_e32 v13, 0xbfb8aa3b, v13
	v_mul_f32_e32 v15, 0x3c800000, v95
	v_add_f32_e32 v9, 1.0, v9
	v_exp_f32_e32 v13, v13
	v_mul_f32_e32 v15, 0xbfb8aa3b, v15
	v_rcp_f32_e32 v9, v9
	v_add_f32_e32 v12, 1.0, v12
	v_exp_f32_e32 v15, v15
	v_rcp_f32_e32 v12, v12
	v_add_f32_e32 v14, 1.0, v14
	v_add_f32_e32 v11, 1.0, v11
	v_rcp_f32_e32 v14, v14
	v_rcp_f32_e32 v11, v11
	v_add_f32_e32 v13, 1.0, v13
	v_max_f32_e32 v7, 1.0, v7
	v_fma_f32 v9, v9, s9, 0.5
	v_rcp_f32_e32 v13, v13
	v_add_f32_e32 v15, 1.0, v15
	v_max_f32_e32 v9, 1.0, v9
	v_fma_f32 v12, v12, s9, 0.5
	v_rcp_f32_e32 v15, v15
	v_cvt_pk_u8_f32 v7, v7, 0, 0
	v_max_f32_e32 v12, 1.0, v12
	v_fma_f32 v14, v14, s9, 0.5
	v_cvt_pk_u8_f32 v7, v9, 1, v7
	v_max_f32_e32 v8, 1.0, v8
	v_fma_f32 v11, v11, s9, 0.5
	v_max_f32_e32 v14, 1.0, v14
	v_cvt_pk_u8_f32 v7, v12, 2, v7
	v_max_f32_e32 v11, 1.0, v11
	v_fma_f32 v13, v13, s9, 0.5
	v_cvt_pk_u8_f32 v12, v14, 3, v7
	v_cvt_pk_u8_f32 v7, v8, 0, 0
	v_max_f32_e32 v13, 1.0, v13
	v_fma_f32 v15, v15, s9, 0.5
	v_cvt_pk_u8_f32 v7, v11, 1, v7
	v_max_f32_e32 v15, 1.0, v15
	v_cvt_pk_u8_f32 v7, v13, 2, v7
	v_cvt_pk_u8_f32 v13, v15, 3, v7
	v_mul_f32_e32 v7, 0x3c800000, v80
	v_mul_f32_e32 v7, 0xbfb8aa3b, v7
	v_mul_f32_e32 v9, 0x3c800000, v81
	v_exp_f32_e32 v7, v7
	v_mul_f32_e32 v9, 0xbfb8aa3b, v9
	v_mul_f32_e32 v14, 0x3c800000, v82
	v_mul_f32_e32 v8, 0x3c800000, v76
	v_exp_f32_e32 v9, v9
	v_mul_f32_e32 v14, 0xbfb8aa3b, v14
	v_mul_f32_e32 v16, 0x3c800000, v83
	v_mul_f32_e32 v8, 0xbfb8aa3b, v8
	v_mul_f32_e32 v11, 0x3c800000, v77
	v_exp_f32_e32 v14, v14
	v_mul_f32_e32 v16, 0xbfb8aa3b, v16
	v_exp_f32_e32 v8, v8
	v_mul_f32_e32 v11, 0xbfb8aa3b, v11
	v_mul_f32_e32 v15, 0x3c800000, v78
	v_exp_f32_e32 v16, v16
	v_add_f32_e32 v7, 1.0, v7
	v_exp_f32_e32 v11, v11
	v_mul_f32_e32 v15, 0xbfb8aa3b, v15
	v_mul_f32_e32 v17, 0x3c800000, v79
	v_rcp_f32_e32 v7, v7
	v_add_f32_e32 v9, 1.0, v9
	v_exp_f32_e32 v15, v15
	v_mul_f32_e32 v17, 0xbfb8aa3b, v17
	v_rcp_f32_e32 v9, v9
	v_add_f32_e32 v14, 1.0, v14
	v_exp_f32_e32 v17, v17
	v_add_f32_e32 v8, 1.0, v8
	v_rcp_f32_e32 v14, v14
	v_add_f32_e32 v16, 1.0, v16
	v_rcp_f32_e32 v8, v8
	v_add_f32_e32 v11, 1.0, v11
	v_rcp_f32_e32 v16, v16
	v_fma_f32 v7, v7, s9, 0.5
	v_rcp_f32_e32 v11, v11
	v_add_f32_e32 v15, 1.0, v15
	v_max_f32_e32 v7, 1.0, v7
	v_fma_f32 v9, v9, s9, 0.5
	v_rcp_f32_e32 v15, v15
	v_add_f32_e32 v17, 1.0, v17
	v_max_f32_e32 v9, 1.0, v9
	v_fma_f32 v14, v14, s9, 0.5
	v_rcp_f32_e32 v17, v17
	v_cvt_pk_u8_f32 v7, v7, 0, 0
	v_fma_f32 v8, v8, s9, 0.5
	v_max_f32_e32 v14, 1.0, v14
	v_fma_f32 v16, v16, s9, 0.5
	v_cvt_pk_u8_f32 v7, v9, 1, v7
	v_max_f32_e32 v8, 1.0, v8
	v_fma_f32 v11, v11, s9, 0.5
	v_max_f32_e32 v16, 1.0, v16
	v_cvt_pk_u8_f32 v7, v14, 2, v7
	v_max_f32_e32 v11, 1.0, v11
	v_fma_f32 v15, v15, s9, 0.5
	v_cvt_pk_u8_f32 v14, v16, 3, v7
	v_cvt_pk_u8_f32 v7, v8, 0, 0
	v_max_f32_e32 v15, 1.0, v15
	v_fma_f32 v17, v17, s9, 0.5
	v_cvt_pk_u8_f32 v7, v11, 1, v7
	v_max_f32_e32 v17, 1.0, v17
	v_cvt_pk_u8_f32 v7, v15, 2, v7
	v_cvt_pk_u8_f32 v15, v17, 3, v7
	v_mul_f32_e32 v7, 0x3c800000, v88
	v_permlane16_swap_b32_e32 v12, v14
	v_mul_f32_e32 v7, 0xbfb8aa3b, v7
	v_permlane16_swap_b32_e32 v13, v15
	v_mul_f32_e32 v9, 0x3c800000, v89
	v_exp_f32_e32 v7, v7
	global_store_dwordx4 v[4:5], v[12:15], off
	v_mul_f32_e32 v9, 0xbfb8aa3b, v9
	v_mul_f32_e32 v8, 0x3c800000, v84
	v_mul_f32_e32 v12, 0x3c800000, v90
	v_exp_f32_e32 v9, v9
	v_mul_f32_e32 v12, 0xbfb8aa3b, v12
	v_mul_f32_e32 v14, 0x3c800000, v91
	v_mul_f32_e32 v8, 0xbfb8aa3b, v8
	v_mul_f32_e32 v11, 0x3c800000, v85
	v_exp_f32_e32 v12, v12
	v_mul_f32_e32 v14, 0xbfb8aa3b, v14
	v_exp_f32_e32 v8, v8
	v_mul_f32_e32 v11, 0xbfb8aa3b, v11
	v_mul_f32_e32 v13, 0x3c800000, v86
	v_exp_f32_e32 v14, v14
	v_add_f32_e32 v7, 1.0, v7
	v_exp_f32_e32 v11, v11
	v_mul_f32_e32 v13, 0xbfb8aa3b, v13
	v_mul_f32_e32 v15, 0x3c800000, v87
	v_rcp_f32_e32 v7, v7
	v_add_f32_e32 v9, 1.0, v9
	v_exp_f32_e32 v13, v13
	v_mul_f32_e32 v15, 0xbfb8aa3b, v15
	v_rcp_f32_e32 v9, v9
	v_add_f32_e32 v12, 1.0, v12
	v_exp_f32_e32 v15, v15
	v_add_f32_e32 v8, 1.0, v8
	v_rcp_f32_e32 v12, v12
	v_add_f32_e32 v14, 1.0, v14
	v_rcp_f32_e32 v8, v8
	v_add_f32_e32 v11, 1.0, v11
	v_rcp_f32_e32 v14, v14
	v_fma_f32 v7, v7, s9, 0.5
	v_rcp_f32_e32 v11, v11
	v_add_f32_e32 v13, 1.0, v13
	v_max_f32_e32 v7, 1.0, v7
	v_fma_f32 v9, v9, s9, 0.5
	v_rcp_f32_e32 v13, v13
	v_add_f32_e32 v15, 1.0, v15
	v_max_f32_e32 v9, 1.0, v9
	v_fma_f32 v12, v12, s9, 0.5
	v_rcp_f32_e32 v15, v15
	v_cvt_pk_u8_f32 v7, v7, 0, 0
	v_fma_f32 v8, v8, s9, 0.5
	v_max_f32_e32 v12, 1.0, v12
	v_fma_f32 v14, v14, s9, 0.5
	v_cvt_pk_u8_f32 v7, v9, 1, v7
	v_max_f32_e32 v8, 1.0, v8
	v_fma_f32 v11, v11, s9, 0.5
	v_max_f32_e32 v14, 1.0, v14
	v_cvt_pk_u8_f32 v7, v12, 2, v7
	v_max_f32_e32 v11, 1.0, v11
	v_fma_f32 v13, v13, s9, 0.5
	v_cvt_pk_u8_f32 v12, v14, 3, v7
	v_cvt_pk_u8_f32 v7, v8, 0, 0
	v_max_f32_e32 v13, 1.0, v13
	v_fma_f32 v15, v15, s9, 0.5
	v_cvt_pk_u8_f32 v7, v11, 1, v7
	v_max_f32_e32 v15, 1.0, v15
	v_cvt_pk_u8_f32 v7, v13, 2, v7
	v_cvt_pk_u8_f32 v13, v15, 3, v7
	v_mul_f32_e32 v7, 0x3c800000, v72
	v_mul_f32_e32 v7, 0xbfb8aa3b, v7
	v_mul_f32_e32 v9, 0x3c800000, v73
	v_exp_f32_e32 v7, v7
	v_mul_f32_e32 v9, 0xbfb8aa3b, v9
	v_mul_f32_e32 v14, 0x3c800000, v74
	v_mul_f32_e32 v8, 0x3c800000, v68
	v_exp_f32_e32 v9, v9
	v_mul_f32_e32 v14, 0xbfb8aa3b, v14
	v_mul_f32_e32 v16, 0x3c800000, v75
	v_mul_f32_e32 v8, 0xbfb8aa3b, v8
	v_mul_f32_e32 v11, 0x3c800000, v69
	v_exp_f32_e32 v14, v14
	v_mul_f32_e32 v16, 0xbfb8aa3b, v16
	v_exp_f32_e32 v8, v8
	v_mul_f32_e32 v11, 0xbfb8aa3b, v11
	v_mul_f32_e32 v15, 0x3c800000, v70
	v_exp_f32_e32 v16, v16
	v_add_f32_e32 v7, 1.0, v7
	v_exp_f32_e32 v11, v11
	v_mul_f32_e32 v15, 0xbfb8aa3b, v15
	v_mul_f32_e32 v17, 0x3c800000, v71
	v_rcp_f32_e32 v7, v7
	v_add_f32_e32 v9, 1.0, v9
	v_exp_f32_e32 v15, v15
	v_mul_f32_e32 v17, 0xbfb8aa3b, v17
	v_rcp_f32_e32 v9, v9
	v_add_f32_e32 v14, 1.0, v14
	v_exp_f32_e32 v17, v17
	v_add_f32_e32 v8, 1.0, v8
	v_rcp_f32_e32 v14, v14
	v_add_f32_e32 v16, 1.0, v16
	v_rcp_f32_e32 v8, v8
	v_add_f32_e32 v11, 1.0, v11
	v_rcp_f32_e32 v16, v16
	v_fma_f32 v7, v7, s9, 0.5
	v_rcp_f32_e32 v11, v11
	v_add_f32_e32 v15, 1.0, v15
	v_max_f32_e32 v7, 1.0, v7
	v_fma_f32 v9, v9, s9, 0.5
	v_rcp_f32_e32 v15, v15
	v_add_f32_e32 v17, 1.0, v17
	v_max_f32_e32 v9, 1.0, v9
	v_fma_f32 v14, v14, s9, 0.5
	v_rcp_f32_e32 v17, v17
	v_cvt_pk_u8_f32 v7, v7, 0, 0
	v_fma_f32 v8, v8, s9, 0.5
	v_max_f32_e32 v14, 1.0, v14
	v_fma_f32 v16, v16, s9, 0.5
	v_cvt_pk_u8_f32 v7, v9, 1, v7
	v_max_f32_e32 v8, 1.0, v8
	v_fma_f32 v11, v11, s9, 0.5
	v_max_f32_e32 v16, 1.0, v16
	v_cvt_pk_u8_f32 v7, v14, 2, v7
	v_max_f32_e32 v11, 1.0, v11
	v_fma_f32 v15, v15, s9, 0.5
	v_cvt_pk_u8_f32 v14, v16, 3, v7
	v_cvt_pk_u8_f32 v7, v8, 0, 0
	v_max_f32_e32 v15, 1.0, v15
	v_fma_f32 v17, v17, s9, 0.5
	v_cvt_pk_u8_f32 v7, v11, 1, v7
	v_max_f32_e32 v17, 1.0, v17
	v_cvt_pk_u8_f32 v7, v15, 2, v7
	v_cvt_pk_u8_f32 v15, v17, 3, v7
	v_permlane16_swap_b32_e32 v12, v14
	s_nop 0
	v_permlane16_swap_b32_e32 v13, v15
	global_store_dwordx4 v[4:5], v[12:15], off offset:128
	v_mul_f32_e32 v4, 0x3c800000, v64
	v_mul_f32_e32 v5, 0x3c800000, v60
	v_add_u32_e32 v6, 0xa0, v6
	v_mul_f32_e32 v4, 0xbfb8aa3b, v4
	v_mul_f32_e32 v5, 0xbfb8aa3b, v5
	v_mad_i64_i32 v[2:3], s[6:7], v6, s8, v[2:3]
	v_mul_f32_e32 v6, 0x3c800000, v65
	v_mul_f32_e32 v7, 0x3c800000, v61
	v_exp_f32_e32 v4, v4
	v_exp_f32_e32 v5, v5
	v_mul_f32_e32 v6, 0xbfb8aa3b, v6
	v_mul_f32_e32 v7, 0xbfb8aa3b, v7
	v_mul_f32_e32 v8, 0x3c800000, v66
	v_mul_f32_e32 v9, 0x3c800000, v62
	v_exp_f32_e32 v6, v6
	v_exp_f32_e32 v7, v7
	v_mul_f32_e32 v8, 0xbfb8aa3b, v8
	v_mul_f32_e32 v9, 0xbfb8aa3b, v9
	v_mul_f32_e32 v11, 0x3c800000, v67
	v_mul_f32_e32 v12, 0x3c800000, v63
	v_exp_f32_e32 v8, v8
	v_exp_f32_e32 v9, v9
	v_mul_f32_e32 v11, 0xbfb8aa3b, v11
	v_mul_f32_e32 v12, 0xbfb8aa3b, v12
	v_exp_f32_e32 v11, v11
	v_exp_f32_e32 v12, v12
	v_add_f32_e32 v4, 1.0, v4
	v_add_f32_e32 v5, 1.0, v5
	v_rcp_f32_e32 v4, v4
	v_rcp_f32_e32 v5, v5
	v_add_f32_e32 v6, 1.0, v6
	v_add_f32_e32 v7, 1.0, v7
	v_rcp_f32_e32 v6, v6
	v_rcp_f32_e32 v7, v7
	v_add_f32_e32 v8, 1.0, v8
	v_add_f32_e32 v9, 1.0, v9
	v_rcp_f32_e32 v8, v8
	v_rcp_f32_e32 v9, v9
	v_add_f32_e32 v11, 1.0, v11
	v_add_f32_e32 v12, 1.0, v12
	v_rcp_f32_e32 v11, v11
	v_rcp_f32_e32 v12, v12
	v_fma_f32 v4, v4, s9, 0.5
	v_fma_f32 v5, v5, s9, 0.5
	v_max_f32_e32 v4, 1.0, v4
	v_max_f32_e32 v5, 1.0, v5
	v_fma_f32 v6, v6, s9, 0.5
	v_fma_f32 v7, v7, s9, 0.5
	v_max_f32_e32 v6, 1.0, v6
	v_max_f32_e32 v7, 1.0, v7
	v_fma_f32 v8, v8, s9, 0.5
	v_fma_f32 v9, v9, s9, 0.5
	v_cvt_pk_u8_f32 v4, v4, 0, 0
	v_cvt_pk_u8_f32 v5, v5, 0, 0
	v_max_f32_e32 v8, 1.0, v8
	v_max_f32_e32 v9, 1.0, v9
	v_fma_f32 v11, v11, s9, 0.5
	v_fma_f32 v12, v12, s9, 0.5
	v_cvt_pk_u8_f32 v4, v6, 1, v4
	v_cvt_pk_u8_f32 v5, v7, 1, v5
	v_max_f32_e32 v11, 1.0, v11
	v_max_f32_e32 v12, 1.0, v12
	v_cvt_pk_u8_f32 v4, v8, 2, v4
	v_cvt_pk_u8_f32 v5, v9, 2, v5
	v_cvt_pk_u8_f32 v4, v11, 3, v4
	v_cvt_pk_u8_f32 v5, v12, 3, v5
	v_mul_f32_e32 v6, 0x3c800000, v48
	v_mul_f32_e32 v7, 0x3c800000, v44
	v_mul_f32_e32 v6, 0xbfb8aa3b, v6
	v_mul_f32_e32 v7, 0xbfb8aa3b, v7
	v_mul_f32_e32 v8, 0x3c800000, v49
	v_mul_f32_e32 v9, 0x3c800000, v45
	v_exp_f32_e32 v6, v6
	v_exp_f32_e32 v7, v7
	v_mul_f32_e32 v8, 0xbfb8aa3b, v8
	v_mul_f32_e32 v9, 0xbfb8aa3b, v9
	v_mul_f32_e32 v11, 0x3c800000, v50
	v_mul_f32_e32 v12, 0x3c800000, v46
	v_exp_f32_e32 v8, v8
	v_exp_f32_e32 v9, v9
	v_mul_f32_e32 v11, 0xbfb8aa3b, v11
	v_mul_f32_e32 v12, 0xbfb8aa3b, v12
	v_mul_f32_e32 v13, 0x3c800000, v51
	v_mul_f32_e32 v14, 0x3c800000, v47
	v_exp_f32_e32 v11, v11
	v_exp_f32_e32 v12, v12
	v_mul_f32_e32 v13, 0xbfb8aa3b, v13
	v_mul_f32_e32 v14, 0xbfb8aa3b, v14
	v_exp_f32_e32 v13, v13
	v_exp_f32_e32 v14, v14
	v_add_f32_e32 v6, 1.0, v6
	v_add_f32_e32 v7, 1.0, v7
	v_rcp_f32_e32 v6, v6
	v_rcp_f32_e32 v7, v7
	v_add_f32_e32 v8, 1.0, v8
	v_add_f32_e32 v9, 1.0, v9
	v_rcp_f32_e32 v8, v8
	v_rcp_f32_e32 v9, v9
	v_add_f32_e32 v11, 1.0, v11
	v_add_f32_e32 v12, 1.0, v12
	v_rcp_f32_e32 v11, v11
	v_rcp_f32_e32 v12, v12
	v_add_f32_e32 v13, 1.0, v13
	v_add_f32_e32 v14, 1.0, v14
	v_rcp_f32_e32 v13, v13
	v_rcp_f32_e32 v14, v14
	v_fma_f32 v6, v6, s9, 0.5
	v_fma_f32 v7, v7, s9, 0.5
	v_max_f32_e32 v6, 1.0, v6
	v_max_f32_e32 v7, 1.0, v7
	v_fma_f32 v8, v8, s9, 0.5
	v_fma_f32 v9, v9, s9, 0.5
	v_max_f32_e32 v8, 1.0, v8
	v_max_f32_e32 v9, 1.0, v9
	v_fma_f32 v11, v11, s9, 0.5
	v_fma_f32 v12, v12, s9, 0.5
	v_cvt_pk_u8_f32 v6, v6, 0, 0
	v_cvt_pk_u8_f32 v7, v7, 0, 0
	v_max_f32_e32 v11, 1.0, v11
	v_max_f32_e32 v12, 1.0, v12
	v_fma_f32 v13, v13, s9, 0.5
	v_fma_f32 v14, v14, s9, 0.5
	v_cvt_pk_u8_f32 v6, v8, 1, v6
	v_cvt_pk_u8_f32 v7, v9, 1, v7
	v_max_f32_e32 v13, 1.0, v13
	v_max_f32_e32 v14, 1.0, v14
	v_cvt_pk_u8_f32 v6, v11, 2, v6
	v_cvt_pk_u8_f32 v7, v12, 2, v7
	v_cvt_pk_u8_f32 v6, v13, 3, v6
	v_cvt_pk_u8_f32 v7, v14, 3, v7
	v_mul_f32_e32 v8, 0x3c800000, v56
	v_mul_f32_e32 v9, 0x3c800000, v52
	v_mul_f32_e32 v8, 0xbfb8aa3b, v8
	v_mul_f32_e32 v9, 0xbfb8aa3b, v9
	v_exp_f32_e32 v8, v8
	v_exp_f32_e32 v9, v9
	v_permlane16_swap_b32_e32 v4, v6
	v_add_f32_e32 v8, 1.0, v8
	v_add_f32_e32 v9, 1.0, v9
	v_rcp_f32_e32 v8, v8
	v_rcp_f32_e32 v9, v9
	v_permlane16_swap_b32_e32 v5, v7
	global_store_dwordx4 v[2:3], v[4:7], off
	v_mul_f32_e32 v11, 0x3c800000, v59
	v_mul_f32_e32 v12, 0x3c800000, v55
	v_mul_f32_e32 v6, 0x3c800000, v57
	v_mul_f32_e32 v7, 0x3c800000, v53
	v_fma_f32 v4, v8, s9, 0.5
	v_fma_f32 v5, v9, s9, 0.5
	v_mul_f32_e32 v6, 0xbfb8aa3b, v6
	v_mul_f32_e32 v7, 0xbfb8aa3b, v7
	v_mul_f32_e32 v8, 0x3c800000, v58
	v_mul_f32_e32 v9, 0x3c800000, v54
	v_exp_f32_e32 v6, v6
	v_exp_f32_e32 v7, v7
	v_mul_f32_e32 v8, 0xbfb8aa3b, v8
	v_mul_f32_e32 v9, 0xbfb8aa3b, v9
	v_exp_f32_e32 v8, v8
	v_exp_f32_e32 v9, v9
	v_mul_f32_e32 v11, 0xbfb8aa3b, v11
	v_mul_f32_e32 v12, 0xbfb8aa3b, v12
	v_exp_f32_e32 v11, v11
	v_exp_f32_e32 v12, v12
	v_add_f32_e32 v6, 1.0, v6
	v_add_f32_e32 v7, 1.0, v7
	v_rcp_f32_e32 v6, v6
	v_rcp_f32_e32 v7, v7
	v_add_f32_e32 v8, 1.0, v8
	v_add_f32_e32 v9, 1.0, v9
	v_rcp_f32_e32 v8, v8
	v_rcp_f32_e32 v9, v9
	v_add_f32_e32 v11, 1.0, v11
	v_add_f32_e32 v12, 1.0, v12
	v_rcp_f32_e32 v11, v11
	v_rcp_f32_e32 v12, v12
	v_max_f32_e32 v4, 1.0, v4
	v_max_f32_e32 v5, 1.0, v5
	v_fma_f32 v6, v6, s9, 0.5
	v_fma_f32 v7, v7, s9, 0.5
	v_max_f32_e32 v6, 1.0, v6
	v_max_f32_e32 v7, 1.0, v7
	v_fma_f32 v8, v8, s9, 0.5
	v_fma_f32 v9, v9, s9, 0.5
	v_cvt_pk_u8_f32 v4, v4, 0, 0
	v_cvt_pk_u8_f32 v5, v5, 0, 0
	v_max_f32_e32 v8, 1.0, v8
	v_max_f32_e32 v9, 1.0, v9
	v_fma_f32 v11, v11, s9, 0.5
	v_fma_f32 v12, v12, s9, 0.5
	v_cvt_pk_u8_f32 v4, v6, 1, v4
	v_cvt_pk_u8_f32 v5, v7, 1, v5
	v_max_f32_e32 v11, 1.0, v11
	v_max_f32_e32 v12, 1.0, v12
	v_cvt_pk_u8_f32 v4, v8, 2, v4
	v_cvt_pk_u8_f32 v5, v9, 2, v5
	v_cvt_pk_u8_f32 v4, v11, 3, v4
	v_cvt_pk_u8_f32 v5, v12, 3, v5
	v_mul_f32_e32 v6, 0x3c800000, v40
	v_mul_f32_e32 v7, 0x3c800000, v36
	v_mul_f32_e32 v6, 0xbfb8aa3b, v6
	v_mul_f32_e32 v7, 0xbfb8aa3b, v7
	v_mul_f32_e32 v8, 0x3c800000, v41
	v_mul_f32_e32 v9, 0x3c800000, v37
	v_exp_f32_e32 v6, v6
	v_exp_f32_e32 v7, v7
	v_mul_f32_e32 v8, 0xbfb8aa3b, v8
	v_mul_f32_e32 v9, 0xbfb8aa3b, v9
	v_mul_f32_e32 v11, 0x3c800000, v42
	v_mul_f32_e32 v12, 0x3c800000, v38
	v_exp_f32_e32 v8, v8
	v_exp_f32_e32 v9, v9
	v_mul_f32_e32 v11, 0xbfb8aa3b, v11
	v_mul_f32_e32 v12, 0xbfb8aa3b, v12
	v_mul_f32_e32 v13, 0x3c800000, v43
	v_mul_f32_e32 v14, 0x3c800000, v39
	v_exp_f32_e32 v11, v11
	v_exp_f32_e32 v12, v12
	v_mul_f32_e32 v13, 0xbfb8aa3b, v13
	v_mul_f32_e32 v14, 0xbfb8aa3b, v14
	v_exp_f32_e32 v13, v13
	v_exp_f32_e32 v14, v14
	v_add_f32_e32 v6, 1.0, v6
	v_add_f32_e32 v7, 1.0, v7
	v_rcp_f32_e32 v6, v6
	v_rcp_f32_e32 v7, v7
	v_add_f32_e32 v8, 1.0, v8
	v_add_f32_e32 v9, 1.0, v9
	v_rcp_f32_e32 v8, v8
	v_rcp_f32_e32 v9, v9
	v_add_f32_e32 v11, 1.0, v11
	v_add_f32_e32 v12, 1.0, v12
	v_rcp_f32_e32 v11, v11
	v_rcp_f32_e32 v12, v12
	v_add_f32_e32 v13, 1.0, v13
	v_add_f32_e32 v14, 1.0, v14
	v_rcp_f32_e32 v13, v13
	v_rcp_f32_e32 v14, v14
	v_fma_f32 v6, v6, s9, 0.5
	v_fma_f32 v7, v7, s9, 0.5
	v_max_f32_e32 v6, 1.0, v6
	v_max_f32_e32 v7, 1.0, v7
	v_fma_f32 v8, v8, s9, 0.5
	v_fma_f32 v9, v9, s9, 0.5
	v_max_f32_e32 v8, 1.0, v8
	v_max_f32_e32 v9, 1.0, v9
	v_fma_f32 v11, v11, s9, 0.5
	v_fma_f32 v12, v12, s9, 0.5
	v_cvt_pk_u8_f32 v6, v6, 0, 0
	v_cvt_pk_u8_f32 v7, v7, 0, 0
	v_max_f32_e32 v11, 1.0, v11
	v_max_f32_e32 v12, 1.0, v12
	v_fma_f32 v13, v13, s9, 0.5
	v_fma_f32 v14, v14, s9, 0.5
	v_cvt_pk_u8_f32 v6, v8, 1, v6
	v_cvt_pk_u8_f32 v7, v9, 1, v7
	v_max_f32_e32 v13, 1.0, v13
	v_max_f32_e32 v14, 1.0, v14
	v_cvt_pk_u8_f32 v6, v11, 2, v6
	v_cvt_pk_u8_f32 v7, v12, 2, v7
	v_cvt_pk_u8_f32 v6, v13, 3, v6
	v_cvt_pk_u8_f32 v7, v14, 3, v7
	s_nop 0
	v_permlane16_swap_b32_e32 v4, v6
	v_permlane16_swap_b32_e32 v5, v7
	global_store_dwordx4 v[2:3], v[4:7], off offset:128

.LBB0_222:
	s_andn2_b64 vcc, exec, s[6:7]
	s_cbranch_vccnz .LBB0_224
	v_mul_f32_e32 v3, 0xbfb8aa3b, v160
	v_exp_f32_e32 v3, v3
	v_mul_f32_e32 v6, 0xbfb8aa3b, v156
	v_exp_f32_e32 v6, v6
	v_ashrrev_i32_e32 v11, 31, v10
	v_lshlrev_b64 v[4:5], 12, v[10:11]
	v_lshl_add_u64 v[12:13], s[56:57], 0, v[4:5]
	v_add_f32_e32 v3, 1.0, v3
	v_mul_f32_e32 v5, 0xbfb8aa3b, v161
	v_rcp_f32_e32 v4, v3
	v_add_f32_e32 v3, 1.0, v6
	v_exp_f32_e32 v5, v5
	v_mul_f32_e32 v6, 0xbfb8aa3b, v157
	v_exp_f32_e32 v7, v6
	v_rcp_f32_e32 v6, v3
	v_add_f32_e32 v3, 1.0, v5
	v_rcp_f32_e32 v5, v3
	v_add_f32_e32 v3, 1.0, v7
	v_mul_f32_e32 v7, 0xbfb8aa3b, v162
	v_exp_f32_e32 v8, v7
	v_mul_f32_e32 v7, 0xbfb8aa3b, v158
	v_exp_f32_e32 v9, v7
	v_rcp_f32_e32 v7, v3
	v_add_f32_e32 v3, 1.0, v8
	v_rcp_f32_e32 v8, v3
	v_add_f32_e32 v3, 1.0, v9
	v_mul_f32_e32 v9, 0xbfb8aa3b, v163
	v_exp_f32_e32 v9, v9
	v_mul_f32_e32 v11, 0xbfb8aa3b, v159
	v_exp_f32_e32 v11, v11
	v_rcp_f32_e32 v14, v3
	v_add_f32_e32 v3, 1.0, v9
	v_rcp_f32_e32 v9, v3
	v_add_f32_e32 v3, 1.0, v11
	v_rcp_f32_e32 v15, v3
	v_or_b32_e32 v2, 0xffffc000, v195
	v_lshl_add_u32 v2, s74, 8, v2
	v_pk_mul_f32 v[4:5], v[160:161], v[4:5]
	v_mov_b32_e32 v3, v34
	v_mul_f32_e32 v11, 0xbfb8aa3b, v152
	v_pk_mul_f32 v[16:17], v[156:157], v[6:7]
	v_pk_mul_f32 v[8:9], v[162:163], v[8:9]
	v_pk_mul_f32 v[14:15], v[158:159], v[14:15]
	v_cvt_pk_bf16_f32 v6, v4, v5
	v_lshlrev_b64 v[4:5], 1, v[2:3]
	v_exp_f32_e32 v11, v11
	v_cvt_pk_bf16_f32 v7, v8, v9
	v_cvt_pk_bf16_f32 v8, v16, v17
	v_cvt_pk_bf16_f32 v9, v14, v15
	v_lshl_add_u64 v[2:3], v[12:13], 0, v[4:5]
	v_mul_f32_e32 v12, 0xbfb8aa3b, v148
	global_store_dwordx4 v[2:3], v[6:9], off
	v_exp_f32_e32 v12, v12
	v_mul_f32_e32 v14, 0xbfb8aa3b, v151
	v_mul_f32_e32 v8, 0xbfb8aa3b, v153
	v_exp_f32_e32 v9, v8
	v_mul_f32_e32 v8, 0xbfb8aa3b, v149
	v_add_f32_e32 v6, 1.0, v11
	v_exp_f32_e32 v11, v8
	v_add_f32_e32 v7, 1.0, v12
	v_rcp_f32_e32 v8, v7
	v_add_f32_e32 v7, 1.0, v9
	v_add_f32_e32 v9, 1.0, v11
	v_mul_f32_e32 v11, 0xbfb8aa3b, v154
	v_exp_f32_e32 v11, v11
	v_mul_f32_e32 v12, 0xbfb8aa3b, v150
	v_exp_f32_e32 v13, v12
	v_exp_f32_e32 v15, v14
	v_add_f32_e32 v11, 1.0, v11
	v_rcp_f32_e32 v12, v11
	v_add_f32_e32 v11, 1.0, v13
	v_mul_f32_e32 v13, 0xbfb8aa3b, v155
	v_exp_f32_e32 v13, v13
	v_rcp_f32_e32 v14, v11
	v_rcp_f32_e32 v6, v6
	v_rcp_f32_e32 v7, v7
	v_add_f32_e32 v11, 1.0, v13
	v_rcp_f32_e32 v13, v11
	v_add_f32_e32 v11, 1.0, v15
	v_rcp_f32_e32 v9, v9
	v_rcp_f32_e32 v15, v11
	v_pk_mul_f32 v[6:7], v[152:153], v[6:7]
	v_pk_mul_f32 v[12:13], v[154:155], v[12:13]
	v_pk_mul_f32 v[8:9], v[148:149], v[8:9]
	v_pk_mul_f32 v[14:15], v[150:151], v[14:15]
	v_cvt_pk_bf16_f32 v6, v6, v7
	v_cvt_pk_bf16_f32 v7, v12, v13
	v_cvt_pk_bf16_f32 v8, v8, v9
	v_cvt_pk_bf16_f32 v9, v14, v15
	global_store_dwordx4 v[2:3], v[6:9], off offset:256
	v_mul_f32_e32 v14, 0xbfb8aa3b, v142
	v_exp_f32_e32 v15, v14
	v_mul_f32_e32 v8, 0xbfb8aa3b, v144
	v_exp_f32_e32 v8, v8
	v_mul_f32_e32 v9, 0xbfb8aa3b, v140
	v_or_b32_e32 v6, 16, v10
	v_exp_f32_e32 v9, v9
	v_ashrrev_i32_e32 v7, 31, v6
	v_lshlrev_b64 v[6:7], 12, v[6:7]
	v_lshl_add_u64 v[12:13], s[56:57], 0, v[6:7]
	v_add_f32_e32 v6, 1.0, v8
	v_mul_f32_e32 v8, 0xbfb8aa3b, v145
	v_add_f32_e32 v7, 1.0, v9
	v_exp_f32_e32 v9, v8
	v_mul_f32_e32 v8, 0xbfb8aa3b, v141
	v_exp_f32_e32 v11, v8
	v_rcp_f32_e32 v8, v7
	v_add_f32_e32 v7, 1.0, v9
	v_mul_f32_e32 v16, 0xbfb8aa3b, v143
	v_add_f32_e32 v9, 1.0, v11
	v_mul_f32_e32 v11, 0xbfb8aa3b, v146
	v_exp_f32_e32 v11, v11
	v_exp_f32_e32 v17, v16
	v_rcp_f32_e32 v6, v6
	v_rcp_f32_e32 v7, v7
	v_add_f32_e32 v11, 1.0, v11
	v_rcp_f32_e32 v14, v11
	v_add_f32_e32 v11, 1.0, v15
	v_mul_f32_e32 v15, 0xbfb8aa3b, v147
	v_exp_f32_e32 v15, v15
	v_rcp_f32_e32 v16, v11
	v_rcp_f32_e32 v9, v9
	v_pk_mul_f32 v[6:7], v[144:145], v[6:7]
	v_add_f32_e32 v11, 1.0, v15
	v_rcp_f32_e32 v15, v11
	v_add_f32_e32 v11, 1.0, v17
	v_rcp_f32_e32 v17, v11
	v_mul_f32_e32 v11, 0xbfb8aa3b, v136
	v_pk_mul_f32 v[8:9], v[140:141], v[8:9]
	v_pk_mul_f32 v[14:15], v[146:147], v[14:15]
	v_pk_mul_f32 v[16:17], v[142:143], v[16:17]
	v_exp_f32_e32 v11, v11
	v_cvt_pk_bf16_f32 v6, v6, v7
	v_cvt_pk_bf16_f32 v7, v14, v15
	v_cvt_pk_bf16_f32 v8, v8, v9
	v_cvt_pk_bf16_f32 v9, v16, v17
	v_lshl_add_u64 v[12:13], v[12:13], 0, v[4:5]
	v_mul_f32_e32 v14, 0xbfb8aa3b, v132
	global_store_dwordx4 v[12:13], v[6:9], off
	v_exp_f32_e32 v14, v14
	v_mul_f32_e32 v16, 0xbfb8aa3b, v135
	v_mul_f32_e32 v8, 0xbfb8aa3b, v137
	v_exp_f32_e32 v9, v8
	v_mul_f32_e32 v8, 0xbfb8aa3b, v133
	v_add_f32_e32 v6, 1.0, v11
	v_exp_f32_e32 v11, v8
	v_add_f32_e32 v7, 1.0, v14
	v_rcp_f32_e32 v8, v7
	v_add_f32_e32 v7, 1.0, v9
	v_add_f32_e32 v9, 1.0, v11
	v_mul_f32_e32 v11, 0xbfb8aa3b, v138
	v_exp_f32_e32 v11, v11
	v_mul_f32_e32 v14, 0xbfb8aa3b, v134
	v_exp_f32_e32 v15, v14
	v_exp_f32_e32 v17, v16
	v_add_f32_e32 v11, 1.0, v11
	v_rcp_f32_e32 v14, v11
	v_add_f32_e32 v11, 1.0, v15
	v_mul_f32_e32 v15, 0xbfb8aa3b, v139
	v_exp_f32_e32 v15, v15
	v_rcp_f32_e32 v16, v11
	v_rcp_f32_e32 v6, v6
	v_rcp_f32_e32 v7, v7
	v_add_f32_e32 v11, 1.0, v15
	v_rcp_f32_e32 v15, v11
	v_add_f32_e32 v11, 1.0, v17
	v_rcp_f32_e32 v9, v9
	v_rcp_f32_e32 v17, v11
	v_pk_mul_f32 v[6:7], v[136:137], v[6:7]
	v_pk_mul_f32 v[14:15], v[138:139], v[14:15]
	v_pk_mul_f32 v[8:9], v[132:133], v[8:9]
	v_pk_mul_f32 v[16:17], v[134:135], v[16:17]
	v_cvt_pk_bf16_f32 v6, v6, v7
	v_cvt_pk_bf16_f32 v7, v14, v15
	v_cvt_pk_bf16_f32 v8, v8, v9
	v_cvt_pk_bf16_f32 v9, v16, v17
	global_store_dwordx4 v[12:13], v[6:9], off offset:256
	v_mul_f32_e32 v14, 0xbfb8aa3b, v126
	v_exp_f32_e32 v15, v14
	v_mul_f32_e32 v8, 0xbfb8aa3b, v128
	v_exp_f32_e32 v8, v8
	v_mul_f32_e32 v9, 0xbfb8aa3b, v124
	v_or_b32_e32 v6, 32, v10
	v_exp_f32_e32 v9, v9
	v_ashrrev_i32_e32 v7, 31, v6
	v_lshlrev_b64 v[6:7], 12, v[6:7]
	v_lshl_add_u64 v[12:13], s[56:57], 0, v[6:7]
	v_add_f32_e32 v6, 1.0, v8
	v_mul_f32_e32 v8, 0xbfb8aa3b, v129
	v_add_f32_e32 v7, 1.0, v9
	v_exp_f32_e32 v9, v8
	v_mul_f32_e32 v8, 0xbfb8aa3b, v125
	v_exp_f32_e32 v11, v8
	v_rcp_f32_e32 v8, v7
	v_add_f32_e32 v7, 1.0, v9
	v_mul_f32_e32 v16, 0xbfb8aa3b, v127
	v_add_f32_e32 v9, 1.0, v11
	v_mul_f32_e32 v11, 0xbfb8aa3b, v130
	v_exp_f32_e32 v11, v11
	v_exp_f32_e32 v17, v16
	v_rcp_f32_e32 v6, v6
	v_rcp_f32_e32 v7, v7
	v_add_f32_e32 v11, 1.0, v11
	v_rcp_f32_e32 v14, v11
	v_add_f32_e32 v11, 1.0, v15
	v_mul_f32_e32 v15, 0xbfb8aa3b, v131
	v_exp_f32_e32 v15, v15
	v_rcp_f32_e32 v16, v11
	v_rcp_f32_e32 v9, v9
	v_pk_mul_f32 v[6:7], v[128:129], v[6:7]
	v_add_f32_e32 v11, 1.0, v15
	v_rcp_f32_e32 v15, v11
	v_add_f32_e32 v11, 1.0, v17
	v_rcp_f32_e32 v17, v11
	v_mul_f32_e32 v11, 0xbfb8aa3b, v120
	v_pk_mul_f32 v[8:9], v[124:125], v[8:9]
	v_pk_mul_f32 v[14:15], v[130:131], v[14:15]
	v_pk_mul_f32 v[16:17], v[126:127], v[16:17]
	v_exp_f32_e32 v11, v11
	v_cvt_pk_bf16_f32 v6, v6, v7
	v_cvt_pk_bf16_f32 v7, v14, v15
	v_cvt_pk_bf16_f32 v8, v8, v9
	v_cvt_pk_bf16_f32 v9, v16, v17
	v_lshl_add_u64 v[12:13], v[12:13], 0, v[4:5]
	v_mul_f32_e32 v14, 0xbfb8aa3b, v116
	global_store_dwordx4 v[12:13], v[6:9], off
	v_exp_f32_e32 v14, v14
	v_mul_f32_e32 v16, 0xbfb8aa3b, v119
	v_mul_f32_e32 v8, 0xbfb8aa3b, v121
	v_exp_f32_e32 v9, v8
	v_mul_f32_e32 v8, 0xbfb8aa3b, v117
	v_add_f32_e32 v6, 1.0, v11
	v_exp_f32_e32 v11, v8
	v_add_f32_e32 v7, 1.0, v14
	v_rcp_f32_e32 v8, v7
	v_add_f32_e32 v7, 1.0, v9
	v_add_f32_e32 v9, 1.0, v11
	v_mul_f32_e32 v11, 0xbfb8aa3b, v122
	v_exp_f32_e32 v11, v11
	v_mul_f32_e32 v14, 0xbfb8aa3b, v118
	v_exp_f32_e32 v15, v14
	v_exp_f32_e32 v17, v16
	v_add_f32_e32 v11, 1.0, v11
	v_rcp_f32_e32 v14, v11
	v_add_f32_e32 v11, 1.0, v15
	v_mul_f32_e32 v15, 0xbfb8aa3b, v123
	v_exp_f32_e32 v15, v15
	v_rcp_f32_e32 v16, v11
	v_rcp_f32_e32 v6, v6
	v_rcp_f32_e32 v7, v7
	v_add_f32_e32 v11, 1.0, v15
	v_rcp_f32_e32 v15, v11
	v_add_f32_e32 v11, 1.0, v17
	v_rcp_f32_e32 v9, v9
	v_rcp_f32_e32 v17, v11
	v_pk_mul_f32 v[6:7], v[120:121], v[6:7]
	v_pk_mul_f32 v[14:15], v[122:123], v[14:15]
	v_pk_mul_f32 v[8:9], v[116:117], v[8:9]
	v_pk_mul_f32 v[16:17], v[118:119], v[16:17]
	v_cvt_pk_bf16_f32 v6, v6, v7
	v_cvt_pk_bf16_f32 v7, v14, v15
	v_cvt_pk_bf16_f32 v8, v8, v9
	v_cvt_pk_bf16_f32 v9, v16, v17
	global_store_dwordx4 v[12:13], v[6:9], off offset:256
	v_mul_f32_e32 v14, 0xbfb8aa3b, v110
	v_exp_f32_e32 v15, v14
	v_mul_f32_e32 v8, 0xbfb8aa3b, v112
	v_exp_f32_e32 v8, v8
	v_mul_f32_e32 v9, 0xbfb8aa3b, v108
	v_or_b32_e32 v6, 48, v10
	v_exp_f32_e32 v9, v9
	v_ashrrev_i32_e32 v7, 31, v6
	v_lshlrev_b64 v[6:7], 12, v[6:7]
	v_lshl_add_u64 v[12:13], s[56:57], 0, v[6:7]
	v_add_f32_e32 v6, 1.0, v8
	v_mul_f32_e32 v8, 0xbfb8aa3b, v113
	v_add_f32_e32 v7, 1.0, v9
	v_exp_f32_e32 v9, v8
	v_mul_f32_e32 v8, 0xbfb8aa3b, v109
	v_exp_f32_e32 v11, v8
	v_rcp_f32_e32 v8, v7
	v_add_f32_e32 v7, 1.0, v9
	v_mul_f32_e32 v16, 0xbfb8aa3b, v111
	v_add_f32_e32 v9, 1.0, v11
	v_mul_f32_e32 v11, 0xbfb8aa3b, v114
	v_exp_f32_e32 v11, v11
	v_exp_f32_e32 v17, v16
	v_rcp_f32_e32 v6, v6
	v_rcp_f32_e32 v7, v7
	v_add_f32_e32 v11, 1.0, v11
	v_rcp_f32_e32 v14, v11
	v_add_f32_e32 v11, 1.0, v15
	v_mul_f32_e32 v15, 0xbfb8aa3b, v115
	v_exp_f32_e32 v15, v15
	v_rcp_f32_e32 v16, v11
	v_rcp_f32_e32 v9, v9
	v_pk_mul_f32 v[6:7], v[112:113], v[6:7]
	v_add_f32_e32 v11, 1.0, v15
	v_rcp_f32_e32 v15, v11
	v_add_f32_e32 v11, 1.0, v17
	v_rcp_f32_e32 v17, v11
	v_pk_mul_f32 v[8:9], v[108:109], v[8:9]
	v_pk_mul_f32 v[14:15], v[114:115], v[14:15]
	v_cvt_pk_bf16_f32 v6, v6, v7
	v_pk_mul_f32 v[16:17], v[110:111], v[16:17]
	v_cvt_pk_bf16_f32 v7, v14, v15
	v_cvt_pk_bf16_f32 v8, v8, v9
	v_cvt_pk_bf16_f32 v9, v16, v17
	v_lshl_add_u64 v[12:13], v[12:13], 0, v[4:5]
	v_mul_f32_e32 v5, 0xbfb8aa3b, v100
	global_store_dwordx4 v[12:13], v[6:9], off
	v_exp_f32_e32 v5, v5
	v_mul_f32_e32 v4, 0xbfb8aa3b, v104
	v_mul_f32_e32 v6, 0xbfb8aa3b, v105
	v_exp_f32_e32 v7, v6
	v_mul_f32_e32 v6, 0xbfb8aa3b, v101
	v_exp_f32_e32 v8, v6
	v_add_f32_e32 v5, 1.0, v5
	v_mul_f32_e32 v9, 0xbfb8aa3b, v102
	v_rcp_f32_e32 v6, v5
	v_add_f32_e32 v5, 1.0, v7
	v_add_f32_e32 v7, 1.0, v8
	v_mul_f32_e32 v8, 0xbfb8aa3b, v106
	v_exp_f32_e32 v9, v9
	v_mul_f32_e32 v11, 0xbfb8aa3b, v107
	v_exp_f32_e32 v4, v4
	v_exp_f32_e32 v8, v8
	v_exp_f32_e32 v11, v11
	v_mul_f32_e32 v14, 0xbfb8aa3b, v103
	v_exp_f32_e32 v15, v14
	v_add_f32_e32 v9, 1.0, v9
	v_add_f32_e32 v4, 1.0, v4
	v_add_f32_e32 v8, 1.0, v8
	v_rcp_f32_e32 v14, v9
	v_add_f32_e32 v9, 1.0, v11
	v_rcp_f32_e32 v4, v4
	v_rcp_f32_e32 v5, v5
	v_rcp_f32_e32 v8, v8
	v_rcp_f32_e32 v9, v9
	v_add_f32_e32 v11, 1.0, v15
	v_rcp_f32_e32 v7, v7
	v_rcp_f32_e32 v15, v11
	v_pk_mul_f32 v[4:5], v[104:105], v[4:5]
	v_pk_mul_f32 v[8:9], v[106:107], v[8:9]
	v_cvt_pk_bf16_f32 v4, v4, v5
	v_cvt_pk_bf16_f32 v5, v8, v9
	v_mul_f32_e32 v8, 0xbfb8aa3b, v96
	v_pk_mul_f32 v[6:7], v[100:101], v[6:7]
	v_pk_mul_f32 v[14:15], v[102:103], v[14:15]
	v_exp_f32_e32 v8, v8
	v_cvt_pk_bf16_f32 v6, v6, v7
	v_cvt_pk_bf16_f32 v7, v14, v15
	v_mul_f32_e32 v9, 0xbfb8aa3b, v92
	global_store_dwordx4 v[12:13], v[4:7], off offset:256
	v_exp_f32_e32 v9, v9
	v_mul_f32_e32 v11, 0xbfb8aa3b, v99
	v_mul_f32_e32 v6, 0xbfb8aa3b, v97
	v_exp_f32_e32 v7, v6
	v_mul_f32_e32 v6, 0xbfb8aa3b, v93
	v_add_f32_e32 v4, 1.0, v8
	v_exp_f32_e32 v8, v6
	v_add_f32_e32 v5, 1.0, v9
	v_mul_f32_e32 v9, 0xbfb8aa3b, v94
	v_rcp_f32_e32 v6, v5
	v_add_f32_e32 v5, 1.0, v7
	v_add_f32_e32 v7, 1.0, v8
	v_mul_f32_e32 v8, 0xbfb8aa3b, v98
	v_exp_f32_e32 v9, v9
	v_exp_f32_e32 v8, v8
	v_exp_f32_e32 v11, v11
	v_mul_f32_e32 v12, 0xbfb8aa3b, v95
	v_exp_f32_e32 v13, v12
	v_add_f32_e32 v9, 1.0, v9
	v_add_f32_e32 v8, 1.0, v8
	v_rcp_f32_e32 v12, v9
	v_add_f32_e32 v9, 1.0, v11
	v_rcp_f32_e32 v4, v4
	v_rcp_f32_e32 v5, v5
	v_rcp_f32_e32 v8, v8
	v_rcp_f32_e32 v9, v9
	v_add_f32_e32 v11, 1.0, v13
	v_rcp_f32_e32 v7, v7
	v_rcp_f32_e32 v13, v11
	v_pk_mul_f32 v[4:5], v[96:97], v[4:5]
	v_pk_mul_f32 v[8:9], v[98:99], v[8:9]
	s_mov_b64 s[6:7], 0x80000
	v_pk_mul_f32 v[6:7], v[92:93], v[6:7]
	v_pk_mul_f32 v[12:13], v[94:95], v[12:13]
	v_cvt_pk_bf16_f32 v4, v4, v5
	v_cvt_pk_bf16_f32 v5, v8, v9
	v_lshl_add_u64 v[8:9], v[2:3], 0, s[6:7]
	s_mov_b32 s6, 0x80000
	v_mul_f32_e32 v11, 0xbfb8aa3b, v88
	v_cvt_pk_bf16_f32 v6, v6, v7
	v_cvt_pk_bf16_f32 v7, v12, v13
	v_add_co_u32_e32 v12, vcc, s6, v2
	v_exp_f32_e32 v11, v11
	s_nop 0
	v_addc_co_u32_e32 v13, vcc, 0, v3, vcc
	v_mul_f32_e32 v14, 0xbfb8aa3b, v84
	global_store_dwordx4 v[12:13], v[4:7], off
	v_exp_f32_e32 v14, v14
	v_mul_f32_e32 v12, 0xbfb8aa3b, v86
	v_mul_f32_e32 v6, 0xbfb8aa3b, v89
	v_exp_f32_e32 v7, v6
	v_mul_f32_e32 v6, 0xbfb8aa3b, v85
	v_add_f32_e32 v4, 1.0, v11
	v_exp_f32_e32 v11, v6
	v_add_f32_e32 v5, 1.0, v14
	v_rcp_f32_e32 v6, v5
	v_add_f32_e32 v5, 1.0, v7
	v_add_f32_e32 v7, 1.0, v11
	v_mul_f32_e32 v11, 0xbfb8aa3b, v90
	v_exp_f32_e32 v11, v11
	v_exp_f32_e32 v13, v12
	v_mul_f32_e32 v14, 0xbfb8aa3b, v87
	v_exp_f32_e32 v15, v14
	v_add_f32_e32 v11, 1.0, v11
	v_rcp_f32_e32 v12, v11
	v_add_f32_e32 v11, 1.0, v13
	v_mul_f32_e32 v13, 0xbfb8aa3b, v91
	v_exp_f32_e32 v13, v13
	v_rcp_f32_e32 v14, v11
	v_rcp_f32_e32 v4, v4
	v_rcp_f32_e32 v5, v5
	v_add_f32_e32 v11, 1.0, v13
	v_rcp_f32_e32 v13, v11
	v_add_f32_e32 v11, 1.0, v15
	v_rcp_f32_e32 v7, v7
	v_rcp_f32_e32 v15, v11
	v_pk_mul_f32 v[4:5], v[88:89], v[4:5]
	v_pk_mul_f32 v[12:13], v[90:91], v[12:13]
	v_pk_mul_f32 v[6:7], v[84:85], v[6:7]
	v_pk_mul_f32 v[14:15], v[86:87], v[14:15]
	v_cvt_pk_bf16_f32 v4, v4, v5
	v_cvt_pk_bf16_f32 v5, v12, v13
	v_cvt_pk_bf16_f32 v6, v6, v7
	v_cvt_pk_bf16_f32 v7, v14, v15
	v_mul_f32_e32 v12, 0xbfb8aa3b, v76
	global_store_dwordx4 v[8:9], v[4:7], off offset:256
	v_mul_f32_e32 v11, 0xbfb8aa3b, v80
	v_exp_f32_e32 v12, v12
	v_mul_f32_e32 v6, 0xbfb8aa3b, v81
	v_exp_f32_e32 v7, v6
	v_mul_f32_e32 v6, 0xbfb8aa3b, v77
	v_exp_f32_e32 v11, v11
	v_exp_f32_e32 v8, v6
	v_add_f32_e32 v5, 1.0, v12
	v_mul_f32_e32 v9, 0xbfb8aa3b, v78
	v_add_f32_e32 v4, 1.0, v11
	v_rcp_f32_e32 v6, v5
	v_add_f32_e32 v5, 1.0, v7
	v_add_f32_e32 v7, 1.0, v8
	v_mul_f32_e32 v8, 0xbfb8aa3b, v82
	v_exp_f32_e32 v9, v9
	v_mul_f32_e32 v11, 0xbfb8aa3b, v83
	v_exp_f32_e32 v8, v8
	v_exp_f32_e32 v11, v11
	v_mul_f32_e32 v12, 0xbfb8aa3b, v79
	v_exp_f32_e32 v13, v12
	v_add_f32_e32 v9, 1.0, v9
	v_add_f32_e32 v8, 1.0, v8
	v_rcp_f32_e32 v12, v9
	v_add_f32_e32 v9, 1.0, v11
	v_rcp_f32_e32 v4, v4
	v_rcp_f32_e32 v5, v5
	v_rcp_f32_e32 v8, v8
	v_rcp_f32_e32 v9, v9
	v_add_f32_e32 v11, 1.0, v13
	v_rcp_f32_e32 v7, v7
	v_rcp_f32_e32 v13, v11
	v_pk_mul_f32 v[4:5], v[80:81], v[4:5]
	v_pk_mul_f32 v[8:9], v[82:83], v[8:9]
	s_mov_b64 s[6:7], 0x90000
	v_pk_mul_f32 v[6:7], v[76:77], v[6:7]
	v_pk_mul_f32 v[12:13], v[78:79], v[12:13]
	v_cvt_pk_bf16_f32 v4, v4, v5
	v_cvt_pk_bf16_f32 v5, v8, v9
	v_lshl_add_u64 v[8:9], v[2:3], 0, s[6:7]
	s_mov_b32 s6, 0x90000
	v_mul_f32_e32 v11, 0xbfb8aa3b, v72
	v_cvt_pk_bf16_f32 v6, v6, v7
	v_cvt_pk_bf16_f32 v7, v12, v13
	v_add_co_u32_e32 v12, vcc, s6, v2
	v_exp_f32_e32 v11, v11
	s_nop 0
	v_addc_co_u32_e32 v13, vcc, 0, v3, vcc
	v_mul_f32_e32 v14, 0xbfb8aa3b, v68
	global_store_dwordx4 v[12:13], v[4:7], off
	v_exp_f32_e32 v14, v14
	v_mul_f32_e32 v12, 0xbfb8aa3b, v70
	v_mul_f32_e32 v6, 0xbfb8aa3b, v73
	v_exp_f32_e32 v7, v6
	v_mul_f32_e32 v6, 0xbfb8aa3b, v69
	v_add_f32_e32 v4, 1.0, v11
	v_exp_f32_e32 v11, v6
	v_add_f32_e32 v5, 1.0, v14
	v_rcp_f32_e32 v6, v5
	v_add_f32_e32 v5, 1.0, v7
	v_add_f32_e32 v7, 1.0, v11
	v_mul_f32_e32 v11, 0xbfb8aa3b, v74
	v_exp_f32_e32 v11, v11
	v_exp_f32_e32 v13, v12
	v_mul_f32_e32 v14, 0xbfb8aa3b, v71
	v_exp_f32_e32 v15, v14
	v_add_f32_e32 v11, 1.0, v11
	v_rcp_f32_e32 v12, v11
	v_add_f32_e32 v11, 1.0, v13
	v_mul_f32_e32 v13, 0xbfb8aa3b, v75
	v_exp_f32_e32 v13, v13
	v_rcp_f32_e32 v14, v11
	v_rcp_f32_e32 v4, v4
	v_rcp_f32_e32 v5, v5
	v_add_f32_e32 v11, 1.0, v13
	v_rcp_f32_e32 v13, v11
	v_add_f32_e32 v11, 1.0, v15
	v_rcp_f32_e32 v7, v7
	v_rcp_f32_e32 v15, v11
	v_pk_mul_f32 v[4:5], v[72:73], v[4:5]
	v_pk_mul_f32 v[12:13], v[74:75], v[12:13]
	v_pk_mul_f32 v[6:7], v[68:69], v[6:7]
	v_pk_mul_f32 v[14:15], v[70:71], v[14:15]
	v_cvt_pk_bf16_f32 v4, v4, v5
	v_cvt_pk_bf16_f32 v5, v12, v13
	v_cvt_pk_bf16_f32 v6, v6, v7
	v_cvt_pk_bf16_f32 v7, v14, v15
	v_mul_f32_e32 v12, 0xbfb8aa3b, v60
	global_store_dwordx4 v[8:9], v[4:7], off offset:256
	v_mul_f32_e32 v11, 0xbfb8aa3b, v64
	v_exp_f32_e32 v12, v12
	v_mul_f32_e32 v6, 0xbfb8aa3b, v65
	v_exp_f32_e32 v7, v6
	v_mul_f32_e32 v6, 0xbfb8aa3b, v61
	v_exp_f32_e32 v11, v11
	v_exp_f32_e32 v8, v6
	v_add_f32_e32 v5, 1.0, v12
	v_mul_f32_e32 v9, 0xbfb8aa3b, v62
	v_add_f32_e32 v4, 1.0, v11
	v_rcp_f32_e32 v6, v5
	v_add_f32_e32 v5, 1.0, v7
	v_add_f32_e32 v7, 1.0, v8
	v_mul_f32_e32 v8, 0xbfb8aa3b, v66
	v_exp_f32_e32 v9, v9
	v_mul_f32_e32 v11, 0xbfb8aa3b, v67
	v_exp_f32_e32 v8, v8
	v_exp_f32_e32 v11, v11
	v_mul_f32_e32 v12, 0xbfb8aa3b, v63
	v_exp_f32_e32 v13, v12
	v_add_f32_e32 v9, 1.0, v9
	v_add_f32_e32 v8, 1.0, v8
	v_rcp_f32_e32 v12, v9
	v_add_f32_e32 v9, 1.0, v11
	v_rcp_f32_e32 v4, v4
	v_rcp_f32_e32 v5, v5
	v_rcp_f32_e32 v8, v8
	v_rcp_f32_e32 v9, v9
	v_add_f32_e32 v11, 1.0, v13
	v_rcp_f32_e32 v7, v7
	v_rcp_f32_e32 v13, v11
	v_pk_mul_f32 v[4:5], v[64:65], v[4:5]
	v_pk_mul_f32 v[8:9], v[66:67], v[8:9]
	s_mov_b64 s[6:7], 0xa0000
	v_pk_mul_f32 v[6:7], v[60:61], v[6:7]
	v_pk_mul_f32 v[12:13], v[62:63], v[12:13]
	v_cvt_pk_bf16_f32 v4, v4, v5
	v_cvt_pk_bf16_f32 v5, v8, v9
	v_lshl_add_u64 v[8:9], v[2:3], 0, s[6:7]
	s_mov_b32 s6, 0xa0000
	v_mul_f32_e32 v11, 0xbfb8aa3b, v56
	v_cvt_pk_bf16_f32 v6, v6, v7
	v_cvt_pk_bf16_f32 v7, v12, v13
	v_add_co_u32_e32 v12, vcc, s6, v2
	v_exp_f32_e32 v11, v11
	s_nop 0
	v_addc_co_u32_e32 v13, vcc, 0, v3, vcc
	v_mul_f32_e32 v14, 0xbfb8aa3b, v52
	global_store_dwordx4 v[12:13], v[4:7], off
	v_exp_f32_e32 v14, v14
	v_mul_f32_e32 v12, 0xbfb8aa3b, v54
	v_mul_f32_e32 v6, 0xbfb8aa3b, v57
	v_exp_f32_e32 v7, v6
	v_mul_f32_e32 v6, 0xbfb8aa3b, v53
	v_add_f32_e32 v4, 1.0, v11
	v_exp_f32_e32 v11, v6
	v_add_f32_e32 v5, 1.0, v14
	v_rcp_f32_e32 v6, v5
	v_add_f32_e32 v5, 1.0, v7
	v_add_f32_e32 v7, 1.0, v11
	v_mul_f32_e32 v11, 0xbfb8aa3b, v58
	v_exp_f32_e32 v11, v11
	v_exp_f32_e32 v13, v12
	v_mul_f32_e32 v14, 0xbfb8aa3b, v55
	v_exp_f32_e32 v15, v14
	v_add_f32_e32 v11, 1.0, v11
	v_rcp_f32_e32 v12, v11
	v_add_f32_e32 v11, 1.0, v13
	v_mul_f32_e32 v13, 0xbfb8aa3b, v59
	v_exp_f32_e32 v13, v13
	v_rcp_f32_e32 v14, v11
	v_rcp_f32_e32 v4, v4
	v_rcp_f32_e32 v5, v5
	v_add_f32_e32 v11, 1.0, v13
	v_rcp_f32_e32 v13, v11
	v_add_f32_e32 v11, 1.0, v15
	v_rcp_f32_e32 v7, v7
	v_rcp_f32_e32 v15, v11
	v_pk_mul_f32 v[4:5], v[56:57], v[4:5]
	v_pk_mul_f32 v[12:13], v[58:59], v[12:13]
	v_pk_mul_f32 v[6:7], v[52:53], v[6:7]
	v_pk_mul_f32 v[14:15], v[54:55], v[14:15]
	v_cvt_pk_bf16_f32 v4, v4, v5
	v_cvt_pk_bf16_f32 v5, v12, v13
	v_cvt_pk_bf16_f32 v6, v6, v7
	v_cvt_pk_bf16_f32 v7, v14, v15
	v_mul_f32_e32 v12, 0xbfb8aa3b, v44
	global_store_dwordx4 v[8:9], v[4:7], off offset:256
	v_mul_f32_e32 v11, 0xbfb8aa3b, v48
	v_exp_f32_e32 v12, v12
	v_mul_f32_e32 v6, 0xbfb8aa3b, v49
	v_exp_f32_e32 v7, v6
	v_mul_f32_e32 v6, 0xbfb8aa3b, v45
	v_exp_f32_e32 v11, v11
	v_exp_f32_e32 v8, v6
	v_add_f32_e32 v5, 1.0, v12
	v_mul_f32_e32 v9, 0xbfb8aa3b, v46
	v_add_f32_e32 v4, 1.0, v11
	v_rcp_f32_e32 v6, v5
	v_add_f32_e32 v5, 1.0, v7
	v_add_f32_e32 v7, 1.0, v8
	v_mul_f32_e32 v8, 0xbfb8aa3b, v50
	v_exp_f32_e32 v9, v9
	v_mul_f32_e32 v11, 0xbfb8aa3b, v51
	v_exp_f32_e32 v8, v8
	v_exp_f32_e32 v11, v11
	v_mul_f32_e32 v12, 0xbfb8aa3b, v47
	v_exp_f32_e32 v13, v12
	v_add_f32_e32 v9, 1.0, v9
	v_add_f32_e32 v8, 1.0, v8
	v_rcp_f32_e32 v12, v9
	v_add_f32_e32 v9, 1.0, v11
	v_rcp_f32_e32 v4, v4
	v_rcp_f32_e32 v5, v5
	v_rcp_f32_e32 v8, v8
	v_rcp_f32_e32 v9, v9
	v_add_f32_e32 v11, 1.0, v13
	v_rcp_f32_e32 v7, v7
	v_rcp_f32_e32 v13, v11
	v_pk_mul_f32 v[4:5], v[48:49], v[4:5]
	v_pk_mul_f32 v[8:9], v[50:51], v[8:9]
	s_mov_b64 s[6:7], 0xb0000
	v_cvt_pk_bf16_f32 v4, v4, v5
	v_cvt_pk_bf16_f32 v5, v8, v9
	v_lshl_add_u64 v[8:9], v[2:3], 0, s[6:7]
	s_mov_b32 s6, 0xb0000
	v_pk_mul_f32 v[6:7], v[44:45], v[6:7]
	v_pk_mul_f32 v[12:13], v[46:47], v[12:13]
	v_add_co_u32_e32 v2, vcc, s6, v2
	v_cvt_pk_bf16_f32 v6, v6, v7
	v_cvt_pk_bf16_f32 v7, v12, v13
	v_addc_co_u32_e32 v3, vcc, 0, v3, vcc
	v_mul_f32_e32 v12, 0xbfb8aa3b, v36
	global_store_dwordx4 v[2:3], v[4:7], off
	v_mul_f32_e32 v11, 0xbfb8aa3b, v40
	v_exp_f32_e32 v12, v12
	v_mul_f32_e32 v4, 0xbfb8aa3b, v41
	v_exp_f32_e32 v5, v4
	v_mul_f32_e32 v4, 0xbfb8aa3b, v37
	v_exp_f32_e32 v11, v11
	v_exp_f32_e32 v6, v4
	v_add_f32_e32 v3, 1.0, v12
	v_mul_f32_e32 v7, 0xbfb8aa3b, v38
	v_add_f32_e32 v2, 1.0, v11
	v_rcp_f32_e32 v4, v3
	v_add_f32_e32 v3, 1.0, v5
	v_add_f32_e32 v5, 1.0, v6
	v_mul_f32_e32 v6, 0xbfb8aa3b, v42
	v_exp_f32_e32 v7, v7
	v_mul_f32_e32 v11, 0xbfb8aa3b, v43
	v_mul_f32_e32 v12, 0xbfb8aa3b, v39
	v_exp_f32_e32 v6, v6
	v_exp_f32_e32 v11, v11
	v_exp_f32_e32 v13, v12
	v_add_f32_e32 v7, 1.0, v7
	v_add_f32_e32 v6, 1.0, v6
	v_rcp_f32_e32 v12, v7
	v_add_f32_e32 v7, 1.0, v11
	v_add_f32_e32 v11, 1.0, v13
	v_rcp_f32_e32 v2, v2
	v_rcp_f32_e32 v3, v3
	v_rcp_f32_e32 v5, v5
	v_rcp_f32_e32 v6, v6
	v_rcp_f32_e32 v7, v7
	v_rcp_f32_e32 v13, v11
	v_pk_mul_f32 v[2:3], v[40:41], v[2:3]
	v_pk_mul_f32 v[4:5], v[36:37], v[4:5]
	v_pk_mul_f32 v[6:7], v[42:43], v[6:7]
	v_pk_mul_f32 v[12:13], v[38:39], v[12:13]
	v_cvt_pk_bf16_f32 v2, v2, v3
	v_cvt_pk_bf16_f32 v3, v6, v7
	v_cvt_pk_bf16_f32 v4, v4, v5
	v_cvt_pk_bf16_f32 v5, v12, v13
	global_store_dwordx4 v[8:9], v[2:5], off offset:256

.LBB0_225:
	s_andn2_b64 vcc, exec, s[6:7]
	s_cbranch_vccnz .LBB0_227
	v_or_b32_e32 v2, 0xffffc800, v195
	v_ashrrev_i32_e32 v11, 31, v10
	v_lshl_add_u32 v6, s74, 8, v2
	v_lshlrev_b64 v[2:3], 12, v[10:11]
	v_mov_b32_e32 v7, v34
	v_lshl_add_u64 v[8:9], s[54:55], 0, v[2:3]
	v_lshlrev_b64 v[6:7], 1, v[6:7]
	v_cvt_pk_bf16_f32 v2, v160, v161
	v_cvt_pk_bf16_f32 v3, v162, v163
	v_cvt_pk_bf16_f32 v4, v156, v157
	v_cvt_pk_bf16_f32 v5, v158, v159
	v_lshl_add_u64 v[8:9], v[8:9], 0, v[6:7]
	global_store_dwordx4 v[8:9], v[2:5], off
	s_mov_b64 s[6:7], 0x80000
	s_nop 0
	v_cvt_pk_bf16_f32 v2, v152, v153
	v_cvt_pk_bf16_f32 v3, v154, v155
	v_cvt_pk_bf16_f32 v4, v148, v149
	v_cvt_pk_bf16_f32 v5, v150, v151
	global_store_dwordx4 v[8:9], v[2:5], off offset:256
	s_nop 1
	v_or_b32_e32 v2, 16, v10
	v_ashrrev_i32_e32 v3, 31, v2
	v_lshlrev_b64 v[2:3], 12, v[2:3]
	v_lshl_add_u64 v[12:13], s[54:55], 0, v[2:3]
	v_cvt_pk_bf16_f32 v2, v144, v145
	v_cvt_pk_bf16_f32 v3, v146, v147
	v_cvt_pk_bf16_f32 v4, v140, v141
	v_cvt_pk_bf16_f32 v5, v142, v143
	v_lshl_add_u64 v[12:13], v[12:13], 0, v[6:7]
	global_store_dwordx4 v[12:13], v[2:5], off
	s_nop 1
	v_cvt_pk_bf16_f32 v2, v136, v137
	v_cvt_pk_bf16_f32 v3, v138, v139
	v_cvt_pk_bf16_f32 v4, v132, v133
	v_cvt_pk_bf16_f32 v5, v134, v135
	global_store_dwordx4 v[12:13], v[2:5], off offset:256
	s_nop 1
	v_or_b32_e32 v2, 32, v10
	v_ashrrev_i32_e32 v3, 31, v2
	v_lshlrev_b64 v[2:3], 12, v[2:3]
	v_lshl_add_u64 v[12:13], s[54:55], 0, v[2:3]
	v_cvt_pk_bf16_f32 v2, v128, v129
	v_cvt_pk_bf16_f32 v3, v130, v131
	v_cvt_pk_bf16_f32 v4, v124, v125
	v_cvt_pk_bf16_f32 v5, v126, v127
	v_lshl_add_u64 v[12:13], v[12:13], 0, v[6:7]
	global_store_dwordx4 v[12:13], v[2:5], off
	s_nop 1
	v_cvt_pk_bf16_f32 v2, v120, v121
	v_cvt_pk_bf16_f32 v3, v122, v123
	v_cvt_pk_bf16_f32 v4, v116, v117
	v_cvt_pk_bf16_f32 v5, v118, v119
	global_store_dwordx4 v[12:13], v[2:5], off offset:256
	s_nop 1
	v_or_b32_e32 v2, 48, v10
	v_ashrrev_i32_e32 v3, 31, v2
	v_lshlrev_b64 v[2:3], 12, v[2:3]
	v_lshl_add_u64 v[12:13], s[54:55], 0, v[2:3]
	v_cvt_pk_bf16_f32 v2, v112, v113
	v_cvt_pk_bf16_f32 v3, v114, v115
	v_cvt_pk_bf16_f32 v4, v108, v109
	v_cvt_pk_bf16_f32 v5, v110, v111
	v_lshl_add_u64 v[6:7], v[12:13], 0, v[6:7]
	global_store_dwordx4 v[6:7], v[2:5], off
	s_nop 1
	v_cvt_pk_bf16_f32 v2, v104, v105
	v_cvt_pk_bf16_f32 v3, v106, v107
	v_cvt_pk_bf16_f32 v4, v100, v101
	v_cvt_pk_bf16_f32 v5, v102, v103
	global_store_dwordx4 v[6:7], v[2:5], off offset:256
	v_lshl_add_u64 v[6:7], v[8:9], 0, s[6:7]
	s_mov_b32 s6, 0x80000
	v_add_co_u32_e32 v12, vcc, s6, v8
	v_cvt_pk_bf16_f32 v2, v96, v97
	v_cvt_pk_bf16_f32 v3, v98, v99
	v_cvt_pk_bf16_f32 v4, v92, v93
	v_cvt_pk_bf16_f32 v5, v94, v95
	v_addc_co_u32_e32 v13, vcc, 0, v9, vcc
	global_store_dwordx4 v[12:13], v[2:5], off
	s_mov_b64 s[6:7], 0x90000
	s_nop 0
	v_cvt_pk_bf16_f32 v2, v88, v89
	v_cvt_pk_bf16_f32 v3, v90, v91
	v_cvt_pk_bf16_f32 v4, v84, v85
	v_cvt_pk_bf16_f32 v5, v86, v87
	global_store_dwordx4 v[6:7], v[2:5], off offset:256
	v_lshl_add_u64 v[6:7], v[8:9], 0, s[6:7]
	s_mov_b32 s6, 0x90000
	v_add_co_u32_e32 v12, vcc, s6, v8
	v_cvt_pk_bf16_f32 v2, v80, v81
	v_cvt_pk_bf16_f32 v3, v82, v83
	v_cvt_pk_bf16_f32 v4, v76, v77
	v_cvt_pk_bf16_f32 v5, v78, v79
	v_addc_co_u32_e32 v13, vcc, 0, v9, vcc
	global_store_dwordx4 v[12:13], v[2:5], off
	s_mov_b64 s[6:7], 0xa0000
	s_nop 0
	v_cvt_pk_bf16_f32 v2, v72, v73
	v_cvt_pk_bf16_f32 v3, v74, v75
	v_cvt_pk_bf16_f32 v4, v68, v69
	v_cvt_pk_bf16_f32 v5, v70, v71
	global_store_dwordx4 v[6:7], v[2:5], off offset:256
	v_lshl_add_u64 v[6:7], v[8:9], 0, s[6:7]
	s_mov_b32 s6, 0xa0000
	v_add_co_u32_e32 v12, vcc, s6, v8
	v_cvt_pk_bf16_f32 v2, v64, v65
	v_cvt_pk_bf16_f32 v3, v66, v67
	v_cvt_pk_bf16_f32 v4, v60, v61
	v_cvt_pk_bf16_f32 v5, v62, v63
	v_addc_co_u32_e32 v13, vcc, 0, v9, vcc
	global_store_dwordx4 v[12:13], v[2:5], off
	s_mov_b64 s[6:7], 0xb0000
	s_nop 0
	v_cvt_pk_bf16_f32 v2, v56, v57
	v_cvt_pk_bf16_f32 v3, v58, v59
	v_cvt_pk_bf16_f32 v4, v52, v53
	v_cvt_pk_bf16_f32 v5, v54, v55
	global_store_dwordx4 v[6:7], v[2:5], off offset:256
	v_lshl_add_u64 v[6:7], v[8:9], 0, s[6:7]
	s_mov_b32 s6, 0xb0000
	v_add_co_u32_e32 v8, vcc, s6, v8
	v_cvt_pk_bf16_f32 v2, v48, v49
	v_cvt_pk_bf16_f32 v3, v50, v51
	v_cvt_pk_bf16_f32 v4, v44, v45
	v_cvt_pk_bf16_f32 v5, v46, v47
	v_addc_co_u32_e32 v9, vcc, 0, v9, vcc
	global_store_dwordx4 v[8:9], v[2:5], off
	s_nop 1
	v_cvt_pk_bf16_f32 v2, v40, v41
	v_cvt_pk_bf16_f32 v3, v42, v43
	v_cvt_pk_bf16_f32 v4, v36, v37
	v_cvt_pk_bf16_f32 v5, v38, v39
	global_store_dwordx4 v[6:7], v[2:5], off offset:256

.LBB0_228:
	s_andn2_b64 vcc, exec, s[6:7]
	s_cbranch_vccnz .LBB0_230
	v_ashrrev_i32_e32 v11, 31, v10
	v_lshl_add_u32 v6, s74, 8, v181
	v_lshlrev_b64 v[2:3], 11, v[10:11]
	v_mov_b32_e32 v7, v34
	v_lshl_add_u64 v[8:9], s[52:53], 0, v[2:3]
	v_lshlrev_b64 v[6:7], 1, v[6:7]
	v_cvt_pk_bf16_f32 v2, v160, v161
	v_cvt_pk_bf16_f32 v3, v162, v163
	v_cvt_pk_bf16_f32 v4, v156, v157
	v_cvt_pk_bf16_f32 v5, v158, v159
	v_lshl_add_u64 v[8:9], v[8:9], 0, v[6:7]
	global_store_dwordx4 v[8:9], v[2:5], off
	s_mov_b64 s[6:7], 0x40000
	s_nop 0
	v_cvt_pk_bf16_f32 v2, v152, v153
	v_cvt_pk_bf16_f32 v3, v154, v155
	v_cvt_pk_bf16_f32 v4, v148, v149
	v_cvt_pk_bf16_f32 v5, v150, v151
	global_store_dwordx4 v[8:9], v[2:5], off offset:256
	s_nop 1
	v_or_b32_e32 v2, 16, v10
	v_ashrrev_i32_e32 v3, 31, v2
	v_lshlrev_b64 v[2:3], 11, v[2:3]
	v_lshl_add_u64 v[12:13], s[52:53], 0, v[2:3]
	v_cvt_pk_bf16_f32 v2, v144, v145
	v_cvt_pk_bf16_f32 v3, v146, v147
	v_cvt_pk_bf16_f32 v4, v140, v141
	v_cvt_pk_bf16_f32 v5, v142, v143
	v_lshl_add_u64 v[12:13], v[12:13], 0, v[6:7]
	global_store_dwordx4 v[12:13], v[2:5], off
	s_nop 1
	v_cvt_pk_bf16_f32 v2, v136, v137
	v_cvt_pk_bf16_f32 v3, v138, v139
	v_cvt_pk_bf16_f32 v4, v132, v133
	v_cvt_pk_bf16_f32 v5, v134, v135
	global_store_dwordx4 v[12:13], v[2:5], off offset:256
	s_nop 1
	v_or_b32_e32 v2, 32, v10
	v_ashrrev_i32_e32 v3, 31, v2
	v_lshlrev_b64 v[2:3], 11, v[2:3]
	v_lshl_add_u64 v[12:13], s[52:53], 0, v[2:3]
	v_cvt_pk_bf16_f32 v2, v128, v129
	v_cvt_pk_bf16_f32 v3, v130, v131
	v_cvt_pk_bf16_f32 v4, v124, v125
	v_cvt_pk_bf16_f32 v5, v126, v127
	v_lshl_add_u64 v[12:13], v[12:13], 0, v[6:7]
	global_store_dwordx4 v[12:13], v[2:5], off
	s_nop 1
	v_cvt_pk_bf16_f32 v2, v120, v121
	v_cvt_pk_bf16_f32 v3, v122, v123
	v_cvt_pk_bf16_f32 v4, v116, v117
	v_cvt_pk_bf16_f32 v5, v118, v119
	global_store_dwordx4 v[12:13], v[2:5], off offset:256
	s_nop 1
	v_or_b32_e32 v2, 48, v10
	v_ashrrev_i32_e32 v3, 31, v2
	v_lshlrev_b64 v[2:3], 11, v[2:3]
	v_lshl_add_u64 v[12:13], s[52:53], 0, v[2:3]
	v_cvt_pk_bf16_f32 v2, v112, v113
	v_cvt_pk_bf16_f32 v3, v114, v115
	v_cvt_pk_bf16_f32 v4, v108, v109
	v_cvt_pk_bf16_f32 v5, v110, v111
	v_lshl_add_u64 v[6:7], v[12:13], 0, v[6:7]
	global_store_dwordx4 v[6:7], v[2:5], off
	s_nop 1
	v_cvt_pk_bf16_f32 v2, v104, v105
	v_cvt_pk_bf16_f32 v3, v106, v107
	v_cvt_pk_bf16_f32 v4, v100, v101
	v_cvt_pk_bf16_f32 v5, v102, v103
	global_store_dwordx4 v[6:7], v[2:5], off offset:256
	v_lshl_add_u64 v[6:7], v[8:9], 0, s[6:7]
	s_mov_b32 s6, 0x40000
	v_add_co_u32_e32 v12, vcc, s6, v8
	v_cvt_pk_bf16_f32 v2, v96, v97
	v_cvt_pk_bf16_f32 v3, v98, v99
	v_cvt_pk_bf16_f32 v4, v92, v93
	v_cvt_pk_bf16_f32 v5, v94, v95
	v_addc_co_u32_e32 v13, vcc, 0, v9, vcc
	global_store_dwordx4 v[12:13], v[2:5], off
	s_mov_b64 s[6:7], 0x48000
	s_nop 0
	v_cvt_pk_bf16_f32 v2, v88, v89
	v_cvt_pk_bf16_f32 v3, v90, v91
	v_cvt_pk_bf16_f32 v4, v84, v85
	v_cvt_pk_bf16_f32 v5, v86, v87
	global_store_dwordx4 v[6:7], v[2:5], off offset:256
	v_lshl_add_u64 v[6:7], v[8:9], 0, s[6:7]
	s_mov_b32 s6, 0x48000
	v_add_co_u32_e32 v12, vcc, s6, v8
	v_cvt_pk_bf16_f32 v2, v80, v81
	v_cvt_pk_bf16_f32 v3, v82, v83
	v_cvt_pk_bf16_f32 v4, v76, v77
	v_cvt_pk_bf16_f32 v5, v78, v79
	v_addc_co_u32_e32 v13, vcc, 0, v9, vcc
	global_store_dwordx4 v[12:13], v[2:5], off
	s_mov_b64 s[6:7], 0x50000
	s_nop 0
	v_cvt_pk_bf16_f32 v2, v72, v73
	v_cvt_pk_bf16_f32 v3, v74, v75
	v_cvt_pk_bf16_f32 v4, v68, v69
	v_cvt_pk_bf16_f32 v5, v70, v71
	global_store_dwordx4 v[6:7], v[2:5], off offset:256
	v_lshl_add_u64 v[6:7], v[8:9], 0, s[6:7]
	s_mov_b32 s6, 0x50000
	v_add_co_u32_e32 v12, vcc, s6, v8
	v_cvt_pk_bf16_f32 v2, v64, v65
	v_cvt_pk_bf16_f32 v3, v66, v67
	v_cvt_pk_bf16_f32 v4, v60, v61
	v_cvt_pk_bf16_f32 v5, v62, v63
	v_addc_co_u32_e32 v13, vcc, 0, v9, vcc
	global_store_dwordx4 v[12:13], v[2:5], off
	s_mov_b64 s[6:7], 0x58000
	s_nop 0
	v_cvt_pk_bf16_f32 v2, v56, v57
	v_cvt_pk_bf16_f32 v3, v58, v59
	v_cvt_pk_bf16_f32 v4, v52, v53
	v_cvt_pk_bf16_f32 v5, v54, v55
	global_store_dwordx4 v[6:7], v[2:5], off offset:256
	v_lshl_add_u64 v[6:7], v[8:9], 0, s[6:7]
	s_mov_b32 s6, 0x58000
	v_add_co_u32_e32 v8, vcc, s6, v8
	v_cvt_pk_bf16_f32 v2, v48, v49
	v_cvt_pk_bf16_f32 v3, v50, v51
	v_cvt_pk_bf16_f32 v4, v44, v45
	v_cvt_pk_bf16_f32 v5, v46, v47
	v_addc_co_u32_e32 v9, vcc, 0, v9, vcc
	global_store_dwordx4 v[8:9], v[2:5], off
	s_nop 1
	v_cvt_pk_bf16_f32 v2, v40, v41
	v_cvt_pk_bf16_f32 v3, v42, v43
	v_cvt_pk_bf16_f32 v4, v36, v37
	v_cvt_pk_bf16_f32 v5, v38, v39
	global_store_dwordx4 v[6:7], v[2:5], off offset:256

.LBB0_231:
	s_andn2_b64 vcc, exec, s[6:7]
	s_cbranch_vccnz .LBB0_233
	v_ashrrev_i32_e32 v11, 31, v10
	v_lshlrev_b64 v[4:5], 11, v[10:11]
	s_mov_b32 s8, 0x3d800000
	v_lshl_add_u32 v2, s74, 8, v218
	v_lshl_add_u64 v[8:9], s[50:51], 0, v[4:5]
	v_pk_mul_f32 v[4:5], v[160:161], s[8:9] op_sel_hi:[1,0]
	v_pk_mul_f32 v[12:13], v[162:163], s[8:9] op_sel_hi:[1,0]
	v_mov_b32_e32 v3, v34
	v_pk_mul_f32 v[6:7], v[156:157], s[8:9] op_sel_hi:[1,0]
	v_pk_mul_f32 v[14:15], v[158:159], s[8:9] op_sel_hi:[1,0]
	v_cvt_pk_bf16_f32 v4, v4, v5
	v_cvt_pk_bf16_f32 v5, v12, v13
	v_lshlrev_b64 v[12:13], 1, v[2:3]
	v_cvt_pk_bf16_f32 v6, v6, v7
	v_cvt_pk_bf16_f32 v7, v14, v15
	v_lshl_add_u64 v[2:3], v[8:9], 0, v[12:13]
	global_store_dwordx4 v[2:3], v[4:7], off
	v_pk_mul_f32 v[8:9], v[154:155], s[8:9] op_sel_hi:[1,0]
	v_pk_mul_f32 v[14:15], v[150:151], s[8:9] op_sel_hi:[1,0]
	v_pk_mul_f32 v[4:5], v[152:153], s[8:9] op_sel_hi:[1,0]
	v_pk_mul_f32 v[6:7], v[148:149], s[8:9] op_sel_hi:[1,0]
	v_cvt_pk_bf16_f32 v4, v4, v5
	v_cvt_pk_bf16_f32 v5, v8, v9
	v_cvt_pk_bf16_f32 v6, v6, v7
	v_cvt_pk_bf16_f32 v7, v14, v15
	global_store_dwordx4 v[2:3], v[4:7], off offset:256
	v_pk_mul_f32 v[14:15], v[146:147], s[8:9] op_sel_hi:[1,0]
	v_pk_mul_f32 v[16:17], v[142:143], s[8:9] op_sel_hi:[1,0]
	v_or_b32_e32 v4, 16, v10
	v_ashrrev_i32_e32 v5, 31, v4
	v_lshlrev_b64 v[4:5], 11, v[4:5]
	v_lshl_add_u64 v[8:9], s[50:51], 0, v[4:5]
	v_pk_mul_f32 v[4:5], v[144:145], s[8:9] op_sel_hi:[1,0]
	v_pk_mul_f32 v[6:7], v[140:141], s[8:9] op_sel_hi:[1,0]
	v_cvt_pk_bf16_f32 v4, v4, v5
	v_cvt_pk_bf16_f32 v5, v14, v15
	v_cvt_pk_bf16_f32 v6, v6, v7
	v_cvt_pk_bf16_f32 v7, v16, v17
	v_lshl_add_u64 v[8:9], v[8:9], 0, v[12:13]
	global_store_dwordx4 v[8:9], v[4:7], off
	v_pk_mul_f32 v[14:15], v[138:139], s[8:9] op_sel_hi:[1,0]
	v_pk_mul_f32 v[16:17], v[134:135], s[8:9] op_sel_hi:[1,0]
	v_pk_mul_f32 v[4:5], v[136:137], s[8:9] op_sel_hi:[1,0]
	v_pk_mul_f32 v[6:7], v[132:133], s[8:9] op_sel_hi:[1,0]
	v_cvt_pk_bf16_f32 v4, v4, v5
	v_cvt_pk_bf16_f32 v5, v14, v15
	v_cvt_pk_bf16_f32 v6, v6, v7
	v_cvt_pk_bf16_f32 v7, v16, v17
	global_store_dwordx4 v[8:9], v[4:7], off offset:256
	v_pk_mul_f32 v[14:15], v[130:131], s[8:9] op_sel_hi:[1,0]
	v_pk_mul_f32 v[16:17], v[126:127], s[8:9] op_sel_hi:[1,0]
	v_or_b32_e32 v4, 32, v10
	v_ashrrev_i32_e32 v5, 31, v4
	v_lshlrev_b64 v[4:5], 11, v[4:5]
	v_lshl_add_u64 v[8:9], s[50:51], 0, v[4:5]
	v_pk_mul_f32 v[4:5], v[128:129], s[8:9] op_sel_hi:[1,0]
	v_pk_mul_f32 v[6:7], v[124:125], s[8:9] op_sel_hi:[1,0]
	v_cvt_pk_bf16_f32 v4, v4, v5
	v_cvt_pk_bf16_f32 v5, v14, v15
	v_cvt_pk_bf16_f32 v6, v6, v7
	v_cvt_pk_bf16_f32 v7, v16, v17
	v_lshl_add_u64 v[8:9], v[8:9], 0, v[12:13]
	global_store_dwordx4 v[8:9], v[4:7], off
	v_pk_mul_f32 v[14:15], v[122:123], s[8:9] op_sel_hi:[1,0]
	v_pk_mul_f32 v[16:17], v[118:119], s[8:9] op_sel_hi:[1,0]
	v_pk_mul_f32 v[4:5], v[120:121], s[8:9] op_sel_hi:[1,0]
	v_pk_mul_f32 v[6:7], v[116:117], s[8:9] op_sel_hi:[1,0]
	v_cvt_pk_bf16_f32 v4, v4, v5
	v_cvt_pk_bf16_f32 v5, v14, v15
	v_cvt_pk_bf16_f32 v6, v6, v7
	v_cvt_pk_bf16_f32 v7, v16, v17
	global_store_dwordx4 v[8:9], v[4:7], off offset:256
	v_pk_mul_f32 v[14:15], v[114:115], s[8:9] op_sel_hi:[1,0]
	v_pk_mul_f32 v[16:17], v[110:111], s[8:9] op_sel_hi:[1,0]
	v_or_b32_e32 v4, 48, v10
	v_ashrrev_i32_e32 v5, 31, v4
	v_lshlrev_b64 v[4:5], 11, v[4:5]
	v_lshl_add_u64 v[8:9], s[50:51], 0, v[4:5]
	v_pk_mul_f32 v[4:5], v[112:113], s[8:9] op_sel_hi:[1,0]
	v_pk_mul_f32 v[6:7], v[108:109], s[8:9] op_sel_hi:[1,0]
	v_cvt_pk_bf16_f32 v4, v4, v5
	v_cvt_pk_bf16_f32 v5, v14, v15
	v_cvt_pk_bf16_f32 v6, v6, v7
	v_cvt_pk_bf16_f32 v7, v16, v17
	v_lshl_add_u64 v[8:9], v[8:9], 0, v[12:13]
	global_store_dwordx4 v[8:9], v[4:7], off
	v_pk_mul_f32 v[12:13], v[106:107], s[8:9] op_sel_hi:[1,0]
	v_pk_mul_f32 v[14:15], v[102:103], s[8:9] op_sel_hi:[1,0]
	v_pk_mul_f32 v[4:5], v[104:105], s[8:9] op_sel_hi:[1,0]
	v_pk_mul_f32 v[6:7], v[100:101], s[8:9] op_sel_hi:[1,0]
	v_cvt_pk_bf16_f32 v4, v4, v5
	v_cvt_pk_bf16_f32 v5, v12, v13
	v_cvt_pk_bf16_f32 v6, v6, v7
	v_cvt_pk_bf16_f32 v7, v14, v15
	global_store_dwordx4 v[8:9], v[4:7], off offset:256
	v_pk_mul_f32 v[8:9], v[98:99], s[8:9] op_sel_hi:[1,0]
	s_mov_b64 s[6:7], 0x40000
	v_pk_mul_f32 v[4:5], v[96:97], s[8:9] op_sel_hi:[1,0]
	v_pk_mul_f32 v[6:7], v[92:93], s[8:9] op_sel_hi:[1,0]
	v_pk_mul_f32 v[12:13], v[94:95], s[8:9] op_sel_hi:[1,0]
	v_cvt_pk_bf16_f32 v4, v4, v5
	v_cvt_pk_bf16_f32 v5, v8, v9
	v_lshl_add_u64 v[8:9], v[2:3], 0, s[6:7]
	s_mov_b32 s6, 0x40000
	v_cvt_pk_bf16_f32 v6, v6, v7
	v_cvt_pk_bf16_f32 v7, v12, v13
	v_add_co_u32_e32 v12, vcc, s6, v2
	v_pk_mul_f32 v[14:15], v[86:87], s[8:9] op_sel_hi:[1,0]
	s_nop 0
	v_addc_co_u32_e32 v13, vcc, 0, v3, vcc
	global_store_dwordx4 v[12:13], v[4:7], off
	v_pk_mul_f32 v[12:13], v[90:91], s[8:9] op_sel_hi:[1,0]
	s_mov_b64 s[6:7], 0x48000
	v_pk_mul_f32 v[4:5], v[88:89], s[8:9] op_sel_hi:[1,0]
	v_pk_mul_f32 v[6:7], v[84:85], s[8:9] op_sel_hi:[1,0]
	v_cvt_pk_bf16_f32 v4, v4, v5
	v_cvt_pk_bf16_f32 v5, v12, v13
	v_cvt_pk_bf16_f32 v6, v6, v7
	v_cvt_pk_bf16_f32 v7, v14, v15
	global_store_dwordx4 v[8:9], v[4:7], off offset:256
	v_pk_mul_f32 v[8:9], v[82:83], s[8:9] op_sel_hi:[1,0]
	v_pk_mul_f32 v[12:13], v[78:79], s[8:9] op_sel_hi:[1,0]
	v_pk_mul_f32 v[4:5], v[80:81], s[8:9] op_sel_hi:[1,0]
	v_pk_mul_f32 v[6:7], v[76:77], s[8:9] op_sel_hi:[1,0]
	v_cvt_pk_bf16_f32 v4, v4, v5
	v_cvt_pk_bf16_f32 v5, v8, v9
	v_lshl_add_u64 v[8:9], v[2:3], 0, s[6:7]
	s_mov_b32 s6, 0x48000
	v_cvt_pk_bf16_f32 v6, v6, v7
	v_cvt_pk_bf16_f32 v7, v12, v13
	v_add_co_u32_e32 v12, vcc, s6, v2
	v_pk_mul_f32 v[14:15], v[70:71], s[8:9] op_sel_hi:[1,0]
	s_nop 0
	v_addc_co_u32_e32 v13, vcc, 0, v3, vcc
	global_store_dwordx4 v[12:13], v[4:7], off
	v_pk_mul_f32 v[12:13], v[74:75], s[8:9] op_sel_hi:[1,0]
	s_mov_b64 s[6:7], 0x50000
	v_pk_mul_f32 v[4:5], v[72:73], s[8:9] op_sel_hi:[1,0]
	v_pk_mul_f32 v[6:7], v[68:69], s[8:9] op_sel_hi:[1,0]
	v_cvt_pk_bf16_f32 v4, v4, v5
	v_cvt_pk_bf16_f32 v5, v12, v13
	v_cvt_pk_bf16_f32 v6, v6, v7
	v_cvt_pk_bf16_f32 v7, v14, v15
	global_store_dwordx4 v[8:9], v[4:7], off offset:256
	v_pk_mul_f32 v[8:9], v[66:67], s[8:9] op_sel_hi:[1,0]
	v_pk_mul_f32 v[12:13], v[62:63], s[8:9] op_sel_hi:[1,0]
	v_pk_mul_f32 v[4:5], v[64:65], s[8:9] op_sel_hi:[1,0]
	v_pk_mul_f32 v[6:7], v[60:61], s[8:9] op_sel_hi:[1,0]
	v_cvt_pk_bf16_f32 v4, v4, v5
	v_cvt_pk_bf16_f32 v5, v8, v9
	v_lshl_add_u64 v[8:9], v[2:3], 0, s[6:7]
	s_mov_b32 s6, 0x50000
	v_cvt_pk_bf16_f32 v6, v6, v7
	v_cvt_pk_bf16_f32 v7, v12, v13
	v_add_co_u32_e32 v12, vcc, s6, v2
	v_pk_mul_f32 v[14:15], v[54:55], s[8:9] op_sel_hi:[1,0]
	s_nop 0
	v_addc_co_u32_e32 v13, vcc, 0, v3, vcc
	global_store_dwordx4 v[12:13], v[4:7], off
	v_pk_mul_f32 v[12:13], v[58:59], s[8:9] op_sel_hi:[1,0]
	s_mov_b64 s[6:7], 0x58000
	v_pk_mul_f32 v[4:5], v[56:57], s[8:9] op_sel_hi:[1,0]
	v_pk_mul_f32 v[6:7], v[52:53], s[8:9] op_sel_hi:[1,0]
	v_cvt_pk_bf16_f32 v4, v4, v5
	v_cvt_pk_bf16_f32 v5, v12, v13
	v_cvt_pk_bf16_f32 v6, v6, v7
	v_cvt_pk_bf16_f32 v7, v14, v15
	global_store_dwordx4 v[8:9], v[4:7], off offset:256
	v_pk_mul_f32 v[8:9], v[50:51], s[8:9] op_sel_hi:[1,0]
	v_pk_mul_f32 v[12:13], v[46:47], s[8:9] op_sel_hi:[1,0]
	v_pk_mul_f32 v[4:5], v[48:49], s[8:9] op_sel_hi:[1,0]
	v_pk_mul_f32 v[6:7], v[44:45], s[8:9] op_sel_hi:[1,0]
	v_cvt_pk_bf16_f32 v4, v4, v5
	v_cvt_pk_bf16_f32 v5, v8, v9
	v_lshl_add_u64 v[8:9], v[2:3], 0, s[6:7]
	s_mov_b32 s6, 0x58000
	v_add_co_u32_e32 v2, vcc, s6, v2
	v_cvt_pk_bf16_f32 v6, v6, v7
	v_cvt_pk_bf16_f32 v7, v12, v13
	v_addc_co_u32_e32 v3, vcc, 0, v3, vcc
	global_store_dwordx4 v[2:3], v[4:7], off
	v_pk_mul_f32 v[2:3], v[40:41], s[8:9] op_sel_hi:[1,0]
	v_pk_mul_f32 v[12:13], v[38:39], s[8:9] op_sel_hi:[1,0]
	v_pk_mul_f32 v[4:5], v[36:37], s[8:9] op_sel_hi:[1,0]
	v_pk_mul_f32 v[6:7], v[42:43], s[8:9] op_sel_hi:[1,0]
	v_cvt_pk_bf16_f32 v2, v2, v3
	v_cvt_pk_bf16_f32 v3, v6, v7
	v_cvt_pk_bf16_f32 v4, v4, v5
	v_cvt_pk_bf16_f32 v5, v12, v13
	global_store_dwordx4 v[8:9], v[2:5], off offset:256

.LBB0_234:
	s_andn2_b64 vcc, exec, s[6:7]
	s_cbranch_vccnz .LBB0_236
	v_mul_f32_e32 v3, 0xbfb8aa3b, v160
	v_exp_f32_e32 v3, v3
	v_mul_f32_e32 v6, 0xbfb8aa3b, v156
	v_exp_f32_e32 v6, v6
	v_ashrrev_i32_e32 v11, 31, v10
	v_lshlrev_b64 v[4:5], 12, v[10:11]
	v_lshl_add_u64 v[12:13], s[48:49], 0, v[4:5]
	v_add_f32_e32 v3, 1.0, v3
	v_mul_f32_e32 v5, 0xbfb8aa3b, v161
	v_rcp_f32_e32 v4, v3
	v_add_f32_e32 v3, 1.0, v6
	v_exp_f32_e32 v5, v5
	v_mul_f32_e32 v6, 0xbfb8aa3b, v157
	v_exp_f32_e32 v7, v6
	v_rcp_f32_e32 v6, v3
	v_add_f32_e32 v3, 1.0, v5
	v_rcp_f32_e32 v5, v3
	v_add_f32_e32 v3, 1.0, v7
	v_mul_f32_e32 v7, 0xbfb8aa3b, v162
	v_exp_f32_e32 v8, v7
	v_mul_f32_e32 v7, 0xbfb8aa3b, v158
	v_exp_f32_e32 v9, v7
	v_rcp_f32_e32 v7, v3
	v_add_f32_e32 v3, 1.0, v8
	v_rcp_f32_e32 v8, v3
	v_add_f32_e32 v3, 1.0, v9
	v_mul_f32_e32 v9, 0xbfb8aa3b, v163
	v_exp_f32_e32 v9, v9
	v_mul_f32_e32 v11, 0xbfb8aa3b, v159
	v_exp_f32_e32 v11, v11
	v_rcp_f32_e32 v14, v3
	v_add_f32_e32 v3, 1.0, v9
	v_rcp_f32_e32 v9, v3
	v_add_f32_e32 v3, 1.0, v11
	v_rcp_f32_e32 v15, v3
	v_lshl_add_u32 v2, s74, 8, v1
	v_pk_mul_f32 v[4:5], v[160:161], v[4:5]
	v_mov_b32_e32 v3, v34
	v_mul_f32_e32 v11, 0xbfb8aa3b, v152
	v_pk_mul_f32 v[16:17], v[156:157], v[6:7]
	v_pk_mul_f32 v[8:9], v[162:163], v[8:9]
	v_pk_mul_f32 v[14:15], v[158:159], v[14:15]
	v_cvt_pk_bf16_f32 v6, v4, v5
	v_lshlrev_b64 v[4:5], 1, v[2:3]
	v_exp_f32_e32 v11, v11
	v_cvt_pk_bf16_f32 v7, v8, v9
	v_cvt_pk_bf16_f32 v8, v16, v17
	v_cvt_pk_bf16_f32 v9, v14, v15
	v_lshl_add_u64 v[2:3], v[12:13], 0, v[4:5]
	v_mul_f32_e32 v12, 0xbfb8aa3b, v148
	global_store_dwordx4 v[2:3], v[6:9], off
	v_exp_f32_e32 v12, v12
	v_mul_f32_e32 v14, 0xbfb8aa3b, v151
	v_mul_f32_e32 v8, 0xbfb8aa3b, v153
	v_exp_f32_e32 v9, v8
	v_mul_f32_e32 v8, 0xbfb8aa3b, v149
	v_add_f32_e32 v6, 1.0, v11
	v_exp_f32_e32 v11, v8
	v_add_f32_e32 v7, 1.0, v12
	v_rcp_f32_e32 v8, v7
	v_add_f32_e32 v7, 1.0, v9
	v_add_f32_e32 v9, 1.0, v11
	v_mul_f32_e32 v11, 0xbfb8aa3b, v154
	v_exp_f32_e32 v11, v11
	v_mul_f32_e32 v12, 0xbfb8aa3b, v150
	v_exp_f32_e32 v13, v12
	v_exp_f32_e32 v15, v14
	v_add_f32_e32 v11, 1.0, v11
	v_rcp_f32_e32 v12, v11
	v_add_f32_e32 v11, 1.0, v13
	v_mul_f32_e32 v13, 0xbfb8aa3b, v155
	v_exp_f32_e32 v13, v13
	v_rcp_f32_e32 v14, v11
	v_rcp_f32_e32 v6, v6
	v_rcp_f32_e32 v7, v7
	v_add_f32_e32 v11, 1.0, v13
	v_rcp_f32_e32 v13, v11
	v_add_f32_e32 v11, 1.0, v15
	v_rcp_f32_e32 v9, v9
	v_rcp_f32_e32 v15, v11
	v_pk_mul_f32 v[6:7], v[152:153], v[6:7]
	v_pk_mul_f32 v[12:13], v[154:155], v[12:13]
	v_pk_mul_f32 v[8:9], v[148:149], v[8:9]
	v_pk_mul_f32 v[14:15], v[150:151], v[14:15]
	v_cvt_pk_bf16_f32 v6, v6, v7
	v_cvt_pk_bf16_f32 v7, v12, v13
	v_cvt_pk_bf16_f32 v8, v8, v9
	v_cvt_pk_bf16_f32 v9, v14, v15
	global_store_dwordx4 v[2:3], v[6:9], off offset:256
	v_mul_f32_e32 v14, 0xbfb8aa3b, v142
	v_exp_f32_e32 v15, v14
	v_mul_f32_e32 v8, 0xbfb8aa3b, v144
	v_exp_f32_e32 v8, v8
	v_mul_f32_e32 v9, 0xbfb8aa3b, v140
	v_or_b32_e32 v6, 16, v10
	v_exp_f32_e32 v9, v9
	v_ashrrev_i32_e32 v7, 31, v6
	v_lshlrev_b64 v[6:7], 12, v[6:7]
	v_lshl_add_u64 v[12:13], s[48:49], 0, v[6:7]
	v_add_f32_e32 v6, 1.0, v8
	v_mul_f32_e32 v8, 0xbfb8aa3b, v145
	v_add_f32_e32 v7, 1.0, v9
	v_exp_f32_e32 v9, v8
	v_mul_f32_e32 v8, 0xbfb8aa3b, v141
	v_exp_f32_e32 v11, v8
	v_rcp_f32_e32 v8, v7
	v_add_f32_e32 v7, 1.0, v9
	v_mul_f32_e32 v16, 0xbfb8aa3b, v143
	v_add_f32_e32 v9, 1.0, v11
	v_mul_f32_e32 v11, 0xbfb8aa3b, v146
	v_exp_f32_e32 v11, v11
	v_exp_f32_e32 v17, v16
	v_rcp_f32_e32 v6, v6
	v_rcp_f32_e32 v7, v7
	v_add_f32_e32 v11, 1.0, v11
	v_rcp_f32_e32 v14, v11
	v_add_f32_e32 v11, 1.0, v15
	v_mul_f32_e32 v15, 0xbfb8aa3b, v147
	v_exp_f32_e32 v15, v15
	v_rcp_f32_e32 v16, v11
	v_rcp_f32_e32 v9, v9
	v_pk_mul_f32 v[6:7], v[144:145], v[6:7]
	v_add_f32_e32 v11, 1.0, v15
	v_rcp_f32_e32 v15, v11
	v_add_f32_e32 v11, 1.0, v17
	v_rcp_f32_e32 v17, v11
	v_mul_f32_e32 v11, 0xbfb8aa3b, v136
	v_pk_mul_f32 v[8:9], v[140:141], v[8:9]
	v_pk_mul_f32 v[14:15], v[146:147], v[14:15]
	v_pk_mul_f32 v[16:17], v[142:143], v[16:17]
	v_exp_f32_e32 v11, v11
	v_cvt_pk_bf16_f32 v6, v6, v7
	v_cvt_pk_bf16_f32 v7, v14, v15
	v_cvt_pk_bf16_f32 v8, v8, v9
	v_cvt_pk_bf16_f32 v9, v16, v17
	v_lshl_add_u64 v[12:13], v[12:13], 0, v[4:5]
	v_mul_f32_e32 v14, 0xbfb8aa3b, v132
	global_store_dwordx4 v[12:13], v[6:9], off
	v_exp_f32_e32 v14, v14
	v_mul_f32_e32 v16, 0xbfb8aa3b, v135
	v_mul_f32_e32 v8, 0xbfb8aa3b, v137
	v_exp_f32_e32 v9, v8
	v_mul_f32_e32 v8, 0xbfb8aa3b, v133
	v_add_f32_e32 v6, 1.0, v11
	v_exp_f32_e32 v11, v8
	v_add_f32_e32 v7, 1.0, v14
	v_rcp_f32_e32 v8, v7
	v_add_f32_e32 v7, 1.0, v9
	v_add_f32_e32 v9, 1.0, v11
	v_mul_f32_e32 v11, 0xbfb8aa3b, v138
	v_exp_f32_e32 v11, v11
	v_mul_f32_e32 v14, 0xbfb8aa3b, v134
	v_exp_f32_e32 v15, v14
	v_exp_f32_e32 v17, v16
	v_add_f32_e32 v11, 1.0, v11
	v_rcp_f32_e32 v14, v11
	v_add_f32_e32 v11, 1.0, v15
	v_mul_f32_e32 v15, 0xbfb8aa3b, v139
	v_exp_f32_e32 v15, v15
	v_rcp_f32_e32 v16, v11
	v_rcp_f32_e32 v6, v6
	v_rcp_f32_e32 v7, v7
	v_add_f32_e32 v11, 1.0, v15
	v_rcp_f32_e32 v15, v11
	v_add_f32_e32 v11, 1.0, v17
	v_rcp_f32_e32 v9, v9
	v_rcp_f32_e32 v17, v11
	v_pk_mul_f32 v[6:7], v[136:137], v[6:7]
	v_pk_mul_f32 v[14:15], v[138:139], v[14:15]
	v_pk_mul_f32 v[8:9], v[132:133], v[8:9]
	v_pk_mul_f32 v[16:17], v[134:135], v[16:17]
	v_cvt_pk_bf16_f32 v6, v6, v7
	v_cvt_pk_bf16_f32 v7, v14, v15
	v_cvt_pk_bf16_f32 v8, v8, v9
	v_cvt_pk_bf16_f32 v9, v16, v17
	global_store_dwordx4 v[12:13], v[6:9], off offset:256
	v_mul_f32_e32 v14, 0xbfb8aa3b, v126
	v_exp_f32_e32 v15, v14
	v_mul_f32_e32 v8, 0xbfb8aa3b, v128
	v_exp_f32_e32 v8, v8
	v_mul_f32_e32 v9, 0xbfb8aa3b, v124
	v_or_b32_e32 v6, 32, v10
	v_exp_f32_e32 v9, v9
	v_ashrrev_i32_e32 v7, 31, v6
	v_lshlrev_b64 v[6:7], 12, v[6:7]
	v_lshl_add_u64 v[12:13], s[48:49], 0, v[6:7]
	v_add_f32_e32 v6, 1.0, v8
	v_mul_f32_e32 v8, 0xbfb8aa3b, v129
	v_add_f32_e32 v7, 1.0, v9
	v_exp_f32_e32 v9, v8
	v_mul_f32_e32 v8, 0xbfb8aa3b, v125
	v_exp_f32_e32 v11, v8
	v_rcp_f32_e32 v8, v7
	v_add_f32_e32 v7, 1.0, v9
	v_mul_f32_e32 v16, 0xbfb8aa3b, v127
	v_add_f32_e32 v9, 1.0, v11
	v_mul_f32_e32 v11, 0xbfb8aa3b, v130
	v_exp_f32_e32 v11, v11
	v_exp_f32_e32 v17, v16
	v_rcp_f32_e32 v6, v6
	v_rcp_f32_e32 v7, v7
	v_add_f32_e32 v11, 1.0, v11
	v_rcp_f32_e32 v14, v11
	v_add_f32_e32 v11, 1.0, v15
	v_mul_f32_e32 v15, 0xbfb8aa3b, v131
	v_exp_f32_e32 v15, v15
	v_rcp_f32_e32 v16, v11
	v_rcp_f32_e32 v9, v9
	v_pk_mul_f32 v[6:7], v[128:129], v[6:7]
	v_add_f32_e32 v11, 1.0, v15
	v_rcp_f32_e32 v15, v11
	v_add_f32_e32 v11, 1.0, v17
	v_rcp_f32_e32 v17, v11
	v_mul_f32_e32 v11, 0xbfb8aa3b, v120
	v_pk_mul_f32 v[8:9], v[124:125], v[8:9]
	v_pk_mul_f32 v[14:15], v[130:131], v[14:15]
	v_pk_mul_f32 v[16:17], v[126:127], v[16:17]
	v_exp_f32_e32 v11, v11
	v_cvt_pk_bf16_f32 v6, v6, v7
	v_cvt_pk_bf16_f32 v7, v14, v15
	v_cvt_pk_bf16_f32 v8, v8, v9
	v_cvt_pk_bf16_f32 v9, v16, v17
	v_lshl_add_u64 v[12:13], v[12:13], 0, v[4:5]
	v_mul_f32_e32 v14, 0xbfb8aa3b, v116
	global_store_dwordx4 v[12:13], v[6:9], off
	v_exp_f32_e32 v14, v14
	v_mul_f32_e32 v16, 0xbfb8aa3b, v119
	v_mul_f32_e32 v8, 0xbfb8aa3b, v121
	v_exp_f32_e32 v9, v8
	v_mul_f32_e32 v8, 0xbfb8aa3b, v117
	v_add_f32_e32 v6, 1.0, v11
	v_exp_f32_e32 v11, v8
	v_add_f32_e32 v7, 1.0, v14
	v_rcp_f32_e32 v8, v7
	v_add_f32_e32 v7, 1.0, v9
	v_add_f32_e32 v9, 1.0, v11
	v_mul_f32_e32 v11, 0xbfb8aa3b, v122
	v_exp_f32_e32 v11, v11
	v_mul_f32_e32 v14, 0xbfb8aa3b, v118
	v_exp_f32_e32 v15, v14
	v_exp_f32_e32 v17, v16
	v_add_f32_e32 v11, 1.0, v11
	v_rcp_f32_e32 v14, v11
	v_add_f32_e32 v11, 1.0, v15
	v_mul_f32_e32 v15, 0xbfb8aa3b, v123
	v_exp_f32_e32 v15, v15
	v_rcp_f32_e32 v16, v11
	v_rcp_f32_e32 v6, v6
	v_rcp_f32_e32 v7, v7
	v_add_f32_e32 v11, 1.0, v15
	v_rcp_f32_e32 v15, v11
	v_add_f32_e32 v11, 1.0, v17
	v_rcp_f32_e32 v9, v9
	v_rcp_f32_e32 v17, v11
	v_pk_mul_f32 v[6:7], v[120:121], v[6:7]
	v_pk_mul_f32 v[14:15], v[122:123], v[14:15]
	v_pk_mul_f32 v[8:9], v[116:117], v[8:9]
	v_pk_mul_f32 v[16:17], v[118:119], v[16:17]
	v_cvt_pk_bf16_f32 v6, v6, v7
	v_cvt_pk_bf16_f32 v7, v14, v15
	v_cvt_pk_bf16_f32 v8, v8, v9
	v_cvt_pk_bf16_f32 v9, v16, v17
	global_store_dwordx4 v[12:13], v[6:9], off offset:256
	v_mul_f32_e32 v14, 0xbfb8aa3b, v110
	v_exp_f32_e32 v15, v14
	v_mul_f32_e32 v8, 0xbfb8aa3b, v112
	v_exp_f32_e32 v8, v8
	v_mul_f32_e32 v9, 0xbfb8aa3b, v108
	v_or_b32_e32 v6, 48, v10
	v_exp_f32_e32 v9, v9
	v_ashrrev_i32_e32 v7, 31, v6
	v_lshlrev_b64 v[6:7], 12, v[6:7]
	v_lshl_add_u64 v[12:13], s[48:49], 0, v[6:7]
	v_add_f32_e32 v6, 1.0, v8
	v_mul_f32_e32 v8, 0xbfb8aa3b, v113
	v_add_f32_e32 v7, 1.0, v9
	v_exp_f32_e32 v9, v8
	v_mul_f32_e32 v8, 0xbfb8aa3b, v109
	v_exp_f32_e32 v11, v8
	v_rcp_f32_e32 v8, v7
	v_add_f32_e32 v7, 1.0, v9
	v_mul_f32_e32 v16, 0xbfb8aa3b, v111
	v_add_f32_e32 v9, 1.0, v11
	v_mul_f32_e32 v11, 0xbfb8aa3b, v114
	v_exp_f32_e32 v11, v11
	v_exp_f32_e32 v17, v16
	v_rcp_f32_e32 v6, v6
	v_rcp_f32_e32 v7, v7
	v_add_f32_e32 v11, 1.0, v11
	v_rcp_f32_e32 v14, v11
	v_add_f32_e32 v11, 1.0, v15
	v_mul_f32_e32 v15, 0xbfb8aa3b, v115
	v_exp_f32_e32 v15, v15
	v_rcp_f32_e32 v16, v11
	v_rcp_f32_e32 v9, v9
	v_pk_mul_f32 v[6:7], v[112:113], v[6:7]
	v_add_f32_e32 v11, 1.0, v15
	v_rcp_f32_e32 v15, v11
	v_add_f32_e32 v11, 1.0, v17
	v_rcp_f32_e32 v17, v11
	v_pk_mul_f32 v[8:9], v[108:109], v[8:9]
	v_pk_mul_f32 v[14:15], v[114:115], v[14:15]
	v_cvt_pk_bf16_f32 v6, v6, v7
	v_pk_mul_f32 v[16:17], v[110:111], v[16:17]
	v_cvt_pk_bf16_f32 v7, v14, v15
	v_cvt_pk_bf16_f32 v8, v8, v9
	v_cvt_pk_bf16_f32 v9, v16, v17
	v_lshl_add_u64 v[12:13], v[12:13], 0, v[4:5]
	v_mul_f32_e32 v5, 0xbfb8aa3b, v100
	global_store_dwordx4 v[12:13], v[6:9], off
	v_exp_f32_e32 v5, v5
	v_mul_f32_e32 v4, 0xbfb8aa3b, v104
	v_mul_f32_e32 v6, 0xbfb8aa3b, v105
	v_exp_f32_e32 v7, v6
	v_mul_f32_e32 v6, 0xbfb8aa3b, v101
	v_exp_f32_e32 v8, v6
	v_add_f32_e32 v5, 1.0, v5
	v_mul_f32_e32 v9, 0xbfb8aa3b, v102
	v_rcp_f32_e32 v6, v5
	v_add_f32_e32 v5, 1.0, v7
	v_add_f32_e32 v7, 1.0, v8
	v_mul_f32_e32 v8, 0xbfb8aa3b, v106
	v_exp_f32_e32 v9, v9
	v_mul_f32_e32 v11, 0xbfb8aa3b, v107
	v_exp_f32_e32 v4, v4
	v_exp_f32_e32 v8, v8
	v_exp_f32_e32 v11, v11
	v_mul_f32_e32 v14, 0xbfb8aa3b, v103
	v_exp_f32_e32 v15, v14
	v_add_f32_e32 v9, 1.0, v9
	v_add_f32_e32 v4, 1.0, v4
	v_add_f32_e32 v8, 1.0, v8
	v_rcp_f32_e32 v14, v9
	v_add_f32_e32 v9, 1.0, v11
	v_rcp_f32_e32 v4, v4
	v_rcp_f32_e32 v5, v5
	v_rcp_f32_e32 v8, v8
	v_rcp_f32_e32 v9, v9
	v_add_f32_e32 v11, 1.0, v15
	v_rcp_f32_e32 v7, v7
	v_rcp_f32_e32 v15, v11
	v_pk_mul_f32 v[4:5], v[104:105], v[4:5]
	v_pk_mul_f32 v[8:9], v[106:107], v[8:9]
	v_cvt_pk_bf16_f32 v4, v4, v5
	v_cvt_pk_bf16_f32 v5, v8, v9
	v_mul_f32_e32 v8, 0xbfb8aa3b, v96
	v_pk_mul_f32 v[6:7], v[100:101], v[6:7]
	v_pk_mul_f32 v[14:15], v[102:103], v[14:15]
	v_exp_f32_e32 v8, v8
	v_cvt_pk_bf16_f32 v6, v6, v7
	v_cvt_pk_bf16_f32 v7, v14, v15
	v_mul_f32_e32 v9, 0xbfb8aa3b, v92
	global_store_dwordx4 v[12:13], v[4:7], off offset:256
	v_exp_f32_e32 v9, v9
	v_mul_f32_e32 v11, 0xbfb8aa3b, v99
	v_mul_f32_e32 v6, 0xbfb8aa3b, v97
	v_exp_f32_e32 v7, v6
	v_mul_f32_e32 v6, 0xbfb8aa3b, v93
	v_add_f32_e32 v4, 1.0, v8
	v_exp_f32_e32 v8, v6
	v_add_f32_e32 v5, 1.0, v9
	v_mul_f32_e32 v9, 0xbfb8aa3b, v94
	v_rcp_f32_e32 v6, v5
	v_add_f32_e32 v5, 1.0, v7
	v_add_f32_e32 v7, 1.0, v8
	v_mul_f32_e32 v8, 0xbfb8aa3b, v98
	v_exp_f32_e32 v9, v9
	v_exp_f32_e32 v8, v8
	v_exp_f32_e32 v11, v11
	v_mul_f32_e32 v12, 0xbfb8aa3b, v95
	v_exp_f32_e32 v13, v12
	v_add_f32_e32 v9, 1.0, v9
	v_add_f32_e32 v8, 1.0, v8
	v_rcp_f32_e32 v12, v9
	v_add_f32_e32 v9, 1.0, v11
	v_rcp_f32_e32 v4, v4
	v_rcp_f32_e32 v5, v5
	v_rcp_f32_e32 v8, v8
	v_rcp_f32_e32 v9, v9
	v_add_f32_e32 v11, 1.0, v13
	v_rcp_f32_e32 v7, v7
	v_rcp_f32_e32 v13, v11
	v_pk_mul_f32 v[4:5], v[96:97], v[4:5]
	v_pk_mul_f32 v[8:9], v[98:99], v[8:9]
	s_mov_b64 s[6:7], 0x80000
	v_pk_mul_f32 v[6:7], v[92:93], v[6:7]
	v_pk_mul_f32 v[12:13], v[94:95], v[12:13]
	v_cvt_pk_bf16_f32 v4, v4, v5
	v_cvt_pk_bf16_f32 v5, v8, v9
	v_lshl_add_u64 v[8:9], v[2:3], 0, s[6:7]
	s_mov_b32 s6, 0x80000
	v_mul_f32_e32 v11, 0xbfb8aa3b, v88
	v_cvt_pk_bf16_f32 v6, v6, v7
	v_cvt_pk_bf16_f32 v7, v12, v13
	v_add_co_u32_e32 v12, vcc, s6, v2
	v_exp_f32_e32 v11, v11
	s_nop 0
	v_addc_co_u32_e32 v13, vcc, 0, v3, vcc
	v_mul_f32_e32 v14, 0xbfb8aa3b, v84
	global_store_dwordx4 v[12:13], v[4:7], off
	v_exp_f32_e32 v14, v14
	v_mul_f32_e32 v12, 0xbfb8aa3b, v86
	v_mul_f32_e32 v6, 0xbfb8aa3b, v89
	v_exp_f32_e32 v7, v6
	v_mul_f32_e32 v6, 0xbfb8aa3b, v85
	v_add_f32_e32 v4, 1.0, v11
	v_exp_f32_e32 v11, v6
	v_add_f32_e32 v5, 1.0, v14
	v_rcp_f32_e32 v6, v5
	v_add_f32_e32 v5, 1.0, v7
	v_add_f32_e32 v7, 1.0, v11
	v_mul_f32_e32 v11, 0xbfb8aa3b, v90
	v_exp_f32_e32 v11, v11
	v_exp_f32_e32 v13, v12
	v_mul_f32_e32 v14, 0xbfb8aa3b, v87
	v_exp_f32_e32 v15, v14
	v_add_f32_e32 v11, 1.0, v11
	v_rcp_f32_e32 v12, v11
	v_add_f32_e32 v11, 1.0, v13
	v_mul_f32_e32 v13, 0xbfb8aa3b, v91
	v_exp_f32_e32 v13, v13
	v_rcp_f32_e32 v14, v11
	v_rcp_f32_e32 v4, v4
	v_rcp_f32_e32 v5, v5
	v_add_f32_e32 v11, 1.0, v13
	v_rcp_f32_e32 v13, v11
	v_add_f32_e32 v11, 1.0, v15
	v_rcp_f32_e32 v7, v7
	v_rcp_f32_e32 v15, v11
	v_pk_mul_f32 v[4:5], v[88:89], v[4:5]
	v_pk_mul_f32 v[12:13], v[90:91], v[12:13]
	v_pk_mul_f32 v[6:7], v[84:85], v[6:7]
	v_pk_mul_f32 v[14:15], v[86:87], v[14:15]
	v_cvt_pk_bf16_f32 v4, v4, v5
	v_cvt_pk_bf16_f32 v5, v12, v13
	v_cvt_pk_bf16_f32 v6, v6, v7
	v_cvt_pk_bf16_f32 v7, v14, v15
	v_mul_f32_e32 v12, 0xbfb8aa3b, v76
	global_store_dwordx4 v[8:9], v[4:7], off offset:256
	v_mul_f32_e32 v11, 0xbfb8aa3b, v80
	v_exp_f32_e32 v12, v12
	v_mul_f32_e32 v6, 0xbfb8aa3b, v81
	v_exp_f32_e32 v7, v6
	v_mul_f32_e32 v6, 0xbfb8aa3b, v77
	v_exp_f32_e32 v11, v11
	v_exp_f32_e32 v8, v6
	v_add_f32_e32 v5, 1.0, v12
	v_mul_f32_e32 v9, 0xbfb8aa3b, v78
	v_add_f32_e32 v4, 1.0, v11
	v_rcp_f32_e32 v6, v5
	v_add_f32_e32 v5, 1.0, v7
	v_add_f32_e32 v7, 1.0, v8
	v_mul_f32_e32 v8, 0xbfb8aa3b, v82
	v_exp_f32_e32 v9, v9
	v_mul_f32_e32 v11, 0xbfb8aa3b, v83
	v_exp_f32_e32 v8, v8
	v_exp_f32_e32 v11, v11
	v_mul_f32_e32 v12, 0xbfb8aa3b, v79
	v_exp_f32_e32 v13, v12
	v_add_f32_e32 v9, 1.0, v9
	v_add_f32_e32 v8, 1.0, v8
	v_rcp_f32_e32 v12, v9
	v_add_f32_e32 v9, 1.0, v11
	v_rcp_f32_e32 v4, v4
	v_rcp_f32_e32 v5, v5
	v_rcp_f32_e32 v8, v8
	v_rcp_f32_e32 v9, v9
	v_add_f32_e32 v11, 1.0, v13
	v_rcp_f32_e32 v7, v7
	v_rcp_f32_e32 v13, v11
	v_pk_mul_f32 v[4:5], v[80:81], v[4:5]
	v_pk_mul_f32 v[8:9], v[82:83], v[8:9]
	s_mov_b64 s[6:7], 0x90000
	v_pk_mul_f32 v[6:7], v[76:77], v[6:7]
	v_pk_mul_f32 v[12:13], v[78:79], v[12:13]
	v_cvt_pk_bf16_f32 v4, v4, v5
	v_cvt_pk_bf16_f32 v5, v8, v9
	v_lshl_add_u64 v[8:9], v[2:3], 0, s[6:7]
	s_mov_b32 s6, 0x90000
	v_mul_f32_e32 v11, 0xbfb8aa3b, v72
	v_cvt_pk_bf16_f32 v6, v6, v7
	v_cvt_pk_bf16_f32 v7, v12, v13
	v_add_co_u32_e32 v12, vcc, s6, v2
	v_exp_f32_e32 v11, v11
	s_nop 0
	v_addc_co_u32_e32 v13, vcc, 0, v3, vcc
	v_mul_f32_e32 v14, 0xbfb8aa3b, v68
	global_store_dwordx4 v[12:13], v[4:7], off
	v_exp_f32_e32 v14, v14
	v_mul_f32_e32 v12, 0xbfb8aa3b, v70
	v_mul_f32_e32 v6, 0xbfb8aa3b, v73
	v_exp_f32_e32 v7, v6
	v_mul_f32_e32 v6, 0xbfb8aa3b, v69
	v_add_f32_e32 v4, 1.0, v11
	v_exp_f32_e32 v11, v6
	v_add_f32_e32 v5, 1.0, v14
	v_rcp_f32_e32 v6, v5
	v_add_f32_e32 v5, 1.0, v7
	v_add_f32_e32 v7, 1.0, v11
	v_mul_f32_e32 v11, 0xbfb8aa3b, v74
	v_exp_f32_e32 v11, v11
	v_exp_f32_e32 v13, v12
	v_mul_f32_e32 v14, 0xbfb8aa3b, v71
	v_exp_f32_e32 v15, v14
	v_add_f32_e32 v11, 1.0, v11
	v_rcp_f32_e32 v12, v11
	v_add_f32_e32 v11, 1.0, v13
	v_mul_f32_e32 v13, 0xbfb8aa3b, v75
	v_exp_f32_e32 v13, v13
	v_rcp_f32_e32 v14, v11
	v_rcp_f32_e32 v4, v4
	v_rcp_f32_e32 v5, v5
	v_add_f32_e32 v11, 1.0, v13
	v_rcp_f32_e32 v13, v11
	v_add_f32_e32 v11, 1.0, v15
	v_rcp_f32_e32 v7, v7
	v_rcp_f32_e32 v15, v11
	v_pk_mul_f32 v[4:5], v[72:73], v[4:5]
	v_pk_mul_f32 v[12:13], v[74:75], v[12:13]
	v_pk_mul_f32 v[6:7], v[68:69], v[6:7]
	v_pk_mul_f32 v[14:15], v[70:71], v[14:15]
	v_cvt_pk_bf16_f32 v4, v4, v5
	v_cvt_pk_bf16_f32 v5, v12, v13
	v_cvt_pk_bf16_f32 v6, v6, v7
	v_cvt_pk_bf16_f32 v7, v14, v15
	v_mul_f32_e32 v12, 0xbfb8aa3b, v60
	global_store_dwordx4 v[8:9], v[4:7], off offset:256
	v_mul_f32_e32 v11, 0xbfb8aa3b, v64
	v_exp_f32_e32 v12, v12
	v_mul_f32_e32 v6, 0xbfb8aa3b, v65
	v_exp_f32_e32 v7, v6
	v_mul_f32_e32 v6, 0xbfb8aa3b, v61
	v_exp_f32_e32 v11, v11
	v_exp_f32_e32 v8, v6
	v_add_f32_e32 v5, 1.0, v12
	v_mul_f32_e32 v9, 0xbfb8aa3b, v62
	v_add_f32_e32 v4, 1.0, v11
	v_rcp_f32_e32 v6, v5
	v_add_f32_e32 v5, 1.0, v7
	v_add_f32_e32 v7, 1.0, v8
	v_mul_f32_e32 v8, 0xbfb8aa3b, v66
	v_exp_f32_e32 v9, v9
	v_mul_f32_e32 v11, 0xbfb8aa3b, v67
	v_exp_f32_e32 v8, v8
	v_exp_f32_e32 v11, v11
	v_mul_f32_e32 v12, 0xbfb8aa3b, v63
	v_exp_f32_e32 v13, v12
	v_add_f32_e32 v9, 1.0, v9
	v_add_f32_e32 v8, 1.0, v8
	v_rcp_f32_e32 v12, v9
	v_add_f32_e32 v9, 1.0, v11
	v_rcp_f32_e32 v4, v4
	v_rcp_f32_e32 v5, v5
	v_rcp_f32_e32 v8, v8
	v_rcp_f32_e32 v9, v9
	v_add_f32_e32 v11, 1.0, v13
	v_rcp_f32_e32 v7, v7
	v_rcp_f32_e32 v13, v11
	v_pk_mul_f32 v[4:5], v[64:65], v[4:5]
	v_pk_mul_f32 v[8:9], v[66:67], v[8:9]
	s_mov_b64 s[6:7], 0xa0000
	v_pk_mul_f32 v[6:7], v[60:61], v[6:7]
	v_pk_mul_f32 v[12:13], v[62:63], v[12:13]
	v_cvt_pk_bf16_f32 v4, v4, v5
	v_cvt_pk_bf16_f32 v5, v8, v9
	v_lshl_add_u64 v[8:9], v[2:3], 0, s[6:7]
	s_mov_b32 s6, 0xa0000
	v_mul_f32_e32 v11, 0xbfb8aa3b, v56
	v_cvt_pk_bf16_f32 v6, v6, v7
	v_cvt_pk_bf16_f32 v7, v12, v13
	v_add_co_u32_e32 v12, vcc, s6, v2
	v_exp_f32_e32 v11, v11
	s_nop 0
	v_addc_co_u32_e32 v13, vcc, 0, v3, vcc
	v_mul_f32_e32 v14, 0xbfb8aa3b, v52
	global_store_dwordx4 v[12:13], v[4:7], off
	v_exp_f32_e32 v14, v14
	v_mul_f32_e32 v12, 0xbfb8aa3b, v54
	v_mul_f32_e32 v6, 0xbfb8aa3b, v57
	v_exp_f32_e32 v7, v6
	v_mul_f32_e32 v6, 0xbfb8aa3b, v53
	v_add_f32_e32 v4, 1.0, v11
	v_exp_f32_e32 v11, v6
	v_add_f32_e32 v5, 1.0, v14
	v_rcp_f32_e32 v6, v5
	v_add_f32_e32 v5, 1.0, v7
	v_add_f32_e32 v7, 1.0, v11
	v_mul_f32_e32 v11, 0xbfb8aa3b, v58
	v_exp_f32_e32 v11, v11
	v_exp_f32_e32 v13, v12
	v_mul_f32_e32 v14, 0xbfb8aa3b, v55
	v_exp_f32_e32 v15, v14
	v_add_f32_e32 v11, 1.0, v11
	v_rcp_f32_e32 v12, v11
	v_add_f32_e32 v11, 1.0, v13
	v_mul_f32_e32 v13, 0xbfb8aa3b, v59
	v_exp_f32_e32 v13, v13
	v_rcp_f32_e32 v14, v11
	v_rcp_f32_e32 v4, v4
	v_rcp_f32_e32 v5, v5
	v_add_f32_e32 v11, 1.0, v13
	v_rcp_f32_e32 v13, v11
	v_add_f32_e32 v11, 1.0, v15
	v_rcp_f32_e32 v7, v7
	v_rcp_f32_e32 v15, v11
	v_pk_mul_f32 v[4:5], v[56:57], v[4:5]
	v_pk_mul_f32 v[12:13], v[58:59], v[12:13]
	v_pk_mul_f32 v[6:7], v[52:53], v[6:7]
	v_pk_mul_f32 v[14:15], v[54:55], v[14:15]
	v_cvt_pk_bf16_f32 v4, v4, v5
	v_cvt_pk_bf16_f32 v5, v12, v13
	v_cvt_pk_bf16_f32 v6, v6, v7
	v_cvt_pk_bf16_f32 v7, v14, v15
	v_mul_f32_e32 v12, 0xbfb8aa3b, v44
	global_store_dwordx4 v[8:9], v[4:7], off offset:256
	v_mul_f32_e32 v11, 0xbfb8aa3b, v48
	v_exp_f32_e32 v12, v12
	v_mul_f32_e32 v6, 0xbfb8aa3b, v49
	v_exp_f32_e32 v7, v6
	v_mul_f32_e32 v6, 0xbfb8aa3b, v45
	v_exp_f32_e32 v11, v11
	v_exp_f32_e32 v8, v6
	v_add_f32_e32 v5, 1.0, v12
	v_mul_f32_e32 v9, 0xbfb8aa3b, v46
	v_add_f32_e32 v4, 1.0, v11
	v_rcp_f32_e32 v6, v5
	v_add_f32_e32 v5, 1.0, v7
	v_add_f32_e32 v7, 1.0, v8
	v_mul_f32_e32 v8, 0xbfb8aa3b, v50
	v_exp_f32_e32 v9, v9
	v_mul_f32_e32 v11, 0xbfb8aa3b, v51
	v_exp_f32_e32 v8, v8
	v_exp_f32_e32 v11, v11
	v_mul_f32_e32 v12, 0xbfb8aa3b, v47
	v_exp_f32_e32 v13, v12
	v_add_f32_e32 v9, 1.0, v9
	v_add_f32_e32 v8, 1.0, v8
	v_rcp_f32_e32 v12, v9
	v_add_f32_e32 v9, 1.0, v11
	v_rcp_f32_e32 v4, v4
	v_rcp_f32_e32 v5, v5
	v_rcp_f32_e32 v8, v8
	v_rcp_f32_e32 v9, v9
	v_add_f32_e32 v11, 1.0, v13
	v_rcp_f32_e32 v7, v7
	v_rcp_f32_e32 v13, v11
	v_pk_mul_f32 v[4:5], v[48:49], v[4:5]
	v_pk_mul_f32 v[8:9], v[50:51], v[8:9]
	s_mov_b64 s[6:7], 0xb0000
	v_cvt_pk_bf16_f32 v4, v4, v5
	v_cvt_pk_bf16_f32 v5, v8, v9
	v_lshl_add_u64 v[8:9], v[2:3], 0, s[6:7]
	s_mov_b32 s6, 0xb0000
	v_pk_mul_f32 v[6:7], v[44:45], v[6:7]
	v_pk_mul_f32 v[12:13], v[46:47], v[12:13]
	v_add_co_u32_e32 v2, vcc, s6, v2
	v_cvt_pk_bf16_f32 v6, v6, v7
	v_cvt_pk_bf16_f32 v7, v12, v13
	v_addc_co_u32_e32 v3, vcc, 0, v3, vcc
	v_mul_f32_e32 v12, 0xbfb8aa3b, v36
	global_store_dwordx4 v[2:3], v[4:7], off
	v_mul_f32_e32 v11, 0xbfb8aa3b, v40
	v_exp_f32_e32 v12, v12
	v_mul_f32_e32 v4, 0xbfb8aa3b, v41
	v_exp_f32_e32 v5, v4
	v_mul_f32_e32 v4, 0xbfb8aa3b, v37
	v_exp_f32_e32 v11, v11
	v_exp_f32_e32 v6, v4
	v_add_f32_e32 v3, 1.0, v12
	v_mul_f32_e32 v7, 0xbfb8aa3b, v38
	v_add_f32_e32 v2, 1.0, v11
	v_rcp_f32_e32 v4, v3
	v_add_f32_e32 v3, 1.0, v5
	v_add_f32_e32 v5, 1.0, v6
	v_mul_f32_e32 v6, 0xbfb8aa3b, v42
	v_exp_f32_e32 v7, v7
	v_mul_f32_e32 v11, 0xbfb8aa3b, v43
	v_mul_f32_e32 v12, 0xbfb8aa3b, v39
	v_exp_f32_e32 v6, v6
	v_exp_f32_e32 v11, v11
	v_exp_f32_e32 v13, v12
	v_add_f32_e32 v7, 1.0, v7
	v_add_f32_e32 v6, 1.0, v6
	v_rcp_f32_e32 v12, v7
	v_add_f32_e32 v7, 1.0, v11
	v_add_f32_e32 v11, 1.0, v13
	v_rcp_f32_e32 v2, v2
	v_rcp_f32_e32 v3, v3
	v_rcp_f32_e32 v5, v5
	v_rcp_f32_e32 v6, v6
	v_rcp_f32_e32 v7, v7
	v_rcp_f32_e32 v13, v11
	v_pk_mul_f32 v[2:3], v[40:41], v[2:3]
	v_pk_mul_f32 v[4:5], v[36:37], v[4:5]
	v_pk_mul_f32 v[6:7], v[42:43], v[6:7]
	v_pk_mul_f32 v[12:13], v[38:39], v[12:13]
	v_cvt_pk_bf16_f32 v2, v2, v3
	v_cvt_pk_bf16_f32 v3, v6, v7
	v_cvt_pk_bf16_f32 v4, v4, v5
	v_cvt_pk_bf16_f32 v5, v12, v13
	global_store_dwordx4 v[8:9], v[2:5], off offset:256

.LBB0_237:
	s_andn2_b64 vcc, exec, s[6:7]
	s_cbranch_vccnz .LBB0_239
	v_or_b32_e32 v6, 16, v10
	v_or_b32_e32 v2, 0xffffe000, v195
	v_ashrrev_i32_e32 v11, 31, v10
	v_ashrrev_i32_e32 v7, 31, v6
	v_lshl_add_u32 v2, s74, 8, v2
	v_lshlrev_b64 v[4:5], 13, v[10:11]
	v_mov_b32_e32 v3, v34
	v_lshlrev_b64 v[6:7], 13, v[6:7]
	v_lshl_add_u64 v[4:5], s[62:63], 0, v[4:5]
	v_lshlrev_b64 v[2:3], 2, v[2:3]
	v_lshl_add_u64 v[6:7], s[62:63], 0, v[6:7]
	v_lshl_add_u64 v[4:5], v[4:5], 0, v[2:3]
	v_lshl_add_u64 v[6:7], v[6:7], 0, v[2:3]
	global_store_dwordx4 v[4:5], v[160:163], off
	global_store_dwordx4 v[4:5], v[156:159], off offset:16
	global_store_dwordx4 v[4:5], v[152:155], off offset:512
	global_store_dwordx4 v[4:5], v[148:151], off offset:528
	global_store_dwordx4 v[6:7], v[144:147], off
	global_store_dwordx4 v[6:7], v[140:143], off offset:16
	global_store_dwordx4 v[6:7], v[136:139], off offset:512
	global_store_dwordx4 v[6:7], v[132:135], off offset:528
	v_or_b32_e32 v6, 32, v10
	v_ashrrev_i32_e32 v7, 31, v6
	v_lshlrev_b64 v[6:7], 13, v[6:7]
	v_lshl_add_u64 v[6:7], s[62:63], 0, v[6:7]
	v_lshl_add_u64 v[6:7], v[6:7], 0, v[2:3]
	global_store_dwordx4 v[6:7], v[128:131], off
	global_store_dwordx4 v[6:7], v[124:127], off offset:16
	global_store_dwordx4 v[6:7], v[120:123], off offset:512
	global_store_dwordx4 v[6:7], v[116:119], off offset:528
	v_or_b32_e32 v6, 48, v10
	v_ashrrev_i32_e32 v7, 31, v6
	v_lshlrev_b64 v[6:7], 13, v[6:7]
	v_lshl_add_u64 v[6:7], s[62:63], 0, v[6:7]
	v_lshl_add_u64 v[2:3], v[6:7], 0, v[2:3]
	s_mov_b64 s[6:7], 0x100000
	global_store_dwordx4 v[2:3], v[112:115], off
	global_store_dwordx4 v[2:3], v[108:111], off offset:16
	global_store_dwordx4 v[2:3], v[104:107], off offset:512
	global_store_dwordx4 v[2:3], v[100:103], off offset:528
	v_lshl_add_u64 v[2:3], v[4:5], 0, s[6:7]
	s_mov_b32 s6, 0x100000
	v_add_co_u32_e32 v6, vcc, s6, v4
	s_mov_b64 s[6:7], 0x120000
	s_nop 0
	v_addc_co_u32_e32 v7, vcc, 0, v5, vcc
	global_store_dwordx4 v[6:7], v[96:99], off
	global_store_dwordx4 v[2:3], v[92:95], off offset:16
	global_store_dwordx4 v[2:3], v[88:91], off offset:512
	global_store_dwordx4 v[2:3], v[84:87], off offset:528
	v_lshl_add_u64 v[2:3], v[4:5], 0, s[6:7]
	s_mov_b32 s6, 0x120000
	v_add_co_u32_e32 v6, vcc, s6, v4
	s_mov_b64 s[6:7], 0x140000
	s_nop 0
	v_addc_co_u32_e32 v7, vcc, 0, v5, vcc
	global_store_dwordx4 v[6:7], v[80:83], off
	global_store_dwordx4 v[2:3], v[76:79], off offset:16
	global_store_dwordx4 v[2:3], v[72:75], off offset:512
	global_store_dwordx4 v[2:3], v[68:71], off offset:528
	v_add_co_u32_e32 v6, vcc, 0x140000, v4
	v_lshl_add_u64 v[2:3], v[4:5], 0, s[6:7]
	s_nop 0
	v_addc_co_u32_e32 v7, vcc, 0, v5, vcc
	s_mov_b64 s[6:7], 0x160000
	global_store_dwordx4 v[6:7], v[64:67], off
	global_store_dwordx4 v[2:3], v[60:63], off offset:16
	global_store_dwordx4 v[2:3], v[56:59], off offset:512
	global_store_dwordx4 v[2:3], v[52:55], off offset:528
	v_lshl_add_u64 v[2:3], v[4:5], 0, s[6:7]
	v_add_co_u32_e32 v4, vcc, 0x160000, v4
	s_nop 1
	v_addc_co_u32_e32 v5, vcc, 0, v5, vcc
	global_store_dwordx4 v[4:5], v[48:51], off
	global_store_dwordx4 v[2:3], v[44:47], off offset:16
	global_store_dwordx4 v[2:3], v[40:43], off offset:512
	global_store_dwordx4 v[2:3], v[36:39], off offset:528

.LBB0_240:
	s_andn2_b64 vcc, exec, s[6:7]
	s_cbranch_vccnz .LBB0_242
	v_mul_f32_e32 v3, 0xbfb8aa3b, v160
	v_exp_f32_e32 v3, v3
	v_mul_f32_e32 v6, 0xbfb8aa3b, v156
	v_exp_f32_e32 v6, v6
	v_ashrrev_i32_e32 v11, 31, v10
	v_lshlrev_b64 v[4:5], 12, v[10:11]
	v_lshl_add_u64 v[12:13], s[46:47], 0, v[4:5]
	v_add_f32_e32 v3, 1.0, v3
	v_mul_f32_e32 v5, 0xbfb8aa3b, v161
	v_rcp_f32_e32 v4, v3
	v_add_f32_e32 v3, 1.0, v6
	v_exp_f32_e32 v5, v5
	v_mul_f32_e32 v6, 0xbfb8aa3b, v157
	v_exp_f32_e32 v7, v6
	v_rcp_f32_e32 v6, v3
	v_add_f32_e32 v3, 1.0, v5
	v_rcp_f32_e32 v5, v3
	v_add_f32_e32 v3, 1.0, v7
	v_mul_f32_e32 v7, 0xbfb8aa3b, v162
	v_exp_f32_e32 v8, v7
	v_mul_f32_e32 v7, 0xbfb8aa3b, v158
	v_exp_f32_e32 v9, v7
	v_rcp_f32_e32 v7, v3
	v_add_f32_e32 v3, 1.0, v8
	v_rcp_f32_e32 v8, v3
	v_add_f32_e32 v3, 1.0, v9
	v_mul_f32_e32 v9, 0xbfb8aa3b, v163
	v_exp_f32_e32 v9, v9
	v_mul_f32_e32 v11, 0xbfb8aa3b, v159
	v_exp_f32_e32 v11, v11
	v_rcp_f32_e32 v14, v3
	v_add_f32_e32 v3, 1.0, v9
	v_rcp_f32_e32 v9, v3
	v_add_f32_e32 v3, 1.0, v11
	v_rcp_f32_e32 v15, v3
	v_lshl_add_u32 v2, s74, 8, v180
	v_pk_mul_f32 v[4:5], v[160:161], v[4:5]
	v_mov_b32_e32 v3, v34
	v_mul_f32_e32 v11, 0xbfb8aa3b, v152
	v_pk_mul_f32 v[16:17], v[156:157], v[6:7]
	v_pk_mul_f32 v[8:9], v[162:163], v[8:9]
	v_pk_mul_f32 v[14:15], v[158:159], v[14:15]
	v_cvt_pk_bf16_f32 v6, v4, v5
	v_lshlrev_b64 v[4:5], 1, v[2:3]
	v_exp_f32_e32 v11, v11
	v_cvt_pk_bf16_f32 v7, v8, v9
	v_cvt_pk_bf16_f32 v8, v16, v17
	v_cvt_pk_bf16_f32 v9, v14, v15
	v_lshl_add_u64 v[2:3], v[12:13], 0, v[4:5]
	v_mul_f32_e32 v12, 0xbfb8aa3b, v148
	global_store_dwordx4 v[2:3], v[6:9], off
	v_exp_f32_e32 v12, v12
	v_mul_f32_e32 v14, 0xbfb8aa3b, v151
	v_mul_f32_e32 v8, 0xbfb8aa3b, v153
	v_exp_f32_e32 v9, v8
	v_mul_f32_e32 v8, 0xbfb8aa3b, v149
	v_add_f32_e32 v6, 1.0, v11
	v_exp_f32_e32 v11, v8
	v_add_f32_e32 v7, 1.0, v12
	v_rcp_f32_e32 v8, v7
	v_add_f32_e32 v7, 1.0, v9
	v_add_f32_e32 v9, 1.0, v11
	v_mul_f32_e32 v11, 0xbfb8aa3b, v154
	v_exp_f32_e32 v11, v11
	v_mul_f32_e32 v12, 0xbfb8aa3b, v150
	v_exp_f32_e32 v13, v12
	v_exp_f32_e32 v15, v14
	v_add_f32_e32 v11, 1.0, v11
	v_rcp_f32_e32 v12, v11
	v_add_f32_e32 v11, 1.0, v13
	v_mul_f32_e32 v13, 0xbfb8aa3b, v155
	v_exp_f32_e32 v13, v13
	v_rcp_f32_e32 v14, v11
	v_rcp_f32_e32 v6, v6
	v_rcp_f32_e32 v7, v7
	v_add_f32_e32 v11, 1.0, v13
	v_rcp_f32_e32 v13, v11
	v_add_f32_e32 v11, 1.0, v15
	v_rcp_f32_e32 v9, v9
	v_rcp_f32_e32 v15, v11
	v_pk_mul_f32 v[6:7], v[152:153], v[6:7]
	v_pk_mul_f32 v[12:13], v[154:155], v[12:13]
	v_pk_mul_f32 v[8:9], v[148:149], v[8:9]
	v_pk_mul_f32 v[14:15], v[150:151], v[14:15]
	v_cvt_pk_bf16_f32 v6, v6, v7
	v_cvt_pk_bf16_f32 v7, v12, v13
	v_cvt_pk_bf16_f32 v8, v8, v9
	v_cvt_pk_bf16_f32 v9, v14, v15
	global_store_dwordx4 v[2:3], v[6:9], off offset:256
	v_mul_f32_e32 v14, 0xbfb8aa3b, v142
	v_exp_f32_e32 v15, v14
	v_mul_f32_e32 v8, 0xbfb8aa3b, v144
	v_exp_f32_e32 v8, v8
	v_mul_f32_e32 v9, 0xbfb8aa3b, v140
	v_or_b32_e32 v6, 16, v10
	v_exp_f32_e32 v9, v9
	v_ashrrev_i32_e32 v7, 31, v6
	v_lshlrev_b64 v[6:7], 12, v[6:7]
	v_lshl_add_u64 v[12:13], s[46:47], 0, v[6:7]
	v_add_f32_e32 v6, 1.0, v8
	v_mul_f32_e32 v8, 0xbfb8aa3b, v145
	v_add_f32_e32 v7, 1.0, v9
	v_exp_f32_e32 v9, v8
	v_mul_f32_e32 v8, 0xbfb8aa3b, v141
	v_exp_f32_e32 v11, v8
	v_rcp_f32_e32 v8, v7
	v_add_f32_e32 v7, 1.0, v9
	v_mul_f32_e32 v16, 0xbfb8aa3b, v143
	v_add_f32_e32 v9, 1.0, v11
	v_mul_f32_e32 v11, 0xbfb8aa3b, v146
	v_exp_f32_e32 v11, v11
	v_exp_f32_e32 v17, v16
	v_rcp_f32_e32 v6, v6
	v_rcp_f32_e32 v7, v7
	v_add_f32_e32 v11, 1.0, v11
	v_rcp_f32_e32 v14, v11
	v_add_f32_e32 v11, 1.0, v15
	v_mul_f32_e32 v15, 0xbfb8aa3b, v147
	v_exp_f32_e32 v15, v15
	v_rcp_f32_e32 v16, v11
	v_rcp_f32_e32 v9, v9
	v_pk_mul_f32 v[6:7], v[144:145], v[6:7]
	v_add_f32_e32 v11, 1.0, v15
	v_rcp_f32_e32 v15, v11
	v_add_f32_e32 v11, 1.0, v17
	v_rcp_f32_e32 v17, v11
	v_mul_f32_e32 v11, 0xbfb8aa3b, v136
	v_pk_mul_f32 v[8:9], v[140:141], v[8:9]
	v_pk_mul_f32 v[14:15], v[146:147], v[14:15]
	v_pk_mul_f32 v[16:17], v[142:143], v[16:17]
	v_exp_f32_e32 v11, v11
	v_cvt_pk_bf16_f32 v6, v6, v7
	v_cvt_pk_bf16_f32 v7, v14, v15
	v_cvt_pk_bf16_f32 v8, v8, v9
	v_cvt_pk_bf16_f32 v9, v16, v17
	v_lshl_add_u64 v[12:13], v[12:13], 0, v[4:5]
	v_mul_f32_e32 v14, 0xbfb8aa3b, v132
	global_store_dwordx4 v[12:13], v[6:9], off
	v_exp_f32_e32 v14, v14
	v_mul_f32_e32 v16, 0xbfb8aa3b, v135
	v_mul_f32_e32 v8, 0xbfb8aa3b, v137
	v_exp_f32_e32 v9, v8
	v_mul_f32_e32 v8, 0xbfb8aa3b, v133
	v_add_f32_e32 v6, 1.0, v11
	v_exp_f32_e32 v11, v8
	v_add_f32_e32 v7, 1.0, v14
	v_rcp_f32_e32 v8, v7
	v_add_f32_e32 v7, 1.0, v9
	v_add_f32_e32 v9, 1.0, v11
	v_mul_f32_e32 v11, 0xbfb8aa3b, v138
	v_exp_f32_e32 v11, v11
	v_mul_f32_e32 v14, 0xbfb8aa3b, v134
	v_exp_f32_e32 v15, v14
	v_exp_f32_e32 v17, v16
	v_add_f32_e32 v11, 1.0, v11
	v_rcp_f32_e32 v14, v11
	v_add_f32_e32 v11, 1.0, v15
	v_mul_f32_e32 v15, 0xbfb8aa3b, v139
	v_exp_f32_e32 v15, v15
	v_rcp_f32_e32 v16, v11
	v_rcp_f32_e32 v6, v6
	v_rcp_f32_e32 v7, v7
	v_add_f32_e32 v11, 1.0, v15
	v_rcp_f32_e32 v15, v11
	v_add_f32_e32 v11, 1.0, v17
	v_rcp_f32_e32 v9, v9
	v_rcp_f32_e32 v17, v11
	v_pk_mul_f32 v[6:7], v[136:137], v[6:7]
	v_pk_mul_f32 v[14:15], v[138:139], v[14:15]
	v_pk_mul_f32 v[8:9], v[132:133], v[8:9]
	v_pk_mul_f32 v[16:17], v[134:135], v[16:17]
	v_cvt_pk_bf16_f32 v6, v6, v7
	v_cvt_pk_bf16_f32 v7, v14, v15
	v_cvt_pk_bf16_f32 v8, v8, v9
	v_cvt_pk_bf16_f32 v9, v16, v17
	global_store_dwordx4 v[12:13], v[6:9], off offset:256
	v_mul_f32_e32 v14, 0xbfb8aa3b, v126
	v_exp_f32_e32 v15, v14
	v_mul_f32_e32 v8, 0xbfb8aa3b, v128
	v_exp_f32_e32 v8, v8
	v_mul_f32_e32 v9, 0xbfb8aa3b, v124
	v_or_b32_e32 v6, 32, v10
	v_exp_f32_e32 v9, v9
	v_ashrrev_i32_e32 v7, 31, v6
	v_lshlrev_b64 v[6:7], 12, v[6:7]
	v_lshl_add_u64 v[12:13], s[46:47], 0, v[6:7]
	v_add_f32_e32 v6, 1.0, v8
	v_mul_f32_e32 v8, 0xbfb8aa3b, v129
	v_add_f32_e32 v7, 1.0, v9
	v_exp_f32_e32 v9, v8
	v_mul_f32_e32 v8, 0xbfb8aa3b, v125
	v_exp_f32_e32 v11, v8
	v_rcp_f32_e32 v8, v7
	v_add_f32_e32 v7, 1.0, v9
	v_mul_f32_e32 v16, 0xbfb8aa3b, v127
	v_add_f32_e32 v9, 1.0, v11
	v_mul_f32_e32 v11, 0xbfb8aa3b, v130
	v_exp_f32_e32 v11, v11
	v_exp_f32_e32 v17, v16
	v_rcp_f32_e32 v6, v6
	v_rcp_f32_e32 v7, v7
	v_add_f32_e32 v11, 1.0, v11
	v_rcp_f32_e32 v14, v11
	v_add_f32_e32 v11, 1.0, v15
	v_mul_f32_e32 v15, 0xbfb8aa3b, v131
	v_exp_f32_e32 v15, v15
	v_rcp_f32_e32 v16, v11
	v_rcp_f32_e32 v9, v9
	v_pk_mul_f32 v[6:7], v[128:129], v[6:7]
	v_add_f32_e32 v11, 1.0, v15
	v_rcp_f32_e32 v15, v11
	v_add_f32_e32 v11, 1.0, v17
	v_rcp_f32_e32 v17, v11
	v_mul_f32_e32 v11, 0xbfb8aa3b, v120
	v_pk_mul_f32 v[8:9], v[124:125], v[8:9]
	v_pk_mul_f32 v[14:15], v[130:131], v[14:15]
	v_pk_mul_f32 v[16:17], v[126:127], v[16:17]
	v_exp_f32_e32 v11, v11
	v_cvt_pk_bf16_f32 v6, v6, v7
	v_cvt_pk_bf16_f32 v7, v14, v15
	v_cvt_pk_bf16_f32 v8, v8, v9
	v_cvt_pk_bf16_f32 v9, v16, v17
	v_lshl_add_u64 v[12:13], v[12:13], 0, v[4:5]
	v_mul_f32_e32 v14, 0xbfb8aa3b, v116
	global_store_dwordx4 v[12:13], v[6:9], off
	v_exp_f32_e32 v14, v14
	v_mul_f32_e32 v16, 0xbfb8aa3b, v119
	v_mul_f32_e32 v8, 0xbfb8aa3b, v121
	v_exp_f32_e32 v9, v8
	v_mul_f32_e32 v8, 0xbfb8aa3b, v117
	v_add_f32_e32 v6, 1.0, v11
	v_exp_f32_e32 v11, v8
	v_add_f32_e32 v7, 1.0, v14
	v_rcp_f32_e32 v8, v7
	v_add_f32_e32 v7, 1.0, v9
	v_add_f32_e32 v9, 1.0, v11
	v_mul_f32_e32 v11, 0xbfb8aa3b, v122
	v_exp_f32_e32 v11, v11
	v_mul_f32_e32 v14, 0xbfb8aa3b, v118
	v_exp_f32_e32 v15, v14
	v_exp_f32_e32 v17, v16
	v_add_f32_e32 v11, 1.0, v11
	v_rcp_f32_e32 v14, v11
	v_add_f32_e32 v11, 1.0, v15
	v_mul_f32_e32 v15, 0xbfb8aa3b, v123
	v_exp_f32_e32 v15, v15
	v_rcp_f32_e32 v16, v11
	v_rcp_f32_e32 v6, v6
	v_rcp_f32_e32 v7, v7
	v_add_f32_e32 v11, 1.0, v15
	v_rcp_f32_e32 v15, v11
	v_add_f32_e32 v11, 1.0, v17
	v_rcp_f32_e32 v9, v9
	v_rcp_f32_e32 v17, v11
	v_pk_mul_f32 v[6:7], v[120:121], v[6:7]
	v_pk_mul_f32 v[14:15], v[122:123], v[14:15]
	v_pk_mul_f32 v[8:9], v[116:117], v[8:9]
	v_pk_mul_f32 v[16:17], v[118:119], v[16:17]
	v_cvt_pk_bf16_f32 v6, v6, v7
	v_cvt_pk_bf16_f32 v7, v14, v15
	v_cvt_pk_bf16_f32 v8, v8, v9
	v_cvt_pk_bf16_f32 v9, v16, v17
	global_store_dwordx4 v[12:13], v[6:9], off offset:256
	v_mul_f32_e32 v14, 0xbfb8aa3b, v110
	v_exp_f32_e32 v15, v14
	v_mul_f32_e32 v8, 0xbfb8aa3b, v112
	v_exp_f32_e32 v8, v8
	v_mul_f32_e32 v9, 0xbfb8aa3b, v108
	v_or_b32_e32 v6, 48, v10
	v_exp_f32_e32 v9, v9
	v_ashrrev_i32_e32 v7, 31, v6
	v_lshlrev_b64 v[6:7], 12, v[6:7]
	v_lshl_add_u64 v[12:13], s[46:47], 0, v[6:7]
	v_add_f32_e32 v6, 1.0, v8
	v_mul_f32_e32 v8, 0xbfb8aa3b, v113
	v_add_f32_e32 v7, 1.0, v9
	v_exp_f32_e32 v9, v8
	v_mul_f32_e32 v8, 0xbfb8aa3b, v109
	v_exp_f32_e32 v11, v8
	v_rcp_f32_e32 v8, v7
	v_add_f32_e32 v7, 1.0, v9
	v_mul_f32_e32 v16, 0xbfb8aa3b, v111
	v_add_f32_e32 v9, 1.0, v11
	v_mul_f32_e32 v11, 0xbfb8aa3b, v114
	v_exp_f32_e32 v11, v11
	v_exp_f32_e32 v17, v16
	v_rcp_f32_e32 v6, v6
	v_rcp_f32_e32 v7, v7
	v_add_f32_e32 v11, 1.0, v11
	v_rcp_f32_e32 v14, v11
	v_add_f32_e32 v11, 1.0, v15
	v_mul_f32_e32 v15, 0xbfb8aa3b, v115
	v_exp_f32_e32 v15, v15
	v_rcp_f32_e32 v16, v11
	v_rcp_f32_e32 v9, v9
	v_pk_mul_f32 v[6:7], v[112:113], v[6:7]
	v_add_f32_e32 v11, 1.0, v15
	v_rcp_f32_e32 v15, v11
	v_add_f32_e32 v11, 1.0, v17
	v_rcp_f32_e32 v17, v11
	v_pk_mul_f32 v[8:9], v[108:109], v[8:9]
	v_pk_mul_f32 v[14:15], v[114:115], v[14:15]
	v_cvt_pk_bf16_f32 v6, v6, v7
	v_pk_mul_f32 v[16:17], v[110:111], v[16:17]
	v_cvt_pk_bf16_f32 v7, v14, v15
	v_cvt_pk_bf16_f32 v8, v8, v9
	v_cvt_pk_bf16_f32 v9, v16, v17
	v_lshl_add_u64 v[12:13], v[12:13], 0, v[4:5]
	v_mul_f32_e32 v5, 0xbfb8aa3b, v100
	global_store_dwordx4 v[12:13], v[6:9], off
	v_exp_f32_e32 v5, v5
	v_mul_f32_e32 v4, 0xbfb8aa3b, v104
	v_mul_f32_e32 v6, 0xbfb8aa3b, v105
	v_exp_f32_e32 v7, v6
	v_mul_f32_e32 v6, 0xbfb8aa3b, v101
	v_exp_f32_e32 v8, v6
	v_add_f32_e32 v5, 1.0, v5
	v_mul_f32_e32 v9, 0xbfb8aa3b, v102
	v_rcp_f32_e32 v6, v5
	v_add_f32_e32 v5, 1.0, v7
	v_add_f32_e32 v7, 1.0, v8
	v_mul_f32_e32 v8, 0xbfb8aa3b, v106
	v_exp_f32_e32 v9, v9
	v_mul_f32_e32 v11, 0xbfb8aa3b, v107
	v_exp_f32_e32 v4, v4
	v_exp_f32_e32 v8, v8
	v_exp_f32_e32 v11, v11
	v_mul_f32_e32 v14, 0xbfb8aa3b, v103
	v_exp_f32_e32 v15, v14
	v_add_f32_e32 v9, 1.0, v9
	v_add_f32_e32 v4, 1.0, v4
	v_add_f32_e32 v8, 1.0, v8
	v_rcp_f32_e32 v14, v9
	v_add_f32_e32 v9, 1.0, v11
	v_rcp_f32_e32 v4, v4
	v_rcp_f32_e32 v5, v5
	v_rcp_f32_e32 v8, v8
	v_rcp_f32_e32 v9, v9
	v_add_f32_e32 v11, 1.0, v15
	v_rcp_f32_e32 v7, v7
	v_rcp_f32_e32 v15, v11
	v_pk_mul_f32 v[4:5], v[104:105], v[4:5]
	v_pk_mul_f32 v[8:9], v[106:107], v[8:9]
	v_cvt_pk_bf16_f32 v4, v4, v5
	v_cvt_pk_bf16_f32 v5, v8, v9
	v_mul_f32_e32 v8, 0xbfb8aa3b, v96
	v_pk_mul_f32 v[6:7], v[100:101], v[6:7]
	v_pk_mul_f32 v[14:15], v[102:103], v[14:15]
	v_exp_f32_e32 v8, v8
	v_cvt_pk_bf16_f32 v6, v6, v7
	v_cvt_pk_bf16_f32 v7, v14, v15
	v_mul_f32_e32 v9, 0xbfb8aa3b, v92
	global_store_dwordx4 v[12:13], v[4:7], off offset:256
	v_exp_f32_e32 v9, v9
	v_mul_f32_e32 v11, 0xbfb8aa3b, v99
	v_mul_f32_e32 v6, 0xbfb8aa3b, v97
	v_exp_f32_e32 v7, v6
	v_mul_f32_e32 v6, 0xbfb8aa3b, v93
	v_add_f32_e32 v4, 1.0, v8
	v_exp_f32_e32 v8, v6
	v_add_f32_e32 v5, 1.0, v9
	v_mul_f32_e32 v9, 0xbfb8aa3b, v94
	v_rcp_f32_e32 v6, v5
	v_add_f32_e32 v5, 1.0, v7
	v_add_f32_e32 v7, 1.0, v8
	v_mul_f32_e32 v8, 0xbfb8aa3b, v98
	v_exp_f32_e32 v9, v9
	v_exp_f32_e32 v8, v8
	v_exp_f32_e32 v11, v11
	v_mul_f32_e32 v12, 0xbfb8aa3b, v95
	v_exp_f32_e32 v13, v12
	v_add_f32_e32 v9, 1.0, v9
	v_add_f32_e32 v8, 1.0, v8
	v_rcp_f32_e32 v12, v9
	v_add_f32_e32 v9, 1.0, v11
	v_rcp_f32_e32 v4, v4
	v_rcp_f32_e32 v5, v5
	v_rcp_f32_e32 v8, v8
	v_rcp_f32_e32 v9, v9
	v_add_f32_e32 v11, 1.0, v13
	v_rcp_f32_e32 v7, v7
	v_rcp_f32_e32 v13, v11
	v_pk_mul_f32 v[4:5], v[96:97], v[4:5]
	v_pk_mul_f32 v[8:9], v[98:99], v[8:9]
	s_mov_b64 s[6:7], 0x80000
	v_pk_mul_f32 v[6:7], v[92:93], v[6:7]
	v_pk_mul_f32 v[12:13], v[94:95], v[12:13]
	v_cvt_pk_bf16_f32 v4, v4, v5
	v_cvt_pk_bf16_f32 v5, v8, v9
	v_lshl_add_u64 v[8:9], v[2:3], 0, s[6:7]
	s_mov_b32 s6, 0x80000
	v_mul_f32_e32 v11, 0xbfb8aa3b, v88
	v_cvt_pk_bf16_f32 v6, v6, v7
	v_cvt_pk_bf16_f32 v7, v12, v13
	v_add_co_u32_e32 v12, vcc, s6, v2
	v_exp_f32_e32 v11, v11
	s_nop 0
	v_addc_co_u32_e32 v13, vcc, 0, v3, vcc
	v_mul_f32_e32 v14, 0xbfb8aa3b, v84
	global_store_dwordx4 v[12:13], v[4:7], off
	v_exp_f32_e32 v14, v14
	v_mul_f32_e32 v12, 0xbfb8aa3b, v86
	v_mul_f32_e32 v6, 0xbfb8aa3b, v89
	v_exp_f32_e32 v7, v6
	v_mul_f32_e32 v6, 0xbfb8aa3b, v85
	v_add_f32_e32 v4, 1.0, v11
	v_exp_f32_e32 v11, v6
	v_add_f32_e32 v5, 1.0, v14
	v_rcp_f32_e32 v6, v5
	v_add_f32_e32 v5, 1.0, v7
	v_add_f32_e32 v7, 1.0, v11
	v_mul_f32_e32 v11, 0xbfb8aa3b, v90
	v_exp_f32_e32 v11, v11
	v_exp_f32_e32 v13, v12
	v_mul_f32_e32 v14, 0xbfb8aa3b, v87
	v_exp_f32_e32 v15, v14
	v_add_f32_e32 v11, 1.0, v11
	v_rcp_f32_e32 v12, v11
	v_add_f32_e32 v11, 1.0, v13
	v_mul_f32_e32 v13, 0xbfb8aa3b, v91
	v_exp_f32_e32 v13, v13
	v_rcp_f32_e32 v14, v11
	v_rcp_f32_e32 v4, v4
	v_rcp_f32_e32 v5, v5
	v_add_f32_e32 v11, 1.0, v13
	v_rcp_f32_e32 v13, v11
	v_add_f32_e32 v11, 1.0, v15
	v_rcp_f32_e32 v7, v7
	v_rcp_f32_e32 v15, v11
	v_pk_mul_f32 v[4:5], v[88:89], v[4:5]
	v_pk_mul_f32 v[12:13], v[90:91], v[12:13]
	v_pk_mul_f32 v[6:7], v[84:85], v[6:7]
	v_pk_mul_f32 v[14:15], v[86:87], v[14:15]
	v_cvt_pk_bf16_f32 v4, v4, v5
	v_cvt_pk_bf16_f32 v5, v12, v13
	v_cvt_pk_bf16_f32 v6, v6, v7
	v_cvt_pk_bf16_f32 v7, v14, v15
	v_mul_f32_e32 v12, 0xbfb8aa3b, v76
	global_store_dwordx4 v[8:9], v[4:7], off offset:256
	v_mul_f32_e32 v11, 0xbfb8aa3b, v80
	v_exp_f32_e32 v12, v12
	v_mul_f32_e32 v6, 0xbfb8aa3b, v81
	v_exp_f32_e32 v7, v6
	v_mul_f32_e32 v6, 0xbfb8aa3b, v77
	v_exp_f32_e32 v11, v11
	v_exp_f32_e32 v8, v6
	v_add_f32_e32 v5, 1.0, v12
	v_mul_f32_e32 v9, 0xbfb8aa3b, v78
	v_add_f32_e32 v4, 1.0, v11
	v_rcp_f32_e32 v6, v5
	v_add_f32_e32 v5, 1.0, v7
	v_add_f32_e32 v7, 1.0, v8
	v_mul_f32_e32 v8, 0xbfb8aa3b, v82
	v_exp_f32_e32 v9, v9
	v_mul_f32_e32 v11, 0xbfb8aa3b, v83
	v_exp_f32_e32 v8, v8
	v_exp_f32_e32 v11, v11
	v_mul_f32_e32 v12, 0xbfb8aa3b, v79
	v_exp_f32_e32 v13, v12
	v_add_f32_e32 v9, 1.0, v9
	v_add_f32_e32 v8, 1.0, v8
	v_rcp_f32_e32 v12, v9
	v_add_f32_e32 v9, 1.0, v11
	v_rcp_f32_e32 v4, v4
	v_rcp_f32_e32 v5, v5
	v_rcp_f32_e32 v8, v8
	v_rcp_f32_e32 v9, v9
	v_add_f32_e32 v11, 1.0, v13
	v_rcp_f32_e32 v7, v7
	v_rcp_f32_e32 v13, v11
	v_pk_mul_f32 v[4:5], v[80:81], v[4:5]
	v_pk_mul_f32 v[8:9], v[82:83], v[8:9]
	s_mov_b64 s[6:7], 0x90000
	v_pk_mul_f32 v[6:7], v[76:77], v[6:7]
	v_pk_mul_f32 v[12:13], v[78:79], v[12:13]
	v_cvt_pk_bf16_f32 v4, v4, v5
	v_cvt_pk_bf16_f32 v5, v8, v9
	v_lshl_add_u64 v[8:9], v[2:3], 0, s[6:7]
	s_mov_b32 s6, 0x90000
	v_mul_f32_e32 v11, 0xbfb8aa3b, v72
	v_cvt_pk_bf16_f32 v6, v6, v7
	v_cvt_pk_bf16_f32 v7, v12, v13
	v_add_co_u32_e32 v12, vcc, s6, v2
	v_exp_f32_e32 v11, v11
	s_nop 0
	v_addc_co_u32_e32 v13, vcc, 0, v3, vcc
	v_mul_f32_e32 v14, 0xbfb8aa3b, v68
	global_store_dwordx4 v[12:13], v[4:7], off
	v_exp_f32_e32 v14, v14
	v_mul_f32_e32 v12, 0xbfb8aa3b, v70
	v_mul_f32_e32 v6, 0xbfb8aa3b, v73
	v_exp_f32_e32 v7, v6
	v_mul_f32_e32 v6, 0xbfb8aa3b, v69
	v_add_f32_e32 v4, 1.0, v11
	v_exp_f32_e32 v11, v6
	v_add_f32_e32 v5, 1.0, v14
	v_rcp_f32_e32 v6, v5
	v_add_f32_e32 v5, 1.0, v7
	v_add_f32_e32 v7, 1.0, v11
	v_mul_f32_e32 v11, 0xbfb8aa3b, v74
	v_exp_f32_e32 v11, v11
	v_exp_f32_e32 v13, v12
	v_mul_f32_e32 v14, 0xbfb8aa3b, v71
	v_exp_f32_e32 v15, v14
	v_add_f32_e32 v11, 1.0, v11
	v_rcp_f32_e32 v12, v11
	v_add_f32_e32 v11, 1.0, v13
	v_mul_f32_e32 v13, 0xbfb8aa3b, v75
	v_exp_f32_e32 v13, v13
	v_rcp_f32_e32 v14, v11
	v_rcp_f32_e32 v4, v4
	v_rcp_f32_e32 v5, v5
	v_add_f32_e32 v11, 1.0, v13
	v_rcp_f32_e32 v13, v11
	v_add_f32_e32 v11, 1.0, v15
	v_rcp_f32_e32 v7, v7
	v_rcp_f32_e32 v15, v11
	v_pk_mul_f32 v[4:5], v[72:73], v[4:5]
	v_pk_mul_f32 v[12:13], v[74:75], v[12:13]
	v_pk_mul_f32 v[6:7], v[68:69], v[6:7]
	v_pk_mul_f32 v[14:15], v[70:71], v[14:15]
	v_cvt_pk_bf16_f32 v4, v4, v5
	v_cvt_pk_bf16_f32 v5, v12, v13
	v_cvt_pk_bf16_f32 v6, v6, v7
	v_cvt_pk_bf16_f32 v7, v14, v15
	v_mul_f32_e32 v12, 0xbfb8aa3b, v60
	global_store_dwordx4 v[8:9], v[4:7], off offset:256
	v_mul_f32_e32 v11, 0xbfb8aa3b, v64
	v_exp_f32_e32 v12, v12
	v_mul_f32_e32 v6, 0xbfb8aa3b, v65
	v_exp_f32_e32 v7, v6
	v_mul_f32_e32 v6, 0xbfb8aa3b, v61
	v_exp_f32_e32 v11, v11
	v_exp_f32_e32 v8, v6
	v_add_f32_e32 v5, 1.0, v12
	v_mul_f32_e32 v9, 0xbfb8aa3b, v62
	v_add_f32_e32 v4, 1.0, v11
	v_rcp_f32_e32 v6, v5
	v_add_f32_e32 v5, 1.0, v7
	v_add_f32_e32 v7, 1.0, v8
	v_mul_f32_e32 v8, 0xbfb8aa3b, v66
	v_exp_f32_e32 v9, v9
	v_mul_f32_e32 v11, 0xbfb8aa3b, v67
	v_exp_f32_e32 v8, v8
	v_exp_f32_e32 v11, v11
	v_mul_f32_e32 v12, 0xbfb8aa3b, v63
	v_exp_f32_e32 v13, v12
	v_add_f32_e32 v9, 1.0, v9
	v_add_f32_e32 v8, 1.0, v8
	v_rcp_f32_e32 v12, v9
	v_add_f32_e32 v9, 1.0, v11
	v_rcp_f32_e32 v4, v4
	v_rcp_f32_e32 v5, v5
	v_rcp_f32_e32 v8, v8
	v_rcp_f32_e32 v9, v9
	v_add_f32_e32 v11, 1.0, v13
	v_rcp_f32_e32 v7, v7
	v_rcp_f32_e32 v13, v11
	v_pk_mul_f32 v[4:5], v[64:65], v[4:5]
	v_pk_mul_f32 v[8:9], v[66:67], v[8:9]
	s_mov_b64 s[6:7], 0xa0000
	v_pk_mul_f32 v[6:7], v[60:61], v[6:7]
	v_pk_mul_f32 v[12:13], v[62:63], v[12:13]
	v_cvt_pk_bf16_f32 v4, v4, v5
	v_cvt_pk_bf16_f32 v5, v8, v9
	v_lshl_add_u64 v[8:9], v[2:3], 0, s[6:7]
	s_mov_b32 s6, 0xa0000
	v_mul_f32_e32 v11, 0xbfb8aa3b, v56
	v_cvt_pk_bf16_f32 v6, v6, v7
	v_cvt_pk_bf16_f32 v7, v12, v13
	v_add_co_u32_e32 v12, vcc, s6, v2
	v_exp_f32_e32 v11, v11
	s_nop 0
	v_addc_co_u32_e32 v13, vcc, 0, v3, vcc
	v_mul_f32_e32 v14, 0xbfb8aa3b, v52
	global_store_dwordx4 v[12:13], v[4:7], off
	v_exp_f32_e32 v14, v14
	v_mul_f32_e32 v12, 0xbfb8aa3b, v54
	v_mul_f32_e32 v6, 0xbfb8aa3b, v57
	v_exp_f32_e32 v7, v6
	v_mul_f32_e32 v6, 0xbfb8aa3b, v53
	v_add_f32_e32 v4, 1.0, v11
	v_exp_f32_e32 v11, v6
	v_add_f32_e32 v5, 1.0, v14
	v_rcp_f32_e32 v6, v5
	v_add_f32_e32 v5, 1.0, v7
	v_add_f32_e32 v7, 1.0, v11
	v_mul_f32_e32 v11, 0xbfb8aa3b, v58
	v_exp_f32_e32 v11, v11
	v_exp_f32_e32 v13, v12
	v_mul_f32_e32 v14, 0xbfb8aa3b, v55
	v_exp_f32_e32 v15, v14
	v_add_f32_e32 v11, 1.0, v11
	v_rcp_f32_e32 v12, v11
	v_add_f32_e32 v11, 1.0, v13
	v_mul_f32_e32 v13, 0xbfb8aa3b, v59
	v_exp_f32_e32 v13, v13
	v_rcp_f32_e32 v14, v11
	v_rcp_f32_e32 v4, v4
	v_rcp_f32_e32 v5, v5
	v_add_f32_e32 v11, 1.0, v13
	v_rcp_f32_e32 v13, v11
	v_add_f32_e32 v11, 1.0, v15
	v_rcp_f32_e32 v7, v7
	v_rcp_f32_e32 v15, v11
	v_pk_mul_f32 v[4:5], v[56:57], v[4:5]
	v_pk_mul_f32 v[12:13], v[58:59], v[12:13]
	v_pk_mul_f32 v[6:7], v[52:53], v[6:7]
	v_pk_mul_f32 v[14:15], v[54:55], v[14:15]
	v_cvt_pk_bf16_f32 v4, v4, v5
	v_cvt_pk_bf16_f32 v5, v12, v13
	v_cvt_pk_bf16_f32 v6, v6, v7
	v_cvt_pk_bf16_f32 v7, v14, v15
	v_mul_f32_e32 v12, 0xbfb8aa3b, v44
	global_store_dwordx4 v[8:9], v[4:7], off offset:256
	v_mul_f32_e32 v11, 0xbfb8aa3b, v48
	v_exp_f32_e32 v12, v12
	v_mul_f32_e32 v6, 0xbfb8aa3b, v49
	v_exp_f32_e32 v7, v6
	v_mul_f32_e32 v6, 0xbfb8aa3b, v45
	v_exp_f32_e32 v11, v11
	v_exp_f32_e32 v8, v6
	v_add_f32_e32 v5, 1.0, v12
	v_mul_f32_e32 v9, 0xbfb8aa3b, v46
	v_add_f32_e32 v4, 1.0, v11
	v_rcp_f32_e32 v6, v5
	v_add_f32_e32 v5, 1.0, v7
	v_add_f32_e32 v7, 1.0, v8
	v_mul_f32_e32 v8, 0xbfb8aa3b, v50
	v_exp_f32_e32 v9, v9
	v_mul_f32_e32 v11, 0xbfb8aa3b, v51
	v_exp_f32_e32 v8, v8
	v_exp_f32_e32 v11, v11
	v_mul_f32_e32 v12, 0xbfb8aa3b, v47
	v_exp_f32_e32 v13, v12
	v_add_f32_e32 v9, 1.0, v9
	v_add_f32_e32 v8, 1.0, v8
	v_rcp_f32_e32 v12, v9
	v_add_f32_e32 v9, 1.0, v11
	v_rcp_f32_e32 v4, v4
	v_rcp_f32_e32 v5, v5
	v_rcp_f32_e32 v8, v8
	v_rcp_f32_e32 v9, v9
	v_add_f32_e32 v11, 1.0, v13
	v_rcp_f32_e32 v7, v7
	v_rcp_f32_e32 v13, v11
	v_pk_mul_f32 v[4:5], v[48:49], v[4:5]
	v_pk_mul_f32 v[8:9], v[50:51], v[8:9]
	s_mov_b64 s[6:7], 0xb0000
	v_cvt_pk_bf16_f32 v4, v4, v5
	v_cvt_pk_bf16_f32 v5, v8, v9
	v_lshl_add_u64 v[8:9], v[2:3], 0, s[6:7]
	s_mov_b32 s6, 0xb0000
	v_pk_mul_f32 v[6:7], v[44:45], v[6:7]
	v_pk_mul_f32 v[12:13], v[46:47], v[12:13]
	v_add_co_u32_e32 v2, vcc, s6, v2
	v_cvt_pk_bf16_f32 v6, v6, v7
	v_cvt_pk_bf16_f32 v7, v12, v13
	v_addc_co_u32_e32 v3, vcc, 0, v3, vcc
	v_mul_f32_e32 v12, 0xbfb8aa3b, v36
	global_store_dwordx4 v[2:3], v[4:7], off
	v_mul_f32_e32 v11, 0xbfb8aa3b, v40
	v_exp_f32_e32 v12, v12
	v_mul_f32_e32 v4, 0xbfb8aa3b, v41
	v_exp_f32_e32 v5, v4
	v_mul_f32_e32 v4, 0xbfb8aa3b, v37
	v_exp_f32_e32 v11, v11
	v_exp_f32_e32 v6, v4
	v_add_f32_e32 v3, 1.0, v12
	v_mul_f32_e32 v7, 0xbfb8aa3b, v38
	v_add_f32_e32 v2, 1.0, v11
	v_rcp_f32_e32 v4, v3
	v_add_f32_e32 v3, 1.0, v5
	v_add_f32_e32 v5, 1.0, v6
	v_mul_f32_e32 v6, 0xbfb8aa3b, v42
	v_exp_f32_e32 v7, v7
	v_mul_f32_e32 v11, 0xbfb8aa3b, v43
	v_mul_f32_e32 v12, 0xbfb8aa3b, v39
	v_exp_f32_e32 v6, v6
	v_exp_f32_e32 v11, v11
	v_exp_f32_e32 v13, v12
	v_add_f32_e32 v7, 1.0, v7
	v_add_f32_e32 v6, 1.0, v6
	v_rcp_f32_e32 v12, v7
	v_add_f32_e32 v7, 1.0, v11
	v_add_f32_e32 v11, 1.0, v13
	v_rcp_f32_e32 v2, v2
	v_rcp_f32_e32 v3, v3
	v_rcp_f32_e32 v5, v5
	v_rcp_f32_e32 v6, v6
	v_rcp_f32_e32 v7, v7
	v_rcp_f32_e32 v13, v11
	v_pk_mul_f32 v[2:3], v[40:41], v[2:3]
	v_pk_mul_f32 v[4:5], v[36:37], v[4:5]
	v_pk_mul_f32 v[6:7], v[42:43], v[6:7]
	v_pk_mul_f32 v[12:13], v[38:39], v[12:13]
	v_cvt_pk_bf16_f32 v2, v2, v3
	v_cvt_pk_bf16_f32 v3, v6, v7
	v_cvt_pk_bf16_f32 v4, v4, v5
	v_cvt_pk_bf16_f32 v5, v12, v13
	global_store_dwordx4 v[8:9], v[2:5], off offset:256

.LBB0_243:
	s_andn2_b64 vcc, exec, s[6:7]
	s_cbranch_vccnz .LBB0_245
	v_ashrrev_i32_e32 v11, 31, v10
	v_lshl_add_u32 v6, s74, 8, v204
	v_lshlrev_b64 v[2:3], 12, v[10:11]
	v_mov_b32_e32 v7, v34
	v_lshl_add_u64 v[8:9], s[44:45], 0, v[2:3]
	v_lshlrev_b64 v[6:7], 1, v[6:7]
	v_cvt_pk_bf16_f32 v2, v160, v161
	v_cvt_pk_bf16_f32 v3, v162, v163
	v_cvt_pk_bf16_f32 v4, v156, v157
	v_cvt_pk_bf16_f32 v5, v158, v159
	v_lshl_add_u64 v[8:9], v[8:9], 0, v[6:7]
	global_store_dwordx4 v[8:9], v[2:5], off
	s_mov_b64 s[6:7], 0x80000
	s_nop 0
	v_cvt_pk_bf16_f32 v2, v152, v153
	v_cvt_pk_bf16_f32 v3, v154, v155
	v_cvt_pk_bf16_f32 v4, v148, v149
	v_cvt_pk_bf16_f32 v5, v150, v151
	global_store_dwordx4 v[8:9], v[2:5], off offset:256
	s_nop 1
	v_or_b32_e32 v2, 16, v10
	v_ashrrev_i32_e32 v3, 31, v2
	v_lshlrev_b64 v[2:3], 12, v[2:3]
	v_lshl_add_u64 v[12:13], s[44:45], 0, v[2:3]
	v_cvt_pk_bf16_f32 v2, v144, v145
	v_cvt_pk_bf16_f32 v3, v146, v147
	v_cvt_pk_bf16_f32 v4, v140, v141
	v_cvt_pk_bf16_f32 v5, v142, v143
	v_lshl_add_u64 v[12:13], v[12:13], 0, v[6:7]
	global_store_dwordx4 v[12:13], v[2:5], off
	s_nop 1
	v_cvt_pk_bf16_f32 v2, v136, v137
	v_cvt_pk_bf16_f32 v3, v138, v139
	v_cvt_pk_bf16_f32 v4, v132, v133
	v_cvt_pk_bf16_f32 v5, v134, v135
	global_store_dwordx4 v[12:13], v[2:5], off offset:256
	s_nop 1
	v_or_b32_e32 v2, 32, v10
	v_ashrrev_i32_e32 v3, 31, v2
	v_lshlrev_b64 v[2:3], 12, v[2:3]
	v_lshl_add_u64 v[12:13], s[44:45], 0, v[2:3]
	v_cvt_pk_bf16_f32 v2, v128, v129
	v_cvt_pk_bf16_f32 v3, v130, v131
	v_cvt_pk_bf16_f32 v4, v124, v125
	v_cvt_pk_bf16_f32 v5, v126, v127
	v_lshl_add_u64 v[12:13], v[12:13], 0, v[6:7]
	global_store_dwordx4 v[12:13], v[2:5], off
	s_nop 1
	v_cvt_pk_bf16_f32 v2, v120, v121
	v_cvt_pk_bf16_f32 v3, v122, v123
	v_cvt_pk_bf16_f32 v4, v116, v117
	v_cvt_pk_bf16_f32 v5, v118, v119
	global_store_dwordx4 v[12:13], v[2:5], off offset:256
	s_nop 1
	v_or_b32_e32 v2, 48, v10
	v_ashrrev_i32_e32 v3, 31, v2
	v_lshlrev_b64 v[2:3], 12, v[2:3]
	v_lshl_add_u64 v[12:13], s[44:45], 0, v[2:3]
	v_cvt_pk_bf16_f32 v2, v112, v113
	v_cvt_pk_bf16_f32 v3, v114, v115
	v_cvt_pk_bf16_f32 v4, v108, v109
	v_cvt_pk_bf16_f32 v5, v110, v111
	v_lshl_add_u64 v[6:7], v[12:13], 0, v[6:7]
	global_store_dwordx4 v[6:7], v[2:5], off
	s_nop 1
	v_cvt_pk_bf16_f32 v2, v104, v105
	v_cvt_pk_bf16_f32 v3, v106, v107
	v_cvt_pk_bf16_f32 v4, v100, v101
	v_cvt_pk_bf16_f32 v5, v102, v103
	global_store_dwordx4 v[6:7], v[2:5], off offset:256
	v_lshl_add_u64 v[6:7], v[8:9], 0, s[6:7]
	s_mov_b32 s6, 0x80000
	v_add_co_u32_e32 v12, vcc, s6, v8
	v_cvt_pk_bf16_f32 v2, v96, v97
	v_cvt_pk_bf16_f32 v3, v98, v99
	v_cvt_pk_bf16_f32 v4, v92, v93
	v_cvt_pk_bf16_f32 v5, v94, v95
	v_addc_co_u32_e32 v13, vcc, 0, v9, vcc
	global_store_dwordx4 v[12:13], v[2:5], off
	s_mov_b64 s[6:7], 0x90000
	s_nop 0
	v_cvt_pk_bf16_f32 v2, v88, v89
	v_cvt_pk_bf16_f32 v3, v90, v91
	v_cvt_pk_bf16_f32 v4, v84, v85
	v_cvt_pk_bf16_f32 v5, v86, v87
	global_store_dwordx4 v[6:7], v[2:5], off offset:256
	v_lshl_add_u64 v[6:7], v[8:9], 0, s[6:7]
	s_mov_b32 s6, 0x90000
	v_add_co_u32_e32 v12, vcc, s6, v8
	v_cvt_pk_bf16_f32 v2, v80, v81
	v_cvt_pk_bf16_f32 v3, v82, v83
	v_cvt_pk_bf16_f32 v4, v76, v77
	v_cvt_pk_bf16_f32 v5, v78, v79
	v_addc_co_u32_e32 v13, vcc, 0, v9, vcc
	global_store_dwordx4 v[12:13], v[2:5], off
	s_mov_b64 s[6:7], 0xa0000
	s_nop 0
	v_cvt_pk_bf16_f32 v2, v72, v73
	v_cvt_pk_bf16_f32 v3, v74, v75
	v_cvt_pk_bf16_f32 v4, v68, v69
	v_cvt_pk_bf16_f32 v5, v70, v71
	global_store_dwordx4 v[6:7], v[2:5], off offset:256
	v_lshl_add_u64 v[6:7], v[8:9], 0, s[6:7]
	s_mov_b32 s6, 0xa0000
	v_add_co_u32_e32 v12, vcc, s6, v8
	v_cvt_pk_bf16_f32 v2, v64, v65
	v_cvt_pk_bf16_f32 v3, v66, v67
	v_cvt_pk_bf16_f32 v4, v60, v61
	v_cvt_pk_bf16_f32 v5, v62, v63
	v_addc_co_u32_e32 v13, vcc, 0, v9, vcc
	global_store_dwordx4 v[12:13], v[2:5], off
	s_mov_b64 s[6:7], 0xb0000
	s_nop 0
	v_cvt_pk_bf16_f32 v2, v56, v57
	v_cvt_pk_bf16_f32 v3, v58, v59
	v_cvt_pk_bf16_f32 v4, v52, v53
	v_cvt_pk_bf16_f32 v5, v54, v55
	global_store_dwordx4 v[6:7], v[2:5], off offset:256
	v_lshl_add_u64 v[6:7], v[8:9], 0, s[6:7]
	s_mov_b32 s6, 0xb0000
	v_add_co_u32_e32 v8, vcc, s6, v8
	v_cvt_pk_bf16_f32 v2, v48, v49
	v_cvt_pk_bf16_f32 v3, v50, v51
	v_cvt_pk_bf16_f32 v4, v44, v45
	v_cvt_pk_bf16_f32 v5, v46, v47
	v_addc_co_u32_e32 v9, vcc, 0, v9, vcc
	global_store_dwordx4 v[8:9], v[2:5], off
	s_nop 1
	v_cvt_pk_bf16_f32 v2, v40, v41
	v_cvt_pk_bf16_f32 v3, v42, v43
	v_cvt_pk_bf16_f32 v4, v36, v37
	v_cvt_pk_bf16_f32 v5, v38, v39
	global_store_dwordx4 v[6:7], v[2:5], off offset:256

.LBB0_267:
	v_ashrrev_i32_e32 v11, 31, v10
	s_waitcnt vmcnt(0)
	v_lshlrev_b64 v[2:3], 13, v[10:11]
	v_lshl_add_u64 v[12:13], s[60:61], 0, v[2:3]
	v_mul_f32_e32 v2, 0xbfb8aa3b, v160
	v_exp_f32_e32 v2, v2
	v_sub_f32_e32 v186, 1.0, v32
	s_mov_b32 s7, 0x800000
	s_mov_b32 s8, 0x3f317217
	v_add_f32_e32 v2, 1.0, v2
	v_rcp_f32_e32 v2, v2
	s_mov_b32 s9, 0x7f800000
	v_sub_f32_e32 v11, 1.0, v33
	v_sub_f32_e32 v188, 1.0, v30
	v_fma_f32 v2, v2, v186, v32
	v_max_f32_e32 v2, 0x358637bd, v2
	v_cmp_gt_f32_e32 vcc, s7, v2
	v_sub_f32_e32 v187, 1.0, v31
	v_sub_f32_e32 v190, 1.0, v28
	v_cndmask_b32_e64 v3, 0, 32, vcc
	v_ldexp_f32 v2, v2, v3
	v_log_f32_e32 v2, v2
	v_sub_f32_e32 v189, 1.0, v29
	v_sub_f32_e32 v191, 1.0, v24
	v_sub_f32_e32 v192, 1.0, v26
	v_mul_f32_e32 v3, 0x3f317217, v2
	v_fma_f32 v3, v2, s8, -v3
	v_fmac_f32_e32 v3, 0x3377d1cf, v2
	v_fmac_f32_e32 v3, 0x3f317217, v2
	v_cmp_lt_f32_e64 s[40:41], |v2|, s9
	v_lshl_add_u64 v[12:13], v[12:13], 0, v[14:15]
	v_sub_f32_e32 v193, 1.0, v25
	v_cndmask_b32_e64 v2, v2, v3, s[40:41]
	v_cndmask_b32_e32 v3, 0, v226, vcc
	v_sub_f32_e32 v2, v2, v3
	v_mul_f32_e32 v3, 0xbfb8aa3b, v156
	v_exp_f32_e32 v3, v3
	v_sub_f32_e32 v207, 1.0, v27
	v_sub_f32_e32 v209, 1.0, v22
	v_sub_f32_e32 v208, 1.0, v23
	v_add_f32_e32 v3, 1.0, v3
	v_rcp_f32_e32 v3, v3
	v_sub_f32_e32 v211, 1.0, v20
	v_sub_f32_e32 v210, 1.0, v21
	v_sub_f32_e32 v212, 1.0, v18
	v_fma_f32 v3, v3, v11, v33
	v_max_f32_e32 v3, 0x358637bd, v3
	v_cmp_gt_f32_e32 vcc, s7, v3
	v_sub_f32_e32 v213, 1.0, v19
	s_mov_b32 s6, 0x100000
	v_cndmask_b32_e64 v4, 0, 32, vcc
	v_ldexp_f32 v3, v3, v4
	v_log_f32_e32 v3, v3
	s_mov_b64 s[10:11], 0x100000
	v_mul_f32_e32 v4, 0x3f317217, v3
	v_fma_f32 v4, v3, s8, -v4
	v_fmac_f32_e32 v4, 0x3377d1cf, v3
	v_fmac_f32_e32 v4, 0x3f317217, v3
	v_cmp_lt_f32_e64 s[40:41], |v3|, s9
	s_nop 1
	v_cndmask_b32_e64 v3, v3, v4, s[40:41]
	v_cndmask_b32_e32 v4, 0, v226, vcc
	v_sub_f32_e32 v6, v3, v4
	v_mul_f32_e32 v3, 0xbfb8aa3b, v161
	v_exp_f32_e32 v3, v3
	s_nop 0
	v_add_f32_e32 v3, 1.0, v3
	v_rcp_f32_e32 v3, v3
	s_nop 0
	v_fma_f32 v3, v3, v188, v30
	v_max_f32_e32 v3, 0x358637bd, v3
	v_cmp_gt_f32_e32 vcc, s7, v3
	s_nop 1
	v_cndmask_b32_e64 v4, 0, 32, vcc
	v_ldexp_f32 v3, v3, v4
	v_log_f32_e32 v3, v3
	s_nop 0
	v_mul_f32_e32 v4, 0x3f317217, v3
	v_fma_f32 v4, v3, s8, -v4
	v_fmac_f32_e32 v4, 0x3377d1cf, v3
	v_fmac_f32_e32 v4, 0x3f317217, v3
	v_cmp_lt_f32_e64 s[40:41], |v3|, s9
	s_nop 1
	v_cndmask_b32_e64 v3, v3, v4, s[40:41]
	v_cndmask_b32_e32 v4, 0, v226, vcc
	v_sub_f32_e32 v3, v3, v4
	v_mul_f32_e32 v4, 0xbfb8aa3b, v157
	v_exp_f32_e32 v4, v4
	s_nop 0
	v_add_f32_e32 v4, 1.0, v4
	v_rcp_f32_e32 v4, v4
	s_nop 0
	v_fma_f32 v4, v4, v187, v31
	v_max_f32_e32 v4, 0x358637bd, v4
	v_cmp_gt_f32_e32 vcc, s7, v4
	s_nop 1
	v_cndmask_b32_e64 v5, 0, 32, vcc
	v_ldexp_f32 v4, v4, v5
	v_log_f32_e32 v4, v4
	s_nop 0
	v_mul_f32_e32 v5, 0x3f317217, v4
	v_fma_f32 v5, v4, s8, -v5
	v_fmac_f32_e32 v5, 0x3377d1cf, v4
	v_fmac_f32_e32 v5, 0x3f317217, v4
	v_cmp_lt_f32_e64 s[40:41], |v4|, s9
	s_nop 1
	v_cndmask_b32_e64 v4, v4, v5, s[40:41]
	v_cndmask_b32_e32 v5, 0, v226, vcc
	v_sub_f32_e32 v7, v4, v5
	v_mul_f32_e32 v4, 0xbfb8aa3b, v162
	v_exp_f32_e32 v4, v4
	s_nop 0
	v_add_f32_e32 v4, 1.0, v4
	v_rcp_f32_e32 v4, v4
	s_nop 0
	v_fma_f32 v4, v4, v190, v28
	v_max_f32_e32 v4, 0x358637bd, v4
	v_cmp_gt_f32_e32 vcc, s7, v4
	s_nop 1
	v_cndmask_b32_e64 v5, 0, 32, vcc
	v_ldexp_f32 v4, v4, v5
	v_log_f32_e32 v4, v4
	s_nop 0
	v_mul_f32_e32 v5, 0x3f317217, v4
	v_fma_f32 v5, v4, s8, -v5
	v_fmac_f32_e32 v5, 0x3377d1cf, v4
	v_fmac_f32_e32 v5, 0x3f317217, v4
	v_cmp_lt_f32_e64 s[40:41], |v4|, s9
	s_nop 1
	v_cndmask_b32_e64 v4, v4, v5, s[40:41]
	v_cndmask_b32_e32 v5, 0, v226, vcc
	v_sub_f32_e32 v4, v4, v5
	v_mul_f32_e32 v5, 0xbfb8aa3b, v158
	v_exp_f32_e32 v5, v5
	s_nop 0
	v_add_f32_e32 v5, 1.0, v5
	v_rcp_f32_e32 v5, v5
	s_nop 0
	v_fma_f32 v5, v5, v189, v29
	v_max_f32_e32 v5, 0x358637bd, v5
	v_cmp_gt_f32_e32 vcc, s7, v5
	s_nop 1
	v_cndmask_b32_e64 v8, 0, 32, vcc
	v_ldexp_f32 v5, v5, v8
	v_log_f32_e32 v5, v5
	s_nop 0
	v_mul_f32_e32 v8, 0x3f317217, v5
	v_fma_f32 v8, v5, s8, -v8
	v_fmac_f32_e32 v8, 0x3377d1cf, v5
	v_fmac_f32_e32 v8, 0x3f317217, v5
	v_cmp_lt_f32_e64 s[40:41], |v5|, s9
	s_nop 1
	v_cndmask_b32_e64 v5, v5, v8, s[40:41]
	v_cndmask_b32_e32 v8, 0, v226, vcc
	v_sub_f32_e32 v8, v5, v8
	v_mul_f32_e32 v5, 0xbfb8aa3b, v163
	v_exp_f32_e32 v5, v5
	s_nop 0
	v_add_f32_e32 v5, 1.0, v5
	v_rcp_f32_e32 v5, v5
	s_nop 0
	v_fma_f32 v5, v5, v191, v24
	v_max_f32_e32 v5, 0x358637bd, v5
	v_cmp_gt_f32_e32 vcc, s7, v5
	s_nop 1
	v_cndmask_b32_e64 v9, 0, 32, vcc
	v_ldexp_f32 v5, v5, v9
	v_log_f32_e32 v5, v5
	s_nop 0
	v_mul_f32_e32 v9, 0x3f317217, v5
	v_fma_f32 v9, v5, s8, -v9
	v_fmac_f32_e32 v9, 0x3377d1cf, v5
	v_fmac_f32_e32 v9, 0x3f317217, v5
	v_cmp_lt_f32_e64 s[40:41], |v5|, s9
	s_nop 1
	v_cndmask_b32_e64 v5, v5, v9, s[40:41]
	v_cndmask_b32_e32 v9, 0, v226, vcc
	v_sub_f32_e32 v5, v5, v9
	v_mul_f32_e32 v9, 0xbfb8aa3b, v159
	v_exp_f32_e32 v9, v9
	s_nop 0
	v_add_f32_e32 v9, 1.0, v9
	v_rcp_f32_e32 v9, v9
	s_nop 0
	v_fma_f32 v9, v9, v192, v26
	v_max_f32_e32 v9, 0x358637bd, v9
	v_cmp_gt_f32_e32 vcc, s7, v9
	s_nop 1
	v_cndmask_b32_e64 v16, 0, 32, vcc
	v_ldexp_f32 v9, v9, v16
	v_log_f32_e32 v9, v9
	s_nop 0
	v_mul_f32_e32 v16, 0x3f317217, v9
	v_fma_f32 v16, v9, s8, -v16
	v_fmac_f32_e32 v16, 0x3377d1cf, v9
	v_fmac_f32_e32 v16, 0x3f317217, v9
	v_cmp_lt_f32_e64 s[40:41], |v9|, s9
	s_nop 1
	v_cndmask_b32_e64 v9, v9, v16, s[40:41]
	v_cndmask_b32_e32 v16, 0, v226, vcc
	v_sub_f32_e32 v9, v9, v16
	global_store_dwordx4 v[12:13], v[2:5], off
	global_store_dwordx4 v[12:13], v[6:9], off offset:16
	s_nop 0
	v_mul_f32_e32 v2, 0xbfb8aa3b, v152
	v_exp_f32_e32 v2, v2
	s_nop 0
	v_add_f32_e32 v2, 1.0, v2
	v_rcp_f32_e32 v2, v2
	s_nop 0
	v_fma_f32 v2, v2, v193, v25
	v_max_f32_e32 v2, 0x358637bd, v2
	v_cmp_gt_f32_e32 vcc, s7, v2
	s_nop 1
	v_cndmask_b32_e64 v3, 0, 32, vcc
	v_ldexp_f32 v2, v2, v3
	v_log_f32_e32 v2, v2
	s_nop 0
	v_mul_f32_e32 v3, 0x3f317217, v2
	v_fma_f32 v3, v2, s8, -v3
	v_fmac_f32_e32 v3, 0x3377d1cf, v2
	v_fmac_f32_e32 v3, 0x3f317217, v2
	v_cmp_lt_f32_e64 s[40:41], |v2|, s9
	s_nop 1
	v_cndmask_b32_e64 v2, v2, v3, s[40:41]
	v_cndmask_b32_e32 v3, 0, v226, vcc
	v_sub_f32_e32 v2, v2, v3
	v_mul_f32_e32 v3, 0xbfb8aa3b, v148
	v_exp_f32_e32 v3, v3
	s_nop 0
	v_add_f32_e32 v3, 1.0, v3
	v_rcp_f32_e32 v3, v3
	s_nop 0
	v_fma_f32 v3, v3, v207, v27
	v_max_f32_e32 v3, 0x358637bd, v3
	v_cmp_gt_f32_e32 vcc, s7, v3
	s_nop 1
	v_cndmask_b32_e64 v4, 0, 32, vcc
	v_ldexp_f32 v3, v3, v4
	v_log_f32_e32 v3, v3
	s_nop 0
	v_mul_f32_e32 v4, 0x3f317217, v3
	v_fma_f32 v4, v3, s8, -v4
	v_fmac_f32_e32 v4, 0x3377d1cf, v3
	v_fmac_f32_e32 v4, 0x3f317217, v3
	v_cmp_lt_f32_e64 s[40:41], |v3|, s9
	s_nop 1
	v_cndmask_b32_e64 v3, v3, v4, s[40:41]
	v_cndmask_b32_e32 v4, 0, v226, vcc
	v_sub_f32_e32 v6, v3, v4
	v_mul_f32_e32 v3, 0xbfb8aa3b, v153
	v_exp_f32_e32 v3, v3
	s_nop 0
	v_add_f32_e32 v3, 1.0, v3
	v_rcp_f32_e32 v3, v3
	s_nop 0
	v_fma_f32 v3, v3, v209, v22
	v_max_f32_e32 v3, 0x358637bd, v3
	v_cmp_gt_f32_e32 vcc, s7, v3
	s_nop 1
	v_cndmask_b32_e64 v4, 0, 32, vcc
	v_ldexp_f32 v3, v3, v4
	v_log_f32_e32 v3, v3
	s_nop 0
	v_mul_f32_e32 v4, 0x3f317217, v3
	v_fma_f32 v4, v3, s8, -v4
	v_fmac_f32_e32 v4, 0x3377d1cf, v3
	v_fmac_f32_e32 v4, 0x3f317217, v3
	v_cmp_lt_f32_e64 s[40:41], |v3|, s9
	s_nop 1
	v_cndmask_b32_e64 v3, v3, v4, s[40:41]
	v_cndmask_b32_e32 v4, 0, v226, vcc
	v_sub_f32_e32 v3, v3, v4
	v_mul_f32_e32 v4, 0xbfb8aa3b, v149
	v_exp_f32_e32 v4, v4
	s_nop 0
	v_add_f32_e32 v4, 1.0, v4
	v_rcp_f32_e32 v4, v4
	s_nop 0
	v_fma_f32 v4, v4, v208, v23
	v_max_f32_e32 v4, 0x358637bd, v4
	v_cmp_gt_f32_e32 vcc, s7, v4
	s_nop 1
	v_cndmask_b32_e64 v5, 0, 32, vcc
	v_ldexp_f32 v4, v4, v5
	v_log_f32_e32 v4, v4
	s_nop 0
	v_mul_f32_e32 v5, 0x3f317217, v4
	v_fma_f32 v5, v4, s8, -v5
	v_fmac_f32_e32 v5, 0x3377d1cf, v4
	v_fmac_f32_e32 v5, 0x3f317217, v4
	v_cmp_lt_f32_e64 s[40:41], |v4|, s9
	s_nop 1
	v_cndmask_b32_e64 v4, v4, v5, s[40:41]
	v_cndmask_b32_e32 v5, 0, v226, vcc
	v_sub_f32_e32 v7, v4, v5
	v_mul_f32_e32 v4, 0xbfb8aa3b, v154
	v_exp_f32_e32 v4, v4
	s_nop 0
	v_add_f32_e32 v4, 1.0, v4
	v_rcp_f32_e32 v4, v4
	s_nop 0
	v_fma_f32 v4, v4, v211, v20
	v_max_f32_e32 v4, 0x358637bd, v4
	v_cmp_gt_f32_e32 vcc, s7, v4
	s_nop 1
	v_cndmask_b32_e64 v5, 0, 32, vcc
	v_ldexp_f32 v4, v4, v5
	v_log_f32_e32 v4, v4
	s_nop 0
	v_mul_f32_e32 v5, 0x3f317217, v4
	v_fma_f32 v5, v4, s8, -v5
	v_fmac_f32_e32 v5, 0x3377d1cf, v4
	v_fmac_f32_e32 v5, 0x3f317217, v4
	v_cmp_lt_f32_e64 s[40:41], |v4|, s9
	s_nop 1
	v_cndmask_b32_e64 v4, v4, v5, s[40:41]
	v_cndmask_b32_e32 v5, 0, v226, vcc
	v_sub_f32_e32 v4, v4, v5
	v_mul_f32_e32 v5, 0xbfb8aa3b, v150
	v_exp_f32_e32 v5, v5
	s_nop 0
	v_add_f32_e32 v5, 1.0, v5
	v_rcp_f32_e32 v5, v5
	s_nop 0
	v_fma_f32 v5, v5, v210, v21
	v_max_f32_e32 v5, 0x358637bd, v5
	v_cmp_gt_f32_e32 vcc, s7, v5
	s_nop 1
	v_cndmask_b32_e64 v8, 0, 32, vcc
	v_ldexp_f32 v5, v5, v8
	v_log_f32_e32 v5, v5
	s_nop 0
	v_mul_f32_e32 v8, 0x3f317217, v5
	v_fma_f32 v8, v5, s8, -v8
	v_fmac_f32_e32 v8, 0x3377d1cf, v5
	v_fmac_f32_e32 v8, 0x3f317217, v5
	v_cmp_lt_f32_e64 s[40:41], |v5|, s9
	s_nop 1
	v_cndmask_b32_e64 v5, v5, v8, s[40:41]
	v_cndmask_b32_e32 v8, 0, v226, vcc
	v_sub_f32_e32 v8, v5, v8
	v_mul_f32_e32 v5, 0xbfb8aa3b, v155
	v_exp_f32_e32 v5, v5
	s_nop 0
	v_add_f32_e32 v5, 1.0, v5
	v_rcp_f32_e32 v5, v5
	s_nop 0
	v_fma_f32 v5, v5, v212, v18
	v_max_f32_e32 v5, 0x358637bd, v5
	v_cmp_gt_f32_e32 vcc, s7, v5
	s_nop 1
	v_cndmask_b32_e64 v9, 0, 32, vcc
	v_ldexp_f32 v5, v5, v9
	v_log_f32_e32 v5, v5
	s_nop 0
	v_mul_f32_e32 v9, 0x3f317217, v5
	v_fma_f32 v9, v5, s8, -v9
	v_fmac_f32_e32 v9, 0x3377d1cf, v5
	v_fmac_f32_e32 v9, 0x3f317217, v5
	v_cmp_lt_f32_e64 s[40:41], |v5|, s9
	s_nop 1
	v_cndmask_b32_e64 v5, v5, v9, s[40:41]
	v_cndmask_b32_e32 v9, 0, v226, vcc
	v_sub_f32_e32 v5, v5, v9
	v_mul_f32_e32 v9, 0xbfb8aa3b, v151
	v_exp_f32_e32 v9, v9
	s_nop 0
	v_add_f32_e32 v9, 1.0, v9
	v_rcp_f32_e32 v9, v9
	s_nop 0
	v_fma_f32 v9, v9, v213, v19
	v_max_f32_e32 v9, 0x358637bd, v9
	v_cmp_gt_f32_e32 vcc, s7, v9
	s_nop 1
	v_cndmask_b32_e64 v16, 0, 32, vcc
	v_ldexp_f32 v9, v9, v16
	v_log_f32_e32 v9, v9
	s_nop 0
	v_mul_f32_e32 v16, 0x3f317217, v9
	v_fma_f32 v16, v9, s8, -v16
	v_fmac_f32_e32 v16, 0x3377d1cf, v9
	v_fmac_f32_e32 v16, 0x3f317217, v9
	v_cmp_lt_f32_e64 s[40:41], |v9|, s9
	s_nop 1
	v_cndmask_b32_e64 v9, v9, v16, s[40:41]
	v_cndmask_b32_e32 v16, 0, v226, vcc
	v_sub_f32_e32 v9, v9, v16
	global_store_dwordx4 v[12:13], v[2:5], off offset:512
	global_store_dwordx4 v[12:13], v[6:9], off offset:528
	s_nop 0
	v_or_b32_e32 v2, 16, v10
	v_ashrrev_i32_e32 v3, 31, v2
	v_lshlrev_b64 v[2:3], 13, v[2:3]
	v_lshl_add_u64 v[16:17], s[60:61], 0, v[2:3]
	v_mul_f32_e32 v2, 0xbfb8aa3b, v144
	v_exp_f32_e32 v2, v2
	v_lshl_add_u64 v[16:17], v[16:17], 0, v[14:15]
	v_add_f32_e32 v2, 1.0, v2
	v_rcp_f32_e32 v2, v2
	s_nop 0
	v_fma_f32 v2, v2, v186, v32
	v_max_f32_e32 v2, 0x358637bd, v2
	v_cmp_gt_f32_e32 vcc, s7, v2
	s_nop 1
	v_cndmask_b32_e64 v3, 0, 32, vcc
	v_ldexp_f32 v2, v2, v3
	v_log_f32_e32 v2, v2
	s_nop 0
	v_mul_f32_e32 v3, 0x3f317217, v2
	v_fma_f32 v3, v2, s8, -v3
	v_fmac_f32_e32 v3, 0x3377d1cf, v2
	v_fmac_f32_e32 v3, 0x3f317217, v2
	v_cmp_lt_f32_e64 s[40:41], |v2|, s9
	s_nop 1
	v_cndmask_b32_e64 v2, v2, v3, s[40:41]
	v_cndmask_b32_e32 v3, 0, v226, vcc
	v_sub_f32_e32 v2, v2, v3
	v_mul_f32_e32 v3, 0xbfb8aa3b, v140
	v_exp_f32_e32 v3, v3
	s_nop 0
	v_add_f32_e32 v3, 1.0, v3
	v_rcp_f32_e32 v3, v3
	s_nop 0
	v_fma_f32 v3, v3, v11, v33
	v_max_f32_e32 v3, 0x358637bd, v3
	v_cmp_gt_f32_e32 vcc, s7, v3
	s_nop 1
	v_cndmask_b32_e64 v4, 0, 32, vcc
	v_ldexp_f32 v3, v3, v4
	v_log_f32_e32 v3, v3
	s_nop 0
	v_mul_f32_e32 v4, 0x3f317217, v3
	v_fma_f32 v4, v3, s8, -v4
	v_fmac_f32_e32 v4, 0x3377d1cf, v3
	v_fmac_f32_e32 v4, 0x3f317217, v3
	v_cmp_lt_f32_e64 s[40:41], |v3|, s9
	s_nop 1
	v_cndmask_b32_e64 v3, v3, v4, s[40:41]
	v_cndmask_b32_e32 v4, 0, v226, vcc
	v_sub_f32_e32 v6, v3, v4
	v_mul_f32_e32 v3, 0xbfb8aa3b, v145
	v_exp_f32_e32 v3, v3
	s_nop 0
	v_add_f32_e32 v3, 1.0, v3
	v_rcp_f32_e32 v3, v3
	s_nop 0
	v_fma_f32 v3, v3, v188, v30
	v_max_f32_e32 v3, 0x358637bd, v3
	v_cmp_gt_f32_e32 vcc, s7, v3
	s_nop 1
	v_cndmask_b32_e64 v4, 0, 32, vcc
	v_ldexp_f32 v3, v3, v4
	v_log_f32_e32 v3, v3
	s_nop 0
	v_mul_f32_e32 v4, 0x3f317217, v3
	v_fma_f32 v4, v3, s8, -v4
	v_fmac_f32_e32 v4, 0x3377d1cf, v3
	v_fmac_f32_e32 v4, 0x3f317217, v3
	v_cmp_lt_f32_e64 s[40:41], |v3|, s9
	s_nop 1
	v_cndmask_b32_e64 v3, v3, v4, s[40:41]
	v_cndmask_b32_e32 v4, 0, v226, vcc
	v_sub_f32_e32 v3, v3, v4
	v_mul_f32_e32 v4, 0xbfb8aa3b, v141
	v_exp_f32_e32 v4, v4
	s_nop 0
	v_add_f32_e32 v4, 1.0, v4
	v_rcp_f32_e32 v4, v4
	s_nop 0
	v_fma_f32 v4, v4, v187, v31
	v_max_f32_e32 v4, 0x358637bd, v4
	v_cmp_gt_f32_e32 vcc, s7, v4
	s_nop 1
	v_cndmask_b32_e64 v5, 0, 32, vcc
	v_ldexp_f32 v4, v4, v5
	v_log_f32_e32 v4, v4
	s_nop 0
	v_mul_f32_e32 v5, 0x3f317217, v4
	v_fma_f32 v5, v4, s8, -v5
	v_fmac_f32_e32 v5, 0x3377d1cf, v4
	v_fmac_f32_e32 v5, 0x3f317217, v4
	v_cmp_lt_f32_e64 s[40:41], |v4|, s9
	s_nop 1
	v_cndmask_b32_e64 v4, v4, v5, s[40:41]
	v_cndmask_b32_e32 v5, 0, v226, vcc
	v_sub_f32_e32 v7, v4, v5
	v_mul_f32_e32 v4, 0xbfb8aa3b, v146
	v_exp_f32_e32 v4, v4
	s_nop 0
	v_add_f32_e32 v4, 1.0, v4
	v_rcp_f32_e32 v4, v4
	s_nop 0
	v_fma_f32 v4, v4, v190, v28
	v_max_f32_e32 v4, 0x358637bd, v4
	v_cmp_gt_f32_e32 vcc, s7, v4
	s_nop 1
	v_cndmask_b32_e64 v5, 0, 32, vcc
	v_ldexp_f32 v4, v4, v5
	v_log_f32_e32 v4, v4
	s_nop 0
	v_mul_f32_e32 v5, 0x3f317217, v4
	v_fma_f32 v5, v4, s8, -v5
	v_fmac_f32_e32 v5, 0x3377d1cf, v4
	v_fmac_f32_e32 v5, 0x3f317217, v4
	v_cmp_lt_f32_e64 s[40:41], |v4|, s9
	s_nop 1
	v_cndmask_b32_e64 v4, v4, v5, s[40:41]
	v_cndmask_b32_e32 v5, 0, v226, vcc
	v_sub_f32_e32 v4, v4, v5
	v_mul_f32_e32 v5, 0xbfb8aa3b, v142
	v_exp_f32_e32 v5, v5
	s_nop 0
	v_add_f32_e32 v5, 1.0, v5
	v_rcp_f32_e32 v5, v5
	s_nop 0
	v_fma_f32 v5, v5, v189, v29
	v_max_f32_e32 v5, 0x358637bd, v5
	v_cmp_gt_f32_e32 vcc, s7, v5
	s_nop 1
	v_cndmask_b32_e64 v8, 0, 32, vcc
	v_ldexp_f32 v5, v5, v8
	v_log_f32_e32 v5, v5
	s_nop 0
	v_mul_f32_e32 v8, 0x3f317217, v5
	v_fma_f32 v8, v5, s8, -v8
	v_fmac_f32_e32 v8, 0x3377d1cf, v5
	v_fmac_f32_e32 v8, 0x3f317217, v5
	v_cmp_lt_f32_e64 s[40:41], |v5|, s9
	s_nop 1
	v_cndmask_b32_e64 v5, v5, v8, s[40:41]
	v_cndmask_b32_e32 v8, 0, v226, vcc
	v_sub_f32_e32 v8, v5, v8
	v_mul_f32_e32 v5, 0xbfb8aa3b, v147
	v_exp_f32_e32 v5, v5
	s_nop 0
	v_add_f32_e32 v5, 1.0, v5
	v_rcp_f32_e32 v5, v5
	s_nop 0
	v_fma_f32 v5, v5, v191, v24
	v_max_f32_e32 v5, 0x358637bd, v5
	v_cmp_gt_f32_e32 vcc, s7, v5
	s_nop 1
	v_cndmask_b32_e64 v9, 0, 32, vcc
	v_ldexp_f32 v5, v5, v9
	v_log_f32_e32 v5, v5
	s_nop 0
	v_mul_f32_e32 v9, 0x3f317217, v5
	v_fma_f32 v9, v5, s8, -v9
	v_fmac_f32_e32 v9, 0x3377d1cf, v5
	v_fmac_f32_e32 v9, 0x3f317217, v5
	v_cmp_lt_f32_e64 s[40:41], |v5|, s9
	s_nop 1
	v_cndmask_b32_e64 v5, v5, v9, s[40:41]
	v_cndmask_b32_e32 v9, 0, v226, vcc
	v_sub_f32_e32 v5, v5, v9
	v_mul_f32_e32 v9, 0xbfb8aa3b, v143
	v_exp_f32_e32 v9, v9
	s_nop 0
	v_add_f32_e32 v9, 1.0, v9
	v_rcp_f32_e32 v9, v9
	s_nop 0
	v_fma_f32 v9, v9, v192, v26
	v_max_f32_e32 v9, 0x358637bd, v9
	v_cmp_gt_f32_e32 vcc, s7, v9
	s_nop 1
	v_cndmask_b32_e64 v196, 0, 32, vcc
	v_ldexp_f32 v9, v9, v196
	v_log_f32_e32 v9, v9
	s_nop 0
	v_mul_f32_e32 v196, 0x3f317217, v9
	v_fma_f32 v196, v9, s8, -v196
	v_fmac_f32_e32 v196, 0x3377d1cf, v9
	v_fmac_f32_e32 v196, 0x3f317217, v9
	v_cmp_lt_f32_e64 s[40:41], |v9|, s9
	s_nop 1
	v_cndmask_b32_e64 v9, v9, v196, s[40:41]
	v_cndmask_b32_e32 v196, 0, v226, vcc
	v_sub_f32_e32 v9, v9, v196
	global_store_dwordx4 v[16:17], v[2:5], off
	global_store_dwordx4 v[16:17], v[6:9], off offset:16
	s_nop 0
	v_mul_f32_e32 v2, 0xbfb8aa3b, v136
	v_exp_f32_e32 v2, v2
	s_nop 0
	v_add_f32_e32 v2, 1.0, v2
	v_rcp_f32_e32 v2, v2
	s_nop 0
	v_fma_f32 v2, v2, v193, v25
	v_max_f32_e32 v2, 0x358637bd, v2
	v_cmp_gt_f32_e32 vcc, s7, v2
	s_nop 1
	v_cndmask_b32_e64 v3, 0, 32, vcc
	v_ldexp_f32 v2, v2, v3
	v_log_f32_e32 v2, v2
	s_nop 0
	v_mul_f32_e32 v3, 0x3f317217, v2
	v_fma_f32 v3, v2, s8, -v3
	v_fmac_f32_e32 v3, 0x3377d1cf, v2
	v_fmac_f32_e32 v3, 0x3f317217, v2
	v_cmp_lt_f32_e64 s[40:41], |v2|, s9
	s_nop 1
	v_cndmask_b32_e64 v2, v2, v3, s[40:41]
	v_cndmask_b32_e32 v3, 0, v226, vcc
	v_sub_f32_e32 v2, v2, v3
	v_mul_f32_e32 v3, 0xbfb8aa3b, v132
	v_exp_f32_e32 v3, v3
	s_nop 0
	v_add_f32_e32 v3, 1.0, v3
	v_rcp_f32_e32 v3, v3
	s_nop 0
	v_fma_f32 v3, v3, v207, v27
	v_max_f32_e32 v3, 0x358637bd, v3
	v_cmp_gt_f32_e32 vcc, s7, v3
	s_nop 1
	v_cndmask_b32_e64 v4, 0, 32, vcc
	v_ldexp_f32 v3, v3, v4
	v_log_f32_e32 v3, v3
	s_nop 0
	v_mul_f32_e32 v4, 0x3f317217, v3
	v_fma_f32 v4, v3, s8, -v4
	v_fmac_f32_e32 v4, 0x3377d1cf, v3
	v_fmac_f32_e32 v4, 0x3f317217, v3
	v_cmp_lt_f32_e64 s[40:41], |v3|, s9
	s_nop 1
	v_cndmask_b32_e64 v3, v3, v4, s[40:41]
	v_cndmask_b32_e32 v4, 0, v226, vcc
	v_sub_f32_e32 v6, v3, v4
	v_mul_f32_e32 v3, 0xbfb8aa3b, v137
	v_exp_f32_e32 v3, v3
	s_nop 0
	v_add_f32_e32 v3, 1.0, v3
	v_rcp_f32_e32 v3, v3
	s_nop 0
	v_fma_f32 v3, v3, v209, v22
	v_max_f32_e32 v3, 0x358637bd, v3
	v_cmp_gt_f32_e32 vcc, s7, v3
	s_nop 1
	v_cndmask_b32_e64 v4, 0, 32, vcc
	v_ldexp_f32 v3, v3, v4
	v_log_f32_e32 v3, v3
	s_nop 0
	v_mul_f32_e32 v4, 0x3f317217, v3
	v_fma_f32 v4, v3, s8, -v4
	v_fmac_f32_e32 v4, 0x3377d1cf, v3
	v_fmac_f32_e32 v4, 0x3f317217, v3
	v_cmp_lt_f32_e64 s[40:41], |v3|, s9
	s_nop 1
	v_cndmask_b32_e64 v3, v3, v4, s[40:41]
	v_cndmask_b32_e32 v4, 0, v226, vcc
	v_sub_f32_e32 v3, v3, v4
	v_mul_f32_e32 v4, 0xbfb8aa3b, v133
	v_exp_f32_e32 v4, v4
	s_nop 0
	v_add_f32_e32 v4, 1.0, v4
	v_rcp_f32_e32 v4, v4
	s_nop 0
	v_fma_f32 v4, v4, v208, v23
	v_max_f32_e32 v4, 0x358637bd, v4
	v_cmp_gt_f32_e32 vcc, s7, v4
	s_nop 1
	v_cndmask_b32_e64 v5, 0, 32, vcc
	v_ldexp_f32 v4, v4, v5
	v_log_f32_e32 v4, v4
	s_nop 0
	v_mul_f32_e32 v5, 0x3f317217, v4
	v_fma_f32 v5, v4, s8, -v5
	v_fmac_f32_e32 v5, 0x3377d1cf, v4
	v_fmac_f32_e32 v5, 0x3f317217, v4
	v_cmp_lt_f32_e64 s[40:41], |v4|, s9
	s_nop 1
	v_cndmask_b32_e64 v4, v4, v5, s[40:41]
	v_cndmask_b32_e32 v5, 0, v226, vcc
	v_sub_f32_e32 v7, v4, v5
	v_mul_f32_e32 v4, 0xbfb8aa3b, v138
	v_exp_f32_e32 v4, v4
	s_nop 0
	v_add_f32_e32 v4, 1.0, v4
	v_rcp_f32_e32 v4, v4
	s_nop 0
	v_fma_f32 v4, v4, v211, v20
	v_max_f32_e32 v4, 0x358637bd, v4
	v_cmp_gt_f32_e32 vcc, s7, v4
	s_nop 1
	v_cndmask_b32_e64 v5, 0, 32, vcc
	v_ldexp_f32 v4, v4, v5
	v_log_f32_e32 v4, v4
	s_nop 0
	v_mul_f32_e32 v5, 0x3f317217, v4
	v_fma_f32 v5, v4, s8, -v5
	v_fmac_f32_e32 v5, 0x3377d1cf, v4
	v_fmac_f32_e32 v5, 0x3f317217, v4
	v_cmp_lt_f32_e64 s[40:41], |v4|, s9
	s_nop 1
	v_cndmask_b32_e64 v4, v4, v5, s[40:41]
	v_cndmask_b32_e32 v5, 0, v226, vcc
	v_sub_f32_e32 v4, v4, v5
	v_mul_f32_e32 v5, 0xbfb8aa3b, v134
	v_exp_f32_e32 v5, v5
	s_nop 0
	v_add_f32_e32 v5, 1.0, v5
	v_rcp_f32_e32 v5, v5
	s_nop 0
	v_fma_f32 v5, v5, v210, v21
	v_max_f32_e32 v5, 0x358637bd, v5
	v_cmp_gt_f32_e32 vcc, s7, v5
	s_nop 1
	v_cndmask_b32_e64 v8, 0, 32, vcc
	v_ldexp_f32 v5, v5, v8
	v_log_f32_e32 v5, v5
	s_nop 0
	v_mul_f32_e32 v8, 0x3f317217, v5
	v_fma_f32 v8, v5, s8, -v8
	v_fmac_f32_e32 v8, 0x3377d1cf, v5
	v_fmac_f32_e32 v8, 0x3f317217, v5
	v_cmp_lt_f32_e64 s[40:41], |v5|, s9
	s_nop 1
	v_cndmask_b32_e64 v5, v5, v8, s[40:41]
	v_cndmask_b32_e32 v8, 0, v226, vcc
	v_sub_f32_e32 v8, v5, v8
	v_mul_f32_e32 v5, 0xbfb8aa3b, v139
	v_exp_f32_e32 v5, v5
	s_nop 0
	v_add_f32_e32 v5, 1.0, v5
	v_rcp_f32_e32 v5, v5
	s_nop 0
	v_fma_f32 v5, v5, v212, v18
	v_max_f32_e32 v5, 0x358637bd, v5
	v_cmp_gt_f32_e32 vcc, s7, v5
	s_nop 1
	v_cndmask_b32_e64 v9, 0, 32, vcc
	v_ldexp_f32 v5, v5, v9
	v_log_f32_e32 v5, v5
	s_nop 0
	v_mul_f32_e32 v9, 0x3f317217, v5
	v_fma_f32 v9, v5, s8, -v9
	v_fmac_f32_e32 v9, 0x3377d1cf, v5
	v_fmac_f32_e32 v9, 0x3f317217, v5
	v_cmp_lt_f32_e64 s[40:41], |v5|, s9
	s_nop 1
	v_cndmask_b32_e64 v5, v5, v9, s[40:41]
	v_cndmask_b32_e32 v9, 0, v226, vcc
	v_sub_f32_e32 v5, v5, v9
	v_mul_f32_e32 v9, 0xbfb8aa3b, v135
	v_exp_f32_e32 v9, v9
	s_nop 0
	v_add_f32_e32 v9, 1.0, v9
	v_rcp_f32_e32 v9, v9
	s_nop 0
	v_fma_f32 v9, v9, v213, v19
	v_max_f32_e32 v9, 0x358637bd, v9
	v_cmp_gt_f32_e32 vcc, s7, v9
	s_nop 1
	v_cndmask_b32_e64 v196, 0, 32, vcc
	v_ldexp_f32 v9, v9, v196
	v_log_f32_e32 v9, v9
	s_nop 0
	v_mul_f32_e32 v196, 0x3f317217, v9
	v_fma_f32 v196, v9, s8, -v196
	v_fmac_f32_e32 v196, 0x3377d1cf, v9
	v_fmac_f32_e32 v196, 0x3f317217, v9
	v_cmp_lt_f32_e64 s[40:41], |v9|, s9
	s_nop 1
	v_cndmask_b32_e64 v9, v9, v196, s[40:41]
	v_cndmask_b32_e32 v196, 0, v226, vcc
	v_sub_f32_e32 v9, v9, v196
	global_store_dwordx4 v[16:17], v[2:5], off offset:512
	global_store_dwordx4 v[16:17], v[6:9], off offset:528
	s_nop 0
	v_or_b32_e32 v2, 32, v10
	v_ashrrev_i32_e32 v3, 31, v2
	v_lshlrev_b64 v[2:3], 13, v[2:3]
	v_lshl_add_u64 v[16:17], s[60:61], 0, v[2:3]
	v_mul_f32_e32 v2, 0xbfb8aa3b, v128
	v_exp_f32_e32 v2, v2
	v_lshl_add_u64 v[16:17], v[16:17], 0, v[14:15]
	v_add_f32_e32 v2, 1.0, v2
	v_rcp_f32_e32 v2, v2
	s_nop 0
	v_fma_f32 v2, v2, v186, v32
	v_max_f32_e32 v2, 0x358637bd, v2
	v_cmp_gt_f32_e32 vcc, s7, v2
	s_nop 1
	v_cndmask_b32_e64 v3, 0, 32, vcc
	v_ldexp_f32 v2, v2, v3
	v_log_f32_e32 v2, v2
	s_nop 0
	v_mul_f32_e32 v3, 0x3f317217, v2
	v_fma_f32 v3, v2, s8, -v3
	v_fmac_f32_e32 v3, 0x3377d1cf, v2
	v_fmac_f32_e32 v3, 0x3f317217, v2
	v_cmp_lt_f32_e64 s[40:41], |v2|, s9
	s_nop 1
	v_cndmask_b32_e64 v2, v2, v3, s[40:41]
	v_cndmask_b32_e32 v3, 0, v226, vcc
	v_sub_f32_e32 v2, v2, v3
	v_mul_f32_e32 v3, 0xbfb8aa3b, v124
	v_exp_f32_e32 v3, v3
	s_nop 0
	v_add_f32_e32 v3, 1.0, v3
	v_rcp_f32_e32 v3, v3
	s_nop 0
	v_fma_f32 v3, v3, v11, v33
	v_max_f32_e32 v3, 0x358637bd, v3
	v_cmp_gt_f32_e32 vcc, s7, v3
	s_nop 1
	v_cndmask_b32_e64 v4, 0, 32, vcc
	v_ldexp_f32 v3, v3, v4
	v_log_f32_e32 v3, v3
	s_nop 0
	v_mul_f32_e32 v4, 0x3f317217, v3
	v_fma_f32 v4, v3, s8, -v4
	v_fmac_f32_e32 v4, 0x3377d1cf, v3
	v_fmac_f32_e32 v4, 0x3f317217, v3
	v_cmp_lt_f32_e64 s[40:41], |v3|, s9
	s_nop 1
	v_cndmask_b32_e64 v3, v3, v4, s[40:41]
	v_cndmask_b32_e32 v4, 0, v226, vcc
	v_sub_f32_e32 v6, v3, v4
	v_mul_f32_e32 v3, 0xbfb8aa3b, v129
	v_exp_f32_e32 v3, v3
	s_nop 0
	v_add_f32_e32 v3, 1.0, v3
	v_rcp_f32_e32 v3, v3
	s_nop 0
	v_fma_f32 v3, v3, v188, v30
	v_max_f32_e32 v3, 0x358637bd, v3
	v_cmp_gt_f32_e32 vcc, s7, v3
	s_nop 1
	v_cndmask_b32_e64 v4, 0, 32, vcc
	v_ldexp_f32 v3, v3, v4
	v_log_f32_e32 v3, v3
	s_nop 0
	v_mul_f32_e32 v4, 0x3f317217, v3
	v_fma_f32 v4, v3, s8, -v4
	v_fmac_f32_e32 v4, 0x3377d1cf, v3
	v_fmac_f32_e32 v4, 0x3f317217, v3
	v_cmp_lt_f32_e64 s[40:41], |v3|, s9
	s_nop 1
	v_cndmask_b32_e64 v3, v3, v4, s[40:41]
	v_cndmask_b32_e32 v4, 0, v226, vcc
	v_sub_f32_e32 v3, v3, v4
	v_mul_f32_e32 v4, 0xbfb8aa3b, v125
	v_exp_f32_e32 v4, v4
	s_nop 0
	v_add_f32_e32 v4, 1.0, v4
	v_rcp_f32_e32 v4, v4
	s_nop 0
	v_fma_f32 v4, v4, v187, v31
	v_max_f32_e32 v4, 0x358637bd, v4
	v_cmp_gt_f32_e32 vcc, s7, v4
	s_nop 1
	v_cndmask_b32_e64 v5, 0, 32, vcc
	v_ldexp_f32 v4, v4, v5
	v_log_f32_e32 v4, v4
	s_nop 0
	v_mul_f32_e32 v5, 0x3f317217, v4
	v_fma_f32 v5, v4, s8, -v5
	v_fmac_f32_e32 v5, 0x3377d1cf, v4
	v_fmac_f32_e32 v5, 0x3f317217, v4
	v_cmp_lt_f32_e64 s[40:41], |v4|, s9
	s_nop 1
	v_cndmask_b32_e64 v4, v4, v5, s[40:41]
	v_cndmask_b32_e32 v5, 0, v226, vcc
	v_sub_f32_e32 v7, v4, v5
	v_mul_f32_e32 v4, 0xbfb8aa3b, v130
	v_exp_f32_e32 v4, v4
	s_nop 0
	v_add_f32_e32 v4, 1.0, v4
	v_rcp_f32_e32 v4, v4
	s_nop 0
	v_fma_f32 v4, v4, v190, v28
	v_max_f32_e32 v4, 0x358637bd, v4
	v_cmp_gt_f32_e32 vcc, s7, v4
	s_nop 1
	v_cndmask_b32_e64 v5, 0, 32, vcc
	v_ldexp_f32 v4, v4, v5
	v_log_f32_e32 v4, v4
	s_nop 0
	v_mul_f32_e32 v5, 0x3f317217, v4
	v_fma_f32 v5, v4, s8, -v5
	v_fmac_f32_e32 v5, 0x3377d1cf, v4
	v_fmac_f32_e32 v5, 0x3f317217, v4
	v_cmp_lt_f32_e64 s[40:41], |v4|, s9
	s_nop 1
	v_cndmask_b32_e64 v4, v4, v5, s[40:41]
	v_cndmask_b32_e32 v5, 0, v226, vcc
	v_sub_f32_e32 v4, v4, v5
	v_mul_f32_e32 v5, 0xbfb8aa3b, v126
	v_exp_f32_e32 v5, v5
	s_nop 0
	v_add_f32_e32 v5, 1.0, v5
	v_rcp_f32_e32 v5, v5
	s_nop 0
	v_fma_f32 v5, v5, v189, v29
	v_max_f32_e32 v5, 0x358637bd, v5
	v_cmp_gt_f32_e32 vcc, s7, v5
	s_nop 1
	v_cndmask_b32_e64 v8, 0, 32, vcc
	v_ldexp_f32 v5, v5, v8
	v_log_f32_e32 v5, v5
	s_nop 0
	v_mul_f32_e32 v8, 0x3f317217, v5
	v_fma_f32 v8, v5, s8, -v8
	v_fmac_f32_e32 v8, 0x3377d1cf, v5
	v_fmac_f32_e32 v8, 0x3f317217, v5
	v_cmp_lt_f32_e64 s[40:41], |v5|, s9
	s_nop 1
	v_cndmask_b32_e64 v5, v5, v8, s[40:41]
	v_cndmask_b32_e32 v8, 0, v226, vcc
	v_sub_f32_e32 v8, v5, v8
	v_mul_f32_e32 v5, 0xbfb8aa3b, v131
	v_exp_f32_e32 v5, v5
	s_nop 0
	v_add_f32_e32 v5, 1.0, v5
	v_rcp_f32_e32 v5, v5
	s_nop 0
	v_fma_f32 v5, v5, v191, v24
	v_max_f32_e32 v5, 0x358637bd, v5
	v_cmp_gt_f32_e32 vcc, s7, v5
	s_nop 1
	v_cndmask_b32_e64 v9, 0, 32, vcc
	v_ldexp_f32 v5, v5, v9
	v_log_f32_e32 v5, v5
	s_nop 0
	v_mul_f32_e32 v9, 0x3f317217, v5
	v_fma_f32 v9, v5, s8, -v9
	v_fmac_f32_e32 v9, 0x3377d1cf, v5
	v_fmac_f32_e32 v9, 0x3f317217, v5
	v_cmp_lt_f32_e64 s[40:41], |v5|, s9
	s_nop 1
	v_cndmask_b32_e64 v5, v5, v9, s[40:41]
	v_cndmask_b32_e32 v9, 0, v226, vcc
	v_sub_f32_e32 v5, v5, v9
	v_mul_f32_e32 v9, 0xbfb8aa3b, v127
	v_exp_f32_e32 v9, v9
	s_nop 0
	v_add_f32_e32 v9, 1.0, v9
	v_rcp_f32_e32 v9, v9
	s_nop 0
	v_fma_f32 v9, v9, v192, v26
	v_max_f32_e32 v9, 0x358637bd, v9
	v_cmp_gt_f32_e32 vcc, s7, v9
	s_nop 1
	v_cndmask_b32_e64 v196, 0, 32, vcc
	v_ldexp_f32 v9, v9, v196
	v_log_f32_e32 v9, v9
	s_nop 0
	v_mul_f32_e32 v196, 0x3f317217, v9
	v_fma_f32 v196, v9, s8, -v196
	v_fmac_f32_e32 v196, 0x3377d1cf, v9
	v_fmac_f32_e32 v196, 0x3f317217, v9
	v_cmp_lt_f32_e64 s[40:41], |v9|, s9
	s_nop 1
	v_cndmask_b32_e64 v9, v9, v196, s[40:41]
	v_cndmask_b32_e32 v196, 0, v226, vcc
	v_sub_f32_e32 v9, v9, v196
	global_store_dwordx4 v[16:17], v[2:5], off
	global_store_dwordx4 v[16:17], v[6:9], off offset:16
	s_nop 0
	v_mul_f32_e32 v2, 0xbfb8aa3b, v120
	v_exp_f32_e32 v2, v2
	s_nop 0
	v_add_f32_e32 v2, 1.0, v2
	v_rcp_f32_e32 v2, v2
	s_nop 0
	v_fma_f32 v2, v2, v193, v25
	v_max_f32_e32 v2, 0x358637bd, v2
	v_cmp_gt_f32_e32 vcc, s7, v2
	s_nop 1
	v_cndmask_b32_e64 v3, 0, 32, vcc
	v_ldexp_f32 v2, v2, v3
	v_log_f32_e32 v2, v2
	s_nop 0
	v_mul_f32_e32 v3, 0x3f317217, v2
	v_fma_f32 v3, v2, s8, -v3
	v_fmac_f32_e32 v3, 0x3377d1cf, v2
	v_fmac_f32_e32 v3, 0x3f317217, v2
	v_cmp_lt_f32_e64 s[40:41], |v2|, s9
	s_nop 1
	v_cndmask_b32_e64 v2, v2, v3, s[40:41]
	v_cndmask_b32_e32 v3, 0, v226, vcc
	v_sub_f32_e32 v2, v2, v3
	v_mul_f32_e32 v3, 0xbfb8aa3b, v116
	v_exp_f32_e32 v3, v3
	s_nop 0
	v_add_f32_e32 v3, 1.0, v3
	v_rcp_f32_e32 v3, v3
	s_nop 0
	v_fma_f32 v3, v3, v207, v27
	v_max_f32_e32 v3, 0x358637bd, v3
	v_cmp_gt_f32_e32 vcc, s7, v3
	s_nop 1
	v_cndmask_b32_e64 v4, 0, 32, vcc
	v_ldexp_f32 v3, v3, v4
	v_log_f32_e32 v3, v3
	s_nop 0
	v_mul_f32_e32 v4, 0x3f317217, v3
	v_fma_f32 v4, v3, s8, -v4
	v_fmac_f32_e32 v4, 0x3377d1cf, v3
	v_fmac_f32_e32 v4, 0x3f317217, v3
	v_cmp_lt_f32_e64 s[40:41], |v3|, s9
	s_nop 1
	v_cndmask_b32_e64 v3, v3, v4, s[40:41]
	v_cndmask_b32_e32 v4, 0, v226, vcc
	v_sub_f32_e32 v6, v3, v4
	v_mul_f32_e32 v3, 0xbfb8aa3b, v121
	v_exp_f32_e32 v3, v3
	s_nop 0
	v_add_f32_e32 v3, 1.0, v3
	v_rcp_f32_e32 v3, v3
	s_nop 0
	v_fma_f32 v3, v3, v209, v22
	v_max_f32_e32 v3, 0x358637bd, v3
	v_cmp_gt_f32_e32 vcc, s7, v3
	s_nop 1
	v_cndmask_b32_e64 v4, 0, 32, vcc
	v_ldexp_f32 v3, v3, v4
	v_log_f32_e32 v3, v3
	s_nop 0
	v_mul_f32_e32 v4, 0x3f317217, v3
	v_fma_f32 v4, v3, s8, -v4
	v_fmac_f32_e32 v4, 0x3377d1cf, v3
	v_fmac_f32_e32 v4, 0x3f317217, v3
	v_cmp_lt_f32_e64 s[40:41], |v3|, s9
	s_nop 1
	v_cndmask_b32_e64 v3, v3, v4, s[40:41]
	v_cndmask_b32_e32 v4, 0, v226, vcc
	v_sub_f32_e32 v3, v3, v4
	v_mul_f32_e32 v4, 0xbfb8aa3b, v117
	v_exp_f32_e32 v4, v4
	s_nop 0
	v_add_f32_e32 v4, 1.0, v4
	v_rcp_f32_e32 v4, v4
	s_nop 0
	v_fma_f32 v4, v4, v208, v23
	v_max_f32_e32 v4, 0x358637bd, v4
	v_cmp_gt_f32_e32 vcc, s7, v4
	s_nop 1
	v_cndmask_b32_e64 v5, 0, 32, vcc
	v_ldexp_f32 v4, v4, v5
	v_log_f32_e32 v4, v4
	s_nop 0
	v_mul_f32_e32 v5, 0x3f317217, v4
	v_fma_f32 v5, v4, s8, -v5
	v_fmac_f32_e32 v5, 0x3377d1cf, v4
	v_fmac_f32_e32 v5, 0x3f317217, v4
	v_cmp_lt_f32_e64 s[40:41], |v4|, s9
	s_nop 1
	v_cndmask_b32_e64 v4, v4, v5, s[40:41]
	v_cndmask_b32_e32 v5, 0, v226, vcc
	v_sub_f32_e32 v7, v4, v5
	v_mul_f32_e32 v4, 0xbfb8aa3b, v122
	v_exp_f32_e32 v4, v4
	s_nop 0
	v_add_f32_e32 v4, 1.0, v4
	v_rcp_f32_e32 v4, v4
	s_nop 0
	v_fma_f32 v4, v4, v211, v20
	v_max_f32_e32 v4, 0x358637bd, v4
	v_cmp_gt_f32_e32 vcc, s7, v4
	s_nop 1
	v_cndmask_b32_e64 v5, 0, 32, vcc
	v_ldexp_f32 v4, v4, v5
	v_log_f32_e32 v4, v4
	s_nop 0
	v_mul_f32_e32 v5, 0x3f317217, v4
	v_fma_f32 v5, v4, s8, -v5
	v_fmac_f32_e32 v5, 0x3377d1cf, v4
	v_fmac_f32_e32 v5, 0x3f317217, v4
	v_cmp_lt_f32_e64 s[40:41], |v4|, s9
	s_nop 1
	v_cndmask_b32_e64 v4, v4, v5, s[40:41]
	v_cndmask_b32_e32 v5, 0, v226, vcc
	v_sub_f32_e32 v4, v4, v5
	v_mul_f32_e32 v5, 0xbfb8aa3b, v118
	v_exp_f32_e32 v5, v5
	s_nop 0
	v_add_f32_e32 v5, 1.0, v5
	v_rcp_f32_e32 v5, v5
	s_nop 0
	v_fma_f32 v5, v5, v210, v21
	v_max_f32_e32 v5, 0x358637bd, v5
	v_cmp_gt_f32_e32 vcc, s7, v5
	s_nop 1
	v_cndmask_b32_e64 v8, 0, 32, vcc
	v_ldexp_f32 v5, v5, v8
	v_log_f32_e32 v5, v5
	s_nop 0
	v_mul_f32_e32 v8, 0x3f317217, v5
	v_fma_f32 v8, v5, s8, -v8
	v_fmac_f32_e32 v8, 0x3377d1cf, v5
	v_fmac_f32_e32 v8, 0x3f317217, v5
	v_cmp_lt_f32_e64 s[40:41], |v5|, s9
	s_nop 1
	v_cndmask_b32_e64 v5, v5, v8, s[40:41]
	v_cndmask_b32_e32 v8, 0, v226, vcc
	v_sub_f32_e32 v8, v5, v8
	v_mul_f32_e32 v5, 0xbfb8aa3b, v123
	v_exp_f32_e32 v5, v5
	s_nop 0
	v_add_f32_e32 v5, 1.0, v5
	v_rcp_f32_e32 v5, v5
	s_nop 0
	v_fma_f32 v5, v5, v212, v18
	v_max_f32_e32 v5, 0x358637bd, v5
	v_cmp_gt_f32_e32 vcc, s7, v5
	s_nop 1
	v_cndmask_b32_e64 v9, 0, 32, vcc
	v_ldexp_f32 v5, v5, v9
	v_log_f32_e32 v5, v5
	s_nop 0
	v_mul_f32_e32 v9, 0x3f317217, v5
	v_fma_f32 v9, v5, s8, -v9
	v_fmac_f32_e32 v9, 0x3377d1cf, v5
	v_fmac_f32_e32 v9, 0x3f317217, v5
	v_cmp_lt_f32_e64 s[40:41], |v5|, s9
	s_nop 1
	v_cndmask_b32_e64 v5, v5, v9, s[40:41]
	v_cndmask_b32_e32 v9, 0, v226, vcc
	v_sub_f32_e32 v5, v5, v9
	v_mul_f32_e32 v9, 0xbfb8aa3b, v119
	v_exp_f32_e32 v9, v9
	s_nop 0
	v_add_f32_e32 v9, 1.0, v9
	v_rcp_f32_e32 v9, v9
	s_nop 0
	v_fma_f32 v9, v9, v213, v19
	v_max_f32_e32 v9, 0x358637bd, v9
	v_cmp_gt_f32_e32 vcc, s7, v9
	s_nop 1
	v_cndmask_b32_e64 v196, 0, 32, vcc
	v_ldexp_f32 v9, v9, v196
	v_log_f32_e32 v9, v9
	s_nop 0
	v_mul_f32_e32 v196, 0x3f317217, v9
	v_fma_f32 v196, v9, s8, -v196
	v_fmac_f32_e32 v196, 0x3377d1cf, v9
	v_fmac_f32_e32 v196, 0x3f317217, v9
	v_cmp_lt_f32_e64 s[40:41], |v9|, s9
	s_nop 1
	v_cndmask_b32_e64 v9, v9, v196, s[40:41]
	v_cndmask_b32_e32 v196, 0, v226, vcc
	v_sub_f32_e32 v9, v9, v196
	global_store_dwordx4 v[16:17], v[2:5], off offset:512
	global_store_dwordx4 v[16:17], v[6:9], off offset:528
	s_nop 0
	v_or_b32_e32 v2, 48, v10
	v_ashrrev_i32_e32 v3, 31, v2
	v_lshlrev_b64 v[2:3], 13, v[2:3]
	v_lshl_add_u64 v[16:17], s[60:61], 0, v[2:3]
	v_mul_f32_e32 v2, 0xbfb8aa3b, v112
	v_exp_f32_e32 v2, v2
	v_lshl_add_u64 v[14:15], v[16:17], 0, v[14:15]
	v_add_f32_e32 v2, 1.0, v2
	v_rcp_f32_e32 v2, v2
	s_nop 0
	v_fma_f32 v2, v2, v186, v32
	v_max_f32_e32 v2, 0x358637bd, v2
	v_cmp_gt_f32_e32 vcc, s7, v2
	s_nop 1
	v_cndmask_b32_e64 v3, 0, 32, vcc
	v_ldexp_f32 v2, v2, v3
	v_log_f32_e32 v2, v2
	s_nop 0
	v_mul_f32_e32 v3, 0x3f317217, v2
	v_fma_f32 v3, v2, s8, -v3
	v_fmac_f32_e32 v3, 0x3377d1cf, v2
	v_fmac_f32_e32 v3, 0x3f317217, v2
	v_cmp_lt_f32_e64 s[40:41], |v2|, s9
	s_nop 1
	v_cndmask_b32_e64 v2, v2, v3, s[40:41]
	v_cndmask_b32_e32 v3, 0, v226, vcc
	v_sub_f32_e32 v2, v2, v3
	v_mul_f32_e32 v3, 0xbfb8aa3b, v108
	v_exp_f32_e32 v3, v3
	s_nop 0
	v_add_f32_e32 v3, 1.0, v3
	v_rcp_f32_e32 v3, v3
	s_nop 0
	v_fma_f32 v3, v3, v11, v33
	v_max_f32_e32 v3, 0x358637bd, v3
	v_cmp_gt_f32_e32 vcc, s7, v3
	s_nop 1
	v_cndmask_b32_e64 v4, 0, 32, vcc
	v_ldexp_f32 v3, v3, v4
	v_log_f32_e32 v3, v3
	s_nop 0
	v_mul_f32_e32 v4, 0x3f317217, v3
	v_fma_f32 v4, v3, s8, -v4
	v_fmac_f32_e32 v4, 0x3377d1cf, v3
	v_fmac_f32_e32 v4, 0x3f317217, v3
	v_cmp_lt_f32_e64 s[40:41], |v3|, s9
	s_nop 1
	v_cndmask_b32_e64 v3, v3, v4, s[40:41]
	v_cndmask_b32_e32 v4, 0, v226, vcc
	v_sub_f32_e32 v6, v3, v4
	v_mul_f32_e32 v3, 0xbfb8aa3b, v113
	v_exp_f32_e32 v3, v3
	s_nop 0
	v_add_f32_e32 v3, 1.0, v3
	v_rcp_f32_e32 v3, v3
	s_nop 0
	v_fma_f32 v3, v3, v188, v30
	v_max_f32_e32 v3, 0x358637bd, v3
	v_cmp_gt_f32_e32 vcc, s7, v3
	s_nop 1
	v_cndmask_b32_e64 v4, 0, 32, vcc
	v_ldexp_f32 v3, v3, v4
	v_log_f32_e32 v3, v3
	s_nop 0
	v_mul_f32_e32 v4, 0x3f317217, v3
	v_fma_f32 v4, v3, s8, -v4
	v_fmac_f32_e32 v4, 0x3377d1cf, v3
	v_fmac_f32_e32 v4, 0x3f317217, v3
	v_cmp_lt_f32_e64 s[40:41], |v3|, s9
	s_nop 1
	v_cndmask_b32_e64 v3, v3, v4, s[40:41]
	v_cndmask_b32_e32 v4, 0, v226, vcc
	v_sub_f32_e32 v3, v3, v4
	v_mul_f32_e32 v4, 0xbfb8aa3b, v109
	v_exp_f32_e32 v4, v4
	s_nop 0
	v_add_f32_e32 v4, 1.0, v4
	v_rcp_f32_e32 v4, v4
	s_nop 0
	v_fma_f32 v4, v4, v187, v31
	v_max_f32_e32 v4, 0x358637bd, v4
	v_cmp_gt_f32_e32 vcc, s7, v4
	s_nop 1
	v_cndmask_b32_e64 v5, 0, 32, vcc
	v_ldexp_f32 v4, v4, v5
	v_log_f32_e32 v4, v4
	s_nop 0
	v_mul_f32_e32 v5, 0x3f317217, v4
	v_fma_f32 v5, v4, s8, -v5
	v_fmac_f32_e32 v5, 0x3377d1cf, v4
	v_fmac_f32_e32 v5, 0x3f317217, v4
	v_cmp_lt_f32_e64 s[40:41], |v4|, s9
	s_nop 1
	v_cndmask_b32_e64 v4, v4, v5, s[40:41]
	v_cndmask_b32_e32 v5, 0, v226, vcc
	v_sub_f32_e32 v7, v4, v5
	v_mul_f32_e32 v4, 0xbfb8aa3b, v114
	v_exp_f32_e32 v4, v4
	s_nop 0
	v_add_f32_e32 v4, 1.0, v4
	v_rcp_f32_e32 v4, v4
	s_nop 0
	v_fma_f32 v4, v4, v190, v28
	v_max_f32_e32 v4, 0x358637bd, v4
	v_cmp_gt_f32_e32 vcc, s7, v4
	s_nop 1
	v_cndmask_b32_e64 v5, 0, 32, vcc
	v_ldexp_f32 v4, v4, v5
	v_log_f32_e32 v4, v4
	s_nop 0
	v_mul_f32_e32 v5, 0x3f317217, v4
	v_fma_f32 v5, v4, s8, -v5
	v_fmac_f32_e32 v5, 0x3377d1cf, v4
	v_fmac_f32_e32 v5, 0x3f317217, v4
	v_cmp_lt_f32_e64 s[40:41], |v4|, s9
	s_nop 1
	v_cndmask_b32_e64 v4, v4, v5, s[40:41]
	v_cndmask_b32_e32 v5, 0, v226, vcc
	v_sub_f32_e32 v4, v4, v5
	v_mul_f32_e32 v5, 0xbfb8aa3b, v110
	v_exp_f32_e32 v5, v5
	s_nop 0
	v_add_f32_e32 v5, 1.0, v5
	v_rcp_f32_e32 v5, v5
	s_nop 0
	v_fma_f32 v5, v5, v189, v29
	v_max_f32_e32 v5, 0x358637bd, v5
	v_cmp_gt_f32_e32 vcc, s7, v5
	s_nop 1
	v_cndmask_b32_e64 v8, 0, 32, vcc
	v_ldexp_f32 v5, v5, v8
	v_log_f32_e32 v5, v5
	s_nop 0
	v_mul_f32_e32 v8, 0x3f317217, v5
	v_fma_f32 v8, v5, s8, -v8
	v_fmac_f32_e32 v8, 0x3377d1cf, v5
	v_fmac_f32_e32 v8, 0x3f317217, v5
	v_cmp_lt_f32_e64 s[40:41], |v5|, s9
	s_nop 1
	v_cndmask_b32_e64 v5, v5, v8, s[40:41]
	v_cndmask_b32_e32 v8, 0, v226, vcc
	v_sub_f32_e32 v8, v5, v8
	v_mul_f32_e32 v5, 0xbfb8aa3b, v115
	v_exp_f32_e32 v5, v5
	s_nop 0
	v_add_f32_e32 v5, 1.0, v5
	v_rcp_f32_e32 v5, v5
	s_nop 0
	v_fma_f32 v5, v5, v191, v24
	v_max_f32_e32 v5, 0x358637bd, v5
	v_cmp_gt_f32_e32 vcc, s7, v5
	s_nop 1
	v_cndmask_b32_e64 v9, 0, 32, vcc
	v_ldexp_f32 v5, v5, v9
	v_log_f32_e32 v5, v5
	s_nop 0
	v_mul_f32_e32 v9, 0x3f317217, v5
	v_fma_f32 v9, v5, s8, -v9
	v_fmac_f32_e32 v9, 0x3377d1cf, v5
	v_fmac_f32_e32 v9, 0x3f317217, v5
	v_cmp_lt_f32_e64 s[40:41], |v5|, s9
	s_nop 1
	v_cndmask_b32_e64 v5, v5, v9, s[40:41]
	v_cndmask_b32_e32 v9, 0, v226, vcc
	v_sub_f32_e32 v5, v5, v9
	v_mul_f32_e32 v9, 0xbfb8aa3b, v111
	v_exp_f32_e32 v9, v9
	s_nop 0
	v_add_f32_e32 v9, 1.0, v9
	v_rcp_f32_e32 v9, v9
	s_nop 0
	v_fma_f32 v9, v9, v192, v26
	v_max_f32_e32 v9, 0x358637bd, v9
	v_cmp_gt_f32_e32 vcc, s7, v9
	s_nop 1
	v_cndmask_b32_e64 v196, 0, 32, vcc
	v_ldexp_f32 v9, v9, v196
	v_log_f32_e32 v9, v9
	s_nop 0
	v_mul_f32_e32 v196, 0x3f317217, v9
	v_fma_f32 v196, v9, s8, -v196
	v_fmac_f32_e32 v196, 0x3377d1cf, v9
	v_fmac_f32_e32 v196, 0x3f317217, v9
	v_cmp_lt_f32_e64 s[40:41], |v9|, s9
	s_nop 1
	v_cndmask_b32_e64 v9, v9, v196, s[40:41]
	v_cndmask_b32_e32 v196, 0, v226, vcc
	v_sub_f32_e32 v9, v9, v196
	global_store_dwordx4 v[14:15], v[2:5], off
	global_store_dwordx4 v[14:15], v[6:9], off offset:16
	s_nop 0
	v_mul_f32_e32 v2, 0xbfb8aa3b, v104
	v_exp_f32_e32 v2, v2
	s_nop 0
	v_add_f32_e32 v2, 1.0, v2
	v_rcp_f32_e32 v2, v2
	s_nop 0
	v_fma_f32 v2, v2, v193, v25
	v_max_f32_e32 v2, 0x358637bd, v2
	v_cmp_gt_f32_e32 vcc, s7, v2
	s_nop 1
	v_cndmask_b32_e64 v3, 0, 32, vcc
	v_ldexp_f32 v2, v2, v3
	v_log_f32_e32 v2, v2
	s_nop 0
	v_mul_f32_e32 v3, 0x3f317217, v2
	v_fma_f32 v3, v2, s8, -v3
	v_fmac_f32_e32 v3, 0x3377d1cf, v2
	v_fmac_f32_e32 v3, 0x3f317217, v2
	v_cmp_lt_f32_e64 s[40:41], |v2|, s9
	s_nop 1
	v_cndmask_b32_e64 v2, v2, v3, s[40:41]
	v_cndmask_b32_e32 v3, 0, v226, vcc
	v_sub_f32_e32 v2, v2, v3
	v_mul_f32_e32 v3, 0xbfb8aa3b, v100
	v_exp_f32_e32 v3, v3
	s_nop 0
	v_add_f32_e32 v3, 1.0, v3
	v_rcp_f32_e32 v3, v3
	s_nop 0
	v_fma_f32 v3, v3, v207, v27
	v_max_f32_e32 v3, 0x358637bd, v3
	v_cmp_gt_f32_e32 vcc, s7, v3
	s_nop 1
	v_cndmask_b32_e64 v4, 0, 32, vcc
	v_ldexp_f32 v3, v3, v4
	v_log_f32_e32 v3, v3
	s_nop 0
	v_mul_f32_e32 v4, 0x3f317217, v3
	v_fma_f32 v4, v3, s8, -v4
	v_fmac_f32_e32 v4, 0x3377d1cf, v3
	v_fmac_f32_e32 v4, 0x3f317217, v3
	v_cmp_lt_f32_e64 s[40:41], |v3|, s9
	s_nop 1
	v_cndmask_b32_e64 v3, v3, v4, s[40:41]
	v_cndmask_b32_e32 v4, 0, v226, vcc
	v_sub_f32_e32 v6, v3, v4
	v_mul_f32_e32 v3, 0xbfb8aa3b, v105
	v_exp_f32_e32 v3, v3
	s_nop 0
	v_add_f32_e32 v3, 1.0, v3
	v_rcp_f32_e32 v3, v3
	s_nop 0
	v_fma_f32 v3, v3, v209, v22
	v_max_f32_e32 v3, 0x358637bd, v3
	v_cmp_gt_f32_e32 vcc, s7, v3
	s_nop 1
	v_cndmask_b32_e64 v4, 0, 32, vcc
	v_ldexp_f32 v3, v3, v4
	v_log_f32_e32 v3, v3
	s_nop 0
	v_mul_f32_e32 v4, 0x3f317217, v3
	v_fma_f32 v4, v3, s8, -v4
	v_fmac_f32_e32 v4, 0x3377d1cf, v3
	v_fmac_f32_e32 v4, 0x3f317217, v3
	v_cmp_lt_f32_e64 s[40:41], |v3|, s9
	s_nop 1
	v_cndmask_b32_e64 v3, v3, v4, s[40:41]
	v_cndmask_b32_e32 v4, 0, v226, vcc
	v_sub_f32_e32 v3, v3, v4
	v_mul_f32_e32 v4, 0xbfb8aa3b, v101
	v_exp_f32_e32 v4, v4
	s_nop 0
	v_add_f32_e32 v4, 1.0, v4
	v_rcp_f32_e32 v4, v4
	s_nop 0
	v_fma_f32 v4, v4, v208, v23
	v_max_f32_e32 v4, 0x358637bd, v4
	v_cmp_gt_f32_e32 vcc, s7, v4
	s_nop 1
	v_cndmask_b32_e64 v5, 0, 32, vcc
	v_ldexp_f32 v4, v4, v5
	v_log_f32_e32 v4, v4
	s_nop 0
	v_mul_f32_e32 v5, 0x3f317217, v4
	v_fma_f32 v5, v4, s8, -v5
	v_fmac_f32_e32 v5, 0x3377d1cf, v4
	v_fmac_f32_e32 v5, 0x3f317217, v4
	v_cmp_lt_f32_e64 s[40:41], |v4|, s9
	s_nop 1
	v_cndmask_b32_e64 v4, v4, v5, s[40:41]
	v_cndmask_b32_e32 v5, 0, v226, vcc
	v_sub_f32_e32 v7, v4, v5
	v_mul_f32_e32 v4, 0xbfb8aa3b, v106
	v_exp_f32_e32 v4, v4
	s_nop 0
	v_add_f32_e32 v4, 1.0, v4
	v_rcp_f32_e32 v4, v4
	s_nop 0
	v_fma_f32 v4, v4, v211, v20
	v_max_f32_e32 v4, 0x358637bd, v4
	v_cmp_gt_f32_e32 vcc, s7, v4
	s_nop 1
	v_cndmask_b32_e64 v5, 0, 32, vcc
	v_ldexp_f32 v4, v4, v5
	v_log_f32_e32 v4, v4
	s_nop 0
	v_mul_f32_e32 v5, 0x3f317217, v4
	v_fma_f32 v5, v4, s8, -v5
	v_fmac_f32_e32 v5, 0x3377d1cf, v4
	v_fmac_f32_e32 v5, 0x3f317217, v4
	v_cmp_lt_f32_e64 s[40:41], |v4|, s9
	s_nop 1
	v_cndmask_b32_e64 v4, v4, v5, s[40:41]
	v_cndmask_b32_e32 v5, 0, v226, vcc
	v_sub_f32_e32 v4, v4, v5
	v_mul_f32_e32 v5, 0xbfb8aa3b, v102
	v_exp_f32_e32 v5, v5
	s_nop 0
	v_add_f32_e32 v5, 1.0, v5
	v_rcp_f32_e32 v5, v5
	s_nop 0
	v_fma_f32 v5, v5, v210, v21
	v_max_f32_e32 v5, 0x358637bd, v5
	v_cmp_gt_f32_e32 vcc, s7, v5
	s_nop 1
	v_cndmask_b32_e64 v8, 0, 32, vcc
	v_ldexp_f32 v5, v5, v8
	v_log_f32_e32 v5, v5
	s_nop 0
	v_mul_f32_e32 v8, 0x3f317217, v5
	v_fma_f32 v8, v5, s8, -v8
	v_fmac_f32_e32 v8, 0x3377d1cf, v5
	v_fmac_f32_e32 v8, 0x3f317217, v5
	v_cmp_lt_f32_e64 s[40:41], |v5|, s9
	s_nop 1
	v_cndmask_b32_e64 v5, v5, v8, s[40:41]
	v_cndmask_b32_e32 v8, 0, v226, vcc
	v_sub_f32_e32 v8, v5, v8
	v_mul_f32_e32 v5, 0xbfb8aa3b, v107
	v_exp_f32_e32 v5, v5
	s_nop 0
	v_add_f32_e32 v5, 1.0, v5
	v_rcp_f32_e32 v5, v5
	s_nop 0
	v_fma_f32 v5, v5, v212, v18
	v_max_f32_e32 v5, 0x358637bd, v5
	v_cmp_gt_f32_e32 vcc, s7, v5
	s_nop 1
	v_cndmask_b32_e64 v9, 0, 32, vcc
	v_ldexp_f32 v5, v5, v9
	v_log_f32_e32 v5, v5
	s_nop 0
	v_mul_f32_e32 v9, 0x3f317217, v5
	v_fma_f32 v9, v5, s8, -v9
	v_fmac_f32_e32 v9, 0x3377d1cf, v5
	v_fmac_f32_e32 v9, 0x3f317217, v5
	v_cmp_lt_f32_e64 s[40:41], |v5|, s9
	s_nop 1
	v_cndmask_b32_e64 v5, v5, v9, s[40:41]
	v_cndmask_b32_e32 v9, 0, v226, vcc
	v_sub_f32_e32 v5, v5, v9
	v_mul_f32_e32 v9, 0xbfb8aa3b, v103
	v_exp_f32_e32 v9, v9
	s_nop 0
	v_add_f32_e32 v9, 1.0, v9
	v_rcp_f32_e32 v9, v9
	s_nop 0
	v_fma_f32 v9, v9, v213, v19
	v_max_f32_e32 v9, 0x358637bd, v9
	v_cmp_gt_f32_e32 vcc, s7, v9
	s_nop 1
	v_cndmask_b32_e64 v16, 0, 32, vcc
	v_ldexp_f32 v9, v9, v16
	v_log_f32_e32 v9, v9
	s_nop 0
	v_mul_f32_e32 v16, 0x3f317217, v9
	v_fma_f32 v16, v9, s8, -v16
	v_fmac_f32_e32 v16, 0x3377d1cf, v9
	v_fmac_f32_e32 v16, 0x3f317217, v9
	v_cmp_lt_f32_e64 s[40:41], |v9|, s9
	s_nop 1
	v_cndmask_b32_e64 v9, v9, v16, s[40:41]
	v_cndmask_b32_e32 v16, 0, v226, vcc
	v_sub_f32_e32 v9, v9, v16
	global_store_dwordx4 v[14:15], v[2:5], off offset:512
	global_store_dwordx4 v[14:15], v[6:9], off offset:528
	s_nop 0
	v_mul_f32_e32 v2, 0xbfb8aa3b, v96
	v_exp_f32_e32 v2, v2
	s_nop 0
	v_add_f32_e32 v2, 1.0, v2
	v_rcp_f32_e32 v2, v2
	s_nop 0
	v_fma_f32 v2, v2, v186, v32
	v_max_f32_e32 v2, 0x358637bd, v2
	v_cmp_gt_f32_e32 vcc, s7, v2
	s_nop 1
	v_cndmask_b32_e64 v3, 0, 32, vcc
	v_ldexp_f32 v2, v2, v3
	v_log_f32_e32 v2, v2
	s_nop 0
	v_mul_f32_e32 v3, 0x3f317217, v2
	v_fma_f32 v3, v2, s8, -v3
	v_fmac_f32_e32 v3, 0x3377d1cf, v2
	v_fmac_f32_e32 v3, 0x3f317217, v2
	v_cmp_lt_f32_e64 s[40:41], |v2|, s9
	s_nop 1
	v_cndmask_b32_e64 v2, v2, v3, s[40:41]
	v_cndmask_b32_e32 v3, 0, v226, vcc
	v_sub_f32_e32 v2, v2, v3
	v_mul_f32_e32 v3, 0xbfb8aa3b, v92
	v_exp_f32_e32 v3, v3
	s_nop 0
	v_add_f32_e32 v3, 1.0, v3
	v_rcp_f32_e32 v3, v3
	s_nop 0
	v_fma_f32 v3, v3, v11, v33
	v_max_f32_e32 v3, 0x358637bd, v3
	v_cmp_gt_f32_e32 vcc, s7, v3
	s_nop 1
	v_cndmask_b32_e64 v4, 0, 32, vcc
	v_ldexp_f32 v3, v3, v4
	v_log_f32_e32 v3, v3
	s_nop 0
	v_mul_f32_e32 v4, 0x3f317217, v3
	v_fma_f32 v4, v3, s8, -v4
	v_fmac_f32_e32 v4, 0x3377d1cf, v3
	v_fmac_f32_e32 v4, 0x3f317217, v3
	v_cmp_lt_f32_e64 s[40:41], |v3|, s9
	s_nop 1
	v_cndmask_b32_e64 v3, v3, v4, s[40:41]
	v_cndmask_b32_e32 v4, 0, v226, vcc
	v_sub_f32_e32 v6, v3, v4
	v_mul_f32_e32 v3, 0xbfb8aa3b, v97
	v_exp_f32_e32 v3, v3
	s_nop 0
	v_add_f32_e32 v3, 1.0, v3
	v_rcp_f32_e32 v3, v3
	s_nop 0
	v_fma_f32 v3, v3, v188, v30
	v_max_f32_e32 v3, 0x358637bd, v3
	v_cmp_gt_f32_e32 vcc, s7, v3
	s_nop 1
	v_cndmask_b32_e64 v4, 0, 32, vcc
	v_ldexp_f32 v3, v3, v4
	v_log_f32_e32 v3, v3
	s_nop 0
	v_mul_f32_e32 v4, 0x3f317217, v3
	v_fma_f32 v4, v3, s8, -v4
	v_fmac_f32_e32 v4, 0x3377d1cf, v3
	v_fmac_f32_e32 v4, 0x3f317217, v3
	v_cmp_lt_f32_e64 s[40:41], |v3|, s9
	s_nop 1
	v_cndmask_b32_e64 v3, v3, v4, s[40:41]
	v_cndmask_b32_e32 v4, 0, v226, vcc
	v_sub_f32_e32 v3, v3, v4
	v_mul_f32_e32 v4, 0xbfb8aa3b, v93
	v_exp_f32_e32 v4, v4
	s_nop 0
	v_add_f32_e32 v4, 1.0, v4
	v_rcp_f32_e32 v4, v4
	s_nop 0
	v_fma_f32 v4, v4, v187, v31
	v_max_f32_e32 v4, 0x358637bd, v4
	v_cmp_gt_f32_e32 vcc, s7, v4
	s_nop 1
	v_cndmask_b32_e64 v5, 0, 32, vcc
	v_ldexp_f32 v4, v4, v5
	v_log_f32_e32 v4, v4
	s_nop 0
	v_mul_f32_e32 v5, 0x3f317217, v4
	v_fma_f32 v5, v4, s8, -v5
	v_fmac_f32_e32 v5, 0x3377d1cf, v4
	v_fmac_f32_e32 v5, 0x3f317217, v4
	v_cmp_lt_f32_e64 s[40:41], |v4|, s9
	s_nop 1
	v_cndmask_b32_e64 v4, v4, v5, s[40:41]
	v_cndmask_b32_e32 v5, 0, v226, vcc
	v_sub_f32_e32 v7, v4, v5
	v_mul_f32_e32 v4, 0xbfb8aa3b, v98
	v_exp_f32_e32 v4, v4
	s_nop 0
	v_add_f32_e32 v4, 1.0, v4
	v_rcp_f32_e32 v4, v4
	s_nop 0
	v_fma_f32 v4, v4, v190, v28
	v_max_f32_e32 v4, 0x358637bd, v4
	v_cmp_gt_f32_e32 vcc, s7, v4
	s_nop 1
	v_cndmask_b32_e64 v5, 0, 32, vcc
	v_ldexp_f32 v4, v4, v5
	v_log_f32_e32 v4, v4
	s_nop 0
	v_mul_f32_e32 v5, 0x3f317217, v4
	v_fma_f32 v5, v4, s8, -v5
	v_fmac_f32_e32 v5, 0x3377d1cf, v4
	v_fmac_f32_e32 v5, 0x3f317217, v4
	v_cmp_lt_f32_e64 s[40:41], |v4|, s9
	s_nop 1
	v_cndmask_b32_e64 v4, v4, v5, s[40:41]
	v_cndmask_b32_e32 v5, 0, v226, vcc
	v_sub_f32_e32 v4, v4, v5
	v_mul_f32_e32 v5, 0xbfb8aa3b, v94
	v_exp_f32_e32 v5, v5
	s_nop 0
	v_add_f32_e32 v5, 1.0, v5
	v_rcp_f32_e32 v5, v5
	s_nop 0
	v_fma_f32 v5, v5, v189, v29
	v_max_f32_e32 v5, 0x358637bd, v5
	v_cmp_gt_f32_e32 vcc, s7, v5
	s_nop 1
	v_cndmask_b32_e64 v8, 0, 32, vcc
	v_ldexp_f32 v5, v5, v8
	v_log_f32_e32 v5, v5
	s_nop 0
	v_mul_f32_e32 v8, 0x3f317217, v5
	v_fma_f32 v8, v5, s8, -v8
	v_fmac_f32_e32 v8, 0x3377d1cf, v5
	v_fmac_f32_e32 v8, 0x3f317217, v5
	v_cmp_lt_f32_e64 s[40:41], |v5|, s9
	s_nop 1
	v_cndmask_b32_e64 v5, v5, v8, s[40:41]
	v_cndmask_b32_e32 v8, 0, v226, vcc
	v_sub_f32_e32 v8, v5, v8
	v_mul_f32_e32 v5, 0xbfb8aa3b, v99
	v_exp_f32_e32 v5, v5
	s_nop 0
	v_add_f32_e32 v5, 1.0, v5
	v_rcp_f32_e32 v5, v5
	s_nop 0
	v_fma_f32 v5, v5, v191, v24
	v_max_f32_e32 v5, 0x358637bd, v5
	v_cmp_gt_f32_e32 vcc, s7, v5
	s_nop 1
	v_cndmask_b32_e64 v9, 0, 32, vcc
	v_ldexp_f32 v5, v5, v9
	v_log_f32_e32 v5, v5
	s_nop 0
	v_mul_f32_e32 v9, 0x3f317217, v5
	v_fma_f32 v9, v5, s8, -v9
	v_fmac_f32_e32 v9, 0x3377d1cf, v5
	v_fmac_f32_e32 v9, 0x3f317217, v5
	v_cmp_lt_f32_e64 s[40:41], |v5|, s9
	s_nop 1
	v_cndmask_b32_e64 v5, v5, v9, s[40:41]
	v_cndmask_b32_e32 v9, 0, v226, vcc
	v_sub_f32_e32 v5, v5, v9
	v_mul_f32_e32 v9, 0xbfb8aa3b, v95
	v_exp_f32_e32 v9, v9
	s_nop 0
	v_add_f32_e32 v9, 1.0, v9
	v_rcp_f32_e32 v9, v9
	s_nop 0
	v_fma_f32 v9, v9, v192, v26
	v_max_f32_e32 v9, 0x358637bd, v9
	v_cmp_gt_f32_e32 vcc, s7, v9
	s_nop 1
	v_cndmask_b32_e64 v14, 0, 32, vcc
	v_ldexp_f32 v9, v9, v14
	v_log_f32_e32 v9, v9
	s_nop 0
	v_mul_f32_e32 v14, 0x3f317217, v9
	v_fma_f32 v14, v9, s8, -v14
	v_fmac_f32_e32 v14, 0x3377d1cf, v9
	v_fmac_f32_e32 v14, 0x3f317217, v9
	v_cmp_lt_f32_e64 s[40:41], |v9|, s9
	s_nop 1
	v_cndmask_b32_e64 v9, v9, v14, s[40:41]
	v_cndmask_b32_e32 v14, 0, v226, vcc
	v_add_co_u32_e32 v16, vcc, s6, v12
	v_sub_f32_e32 v9, v9, v14
	s_nop 0
	v_addc_co_u32_e32 v17, vcc, 0, v13, vcc
	v_lshl_add_u64 v[14:15], v[12:13], 0, s[10:11]
	global_store_dwordx4 v[16:17], v[2:5], off
	global_store_dwordx4 v[14:15], v[6:9], off offset:16
	s_mov_b32 s6, 0x120000
	v_mul_f32_e32 v2, 0xbfb8aa3b, v88
	v_exp_f32_e32 v2, v2
	s_mov_b64 s[10:11], 0x120000
	v_add_f32_e32 v2, 1.0, v2
	v_rcp_f32_e32 v2, v2
	s_nop 0
	v_fma_f32 v2, v2, v193, v25
	v_max_f32_e32 v2, 0x358637bd, v2
	v_cmp_gt_f32_e32 vcc, s7, v2
	s_nop 1
	v_cndmask_b32_e64 v3, 0, 32, vcc
	v_ldexp_f32 v2, v2, v3
	v_log_f32_e32 v2, v2
	s_nop 0
	v_mul_f32_e32 v3, 0x3f317217, v2
	v_fma_f32 v3, v2, s8, -v3
	v_fmac_f32_e32 v3, 0x3377d1cf, v2
	v_fmac_f32_e32 v3, 0x3f317217, v2
	v_cmp_lt_f32_e64 s[40:41], |v2|, s9
	s_nop 1
	v_cndmask_b32_e64 v2, v2, v3, s[40:41]
	v_cndmask_b32_e32 v3, 0, v226, vcc
	v_sub_f32_e32 v2, v2, v3
	v_mul_f32_e32 v3, 0xbfb8aa3b, v84
	v_exp_f32_e32 v3, v3
	s_nop 0
	v_add_f32_e32 v3, 1.0, v3
	v_rcp_f32_e32 v3, v3
	s_nop 0
	v_fma_f32 v3, v3, v207, v27
	v_max_f32_e32 v3, 0x358637bd, v3
	v_cmp_gt_f32_e32 vcc, s7, v3
	s_nop 1
	v_cndmask_b32_e64 v4, 0, 32, vcc
	v_ldexp_f32 v3, v3, v4
	v_log_f32_e32 v3, v3
	s_nop 0
	v_mul_f32_e32 v4, 0x3f317217, v3
	v_fma_f32 v4, v3, s8, -v4
	v_fmac_f32_e32 v4, 0x3377d1cf, v3
	v_fmac_f32_e32 v4, 0x3f317217, v3
	v_cmp_lt_f32_e64 s[40:41], |v3|, s9
	s_nop 1
	v_cndmask_b32_e64 v3, v3, v4, s[40:41]
	v_cndmask_b32_e32 v4, 0, v226, vcc
	v_sub_f32_e32 v6, v3, v4
	v_mul_f32_e32 v3, 0xbfb8aa3b, v89
	v_exp_f32_e32 v3, v3
	s_nop 0
	v_add_f32_e32 v3, 1.0, v3
	v_rcp_f32_e32 v3, v3
	s_nop 0
	v_fma_f32 v3, v3, v209, v22
	v_max_f32_e32 v3, 0x358637bd, v3
	v_cmp_gt_f32_e32 vcc, s7, v3
	s_nop 1
	v_cndmask_b32_e64 v4, 0, 32, vcc
	v_ldexp_f32 v3, v3, v4
	v_log_f32_e32 v3, v3
	s_nop 0
	v_mul_f32_e32 v4, 0x3f317217, v3
	v_fma_f32 v4, v3, s8, -v4
	v_fmac_f32_e32 v4, 0x3377d1cf, v3
	v_fmac_f32_e32 v4, 0x3f317217, v3
	v_cmp_lt_f32_e64 s[40:41], |v3|, s9
	s_nop 1
	v_cndmask_b32_e64 v3, v3, v4, s[40:41]
	v_cndmask_b32_e32 v4, 0, v226, vcc
	v_sub_f32_e32 v3, v3, v4
	v_mul_f32_e32 v4, 0xbfb8aa3b, v85
	v_exp_f32_e32 v4, v4
	s_nop 0
	v_add_f32_e32 v4, 1.0, v4
	v_rcp_f32_e32 v4, v4
	s_nop 0
	v_fma_f32 v4, v4, v208, v23
	v_max_f32_e32 v4, 0x358637bd, v4
	v_cmp_gt_f32_e32 vcc, s7, v4
	s_nop 1
	v_cndmask_b32_e64 v5, 0, 32, vcc
	v_ldexp_f32 v4, v4, v5
	v_log_f32_e32 v4, v4
	s_nop 0
	v_mul_f32_e32 v5, 0x3f317217, v4
	v_fma_f32 v5, v4, s8, -v5
	v_fmac_f32_e32 v5, 0x3377d1cf, v4
	v_fmac_f32_e32 v5, 0x3f317217, v4
	v_cmp_lt_f32_e64 s[40:41], |v4|, s9
	s_nop 1
	v_cndmask_b32_e64 v4, v4, v5, s[40:41]
	v_cndmask_b32_e32 v5, 0, v226, vcc
	v_sub_f32_e32 v7, v4, v5
	v_mul_f32_e32 v4, 0xbfb8aa3b, v90
	v_exp_f32_e32 v4, v4
	s_nop 0
	v_add_f32_e32 v4, 1.0, v4
	v_rcp_f32_e32 v4, v4
	s_nop 0
	v_fma_f32 v4, v4, v211, v20
	v_max_f32_e32 v4, 0x358637bd, v4
	v_cmp_gt_f32_e32 vcc, s7, v4
	s_nop 1
	v_cndmask_b32_e64 v5, 0, 32, vcc
	v_ldexp_f32 v4, v4, v5
	v_log_f32_e32 v4, v4
	s_nop 0
	v_mul_f32_e32 v5, 0x3f317217, v4
	v_fma_f32 v5, v4, s8, -v5
	v_fmac_f32_e32 v5, 0x3377d1cf, v4
	v_fmac_f32_e32 v5, 0x3f317217, v4
	v_cmp_lt_f32_e64 s[40:41], |v4|, s9
	s_nop 1
	v_cndmask_b32_e64 v4, v4, v5, s[40:41]
	v_cndmask_b32_e32 v5, 0, v226, vcc
	v_sub_f32_e32 v4, v4, v5
	v_mul_f32_e32 v5, 0xbfb8aa3b, v86
	v_exp_f32_e32 v5, v5
	s_nop 0
	v_add_f32_e32 v5, 1.0, v5
	v_rcp_f32_e32 v5, v5
	s_nop 0
	v_fma_f32 v5, v5, v210, v21
	v_max_f32_e32 v5, 0x358637bd, v5
	v_cmp_gt_f32_e32 vcc, s7, v5
	s_nop 1
	v_cndmask_b32_e64 v8, 0, 32, vcc
	v_ldexp_f32 v5, v5, v8
	v_log_f32_e32 v5, v5
	s_nop 0
	v_mul_f32_e32 v8, 0x3f317217, v5
	v_fma_f32 v8, v5, s8, -v8
	v_fmac_f32_e32 v8, 0x3377d1cf, v5
	v_fmac_f32_e32 v8, 0x3f317217, v5
	v_cmp_lt_f32_e64 s[40:41], |v5|, s9
	s_nop 1
	v_cndmask_b32_e64 v5, v5, v8, s[40:41]
	v_cndmask_b32_e32 v8, 0, v226, vcc
	v_sub_f32_e32 v8, v5, v8
	v_mul_f32_e32 v5, 0xbfb8aa3b, v91
	v_exp_f32_e32 v5, v5
	s_nop 0
	v_add_f32_e32 v5, 1.0, v5
	v_rcp_f32_e32 v5, v5
	s_nop 0
	v_fma_f32 v5, v5, v212, v18
	v_max_f32_e32 v5, 0x358637bd, v5
	v_cmp_gt_f32_e32 vcc, s7, v5
	s_nop 1
	v_cndmask_b32_e64 v9, 0, 32, vcc
	v_ldexp_f32 v5, v5, v9
	v_log_f32_e32 v5, v5
	s_nop 0
	v_mul_f32_e32 v9, 0x3f317217, v5
	v_fma_f32 v9, v5, s8, -v9
	v_fmac_f32_e32 v9, 0x3377d1cf, v5
	v_fmac_f32_e32 v9, 0x3f317217, v5
	v_cmp_lt_f32_e64 s[40:41], |v5|, s9
	s_nop 1
	v_cndmask_b32_e64 v5, v5, v9, s[40:41]
	v_cndmask_b32_e32 v9, 0, v226, vcc
	v_sub_f32_e32 v5, v5, v9
	v_mul_f32_e32 v9, 0xbfb8aa3b, v87
	v_exp_f32_e32 v9, v9
	s_nop 0
	v_add_f32_e32 v9, 1.0, v9
	v_rcp_f32_e32 v9, v9
	s_nop 0
	v_fma_f32 v9, v9, v213, v19
	v_max_f32_e32 v9, 0x358637bd, v9
	v_cmp_gt_f32_e32 vcc, s7, v9
	s_nop 1
	v_cndmask_b32_e64 v16, 0, 32, vcc
	v_ldexp_f32 v9, v9, v16
	v_log_f32_e32 v9, v9
	s_nop 0
	v_mul_f32_e32 v16, 0x3f317217, v9
	v_fma_f32 v16, v9, s8, -v16
	v_fmac_f32_e32 v16, 0x3377d1cf, v9
	v_fmac_f32_e32 v16, 0x3f317217, v9
	v_cmp_lt_f32_e64 s[40:41], |v9|, s9
	s_nop 1
	v_cndmask_b32_e64 v9, v9, v16, s[40:41]
	v_cndmask_b32_e32 v16, 0, v226, vcc
	v_sub_f32_e32 v9, v9, v16
	global_store_dwordx4 v[14:15], v[2:5], off offset:512
	global_store_dwordx4 v[14:15], v[6:9], off offset:528
	s_nop 0
	v_mul_f32_e32 v2, 0xbfb8aa3b, v80
	v_exp_f32_e32 v2, v2
	s_nop 0
	v_add_f32_e32 v2, 1.0, v2
	v_rcp_f32_e32 v2, v2
	s_nop 0
	v_fma_f32 v2, v2, v186, v32
	v_max_f32_e32 v2, 0x358637bd, v2
	v_cmp_gt_f32_e32 vcc, s7, v2
	s_nop 1
	v_cndmask_b32_e64 v3, 0, 32, vcc
	v_ldexp_f32 v2, v2, v3
	v_log_f32_e32 v2, v2
	s_nop 0
	v_mul_f32_e32 v3, 0x3f317217, v2
	v_fma_f32 v3, v2, s8, -v3
	v_fmac_f32_e32 v3, 0x3377d1cf, v2
	v_fmac_f32_e32 v3, 0x3f317217, v2
	v_cmp_lt_f32_e64 s[40:41], |v2|, s9
	s_nop 1
	v_cndmask_b32_e64 v2, v2, v3, s[40:41]
	v_cndmask_b32_e32 v3, 0, v226, vcc
	v_sub_f32_e32 v2, v2, v3
	v_mul_f32_e32 v3, 0xbfb8aa3b, v76
	v_exp_f32_e32 v3, v3
	s_nop 0
	v_add_f32_e32 v3, 1.0, v3
	v_rcp_f32_e32 v3, v3
	s_nop 0
	v_fma_f32 v3, v3, v11, v33
	v_max_f32_e32 v3, 0x358637bd, v3
	v_cmp_gt_f32_e32 vcc, s7, v3
	s_nop 1
	v_cndmask_b32_e64 v4, 0, 32, vcc
	v_ldexp_f32 v3, v3, v4
	v_log_f32_e32 v3, v3
	s_nop 0
	v_mul_f32_e32 v4, 0x3f317217, v3
	v_fma_f32 v4, v3, s8, -v4
	v_fmac_f32_e32 v4, 0x3377d1cf, v3
	v_fmac_f32_e32 v4, 0x3f317217, v3
	v_cmp_lt_f32_e64 s[40:41], |v3|, s9
	s_nop 1
	v_cndmask_b32_e64 v3, v3, v4, s[40:41]
	v_cndmask_b32_e32 v4, 0, v226, vcc
	v_sub_f32_e32 v6, v3, v4
	v_mul_f32_e32 v3, 0xbfb8aa3b, v81
	v_exp_f32_e32 v3, v3
	s_nop 0
	v_add_f32_e32 v3, 1.0, v3
	v_rcp_f32_e32 v3, v3
	s_nop 0
	v_fma_f32 v3, v3, v188, v30
	v_max_f32_e32 v3, 0x358637bd, v3
	v_cmp_gt_f32_e32 vcc, s7, v3
	s_nop 1
	v_cndmask_b32_e64 v4, 0, 32, vcc
	v_ldexp_f32 v3, v3, v4
	v_log_f32_e32 v3, v3
	s_nop 0
	v_mul_f32_e32 v4, 0x3f317217, v3
	v_fma_f32 v4, v3, s8, -v4
	v_fmac_f32_e32 v4, 0x3377d1cf, v3
	v_fmac_f32_e32 v4, 0x3f317217, v3
	v_cmp_lt_f32_e64 s[40:41], |v3|, s9
	s_nop 1
	v_cndmask_b32_e64 v3, v3, v4, s[40:41]
	v_cndmask_b32_e32 v4, 0, v226, vcc
	v_sub_f32_e32 v3, v3, v4
	v_mul_f32_e32 v4, 0xbfb8aa3b, v77
	v_exp_f32_e32 v4, v4
	s_nop 0
	v_add_f32_e32 v4, 1.0, v4
	v_rcp_f32_e32 v4, v4
	s_nop 0
	v_fma_f32 v4, v4, v187, v31
	v_max_f32_e32 v4, 0x358637bd, v4
	v_cmp_gt_f32_e32 vcc, s7, v4
	s_nop 1
	v_cndmask_b32_e64 v5, 0, 32, vcc
	v_ldexp_f32 v4, v4, v5
	v_log_f32_e32 v4, v4
	s_nop 0
	v_mul_f32_e32 v5, 0x3f317217, v4
	v_fma_f32 v5, v4, s8, -v5
	v_fmac_f32_e32 v5, 0x3377d1cf, v4
	v_fmac_f32_e32 v5, 0x3f317217, v4
	v_cmp_lt_f32_e64 s[40:41], |v4|, s9
	s_nop 1
	v_cndmask_b32_e64 v4, v4, v5, s[40:41]
	v_cndmask_b32_e32 v5, 0, v226, vcc
	v_sub_f32_e32 v7, v4, v5
	v_mul_f32_e32 v4, 0xbfb8aa3b, v82
	v_exp_f32_e32 v4, v4
	s_nop 0
	v_add_f32_e32 v4, 1.0, v4
	v_rcp_f32_e32 v4, v4
	s_nop 0
	v_fma_f32 v4, v4, v190, v28
	v_max_f32_e32 v4, 0x358637bd, v4
	v_cmp_gt_f32_e32 vcc, s7, v4
	s_nop 1
	v_cndmask_b32_e64 v5, 0, 32, vcc
	v_ldexp_f32 v4, v4, v5
	v_log_f32_e32 v4, v4
	s_nop 0
	v_mul_f32_e32 v5, 0x3f317217, v4
	v_fma_f32 v5, v4, s8, -v5
	v_fmac_f32_e32 v5, 0x3377d1cf, v4
	v_fmac_f32_e32 v5, 0x3f317217, v4
	v_cmp_lt_f32_e64 s[40:41], |v4|, s9
	s_nop 1
	v_cndmask_b32_e64 v4, v4, v5, s[40:41]
	v_cndmask_b32_e32 v5, 0, v226, vcc
	v_sub_f32_e32 v4, v4, v5
	v_mul_f32_e32 v5, 0xbfb8aa3b, v78
	v_exp_f32_e32 v5, v5
	s_nop 0
	v_add_f32_e32 v5, 1.0, v5
	v_rcp_f32_e32 v5, v5
	s_nop 0
	v_fma_f32 v5, v5, v189, v29
	v_max_f32_e32 v5, 0x358637bd, v5
	v_cmp_gt_f32_e32 vcc, s7, v5
	s_nop 1
	v_cndmask_b32_e64 v8, 0, 32, vcc
	v_ldexp_f32 v5, v5, v8
	v_log_f32_e32 v5, v5
	s_nop 0
	v_mul_f32_e32 v8, 0x3f317217, v5
	v_fma_f32 v8, v5, s8, -v8
	v_fmac_f32_e32 v8, 0x3377d1cf, v5
	v_fmac_f32_e32 v8, 0x3f317217, v5
	v_cmp_lt_f32_e64 s[40:41], |v5|, s9
	s_nop 1
	v_cndmask_b32_e64 v5, v5, v8, s[40:41]
	v_cndmask_b32_e32 v8, 0, v226, vcc
	v_sub_f32_e32 v8, v5, v8
	v_mul_f32_e32 v5, 0xbfb8aa3b, v83
	v_exp_f32_e32 v5, v5
	s_nop 0
	v_add_f32_e32 v5, 1.0, v5
	v_rcp_f32_e32 v5, v5
	s_nop 0
	v_fma_f32 v5, v5, v191, v24
	v_max_f32_e32 v5, 0x358637bd, v5
	v_cmp_gt_f32_e32 vcc, s7, v5
	s_nop 1
	v_cndmask_b32_e64 v9, 0, 32, vcc
	v_ldexp_f32 v5, v5, v9
	v_log_f32_e32 v5, v5
	s_nop 0
	v_mul_f32_e32 v9, 0x3f317217, v5
	v_fma_f32 v9, v5, s8, -v9
	v_fmac_f32_e32 v9, 0x3377d1cf, v5
	v_fmac_f32_e32 v9, 0x3f317217, v5
	v_cmp_lt_f32_e64 s[40:41], |v5|, s9
	s_nop 1
	v_cndmask_b32_e64 v5, v5, v9, s[40:41]
	v_cndmask_b32_e32 v9, 0, v226, vcc
	v_sub_f32_e32 v5, v5, v9
	v_mul_f32_e32 v9, 0xbfb8aa3b, v79
	v_exp_f32_e32 v9, v9
	s_nop 0
	v_add_f32_e32 v9, 1.0, v9
	v_rcp_f32_e32 v9, v9
	s_nop 0
	v_fma_f32 v9, v9, v192, v26
	v_max_f32_e32 v9, 0x358637bd, v9
	v_cmp_gt_f32_e32 vcc, s7, v9
	s_nop 1
	v_cndmask_b32_e64 v14, 0, 32, vcc
	v_ldexp_f32 v9, v9, v14
	v_log_f32_e32 v9, v9
	s_nop 0
	v_mul_f32_e32 v14, 0x3f317217, v9
	v_fma_f32 v14, v9, s8, -v14
	v_fmac_f32_e32 v14, 0x3377d1cf, v9
	v_fmac_f32_e32 v14, 0x3f317217, v9
	v_cmp_lt_f32_e64 s[40:41], |v9|, s9
	s_nop 1
	v_cndmask_b32_e64 v9, v9, v14, s[40:41]
	v_cndmask_b32_e32 v14, 0, v226, vcc
	v_add_co_u32_e32 v16, vcc, s6, v12
	v_sub_f32_e32 v9, v9, v14
	s_nop 0
	v_addc_co_u32_e32 v17, vcc, 0, v13, vcc
	v_lshl_add_u64 v[14:15], v[12:13], 0, s[10:11]
	global_store_dwordx4 v[16:17], v[2:5], off
	global_store_dwordx4 v[14:15], v[6:9], off offset:16
	s_mov_b32 s6, 0x140000
	v_mul_f32_e32 v2, 0xbfb8aa3b, v72
	v_exp_f32_e32 v2, v2
	s_mov_b64 s[10:11], 0x140000
	v_add_f32_e32 v2, 1.0, v2
	v_rcp_f32_e32 v2, v2
	s_nop 0
	v_fma_f32 v2, v2, v193, v25
	v_max_f32_e32 v2, 0x358637bd, v2
	v_cmp_gt_f32_e32 vcc, s7, v2
	s_nop 1
	v_cndmask_b32_e64 v3, 0, 32, vcc
	v_ldexp_f32 v2, v2, v3
	v_log_f32_e32 v2, v2
	s_nop 0
	v_mul_f32_e32 v3, 0x3f317217, v2
	v_fma_f32 v3, v2, s8, -v3
	v_fmac_f32_e32 v3, 0x3377d1cf, v2
	v_fmac_f32_e32 v3, 0x3f317217, v2
	v_cmp_lt_f32_e64 s[40:41], |v2|, s9
	s_nop 1
	v_cndmask_b32_e64 v2, v2, v3, s[40:41]
	v_cndmask_b32_e32 v3, 0, v226, vcc
	v_sub_f32_e32 v2, v2, v3
	v_mul_f32_e32 v3, 0xbfb8aa3b, v68
	v_exp_f32_e32 v3, v3
	s_nop 0
	v_add_f32_e32 v3, 1.0, v3
	v_rcp_f32_e32 v3, v3
	s_nop 0
	v_fma_f32 v3, v3, v207, v27
	v_max_f32_e32 v3, 0x358637bd, v3
	v_cmp_gt_f32_e32 vcc, s7, v3
	s_nop 1
	v_cndmask_b32_e64 v4, 0, 32, vcc
	v_ldexp_f32 v3, v3, v4
	v_log_f32_e32 v3, v3
	s_nop 0
	v_mul_f32_e32 v4, 0x3f317217, v3
	v_fma_f32 v4, v3, s8, -v4
	v_fmac_f32_e32 v4, 0x3377d1cf, v3
	v_fmac_f32_e32 v4, 0x3f317217, v3
	v_cmp_lt_f32_e64 s[40:41], |v3|, s9
	s_nop 1
	v_cndmask_b32_e64 v3, v3, v4, s[40:41]
	v_cndmask_b32_e32 v4, 0, v226, vcc
	v_sub_f32_e32 v6, v3, v4
	v_mul_f32_e32 v3, 0xbfb8aa3b, v73
	v_exp_f32_e32 v3, v3
	s_nop 0
	v_add_f32_e32 v3, 1.0, v3
	v_rcp_f32_e32 v3, v3
	s_nop 0
	v_fma_f32 v3, v3, v209, v22
	v_max_f32_e32 v3, 0x358637bd, v3
	v_cmp_gt_f32_e32 vcc, s7, v3
	s_nop 1
	v_cndmask_b32_e64 v4, 0, 32, vcc
	v_ldexp_f32 v3, v3, v4
	v_log_f32_e32 v3, v3
	s_nop 0
	v_mul_f32_e32 v4, 0x3f317217, v3
	v_fma_f32 v4, v3, s8, -v4
	v_fmac_f32_e32 v4, 0x3377d1cf, v3
	v_fmac_f32_e32 v4, 0x3f317217, v3
	v_cmp_lt_f32_e64 s[40:41], |v3|, s9
	s_nop 1
	v_cndmask_b32_e64 v3, v3, v4, s[40:41]
	v_cndmask_b32_e32 v4, 0, v226, vcc
	v_sub_f32_e32 v3, v3, v4
	v_mul_f32_e32 v4, 0xbfb8aa3b, v69
	v_exp_f32_e32 v4, v4
	s_nop 0
	v_add_f32_e32 v4, 1.0, v4
	v_rcp_f32_e32 v4, v4
	s_nop 0
	v_fma_f32 v4, v4, v208, v23
	v_max_f32_e32 v4, 0x358637bd, v4
	v_cmp_gt_f32_e32 vcc, s7, v4
	s_nop 1
	v_cndmask_b32_e64 v5, 0, 32, vcc
	v_ldexp_f32 v4, v4, v5
	v_log_f32_e32 v4, v4
	s_nop 0
	v_mul_f32_e32 v5, 0x3f317217, v4
	v_fma_f32 v5, v4, s8, -v5
	v_fmac_f32_e32 v5, 0x3377d1cf, v4
	v_fmac_f32_e32 v5, 0x3f317217, v4
	v_cmp_lt_f32_e64 s[40:41], |v4|, s9
	s_nop 1
	v_cndmask_b32_e64 v4, v4, v5, s[40:41]
	v_cndmask_b32_e32 v5, 0, v226, vcc
	v_sub_f32_e32 v7, v4, v5
	v_mul_f32_e32 v4, 0xbfb8aa3b, v74
	v_exp_f32_e32 v4, v4
	s_nop 0
	v_add_f32_e32 v4, 1.0, v4
	v_rcp_f32_e32 v4, v4
	s_nop 0
	v_fma_f32 v4, v4, v211, v20
	v_max_f32_e32 v4, 0x358637bd, v4
	v_cmp_gt_f32_e32 vcc, s7, v4
	s_nop 1
	v_cndmask_b32_e64 v5, 0, 32, vcc
	v_ldexp_f32 v4, v4, v5
	v_log_f32_e32 v4, v4
	s_nop 0
	v_mul_f32_e32 v5, 0x3f317217, v4
	v_fma_f32 v5, v4, s8, -v5
	v_fmac_f32_e32 v5, 0x3377d1cf, v4
	v_fmac_f32_e32 v5, 0x3f317217, v4
	v_cmp_lt_f32_e64 s[40:41], |v4|, s9
	s_nop 1
	v_cndmask_b32_e64 v4, v4, v5, s[40:41]
	v_cndmask_b32_e32 v5, 0, v226, vcc
	v_sub_f32_e32 v4, v4, v5
	v_mul_f32_e32 v5, 0xbfb8aa3b, v70
	v_exp_f32_e32 v5, v5
	s_nop 0
	v_add_f32_e32 v5, 1.0, v5
	v_rcp_f32_e32 v5, v5
	s_nop 0
	v_fma_f32 v5, v5, v210, v21
	v_max_f32_e32 v5, 0x358637bd, v5
	v_cmp_gt_f32_e32 vcc, s7, v5
	s_nop 1
	v_cndmask_b32_e64 v8, 0, 32, vcc
	v_ldexp_f32 v5, v5, v8
	v_log_f32_e32 v5, v5
	s_nop 0
	v_mul_f32_e32 v8, 0x3f317217, v5
	v_fma_f32 v8, v5, s8, -v8
	v_fmac_f32_e32 v8, 0x3377d1cf, v5
	v_fmac_f32_e32 v8, 0x3f317217, v5
	v_cmp_lt_f32_e64 s[40:41], |v5|, s9
	s_nop 1
	v_cndmask_b32_e64 v5, v5, v8, s[40:41]
	v_cndmask_b32_e32 v8, 0, v226, vcc
	v_sub_f32_e32 v8, v5, v8
	v_mul_f32_e32 v5, 0xbfb8aa3b, v75
	v_exp_f32_e32 v5, v5
	s_nop 0
	v_add_f32_e32 v5, 1.0, v5
	v_rcp_f32_e32 v5, v5
	s_nop 0
	v_fma_f32 v5, v5, v212, v18
	v_max_f32_e32 v5, 0x358637bd, v5
	v_cmp_gt_f32_e32 vcc, s7, v5
	s_nop 1
	v_cndmask_b32_e64 v9, 0, 32, vcc
	v_ldexp_f32 v5, v5, v9
	v_log_f32_e32 v5, v5
	s_nop 0
	v_mul_f32_e32 v9, 0x3f317217, v5
	v_fma_f32 v9, v5, s8, -v9
	v_fmac_f32_e32 v9, 0x3377d1cf, v5
	v_fmac_f32_e32 v9, 0x3f317217, v5
	v_cmp_lt_f32_e64 s[40:41], |v5|, s9
	s_nop 1
	v_cndmask_b32_e64 v5, v5, v9, s[40:41]
	v_cndmask_b32_e32 v9, 0, v226, vcc
	v_sub_f32_e32 v5, v5, v9
	v_mul_f32_e32 v9, 0xbfb8aa3b, v71
	v_exp_f32_e32 v9, v9
	s_nop 0
	v_add_f32_e32 v9, 1.0, v9
	v_rcp_f32_e32 v9, v9
	s_nop 0
	v_fma_f32 v9, v9, v213, v19
	v_max_f32_e32 v9, 0x358637bd, v9
	v_cmp_gt_f32_e32 vcc, s7, v9
	s_nop 1
	v_cndmask_b32_e64 v16, 0, 32, vcc
	v_ldexp_f32 v9, v9, v16
	v_log_f32_e32 v9, v9
	s_nop 0
	v_mul_f32_e32 v16, 0x3f317217, v9
	v_fma_f32 v16, v9, s8, -v16
	v_fmac_f32_e32 v16, 0x3377d1cf, v9
	v_fmac_f32_e32 v16, 0x3f317217, v9
	v_cmp_lt_f32_e64 s[40:41], |v9|, s9
	s_nop 1
	v_cndmask_b32_e64 v9, v9, v16, s[40:41]
	v_cndmask_b32_e32 v16, 0, v226, vcc
	v_sub_f32_e32 v9, v9, v16
	global_store_dwordx4 v[14:15], v[2:5], off offset:512
	global_store_dwordx4 v[14:15], v[6:9], off offset:528
	s_nop 0
	v_mul_f32_e32 v2, 0xbfb8aa3b, v64
	v_exp_f32_e32 v2, v2
	s_nop 0
	v_add_f32_e32 v2, 1.0, v2
	v_rcp_f32_e32 v2, v2
	s_nop 0
	v_fma_f32 v2, v2, v186, v32
	v_max_f32_e32 v2, 0x358637bd, v2
	v_cmp_gt_f32_e32 vcc, s7, v2
	s_nop 1
	v_cndmask_b32_e64 v3, 0, 32, vcc
	v_ldexp_f32 v2, v2, v3
	v_log_f32_e32 v2, v2
	s_nop 0
	v_mul_f32_e32 v3, 0x3f317217, v2
	v_fma_f32 v3, v2, s8, -v3
	v_fmac_f32_e32 v3, 0x3377d1cf, v2
	v_fmac_f32_e32 v3, 0x3f317217, v2
	v_cmp_lt_f32_e64 s[40:41], |v2|, s9
	s_nop 1
	v_cndmask_b32_e64 v2, v2, v3, s[40:41]
	v_cndmask_b32_e32 v3, 0, v226, vcc
	v_sub_f32_e32 v2, v2, v3
	v_mul_f32_e32 v3, 0xbfb8aa3b, v60
	v_exp_f32_e32 v3, v3
	s_nop 0
	v_add_f32_e32 v3, 1.0, v3
	v_rcp_f32_e32 v3, v3
	s_nop 0
	v_fma_f32 v3, v3, v11, v33
	v_max_f32_e32 v3, 0x358637bd, v3
	v_cmp_gt_f32_e32 vcc, s7, v3
	s_nop 1
	v_cndmask_b32_e64 v4, 0, 32, vcc
	v_ldexp_f32 v3, v3, v4
	v_log_f32_e32 v3, v3
	s_nop 0
	v_mul_f32_e32 v4, 0x3f317217, v3
	v_fma_f32 v4, v3, s8, -v4
	v_fmac_f32_e32 v4, 0x3377d1cf, v3
	v_fmac_f32_e32 v4, 0x3f317217, v3
	v_cmp_lt_f32_e64 s[40:41], |v3|, s9
	s_nop 1
	v_cndmask_b32_e64 v3, v3, v4, s[40:41]
	v_cndmask_b32_e32 v4, 0, v226, vcc
	v_sub_f32_e32 v6, v3, v4
	v_mul_f32_e32 v3, 0xbfb8aa3b, v65
	v_exp_f32_e32 v3, v3
	s_nop 0
	v_add_f32_e32 v3, 1.0, v3
	v_rcp_f32_e32 v3, v3
	s_nop 0
	v_fma_f32 v3, v3, v188, v30
	v_max_f32_e32 v3, 0x358637bd, v3
	v_cmp_gt_f32_e32 vcc, s7, v3
	s_nop 1
	v_cndmask_b32_e64 v4, 0, 32, vcc
	v_ldexp_f32 v3, v3, v4
	v_log_f32_e32 v3, v3
	s_nop 0
	v_mul_f32_e32 v4, 0x3f317217, v3
	v_fma_f32 v4, v3, s8, -v4
	v_fmac_f32_e32 v4, 0x3377d1cf, v3
	v_fmac_f32_e32 v4, 0x3f317217, v3
	v_cmp_lt_f32_e64 s[40:41], |v3|, s9
	s_nop 1
	v_cndmask_b32_e64 v3, v3, v4, s[40:41]
	v_cndmask_b32_e32 v4, 0, v226, vcc
	v_sub_f32_e32 v3, v3, v4
	v_mul_f32_e32 v4, 0xbfb8aa3b, v61
	v_exp_f32_e32 v4, v4
	s_nop 0
	v_add_f32_e32 v4, 1.0, v4
	v_rcp_f32_e32 v4, v4
	s_nop 0
	v_fma_f32 v4, v4, v187, v31
	v_max_f32_e32 v4, 0x358637bd, v4
	v_cmp_gt_f32_e32 vcc, s7, v4
	s_nop 1
	v_cndmask_b32_e64 v5, 0, 32, vcc
	v_ldexp_f32 v4, v4, v5
	v_log_f32_e32 v4, v4
	s_nop 0
	v_mul_f32_e32 v5, 0x3f317217, v4
	v_fma_f32 v5, v4, s8, -v5
	v_fmac_f32_e32 v5, 0x3377d1cf, v4
	v_fmac_f32_e32 v5, 0x3f317217, v4
	v_cmp_lt_f32_e64 s[40:41], |v4|, s9
	s_nop 1
	v_cndmask_b32_e64 v4, v4, v5, s[40:41]
	v_cndmask_b32_e32 v5, 0, v226, vcc
	v_sub_f32_e32 v7, v4, v5
	v_mul_f32_e32 v4, 0xbfb8aa3b, v66
	v_exp_f32_e32 v4, v4
	s_nop 0
	v_add_f32_e32 v4, 1.0, v4
	v_rcp_f32_e32 v4, v4
	s_nop 0
	v_fma_f32 v4, v4, v190, v28
	v_max_f32_e32 v4, 0x358637bd, v4
	v_cmp_gt_f32_e32 vcc, s7, v4
	s_nop 1
	v_cndmask_b32_e64 v5, 0, 32, vcc
	v_ldexp_f32 v4, v4, v5
	v_log_f32_e32 v4, v4
	s_nop 0
	v_mul_f32_e32 v5, 0x3f317217, v4
	v_fma_f32 v5, v4, s8, -v5
	v_fmac_f32_e32 v5, 0x3377d1cf, v4
	v_fmac_f32_e32 v5, 0x3f317217, v4
	v_cmp_lt_f32_e64 s[40:41], |v4|, s9
	s_nop 1
	v_cndmask_b32_e64 v4, v4, v5, s[40:41]
	v_cndmask_b32_e32 v5, 0, v226, vcc
	v_sub_f32_e32 v4, v4, v5
	v_mul_f32_e32 v5, 0xbfb8aa3b, v62
	v_exp_f32_e32 v5, v5
	s_nop 0
	v_add_f32_e32 v5, 1.0, v5
	v_rcp_f32_e32 v5, v5
	s_nop 0
	v_fma_f32 v5, v5, v189, v29
	v_max_f32_e32 v5, 0x358637bd, v5
	v_cmp_gt_f32_e32 vcc, s7, v5
	s_nop 1
	v_cndmask_b32_e64 v8, 0, 32, vcc
	v_ldexp_f32 v5, v5, v8
	v_log_f32_e32 v5, v5
	s_nop 0
	v_mul_f32_e32 v8, 0x3f317217, v5
	v_fma_f32 v8, v5, s8, -v8
	v_fmac_f32_e32 v8, 0x3377d1cf, v5
	v_fmac_f32_e32 v8, 0x3f317217, v5
	v_cmp_lt_f32_e64 s[40:41], |v5|, s9
	s_nop 1
	v_cndmask_b32_e64 v5, v5, v8, s[40:41]
	v_cndmask_b32_e32 v8, 0, v226, vcc
	v_sub_f32_e32 v8, v5, v8
	v_mul_f32_e32 v5, 0xbfb8aa3b, v67
	v_exp_f32_e32 v5, v5
	s_nop 0
	v_add_f32_e32 v5, 1.0, v5
	v_rcp_f32_e32 v5, v5
	s_nop 0
	v_fma_f32 v5, v5, v191, v24
	v_max_f32_e32 v5, 0x358637bd, v5
	v_cmp_gt_f32_e32 vcc, s7, v5
	s_nop 1
	v_cndmask_b32_e64 v9, 0, 32, vcc
	v_ldexp_f32 v5, v5, v9
	v_log_f32_e32 v5, v5
	s_nop 0
	v_mul_f32_e32 v9, 0x3f317217, v5
	v_fma_f32 v9, v5, s8, -v9
	v_fmac_f32_e32 v9, 0x3377d1cf, v5
	v_fmac_f32_e32 v9, 0x3f317217, v5
	v_cmp_lt_f32_e64 s[40:41], |v5|, s9
	s_nop 1
	v_cndmask_b32_e64 v5, v5, v9, s[40:41]
	v_cndmask_b32_e32 v9, 0, v226, vcc
	v_sub_f32_e32 v5, v5, v9
	v_mul_f32_e32 v9, 0xbfb8aa3b, v63
	v_exp_f32_e32 v9, v9
	s_nop 0
	v_add_f32_e32 v9, 1.0, v9
	v_rcp_f32_e32 v9, v9
	s_nop 0
	v_fma_f32 v9, v9, v192, v26
	v_max_f32_e32 v9, 0x358637bd, v9
	v_cmp_gt_f32_e32 vcc, s7, v9
	s_nop 1
	v_cndmask_b32_e64 v14, 0, 32, vcc
	v_ldexp_f32 v9, v9, v14
	v_log_f32_e32 v9, v9
	s_nop 0
	v_mul_f32_e32 v14, 0x3f317217, v9
	v_fma_f32 v14, v9, s8, -v14
	v_fmac_f32_e32 v14, 0x3377d1cf, v9
	v_fmac_f32_e32 v14, 0x3f317217, v9
	v_cmp_lt_f32_e64 s[40:41], |v9|, s9
	s_nop 1
	v_cndmask_b32_e64 v9, v9, v14, s[40:41]
	v_cndmask_b32_e32 v14, 0, v226, vcc
	v_add_co_u32_e32 v16, vcc, s6, v12
	v_sub_f32_e32 v9, v9, v14
	s_nop 0
	v_addc_co_u32_e32 v17, vcc, 0, v13, vcc
	v_lshl_add_u64 v[14:15], v[12:13], 0, s[10:11]
	global_store_dwordx4 v[16:17], v[2:5], off
	global_store_dwordx4 v[14:15], v[6:9], off offset:16
	s_mov_b64 s[10:11], 0x160000
	v_mul_f32_e32 v2, 0xbfb8aa3b, v56
	v_exp_f32_e32 v2, v2
	s_mov_b32 s6, 0x160000
	v_add_f32_e32 v2, 1.0, v2
	v_rcp_f32_e32 v2, v2
	s_nop 0
	v_fma_f32 v2, v2, v193, v25
	v_max_f32_e32 v2, 0x358637bd, v2
	v_cmp_gt_f32_e32 vcc, s7, v2
	s_nop 1
	v_cndmask_b32_e64 v3, 0, 32, vcc
	v_ldexp_f32 v2, v2, v3
	v_log_f32_e32 v2, v2
	s_nop 0
	v_mul_f32_e32 v3, 0x3f317217, v2
	v_fma_f32 v3, v2, s8, -v3
	v_fmac_f32_e32 v3, 0x3377d1cf, v2
	v_fmac_f32_e32 v3, 0x3f317217, v2
	v_cmp_lt_f32_e64 s[40:41], |v2|, s9
	s_nop 1
	v_cndmask_b32_e64 v2, v2, v3, s[40:41]
	v_cndmask_b32_e32 v3, 0, v226, vcc
	v_sub_f32_e32 v2, v2, v3
	v_mul_f32_e32 v3, 0xbfb8aa3b, v52
	v_exp_f32_e32 v3, v3
	s_nop 0
	v_add_f32_e32 v3, 1.0, v3
	v_rcp_f32_e32 v3, v3
	s_nop 0
	v_fma_f32 v3, v3, v207, v27
	v_max_f32_e32 v3, 0x358637bd, v3
	v_cmp_gt_f32_e32 vcc, s7, v3
	s_nop 1
	v_cndmask_b32_e64 v4, 0, 32, vcc
	v_ldexp_f32 v3, v3, v4
	v_log_f32_e32 v3, v3
	s_nop 0
	v_mul_f32_e32 v4, 0x3f317217, v3
	v_fma_f32 v4, v3, s8, -v4
	v_fmac_f32_e32 v4, 0x3377d1cf, v3
	v_fmac_f32_e32 v4, 0x3f317217, v3
	v_cmp_lt_f32_e64 s[40:41], |v3|, s9
	s_nop 1
	v_cndmask_b32_e64 v3, v3, v4, s[40:41]
	v_cndmask_b32_e32 v4, 0, v226, vcc
	v_sub_f32_e32 v6, v3, v4
	v_mul_f32_e32 v3, 0xbfb8aa3b, v57
	v_exp_f32_e32 v3, v3
	s_nop 0
	v_add_f32_e32 v3, 1.0, v3
	v_rcp_f32_e32 v3, v3
	s_nop 0
	v_fma_f32 v3, v3, v209, v22
	v_max_f32_e32 v3, 0x358637bd, v3
	v_cmp_gt_f32_e32 vcc, s7, v3
	s_nop 1
	v_cndmask_b32_e64 v4, 0, 32, vcc
	v_ldexp_f32 v3, v3, v4
	v_log_f32_e32 v3, v3
	s_nop 0
	v_mul_f32_e32 v4, 0x3f317217, v3
	v_fma_f32 v4, v3, s8, -v4
	v_fmac_f32_e32 v4, 0x3377d1cf, v3
	v_fmac_f32_e32 v4, 0x3f317217, v3
	v_cmp_lt_f32_e64 s[40:41], |v3|, s9
	s_nop 1
	v_cndmask_b32_e64 v3, v3, v4, s[40:41]
	v_cndmask_b32_e32 v4, 0, v226, vcc
	v_sub_f32_e32 v3, v3, v4
	v_mul_f32_e32 v4, 0xbfb8aa3b, v53
	v_exp_f32_e32 v4, v4
	s_nop 0
	v_add_f32_e32 v4, 1.0, v4
	v_rcp_f32_e32 v4, v4
	s_nop 0
	v_fma_f32 v4, v4, v208, v23
	v_max_f32_e32 v4, 0x358637bd, v4
	v_cmp_gt_f32_e32 vcc, s7, v4
	s_nop 1
	v_cndmask_b32_e64 v5, 0, 32, vcc
	v_ldexp_f32 v4, v4, v5
	v_log_f32_e32 v4, v4
	s_nop 0
	v_mul_f32_e32 v5, 0x3f317217, v4
	v_fma_f32 v5, v4, s8, -v5
	v_fmac_f32_e32 v5, 0x3377d1cf, v4
	v_fmac_f32_e32 v5, 0x3f317217, v4
	v_cmp_lt_f32_e64 s[40:41], |v4|, s9
	s_nop 1
	v_cndmask_b32_e64 v4, v4, v5, s[40:41]
	v_cndmask_b32_e32 v5, 0, v226, vcc
	v_sub_f32_e32 v7, v4, v5
	v_mul_f32_e32 v4, 0xbfb8aa3b, v58
	v_exp_f32_e32 v4, v4
	s_nop 0
	v_add_f32_e32 v4, 1.0, v4
	v_rcp_f32_e32 v4, v4
	s_nop 0
	v_fma_f32 v4, v4, v211, v20
	v_max_f32_e32 v4, 0x358637bd, v4
	v_cmp_gt_f32_e32 vcc, s7, v4
	s_nop 1
	v_cndmask_b32_e64 v5, 0, 32, vcc
	v_ldexp_f32 v4, v4, v5
	v_log_f32_e32 v4, v4
	s_nop 0
	v_mul_f32_e32 v5, 0x3f317217, v4
	v_fma_f32 v5, v4, s8, -v5
	v_fmac_f32_e32 v5, 0x3377d1cf, v4
	v_fmac_f32_e32 v5, 0x3f317217, v4
	v_cmp_lt_f32_e64 s[40:41], |v4|, s9
	s_nop 1
	v_cndmask_b32_e64 v4, v4, v5, s[40:41]
	v_cndmask_b32_e32 v5, 0, v226, vcc
	v_sub_f32_e32 v4, v4, v5
	v_mul_f32_e32 v5, 0xbfb8aa3b, v54
	v_exp_f32_e32 v5, v5
	s_nop 0
	v_add_f32_e32 v5, 1.0, v5
	v_rcp_f32_e32 v5, v5
	s_nop 0
	v_fma_f32 v5, v5, v210, v21
	v_max_f32_e32 v5, 0x358637bd, v5
	v_cmp_gt_f32_e32 vcc, s7, v5
	s_nop 1
	v_cndmask_b32_e64 v8, 0, 32, vcc
	v_ldexp_f32 v5, v5, v8
	v_log_f32_e32 v5, v5
	s_nop 0
	v_mul_f32_e32 v8, 0x3f317217, v5
	v_fma_f32 v8, v5, s8, -v8
	v_fmac_f32_e32 v8, 0x3377d1cf, v5
	v_fmac_f32_e32 v8, 0x3f317217, v5
	v_cmp_lt_f32_e64 s[40:41], |v5|, s9
	s_nop 1
	v_cndmask_b32_e64 v5, v5, v8, s[40:41]
	v_cndmask_b32_e32 v8, 0, v226, vcc
	v_sub_f32_e32 v8, v5, v8
	v_mul_f32_e32 v5, 0xbfb8aa3b, v59
	v_exp_f32_e32 v5, v5
	s_nop 0
	v_add_f32_e32 v5, 1.0, v5
	v_rcp_f32_e32 v5, v5
	s_nop 0
	v_fma_f32 v5, v5, v212, v18
	v_max_f32_e32 v5, 0x358637bd, v5
	v_cmp_gt_f32_e32 vcc, s7, v5
	s_nop 1
	v_cndmask_b32_e64 v9, 0, 32, vcc
	v_ldexp_f32 v5, v5, v9
	v_log_f32_e32 v5, v5
	s_nop 0
	v_mul_f32_e32 v9, 0x3f317217, v5
	v_fma_f32 v9, v5, s8, -v9
	v_fmac_f32_e32 v9, 0x3377d1cf, v5
	v_fmac_f32_e32 v9, 0x3f317217, v5
	v_cmp_lt_f32_e64 s[40:41], |v5|, s9
	s_nop 1
	v_cndmask_b32_e64 v5, v5, v9, s[40:41]
	v_cndmask_b32_e32 v9, 0, v226, vcc
	v_sub_f32_e32 v5, v5, v9
	v_mul_f32_e32 v9, 0xbfb8aa3b, v55
	v_exp_f32_e32 v9, v9
	s_nop 0
	v_add_f32_e32 v9, 1.0, v9
	v_rcp_f32_e32 v9, v9
	s_nop 0
	v_fma_f32 v9, v9, v213, v19
	v_max_f32_e32 v9, 0x358637bd, v9
	v_cmp_gt_f32_e32 vcc, s7, v9
	s_nop 1
	v_cndmask_b32_e64 v16, 0, 32, vcc
	v_ldexp_f32 v9, v9, v16
	v_log_f32_e32 v9, v9
	s_nop 0
	v_mul_f32_e32 v16, 0x3f317217, v9
	v_fma_f32 v16, v9, s8, -v16
	v_fmac_f32_e32 v16, 0x3377d1cf, v9
	v_fmac_f32_e32 v16, 0x3f317217, v9
	v_cmp_lt_f32_e64 s[40:41], |v9|, s9
	s_nop 1
	v_cndmask_b32_e64 v9, v9, v16, s[40:41]
	v_cndmask_b32_e32 v16, 0, v226, vcc
	v_sub_f32_e32 v9, v9, v16
	global_store_dwordx4 v[14:15], v[2:5], off offset:512
	global_store_dwordx4 v[14:15], v[6:9], off offset:528
	v_lshl_add_u64 v[14:15], v[12:13], 0, s[10:11]
	v_mul_f32_e32 v2, 0xbfb8aa3b, v48
	v_exp_f32_e32 v2, v2
	s_nop 0
	v_add_f32_e32 v2, 1.0, v2
	v_rcp_f32_e32 v2, v2
	s_nop 0
	v_fmac_f32_e32 v32, v2, v186
	v_max_f32_e32 v2, 0x358637bd, v32
	v_cmp_gt_f32_e32 vcc, s7, v2
	s_nop 1
	v_cndmask_b32_e64 v3, 0, 32, vcc
	v_ldexp_f32 v2, v2, v3
	v_log_f32_e32 v2, v2
	s_nop 0
	v_mul_f32_e32 v3, 0x3f317217, v2
	v_fma_f32 v3, v2, s8, -v3
	v_fmac_f32_e32 v3, 0x3377d1cf, v2
	v_fmac_f32_e32 v3, 0x3f317217, v2
	v_cmp_lt_f32_e64 s[40:41], |v2|, s9
	s_nop 1
	v_cndmask_b32_e64 v2, v2, v3, s[40:41]
	v_cndmask_b32_e32 v3, 0, v226, vcc
	v_sub_f32_e32 v2, v2, v3
	v_mul_f32_e32 v3, 0xbfb8aa3b, v44
	v_exp_f32_e32 v3, v3
	s_nop 0
	v_add_f32_e32 v3, 1.0, v3
	v_rcp_f32_e32 v3, v3
	s_nop 0
	v_fmac_f32_e32 v33, v3, v11
	v_max_f32_e32 v3, 0x358637bd, v33
	v_cmp_gt_f32_e32 vcc, s7, v3
	s_nop 1
	v_cndmask_b32_e64 v4, 0, 32, vcc
	v_ldexp_f32 v3, v3, v4
	v_log_f32_e32 v3, v3
	s_nop 0
	v_mul_f32_e32 v4, 0x3f317217, v3
	v_fma_f32 v4, v3, s8, -v4
	v_fmac_f32_e32 v4, 0x3377d1cf, v3
	v_fmac_f32_e32 v4, 0x3f317217, v3
	v_cmp_lt_f32_e64 s[40:41], |v3|, s9
	s_nop 1
	v_cndmask_b32_e64 v3, v3, v4, s[40:41]
	v_cndmask_b32_e32 v4, 0, v226, vcc
	v_sub_f32_e32 v6, v3, v4
	v_mul_f32_e32 v3, 0xbfb8aa3b, v49
	v_exp_f32_e32 v3, v3
	s_nop 0
	v_add_f32_e32 v3, 1.0, v3
	v_rcp_f32_e32 v3, v3
	s_nop 0
	v_fmac_f32_e32 v30, v3, v188
	v_max_f32_e32 v3, 0x358637bd, v30
	v_cmp_gt_f32_e32 vcc, s7, v3
	s_nop 1
	v_cndmask_b32_e64 v4, 0, 32, vcc
	v_ldexp_f32 v3, v3, v4
	v_log_f32_e32 v3, v3
	s_nop 0
	v_mul_f32_e32 v4, 0x3f317217, v3
	v_fma_f32 v4, v3, s8, -v4
	v_fmac_f32_e32 v4, 0x3377d1cf, v3
	v_fmac_f32_e32 v4, 0x3f317217, v3
	v_cmp_lt_f32_e64 s[40:41], |v3|, s9
	s_nop 1
	v_cndmask_b32_e64 v3, v3, v4, s[40:41]
	v_cndmask_b32_e32 v4, 0, v226, vcc
	v_sub_f32_e32 v3, v3, v4
	v_mul_f32_e32 v4, 0xbfb8aa3b, v45
	v_exp_f32_e32 v4, v4
	s_nop 0
	v_add_f32_e32 v4, 1.0, v4
	v_rcp_f32_e32 v4, v4
	s_nop 0
	v_fmac_f32_e32 v31, v4, v187
	v_max_f32_e32 v4, 0x358637bd, v31
	v_cmp_gt_f32_e32 vcc, s7, v4
	s_nop 1
	v_cndmask_b32_e64 v5, 0, 32, vcc
	v_ldexp_f32 v4, v4, v5
	v_log_f32_e32 v4, v4
	s_nop 0
	v_mul_f32_e32 v5, 0x3f317217, v4
	v_fma_f32 v5, v4, s8, -v5
	v_fmac_f32_e32 v5, 0x3377d1cf, v4
	v_fmac_f32_e32 v5, 0x3f317217, v4
	v_cmp_lt_f32_e64 s[40:41], |v4|, s9
	s_nop 1
	v_cndmask_b32_e64 v4, v4, v5, s[40:41]
	v_cndmask_b32_e32 v5, 0, v226, vcc
	v_sub_f32_e32 v7, v4, v5
	v_mul_f32_e32 v4, 0xbfb8aa3b, v50
	v_exp_f32_e32 v4, v4
	s_nop 0
	v_add_f32_e32 v4, 1.0, v4
	v_rcp_f32_e32 v4, v4
	s_nop 0
	v_fmac_f32_e32 v28, v4, v190
	v_max_f32_e32 v4, 0x358637bd, v28
	v_cmp_gt_f32_e32 vcc, s7, v4
	s_nop 1
	v_cndmask_b32_e64 v5, 0, 32, vcc
	v_ldexp_f32 v4, v4, v5
	v_log_f32_e32 v4, v4
	s_nop 0
	v_mul_f32_e32 v5, 0x3f317217, v4
	v_fma_f32 v5, v4, s8, -v5
	v_fmac_f32_e32 v5, 0x3377d1cf, v4
	v_fmac_f32_e32 v5, 0x3f317217, v4
	v_cmp_lt_f32_e64 s[40:41], |v4|, s9
	s_nop 1
	v_cndmask_b32_e64 v4, v4, v5, s[40:41]
	v_cndmask_b32_e32 v5, 0, v226, vcc
	v_sub_f32_e32 v4, v4, v5
	v_mul_f32_e32 v5, 0xbfb8aa3b, v46
	v_exp_f32_e32 v5, v5
	s_nop 0
	v_add_f32_e32 v5, 1.0, v5
	v_rcp_f32_e32 v5, v5
	s_nop 0
	v_fmac_f32_e32 v29, v5, v189
	v_max_f32_e32 v5, 0x358637bd, v29
	v_cmp_gt_f32_e32 vcc, s7, v5
	s_nop 1
	v_cndmask_b32_e64 v8, 0, 32, vcc
	v_ldexp_f32 v5, v5, v8
	v_log_f32_e32 v5, v5
	s_nop 0
	v_mul_f32_e32 v8, 0x3f317217, v5
	v_fma_f32 v8, v5, s8, -v8
	v_fmac_f32_e32 v8, 0x3377d1cf, v5
	v_fmac_f32_e32 v8, 0x3f317217, v5
	v_cmp_lt_f32_e64 s[40:41], |v5|, s9
	s_nop 1
	v_cndmask_b32_e64 v5, v5, v8, s[40:41]
	v_cndmask_b32_e32 v8, 0, v226, vcc
	v_sub_f32_e32 v8, v5, v8
	v_mul_f32_e32 v5, 0xbfb8aa3b, v51
	v_exp_f32_e32 v5, v5
	s_nop 0
	v_add_f32_e32 v5, 1.0, v5
	v_rcp_f32_e32 v5, v5
	s_nop 0
	v_fmac_f32_e32 v24, v5, v191
	v_max_f32_e32 v5, 0x358637bd, v24
	v_cmp_gt_f32_e32 vcc, s7, v5
	s_nop 1
	v_cndmask_b32_e64 v9, 0, 32, vcc
	v_ldexp_f32 v5, v5, v9
	v_log_f32_e32 v5, v5
	s_nop 0
	v_mul_f32_e32 v9, 0x3f317217, v5
	v_fma_f32 v9, v5, s8, -v9
	v_fmac_f32_e32 v9, 0x3377d1cf, v5
	v_fmac_f32_e32 v9, 0x3f317217, v5
	v_cmp_lt_f32_e64 s[40:41], |v5|, s9
	s_nop 1
	v_cndmask_b32_e64 v5, v5, v9, s[40:41]
	v_cndmask_b32_e32 v9, 0, v226, vcc
	v_sub_f32_e32 v5, v5, v9
	v_mul_f32_e32 v9, 0xbfb8aa3b, v47
	v_exp_f32_e32 v9, v9
	s_nop 0
	v_add_f32_e32 v9, 1.0, v9
	v_rcp_f32_e32 v9, v9
	s_nop 0
	v_fmac_f32_e32 v26, v9, v192
	v_max_f32_e32 v9, 0x358637bd, v26
	v_cmp_gt_f32_e32 vcc, s7, v9
	s_nop 1
	v_cndmask_b32_e64 v11, 0, 32, vcc
	v_ldexp_f32 v9, v9, v11
	v_log_f32_e32 v9, v9
	s_nop 0
	v_mul_f32_e32 v11, 0x3f317217, v9
	v_fma_f32 v11, v9, s8, -v11
	v_fmac_f32_e32 v11, 0x3377d1cf, v9
	v_fmac_f32_e32 v11, 0x3f317217, v9
	v_cmp_lt_f32_e64 s[40:41], |v9|, s9
	s_nop 1
	v_cndmask_b32_e64 v9, v9, v11, s[40:41]
	v_cndmask_b32_e32 v11, 0, v226, vcc
	v_add_co_u32_e32 v12, vcc, s6, v12
	v_sub_f32_e32 v9, v9, v11
	s_nop 0
	v_addc_co_u32_e32 v13, vcc, 0, v13, vcc
	global_store_dwordx4 v[12:13], v[2:5], off
	global_store_dwordx4 v[14:15], v[6:9], off offset:16
	s_nop 0
	v_mul_f32_e32 v2, 0xbfb8aa3b, v40
	v_exp_f32_e32 v2, v2
	s_nop 0
	v_add_f32_e32 v2, 1.0, v2
	v_rcp_f32_e32 v2, v2
	s_nop 0
	v_fmac_f32_e32 v25, v2, v193
	v_max_f32_e32 v2, 0x358637bd, v25
	v_cmp_gt_f32_e32 vcc, s7, v2
	s_nop 1
	v_cndmask_b32_e64 v3, 0, 32, vcc
	v_ldexp_f32 v2, v2, v3
	v_log_f32_e32 v2, v2
	s_nop 0
	v_mul_f32_e32 v3, 0x3f317217, v2
	v_fma_f32 v3, v2, s8, -v3
	v_fmac_f32_e32 v3, 0x3377d1cf, v2
	v_fmac_f32_e32 v3, 0x3f317217, v2
	v_cmp_lt_f32_e64 s[40:41], |v2|, s9
	s_nop 1
	v_cndmask_b32_e64 v2, v2, v3, s[40:41]
	v_cndmask_b32_e32 v3, 0, v226, vcc
	v_sub_f32_e32 v2, v2, v3
	v_mul_f32_e32 v3, 0xbfb8aa3b, v36
	v_exp_f32_e32 v3, v3
	s_nop 0
	v_add_f32_e32 v3, 1.0, v3
	v_rcp_f32_e32 v3, v3
	s_nop 0
	v_fmac_f32_e32 v27, v3, v207
	v_max_f32_e32 v3, 0x358637bd, v27
	v_cmp_gt_f32_e32 vcc, s7, v3
	s_nop 1
	v_cndmask_b32_e64 v4, 0, 32, vcc
	v_ldexp_f32 v3, v3, v4
	v_log_f32_e32 v3, v3
	s_nop 0
	v_mul_f32_e32 v4, 0x3f317217, v3
	v_fma_f32 v4, v3, s8, -v4
	v_fmac_f32_e32 v4, 0x3377d1cf, v3
	v_fmac_f32_e32 v4, 0x3f317217, v3
	v_cmp_lt_f32_e64 s[40:41], |v3|, s9
	s_nop 1
	v_cndmask_b32_e64 v3, v3, v4, s[40:41]
	v_cndmask_b32_e32 v4, 0, v226, vcc
	v_sub_f32_e32 v6, v3, v4
	v_mul_f32_e32 v3, 0xbfb8aa3b, v41
	v_exp_f32_e32 v3, v3
	s_nop 0
	v_add_f32_e32 v3, 1.0, v3
	v_rcp_f32_e32 v3, v3
	s_nop 0
	v_fmac_f32_e32 v22, v3, v209
	v_max_f32_e32 v3, 0x358637bd, v22
	v_cmp_gt_f32_e32 vcc, s7, v3
	s_nop 1
	v_cndmask_b32_e64 v4, 0, 32, vcc
	v_ldexp_f32 v3, v3, v4
	v_log_f32_e32 v3, v3
	s_nop 0
	v_mul_f32_e32 v4, 0x3f317217, v3
	v_fma_f32 v4, v3, s8, -v4
	v_fmac_f32_e32 v4, 0x3377d1cf, v3
	v_fmac_f32_e32 v4, 0x3f317217, v3
	v_cmp_lt_f32_e64 s[40:41], |v3|, s9
	s_nop 1
	v_cndmask_b32_e64 v3, v3, v4, s[40:41]
	v_cndmask_b32_e32 v4, 0, v226, vcc
	v_sub_f32_e32 v3, v3, v4
	v_mul_f32_e32 v4, 0xbfb8aa3b, v37
	v_exp_f32_e32 v4, v4
	s_nop 0
	v_add_f32_e32 v4, 1.0, v4
	v_rcp_f32_e32 v4, v4
	s_nop 0
	v_fmac_f32_e32 v23, v4, v208
	v_max_f32_e32 v4, 0x358637bd, v23
	v_cmp_gt_f32_e32 vcc, s7, v4
	s_nop 1
	v_cndmask_b32_e64 v5, 0, 32, vcc
	v_ldexp_f32 v4, v4, v5
	v_log_f32_e32 v4, v4
	s_nop 0
	v_mul_f32_e32 v5, 0x3f317217, v4
	v_fma_f32 v5, v4, s8, -v5
	v_fmac_f32_e32 v5, 0x3377d1cf, v4
	v_fmac_f32_e32 v5, 0x3f317217, v4
	v_cmp_lt_f32_e64 s[40:41], |v4|, s9
	s_nop 1
	v_cndmask_b32_e64 v4, v4, v5, s[40:41]
	v_cndmask_b32_e32 v5, 0, v226, vcc
	v_sub_f32_e32 v7, v4, v5
	v_mul_f32_e32 v4, 0xbfb8aa3b, v42
	v_exp_f32_e32 v4, v4
	s_nop 0
	v_add_f32_e32 v4, 1.0, v4
	v_rcp_f32_e32 v4, v4
	s_nop 0
	v_fmac_f32_e32 v20, v4, v211
	v_max_f32_e32 v4, 0x358637bd, v20
	v_cmp_gt_f32_e32 vcc, s7, v4
	s_nop 1
	v_cndmask_b32_e64 v5, 0, 32, vcc
	v_ldexp_f32 v4, v4, v5
	v_log_f32_e32 v4, v4
	s_nop 0
	v_mul_f32_e32 v5, 0x3f317217, v4
	v_fma_f32 v5, v4, s8, -v5
	v_fmac_f32_e32 v5, 0x3377d1cf, v4
	v_fmac_f32_e32 v5, 0x3f317217, v4
	v_cmp_lt_f32_e64 s[40:41], |v4|, s9
	s_nop 1
	v_cndmask_b32_e64 v4, v4, v5, s[40:41]
	v_cndmask_b32_e32 v5, 0, v226, vcc
	v_sub_f32_e32 v4, v4, v5
	v_mul_f32_e32 v5, 0xbfb8aa3b, v38
	v_exp_f32_e32 v5, v5
	s_nop 0
	v_add_f32_e32 v5, 1.0, v5
	v_rcp_f32_e32 v5, v5
	s_nop 0
	v_fmac_f32_e32 v21, v5, v210
	v_max_f32_e32 v5, 0x358637bd, v21
	v_cmp_gt_f32_e32 vcc, s7, v5
	s_nop 1
	v_cndmask_b32_e64 v8, 0, 32, vcc
	v_ldexp_f32 v5, v5, v8
	v_log_f32_e32 v5, v5
	s_nop 0
	v_mul_f32_e32 v8, 0x3f317217, v5
	v_fma_f32 v8, v5, s8, -v8
	v_fmac_f32_e32 v8, 0x3377d1cf, v5
	v_fmac_f32_e32 v8, 0x3f317217, v5
	v_cmp_lt_f32_e64 s[40:41], |v5|, s9
	s_nop 1
	v_cndmask_b32_e64 v5, v5, v8, s[40:41]
	v_cndmask_b32_e32 v8, 0, v226, vcc
	v_sub_f32_e32 v8, v5, v8
	v_mul_f32_e32 v5, 0xbfb8aa3b, v43
	v_exp_f32_e32 v5, v5
	s_nop 0
	v_add_f32_e32 v5, 1.0, v5
	v_rcp_f32_e32 v5, v5
	s_nop 0
	v_fmac_f32_e32 v18, v5, v212
	v_max_f32_e32 v5, 0x358637bd, v18
	v_cmp_gt_f32_e32 vcc, s7, v5
	s_nop 1
	v_cndmask_b32_e64 v9, 0, 32, vcc
	v_ldexp_f32 v5, v5, v9
	v_log_f32_e32 v5, v5
	s_nop 0
	v_mul_f32_e32 v9, 0x3f317217, v5
	v_fma_f32 v9, v5, s8, -v9
	v_fmac_f32_e32 v9, 0x3377d1cf, v5
	v_fmac_f32_e32 v9, 0x3f317217, v5
	v_cmp_lt_f32_e64 s[40:41], |v5|, s9
	s_nop 1
	v_cndmask_b32_e64 v5, v5, v9, s[40:41]
	v_cndmask_b32_e32 v9, 0, v226, vcc
	v_sub_f32_e32 v5, v5, v9
	v_mul_f32_e32 v9, 0xbfb8aa3b, v39
	v_exp_f32_e32 v9, v9
	s_nop 0
	v_add_f32_e32 v9, 1.0, v9
	v_rcp_f32_e32 v9, v9
	s_nop 0
	v_fmac_f32_e32 v19, v9, v213
	v_max_f32_e32 v9, 0x358637bd, v19
	v_cmp_gt_f32_e32 vcc, s7, v9
	s_nop 1
	v_cndmask_b32_e64 v11, 0, 32, vcc
	v_ldexp_f32 v9, v9, v11
	v_log_f32_e32 v9, v9
	s_nop 0
	v_mul_f32_e32 v11, 0x3f317217, v9
	v_fma_f32 v11, v9, s8, -v11
	v_fmac_f32_e32 v11, 0x3377d1cf, v9
	v_fmac_f32_e32 v11, 0x3f317217, v9
	v_cmp_lt_f32_e64 s[40:41], |v9|, s9
	s_nop 1
	v_cndmask_b32_e64 v9, v9, v11, s[40:41]
	v_cndmask_b32_e32 v11, 0, v226, vcc
	v_sub_f32_e32 v9, v9, v11
	global_store_dwordx4 v[14:15], v[2:5], off offset:512
	global_store_dwordx4 v[14:15], v[6:9], off offset:528

.LBB0_269:
	v_mul_f32_e32 v3, 0xbfb8aa3b, v160
	v_exp_f32_e32 v3, v3
	v_ashrrev_i32_e32 v11, 31, v10
	v_lshlrev_b64 v[4:5], 12, v[10:11]
	v_lshl_add_u64 v[12:13], s[42:43], 0, v[4:5]
	v_add_f32_e32 v3, 1.0, v3
	v_rcp_f32_e32 v4, v3
	v_mul_f32_e32 v3, 0xbfb8aa3b, v156
	v_exp_f32_e32 v3, v3
	v_mul_f32_e32 v11, 0xbfb8aa3b, v154
	v_exp_f32_e32 v11, v11
	v_lshl_or_b32 v2, s74, 8, v195
	v_add_f32_e32 v3, 1.0, v3
	v_rcp_f32_e32 v6, v3
	v_mul_f32_e32 v3, 0xbfb8aa3b, v161
	v_exp_f32_e32 v3, v3
	v_add_f32_e32 v11, 1.0, v11
	s_mov_b64 s[6:7], 0x80000
	v_add_f32_e32 v3, 1.0, v3
	v_rcp_f32_e32 v5, v3
	v_mul_f32_e32 v3, 0xbfb8aa3b, v157
	v_exp_f32_e32 v3, v3
	v_pk_mul_f32 v[4:5], v[160:161], v[4:5]
	v_add_f32_e32 v3, 1.0, v3
	v_rcp_f32_e32 v7, v3
	v_mul_f32_e32 v3, 0xbfb8aa3b, v162
	v_exp_f32_e32 v3, v3
	v_pk_mul_f32 v[8:9], v[156:157], v[6:7]
	s_nop 0
	v_cvt_pk_bf16_f32 v8, v8, v9
	v_add_f32_e32 v3, 1.0, v3
	v_rcp_f32_e32 v6, v3
	v_mul_f32_e32 v3, 0xbfb8aa3b, v158
	v_exp_f32_e32 v3, v3
	s_nop 0
	v_add_f32_e32 v3, 1.0, v3
	v_rcp_f32_e32 v14, v3
	v_mul_f32_e32 v3, 0xbfb8aa3b, v163
	v_exp_f32_e32 v3, v3
	s_nop 0
	v_add_f32_e32 v3, 1.0, v3
	v_rcp_f32_e32 v7, v3
	v_mul_f32_e32 v3, 0xbfb8aa3b, v159
	v_exp_f32_e32 v3, v3
	v_pk_mul_f32 v[16:17], v[162:163], v[6:7]
	v_cvt_pk_bf16_f32 v6, v4, v5
	v_add_f32_e32 v3, 1.0, v3
	v_rcp_f32_e32 v15, v3
	v_ashrrev_i32_e32 v3, 31, v2
	v_lshlrev_b64 v[4:5], 1, v[2:3]
	v_lshl_add_u64 v[2:3], v[12:13], 0, v[4:5]
	v_rcp_f32_e32 v12, v11
	v_mul_f32_e32 v11, 0xbfb8aa3b, v150
	v_exp_f32_e32 v11, v11
	v_pk_mul_f32 v[14:15], v[158:159], v[14:15]
	v_cvt_pk_bf16_f32 v7, v16, v17
	v_cvt_pk_bf16_f32 v9, v14, v15
	v_add_f32_e32 v11, 1.0, v11
	v_rcp_f32_e32 v14, v11
	v_mul_f32_e32 v11, 0xbfb8aa3b, v155
	v_exp_f32_e32 v11, v11
	global_store_dwordx4 v[2:3], v[6:9], off
	v_add_f32_e32 v11, 1.0, v11
	s_nop 0
	v_mul_f32_e32 v7, 0xbfb8aa3b, v148
	v_exp_f32_e32 v7, v7
	v_rcp_f32_e32 v13, v11
	v_mul_f32_e32 v11, 0xbfb8aa3b, v151
	v_mul_f32_e32 v9, 0xbfb8aa3b, v149
	v_exp_f32_e32 v11, v11
	v_exp_f32_e32 v9, v9
	v_add_f32_e32 v7, 1.0, v7
	v_mul_f32_e32 v6, 0xbfb8aa3b, v152
	v_rcp_f32_e32 v8, v7
	v_mul_f32_e32 v7, 0xbfb8aa3b, v153
	v_exp_f32_e32 v6, v6
	v_exp_f32_e32 v7, v7
	v_add_f32_e32 v11, 1.0, v11
	v_add_f32_e32 v9, 1.0, v9
	v_rcp_f32_e32 v15, v11
	v_mul_f32_e32 v11, 0xbfb8aa3b, v146
	v_rcp_f32_e32 v9, v9
	v_exp_f32_e32 v11, v11
	v_add_f32_e32 v6, 1.0, v6
	v_add_f32_e32 v7, 1.0, v7
	v_rcp_f32_e32 v6, v6
	v_rcp_f32_e32 v7, v7
	v_pk_mul_f32 v[8:9], v[148:149], v[8:9]
	v_pk_mul_f32 v[14:15], v[150:151], v[14:15]
	v_add_f32_e32 v11, 1.0, v11
	v_cvt_pk_bf16_f32 v8, v8, v9
	v_cvt_pk_bf16_f32 v9, v14, v15
	v_rcp_f32_e32 v14, v11
	v_mul_f32_e32 v11, 0xbfb8aa3b, v142
	v_exp_f32_e32 v11, v11
	v_pk_mul_f32 v[6:7], v[152:153], v[6:7]
	v_pk_mul_f32 v[12:13], v[154:155], v[12:13]
	v_cvt_pk_bf16_f32 v6, v6, v7
	v_cvt_pk_bf16_f32 v7, v12, v13
	global_store_dwordx4 v[2:3], v[6:9], off offset:256
	v_add_f32_e32 v11, 1.0, v11
	v_rcp_f32_e32 v16, v11
	v_or_b32_e32 v6, 16, v10
	v_ashrrev_i32_e32 v7, 31, v6
	v_lshlrev_b64 v[6:7], 12, v[6:7]
	v_mul_f32_e32 v11, 0xbfb8aa3b, v147
	v_lshl_add_u64 v[12:13], s[42:43], 0, v[6:7]
	v_mul_f32_e32 v7, 0xbfb8aa3b, v140
	v_exp_f32_e32 v11, v11
	v_exp_f32_e32 v7, v7
	v_mul_f32_e32 v6, 0xbfb8aa3b, v144
	v_exp_f32_e32 v6, v6
	v_add_f32_e32 v11, 1.0, v11
	v_add_f32_e32 v7, 1.0, v7
	v_rcp_f32_e32 v15, v11
	v_mul_f32_e32 v11, 0xbfb8aa3b, v143
	v_rcp_f32_e32 v8, v7
	v_mul_f32_e32 v7, 0xbfb8aa3b, v145
	v_exp_f32_e32 v11, v11
	v_exp_f32_e32 v7, v7
	v_add_f32_e32 v6, 1.0, v6
	v_rcp_f32_e32 v6, v6
	v_add_f32_e32 v11, 1.0, v11
	v_add_f32_e32 v7, 1.0, v7
	v_rcp_f32_e32 v17, v11
	v_mul_f32_e32 v11, 0xbfb8aa3b, v138
	v_rcp_f32_e32 v7, v7
	v_mul_f32_e32 v9, 0xbfb8aa3b, v141
	v_exp_f32_e32 v11, v11
	v_exp_f32_e32 v9, v9
	v_pk_mul_f32 v[6:7], v[144:145], v[6:7]
	v_pk_mul_f32 v[14:15], v[146:147], v[14:15]
	v_add_f32_e32 v11, 1.0, v11
	v_add_f32_e32 v9, 1.0, v9
	v_cvt_pk_bf16_f32 v6, v6, v7
	v_cvt_pk_bf16_f32 v7, v14, v15
	v_rcp_f32_e32 v14, v11
	v_mul_f32_e32 v11, 0xbfb8aa3b, v134
	v_rcp_f32_e32 v9, v9
	v_exp_f32_e32 v11, v11
	v_pk_mul_f32 v[16:17], v[142:143], v[16:17]
	v_lshl_add_u64 v[12:13], v[12:13], 0, v[4:5]
	v_pk_mul_f32 v[8:9], v[140:141], v[8:9]
	v_add_f32_e32 v11, 1.0, v11
	v_cvt_pk_bf16_f32 v8, v8, v9
	v_cvt_pk_bf16_f32 v9, v16, v17
	v_rcp_f32_e32 v16, v11
	v_mul_f32_e32 v11, 0xbfb8aa3b, v139
	global_store_dwordx4 v[12:13], v[6:9], off
	v_exp_f32_e32 v11, v11
	s_nop 0
	v_mul_f32_e32 v7, 0xbfb8aa3b, v132
	v_exp_f32_e32 v7, v7
	v_add_f32_e32 v11, 1.0, v11
	v_rcp_f32_e32 v15, v11
	v_mul_f32_e32 v11, 0xbfb8aa3b, v135
	v_add_f32_e32 v7, 1.0, v7
	v_mul_f32_e32 v6, 0xbfb8aa3b, v136
	v_rcp_f32_e32 v8, v7
	v_mul_f32_e32 v7, 0xbfb8aa3b, v137
	v_exp_f32_e32 v11, v11
	v_exp_f32_e32 v6, v6
	v_exp_f32_e32 v7, v7
	v_mul_f32_e32 v9, 0xbfb8aa3b, v133
	v_exp_f32_e32 v9, v9
	v_add_f32_e32 v11, 1.0, v11
	v_add_f32_e32 v6, 1.0, v6
	v_add_f32_e32 v7, 1.0, v7
	v_rcp_f32_e32 v17, v11
	v_mul_f32_e32 v11, 0xbfb8aa3b, v130
	v_rcp_f32_e32 v6, v6
	v_rcp_f32_e32 v7, v7
	v_exp_f32_e32 v11, v11
	v_add_f32_e32 v9, 1.0, v9
	v_rcp_f32_e32 v9, v9
	v_pk_mul_f32 v[6:7], v[136:137], v[6:7]
	v_pk_mul_f32 v[14:15], v[138:139], v[14:15]
	v_add_f32_e32 v11, 1.0, v11
	v_cvt_pk_bf16_f32 v6, v6, v7
	v_cvt_pk_bf16_f32 v7, v14, v15
	v_rcp_f32_e32 v14, v11
	v_mul_f32_e32 v11, 0xbfb8aa3b, v126
	v_exp_f32_e32 v11, v11
	v_pk_mul_f32 v[8:9], v[132:133], v[8:9]
	v_pk_mul_f32 v[16:17], v[134:135], v[16:17]
	v_cvt_pk_bf16_f32 v8, v8, v9
	v_cvt_pk_bf16_f32 v9, v16, v17
	global_store_dwordx4 v[12:13], v[6:9], off offset:256
	v_add_f32_e32 v11, 1.0, v11
	v_rcp_f32_e32 v16, v11
	v_or_b32_e32 v6, 32, v10
	v_ashrrev_i32_e32 v7, 31, v6
	v_lshlrev_b64 v[6:7], 12, v[6:7]
	v_mul_f32_e32 v11, 0xbfb8aa3b, v131
	v_lshl_add_u64 v[12:13], s[42:43], 0, v[6:7]
	v_mul_f32_e32 v7, 0xbfb8aa3b, v124
	v_exp_f32_e32 v11, v11
	v_exp_f32_e32 v7, v7
	v_mul_f32_e32 v6, 0xbfb8aa3b, v128
	v_exp_f32_e32 v6, v6
	v_add_f32_e32 v11, 1.0, v11
	v_add_f32_e32 v7, 1.0, v7
	v_rcp_f32_e32 v15, v11
	v_mul_f32_e32 v11, 0xbfb8aa3b, v127
	v_rcp_f32_e32 v8, v7
	v_mul_f32_e32 v7, 0xbfb8aa3b, v129
	v_exp_f32_e32 v11, v11
	v_exp_f32_e32 v7, v7
	v_add_f32_e32 v6, 1.0, v6
	v_mul_f32_e32 v9, 0xbfb8aa3b, v125
	v_add_f32_e32 v11, 1.0, v11
	v_add_f32_e32 v7, 1.0, v7
	v_rcp_f32_e32 v17, v11
	v_mul_f32_e32 v11, 0xbfb8aa3b, v122
	v_rcp_f32_e32 v6, v6
	v_rcp_f32_e32 v7, v7
	v_exp_f32_e32 v9, v9
	v_exp_f32_e32 v11, v11
	v_pk_mul_f32 v[14:15], v[130:131], v[14:15]
	v_pk_mul_f32 v[6:7], v[128:129], v[6:7]
	v_add_f32_e32 v9, 1.0, v9
	v_add_f32_e32 v11, 1.0, v11
	v_rcp_f32_e32 v9, v9
	v_cvt_pk_bf16_f32 v6, v6, v7
	v_cvt_pk_bf16_f32 v7, v14, v15
	v_rcp_f32_e32 v14, v11
	v_mul_f32_e32 v11, 0xbfb8aa3b, v118
	v_exp_f32_e32 v11, v11
	v_pk_mul_f32 v[8:9], v[124:125], v[8:9]
	v_pk_mul_f32 v[16:17], v[126:127], v[16:17]
	v_cvt_pk_bf16_f32 v8, v8, v9
	v_cvt_pk_bf16_f32 v9, v16, v17
	v_lshl_add_u64 v[12:13], v[12:13], 0, v[4:5]
	v_add_f32_e32 v11, 1.0, v11
	global_store_dwordx4 v[12:13], v[6:9], off
	v_rcp_f32_e32 v16, v11
	v_mul_f32_e32 v11, 0xbfb8aa3b, v123
	v_mul_f32_e32 v7, 0xbfb8aa3b, v116
	v_exp_f32_e32 v7, v7
	v_exp_f32_e32 v11, v11
	v_mul_f32_e32 v6, 0xbfb8aa3b, v120
	v_mul_f32_e32 v9, 0xbfb8aa3b, v117
	v_add_f32_e32 v7, 1.0, v7
	v_add_f32_e32 v11, 1.0, v11
	v_rcp_f32_e32 v8, v7
	v_mul_f32_e32 v7, 0xbfb8aa3b, v121
	v_rcp_f32_e32 v15, v11
	v_mul_f32_e32 v11, 0xbfb8aa3b, v119
	v_exp_f32_e32 v6, v6
	v_exp_f32_e32 v7, v7
	v_exp_f32_e32 v9, v9
	v_exp_f32_e32 v11, v11
	v_add_f32_e32 v6, 1.0, v6
	v_add_f32_e32 v7, 1.0, v7
	v_add_f32_e32 v9, 1.0, v9
	v_add_f32_e32 v11, 1.0, v11
	v_rcp_f32_e32 v6, v6
	v_rcp_f32_e32 v7, v7
	v_rcp_f32_e32 v9, v9
	v_rcp_f32_e32 v17, v11
	v_pk_mul_f32 v[14:15], v[122:123], v[14:15]
	v_pk_mul_f32 v[6:7], v[120:121], v[6:7]
	v_pk_mul_f32 v[8:9], v[116:117], v[8:9]
	v_pk_mul_f32 v[16:17], v[118:119], v[16:17]
	v_cvt_pk_bf16_f32 v6, v6, v7
	v_cvt_pk_bf16_f32 v7, v14, v15
	v_cvt_pk_bf16_f32 v8, v8, v9
	v_cvt_pk_bf16_f32 v9, v16, v17
	global_store_dwordx4 v[12:13], v[6:9], off offset:256
	v_mul_f32_e32 v13, 0xbfb8aa3b, v110
	v_exp_f32_e32 v13, v13
	v_or_b32_e32 v6, 48, v10
	v_ashrrev_i32_e32 v7, 31, v6
	v_lshlrev_b64 v[6:7], 12, v[6:7]
	v_lshl_add_u64 v[10:11], s[42:43], 0, v[6:7]
	v_mul_f32_e32 v7, 0xbfb8aa3b, v108
	v_exp_f32_e32 v7, v7
	v_add_f32_e32 v13, 1.0, v13
	v_mul_f32_e32 v6, 0xbfb8aa3b, v112
	v_mul_f32_e32 v9, 0xbfb8aa3b, v109
	v_add_f32_e32 v7, 1.0, v7
	v_rcp_f32_e32 v8, v7
	v_mul_f32_e32 v7, 0xbfb8aa3b, v113
	v_mul_f32_e32 v12, 0xbfb8aa3b, v114
	v_rcp_f32_e32 v14, v13
	v_mul_f32_e32 v13, 0xbfb8aa3b, v115
	v_mul_f32_e32 v15, 0xbfb8aa3b, v111
	v_exp_f32_e32 v6, v6
	v_exp_f32_e32 v7, v7
	v_exp_f32_e32 v9, v9
	v_exp_f32_e32 v12, v12
	v_exp_f32_e32 v13, v13
	v_exp_f32_e32 v15, v15
	v_add_f32_e32 v6, 1.0, v6
	v_add_f32_e32 v7, 1.0, v7
	v_add_f32_e32 v9, 1.0, v9
	v_add_f32_e32 v12, 1.0, v12
	v_add_f32_e32 v13, 1.0, v13
	v_add_f32_e32 v15, 1.0, v15
	v_rcp_f32_e32 v6, v6
	v_rcp_f32_e32 v7, v7
	v_rcp_f32_e32 v9, v9
	v_rcp_f32_e32 v12, v12
	v_rcp_f32_e32 v13, v13
	v_rcp_f32_e32 v15, v15
	v_pk_mul_f32 v[6:7], v[112:113], v[6:7]
	v_pk_mul_f32 v[8:9], v[108:109], v[8:9]
	v_pk_mul_f32 v[12:13], v[114:115], v[12:13]
	v_pk_mul_f32 v[14:15], v[110:111], v[14:15]
	v_cvt_pk_bf16_f32 v6, v6, v7
	v_cvt_pk_bf16_f32 v7, v12, v13
	v_cvt_pk_bf16_f32 v8, v8, v9
	v_cvt_pk_bf16_f32 v9, v14, v15
	v_lshl_add_u64 v[10:11], v[10:11], 0, v[4:5]
	global_store_dwordx4 v[10:11], v[6:9], off
	v_mul_f32_e32 v5, 0xbfb8aa3b, v100
	v_exp_f32_e32 v5, v5
	v_mul_f32_e32 v9, 0xbfb8aa3b, v102
	v_exp_f32_e32 v9, v9
	v_mul_f32_e32 v4, 0xbfb8aa3b, v104
	v_add_f32_e32 v5, 1.0, v5
	v_rcp_f32_e32 v6, v5
	v_add_f32_e32 v9, 1.0, v9
	v_mul_f32_e32 v5, 0xbfb8aa3b, v105
	v_mul_f32_e32 v7, 0xbfb8aa3b, v101
	v_mul_f32_e32 v8, 0xbfb8aa3b, v106
	v_rcp_f32_e32 v12, v9
	v_mul_f32_e32 v9, 0xbfb8aa3b, v107
	v_mul_f32_e32 v13, 0xbfb8aa3b, v103
	v_exp_f32_e32 v4, v4
	v_exp_f32_e32 v5, v5
	v_exp_f32_e32 v7, v7
	v_exp_f32_e32 v8, v8
	v_exp_f32_e32 v9, v9
	v_exp_f32_e32 v13, v13
	v_add_f32_e32 v4, 1.0, v4
	v_add_f32_e32 v5, 1.0, v5
	v_add_f32_e32 v7, 1.0, v7
	v_add_f32_e32 v8, 1.0, v8
	v_add_f32_e32 v9, 1.0, v9
	v_add_f32_e32 v13, 1.0, v13
	v_rcp_f32_e32 v4, v4
	v_rcp_f32_e32 v5, v5
	v_rcp_f32_e32 v7, v7
	v_rcp_f32_e32 v8, v8
	v_rcp_f32_e32 v9, v9
	v_rcp_f32_e32 v13, v13
	v_pk_mul_f32 v[4:5], v[104:105], v[4:5]
	v_pk_mul_f32 v[6:7], v[100:101], v[6:7]
	v_pk_mul_f32 v[8:9], v[106:107], v[8:9]
	v_pk_mul_f32 v[12:13], v[102:103], v[12:13]
	v_cvt_pk_bf16_f32 v4, v4, v5
	v_cvt_pk_bf16_f32 v5, v8, v9
	v_cvt_pk_bf16_f32 v6, v6, v7
	v_cvt_pk_bf16_f32 v7, v12, v13
	global_store_dwordx4 v[10:11], v[4:7], off offset:256
	v_mul_f32_e32 v9, 0xbfb8aa3b, v94
	v_exp_f32_e32 v9, v9
	v_mul_f32_e32 v5, 0xbfb8aa3b, v92
	v_exp_f32_e32 v5, v5
	v_mul_f32_e32 v4, 0xbfb8aa3b, v96
	v_add_f32_e32 v9, 1.0, v9
	v_mul_f32_e32 v8, 0xbfb8aa3b, v98
	v_add_f32_e32 v5, 1.0, v5
	v_rcp_f32_e32 v6, v5
	v_mul_f32_e32 v5, 0xbfb8aa3b, v97
	v_rcp_f32_e32 v10, v9
	v_mul_f32_e32 v9, 0xbfb8aa3b, v99
	v_exp_f32_e32 v4, v4
	v_exp_f32_e32 v5, v5
	v_mul_f32_e32 v7, 0xbfb8aa3b, v93
	v_exp_f32_e32 v8, v8
	v_exp_f32_e32 v9, v9
	v_mul_f32_e32 v11, 0xbfb8aa3b, v95
	v_exp_f32_e32 v7, v7
	v_exp_f32_e32 v11, v11
	v_add_f32_e32 v4, 1.0, v4
	v_add_f32_e32 v5, 1.0, v5
	v_add_f32_e32 v8, 1.0, v8
	v_add_f32_e32 v9, 1.0, v9
	v_rcp_f32_e32 v4, v4
	v_rcp_f32_e32 v5, v5
	v_add_f32_e32 v7, 1.0, v7
	v_rcp_f32_e32 v8, v8
	v_rcp_f32_e32 v9, v9
	v_add_f32_e32 v11, 1.0, v11
	v_rcp_f32_e32 v7, v7
	v_rcp_f32_e32 v11, v11
	v_pk_mul_f32 v[4:5], v[96:97], v[4:5]
	v_pk_mul_f32 v[8:9], v[98:99], v[8:9]
	v_pk_mul_f32 v[6:7], v[92:93], v[6:7]
	v_pk_mul_f32 v[10:11], v[94:95], v[10:11]
	v_cvt_pk_bf16_f32 v4, v4, v5
	v_cvt_pk_bf16_f32 v5, v8, v9
	v_lshl_add_u64 v[8:9], v[2:3], 0, s[6:7]
	s_mov_b32 s6, 0x80000
	v_cvt_pk_bf16_f32 v6, v6, v7
	v_cvt_pk_bf16_f32 v7, v10, v11
	v_add_co_u32_e32 v10, vcc, s6, v2
	v_mul_f32_e32 v13, 0xbfb8aa3b, v87
	s_nop 0
	v_addc_co_u32_e32 v11, vcc, 0, v3, vcc
	global_store_dwordx4 v[10:11], v[4:7], off
	v_mul_f32_e32 v11, 0xbfb8aa3b, v86
	v_exp_f32_e32 v11, v11
	v_mul_f32_e32 v5, 0xbfb8aa3b, v84
	v_exp_f32_e32 v5, v5
	v_mul_f32_e32 v4, 0xbfb8aa3b, v88
	v_add_f32_e32 v11, 1.0, v11
	v_mul_f32_e32 v7, 0xbfb8aa3b, v85
	v_add_f32_e32 v5, 1.0, v5
	v_rcp_f32_e32 v6, v5
	v_mul_f32_e32 v5, 0xbfb8aa3b, v89
	v_mul_f32_e32 v10, 0xbfb8aa3b, v90
	v_rcp_f32_e32 v12, v11
	v_mul_f32_e32 v11, 0xbfb8aa3b, v91
	v_exp_f32_e32 v4, v4
	v_exp_f32_e32 v5, v5
	v_exp_f32_e32 v7, v7
	v_exp_f32_e32 v10, v10
	v_exp_f32_e32 v11, v11
	v_exp_f32_e32 v13, v13
	v_add_f32_e32 v4, 1.0, v4
	v_add_f32_e32 v5, 1.0, v5
	v_add_f32_e32 v7, 1.0, v7
	v_add_f32_e32 v10, 1.0, v10
	v_add_f32_e32 v11, 1.0, v11
	v_add_f32_e32 v13, 1.0, v13
	v_rcp_f32_e32 v4, v4
	v_rcp_f32_e32 v5, v5
	v_rcp_f32_e32 v7, v7
	v_rcp_f32_e32 v10, v10
	v_rcp_f32_e32 v11, v11
	v_rcp_f32_e32 v13, v13
	v_pk_mul_f32 v[4:5], v[88:89], v[4:5]
	v_pk_mul_f32 v[6:7], v[84:85], v[6:7]
	v_pk_mul_f32 v[10:11], v[90:91], v[10:11]
	v_pk_mul_f32 v[12:13], v[86:87], v[12:13]
	v_cvt_pk_bf16_f32 v4, v4, v5
	v_cvt_pk_bf16_f32 v5, v10, v11
	v_cvt_pk_bf16_f32 v6, v6, v7
	v_cvt_pk_bf16_f32 v7, v12, v13
	global_store_dwordx4 v[8:9], v[4:7], off offset:256
	v_mul_f32_e32 v9, 0xbfb8aa3b, v78
	v_exp_f32_e32 v9, v9
	v_mul_f32_e32 v5, 0xbfb8aa3b, v76
	v_exp_f32_e32 v5, v5
	v_mul_f32_e32 v4, 0xbfb8aa3b, v80
	v_add_f32_e32 v9, 1.0, v9
	v_mul_f32_e32 v8, 0xbfb8aa3b, v82
	v_add_f32_e32 v5, 1.0, v5
	v_rcp_f32_e32 v6, v5
	v_mul_f32_e32 v5, 0xbfb8aa3b, v81
	v_rcp_f32_e32 v10, v9
	v_mul_f32_e32 v9, 0xbfb8aa3b, v83
	v_exp_f32_e32 v4, v4
	v_exp_f32_e32 v5, v5
	v_mul_f32_e32 v7, 0xbfb8aa3b, v77
	v_exp_f32_e32 v8, v8
	v_exp_f32_e32 v9, v9
	v_mul_f32_e32 v11, 0xbfb8aa3b, v79
	v_exp_f32_e32 v7, v7
	v_exp_f32_e32 v11, v11
	v_add_f32_e32 v4, 1.0, v4
	v_add_f32_e32 v5, 1.0, v5
	v_add_f32_e32 v8, 1.0, v8
	v_add_f32_e32 v9, 1.0, v9
	v_rcp_f32_e32 v4, v4
	v_rcp_f32_e32 v5, v5
	v_add_f32_e32 v7, 1.0, v7
	v_rcp_f32_e32 v8, v8
	v_rcp_f32_e32 v9, v9
	v_add_f32_e32 v11, 1.0, v11
	v_rcp_f32_e32 v7, v7
	v_rcp_f32_e32 v11, v11
	v_pk_mul_f32 v[4:5], v[80:81], v[4:5]
	v_pk_mul_f32 v[8:9], v[82:83], v[8:9]
	s_mov_b64 s[6:7], 0x90000
	v_pk_mul_f32 v[6:7], v[76:77], v[6:7]
	v_pk_mul_f32 v[10:11], v[78:79], v[10:11]
	v_cvt_pk_bf16_f32 v4, v4, v5
	v_cvt_pk_bf16_f32 v5, v8, v9
	v_lshl_add_u64 v[8:9], v[2:3], 0, s[6:7]
	s_mov_b32 s6, 0x90000
	v_cvt_pk_bf16_f32 v6, v6, v7
	v_cvt_pk_bf16_f32 v7, v10, v11
	v_add_co_u32_e32 v10, vcc, s6, v2
	v_mul_f32_e32 v13, 0xbfb8aa3b, v71
	s_nop 0
	v_addc_co_u32_e32 v11, vcc, 0, v3, vcc
	global_store_dwordx4 v[10:11], v[4:7], off
	v_mul_f32_e32 v11, 0xbfb8aa3b, v70
	v_exp_f32_e32 v11, v11
	v_mul_f32_e32 v5, 0xbfb8aa3b, v68
	v_exp_f32_e32 v5, v5
	v_mul_f32_e32 v4, 0xbfb8aa3b, v72
	v_add_f32_e32 v11, 1.0, v11
	v_mul_f32_e32 v7, 0xbfb8aa3b, v69
	v_add_f32_e32 v5, 1.0, v5
	v_rcp_f32_e32 v6, v5
	v_mul_f32_e32 v5, 0xbfb8aa3b, v73
	v_mul_f32_e32 v10, 0xbfb8aa3b, v74
	v_rcp_f32_e32 v12, v11
	v_mul_f32_e32 v11, 0xbfb8aa3b, v75
	v_exp_f32_e32 v4, v4
	v_exp_f32_e32 v5, v5
	v_exp_f32_e32 v7, v7
	v_exp_f32_e32 v10, v10
	v_exp_f32_e32 v11, v11
	v_exp_f32_e32 v13, v13
	v_add_f32_e32 v4, 1.0, v4
	v_add_f32_e32 v5, 1.0, v5
	v_add_f32_e32 v7, 1.0, v7
	v_add_f32_e32 v10, 1.0, v10
	v_add_f32_e32 v11, 1.0, v11
	v_add_f32_e32 v13, 1.0, v13
	v_rcp_f32_e32 v4, v4
	v_rcp_f32_e32 v5, v5
	v_rcp_f32_e32 v7, v7
	v_rcp_f32_e32 v10, v10
	v_rcp_f32_e32 v11, v11
	v_rcp_f32_e32 v13, v13
	v_pk_mul_f32 v[4:5], v[72:73], v[4:5]
	v_pk_mul_f32 v[6:7], v[68:69], v[6:7]
	v_pk_mul_f32 v[10:11], v[74:75], v[10:11]
	v_pk_mul_f32 v[12:13], v[70:71], v[12:13]
	v_cvt_pk_bf16_f32 v4, v4, v5
	v_cvt_pk_bf16_f32 v5, v10, v11
	v_cvt_pk_bf16_f32 v6, v6, v7
	v_cvt_pk_bf16_f32 v7, v12, v13
	global_store_dwordx4 v[8:9], v[4:7], off offset:256
	v_mul_f32_e32 v9, 0xbfb8aa3b, v62
	v_exp_f32_e32 v9, v9
	v_mul_f32_e32 v5, 0xbfb8aa3b, v60
	v_exp_f32_e32 v5, v5
	v_mul_f32_e32 v4, 0xbfb8aa3b, v64
	v_add_f32_e32 v9, 1.0, v9
	v_mul_f32_e32 v8, 0xbfb8aa3b, v66
	v_add_f32_e32 v5, 1.0, v5
	v_rcp_f32_e32 v6, v5
	v_mul_f32_e32 v5, 0xbfb8aa3b, v65
	v_rcp_f32_e32 v10, v9
	v_mul_f32_e32 v9, 0xbfb8aa3b, v67
	v_exp_f32_e32 v4, v4
	v_exp_f32_e32 v5, v5
	v_mul_f32_e32 v7, 0xbfb8aa3b, v61
	v_exp_f32_e32 v8, v8
	v_exp_f32_e32 v9, v9
	v_mul_f32_e32 v11, 0xbfb8aa3b, v63
	v_exp_f32_e32 v7, v7
	v_exp_f32_e32 v11, v11
	v_add_f32_e32 v4, 1.0, v4
	v_add_f32_e32 v5, 1.0, v5
	v_add_f32_e32 v8, 1.0, v8
	v_add_f32_e32 v9, 1.0, v9
	v_rcp_f32_e32 v4, v4
	v_rcp_f32_e32 v5, v5
	v_add_f32_e32 v7, 1.0, v7
	v_rcp_f32_e32 v8, v8
	v_rcp_f32_e32 v9, v9
	v_add_f32_e32 v11, 1.0, v11
	v_rcp_f32_e32 v7, v7
	v_rcp_f32_e32 v11, v11
	v_pk_mul_f32 v[4:5], v[64:65], v[4:5]
	v_pk_mul_f32 v[8:9], v[66:67], v[8:9]
	s_mov_b64 s[6:7], 0xa0000
	v_pk_mul_f32 v[6:7], v[60:61], v[6:7]
	v_pk_mul_f32 v[10:11], v[62:63], v[10:11]
	v_cvt_pk_bf16_f32 v4, v4, v5
	v_cvt_pk_bf16_f32 v5, v8, v9
	v_lshl_add_u64 v[8:9], v[2:3], 0, s[6:7]
	s_mov_b32 s6, 0xa0000
	v_cvt_pk_bf16_f32 v6, v6, v7
	v_cvt_pk_bf16_f32 v7, v10, v11
	v_add_co_u32_e32 v10, vcc, s6, v2
	v_mul_f32_e32 v13, 0xbfb8aa3b, v55
	s_nop 0
	v_addc_co_u32_e32 v11, vcc, 0, v3, vcc
	global_store_dwordx4 v[10:11], v[4:7], off
	v_mul_f32_e32 v11, 0xbfb8aa3b, v54
	v_exp_f32_e32 v11, v11
	v_mul_f32_e32 v5, 0xbfb8aa3b, v52
	v_exp_f32_e32 v5, v5
	v_mul_f32_e32 v4, 0xbfb8aa3b, v56
	v_add_f32_e32 v11, 1.0, v11
	v_mul_f32_e32 v7, 0xbfb8aa3b, v53
	v_add_f32_e32 v5, 1.0, v5
	v_rcp_f32_e32 v6, v5
	v_mul_f32_e32 v5, 0xbfb8aa3b, v57
	v_mul_f32_e32 v10, 0xbfb8aa3b, v58
	v_rcp_f32_e32 v12, v11
	v_mul_f32_e32 v11, 0xbfb8aa3b, v59
	v_exp_f32_e32 v4, v4
	v_exp_f32_e32 v5, v5
	v_exp_f32_e32 v7, v7
	v_exp_f32_e32 v10, v10
	v_exp_f32_e32 v11, v11
	v_exp_f32_e32 v13, v13
	v_add_f32_e32 v4, 1.0, v4
	v_add_f32_e32 v5, 1.0, v5
	v_add_f32_e32 v7, 1.0, v7
	v_add_f32_e32 v10, 1.0, v10
	v_add_f32_e32 v11, 1.0, v11
	v_add_f32_e32 v13, 1.0, v13
	v_rcp_f32_e32 v4, v4
	v_rcp_f32_e32 v5, v5
	v_rcp_f32_e32 v7, v7
	v_rcp_f32_e32 v10, v10
	v_rcp_f32_e32 v11, v11
	v_rcp_f32_e32 v13, v13
	v_pk_mul_f32 v[4:5], v[56:57], v[4:5]
	v_pk_mul_f32 v[6:7], v[52:53], v[6:7]
	v_pk_mul_f32 v[10:11], v[58:59], v[10:11]
	v_pk_mul_f32 v[12:13], v[54:55], v[12:13]
	v_cvt_pk_bf16_f32 v4, v4, v5
	v_cvt_pk_bf16_f32 v5, v10, v11
	v_cvt_pk_bf16_f32 v6, v6, v7
	v_cvt_pk_bf16_f32 v7, v12, v13
	global_store_dwordx4 v[8:9], v[4:7], off offset:256
	v_mul_f32_e32 v9, 0xbfb8aa3b, v46
	v_exp_f32_e32 v9, v9
	v_mul_f32_e32 v5, 0xbfb8aa3b, v44
	v_exp_f32_e32 v5, v5
	v_mul_f32_e32 v4, 0xbfb8aa3b, v48
	v_add_f32_e32 v9, 1.0, v9
	v_mul_f32_e32 v8, 0xbfb8aa3b, v50
	v_add_f32_e32 v5, 1.0, v5
	v_rcp_f32_e32 v6, v5
	v_mul_f32_e32 v5, 0xbfb8aa3b, v49
	v_rcp_f32_e32 v10, v9
	v_mul_f32_e32 v9, 0xbfb8aa3b, v51
	v_exp_f32_e32 v4, v4
	v_exp_f32_e32 v5, v5
	v_exp_f32_e32 v8, v8
	v_exp_f32_e32 v9, v9
	v_mul_f32_e32 v7, 0xbfb8aa3b, v45
	v_mul_f32_e32 v11, 0xbfb8aa3b, v47
	v_exp_f32_e32 v7, v7
	v_exp_f32_e32 v11, v11
	v_add_f32_e32 v4, 1.0, v4
	v_add_f32_e32 v5, 1.0, v5
	v_add_f32_e32 v8, 1.0, v8
	v_add_f32_e32 v9, 1.0, v9
	v_rcp_f32_e32 v4, v4
	v_rcp_f32_e32 v5, v5
	v_rcp_f32_e32 v8, v8
	v_rcp_f32_e32 v9, v9
	v_add_f32_e32 v7, 1.0, v7
	v_add_f32_e32 v11, 1.0, v11
	v_rcp_f32_e32 v7, v7
	v_rcp_f32_e32 v11, v11
	v_pk_mul_f32 v[4:5], v[48:49], v[4:5]
	v_pk_mul_f32 v[8:9], v[50:51], v[8:9]
	s_mov_b64 s[6:7], 0xb0000
	v_cvt_pk_bf16_f32 v4, v4, v5
	v_cvt_pk_bf16_f32 v5, v8, v9
	v_lshl_add_u64 v[8:9], v[2:3], 0, s[6:7]
	s_mov_b32 s6, 0xb0000
	v_pk_mul_f32 v[6:7], v[44:45], v[6:7]
	v_pk_mul_f32 v[10:11], v[46:47], v[10:11]
	v_add_co_u32_e32 v2, vcc, s6, v2
	v_cvt_pk_bf16_f32 v6, v6, v7
	v_cvt_pk_bf16_f32 v7, v10, v11
	v_addc_co_u32_e32 v3, vcc, 0, v3, vcc
	global_store_dwordx4 v[2:3], v[4:7], off
	v_mul_f32_e32 v3, 0xbfb8aa3b, v36
	v_exp_f32_e32 v3, v3
	v_mul_f32_e32 v7, 0xbfb8aa3b, v38
	v_exp_f32_e32 v7, v7
	v_mul_f32_e32 v2, 0xbfb8aa3b, v40
	v_add_f32_e32 v3, 1.0, v3
	v_rcp_f32_e32 v4, v3
	v_add_f32_e32 v7, 1.0, v7
	v_mul_f32_e32 v3, 0xbfb8aa3b, v41
	v_mul_f32_e32 v5, 0xbfb8aa3b, v37
	v_mul_f32_e32 v6, 0xbfb8aa3b, v42
	v_rcp_f32_e32 v10, v7
	v_mul_f32_e32 v7, 0xbfb8aa3b, v43
	v_mul_f32_e32 v11, 0xbfb8aa3b, v39
	v_exp_f32_e32 v2, v2
	v_exp_f32_e32 v3, v3
	v_exp_f32_e32 v5, v5
	v_exp_f32_e32 v6, v6
	v_exp_f32_e32 v7, v7
	v_exp_f32_e32 v11, v11
	v_add_f32_e32 v2, 1.0, v2
	v_add_f32_e32 v3, 1.0, v3
	v_add_f32_e32 v5, 1.0, v5
	v_add_f32_e32 v6, 1.0, v6
	v_add_f32_e32 v7, 1.0, v7
	v_add_f32_e32 v11, 1.0, v11
	v_rcp_f32_e32 v2, v2
	v_rcp_f32_e32 v3, v3
	v_rcp_f32_e32 v5, v5
	v_rcp_f32_e32 v6, v6
	v_rcp_f32_e32 v7, v7
	v_rcp_f32_e32 v11, v11
	v_pk_mul_f32 v[2:3], v[40:41], v[2:3]
	v_pk_mul_f32 v[4:5], v[36:37], v[4:5]
	v_pk_mul_f32 v[6:7], v[42:43], v[6:7]
	v_pk_mul_f32 v[10:11], v[38:39], v[10:11]
	v_cvt_pk_bf16_f32 v2, v2, v3
	v_cvt_pk_bf16_f32 v3, v6, v7
	v_cvt_pk_bf16_f32 v4, v4, v5
	v_cvt_pk_bf16_f32 v5, v10, v11
	global_store_dwordx4 v[8:9], v[2:5], off offset:256
	s_andn2_b64 vcc, exec, s[38:39]
	s_mov_b64 s[6:7], -1
	s_cbranch_vccnz .LBB0_196

.LBB0_1735:
	v_lshl_add_u32 v148, s41, 8, v35
	v_lshl_or_b32 v150, s40, 8, v145
	v_ashrrev_i32_e32 v149, 31, v148
	v_ashrrev_i32_e32 v151, 31, v150
	v_lshlrev_b64 v[152:153], 13, v[148:149]
	v_lshl_add_u64 v[152:153], s[6:7], 0, v[152:153]
	v_lshlrev_b64 v[150:151], 1, v[150:151]
	v_lshl_add_u64 v[152:153], v[152:153], 0, v[150:151]
	s_mov_b32 s11, 0x100000
	s_mov_b64 s[18:19], 0x100000
	v_cvt_pk_bf16_f32 v60, v60, v61
	v_cvt_pk_bf16_f32 v61, v62, v63
	v_cvt_pk_bf16_f32 v62, v56, v57
	v_add_co_u32_e32 v56, vcc, s11, v152
	v_cvt_pk_bf16_f32 v72, v72, v73
	v_cvt_pk_bf16_f32 v73, v74, v75
	v_cvt_pk_bf16_f32 v74, v68, v69
	v_lshl_add_u64 v[68:69], v[152:153], 0, s[18:19]
	v_addc_co_u32_e32 v57, vcc, 0, v153, vcc
	v_cvt_pk_bf16_f32 v36, v36, v37
	v_cvt_pk_bf16_f32 v37, v38, v39
	v_cvt_pk_bf16_f32 v38, v30, v31
	v_cvt_pk_bf16_f32 v39, v32, v33
	s_mov_b32 s11, 0x120000
	v_cvt_pk_bf16_f32 v112, v112, v113
	v_cvt_pk_bf16_f32 v113, v114, v115
	v_cvt_pk_bf16_f32 v114, v108, v109
	v_or_b32_e32 v108, 16, v148
	global_store_dwordx4 v[68:69], v[36:39], off offset:256
	s_mov_b64 s[18:19], 0x120000
	v_ashrrev_i32_e32 v109, 31, v108
	v_add_co_u32_e32 v38, vcc, s11, v152
	v_cvt_pk_bf16_f32 v96, v96, v97
	v_cvt_pk_bf16_f32 v97, v98, v99
	v_cvt_pk_bf16_f32 v98, v92, v93
	v_or_b32_e32 v92, 32, v148
	v_lshl_add_u64 v[36:37], v[152:153], 0, s[18:19]
	v_addc_co_u32_e32 v39, vcc, 0, v153, vcc
	v_cvt_pk_bf16_f32 v18, v18, v19
	v_cvt_pk_bf16_f32 v19, v20, v21
	v_cvt_pk_bf16_f32 v20, v14, v15
	v_cvt_pk_bf16_f32 v21, v16, v17
	s_mov_b32 s11, 0x140000
	v_lshlrev_b64 v[108:109], 13, v[108:109]
	v_ashrrev_i32_e32 v93, 31, v92
	v_cvt_pk_bf16_f32 v80, v80, v81
	v_cvt_pk_bf16_f32 v81, v82, v83
	v_cvt_pk_bf16_f32 v82, v76, v77
	v_or_b32_e32 v76, 48, v148
	global_store_dwordx4 v[36:37], v[18:21], off offset:256
	s_mov_b64 s[18:19], 0x140000
	v_cvt_pk_bf16_f32 v115, v110, v111
	v_add_co_u32_e32 v20, vcc, s11, v152
	v_lshl_add_u64 v[108:109], s[6:7], 0, v[108:109]
	v_lshlrev_b64 v[92:93], 13, v[92:93]
	v_ashrrev_i32_e32 v77, 31, v76
	v_lshl_add_u64 v[18:19], v[152:153], 0, s[18:19]
	v_addc_co_u32_e32 v21, vcc, 0, v153, vcc
	v_cvt_pk_bf16_f32 v2, v2, v3
	v_cvt_pk_bf16_f32 v3, v4, v5
	v_cvt_pk_bf16_f32 v4, v64, v65
	v_cvt_pk_bf16_f32 v5, v66, v67
	s_mov_b32 s11, 0x160000
	global_store_dwordx4 v[152:153], v[112:115], off offset:256
	v_cvt_pk_bf16_f32 v99, v94, v95
	v_lshl_add_u64 v[92:93], s[6:7], 0, v[92:93]
	v_lshl_add_u64 v[112:113], v[108:109], 0, v[150:151]
	v_lshlrev_b64 v[76:77], 13, v[76:77]
	global_store_dwordx4 v[18:19], v[2:5], off offset:256
	global_store_dwordx4 v[112:113], v[96:99], off offset:256
	v_cvt_pk_bf16_f32 v83, v78, v79
	v_cvt_pk_bf16_f32 v4, v6, v7
	v_add_co_u32_e32 v6, vcc, s11, v152
	v_lshl_add_u64 v[96:97], v[92:93], 0, v[150:151]
	v_lshl_add_u64 v[76:77], s[6:7], 0, v[76:77]
	v_cvt_pk_bf16_f32 v14, v26, v27
	v_cvt_pk_bf16_f32 v15, v28, v29
	v_cvt_pk_bf16_f32 v16, v22, v23
	v_cvt_pk_bf16_f32 v17, v24, v25
	s_mov_b64 s[18:19], 0x160000
	v_cvt_pk_bf16_f32 v2, v10, v11
	v_cvt_pk_bf16_f32 v3, v12, v13
	v_cvt_pk_bf16_f32 v5, v8, v9
	v_addc_co_u32_e32 v7, vcc, 0, v153, vcc
	v_cvt_pk_bf16_f32 v128, v128, v129
	v_cvt_pk_bf16_f32 v129, v130, v131
	v_cvt_pk_bf16_f32 v130, v124, v125
	v_cvt_pk_bf16_f32 v131, v126, v127
	v_cvt_pk_bf16_f32 v108, v120, v121
	v_cvt_pk_bf16_f32 v109, v122, v123
	v_cvt_pk_bf16_f32 v110, v116, v117
	v_cvt_pk_bf16_f32 v111, v118, v119
	v_cvt_pk_bf16_f32 v92, v104, v105
	v_cvt_pk_bf16_f32 v93, v106, v107
	v_cvt_pk_bf16_f32 v94, v100, v101
	v_cvt_pk_bf16_f32 v95, v102, v103
	global_store_dwordx4 v[96:97], v[80:83], off offset:256
	v_cvt_pk_bf16_f32 v78, v84, v85
	v_cvt_pk_bf16_f32 v79, v86, v87
	v_lshl_add_u64 v[80:81], v[76:77], 0, v[150:151]
	v_cvt_pk_bf16_f32 v76, v88, v89
	v_cvt_pk_bf16_f32 v77, v90, v91
	v_cvt_pk_bf16_f32 v75, v70, v71
	v_cvt_pk_bf16_f32 v63, v58, v59
	v_cvt_pk_bf16_f32 v30, v44, v45
	v_cvt_pk_bf16_f32 v31, v46, v47
	v_cvt_pk_bf16_f32 v32, v40, v41
	v_cvt_pk_bf16_f32 v33, v42, v43
	global_store_dwordx4 v[20:21], v[14:17], off
	global_store_dwordx4 v[6:7], v[2:5], off
	s_andn2_b64 vcc, exec, s[36:37]
	v_lshl_add_u64 v[14:15], v[152:153], 0, s[18:19]
	v_cvt_pk_bf16_f32 v2, v48, v49
	v_cvt_pk_bf16_f32 v3, v50, v51
	v_cvt_pk_bf16_f32 v4, v52, v53
	v_cvt_pk_bf16_f32 v5, v54, v55
	s_mov_b64 s[18:19], -1
	global_store_dwordx4 v[152:153], v[128:131], off
	global_store_dwordx4 v[112:113], v[108:111], off
	global_store_dwordx4 v[96:97], v[92:95], off
	global_store_dwordx4 v[80:81], v[76:79], off
	global_store_dwordx4 v[80:81], v[72:75], off offset:256
	global_store_dwordx4 v[56:57], v[60:63], off
	global_store_dwordx4 v[38:39], v[30:33], off
	global_store_dwordx4 v[14:15], v[2:5], off offset:256
	s_cbranch_vccnz .LBB0_1728
	s_andn2_b64 vcc, exec, s[4:5]
	s_cbranch_vccnz .LBB0_1727
	s_barrier
	s_branch .LBB0_1727

.LBB0_1794:
	v_readlane_b32 s12, v251, 19
	s_cmpk_lt_i32 s4, 0x2000
	v_readlane_b32 s13, v251, 20
	s_cselect_b64 s[8:9], -1, 0
	s_xor_b64 s[12:13], s[12:13], -1
	s_or_b64 s[8:9], s[12:13], s[8:9]
	s_mov_b32 s28, s4
	s_mov_b64 s[0:1], -1
	s_and_b64 vcc, exec, s[8:9]
	s_mov_b32 s13, s29
	s_mov_b64 s[8:9], s[28:29]
	s_cbranch_vccz .LBB0_1796
	v_add_co_u32_e32 v2, vcc, 0xffffe200, v146
	s_movk_i32 s0, 0xe800
	s_nop 0
	v_addc_co_u32_e32 v3, vcc, -1, v147, vcc
	v_add_co_u32_e32 v4, vcc, 0xffffe400, v146
	s_mov_b64 s[8:9], s[4:5]
	s_nop 0
	v_addc_co_u32_e32 v5, vcc, -1, v147, vcc
	v_add_co_u32_e32 v6, vcc, 0xffffe600, v146
	s_nop 1
	v_addc_co_u32_e32 v7, vcc, -1, v147, vcc
	v_add_co_u32_e32 v8, vcc, s0, v146
	s_movk_i32 s0, 0xea00
	s_nop 0
	v_addc_co_u32_e32 v9, vcc, -1, v147, vcc
	global_load_dwordx2 v[2:3], v[2:3], off
	s_nop 0
	global_load_dwordx2 v[4:5], v[4:5], off
	s_nop 0
	global_load_dwordx2 v[18:19], v[6:7], off
	global_load_dwordx2 v[20:21], v[8:9], off
	v_add_co_u32_e32 v6, vcc, s0, v146
	s_movk_i32 s0, 0xec00
	s_nop 0
	v_addc_co_u32_e32 v7, vcc, -1, v147, vcc
	global_load_dwordx2 v[22:23], v[6:7], off
	v_add_co_u32_e32 v6, vcc, s0, v146
	s_movk_i32 s0, 0xee00
	s_nop 0
	v_addc_co_u32_e32 v7, vcc, -1, v147, vcc
	v_add_co_u32_e32 v8, vcc, s0, v146
	s_movk_i32 s0, 0xf000
	s_nop 0
	v_addc_co_u32_e32 v9, vcc, -1, v147, vcc
	v_add_co_u32_e32 v10, vcc, s0, v146
	s_movk_i32 s0, 0xf200
	s_nop 0
	v_addc_co_u32_e32 v11, vcc, -1, v147, vcc
	global_load_dwordx2 v[24:25], v[6:7], off
	global_load_dwordx2 v[26:27], v[8:9], off
	global_load_dwordx2 v[28:29], v[10:11], off
	v_add_co_u32_e32 v6, vcc, s0, v146
	s_movk_i32 s0, 0xf400
	s_nop 0
	v_addc_co_u32_e32 v7, vcc, -1, v147, vcc
	v_add_co_u32_e32 v8, vcc, s0, v146
	s_movk_i32 s0, 0xf600
	s_nop 0
	v_addc_co_u32_e32 v9, vcc, -1, v147, vcc
	global_load_dwordx2 v[38:39], v[6:7], off
	global_load_dwordx2 v[52:53], v[8:9], off
	v_add_co_u32_e32 v6, vcc, s0, v146
	s_movk_i32 s0, 0xf800
	s_nop 0
	v_addc_co_u32_e32 v7, vcc, -1, v147, vcc
	v_add_co_u32_e32 v8, vcc, s0, v146
	s_movk_i32 s0, 0xfa00
	s_nop 0
	v_addc_co_u32_e32 v9, vcc, -1, v147, vcc
	global_load_dwordx2 v[54:55], v[6:7], off
	global_load_dwordx2 v[56:57], v[8:9], off
	v_add_co_u32_e32 v6, vcc, s0, v146
	s_movk_i32 s0, 0xfc00
	s_nop 0
	v_addc_co_u32_e32 v7, vcc, -1, v147, vcc
	global_load_dwordx2 v[58:59], v[6:7], off
	v_add_co_u32_e32 v6, vcc, s0, v146
	s_movk_i32 s0, 0xfe00
	s_nop 0
	v_addc_co_u32_e32 v7, vcc, -1, v147, vcc
	global_load_dwordx2 v[60:61], v[6:7], off
	v_add_co_u32_e32 v6, vcc, s0, v146
	s_mov_b64 s[0:1], 0
	s_nop 0
	v_addc_co_u32_e32 v7, vcc, -1, v147, vcc
	global_load_dwordx2 v[62:63], v[6:7], off
	global_load_dwordx2 v[66:67], v[146:147], off
	s_waitcnt vmcnt(0) lgkmcnt(0)
	v_lshlrev_b32_e32 v14, 16, v2
	v_and_b32_e32 v15, 0xffff0000, v2
	v_lshlrev_b32_e32 v16, 16, v3
	v_and_b32_e32 v17, 0xffff0000, v3
	v_lshlrev_b32_e32 v10, 16, v4
	v_and_b32_e32 v11, 0xffff0000, v4
	v_lshlrev_b32_e32 v12, 16, v5
	v_and_b32_e32 v13, 0xffff0000, v5
	v_lshlrev_b32_e32 v6, 16, v18
	v_and_b32_e32 v7, 0xffff0000, v18
	v_lshlrev_b32_e32 v8, 16, v19
	v_and_b32_e32 v9, 0xffff0000, v19
	v_lshlrev_b32_e32 v2, 16, v20
	v_and_b32_e32 v3, 0xffff0000, v20
	v_lshlrev_b32_e32 v4, 16, v21
	v_and_b32_e32 v5, 0xffff0000, v21
	v_lshlrev_b32_e32 v48, 16, v22
	v_and_b32_e32 v49, 0xffff0000, v22
	v_lshlrev_b32_e32 v50, 16, v23
	v_and_b32_e32 v51, 0xffff0000, v23
	v_lshlrev_b32_e32 v44, 16, v24
	v_and_b32_e32 v45, 0xffff0000, v24
	v_lshlrev_b32_e32 v46, 16, v25
	v_and_b32_e32 v47, 0xffff0000, v25
	v_lshlrev_b32_e32 v40, 16, v26
	v_and_b32_e32 v41, 0xffff0000, v26
	v_lshlrev_b32_e32 v42, 16, v27
	v_and_b32_e32 v43, 0xffff0000, v27
	v_lshlrev_b32_e32 v30, 16, v28
	v_and_b32_e32 v31, 0xffff0000, v28
	v_lshlrev_b32_e32 v32, 16, v29
	v_and_b32_e32 v33, 0xffff0000, v29
	v_lshlrev_b32_e32 v36, 16, v38
	v_and_b32_e32 v37, 0xffff0000, v38
	v_lshlrev_b32_e32 v38, 16, v39
	v_and_b32_e32 v39, 0xffff0000, v39
	v_lshlrev_b32_e32 v26, 16, v52
	v_and_b32_e32 v27, 0xffff0000, v52
	v_lshlrev_b32_e32 v28, 16, v53
	v_and_b32_e32 v29, 0xffff0000, v53
	v_lshlrev_b32_e32 v22, 16, v54
	v_and_b32_e32 v23, 0xffff0000, v54
	v_lshlrev_b32_e32 v24, 16, v55
	v_and_b32_e32 v25, 0xffff0000, v55
	v_lshlrev_b32_e32 v18, 16, v56
	v_and_b32_e32 v19, 0xffff0000, v56
	v_lshlrev_b32_e32 v20, 16, v57
	v_and_b32_e32 v21, 0xffff0000, v57
	v_lshlrev_b32_e32 v52, 16, v58
	v_and_b32_e32 v53, 0xffff0000, v58
	v_lshlrev_b32_e32 v54, 16, v59
	v_and_b32_e32 v55, 0xffff0000, v59
	v_lshlrev_b32_e32 v56, 16, v60
	v_and_b32_e32 v57, 0xffff0000, v60
	v_lshlrev_b32_e32 v58, 16, v61
	v_and_b32_e32 v59, 0xffff0000, v61
	v_lshlrev_b32_e32 v60, 16, v62
	v_and_b32_e32 v61, 0xffff0000, v62
	v_lshlrev_b32_e32 v62, 16, v63
	v_and_b32_e32 v63, 0xffff0000, v63
	v_lshlrev_b32_e32 v64, 16, v66
	v_and_b32_e32 v65, 0xffff0000, v66
	v_lshlrev_b32_e32 v66, 16, v67
	v_and_b32_e32 v67, 0xffff0000, v67

.LBB0_1803:
	v_readlane_b32 s8, v251, 19
	s_cmpk_lt_i32 s4, 0x2000
	v_readlane_b32 s9, v251, 20
	s_cselect_b64 s[6:7], -1, 0
	s_xor_b64 s[8:9], s[8:9], -1
	s_or_b64 s[6:7], s[8:9], s[6:7]
	s_mov_b32 s28, s4
	s_mov_b64 s[0:1], -1
	s_and_b64 vcc, exec, s[6:7]
	s_mov_b32 s9, s29
	s_mov_b64 s[6:7], s[28:29]
	s_cbranch_vccz .LBB0_1805
	v_add_co_u32_e32 v2, vcc, 0xffffe200, v216
	s_movk_i32 s0, 0xe800
	s_nop 0
	v_addc_co_u32_e32 v3, vcc, -1, v217, vcc
	v_add_co_u32_e32 v4, vcc, 0xffffe400, v216
	s_mov_b64 s[6:7], s[4:5]
	s_nop 0
	v_addc_co_u32_e32 v5, vcc, -1, v217, vcc
	v_add_co_u32_e32 v6, vcc, 0xffffe600, v216
	s_nop 1
	v_addc_co_u32_e32 v7, vcc, -1, v217, vcc
	v_add_co_u32_e32 v8, vcc, s0, v216
	s_movk_i32 s0, 0xea00
	s_nop 0
	v_addc_co_u32_e32 v9, vcc, -1, v217, vcc
	global_load_dwordx2 v[2:3], v[2:3], off
	s_nop 0
	global_load_dwordx2 v[4:5], v[4:5], off
	s_nop 0
	global_load_dwordx2 v[18:19], v[6:7], off
	global_load_dwordx2 v[20:21], v[8:9], off
	v_add_co_u32_e32 v6, vcc, s0, v216
	s_movk_i32 s0, 0xec00
	s_nop 0
	v_addc_co_u32_e32 v7, vcc, -1, v217, vcc
	global_load_dwordx2 v[22:23], v[6:7], off
	v_add_co_u32_e32 v6, vcc, s0, v216
	s_movk_i32 s0, 0xee00
	s_nop 0
	v_addc_co_u32_e32 v7, vcc, -1, v217, vcc
	v_add_co_u32_e32 v8, vcc, s0, v216
	s_movk_i32 s0, 0xf000
	s_nop 0
	v_addc_co_u32_e32 v9, vcc, -1, v217, vcc
	v_add_co_u32_e32 v10, vcc, s0, v216
	s_movk_i32 s0, 0xf200
	s_nop 0
	v_addc_co_u32_e32 v11, vcc, -1, v217, vcc
	global_load_dwordx2 v[24:25], v[6:7], off
	global_load_dwordx2 v[26:27], v[8:9], off
	global_load_dwordx2 v[28:29], v[10:11], off
	v_add_co_u32_e32 v6, vcc, s0, v216
	s_movk_i32 s0, 0xf400
	s_nop 0
	v_addc_co_u32_e32 v7, vcc, -1, v217, vcc
	v_add_co_u32_e32 v8, vcc, s0, v216
	s_movk_i32 s0, 0xf600
	s_nop 0
	v_addc_co_u32_e32 v9, vcc, -1, v217, vcc
	global_load_dwordx2 v[32:33], v[6:7], off
	global_load_dwordx2 v[52:53], v[8:9], off
	v_add_co_u32_e32 v6, vcc, s0, v216
	s_movk_i32 s0, 0xf800
	s_nop 0
	v_addc_co_u32_e32 v7, vcc, -1, v217, vcc
	v_add_co_u32_e32 v8, vcc, s0, v216
	s_movk_i32 s0, 0xfa00
	s_nop 0
	v_addc_co_u32_e32 v9, vcc, -1, v217, vcc
	global_load_dwordx2 v[54:55], v[6:7], off
	global_load_dwordx2 v[56:57], v[8:9], off
	v_add_co_u32_e32 v6, vcc, s0, v216
	s_movk_i32 s0, 0xfc00
	s_nop 0
	v_addc_co_u32_e32 v7, vcc, -1, v217, vcc
	global_load_dwordx2 v[58:59], v[6:7], off
	v_add_co_u32_e32 v6, vcc, s0, v216
	s_movk_i32 s0, 0xfe00
	s_nop 0
	v_addc_co_u32_e32 v7, vcc, -1, v217, vcc
	global_load_dwordx2 v[62:63], v[6:7], off
	v_add_co_u32_e32 v6, vcc, s0, v216
	s_mov_b64 s[0:1], 0
	s_nop 0
	v_addc_co_u32_e32 v7, vcc, -1, v217, vcc
	global_load_dwordx2 v[68:69], v[6:7], off
	global_load_dwordx2 v[70:71], v[216:217], off
	s_waitcnt vmcnt(0) lgkmcnt(0)
	v_lshlrev_b32_e32 v14, 16, v2
	v_and_b32_e32 v15, 0xffff0000, v2
	v_lshlrev_b32_e32 v16, 16, v3
	v_and_b32_e32 v17, 0xffff0000, v3
	v_lshlrev_b32_e32 v10, 16, v4
	v_and_b32_e32 v11, 0xffff0000, v4
	v_lshlrev_b32_e32 v12, 16, v5
	v_and_b32_e32 v13, 0xffff0000, v5
	v_lshlrev_b32_e32 v6, 16, v18
	v_and_b32_e32 v7, 0xffff0000, v18
	v_lshlrev_b32_e32 v8, 16, v19
	v_and_b32_e32 v9, 0xffff0000, v19
	v_lshlrev_b32_e32 v2, 16, v20
	v_and_b32_e32 v3, 0xffff0000, v20
	v_lshlrev_b32_e32 v4, 16, v21
	v_and_b32_e32 v5, 0xffff0000, v21
	v_lshlrev_b32_e32 v48, 16, v22
	v_and_b32_e32 v49, 0xffff0000, v22
	v_lshlrev_b32_e32 v50, 16, v23
	v_and_b32_e32 v51, 0xffff0000, v23
	v_lshlrev_b32_e32 v44, 16, v24
	v_and_b32_e32 v45, 0xffff0000, v24
	v_lshlrev_b32_e32 v46, 16, v25
	v_and_b32_e32 v47, 0xffff0000, v25
	v_lshlrev_b32_e32 v40, 16, v26
	v_and_b32_e32 v41, 0xffff0000, v26
	v_lshlrev_b32_e32 v42, 16, v27
	v_and_b32_e32 v43, 0xffff0000, v27
	v_lshlrev_b32_e32 v36, 16, v28
	v_and_b32_e32 v37, 0xffff0000, v28
	v_lshlrev_b32_e32 v38, 16, v29
	v_and_b32_e32 v39, 0xffff0000, v29
	v_lshlrev_b32_e32 v30, 16, v32
	v_and_b32_e32 v31, 0xffff0000, v32
	v_lshlrev_b32_e32 v32, 16, v33
	v_and_b32_e32 v33, 0xffff0000, v33
	v_lshlrev_b32_e32 v26, 16, v52
	v_and_b32_e32 v27, 0xffff0000, v52
	v_lshlrev_b32_e32 v28, 16, v53
	v_and_b32_e32 v29, 0xffff0000, v53
	v_lshlrev_b32_e32 v22, 16, v54
	v_and_b32_e32 v23, 0xffff0000, v54
	v_lshlrev_b32_e32 v24, 16, v55
	v_and_b32_e32 v25, 0xffff0000, v55
	v_lshlrev_b32_e32 v18, 16, v56
	v_and_b32_e32 v19, 0xffff0000, v56
	v_lshlrev_b32_e32 v20, 16, v57
	v_and_b32_e32 v21, 0xffff0000, v57
	v_lshlrev_b32_e32 v64, 16, v58
	v_and_b32_e32 v65, 0xffff0000, v58
	v_lshlrev_b32_e32 v66, 16, v59
	v_and_b32_e32 v67, 0xffff0000, v59
	v_lshlrev_b32_e32 v60, 16, v62
	v_and_b32_e32 v61, 0xffff0000, v62
	v_lshlrev_b32_e32 v62, 16, v63
	v_and_b32_e32 v63, 0xffff0000, v63
	v_lshlrev_b32_e32 v56, 16, v68
	v_and_b32_e32 v57, 0xffff0000, v68
	v_lshlrev_b32_e32 v58, 16, v69
	v_and_b32_e32 v59, 0xffff0000, v69
	v_lshlrev_b32_e32 v52, 16, v70
	v_and_b32_e32 v53, 0xffff0000, v70
	v_lshlrev_b32_e32 v54, 16, v71
	v_and_b32_e32 v55, 0xffff0000, v71
